# flat->global for all workspace accesses (no lgkmcnt coupling), removed 4 redundant mid-slice vmcnt(0) in mLSTM slice loop
# speedup vs baseline: 1.0442x; 1.0051x over previous
; #define LAS __attribute__((address_space(3)))
; __device__ __forceinline__ unsigned xb_add(unsigned* p, unsigned v) { return __hip_atomic_fetch_add(p, v, __ATOMIC_RELAXED, __HIP_MEMORY_SCOPE_AGENT); }
; __device__ __forceinline__ unsigned xb_xcc_id() { return (unsigned)__builtin_amdgcn_s_getreg((3 << 11) | 20) & 0xFu; }
; __device__ __forceinline__ XcdBarrier xcd_barrier_post(unsigned* bar, volatile LAS unsigned* st) {
;   XcdBarrier b; b.bar = bar; b.x = xb_xcc_id(); b.st = st;
;   if (threadIdx.x == 0) (void)xb_add(&bar[XB_XCNT(b.x)], 1u);
;   return b;
; }
; __global__ void __launch_bounds__(512) fwd_megakernel(Params p) {
;   cg::grid_group grid = cg::this_grid();
;   volatile LAS unsigned* st = (volatile LAS unsigned*)((LAS unsigned char*)smem + (DYN_LDS - 16));
;   if (threadIdx.x == 0) { st[0] = 0u; st[1] = 0u; }
;   __syncthreads();
;   const XcdBarrier xb = xcd_barrier_post((unsigned*)(ws_of(p) + OFF_BAR), st);
.LBB0_2:
	s_or_b64 exec, exec, s[2:3]
	s_load_dwordx16 s[4:19], s[0:1], 0x0
	s_waitcnt lgkmcnt(0)
	s_mov_b64 s[2:3], s[50:51]
	s_barrier
	v_writelane_b32 v245, s4, 4
	s_nop 1
	v_writelane_b32 v245, s5, 5
	v_writelane_b32 v245, s6, 6
	v_writelane_b32 v245, s7, 7
	v_writelane_b32 v245, s8, 8
	v_writelane_b32 v245, s9, 9
	v_writelane_b32 v245, s10, 10
	v_writelane_b32 v245, s11, 11
	v_writelane_b32 v245, s12, 12
	v_writelane_b32 v245, s13, 13
	v_writelane_b32 v245, s14, 14
	v_writelane_b32 v245, s15, 15
	v_writelane_b32 v245, s16, 16
	v_writelane_b32 v245, s17, 17
	v_writelane_b32 v245, s18, 18
	v_writelane_b32 v245, s19, 19
	s_add_u32 s4, s2, 0x5f080000
	v_writelane_b32 v245, s4, 20
	s_addc_u32 s4, s3, 0
	v_writelane_b32 v245, s4, 21
	s_getreg_b32 s4, hwreg(HW_REG_XCC_ID, 0, 4)
	s_and_b32 s4, s4, 15
	v_writelane_b32 v245, s4, 22
	s_mov_b64 s[4:5], exec
	v_readlane_b32 s6, v245, 2
	v_readlane_b32 s7, v245, 3
	s_and_b64 s[6:7], s[4:5], s[6:7]
	s_mov_b64 exec, s[6:7]
	s_cbranch_execz .LBB0_4
	v_readlane_b32 s6, v245, 22
	s_lshl_b32 s6, s6, 8
	v_readlane_b32 s7, v245, 20
	s_add_u32 s6, s7, s6
	v_readlane_b32 s7, v245, 21
	s_addc_u32 s7, s7, 0
	v_mov_b32_e32 v1, 1
	v_mov_b64_e32 v[2:3], s[6:7]
	global_atomic_add v[2:3], v1, off offset:1024

; __device__ void phase_convert(const Params& p) {
;     ...
;   {
;     bf16_t* xb = (bf16_t*)(ws_of(p) + OFF_XB);
;     const long n8 = (long)MTOK * DM / 8;
;     for (long i = (long)bid * 512 + threadIdx.x; i < n8; i += (long)G * 512) {
;       f32x4 a = *(const f32x4*)(p.x + i * 8), b = *(const f32x4*)(p.x + i * 8 + 4);
;       u32x4 o;
;       o.x = pack2(a[0], a[1]); o.y = pack2(a[2], a[3]); o.z = pack2(b[0], b[1]); o.w = pack2(b[2], b[3]);
;       *(u32x4*)(xb + i * 8) = o;
;     }
.LBB0_6:
	global_load_dwordx4 v[8:11], v[4:5], off offset:-16
	global_load_dwordx4 v[12:15], v[4:5], off
	v_lshl_add_u64 v[2:3], v[2:3], 0, s[6:7]
	v_cmp_lt_i64_e32 vcc, s[14:15], v[2:3]
	v_lshl_add_u64 v[4:5], v[4:5], 0, s[8:9]
	s_or_b64 s[12:13], vcc, s[12:13]
	s_waitcnt vmcnt(0)
	v_cvt_pk_bf16_f32 v8, v8, v9
	v_cvt_pk_bf16_f32 v9, v10, v11
	v_cvt_pk_bf16_f32 v10, v12, v13
	v_cvt_pk_bf16_f32 v11, v14, v15
	global_store_dwordx4 v[6:7], v[8:11], off
	v_lshl_add_u64 v[6:7], v[6:7], 0, s[10:11]
	s_andn2_b64 exec, exec, s[12:13]
	s_cbranch_execnz .LBB0_6

; __device__ __forceinline__ void cvt_tile(const float* __restrict__ src, long ld, int k0, int c0, bf16_t* __restrict__ dst,
;                                          long ldd, int j0, int mode) {
;   float* T = (float*)smem;
;   const int tid = opaque_tid();
;   const int r = tid >> 4, c4 = (tid & 15) * 4;
; #pragma unroll
;   for (int i = 0; i < 2; ++i) {
;     const int row = r + 32 * i;
;     f32x4 v = {0.f, 0.f, 0.f, 0.f};
;     if (mode == 0) v = *(const f32x4*)(src + (long)(k0 + row) * ld + c0 + c4);
;     else {
;       if (c4 < 32) v = *(const f32x4*)(src + (long)(k0 + row) * ld + 9216 + c4);
;       else if (c4 < 48) v = *(const f32x4*)(src + (long)(k0 + row) * ld + 19488 + (c4 - 32));
;     }
;     T[row * 65 + c4 + 0] = v[0];
;     T[row * 65 + c4 + 1] = v[1];
;     T[row * 65 + c4 + 2] = v[2];
;     T[row * 65 + c4 + 3] = v[3];
;   }
;   __syncthreads();
;   const int n = tid >> 3, kk = (tid & 7) * 8;
;   u32x4 o;
;   o.x = pack2(T[(kk + 0) * 65 + n], T[(kk + 1) * 65 + n]);
;   o.y = pack2(T[(kk + 2) * 65 + n], T[(kk + 3) * 65 + n]);
;   o.z = pack2(T[(kk + 4) * 65 + n], T[(kk + 5) * 65 + n]);
;   o.w = pack2(T[(kk + 6) * 65 + n], T[(kk + 7) * 65 + n]);
;   *(u32x4*)(dst + (long)(j0 + n) * ldd + k0 + kk) = o;
;   __syncthreads();
; }
; __device__ void phase_convert(const Params& p) {
;     ...
;     for (int it = bid; it < njt * 32; it += G) {
;       const int jt = it >> 5, kt = it & 31;
;       const int j0 = jt * 64;
;       if (jt < NPROJ / 64) {
;         const int c0 = j0 < 9216 ? j0 : (j0 < 19456 ? j0 + 32 : j0 + 48);
;         cvt_tile(src, IN_DIM, kt * 64, c0, dst, DM, j0, 0);
;       } else cvt_tile(src, IN_DIM, kt * 64, 0, dst, DM, j0, 1);
.LBB0_26:
	s_or_b64 exec, exec, s[0:1]
	v_add_u32_e32 v6, 0x2080, v11
	s_waitcnt vmcnt(0)
	ds_write2_b32 v6, v2, v3 offset1:1
	v_ashrrev_i32_e32 v6, 3, v1
	v_lshlrev_b32_e32 v1, 3, v1
	v_add_u32_e32 v2, 0x2088, v11
	v_and_b32_e32 v1, 56, v1
	ds_write2_b32 v2, v4, v5 offset1:1
	v_mul_u32_u24_e32 v2, 0x104, v1
	v_lshlrev_b32_e32 v3, 2, v6
	v_add3_u32 v8, 0, v2, v3
	s_waitcnt lgkmcnt(0)
	s_barrier
	ds_read2_b32 v[2:3], v8 offset1:65
	ds_read2_b32 v[4:5], v8 offset0:130 offset1:195
	v_add_u32_e32 v10, 0x400, v8
	ds_read2_b32 v[8:9], v10 offset0:4 offset1:69
	ds_read2_b32 v[10:11], v10 offset0:134 offset1:199
	s_waitcnt lgkmcnt(3)
	v_cvt_pk_bf16_f32 v2, v2, v3
	s_waitcnt lgkmcnt(2)
	v_cvt_pk_bf16_f32 v3, v4, v5
	s_waitcnt lgkmcnt(1)
	v_cvt_pk_bf16_f32 v4, v8, v9
	v_add_u32_e32 v8, s37, v6
	v_ashrrev_i32_e32 v9, 31, v8
	v_lshlrev_b64 v[8:9], 12, v[8:9]
	v_lshl_add_u64 v[8:9], s[22:23], 0, v[8:9]
	s_lshl_b32 s16, s16, 1
	v_lshl_add_u64 v[8:9], v[8:9], 0, s[16:17]
	v_lshlrev_b32_e32 v6, 1, v1
	v_lshl_add_u64 v[8:9], v[8:9], 0, v[6:7]
	s_waitcnt lgkmcnt(0)
	v_cvt_pk_bf16_f32 v5, v10, v11
	global_store_dwordx4 v[8:9], v[2:5], off
	s_waitcnt lgkmcnt(0)
	s_barrier
	s_branch .LBB0_11
.LBB0_27:
	s_cmpk_lt_i32 s38, 0x130
	s_cselect_b32 s0, 32, 48
	s_cmpk_gt_i32 s38, 0x8f
	s_cselect_b32 s0, s0, 0
	s_or_b32 s0, s0, s37
	s_ashr_i32 s1, s0, 31
	v_mov_b32_e32 v1, v164
	s_lshl_b64 s[0:1], s[0:1], 2
	s_add_u32 s0, s20, s0
	v_lshlrev_b32_e32 v2, 4, v1
	v_ashrrev_i32_e32 v12, 4, v1
	v_and_b32_e32 v6, 0xf0, v2
	s_addc_u32 s1, s21, s1
	v_lshl_add_u64 v[8:9], s[0:1], 0, v[6:7]
	v_lshl_add_u32 v10, s36, 6, v12
	v_mad_i64_i32 v[2:3], s[0:1], v10, s31, v[8:9]
	global_load_dwordx4 v[2:5], v[2:3], off
	v_add_u32_e32 v10, 32, v10
	v_mad_i64_i32 v[8:9], s[0:1], v10, s31, v[8:9]
	global_load_dwordx4 v[8:11], v[8:9], off
	v_ashrrev_i32_e32 v13, 3, v1
	v_lshlrev_b32_e32 v1, 3, v1
	v_mul_lo_u32 v14, v12, s34
	v_and_b32_e32 v1, 56, v1
	v_lshlrev_b32_e32 v15, 2, v13
	v_add3_u32 v14, 0, v6, v14
	v_mul_u32_u24_e32 v6, 0x104, v1
	v_add_u32_e32 v12, s37, v13
	v_add3_u32 v15, 0, v6, v15
	v_ashrrev_i32_e32 v13, 31, v12
	v_add_u32_e32 v16, 0x2080, v14
	v_add_u32_e32 v17, 0x2088, v14
	v_add_u32_e32 v18, 0x400, v15
	v_lshlrev_b64 v[12:13], 12, v[12:13]
	v_lshl_add_u64 v[12:13], s[22:23], 0, v[12:13]
	s_lshl_b32 s16, s36, 7
	v_lshl_add_u64 v[12:13], v[12:13], 0, s[16:17]
	v_lshlrev_b32_e32 v6, 1, v1
	v_lshl_add_u64 v[12:13], v[12:13], 0, v[6:7]
	s_waitcnt vmcnt(0)
	ds_write2_b32 v14, v2, v3 offset1:1
	ds_write2_b32 v14, v4, v5 offset0:2 offset1:3
	ds_write2_b32 v16, v8, v9 offset1:1
	ds_write2_b32 v17, v10, v11 offset1:1
	s_waitcnt lgkmcnt(0)
	s_barrier
	ds_read2_b32 v[2:3], v15 offset1:65
	ds_read2_b32 v[4:5], v15 offset0:130 offset1:195
	ds_read2_b32 v[8:9], v18 offset0:4 offset1:69
	ds_read2_b32 v[10:11], v18 offset0:134 offset1:199
	s_waitcnt lgkmcnt(3)
	v_cvt_pk_bf16_f32 v2, v2, v3
	s_waitcnt lgkmcnt(2)
	v_cvt_pk_bf16_f32 v3, v4, v5
	s_waitcnt lgkmcnt(1)
	v_cvt_pk_bf16_f32 v4, v8, v9
	s_waitcnt lgkmcnt(0)
	v_cvt_pk_bf16_f32 v5, v10, v11
	global_store_dwordx4 v[12:13], v[2:5], off
	s_waitcnt lgkmcnt(0)
	s_barrier
	s_branch .LBB0_11

; __device__ __forceinline__ void cvt_tile(const float* __restrict__ src, long ld, int k0, int c0, bf16_t* __restrict__ dst,
;                                          long ldd, int j0, int mode) {
;     ...
;   const int r = tid >> 4, c4 = (tid & 15) * 4;
; #pragma unroll
;   for (int i = 0; i < 2; ++i) {
;     const int row = r + 32 * i;
;     f32x4 v = {0.f, 0.f, 0.f, 0.f};
;     if (mode == 0) v = *(const f32x4*)(src + (long)(k0 + row) * ld + c0 + c4);
;     else {
;       if (c4 < 32) v = *(const f32x4*)(src + (long)(k0 + row) * ld + 9216 + c4);
;       else if (c4 < 48) v = *(const f32x4*)(src + (long)(k0 + row) * ld + 19488 + (c4 - 32));
;     }
;     T[row * 65 + c4 + 0] = v[0];
;     T[row * 65 + c4 + 1] = v[1];
;     T[row * 65 + c4 + 2] = v[2];
;     T[row * 65 + c4 + 3] = v[3];
;   }
;   __syncthreads();
;   const int n = tid >> 3, kk = (tid & 7) * 8;
;   u32x4 o;
;   o.x = pack2(T[(kk + 0) * 65 + n], T[(kk + 1) * 65 + n]);
;   o.y = pack2(T[(kk + 2) * 65 + n], T[(kk + 3) * 65 + n]);
;   o.z = pack2(T[(kk + 4) * 65 + n], T[(kk + 5) * 65 + n]);
;   o.w = pack2(T[(kk + 6) * 65 + n], T[(kk + 7) * 65 + n]);
;   *(u32x4*)(dst + (long)(j0 + n) * ldd + k0 + kk) = o;
;   __syncthreads();
; __device__ void phase_convert(const Params& p) {
;     ...
;     for (int it = bid; it < 3 * 32 * 32; it += G) {
;       const int br = it >> 10, jt = (it >> 5) & 31, kt = it & 31;
;       cvt_tile(p.w_branch + ((size_t)l * 3 + br) * DM * DM, DM, kt * 64, jt * 64,
;                (bf16_t*)(ws_of(p) + OFF_WBT + l * WBT_L) + (size_t)br * DM * DM, DM, jt * 64, 0);
;     }
.LBB0_30:
	s_ashr_i32 s22, s20, 10
	s_ashr_i32 s23, s22, 31
	s_add_u32 s26, s0, s22
	s_addc_u32 s27, 0, s23
	s_lshl_b64 s[26:27], s[26:27], 24
	s_mov_b64 s[24:25], s[50:51]
	s_waitcnt lgkmcnt(0)
	s_add_u32 s16, s92, s26
	s_addc_u32 s21, s93, s27
	s_and_b32 s26, s4, 0x7c0
	s_and_b32 s27, s5, 0x7c0
	s_add_u32 s24, s24, s1
	v_mov_b32_e32 v1, v164
	s_addc_u32 s25, s25, 0
	s_lshl_b64 s[22:23], s[22:23], 23
	s_add_u32 s22, s24, s22
	v_ashrrev_i32_e32 v12, 4, v1
	v_lshlrev_b32_e32 v2, 4, v1
	v_and_b32_e32 v6, 0xf0, v2
	v_add_u32_e32 v2, s26, v12
	s_addc_u32 s23, s25, s23
	s_lshl_b32 s24, s27, 2
	v_add_u32_e32 v4, 32, v2
	s_add_u32 s24, s16, s24
	v_ashrrev_i32_e32 v3, 31, v2
	v_ashrrev_i32_e32 v5, 31, v4
	s_addc_u32 s25, s21, 0
	v_lshlrev_b64 v[2:3], 13, v[2:3]
	v_lshlrev_b64 v[4:5], 13, v[4:5]
	v_lshl_add_u64 v[8:9], s[24:25], 0, v[6:7]
	v_lshl_add_u64 v[2:3], v[8:9], 0, v[2:3]
	v_lshl_add_u64 v[8:9], v[8:9], 0, v[4:5]
	global_load_dwordx4 v[2:5], v[2:3], off
	s_nop 0
	global_load_dwordx4 v[8:11], v[8:9], off
	v_ashrrev_i32_e32 v13, 3, v1
	v_lshlrev_b32_e32 v1, 3, v1
	v_mul_lo_u32 v12, v12, s34
	v_and_b32_e32 v1, 56, v1
	v_add3_u32 v15, 0, v6, v12
	v_add_u32_e32 v12, s27, v13
	v_lshlrev_b32_e32 v14, 2, v13
	v_mul_u32_u24_e32 v6, 0x104, v1
	v_ashrrev_i32_e32 v13, 31, v12
	v_add3_u32 v14, 0, v6, v14
	v_lshlrev_b64 v[12:13], 12, v[12:13]
	v_add_u32_e32 v16, 0x2080, v15
	v_add_u32_e32 v17, 0x2088, v15
	v_add_u32_e32 v18, 0x400, v14
	v_lshl_add_u64 v[12:13], s[22:23], 0, v[12:13]
	s_lshl_b32 s16, s26, 1
	v_lshl_add_u64 v[12:13], v[12:13], 0, s[16:17]
	v_lshlrev_b32_e32 v6, 1, v1
	v_lshl_add_u64 v[12:13], v[12:13], 0, v[6:7]
	s_add_i32 s20, s20, s76
	s_add_i32 s5, s5, s29
	s_add_i32 s4, s4, s65
	v_add_co_u32_e32 v12, vcc, 0xc880000, v12
	s_cmpk_gt_i32 s20, 0xbff
	s_nop 0
	v_addc_co_u32_e32 v13, vcc, 0, v13, vcc
	s_waitcnt vmcnt(0)
	ds_write2_b32 v15, v2, v3 offset1:1
	ds_write2_b32 v15, v4, v5 offset0:2 offset1:3
	ds_write2_b32 v16, v8, v9 offset1:1
	ds_write2_b32 v17, v10, v11 offset1:1
	s_waitcnt lgkmcnt(0)
	s_barrier
	ds_read2_b32 v[2:3], v14 offset1:65
	ds_read2_b32 v[4:5], v14 offset0:130 offset1:195
	ds_read2_b32 v[8:9], v18 offset0:4 offset1:69
	ds_read2_b32 v[10:11], v18 offset0:134 offset1:199
	s_waitcnt lgkmcnt(3)
	v_cvt_pk_bf16_f32 v2, v2, v3
	s_waitcnt lgkmcnt(2)
	v_cvt_pk_bf16_f32 v3, v4, v5
	s_waitcnt lgkmcnt(1)
	v_cvt_pk_bf16_f32 v4, v8, v9
	s_waitcnt lgkmcnt(0)
	v_cvt_pk_bf16_f32 v5, v10, v11
	global_store_dwordx4 v[12:13], v[2:5], off
	s_waitcnt lgkmcnt(0)
	s_barrier
	s_cbranch_scc0 .LBB0_30

; __device__ __forceinline__ void cvt_tile(const float* __restrict__ src, long ld, int k0, int c0, bf16_t* __restrict__ dst,
;                                          long ldd, int j0, int mode) {
;     ...
;   const int r = tid >> 4, c4 = (tid & 15) * 4;
; #pragma unroll
;   for (int i = 0; i < 2; ++i) {
;     const int row = r + 32 * i;
;     f32x4 v = {0.f, 0.f, 0.f, 0.f};
;     if (mode == 0) v = *(const f32x4*)(src + (long)(k0 + row) * ld + c0 + c4);
;     else {
;       if (c4 < 32) v = *(const f32x4*)(src + (long)(k0 + row) * ld + 9216 + c4);
;       else if (c4 < 48) v = *(const f32x4*)(src + (long)(k0 + row) * ld + 19488 + (c4 - 32));
;     }
;     T[row * 65 + c4 + 0] = v[0];
;     T[row * 65 + c4 + 1] = v[1];
;     T[row * 65 + c4 + 2] = v[2];
;     T[row * 65 + c4 + 3] = v[3];
;   }
;   __syncthreads();
;   const int n = tid >> 3, kk = (tid & 7) * 8;
;   u32x4 o;
;   o.x = pack2(T[(kk + 0) * 65 + n], T[(kk + 1) * 65 + n]);
;   o.y = pack2(T[(kk + 2) * 65 + n], T[(kk + 3) * 65 + n]);
;   o.z = pack2(T[(kk + 4) * 65 + n], T[(kk + 5) * 65 + n]);
;   o.w = pack2(T[(kk + 6) * 65 + n], T[(kk + 7) * 65 + n]);
;   *(u32x4*)(dst + (long)(j0 + n) * ldd + k0 + kk) = o;
;   __syncthreads();
; __device__ void phase_convert(const Params& p) {
;     ...
;     for (int it = bid; it < 32 * 32; it += G) {
;       const int jt = it >> 5, kt = it & 31;
;       cvt_tile(p.w_out + (size_t)l * DM * DM, DM, kt * 64, jt * 64, (bf16_t*)(ws_of(p) + OFF_WOT + l * WOT_L), DM, jt * 64, 0);
;     }
.LBB0_33:
	s_mov_b64 s[26:27], s[50:51]
	s_and_b32 s16, s20, 0x7c0
	s_and_b32 s24, s21, 0xffffffc0
	v_mov_b32_e32 v1, v164
	s_add_u32 s26, s26, s0
	s_addc_u32 s27, s27, s1
	v_ashrrev_i32_e32 v12, 4, v1
	v_lshlrev_b32_e32 v2, 4, v1
	s_ashr_i32 s25, s24, 31
	v_and_b32_e32 v6, 0xf0, v2
	v_add_u32_e32 v2, s16, v12
	s_lshl_b64 s[36:37], s[24:25], 2
	v_add_u32_e32 v4, 32, v2
	s_add_u32 s36, s4, s36
	v_ashrrev_i32_e32 v3, 31, v2
	v_ashrrev_i32_e32 v5, 31, v4
	s_addc_u32 s37, s5, s37
	v_lshlrev_b64 v[2:3], 13, v[2:3]
	v_lshlrev_b64 v[4:5], 13, v[4:5]
	v_lshl_add_u64 v[8:9], s[36:37], 0, v[6:7]
	v_lshl_add_u64 v[2:3], v[8:9], 0, v[2:3]
	v_lshl_add_u64 v[8:9], v[8:9], 0, v[4:5]
	global_load_dwordx4 v[2:5], v[2:3], off
	s_nop 0
	global_load_dwordx4 v[8:11], v[8:9], off
	v_ashrrev_i32_e32 v13, 3, v1
	v_lshlrev_b32_e32 v1, 3, v1
	v_mul_lo_u32 v14, v12, s34
	v_and_b32_e32 v1, 56, v1
	v_add_u32_e32 v12, s24, v13
	v_lshlrev_b32_e32 v15, 2, v13
	v_add3_u32 v14, 0, v6, v14
	v_mul_u32_u24_e32 v6, 0x104, v1
	v_ashrrev_i32_e32 v13, 31, v12
	v_add3_u32 v15, 0, v6, v15
	v_lshlrev_b64 v[12:13], 12, v[12:13]
	v_add_u32_e32 v16, 0x2080, v14
	v_add_u32_e32 v17, 0x2088, v14
	v_add_u32_e32 v18, 0x400, v15
	v_lshl_add_u64 v[12:13], s[26:27], 0, v[12:13]
	s_lshl_b32 s16, s16, 1
	v_lshl_add_u64 v[12:13], v[12:13], 0, s[16:17]
	v_lshlrev_b32_e32 v6, 1, v1
	v_lshl_add_u64 v[12:13], v[12:13], 0, v[6:7]
	s_add_i32 s22, s22, s76
	s_add_i32 s21, s21, s29
	s_add_i32 s20, s20, s65
	v_add_co_u32_e32 v12, vcc, 0xf880000, v12
	s_cmpk_gt_i32 s22, 0x3ff
	s_nop 0
	v_addc_co_u32_e32 v13, vcc, 0, v13, vcc
	s_waitcnt vmcnt(0)
	ds_write2_b32 v14, v2, v3 offset1:1
	ds_write2_b32 v14, v4, v5 offset0:2 offset1:3
	ds_write2_b32 v16, v8, v9 offset1:1
	ds_write2_b32 v17, v10, v11 offset1:1
	s_waitcnt lgkmcnt(0)
	s_barrier
	ds_read2_b32 v[2:3], v15 offset1:65
	ds_read2_b32 v[4:5], v15 offset0:130 offset1:195
	ds_read2_b32 v[8:9], v18 offset0:4 offset1:69
	ds_read2_b32 v[10:11], v18 offset0:134 offset1:199
	s_waitcnt lgkmcnt(3)
	v_cvt_pk_bf16_f32 v2, v2, v3
	s_waitcnt lgkmcnt(2)
	v_cvt_pk_bf16_f32 v3, v4, v5
	s_waitcnt lgkmcnt(1)
	v_cvt_pk_bf16_f32 v4, v8, v9
	s_waitcnt lgkmcnt(0)
	v_cvt_pk_bf16_f32 v5, v10, v11
	global_store_dwordx4 v[12:13], v[2:5], off
	s_waitcnt lgkmcnt(0)
	s_barrier
	s_cbranch_scc0 .LBB0_33

; __device__ __forceinline__ void cvt_tile(const float* __restrict__ src, long ld, int k0, int c0, bf16_t* __restrict__ dst,
;                                          long ldd, int j0, int mode) {
;     ...
;   const int r = tid >> 4, c4 = (tid & 15) * 4;
; #pragma unroll
;   for (int i = 0; i < 2; ++i) {
;     const int row = r + 32 * i;
;     f32x4 v = {0.f, 0.f, 0.f, 0.f};
;     if (mode == 0) v = *(const f32x4*)(src + (long)(k0 + row) * ld + c0 + c4);
;     else {
;       if (c4 < 32) v = *(const f32x4*)(src + (long)(k0 + row) * ld + 9216 + c4);
;       else if (c4 < 48) v = *(const f32x4*)(src + (long)(k0 + row) * ld + 19488 + (c4 - 32));
;     }
;     T[row * 65 + c4 + 0] = v[0];
;     T[row * 65 + c4 + 1] = v[1];
;     T[row * 65 + c4 + 2] = v[2];
;     T[row * 65 + c4 + 3] = v[3];
;   }
;   __syncthreads();
;   const int n = tid >> 3, kk = (tid & 7) * 8;
;   u32x4 o;
;   o.x = pack2(T[(kk + 0) * 65 + n], T[(kk + 1) * 65 + n]);
;   o.y = pack2(T[(kk + 2) * 65 + n], T[(kk + 3) * 65 + n]);
;   o.z = pack2(T[(kk + 4) * 65 + n], T[(kk + 5) * 65 + n]);
;   o.w = pack2(T[(kk + 6) * 65 + n], T[(kk + 7) * 65 + n]);
;   *(u32x4*)(dst + (long)(j0 + n) * ldd + k0 + kk) = o;
;   __syncthreads();
; __device__ void phase_convert(const Params& p) {
;     ...
;     for (int it = bid; it < 4 * 8 * 8; it += G) {
;       const int g = it >> 6, jt = (it >> 3) & 7, kt = it & 7;
;       cvt_tile(p.w_pool + ((size_t)l * 4 + g) * 512 * 512, 512, kt * 64, jt * 64,
;                (bf16_t*)(ws_of(p) + OFF_WPT + l * WPT_L) + (size_t)g * 512 * 512, 512, jt * 64, 0);
;     }
.LBB0_36:
	s_ashr_i32 s22, s20, 6
	s_ashr_i32 s23, s22, 31
	s_lshl_b64 s[26:27], s[22:23], 20
	s_mov_b64 s[24:25], s[50:51]
	s_add_u32 s16, s4, s26
	s_addc_u32 s21, s5, s27
	s_and_b32 s26, s18, 0x1c0
	s_and_b32 s27, s19, 0x1c0
	s_add_u32 s24, s24, s0
	v_mov_b32_e32 v1, v164
	s_addc_u32 s25, s25, s1
	s_lshl_b64 s[22:23], s[22:23], 19
	s_add_u32 s22, s24, s22
	v_ashrrev_i32_e32 v12, 4, v1
	v_lshlrev_b32_e32 v2, 4, v1
	v_and_b32_e32 v6, 0xf0, v2
	v_add_u32_e32 v2, s26, v12
	s_addc_u32 s23, s25, s23
	s_lshl_b32 s24, s27, 2
	v_add_u32_e32 v4, 32, v2
	s_add_u32 s24, s16, s24
	v_ashrrev_i32_e32 v3, 31, v2
	v_ashrrev_i32_e32 v5, 31, v4
	s_addc_u32 s25, s21, 0
	v_lshlrev_b64 v[2:3], 11, v[2:3]
	v_lshlrev_b64 v[4:5], 11, v[4:5]
	v_lshl_add_u64 v[8:9], s[24:25], 0, v[6:7]
	v_lshl_add_u64 v[2:3], v[8:9], 0, v[2:3]
	v_lshl_add_u64 v[8:9], v[8:9], 0, v[4:5]
	global_load_dwordx4 v[2:5], v[2:3], off
	s_nop 0
	global_load_dwordx4 v[8:11], v[8:9], off
	v_ashrrev_i32_e32 v13, 3, v1
	v_lshlrev_b32_e32 v1, 3, v1
	v_mul_lo_u32 v12, v12, s34
	v_and_b32_e32 v1, 56, v1
	v_add3_u32 v15, 0, v6, v12
	v_add_u32_e32 v12, s27, v13
	v_lshlrev_b32_e32 v14, 2, v13
	v_mul_u32_u24_e32 v6, 0x104, v1
	v_ashrrev_i32_e32 v13, 31, v12
	v_add3_u32 v14, 0, v6, v14
	v_lshlrev_b64 v[12:13], 10, v[12:13]
	v_add_u32_e32 v16, 0x2080, v15
	v_add_u32_e32 v17, 0x2088, v15
	v_add_u32_e32 v18, 0x400, v14
	v_lshl_add_u64 v[12:13], s[22:23], 0, v[12:13]
	s_lshl_b32 s16, s26, 1
	v_lshl_add_u64 v[12:13], v[12:13], 0, s[16:17]
	v_lshlrev_b32_e32 v6, 1, v1
	v_lshl_add_u64 v[12:13], v[12:13], 0, v[6:7]
	s_add_i32 s20, s20, s76
	s_add_i32 s19, s19, s30
	s_add_i32 s18, s18, s65
	v_add_co_u32_e32 v12, vcc, 0x10880000, v12
	s_cmpk_gt_i32 s20, 0xff
	s_nop 0
	v_addc_co_u32_e32 v13, vcc, 0, v13, vcc
	s_waitcnt vmcnt(0)
	ds_write2_b32 v15, v2, v3 offset1:1
	ds_write2_b32 v15, v4, v5 offset0:2 offset1:3
	ds_write2_b32 v16, v8, v9 offset1:1
	ds_write2_b32 v17, v10, v11 offset1:1
	s_waitcnt lgkmcnt(0)
	s_barrier
	ds_read2_b32 v[2:3], v14 offset1:65
	ds_read2_b32 v[4:5], v14 offset0:130 offset1:195
	ds_read2_b32 v[8:9], v18 offset0:4 offset1:69
	ds_read2_b32 v[10:11], v18 offset0:134 offset1:199
	s_waitcnt lgkmcnt(3)
	v_cvt_pk_bf16_f32 v2, v2, v3
	s_waitcnt lgkmcnt(2)
	v_cvt_pk_bf16_f32 v3, v4, v5
	s_waitcnt lgkmcnt(1)
	v_cvt_pk_bf16_f32 v4, v8, v9
	s_waitcnt lgkmcnt(0)
	v_cvt_pk_bf16_f32 v5, v10, v11
	global_store_dwordx4 v[12:13], v[2:5], off
	s_waitcnt lgkmcnt(0)
	s_barrier
	s_cbranch_scc0 .LBB0_36
	s_branch .LBB0_8

; __device__ __forceinline__ unsigned xb_ld(unsigned* p) { return __hip_atomic_load(p, __ATOMIC_RELAXED, __HIP_MEMORY_SCOPE_AGENT); }
; __device__ __forceinline__ void xcd_barrier_complete(unsigned* bar, unsigned x, unsigned& nloc, unsigned& nx) {
;   const unsigned G = gridDim.x * gridDim.y * gridDim.z;
;   unsigned sum, cnt, mine, sp = 0u;
;   for (;;) {
;     sum = 0u; cnt = 0u; mine = 0u;
; #pragma unroll
;     for (unsigned j = 0; j < 16; ++j) { const unsigned c = xb_ld(&bar[XB_XCNT(j)]); sum += c; cnt += (c > 0u) ? 1u : 0u; mine = (j == x) ? c : mine; }
;     if (sum == G) break;
;     __builtin_amdgcn_s_sleep(1);
;     if ((++sp & 255u) == 0u) { if (xb_ld(&bar[XB_TMO])) break; if (sp > XB_SPIN_CAP) { atomicAdd(&bar[XB_TMO], 1u); break; } }
;   }
.LBB0_54:
	global_load_dword v47, v[0:1], off sc1
	global_load_dword v32, v[2:3], off sc1
	global_load_dword v33, v[4:5], off sc1
	global_load_dword v34, v[6:7], off sc1
	global_load_dword v35, v[8:9], off sc1
	global_load_dword v36, v[10:11], off sc1
	global_load_dword v37, v[12:13], off sc1
	global_load_dword v38, v[14:15], off sc1
	global_load_dword v39, v[16:17], off sc1
	global_load_dword v40, v[18:19], off sc1
	global_load_dword v41, v[20:21], off sc1
	global_load_dword v42, v[22:23], off sc1
	global_load_dword v43, v[24:25], off sc1
	global_load_dword v44, v[26:27], off sc1
	global_load_dword v45, v[28:29], off sc1
	global_load_dword v46, v[30:31], off sc1
	s_or_b64 s[12:13], s[12:13], exec
	s_or_b64 s[10:11], s[10:11], exec
	s_waitcnt vmcnt(0) lgkmcnt(0)
	v_add_u32_e32 v48, v32, v47
	v_add_u32_e32 v48, v48, v33
	v_add_u32_e32 v48, v48, v34
	v_add_u32_e32 v48, v48, v35
	v_add_u32_e32 v48, v48, v36
	v_add_u32_e32 v48, v48, v37
	v_add_u32_e32 v48, v48, v38
	v_add_u32_e32 v48, v48, v39
	v_add_u32_e32 v48, v48, v40
	v_add_u32_e32 v48, v48, v41
	v_add_u32_e32 v48, v48, v42
	v_add_u32_e32 v48, v48, v43
	v_add_u32_e32 v48, v48, v44
	v_add_u32_e32 v48, v48, v45
	v_add_u32_e32 v48, v48, v46
	v_cmp_ne_u32_e32 vcc, s24, v48
	s_and_saveexec_b64 s[14:15], vcc
	s_cbranch_execz .LBB0_53
	s_and_b32 s18, s25, 0xff
	s_mov_b64 s[16:17], -1
	s_cmp_eq_u32 s18, 0
	s_mov_b64 s[20:21], -1
	s_mov_b64 s[18:19], -1
	s_sleep 1
	s_cbranch_scc1 .LBB0_57
	s_and_saveexec_b64 s[22:23], s[20:21]
	s_cbranch_execz .LBB0_52
	s_branch .LBB0_60
.LBB0_57:
	v_mov_b64_e32 v[48:49], s[0:1]
	global_load_dword v48, v[48:49], off sc1
	s_mov_b64 s[20:21], 0
	s_waitcnt vmcnt(0) lgkmcnt(0)
	v_cmp_eq_u32_e32 vcc, 0, v48
	s_and_saveexec_b64 s[22:23], vcc
	s_cmp_lt_u32 s25, 0x100001
	s_cselect_b64 s[20:21], -1, 0
	s_xor_b64 s[18:19], exec, -1
	s_and_b64 s[20:21], s[20:21], exec
	s_or_b64 exec, exec, s[22:23]
	s_and_saveexec_b64 s[22:23], s[20:21]
	s_cbranch_execz .LBB0_52

; __device__ __forceinline__ unsigned xb_ld(unsigned* p) { return __hip_atomic_load(p, __ATOMIC_RELAXED, __HIP_MEMORY_SCOPE_AGENT); }
; __device__ __forceinline__ void xcd_barrier_complete(unsigned* bar, unsigned x, unsigned& nloc, unsigned& nx) {
;     ...
;     if ((++sp & 255u) == 0u) { if (xb_ld(&bar[XB_TMO])) break; if (sp > XB_SPIN_CAP) { atomicAdd(&bar[XB_TMO], 1u); break; } }
.LBB0_61:
	s_or_b64 exec, exec, s[6:7]
	s_xor_b64 s[6:7], s[8:9], -1
	s_and_saveexec_b64 s[8:9], s[6:7]
	s_xor_b64 s[6:7], exec, s[8:9]
	s_cbranch_execz .LBB0_63
	v_mov_b32_e32 v2, 1
	v_mov_b64_e32 v[0:1], s[0:1]
	global_atomic_add v[0:1], v2, off

; __device__ __forceinline__ unsigned xb_ld(unsigned* p) { return __hip_atomic_load(p, __ATOMIC_RELAXED, __HIP_MEMORY_SCOPE_AGENT); }
; __device__ __forceinline__ unsigned xb_add(unsigned* p, unsigned v) { return __hip_atomic_fetch_add(p, v, __ATOMIC_RELAXED, __HIP_MEMORY_SCOPE_AGENT); }
; #define XB_SPIN(cond, bar) do { unsigned _sp = 0; while (cond) { __builtin_amdgcn_s_sleep(1); \
;     if ((++_sp & 255u) == 0u) { if (xb_ld(&(bar)[XB_TMO])) break; if (_sp > XB_SPIN_CAP) { atomicAdd(&(bar)[XB_TMO], 1u); break; } } } } while (0)
; __device__ __forceinline__ void xcd_barrier(const XcdBarrier& b) {
;     ...
;     unsigned nloc = b.st[0], nx = b.st[1];
;     if (nloc == 0u) { xcd_barrier_complete(bar, bx, nloc, nx); b.st[0] = nloc; b.st[1] = nx; }
;     const unsigned old = xb_add(&bar[XB_XSUB(bx)], 1u);
;     const unsigned gen = old / nloc;
;     if (old + 1u == (gen + 1u) * nloc) {
;     ...
;       XB_SPIN(xb_ld(&bar[XB_XGEN(bx)]) == gen, bar);
.LBB0_64:
	s_lshl_b32 s26, s41, 6
	s_add_i32 s6, s26, 0x500
	s_mov_b32 s7, 0
	s_lshl_b64 s[0:1], s[6:7], 2
	v_readlane_b32 s6, v245, 20
	s_add_u32 s0, s6, s0
	v_readlane_b32 s6, v245, 21
	s_addc_u32 s1, s6, s1
	v_mov_b32_e32 v1, 1
	v_mov_b64_e32 v[4:5], s[0:1]
	global_atomic_add v1, v[4:5], v1, off sc0
	v_cvt_f32_u32_e32 v3, v2
	v_sub_u32_e32 v4, 0, v2
	v_rcp_iflag_f32_e32 v3, v3
	s_nop 0
	v_mul_f32_e32 v3, 0x4f7ffffe, v3
	v_cvt_u32_f32_e32 v3, v3
	v_mul_lo_u32 v4, v4, v3
	v_mul_hi_u32 v4, v3, v4
	v_add_u32_e32 v3, v3, v4
	s_waitcnt vmcnt(0) lgkmcnt(0)
	v_mul_hi_u32 v3, v1, v3
	v_mul_lo_u32 v5, v3, v2
	v_add_u32_e32 v4, 1, v1
	v_sub_u32_e32 v1, v1, v5
	v_add_u32_e32 v6, 1, v3
	v_cmp_ge_u32_e32 vcc, v1, v2
	v_sub_u32_e32 v5, v1, v2
	s_nop 0
	v_cndmask_b32_e32 v3, v3, v6, vcc
	v_cndmask_b32_e32 v1, v1, v5, vcc
	v_add_u32_e32 v5, 1, v3
	v_cmp_ge_u32_e32 vcc, v1, v2
	s_nop 1
	v_cndmask_b32_e32 v1, v3, v5, vcc
	v_mad_u64_u32 v[2:3], s[0:1], v2, v1, v[2:3]
	v_cmp_ne_u32_e32 vcc, v4, v2
	s_and_saveexec_b64 s[0:1], vcc
	s_xor_b64 s[0:1], exec, s[0:1]
	s_cbranch_execz .LBB0_77
	s_add_i32 s6, s26, 0x900
	s_lshl_b64 s[6:7], s[6:7], 2
	v_readlane_b32 s8, v245, 20
	s_add_u32 s8, s8, s6
	v_readlane_b32 s6, v245, 21
	s_addc_u32 s9, s6, s7
	v_mov_b64_e32 v[2:3], s[8:9]
	global_load_dword v0, v[2:3], off sc1
	s_waitcnt vmcnt(0) lgkmcnt(0)
	v_cmp_eq_u32_e32 vcc, v0, v1
	s_and_saveexec_b64 s[6:7], vcc
	s_cbranch_execz .LBB0_76
	s_add_u32 s10, s2, 0x5f080200
	s_addc_u32 s11, s3, 0
	s_mov_b32 s27, 1
	s_mov_b64 s[12:13], 0
	s_branch .LBB0_68

; __device__ __forceinline__ unsigned xb_ld(unsigned* p) { return __hip_atomic_load(p, __ATOMIC_RELAXED, __HIP_MEMORY_SCOPE_AGENT); }
; #define XB_SPIN(cond, bar) do { unsigned _sp = 0; while (cond) { __builtin_amdgcn_s_sleep(1); \
;     if ((++_sp & 255u) == 0u) { if (xb_ld(&(bar)[XB_TMO])) break; if (_sp > XB_SPIN_CAP) { atomicAdd(&(bar)[XB_TMO], 1u); break; } } } } while (0)
; __device__ __forceinline__ void xcd_barrier(const XcdBarrier& b) {
;     ...
;       XB_SPIN(xb_ld(&bar[XB_XGEN(bx)]) == gen, bar);
.LBB0_68:
	s_and_b32 s20, s27, 0xff
	s_mov_b64 s[18:19], -1
	s_cmp_lg_u32 s20, 0
	s_mov_b64 s[20:21], -1
	s_sleep 1
	s_cbranch_scc1 .LBB0_72
	v_mov_b64_e32 v[2:3], s[10:11]
	global_load_dword v0, v[2:3], off sc1
	s_mov_b64 s[20:21], 0
	s_mov_b64 s[22:23], -1
	s_waitcnt vmcnt(0) lgkmcnt(0)
	v_cmp_eq_u32_e32 vcc, 0, v0
	s_and_saveexec_b64 s[24:25], vcc
	s_cmp_lt_u32 s27, 0x100001
	s_cselect_b64 s[20:21], -1, 0
	s_xor_b64 s[22:23], exec, -1
	s_and_b64 s[20:21], s[20:21], exec
	s_or_b64 exec, exec, s[24:25]
.LBB0_72:
	s_andn2_b64 s[16:17], s[16:17], exec
	s_and_b64 s[22:23], s[22:23], exec
	s_or_b64 s[16:17], s[16:17], s[22:23]
	s_and_saveexec_b64 s[22:23], s[20:21]
	s_cbranch_execz .LBB0_67
	v_mov_b64_e32 v[2:3], s[8:9]
	global_load_dword v0, v[2:3], off sc1
	s_add_i32 s27, s27, 1
	s_or_b64 s[16:17], s[16:17], exec
	s_waitcnt vmcnt(0) lgkmcnt(0)
	v_cmp_ne_u32_e32 vcc, v0, v1
	s_orn2_b64 s[18:19], vcc, exec
	s_branch .LBB0_67
.LBB0_74:
	s_or_b64 exec, exec, s[12:13]
	s_xor_b64 s[8:9], s[14:15], -1
	s_and_saveexec_b64 s[12:13], s[8:9]
	s_xor_b64 s[12:13], exec, s[12:13]
	s_cbranch_execz .LBB0_76
	v_mov_b32_e32 v2, 1
	v_mov_b64_e32 v[0:1], s[10:11]
	global_atomic_add v[0:1], v2, off

; __device__ __forceinline__ unsigned xb_ld(unsigned* p) { return __hip_atomic_load(p, __ATOMIC_RELAXED, __HIP_MEMORY_SCOPE_AGENT); }
; __device__ __forceinline__ unsigned xb_add(unsigned* p, unsigned v) { return __hip_atomic_fetch_add(p, v, __ATOMIC_RELAXED, __HIP_MEMORY_SCOPE_AGENT); }
; #define XB_SPIN(cond, bar) do { unsigned _sp = 0; while (cond) { __builtin_amdgcn_s_sleep(1); \
;     if ((++_sp & 255u) == 0u) { if (xb_ld(&(bar)[XB_TMO])) break; if (_sp > XB_SPIN_CAP) { atomicAdd(&(bar)[XB_TMO], 1u); break; } } } } while (0)
; __device__ __forceinline__ void xcd_barrier(const XcdBarrier& b) {
;     ...
;     if (old + 1u == (gen + 1u) * nloc) {
;       __builtin_amdgcn_fence(__ATOMIC_RELEASE, "agent");
;       asm volatile("s_waitcnt vmcnt(0)" ::: "memory");
;       const unsigned og = xb_add(&bar[XB_TOP], 1u);
;       const unsigned tg = og / nx;
;       if (og + 1u == (tg + 1u) * nx) xb_add(&bar[XB_TOPGEN], 1u);
;       else XB_SPIN(xb_ld(&bar[XB_TOPGEN]) == tg, bar);
.LBB0_77:
	s_andn2_saveexec_b64 s[0:1], s[0:1]
	s_cbranch_execz .LBB0_93
	v_mov_b32_e32 v1, s2
	v_add_co_u32_e32 v2, vcc, 0x5f083000, v1
	v_mov_b32_e32 v1, s3
	buffer_wbl2 sc1
	s_waitcnt vmcnt(0)
	v_addc_co_u32_e32 v3, vcc, 0, v1, vcc
	v_mov_b32_e32 v1, 1
	global_atomic_add v1, v[2:3], v1, off offset:1024 sc0
	v_cvt_f32_u32_e32 v2, v0
	v_sub_u32_e32 v3, 0, v0
	s_add_u32 s0, s2, 0x5f083500
	s_addc_u32 s1, s3, 0
	v_rcp_iflag_f32_e32 v2, v2
	s_mov_b64 s[8:9], -1
	v_mul_f32_e32 v2, 0x4f7ffffe, v2
	v_cvt_u32_f32_e32 v2, v2
	v_mul_lo_u32 v3, v3, v2
	v_mul_hi_u32 v3, v2, v3
	v_add_u32_e32 v2, v2, v3
	s_waitcnt vmcnt(0) lgkmcnt(0)
	v_mul_hi_u32 v2, v1, v2
	v_mul_lo_u32 v4, v2, v0
	v_add_u32_e32 v3, 1, v1
	v_sub_u32_e32 v1, v1, v4
	v_add_u32_e32 v5, 1, v2
	v_cmp_ge_u32_e32 vcc, v1, v0
	v_sub_u32_e32 v4, v1, v0
	s_nop 0
	v_cndmask_b32_e32 v2, v2, v5, vcc
	v_cndmask_b32_e32 v1, v1, v4, vcc
	v_add_u32_e32 v4, 1, v2
	v_cmp_ge_u32_e32 vcc, v1, v0
	s_nop 1
	v_cndmask_b32_e32 v2, v2, v4, vcc
	v_mad_u64_u32 v[0:1], s[6:7], v0, v2, v[0:1]
	v_cmp_ne_u32_e32 vcc, v3, v0
	v_mov_b64_e32 v[0:1], s[0:1]
	s_and_saveexec_b64 s[6:7], vcc
	s_cbranch_execz .LBB0_90
	v_mov_b64_e32 v[0:1], s[0:1]
	global_load_dword v0, v[0:1], off sc1
	s_mov_b64 s[12:13], 0
	s_waitcnt vmcnt(0) lgkmcnt(0)
	v_cmp_eq_u32_e32 vcc, v0, v2
	s_and_saveexec_b64 s[10:11], vcc
	s_cbranch_execz .LBB0_89
	s_add_u32 s8, s2, 0x5f080200
	s_addc_u32 s9, s3, 0
	s_mov_b32 s24, 1
	s_branch .LBB0_82

; __device__ __forceinline__ unsigned xb_ld(unsigned* p) { return __hip_atomic_load(p, __ATOMIC_RELAXED, __HIP_MEMORY_SCOPE_AGENT); }
; #define XB_SPIN(cond, bar) do { unsigned _sp = 0; while (cond) { __builtin_amdgcn_s_sleep(1); \
;     if ((++_sp & 255u) == 0u) { if (xb_ld(&(bar)[XB_TMO])) break; if (_sp > XB_SPIN_CAP) { atomicAdd(&(bar)[XB_TMO], 1u); break; } } } } while (0)
; __device__ __forceinline__ void xcd_barrier(const XcdBarrier& b) {
;     ...
;       else XB_SPIN(xb_ld(&bar[XB_TOPGEN]) == tg, bar);
.LBB0_84:
	v_mov_b64_e32 v[0:1], s[8:9]
	global_load_dword v0, v[0:1], off sc1
	s_mov_b64 s[18:19], 0
	s_mov_b64 s[16:17], -1
	s_waitcnt vmcnt(0) lgkmcnt(0)
	v_cmp_eq_u32_e32 vcc, 0, v0
	s_and_saveexec_b64 s[20:21], vcc
	s_cmp_lt_u32 s24, 0x100001
	s_cselect_b64 s[18:19], -1, 0
	s_xor_b64 s[16:17], exec, -1
	s_and_b64 s[18:19], s[18:19], exec
	s_or_b64 exec, exec, s[20:21]
	s_mov_b64 s[20:21], -1
	s_and_saveexec_b64 s[22:23], s[18:19]
	s_cbranch_execz .LBB0_81
.LBB0_87:
	v_mov_b64_e32 v[0:1], s[0:1]
	global_load_dword v0, v[0:1], off sc1
	s_add_i32 s24, s24, 1
	s_or_b64 s[16:17], s[16:17], exec
	s_waitcnt vmcnt(0) lgkmcnt(0)
	v_cmp_ne_u32_e32 vcc, v0, v2
	s_orn2_b64 s[20:21], vcc, exec
	s_branch .LBB0_81

; __device__ __forceinline__ unsigned xb_ld(unsigned* p) { return __hip_atomic_load(p, __ATOMIC_RELAXED, __HIP_MEMORY_SCOPE_AGENT); }
; __device__ __forceinline__ unsigned xb_add(unsigned* p, unsigned v) { return __hip_atomic_fetch_add(p, v, __ATOMIC_RELAXED, __HIP_MEMORY_SCOPE_AGENT); }
; #define XB_SPIN(cond, bar) do { unsigned _sp = 0; while (cond) { __builtin_amdgcn_s_sleep(1); \
;     if ((++_sp & 255u) == 0u) { if (xb_ld(&(bar)[XB_TMO])) break; if (_sp > XB_SPIN_CAP) { atomicAdd(&(bar)[XB_TMO], 1u); break; } } } } while (0)
; __device__ __forceinline__ void xcd_barrier(const XcdBarrier& b) {
;     ...
;       if (og + 1u == (tg + 1u) * nx) xb_add(&bar[XB_TOPGEN], 1u);
;       else XB_SPIN(xb_ld(&bar[XB_TOPGEN]) == tg, bar);
;       __builtin_amdgcn_fence(__ATOMIC_ACQUIRE, "agent");
;       xb_add(&bar[XB_XGEN(bx)], 1u);
;       asm volatile("s_waitcnt vmcnt(0)" ::: "memory");
.LBB0_90:
	s_or_b64 exec, exec, s[6:7]
	s_and_saveexec_b64 s[0:1], s[8:9]
	s_cbranch_execz .LBB0_92
	v_mov_b32_e32 v2, 1
	global_atomic_add v[0:1], v2, off
.LBB0_92:
	s_or_b64 exec, exec, s[0:1]
	s_add_i32 s0, s26, 0x900
	s_mov_b32 s1, 0
	s_lshl_b64 s[0:1], s[0:1], 2
	v_readlane_b32 s6, v245, 20
	s_add_u32 s0, s6, s0
	v_readlane_b32 s6, v245, 21
	s_addc_u32 s1, s6, s1
	v_mov_b32_e32 v2, 1
	v_mov_b64_e32 v[0:1], s[0:1]
	s_waitcnt vmcnt(0) lgkmcnt(0)
	buffer_inv sc1
	global_atomic_add v[0:1], v2, off
	s_waitcnt vmcnt(0)

; __device__ __forceinline__ unsigned xb_add(unsigned* p, unsigned v) { return __hip_atomic_fetch_add(p, v, __ATOMIC_RELAXED, __HIP_MEMORY_SCOPE_AGENT); }
; __device__ __forceinline__ void xcd_barrier(const XcdBarrier& b) {
;     ...
;       __builtin_amdgcn_fence(__ATOMIC_ACQUIRE, "agent");
;       xb_add(&bar[XB_XGEN(bx)], 1u);
;       asm volatile("s_waitcnt vmcnt(0)" ::: "memory");
.LBB0_94:
	s_or_b64 exec, exec, s[0:1]
	s_add_i32 s72, s22, 0x900
	s_lshl_b64 s[0:1], s[72:73], 2
	v_readlane_b32 s4, v245, 20
	s_add_u32 s0, s4, s0
	v_readlane_b32 s4, v245, 21
	s_addc_u32 s1, s4, s1
	v_mov_b64_e32 v[0:1], s[0:1]
	s_waitcnt vmcnt(0) lgkmcnt(0)
	buffer_inv sc1
	global_atomic_add v[0:1], v165, off
	s_waitcnt vmcnt(0)

; __device__ void phase_proj(const Params& p, int layer) {
;     ...
;     const bf16_t* ap = xb + (size_t)(r0 + fr) * DM + kb + fq * 8;
;     const bf16_t* bp = w1t + (size_t)(NPROJ + fr) * DM + kb + fq * 8;
; #pragma unroll 2
;     for (int ks = 0; ks < 8; ++ks) {
;       bf16x8 af[4], bf[4];
; #pragma unroll
;       for (int i = 0; i < 4; ++i) {
;         af[i] = *(const bf16x8*)(ap + (size_t)i * 16 * DM + ks * 32);
;         bf[i] = *(const bf16x8*)(bp + (size_t)i * 16 * DM + ks * 32);
;       }
; #pragma unroll
;       for (int mi = 0; mi < 4; ++mi)
; #pragma unroll
;         for (int ni = 0; ni < 4; ++ni) acc[mi][ni] = mfma16(bf[ni], af[mi], acc[mi][ni]);
;     }
.LBB0_100:
	v_lshl_add_u64 v[110:111], v[74:75], 0, s[6:7]
	s_mov_b32 s9, 0x43080000
	v_add_co_u32_e32 v118, vcc, s9, v110
	v_lshl_add_u64 v[114:115], v[68:69], 0, s[6:7]
	s_nop 0
	v_addc_co_u32_e32 v119, vcc, 0, v111, vcc
	s_mov_b32 s9, 0x6400000
	v_add_co_u32_e32 v120, vcc, s9, v114
	s_mov_b32 s9, 0x43090000
	s_nop 0
	v_addc_co_u32_e32 v121, vcc, 0, v115, vcc
	v_add_co_u32_e32 v122, vcc, s9, v110
	s_mov_b32 s9, 0x6410000
	s_nop 0
	v_addc_co_u32_e32 v123, vcc, 0, v111, vcc
	v_add_co_u32_e32 v124, vcc, s9, v114
	s_mov_b32 s9, 0x430a0000
	s_nop 0
	v_addc_co_u32_e32 v125, vcc, 0, v115, vcc
	v_add_co_u32_e32 v126, vcc, s9, v110
	s_mov_b32 s9, 0x6420000
	s_nop 0
	v_addc_co_u32_e32 v127, vcc, 0, v111, vcc
	v_add_co_u32_e32 v128, vcc, s9, v114
	s_mov_b32 s9, 0x430b0000
	s_nop 0
	v_addc_co_u32_e32 v129, vcc, 0, v115, vcc
	v_add_co_u32_e32 v130, vcc, s9, v110
	s_mov_b32 s9, 0x6430000
	s_nop 0
	v_addc_co_u32_e32 v131, vcc, 0, v111, vcc
	v_add_co_u32_e32 v132, vcc, s9, v114
	global_load_dwordx4 v[90:93], v[120:121], off
	s_nop 0
	v_addc_co_u32_e32 v133, vcc, 0, v115, vcc
	global_load_dwordx4 v[98:101], v[124:125], off
	global_load_dwordx4 v[106:109], v[128:129], off
	global_load_dwordx4 v[114:117], v[132:133], off
	global_load_dwordx4 v[86:89], v[118:119], off
	global_load_dwordx4 v[94:97], v[122:123], off
	global_load_dwordx4 v[102:105], v[126:127], off
	global_load_dwordx4 v[110:113], v[130:131], off
	s_add_u32 s6, s6, 0x80
	s_addc_u32 s7, s7, 0
	s_cmpk_lg_i32 s6, 0x200
	s_waitcnt vmcnt(0) lgkmcnt(0)
	v_mfma_f32_16x16x32_bf16 v[32:35], v[90:93], v[86:89], v[32:35]
	v_mfma_f32_16x16x32_bf16 v[28:31], v[98:101], v[86:89], v[28:31]
	v_mfma_f32_16x16x32_bf16 v[24:27], v[106:109], v[86:89], v[24:27]
	v_mfma_f32_16x16x32_bf16 v[20:23], v[114:117], v[86:89], v[20:23]
	v_mfma_f32_16x16x32_bf16 v[16:19], v[90:93], v[94:97], v[16:19]
	v_mfma_f32_16x16x32_bf16 v[12:15], v[98:101], v[94:97], v[12:15]
	v_mfma_f32_16x16x32_bf16 v[8:11], v[106:109], v[94:97], v[8:11]
	v_mfma_f32_16x16x32_bf16 v[4:7], v[114:117], v[94:97], v[4:7]
	v_mfma_f32_16x16x32_bf16 v[36:39], v[90:93], v[102:105], v[36:39]
	v_mfma_f32_16x16x32_bf16 v[40:43], v[98:101], v[102:105], v[40:43]
	v_mfma_f32_16x16x32_bf16 v[44:47], v[106:109], v[102:105], v[44:47]
	v_mfma_f32_16x16x32_bf16 v[48:51], v[114:117], v[102:105], v[48:51]
	v_mfma_f32_16x16x32_bf16 v[52:55], v[90:93], v[110:113], v[52:55]
	v_mfma_f32_16x16x32_bf16 v[56:59], v[98:101], v[110:113], v[56:59]
	v_mfma_f32_16x16x32_bf16 v[60:63], v[106:109], v[110:113], v[60:63]
	v_mfma_f32_16x16x32_bf16 v[64:67], v[114:117], v[110:113], v[64:67]
	global_load_dwordx4 v[86:89], v[118:119], off offset:64
	global_load_dwordx4 v[90:93], v[120:121], off offset:64
	global_load_dwordx4 v[94:97], v[122:123], off offset:64
	global_load_dwordx4 v[98:101], v[124:125], off offset:64
	global_load_dwordx4 v[102:105], v[126:127], off offset:64
	global_load_dwordx4 v[106:109], v[128:129], off offset:64
	global_load_dwordx4 v[110:113], v[130:131], off offset:64
	global_load_dwordx4 v[114:117], v[132:133], off offset:64
	s_waitcnt vmcnt(0) lgkmcnt(0)
	v_mfma_f32_16x16x32_bf16 v[32:35], v[90:93], v[86:89], v[32:35]
	v_mfma_f32_16x16x32_bf16 v[28:31], v[98:101], v[86:89], v[28:31]
	v_mfma_f32_16x16x32_bf16 v[24:27], v[106:109], v[86:89], v[24:27]
	v_mfma_f32_16x16x32_bf16 v[20:23], v[114:117], v[86:89], v[20:23]
	v_mfma_f32_16x16x32_bf16 v[16:19], v[90:93], v[94:97], v[16:19]
	v_mfma_f32_16x16x32_bf16 v[12:15], v[98:101], v[94:97], v[12:15]
	v_mfma_f32_16x16x32_bf16 v[8:11], v[106:109], v[94:97], v[8:11]
	v_mfma_f32_16x16x32_bf16 v[4:7], v[114:117], v[94:97], v[4:7]
	v_mfma_f32_16x16x32_bf16 v[36:39], v[90:93], v[102:105], v[36:39]
	v_mfma_f32_16x16x32_bf16 v[40:43], v[98:101], v[102:105], v[40:43]
	v_mfma_f32_16x16x32_bf16 v[44:47], v[106:109], v[102:105], v[44:47]
	v_mfma_f32_16x16x32_bf16 v[48:51], v[114:117], v[102:105], v[48:51]
	v_mfma_f32_16x16x32_bf16 v[52:55], v[90:93], v[110:113], v[52:55]
	v_mfma_f32_16x16x32_bf16 v[56:59], v[98:101], v[110:113], v[56:59]
	v_mfma_f32_16x16x32_bf16 v[60:63], v[106:109], v[110:113], v[60:63]
	v_mfma_f32_16x16x32_bf16 v[64:67], v[114:117], v[110:113], v[64:67]
	s_cbranch_scc1 .LBB0_100
; __device__ void phase_proj(const Params& p, int layer) {
;     ...
;     float* part = (float*)smem + w * 4096;
; #pragma unroll
;     for (int mi = 0; mi < 4; ++mi)
; #pragma unroll
;       for (int ni = 0; ni < 4; ++ni) *(f32x4*)(part + (mi * 16 + fr) * 64 + ni * 16 + fq * 4) = acc[mi][ni];
;     __syncthreads();
;     {
;       const int row = tid >> 3, c8 = (tid & 7) * 8;
;       f32x4 s0 = {0.f, 0.f, 0.f, 0.f}, s1 = s0;
; #pragma unroll
;       for (int ww = 0; ww < 8; ++ww) {
;         const float* pp = (const float*)smem + ww * 4096 + row * 64 + c8;
;         s0 += *(const f32x4*)pp;
;         s1 += *(const f32x4*)(pp + 4);
;       }
;       *(f32x4*)(small + (size_t)(r0 + row) * NSMALL + c8) = s0;
;       *(f32x4*)(small + (size_t)(r0 + row) * NSMALL + c8 + 4) = s1;
;     }
;     __syncthreads();
	ds_write_b128 v2, v[32:35]
	ds_write_b128 v2, v[28:31] offset:64
	ds_write_b128 v2, v[24:27] offset:128
	ds_write_b128 v2, v[20:23] offset:192
	ds_write_b128 v2, v[16:19] offset:4096
	ds_write_b128 v2, v[12:15] offset:4160
	ds_write_b128 v2, v[8:11] offset:4224
	ds_write_b128 v2, v[4:7] offset:4288
	ds_write_b128 v2, v[36:39] offset:8192
	ds_write_b128 v2, v[40:43] offset:8256
	ds_write_b128 v2, v[44:47] offset:8320
	ds_write_b128 v2, v[48:51] offset:8384
	ds_write_b128 v2, v[52:55] offset:12288
	ds_write_b128 v2, v[56:59] offset:12352
	ds_write_b128 v2, v[60:63] offset:12416
	ds_write_b128 v2, v[64:67] offset:12480
	s_waitcnt lgkmcnt(0)
	s_barrier
	ds_read_b128 v[4:7], v77
	ds_read_b128 v[8:11], v77 offset:16
	ds_read_b128 v[12:15], v77 offset:16384
	v_add_u32_e32 v72, s65, v72
	s_waitcnt lgkmcnt(2)
	v_pk_add_f32 v[16:17], v[6:7], 0 op_sel_hi:[1,0]
	v_pk_add_f32 v[18:19], v[4:5], 0 op_sel_hi:[1,0]
	ds_read_b128 v[4:7], v77 offset:16400
	s_waitcnt lgkmcnt(2)
	v_pk_add_f32 v[20:21], v[10:11], 0 op_sel_hi:[1,0]
	v_pk_add_f32 v[22:23], v[8:9], 0 op_sel_hi:[1,0]
	s_waitcnt lgkmcnt(1)
	v_pk_add_f32 v[16:17], v[16:17], v[14:15]
	ds_read_b128 v[8:11], v77 offset:32768
	v_pk_add_f32 v[18:19], v[18:19], v[12:13]
	ds_read_b128 v[12:15], v77 offset:32784
	s_waitcnt lgkmcnt(2)
	v_pk_add_f32 v[20:21], v[20:21], v[6:7]
	v_pk_add_f32 v[22:23], v[22:23], v[4:5]
	ds_read_b128 v[4:7], v77 offset:49152
	s_waitcnt lgkmcnt(2)
	v_pk_add_f32 v[16:17], v[16:17], v[10:11]
	v_pk_add_f32 v[18:19], v[18:19], v[8:9]
	s_waitcnt lgkmcnt(1)
	v_pk_add_f32 v[20:21], v[20:21], v[14:15]
	ds_read_b128 v[8:11], v77 offset:49168
	v_pk_add_f32 v[22:23], v[22:23], v[12:13]
	ds_read_b128 v[12:15], v78
	s_waitcnt lgkmcnt(2)
	v_pk_add_f32 v[16:17], v[16:17], v[6:7]
	v_pk_add_f32 v[18:19], v[18:19], v[4:5]
	ds_read_b128 v[4:7], v79
	s_waitcnt lgkmcnt(2)
	v_pk_add_f32 v[20:21], v[20:21], v[10:11]
	v_pk_add_f32 v[22:23], v[22:23], v[8:9]
	s_waitcnt lgkmcnt(1)
	v_pk_add_f32 v[16:17], v[16:17], v[14:15]
	ds_read_b128 v[8:11], v80
	v_pk_add_f32 v[18:19], v[18:19], v[12:13]
	ds_read_b128 v[12:15], v81
	s_waitcnt lgkmcnt(2)
	v_pk_add_f32 v[20:21], v[20:21], v[6:7]
	v_pk_add_f32 v[22:23], v[22:23], v[4:5]
	ds_read_b128 v[4:7], v82
	s_waitcnt lgkmcnt(2)
	v_pk_add_f32 v[16:17], v[16:17], v[10:11]
	v_pk_add_f32 v[18:19], v[18:19], v[8:9]
	s_waitcnt lgkmcnt(1)
	v_pk_add_f32 v[20:21], v[20:21], v[14:15]
	v_pk_add_f32 v[22:23], v[22:23], v[12:13]
	ds_read_b128 v[8:11], v83
	ds_read_b128 v[12:15], v84
	s_waitcnt lgkmcnt(2)
	v_pk_add_f32 v[16:17], v[16:17], v[6:7]
	v_pk_add_f32 v[18:19], v[18:19], v[4:5]
	ds_read_b128 v[4:7], v85
	s_waitcnt lgkmcnt(2)
	v_pk_add_f32 v[22:23], v[22:23], v[8:9]
	s_waitcnt lgkmcnt(1)
	v_pk_add_f32 v[8:9], v[18:19], v[12:13]
	v_lshl_add_u32 v12, s8, 6, v76
	v_ashrrev_i32_e32 v13, 31, v12
	v_lshlrev_b64 v[12:13], 8, v[12:13]
	s_add_i32 s8, s8, s76
	v_pk_add_f32 v[20:21], v[20:21], v[10:11]
	v_pk_add_f32 v[10:11], v[16:17], v[14:15]
	v_lshl_add_u64 v[12:13], v[0:1], 0, v[12:13]
	s_cmpk_gt_i32 s8, 0xff
	s_waitcnt lgkmcnt(0)
	v_pk_add_f32 v[6:7], v[20:21], v[6:7]
	v_pk_add_f32 v[4:5], v[22:23], v[4:5]
	global_store_dwordx4 v[12:13], v[8:11], off
	global_store_dwordx4 v[12:13], v[4:7], off offset:16
	s_waitcnt lgkmcnt(0)
	s_barrier
	s_cbranch_scc0 .LBB0_99

; #define PG8_WAIT_V(n) asm volatile("s_waitcnt vmcnt(" #n ")" ::: "memory")
; #define PG8_WAIT_L(n) asm volatile("s_waitcnt lgkmcnt(" #n ")" ::: "memory")
; #define PG8_BAR __builtin_amdgcn_s_barrier()
; #define PG8_SCHED __builtin_amdgcn_sched_barrier(0)
; template <class Epi, class AddrA, class AddrB>
; __device__ __forceinline__ void gemm_phase(const Sched S, const int lda, const int ldb, const int K, const AddrA addrA,
;                                            const AddrB addrB, const Epi E) {
;     ...
;     for (int t = 0; t < nt; t += 2) {
;       const bool last = (t == nt - 2);
;       const char* a1 = cA + (size_t)(t + 1) * kstep;
;       const char* a2 = last ? nA : cA + (size_t)(t + 2) * kstep;
;       const char* b2 = last ? nB : cB + (size_t)(t + 2) * kstep;
;       const char* a3 = a2 + kstep;
;       const char* b3 = b2 + kstep;
;       PG8_LDB(B0, 0, 0); PG8_SCHED; PG8_LDA(At, 0, 0); PG8_STAGE(PG8_SA(1, 1), a1 + hstepA, voffA);
;       PG8_WAIT_L(8); PG8_BAR; PG8_WAIT_L(0); PG8_MMA(0, 0, At, B0); PG8_BAR; PG8_SCHED;
;       PG8_LDB(B1, 0, 1); PG8_STAGE(PG8_SB(0, 0), b2, voffB);
;       PG8_BAR; PG8_WAIT_L(0); PG8_MMA(0, 1, At, B1); PG8_BAR;
;       PG8_LDA(At, 0, 1); PG8_STAGE(PG8_SA(0, 0), a2, voffA);
;       PG8_BAR; PG8_WAIT_L(0); PG8_MMA(1, 0, At, B0); PG8_BAR; PG8_SCHED;
;       PG8_STAGE(PG8_SB(0, 1), b2 + hstepB, voffB);
;       PG8_WAIT_V(6); PG8_BAR; PG8_MMA(1, 1, At, B1); PG8_BAR;
.LBB0_109:
	s_add_u32 s14, s12, 0xfff80080
	s_addc_u32 s15, s13, -1
	s_add_i32 s40, 0, 0x10000
	v_add_u32_e32 v142, s40, v145
	ds_read_b128 v[148:151], v142
	ds_read_b128 v[152:155], v142 offset:1024
	ds_read_b128 v[156:159], v142 offset:2048
	ds_read_b128 v[160:163], v142 offset:3072
	s_cmp_eq_u32 s39, 28
	s_cselect_b32 s17, s1, s15
	s_cselect_b32 s16, s11, s14
	s_cselect_b32 s15, s3, s38
	s_cselect_b32 s14, s36, s37
	v_lshl_add_u64 v[142:143], s[12:13], 0, v[140:141]
	s_add_i32 m0, s24, 0xc000
	ds_read_b128 v[168:171], v146
	ds_read_b128 v[172:175], v146 offset:1024
	ds_read_b128 v[176:179], v146 offset:2048
	ds_read_b128 v[180:183], v146 offset:3072
	ds_read_b128 v[184:187], v146 offset:4096
	ds_read_b128 v[188:191], v146 offset:5120
	ds_read_b128 v[192:195], v146 offset:6144
	ds_read_b128 v[212:215], v146 offset:7168
	global_load_lds_dwordx4 v[142:143], off
	v_lshl_add_u64 v[142:143], s[12:13], 0, v[138:139]
	s_add_i32 m0, s24, 0xe000
	s_nop 0
	global_load_lds_dwordx4 v[142:143], off
	s_waitcnt lgkmcnt(8)
	s_barrier
	s_waitcnt lgkmcnt(0)
	s_setprio 1
	s_waitcnt lgkmcnt(0)
	v_mfma_f32_16x16x32_bf16 v[128:131], v[148:151], v[168:171], v[128:131]
	v_mfma_f32_16x16x32_bf16 v[124:127], v[156:159], v[168:171], v[124:127]
	v_mfma_f32_16x16x32_bf16 v[120:123], v[148:151], v[176:179], v[120:123]
	v_mfma_f32_16x16x32_bf16 v[112:115], v[156:159], v[176:179], v[112:115]
	v_mfma_f32_16x16x32_bf16 v[104:107], v[148:151], v[184:187], v[104:107]
	v_mfma_f32_16x16x32_bf16 v[96:99], v[156:159], v[184:187], v[96:99]
	v_mfma_f32_16x16x32_bf16 v[88:91], v[148:151], v[192:195], v[88:91]
	v_mfma_f32_16x16x32_bf16 v[80:83], v[156:159], v[192:195], v[80:83]
	v_mfma_f32_16x16x32_bf16 v[128:131], v[152:155], v[172:175], v[128:131]
	v_mfma_f32_16x16x32_bf16 v[124:127], v[160:163], v[172:175], v[124:127]
	v_mfma_f32_16x16x32_bf16 v[120:123], v[152:155], v[180:183], v[120:123]
	v_mfma_f32_16x16x32_bf16 v[112:115], v[160:163], v[180:183], v[112:115]
	v_mfma_f32_16x16x32_bf16 v[104:107], v[152:155], v[188:191], v[104:107]
	v_mfma_f32_16x16x32_bf16 v[96:99], v[160:163], v[188:191], v[96:99]
	v_mfma_f32_16x16x32_bf16 v[88:91], v[152:155], v[212:215], v[88:91]
	v_mfma_f32_16x16x32_bf16 v[80:83], v[160:163], v[212:215], v[80:83]
	s_setprio 0
	s_barrier
	s_add_i32 s42, 0, 0x14000
	v_add_u32_e32 v142, s42, v145
	s_add_i32 s40, s40, s19
	ds_read_b128 v[216:219], v142
	ds_read_b128 v[220:223], v142 offset:1024
	ds_read_b128 v[224:227], v142 offset:2048
	ds_read_b128 v[228:231], v142 offset:3072
	v_lshl_add_u64 v[142:143], s[14:15], 0, v[134:135]
	s_mov_b32 m0, s40
	v_lshl_add_u64 v[196:197], s[14:15], 0, v[0:1]
	global_load_lds_dwordx4 v[142:143], off
	s_add_i32 m0, s40, 0x2000
	s_nop 0
	global_load_lds_dwordx4 v[196:197], off
	s_barrier
	s_waitcnt lgkmcnt(0)
	s_setprio 1
	s_waitcnt lgkmcnt(0)
	v_mfma_f32_16x16x32_bf16 v[116:119], v[216:219], v[168:171], v[116:119]
	v_mfma_f32_16x16x32_bf16 v[108:111], v[224:227], v[168:171], v[108:111]
	v_mfma_f32_16x16x32_bf16 v[100:103], v[216:219], v[176:179], v[100:103]
	v_mfma_f32_16x16x32_bf16 v[92:95], v[224:227], v[176:179], v[92:95]
	v_mfma_f32_16x16x32_bf16 v[84:87], v[216:219], v[184:187], v[84:87]
	v_mfma_f32_16x16x32_bf16 v[76:79], v[224:227], v[184:187], v[76:79]
	v_mfma_f32_16x16x32_bf16 v[72:75], v[216:219], v[192:195], v[72:75]
	v_mfma_f32_16x16x32_bf16 v[68:71], v[224:227], v[192:195], v[68:71]
	v_mfma_f32_16x16x32_bf16 v[116:119], v[220:223], v[172:175], v[116:119]
	v_mfma_f32_16x16x32_bf16 v[108:111], v[228:231], v[172:175], v[108:111]
	v_mfma_f32_16x16x32_bf16 v[100:103], v[220:223], v[180:183], v[100:103]
	v_mfma_f32_16x16x32_bf16 v[92:95], v[228:231], v[180:183], v[92:95]
	v_mfma_f32_16x16x32_bf16 v[84:87], v[220:223], v[188:191], v[84:87]
	v_mfma_f32_16x16x32_bf16 v[76:79], v[228:231], v[188:191], v[76:79]
	v_mfma_f32_16x16x32_bf16 v[72:75], v[220:223], v[212:215], v[72:75]
	v_mfma_f32_16x16x32_bf16 v[68:71], v[228:231], v[212:215], v[68:71]
	s_setprio 0
	s_mov_b32 m0, s24
	v_lshl_add_u64 v[232:233], s[16:17], 0, v[136:137]
	s_barrier
	ds_read_b128 v[168:171], v146 offset:16384
	ds_read_b128 v[172:175], v146 offset:17408
	ds_read_b128 v[176:179], v146 offset:18432
	ds_read_b128 v[180:183], v146 offset:19456
	ds_read_b128 v[184:187], v146 offset:20480
	ds_read_b128 v[188:191], v146 offset:21504
	ds_read_b128 v[192:195], v146 offset:22528
	ds_read_b128 v[212:215], v146 offset:23552
	global_load_lds_dwordx4 v[232:233], off
	v_lshl_add_u64 v[234:235], s[16:17], 0, v[132:133]
	s_mov_b32 m0, s25
	s_nop 0
	global_load_lds_dwordx4 v[234:235], off
	s_barrier
	s_waitcnt lgkmcnt(0)
	s_setprio 1
	s_waitcnt lgkmcnt(0)
	v_mfma_f32_16x16x32_bf16 v[64:67], v[148:151], v[168:171], v[64:67]
	v_mfma_f32_16x16x32_bf16 v[60:63], v[156:159], v[168:171], v[60:63]
	v_mfma_f32_16x16x32_bf16 v[56:59], v[148:151], v[176:179], v[56:59]
	v_mfma_f32_16x16x32_bf16 v[48:51], v[156:159], v[176:179], v[48:51]
	v_mfma_f32_16x16x32_bf16 v[40:43], v[148:151], v[184:187], v[40:43]
	v_mfma_f32_16x16x32_bf16 v[32:35], v[156:159], v[184:187], v[32:35]
	v_mfma_f32_16x16x32_bf16 v[24:27], v[148:151], v[192:195], v[24:27]
	v_mfma_f32_16x16x32_bf16 v[16:19], v[156:159], v[192:195], v[16:19]
	v_mfma_f32_16x16x32_bf16 v[64:67], v[152:155], v[172:175], v[64:67]
	v_mfma_f32_16x16x32_bf16 v[60:63], v[160:163], v[172:175], v[60:63]
	v_mfma_f32_16x16x32_bf16 v[56:59], v[152:155], v[180:183], v[56:59]
	v_mfma_f32_16x16x32_bf16 v[48:51], v[160:163], v[180:183], v[48:51]
	v_mfma_f32_16x16x32_bf16 v[40:43], v[152:155], v[188:191], v[40:43]
	v_mfma_f32_16x16x32_bf16 v[32:35], v[160:163], v[188:191], v[32:35]
	v_mfma_f32_16x16x32_bf16 v[24:27], v[152:155], v[212:215], v[24:27]
	v_mfma_f32_16x16x32_bf16 v[16:19], v[160:163], v[212:215], v[16:19]
	s_setprio 0
	s_barrier
; #define PG8_WAIT_V(n) asm volatile("s_waitcnt vmcnt(" #n ")" ::: "memory")
; #define PG8_WAIT_L(n) asm volatile("s_waitcnt lgkmcnt(" #n ")" ::: "memory")
; #define PG8_BAR __builtin_amdgcn_s_barrier()
; #define PG8_SCHED __builtin_amdgcn_sched_barrier(0)
; template <class Epi, class AddrA, class AddrB>
; __device__ __forceinline__ void gemm_phase(const Sched S, const int lda, const int ldb, const int K, const AddrA addrA,
;                                            const AddrB addrB, const Epi E) {
;     ...
;       PG8_WAIT_V(6); PG8_BAR; PG8_MMA(1, 1, At, B1); PG8_BAR;
;       PG8_LDB(B0, 1, 0); PG8_SCHED; PG8_LDA(At, 1, 0); PG8_STAGE(PG8_SA(0, 1), a2 + hstepA, voffA);
;       PG8_WAIT_L(8); PG8_BAR; PG8_WAIT_L(0); PG8_MMA(0, 0, At, B0); PG8_BAR; PG8_SCHED;
;       PG8_LDB(B1, 1, 1); PG8_STAGE(PG8_SB(1, 0), b3, voffB);
;       PG8_BAR; PG8_WAIT_L(0); PG8_MMA(0, 1, At, B1); PG8_BAR;
;       PG8_LDA(At, 1, 1); PG8_STAGE(PG8_SA(1, 0), a3, voffA);
;       PG8_BAR; PG8_WAIT_L(0); PG8_MMA(1, 0, At, B0); PG8_BAR; PG8_SCHED;
	s_add_u32 s40, s14, 0x80000
	s_addc_u32 s41, s15, 0
	s_add_i32 s42, s42, s19
	v_lshl_add_u64 v[148:149], s[40:41], 0, v[134:135]
	s_mov_b32 m0, s42
	s_nop 0
	global_load_lds_dwordx4 v[148:149], off
	v_lshl_add_u64 v[148:149], s[40:41], 0, v[0:1]
	s_add_i32 m0, s42, 0x2000
	s_nop 0
	global_load_lds_dwordx4 v[148:149], off
	s_waitcnt vmcnt(6)
	s_barrier
	s_setprio 1
	v_mfma_f32_16x16x32_bf16 v[52:55], v[216:219], v[168:171], v[52:55]
	v_mfma_f32_16x16x32_bf16 v[44:47], v[224:227], v[168:171], v[44:47]
	v_mfma_f32_16x16x32_bf16 v[36:39], v[216:219], v[176:179], v[36:39]
	v_mfma_f32_16x16x32_bf16 v[28:31], v[224:227], v[176:179], v[28:31]
	v_mfma_f32_16x16x32_bf16 v[20:23], v[216:219], v[184:187], v[20:23]
	v_mfma_f32_16x16x32_bf16 v[12:15], v[224:227], v[184:187], v[12:15]
	v_mfma_f32_16x16x32_bf16 v[8:11], v[216:219], v[192:195], v[8:11]
	v_mfma_f32_16x16x32_bf16 v[4:7], v[224:227], v[192:195], v[4:7]
	v_mfma_f32_16x16x32_bf16 v[52:55], v[220:223], v[172:175], v[52:55]
	v_mfma_f32_16x16x32_bf16 v[44:47], v[228:231], v[172:175], v[44:47]
	v_mfma_f32_16x16x32_bf16 v[36:39], v[220:223], v[180:183], v[36:39]
	v_mfma_f32_16x16x32_bf16 v[28:31], v[228:231], v[180:183], v[28:31]
	v_mfma_f32_16x16x32_bf16 v[20:23], v[220:223], v[188:191], v[20:23]
	v_mfma_f32_16x16x32_bf16 v[12:15], v[228:231], v[188:191], v[12:15]
	v_mfma_f32_16x16x32_bf16 v[8:11], v[220:223], v[212:215], v[8:11]
	v_mfma_f32_16x16x32_bf16 v[4:7], v[228:231], v[212:215], v[4:7]
	s_setprio 0
	s_add_i32 s40, 0, 0x18000
	v_add_u32_e32 v147, s40, v145
	s_barrier
	ds_read_b128 v[148:151], v147
	ds_read_b128 v[152:155], v147 offset:1024
	ds_read_b128 v[156:159], v147 offset:2048
	ds_read_b128 v[160:163], v147 offset:3072
	s_add_u32 s16, s16, 0x80000
	s_addc_u32 s17, s17, 0
	s_mov_b32 m0, s26
	v_lshl_add_u64 v[216:217], s[16:17], 0, v[136:137]
	ds_read_b128 v[168:171], v146 offset:32768
	ds_read_b128 v[172:175], v146 offset:33792
	ds_read_b128 v[176:179], v146 offset:34816
	ds_read_b128 v[180:183], v146 offset:35840
	ds_read_b128 v[184:187], v146 offset:36864
	ds_read_b128 v[188:191], v146 offset:37888
	ds_read_b128 v[192:195], v146 offset:38912
	ds_read_b128 v[212:215], v146 offset:39936
	global_load_lds_dwordx4 v[216:217], off
	v_lshl_add_u64 v[216:217], s[16:17], 0, v[132:133]
	s_mov_b32 m0, s27
	s_nop 0
	global_load_lds_dwordx4 v[216:217], off
	s_waitcnt lgkmcnt(8)
	s_barrier
	s_waitcnt lgkmcnt(0)
	s_setprio 1
	s_waitcnt lgkmcnt(0)
	v_mfma_f32_16x16x32_bf16 v[128:131], v[148:151], v[168:171], v[128:131]
	v_mfma_f32_16x16x32_bf16 v[124:127], v[156:159], v[168:171], v[124:127]
	v_mfma_f32_16x16x32_bf16 v[120:123], v[148:151], v[176:179], v[120:123]
	v_mfma_f32_16x16x32_bf16 v[112:115], v[156:159], v[176:179], v[112:115]
	v_mfma_f32_16x16x32_bf16 v[104:107], v[148:151], v[184:187], v[104:107]
	v_mfma_f32_16x16x32_bf16 v[96:99], v[156:159], v[184:187], v[96:99]
	v_mfma_f32_16x16x32_bf16 v[88:91], v[148:151], v[192:195], v[88:91]
	v_mfma_f32_16x16x32_bf16 v[80:83], v[156:159], v[192:195], v[80:83]
	v_mfma_f32_16x16x32_bf16 v[128:131], v[152:155], v[172:175], v[128:131]
	v_mfma_f32_16x16x32_bf16 v[124:127], v[160:163], v[172:175], v[124:127]
	v_mfma_f32_16x16x32_bf16 v[120:123], v[152:155], v[180:183], v[120:123]
	v_mfma_f32_16x16x32_bf16 v[112:115], v[160:163], v[180:183], v[112:115]
	v_mfma_f32_16x16x32_bf16 v[104:107], v[152:155], v[188:191], v[104:107]
	v_mfma_f32_16x16x32_bf16 v[96:99], v[160:163], v[188:191], v[96:99]
	v_mfma_f32_16x16x32_bf16 v[88:91], v[152:155], v[212:215], v[88:91]
	v_mfma_f32_16x16x32_bf16 v[80:83], v[160:163], v[212:215], v[80:83]
	s_setprio 0
	s_barrier
	s_add_i32 s16, 0, 0x1c000
	s_add_i32 s17, s40, s19
	v_add_u32_e32 v147, s16, v145
	v_lshl_add_u64 v[142:143], v[142:143], 0, s[52:53]
	s_mov_b32 m0, s17
	ds_read_b128 v[216:219], v147
	ds_read_b128 v[220:223], v147 offset:1024
	ds_read_b128 v[224:227], v147 offset:2048
	ds_read_b128 v[228:231], v147 offset:3072
	global_load_lds_dwordx4 v[142:143], off
	v_lshl_add_u64 v[142:143], v[196:197], 0, s[52:53]
	s_add_i32 m0, s17, 0x2000
	s_nop 0
	global_load_lds_dwordx4 v[142:143], off
	s_barrier
	s_waitcnt lgkmcnt(0)
	s_setprio 1
	s_waitcnt lgkmcnt(0)
	v_mfma_f32_16x16x32_bf16 v[116:119], v[216:219], v[168:171], v[116:119]
	v_mfma_f32_16x16x32_bf16 v[108:111], v[224:227], v[168:171], v[108:111]
	v_mfma_f32_16x16x32_bf16 v[100:103], v[216:219], v[176:179], v[100:103]
	v_mfma_f32_16x16x32_bf16 v[92:95], v[224:227], v[176:179], v[92:95]
	v_mfma_f32_16x16x32_bf16 v[84:87], v[216:219], v[184:187], v[84:87]
	v_mfma_f32_16x16x32_bf16 v[76:79], v[224:227], v[184:187], v[76:79]
	v_mfma_f32_16x16x32_bf16 v[72:75], v[216:219], v[192:195], v[72:75]
	v_mfma_f32_16x16x32_bf16 v[68:71], v[224:227], v[192:195], v[68:71]
	v_mfma_f32_16x16x32_bf16 v[116:119], v[220:223], v[172:175], v[116:119]
	v_mfma_f32_16x16x32_bf16 v[108:111], v[228:231], v[172:175], v[108:111]
	v_mfma_f32_16x16x32_bf16 v[100:103], v[220:223], v[180:183], v[100:103]
	v_mfma_f32_16x16x32_bf16 v[92:95], v[228:231], v[180:183], v[92:95]
	v_mfma_f32_16x16x32_bf16 v[84:87], v[220:223], v[188:191], v[84:87]
	v_mfma_f32_16x16x32_bf16 v[76:79], v[228:231], v[188:191], v[76:79]
	v_mfma_f32_16x16x32_bf16 v[72:75], v[220:223], v[212:215], v[72:75]
	v_mfma_f32_16x16x32_bf16 v[68:71], v[228:231], v[212:215], v[68:71]
	s_setprio 0
	s_mov_b32 m0, s30
	v_lshl_add_u64 v[142:143], v[232:233], 0, s[52:53]
	s_barrier
	ds_read_b128 v[168:171], v146 offset:49152
	ds_read_b128 v[172:175], v146 offset:50176
	ds_read_b128 v[176:179], v146 offset:51200
	ds_read_b128 v[180:183], v146 offset:52224
	ds_read_b128 v[184:187], v146 offset:53248
	ds_read_b128 v[188:191], v146 offset:54272
	ds_read_b128 v[192:195], v146 offset:55296
	ds_read_b128 v[212:215], v146 offset:56320
	global_load_lds_dwordx4 v[142:143], off
	v_lshl_add_u64 v[142:143], v[234:235], 0, s[52:53]
	s_mov_b32 m0, s31
	s_nop 0
	global_load_lds_dwordx4 v[142:143], off
	s_barrier
; #define PG8_WAIT_V(n) asm volatile("s_waitcnt vmcnt(" #n ")" ::: "memory")
; #define PG8_WAIT_L(n) asm volatile("s_waitcnt lgkmcnt(" #n ")" ::: "memory")
; #define PG8_BAR __builtin_amdgcn_s_barrier()
; #define PG8_SCHED __builtin_amdgcn_sched_barrier(0)
; template <class Epi, class AddrA, class AddrB>
; __device__ __forceinline__ void gemm_phase(const Sched S, const int lda, const int ldb, const int K, const AddrA addrA,
;                                            const AddrB addrB, const Epi E) {
;     ...
;       PG8_BAR; PG8_WAIT_L(0); PG8_MMA(1, 0, At, B0); PG8_BAR; PG8_SCHED;
;       PG8_STAGE(PG8_SB(1, 1), b3 + hstepB, voffB);
;       PG8_WAIT_V(6); PG8_BAR; PG8_MMA(1, 1, At, B1); PG8_BAR;
;     }
	s_waitcnt lgkmcnt(0)
	s_setprio 1
	s_waitcnt lgkmcnt(0)
	v_mfma_f32_16x16x32_bf16 v[64:67], v[148:151], v[168:171], v[64:67]
	v_mfma_f32_16x16x32_bf16 v[60:63], v[156:159], v[168:171], v[60:63]
	v_mfma_f32_16x16x32_bf16 v[56:59], v[148:151], v[176:179], v[56:59]
	v_mfma_f32_16x16x32_bf16 v[48:51], v[156:159], v[176:179], v[48:51]
	v_mfma_f32_16x16x32_bf16 v[40:43], v[148:151], v[184:187], v[40:43]
	v_mfma_f32_16x16x32_bf16 v[32:35], v[156:159], v[184:187], v[32:35]
	v_mfma_f32_16x16x32_bf16 v[24:27], v[148:151], v[192:195], v[24:27]
	v_mfma_f32_16x16x32_bf16 v[16:19], v[156:159], v[192:195], v[16:19]
	v_mfma_f32_16x16x32_bf16 v[64:67], v[152:155], v[172:175], v[64:67]
	v_mfma_f32_16x16x32_bf16 v[60:63], v[160:163], v[172:175], v[60:63]
	v_mfma_f32_16x16x32_bf16 v[56:59], v[152:155], v[180:183], v[56:59]
	v_mfma_f32_16x16x32_bf16 v[48:51], v[160:163], v[180:183], v[48:51]
	v_mfma_f32_16x16x32_bf16 v[40:43], v[152:155], v[188:191], v[40:43]
	v_mfma_f32_16x16x32_bf16 v[32:35], v[160:163], v[188:191], v[32:35]
	v_mfma_f32_16x16x32_bf16 v[24:27], v[152:155], v[212:215], v[24:27]
	v_mfma_f32_16x16x32_bf16 v[16:19], v[160:163], v[212:215], v[16:19]
	s_setprio 0
	s_barrier
	s_add_u32 s14, s14, 0x80080
	s_addc_u32 s15, s15, 0
	s_add_i32 s16, s16, s19
	v_lshl_add_u64 v[142:143], s[14:15], 0, v[134:135]
	s_mov_b32 m0, s16
	s_nop 0
	global_load_lds_dwordx4 v[142:143], off
	v_lshl_add_u64 v[142:143], s[14:15], 0, v[0:1]
	s_add_i32 m0, s16, 0x2000
	s_nop 0
	global_load_lds_dwordx4 v[142:143], off
	s_waitcnt vmcnt(6)
	s_barrier
	s_setprio 1
	v_mfma_f32_16x16x32_bf16 v[52:55], v[216:219], v[168:171], v[52:55]
	v_mfma_f32_16x16x32_bf16 v[44:47], v[224:227], v[168:171], v[44:47]
	v_mfma_f32_16x16x32_bf16 v[36:39], v[216:219], v[176:179], v[36:39]
	v_mfma_f32_16x16x32_bf16 v[28:31], v[224:227], v[176:179], v[28:31]
	v_mfma_f32_16x16x32_bf16 v[20:23], v[216:219], v[184:187], v[20:23]
	v_mfma_f32_16x16x32_bf16 v[12:15], v[224:227], v[184:187], v[12:15]
	v_mfma_f32_16x16x32_bf16 v[8:11], v[216:219], v[192:195], v[8:11]
	v_mfma_f32_16x16x32_bf16 v[4:7], v[224:227], v[192:195], v[4:7]
	v_mfma_f32_16x16x32_bf16 v[52:55], v[220:223], v[172:175], v[52:55]
	v_mfma_f32_16x16x32_bf16 v[44:47], v[228:231], v[172:175], v[44:47]
	v_mfma_f32_16x16x32_bf16 v[36:39], v[220:223], v[180:183], v[36:39]
	v_mfma_f32_16x16x32_bf16 v[28:31], v[228:231], v[180:183], v[28:31]
	v_mfma_f32_16x16x32_bf16 v[20:23], v[220:223], v[188:191], v[20:23]
	v_mfma_f32_16x16x32_bf16 v[12:15], v[228:231], v[188:191], v[12:15]
	v_mfma_f32_16x16x32_bf16 v[8:11], v[220:223], v[212:215], v[8:11]
	v_mfma_f32_16x16x32_bf16 v[4:7], v[228:231], v[212:215], v[4:7]
	s_setprio 0
	s_add_i32 s39, s39, 2
	s_add_u32 s37, s37, 0x100
	s_addc_u32 s38, s38, 0
	s_add_u32 s12, s12, 0x100
	s_addc_u32 s13, s13, 0
	s_cmp_gt_u32 s39, 29
	s_barrier
	s_cbranch_scc0 .LBB0_109
; template <class Epi, class AddrA, class AddrB>
; __device__ __forceinline__ void gemm_phase(const Sched S, const int lda, const int ldb, const int K, const AddrA addrA,
;                                            const AddrB addrB, const Epi E) {
;     ...
;     E(acc, cur, wr, wc, fr, fq);
;     if (!has_next) break;
;     if (!(Epi::KEEP && cur.br + 1 < S.nbr)) {
; #pragma unroll
;       for (int a = 0; a < 2; ++a)
; #pragma unroll
;         for (int b = 0; b < 2; ++b)
; #pragma unroll
;           for (int m = 0; m < 4; ++m)
; #pragma unroll
;             for (int n = 0; n < 2; ++n) acc[a][b][m][n] = (f32x4){0.f, 0.f, 0.f, 0.f};
;     }
;     cur = nxt; cA = nA; cB = nB; ++ui;
;   __device__ __forceinline__ void operator()(EPI_ARGS) const {
;     bf16_t* base = proj + ((size_t)u.pn * MTOK + (size_t)(u.pm * 256 + wr * 64 + fr)) * PLD + wc * 32 + 8 * fq;
; #pragma unroll
;     for (int ai = 0; ai < 2; ++ai)
; #pragma unroll
;       for (int m = 0; m < 4; ++m) {
;         bf16_t* rowp = base + (size_t)(ai * HALF + m * 16) * PLD;
; #pragma unroll
;         for (int bj = 0; bj < 2; ++bj) {
;           const f32x4 v0 = acc[ai][bj][m][0], v1 = acc[ai][bj][m][1];
;           u32x4 o;
;           o.x = pack2(v0[0], v0[1]); o.y = pack2(v0[2], v0[3]); o.z = pack2(v1[0], v1[1]); o.w = pack2(v1[2], v1[3]);
;           *(u32x4*)(rowp + bj * HALF) = o;
;         }
;       }
;   }
	s_ashr_i32 s11, s10, 31
	v_lshl_add_u32 v142, s35, 8, v144
	s_lshl_b64 s[10:11], s[10:11], 23
	v_ashrrev_i32_e32 v143, 31, v142
	s_add_u32 s10, s28, s10
	s_addc_u32 s11, s29, s11
	v_lshlrev_b64 v[142:143], 9, v[142:143]
	v_lshl_add_u64 v[142:143], s[10:11], 0, v[142:143]
	v_lshl_add_u64 v[142:143], v[142:143], 0, s[72:73]
	v_lshl_add_u64 v[142:143], v[142:143], 0, v[2:3]
	v_cvt_pk_bf16_f32 v116, v116, v117
	v_cvt_pk_bf16_f32 v117, v118, v119
	v_cvt_pk_bf16_f32 v119, v110, v111
	v_cvt_pk_bf16_f32 v110, v112, v113
	v_add_co_u32_e32 v112, vcc, s96, v142
	s_movk_i32 s1, 0x4000
	s_nop 0
	v_addc_co_u32_e32 v113, vcc, 0, v143, vcc
	v_cvt_pk_bf16_f32 v100, v100, v101
	v_cvt_pk_bf16_f32 v101, v102, v103
	v_cvt_pk_bf16_f32 v103, v94, v95
	v_cvt_pk_bf16_f32 v94, v96, v97
	v_add_co_u32_e32 v96, vcc, s1, v142
	s_movk_i32 s1, 0x6000
	s_nop 0
	v_addc_co_u32_e32 v97, vcc, 0, v143, vcc
	v_cvt_pk_bf16_f32 v84, v84, v85
	v_cvt_pk_bf16_f32 v85, v86, v87
	v_cvt_pk_bf16_f32 v87, v78, v79
	v_cvt_pk_bf16_f32 v78, v80, v81
	v_add_co_u32_e32 v80, vcc, s1, v142
	v_cvt_pk_bf16_f32 v64, v64, v65
	v_cvt_pk_bf16_f32 v65, v66, v67
	v_cvt_pk_bf16_f32 v66, v60, v61
	s_mov_b32 s1, 0x12000
	s_nop 0
	v_addc_co_u32_e32 v81, vcc, 0, v143, vcc
	v_add_co_u32_e32 v60, vcc, s67, v142
	v_cvt_pk_bf16_f32 v52, v52, v53
	v_cvt_pk_bf16_f32 v53, v54, v55
	v_cvt_pk_bf16_f32 v55, v46, v47
	v_cvt_pk_bf16_f32 v46, v48, v49
	s_nop 1
	v_addc_co_u32_e32 v61, vcc, 0, v143, vcc
	v_add_co_u32_e32 v48, vcc, s1, v142
	s_mov_b32 s1, 0x14000
	s_nop 0
	v_addc_co_u32_e32 v49, vcc, 0, v143, vcc
	v_cvt_pk_bf16_f32 v36, v36, v37
	v_cvt_pk_bf16_f32 v37, v38, v39
	v_cvt_pk_bf16_f32 v39, v30, v31
	v_cvt_pk_bf16_f32 v30, v32, v33
	v_add_co_u32_e32 v32, vcc, s1, v142
	s_mov_b32 s1, 0x16000
	s_nop 0
	v_addc_co_u32_e32 v33, vcc, 0, v143, vcc
	v_cvt_pk_bf16_f32 v20, v20, v21
	v_cvt_pk_bf16_f32 v21, v22, v23
	v_cvt_pk_bf16_f32 v23, v14, v15
	v_cvt_pk_bf16_f32 v14, v16, v17
	v_add_co_u32_e32 v16, vcc, s1, v142
	s_mov_b32 s10, s2
	s_nop 0
	v_addc_co_u32_e32 v17, vcc, 0, v143, vcc
	s_and_b64 vcc, exec, s[4:5]
	s_mov_b32 s35, s0
	s_mov_b64 s[12:13], s[8:9]
	s_mov_b64 s[14:15], s[6:7]
	v_cvt_pk_bf16_f32 v128, v128, v129
	v_cvt_pk_bf16_f32 v129, v130, v131
	v_cvt_pk_bf16_f32 v130, v124, v125
	v_cvt_pk_bf16_f32 v131, v126, v127
	global_store_dwordx4 v[142:143], v[128:131], off
	v_cvt_pk_bf16_f32 v118, v108, v109
	global_store_dwordx4 v[142:143], v[116:119], off offset:256
	v_cvt_pk_bf16_f32 v108, v120, v121
	v_cvt_pk_bf16_f32 v109, v122, v123
	v_cvt_pk_bf16_f32 v111, v114, v115
	global_store_dwordx4 v[112:113], v[108:111], off
	v_cvt_pk_bf16_f32 v102, v92, v93
	global_store_dwordx4 v[112:113], v[100:103], off offset:256
	v_cvt_pk_bf16_f32 v92, v104, v105
	v_cvt_pk_bf16_f32 v93, v106, v107
	v_cvt_pk_bf16_f32 v95, v98, v99
	global_store_dwordx4 v[96:97], v[92:95], off
	v_cvt_pk_bf16_f32 v86, v76, v77
	global_store_dwordx4 v[96:97], v[84:87], off offset:256
	v_cvt_pk_bf16_f32 v76, v88, v89
	v_cvt_pk_bf16_f32 v77, v90, v91
	v_cvt_pk_bf16_f32 v79, v82, v83
	global_store_dwordx4 v[80:81], v[76:79], off
	v_cvt_pk_bf16_f32 v72, v72, v73
	v_cvt_pk_bf16_f32 v73, v74, v75
	v_cvt_pk_bf16_f32 v74, v68, v69
	v_cvt_pk_bf16_f32 v75, v70, v71
	global_store_dwordx4 v[80:81], v[72:75], off offset:256
	v_cvt_pk_bf16_f32 v67, v62, v63
	global_store_dwordx4 v[60:61], v[64:67], off
	v_cvt_pk_bf16_f32 v54, v44, v45
	global_store_dwordx4 v[60:61], v[52:55], off offset:256
	v_cvt_pk_bf16_f32 v44, v56, v57
	v_cvt_pk_bf16_f32 v45, v58, v59
	v_cvt_pk_bf16_f32 v47, v50, v51
	global_store_dwordx4 v[48:49], v[44:47], off
	v_cvt_pk_bf16_f32 v38, v28, v29
	global_store_dwordx4 v[48:49], v[36:39], off offset:256
	v_cvt_pk_bf16_f32 v28, v40, v41
	v_cvt_pk_bf16_f32 v29, v42, v43
	v_cvt_pk_bf16_f32 v31, v34, v35
	global_store_dwordx4 v[32:33], v[28:31], off
	v_cvt_pk_bf16_f32 v22, v12, v13
	global_store_dwordx4 v[32:33], v[20:23], off offset:256
	v_cvt_pk_bf16_f32 v12, v24, v25
	v_cvt_pk_bf16_f32 v13, v26, v27
	v_cvt_pk_bf16_f32 v15, v18, v19
	global_store_dwordx4 v[16:17], v[12:15], off
	v_cvt_pk_bf16_f32 v8, v8, v9
	v_cvt_pk_bf16_f32 v9, v10, v11
	v_cvt_pk_bf16_f32 v10, v4, v5
	v_cvt_pk_bf16_f32 v11, v6, v7
	global_store_dwordx4 v[16:17], v[8:11], off offset:256
	s_cbranch_vccz .LBB0_106
	s_waitcnt vmcnt(0)
	s_cmpk_gt_u32 s18, 0xff
	s_cbranch_scc1 .LBB0_113
	s_barrier

; __device__ __forceinline__ unsigned xb_ld(unsigned* p) { return __hip_atomic_load(p, __ATOMIC_RELAXED, __HIP_MEMORY_SCOPE_AGENT); }
; __device__ __forceinline__ void xcd_barrier_complete(unsigned* bar, unsigned x, unsigned& nloc, unsigned& nx) {
;   const unsigned G = gridDim.x * gridDim.y * gridDim.z;
;   unsigned sum, cnt, mine, sp = 0u;
;   for (;;) {
;     sum = 0u; cnt = 0u; mine = 0u;
; #pragma unroll
;     for (unsigned j = 0; j < 16; ++j) { const unsigned c = xb_ld(&bar[XB_XCNT(j)]); sum += c; cnt += (c > 0u) ? 1u : 0u; mine = (j == x) ? c : mine; }
;     if (sum == G) break;
;     __builtin_amdgcn_s_sleep(1);
;     if ((++sp & 255u) == 0u) { if (xb_ld(&bar[XB_TMO])) break; if (sp > XB_SPIN_CAP) { atomicAdd(&bar[XB_TMO], 1u); break; } }
;   }
.LBB0_119:
	s_waitcnt lgkmcnt(0)
	v_mov_b64_e32 v[0:1], s[68:69]
	v_mov_b64_e32 v[4:5], s[70:71]
	global_load_dword v0, v[0:1], off sc1
	s_or_b64 s[8:9], s[8:9], exec
	global_load_dword v1, v[4:5], off sc1
	v_mov_b64_e32 v[4:5], s[74:75]
	global_load_dword v2, v[4:5], off sc1
	v_mov_b64_e32 v[4:5], s[78:79]
	global_load_dword v4, v[4:5], off sc1
	s_or_b64 s[6:7], s[6:7], exec
	s_waitcnt vmcnt(0) lgkmcnt(0)
	v_add_u32_e32 v6, v1, v0
	v_add_u32_e32 v6, v6, v2
	v_add_u32_e32 v8, v6, v4
	v_mov_b64_e32 v[6:7], s[94:95]
	global_load_dword v5, v[6:7], off sc1
	v_mov_b64_e32 v[6:7], s[54:55]
	global_load_dword v6, v[6:7], off sc1
	s_waitcnt vmcnt(0) lgkmcnt(0)
	v_add_u32_e32 v8, v8, v5
	v_add_u32_e32 v10, v8, v6
	v_mov_b64_e32 v[8:9], s[56:57]
	global_load_dword v7, v[8:9], off sc1
	v_mov_b64_e32 v[8:9], s[58:59]
	global_load_dword v8, v[8:9], off sc1
	s_waitcnt vmcnt(0) lgkmcnt(0)
	v_add_u32_e32 v10, v10, v7
	v_add_u32_e32 v12, v10, v8
	v_mov_b64_e32 v[10:11], s[60:61]
	global_load_dword v9, v[10:11], off sc1
	v_mov_b64_e32 v[10:11], s[62:63]
	global_load_dword v10, v[10:11], off sc1
	s_waitcnt vmcnt(0) lgkmcnt(0)
	v_add_u32_e32 v12, v12, v9
	v_add_u32_e32 v14, v12, v10
	v_mov_b64_e32 v[12:13], s[80:81]
	global_load_dword v11, v[12:13], off sc1
	v_mov_b64_e32 v[12:13], s[82:83]
	global_load_dword v12, v[12:13], off sc1
	s_waitcnt vmcnt(0) lgkmcnt(0)
	v_add_u32_e32 v14, v14, v11
	v_add_u32_e32 v16, v14, v12
	v_mov_b64_e32 v[14:15], s[84:85]
	global_load_dword v13, v[14:15], off sc1
	v_mov_b64_e32 v[14:15], s[86:87]
	global_load_dword v14, v[14:15], off sc1
	s_waitcnt vmcnt(0) lgkmcnt(0)
	v_add_u32_e32 v16, v16, v13
	v_add_u32_e32 v18, v16, v14
	v_mov_b64_e32 v[16:17], s[88:89]
	global_load_dword v15, v[16:17], off sc1
	v_mov_b64_e32 v[16:17], s[90:91]
	global_load_dword v16, v[16:17], off sc1
	s_waitcnt vmcnt(0) lgkmcnt(0)
	v_add_u32_e32 v18, v18, v15
	v_add_u32_e32 v17, v18, v16
	v_cmp_ne_u32_e32 vcc, s92, v17
	s_and_saveexec_b64 s[10:11], vcc
	s_cbranch_execz .LBB0_118
	s_and_b32 s14, s20, 0xff
	s_mov_b64 s[12:13], -1
	s_cmp_eq_u32 s14, 0
	s_mov_b64 s[16:17], -1
	s_mov_b64 s[14:15], -1
	s_sleep 1
	s_cbranch_scc1 .LBB0_122
	s_and_saveexec_b64 s[18:19], s[16:17]
	s_cbranch_execz .LBB0_117
	s_branch .LBB0_125
.LBB0_122:
	v_readlane_b32 s14, v245, 48
	v_readlane_b32 s15, v245, 49
	s_mov_b64 s[16:17], 0
	s_nop 0
	v_mov_b64_e32 v[18:19], s[14:15]
	global_load_dword v17, v[18:19], off sc1
	s_mov_b64 s[14:15], -1
	s_waitcnt vmcnt(0) lgkmcnt(0)
	v_cmp_eq_u32_e32 vcc, 0, v17
	s_and_saveexec_b64 s[18:19], vcc
	s_cmp_lt_u32 s20, 0x100001
	s_cselect_b64 s[16:17], -1, 0
	s_xor_b64 s[14:15], exec, -1
	s_and_b64 s[16:17], s[16:17], exec
	s_or_b64 exec, exec, s[18:19]
	s_and_saveexec_b64 s[18:19], s[16:17]
	s_cbranch_execz .LBB0_117

; __device__ __forceinline__ unsigned xb_ld(unsigned* p) { return __hip_atomic_load(p, __ATOMIC_RELAXED, __HIP_MEMORY_SCOPE_AGENT); }
; __device__ __forceinline__ void xcd_barrier_complete(unsigned* bar, unsigned x, unsigned& nloc, unsigned& nx) {
;     ...
;     if ((++sp & 255u) == 0u) { if (xb_ld(&bar[XB_TMO])) break; if (sp > XB_SPIN_CAP) { atomicAdd(&bar[XB_TMO], 1u); break; } }
.LBB0_126:
	s_or_b64 exec, exec, s[0:1]
	s_xor_b64 s[0:1], s[4:5], -1
	s_and_saveexec_b64 s[4:5], s[0:1]
	s_xor_b64 s[0:1], exec, s[4:5]
	s_cbranch_execz .LBB0_128
	v_readlane_b32 s4, v245, 48
	v_readlane_b32 s5, v245, 49
	s_nop 1
	v_mov_b64_e32 v[18:19], s[4:5]
	global_atomic_add v[18:19], v165, off

; __device__ __forceinline__ unsigned xb_ld(unsigned* p) { return __hip_atomic_load(p, __ATOMIC_RELAXED, __HIP_MEMORY_SCOPE_AGENT); }
; __device__ __forceinline__ unsigned xb_add(unsigned* p, unsigned v) { return __hip_atomic_fetch_add(p, v, __ATOMIC_RELAXED, __HIP_MEMORY_SCOPE_AGENT); }
; #define XB_SPIN(cond, bar) do { unsigned _sp = 0; while (cond) { __builtin_amdgcn_s_sleep(1); \
;     if ((++_sp & 255u) == 0u) { if (xb_ld(&(bar)[XB_TMO])) break; if (_sp > XB_SPIN_CAP) { atomicAdd(&(bar)[XB_TMO], 1u); break; } } } } while (0)
; __device__ __forceinline__ void xcd_barrier(const XcdBarrier& b) {
;     ...
;     unsigned nloc = b.st[0], nx = b.st[1];
;     if (nloc == 0u) { xcd_barrier_complete(bar, bx, nloc, nx); b.st[0] = nloc; b.st[1] = nx; }
;     const unsigned old = xb_add(&bar[XB_XSUB(bx)], 1u);
;     const unsigned gen = old / nloc;
;     if (old + 1u == (gen + 1u) * nloc) {
;       __builtin_amdgcn_fence(__ATOMIC_RELEASE, "agent");
;       asm volatile("s_waitcnt vmcnt(0)" ::: "memory");
;       const unsigned og = xb_add(&bar[XB_TOP], 1u);
;       const unsigned tg = og / nx;
;       if (og + 1u == (tg + 1u) * nx) xb_add(&bar[XB_TOPGEN], 1u);
;       else XB_SPIN(xb_ld(&bar[XB_TOPGEN]) == tg, bar);
;       __builtin_amdgcn_fence(__ATOMIC_ACQUIRE, "agent");
;       xb_add(&bar[XB_XGEN(bx)], 1u);
;       asm volatile("s_waitcnt vmcnt(0)" ::: "memory");
;     } else {
;       XB_SPIN(xb_ld(&bar[XB_XGEN(bx)]) == gen, bar);
.LBB0_129:
	s_lshl_b32 s22, s33, 6
	s_add_i32 s72, s22, 0x500
	s_lshl_b64 s[0:1], s[72:73], 2
	v_readlane_b32 s4, v245, 20
	s_add_u32 s0, s4, s0
	v_readlane_b32 s4, v245, 21
	s_addc_u32 s1, s4, s1
	v_mov_b64_e32 v[4:5], s[0:1]
	global_atomic_add v4, v[4:5], v165, off sc0
	v_cvt_f32_u32_e32 v1, v2
	v_sub_u32_e32 v5, 0, v2
	v_rcp_iflag_f32_e32 v1, v1
	s_nop 0
	v_mul_f32_e32 v1, 0x4f7ffffe, v1
	v_cvt_u32_f32_e32 v1, v1
	v_mul_lo_u32 v5, v5, v1
	v_mul_hi_u32 v5, v1, v5
	v_add_u32_e32 v1, v1, v5
	s_waitcnt vmcnt(0) lgkmcnt(0)
	v_mul_hi_u32 v1, v4, v1
	v_mul_lo_u32 v5, v1, v2
	v_sub_u32_e32 v5, v4, v5
	v_cmp_ge_u32_e32 vcc, v5, v2
	v_add_u32_e32 v6, 1, v1
	s_nop 0
	v_cndmask_b32_e32 v1, v1, v6, vcc
	v_sub_u32_e32 v6, v5, v2
	v_cndmask_b32_e32 v5, v5, v6, vcc
	v_cmp_ge_u32_e32 vcc, v5, v2
	v_add_u32_e32 v5, 1, v1
	v_add_u32_e32 v6, 1, v4
	v_cndmask_b32_e32 v1, v1, v5, vcc
	v_mad_u64_u32 v[4:5], s[0:1], v2, v1, v[2:3]
	v_cmp_ne_u32_e32 vcc, v6, v4
	s_and_saveexec_b64 s[0:1], vcc
	s_xor_b64 s[0:1], exec, s[0:1]
	s_cbranch_execz .LBB0_142
	s_add_i32 s72, s22, 0x900
	s_lshl_b64 s[4:5], s[72:73], 2
	v_readlane_b32 s6, v245, 20
	s_add_u32 s6, s6, s4
	v_readlane_b32 s4, v245, 21
	s_addc_u32 s7, s4, s5
	v_mov_b64_e32 v[4:5], s[6:7]
	global_load_dword v0, v[4:5], off sc1
	s_waitcnt vmcnt(0) lgkmcnt(0)
	v_cmp_eq_u32_e32 vcc, v0, v1
	s_and_saveexec_b64 s[4:5], vcc
	s_cbranch_execz .LBB0_141
	s_mov_b32 s23, 1
	s_mov_b64 s[8:9], 0
	s_branch .LBB0_133

; __device__ __forceinline__ unsigned xb_ld(unsigned* p) { return __hip_atomic_load(p, __ATOMIC_RELAXED, __HIP_MEMORY_SCOPE_AGENT); }
; #define XB_SPIN(cond, bar) do { unsigned _sp = 0; while (cond) { __builtin_amdgcn_s_sleep(1); \
;     if ((++_sp & 255u) == 0u) { if (xb_ld(&(bar)[XB_TMO])) break; if (_sp > XB_SPIN_CAP) { atomicAdd(&(bar)[XB_TMO], 1u); break; } } } } while (0)
; __device__ __forceinline__ void xcd_barrier(const XcdBarrier& b) {
;     ...
;       XB_SPIN(xb_ld(&bar[XB_XGEN(bx)]) == gen, bar);
.LBB0_133:
	s_and_b32 s16, s23, 0xff
	s_mov_b64 s[14:15], -1
	s_cmp_lg_u32 s16, 0
	s_mov_b64 s[16:17], -1
	s_sleep 1
	s_cbranch_scc1 .LBB0_137
	v_readlane_b32 s16, v245, 48
	v_readlane_b32 s17, v245, 49
	s_mov_b64 s[18:19], -1
	s_nop 0
	v_mov_b64_e32 v[4:5], s[16:17]
	global_load_dword v0, v[4:5], off sc1
	s_mov_b64 s[16:17], 0
	s_waitcnt vmcnt(0) lgkmcnt(0)
	v_cmp_eq_u32_e32 vcc, 0, v0
	s_and_saveexec_b64 s[20:21], vcc
	s_cmp_lt_u32 s23, 0x100001
	s_cselect_b64 s[16:17], -1, 0
	s_xor_b64 s[18:19], exec, -1
	s_and_b64 s[16:17], s[16:17], exec
	s_or_b64 exec, exec, s[20:21]
.LBB0_137:
	s_andn2_b64 s[12:13], s[12:13], exec
	s_and_b64 s[18:19], s[18:19], exec
	s_or_b64 s[12:13], s[12:13], s[18:19]
	s_and_saveexec_b64 s[18:19], s[16:17]
	s_cbranch_execz .LBB0_132
	v_mov_b64_e32 v[4:5], s[6:7]
	global_load_dword v0, v[4:5], off sc1
	s_add_i32 s23, s23, 1
	s_or_b64 s[12:13], s[12:13], exec
	s_waitcnt vmcnt(0) lgkmcnt(0)
	v_cmp_ne_u32_e32 vcc, v0, v1
	s_orn2_b64 s[14:15], vcc, exec
	s_branch .LBB0_132
.LBB0_139:
	s_or_b64 exec, exec, s[8:9]
	s_xor_b64 s[6:7], s[10:11], -1
	s_and_saveexec_b64 s[8:9], s[6:7]
	s_xor_b64 s[8:9], exec, s[8:9]
	s_cbranch_execz .LBB0_141
	v_readlane_b32 s6, v245, 48
	v_readlane_b32 s7, v245, 49
	s_nop 1
	v_mov_b64_e32 v[0:1], s[6:7]
	global_atomic_add v[0:1], v165, off

; __device__ __forceinline__ unsigned xb_ld(unsigned* p) { return __hip_atomic_load(p, __ATOMIC_RELAXED, __HIP_MEMORY_SCOPE_AGENT); }
; __device__ __forceinline__ unsigned xb_add(unsigned* p, unsigned v) { return __hip_atomic_fetch_add(p, v, __ATOMIC_RELAXED, __HIP_MEMORY_SCOPE_AGENT); }
; #define XB_SPIN(cond, bar) do { unsigned _sp = 0; while (cond) { __builtin_amdgcn_s_sleep(1); \
;     if ((++_sp & 255u) == 0u) { if (xb_ld(&(bar)[XB_TMO])) break; if (_sp > XB_SPIN_CAP) { atomicAdd(&(bar)[XB_TMO], 1u); break; } } } } while (0)
; __device__ __forceinline__ void xcd_barrier(const XcdBarrier& b) {
;     ...
;     if (old + 1u == (gen + 1u) * nloc) {
;       __builtin_amdgcn_fence(__ATOMIC_RELEASE, "agent");
;       asm volatile("s_waitcnt vmcnt(0)" ::: "memory");
;       const unsigned og = xb_add(&bar[XB_TOP], 1u);
;       const unsigned tg = og / nx;
;       if (og + 1u == (tg + 1u) * nx) xb_add(&bar[XB_TOPGEN], 1u);
;       else XB_SPIN(xb_ld(&bar[XB_TOPGEN]) == tg, bar);
.LBB0_142:
	s_andn2_saveexec_b64 s[0:1], s[0:1]
	s_cbranch_execz .LBB0_158
	v_readlane_b32 s0, v245, 50
	v_readlane_b32 s1, v245, 51
	buffer_wbl2 sc1
	s_waitcnt vmcnt(0)
	v_cvt_f32_u32_e32 v2, v0
	v_mov_b64_e32 v[4:5], s[0:1]
	global_atomic_add v1, v[4:5], v165, off sc0
	v_sub_u32_e32 v4, 0, v0
	v_rcp_iflag_f32_e32 v2, v2
	s_mov_b64 s[4:5], -1
	v_mul_f32_e32 v2, 0x4f7ffffe, v2
	v_cvt_u32_f32_e32 v2, v2
	v_mul_lo_u32 v4, v4, v2
	v_mul_hi_u32 v4, v2, v4
	v_add_u32_e32 v2, v2, v4
	s_waitcnt vmcnt(0) lgkmcnt(0)
	v_mul_hi_u32 v2, v1, v2
	v_mul_lo_u32 v4, v2, v0
	v_sub_u32_e32 v4, v1, v4
	v_cmp_ge_u32_e32 vcc, v4, v0
	v_add_u32_e32 v5, 1, v2
	s_nop 0
	v_cndmask_b32_e32 v2, v2, v5, vcc
	v_sub_u32_e32 v5, v4, v0
	v_cndmask_b32_e32 v4, v4, v5, vcc
	v_cmp_ge_u32_e32 vcc, v4, v0
	v_add_u32_e32 v4, 1, v2
	s_nop 0
	v_cndmask_b32_e32 v2, v2, v4, vcc
	v_add_u32_e32 v4, 1, v1
	v_mad_u64_u32 v[0:1], s[0:1], v0, v2, v[0:1]
	v_readlane_b32 s0, v245, 52
	v_readlane_b32 s1, v245, 53
	v_cmp_ne_u32_e32 vcc, v4, v0
	s_nop 0
	v_mov_b64_e32 v[0:1], s[0:1]
	s_and_saveexec_b64 s[0:1], vcc
	s_cbranch_execz .LBB0_155
	v_readlane_b32 s4, v245, 52
	v_readlane_b32 s5, v245, 53
	s_mov_b64 s[6:7], 0
	s_nop 0
	v_mov_b64_e32 v[0:1], s[4:5]
	global_load_dword v0, v[0:1], off sc1
	s_waitcnt vmcnt(0) lgkmcnt(0)
	v_cmp_eq_u32_e32 vcc, v0, v2
	s_and_saveexec_b64 s[4:5], vcc
	s_cbranch_execz .LBB0_154
	s_mov_b32 s18, 1
	s_branch .LBB0_147

; __device__ __forceinline__ unsigned xb_ld(unsigned* p) { return __hip_atomic_load(p, __ATOMIC_RELAXED, __HIP_MEMORY_SCOPE_AGENT); }
; #define XB_SPIN(cond, bar) do { unsigned _sp = 0; while (cond) { __builtin_amdgcn_s_sleep(1); \
;     if ((++_sp & 255u) == 0u) { if (xb_ld(&(bar)[XB_TMO])) break; if (_sp > XB_SPIN_CAP) { atomicAdd(&(bar)[XB_TMO], 1u); break; } } } } while (0)
; __device__ __forceinline__ void xcd_barrier(const XcdBarrier& b) {
;     ...
;       else XB_SPIN(xb_ld(&bar[XB_TOPGEN]) == tg, bar);
.LBB0_149:
	v_readlane_b32 s12, v245, 48
	v_readlane_b32 s13, v245, 49
	s_mov_b64 s[14:15], 0
	s_nop 0
	v_mov_b64_e32 v[0:1], s[12:13]
	global_load_dword v0, v[0:1], off sc1
	s_mov_b64 s[12:13], -1
	s_waitcnt vmcnt(0) lgkmcnt(0)
	v_cmp_eq_u32_e32 vcc, 0, v0
	s_and_saveexec_b64 s[16:17], vcc
	s_cmp_lt_u32 s18, 0x100001
	s_cselect_b64 s[14:15], -1, 0
	s_xor_b64 s[12:13], exec, -1
	s_and_b64 s[14:15], s[14:15], exec
	s_or_b64 exec, exec, s[16:17]
	s_and_saveexec_b64 s[16:17], s[14:15]
	s_cbranch_execz .LBB0_146
.LBB0_152:
	v_readlane_b32 s10, v245, 52
	v_readlane_b32 s11, v245, 53
	s_add_i32 s18, s18, 1
	s_or_b64 s[12:13], s[12:13], exec
	v_mov_b64_e32 v[0:1], s[10:11]
	global_load_dword v0, v[0:1], off sc1
	s_waitcnt vmcnt(0) lgkmcnt(0)
	v_cmp_ne_u32_e32 vcc, v0, v2
	s_orn2_b64 s[10:11], vcc, exec
	s_branch .LBB0_146

; __device__ __forceinline__ unsigned xb_add(unsigned* p, unsigned v) { return __hip_atomic_fetch_add(p, v, __ATOMIC_RELAXED, __HIP_MEMORY_SCOPE_AGENT); }
; __device__ __forceinline__ void xcd_barrier(const XcdBarrier& b) {
;     ...
;       if (og + 1u == (tg + 1u) * nx) xb_add(&bar[XB_TOPGEN], 1u);
.LBB0_155:
	s_or_b64 exec, exec, s[0:1]
	s_and_saveexec_b64 s[0:1], s[4:5]
	s_cbranch_execz .LBB0_157
	global_atomic_add v[0:1], v165, off

; __device__ __forceinline__ float siluf_(float x) { return x * __builtin_amdgcn_rcpf(1.0f + __expf(-x)); }
; __device__ void conv_prepass(const Params& p, int layer) {
;     ...
; #pragma unroll
;     for (int o = 0; o < 8; ++o) {
;       float y[8];
; #pragma unroll
;       for (int k = 0; k < 8; ++k) y[k] = bv[k];
; #pragma unroll
;       for (int j = 0; j < 4; ++j) {
;         float f[8];
;         unpack8(R[o + j], f);
; #pragma unroll
;         for (int k = 0; k < 8; ++k) y[k] += wv[j][k] * f[k];
;       }
;       u32x4 r;
;       r.x = pack2(siluf_(y[0]), siluf_(y[1])); r.y = pack2(siluf_(y[2]), siluf_(y[3]));
;       r.z = pack2(siluf_(y[4]), siluf_(y[5])); r.w = pack2(siluf_(y[6]), siluf_(y[7]));
;       *(u32x4*)(dst + (long)o * dld) = r;
.LBB0_160:
	s_or_b64 exec, exec, s[8:9]
	s_waitcnt vmcnt(0)
	v_mov_b32_e32 v1, v20
	s_waitcnt lgkmcnt(0)
	v_and_b32_e32 v99, 0xffff0000, v64
	v_and_b32_e32 v98, 0xffff0000, v60
	v_mov_b32_e32 v20, v85
	v_lshlrev_b32_e32 v97, 16, v64
	v_lshlrev_b32_e32 v96, 16, v60
	v_mov_b32_e32 v0, v84
	v_pk_mul_f32 v[84:85], v[20:21], v[98:99]
	v_pk_mul_f32 v[92:93], v[0:1], v[96:97]
	v_add_f32_e32 v60, v85, v29
	v_add_f32_e32 v2, v93, v28
	v_add_f32_e32 v91, v84, v60
	v_lshlrev_b32_e32 v100, 16, v61
	v_lshlrev_b32_e32 v101, 16, v65
	v_mov_b32_e32 v84, v86
	v_mov_b32_e32 v85, v22
	v_add_f32_e32 v2, v92, v2
	v_pk_mul_f32 v[92:93], v[84:85], v[100:101]
	v_and_b32_e32 v103, 0xffff0000, v65
	v_add_f32_e32 v22, v93, v30
	v_add_f32_e32 v97, v92, v22
	v_and_b32_e32 v102, 0xffff0000, v61
	v_mov_b32_e32 v22, v87
	v_pk_mul_f32 v[60:61], v[22:23], v[102:103]
	v_lshlrev_b32_e32 v105, 16, v66
	v_add_f32_e32 v61, v61, v31
	v_add_f32_e32 v101, v60, v61
	v_lshlrev_b32_e32 v104, 16, v62
	v_mov_b32_e32 v60, v80
	v_mov_b32_e32 v61, v16
	v_pk_mul_f32 v[64:65], v[60:61], v[104:105]
	v_and_b32_e32 v107, 0xffff0000, v66
	v_add_f32_e32 v16, v65, v24
	v_add_f32_e32 v105, v64, v16
	v_and_b32_e32 v106, 0xffff0000, v62
	v_mov_b32_e32 v16, v81
	v_pk_mul_f32 v[64:65], v[16:17], v[106:107]
	v_lshlrev_b32_e32 v108, 16, v63
	v_add_f32_e32 v62, v65, v25
	v_add_f32_e32 v114, v64, v62
	v_lshlrev_b32_e32 v109, 16, v67
	v_mov_b32_e32 v64, v82
	v_mov_b32_e32 v65, v18
	v_pk_mul_f32 v[80:81], v[64:65], v[108:109]
	v_and_b32_e32 v111, 0xffff0000, v67
	v_add_f32_e32 v18, v81, v26
	v_add_f32_e32 v109, v80, v18
	v_and_b32_e32 v110, 0xffff0000, v63
	v_mov_b32_e32 v18, v83
	v_pk_mul_f32 v[62:63], v[18:19], v[110:111]
	v_lshlrev_b32_e32 v93, 16, v56
	v_add_f32_e32 v63, v63, v27
	v_add_f32_e32 v115, v62, v63
	v_lshlrev_b32_e32 v92, 16, v68
	v_mov_b32_e32 v62, v76
	v_mov_b32_e32 v63, v12
	v_pk_mul_f32 v[66:67], v[62:63], v[92:93]
	v_and_b32_e32 v87, 0xffff0000, v56
	v_add_f32_e32 v2, v67, v2
	v_and_b32_e32 v86, 0xffff0000, v68
	v_mov_b32_e32 v12, v77
	v_add_f32_e32 v2, v66, v2
	v_pk_mul_f32 v[66:67], v[12:13], v[86:87]
	v_lshlrev_b32_e32 v95, 16, v57
	v_add_f32_e32 v56, v67, v91
	v_add_f32_e32 v91, v66, v56
	v_lshlrev_b32_e32 v94, 16, v69
	v_mov_b32_e32 v66, v78
	v_mov_b32_e32 v67, v14
	v_pk_mul_f32 v[76:77], v[66:67], v[94:95]
	v_and_b32_e32 v83, 0xffff0000, v57
	v_add_f32_e32 v14, v77, v97
	v_add_f32_e32 v97, v76, v14
	v_and_b32_e32 v82, 0xffff0000, v69
	v_mov_b32_e32 v14, v79
	v_pk_mul_f32 v[56:57], v[14:15], v[82:83]
	v_lshlrev_b32_e32 v77, 16, v58
	v_add_f32_e32 v57, v57, v101
	v_add_f32_e32 v101, v56, v57
	v_lshlrev_b32_e32 v76, 16, v70
	v_mov_b32_e32 v56, v72
	v_mov_b32_e32 v57, v4
	v_pk_mul_f32 v[68:69], v[56:57], v[76:77]
	v_and_b32_e32 v81, 0xffff0000, v58
	v_add_f32_e32 v4, v69, v105
	v_add_f32_e32 v105, v68, v4
	v_and_b32_e32 v80, 0xffff0000, v70
	v_mov_b32_e32 v4, v73
	v_pk_mul_f32 v[68:69], v[4:5], v[80:81]
	v_lshlrev_b32_e32 v79, 16, v59
	v_add_f32_e32 v58, v69, v114
	v_add_f32_e32 v70, v68, v58
	v_lshlrev_b32_e32 v78, 16, v71
	v_mov_b32_e32 v68, v74
	v_mov_b32_e32 v69, v6
	v_pk_mul_f32 v[72:73], v[68:69], v[78:79]
	v_readlane_b32 s8, v245, 55
	v_add_f32_e32 v6, v73, v109
	v_add_f32_e32 v74, v72, v6
	v_and_b32_e32 v73, 0xffff0000, v59
	v_and_b32_e32 v72, 0xffff0000, v71
	v_mov_b32_e32 v6, v75
	v_pk_mul_f32 v[58:59], v[6:7], v[72:73]
	v_lshlrev_b32_e32 v71, 16, v48
	v_add_f32_e32 v59, v59, v115
	v_add_f32_e32 v58, v58, v59
	v_mul_f32_e32 v59, 0xbfb8aa3b, v2
	v_exp_f32_e32 v59, v59
	v_add_u32_e32 v112, s8, v112
	s_mov_b32 s8, 0xbffff
	v_cmp_lt_i32_e32 vcc, s8, v112
	v_add_f32_e32 v59, 1.0, v59
	v_rcp_f32_e32 v59, v59
	v_add_u32_e32 v113, s20, v113
	s_or_b64 s[14:15], vcc, s[14:15]
	v_mul_f32_e32 v2, v2, v59
	v_mul_f32_e32 v59, 0xbfb8aa3b, v91
	v_exp_f32_e32 v59, v59
	s_nop 0
	v_add_f32_e32 v59, 1.0, v59
	v_rcp_f32_e32 v59, v59
	s_nop 0
	v_mul_f32_e32 v59, v91, v59
	v_cvt_pk_bf16_f32 v114, v2, v59
	v_mul_f32_e32 v59, 0xbfb8aa3b, v101
	v_mul_f32_e32 v2, 0xbfb8aa3b, v97
	v_exp_f32_e32 v59, v59
	v_exp_f32_e32 v2, v2
	v_add_f32_e32 v59, 1.0, v59
	v_add_f32_e32 v2, 1.0, v2
	v_rcp_f32_e32 v59, v59
	v_rcp_f32_e32 v2, v2
	v_mul_f32_e32 v59, v101, v59
	v_mul_f32_e32 v2, v97, v2
	v_cvt_pk_bf16_f32 v115, v2, v59
	v_mul_f32_e32 v59, 0xbfb8aa3b, v70
	v_mul_f32_e32 v2, 0xbfb8aa3b, v105
	v_exp_f32_e32 v59, v59
	v_exp_f32_e32 v2, v2
	v_add_f32_e32 v59, 1.0, v59
	v_add_f32_e32 v2, 1.0, v2
	v_rcp_f32_e32 v59, v59
	v_rcp_f32_e32 v2, v2
	v_mul_f32_e32 v59, v70, v59
	v_mul_f32_e32 v2, v105, v2
	v_cvt_pk_bf16_f32 v116, v2, v59
	v_mul_f32_e32 v59, 0xbfb8aa3b, v58
	v_mul_f32_e32 v2, 0xbfb8aa3b, v74
	v_exp_f32_e32 v59, v59
	v_exp_f32_e32 v2, v2
	v_lshlrev_b32_e32 v70, 16, v52
	v_add_f32_e32 v59, 1.0, v59
	v_add_f32_e32 v2, 1.0, v2
	v_rcp_f32_e32 v59, v59
	v_rcp_f32_e32 v2, v2
	v_mul_f32_e32 v58, v58, v59
	v_mul_f32_e32 v2, v74, v2
	v_cvt_pk_bf16_f32 v117, v2, v58
	v_pk_mov_b32 v[58:59], v[92:93], v[96:97] op_sel:[1,0]
	global_store_dwordx4 v[88:89], v[114:117], off
	v_pk_mul_f32 v[58:59], v[0:1], v[58:59]
	s_nop 0
	v_add_f32_e32 v2, v59, v28
	v_add_f32_e32 v74, v58, v2
	v_pk_mov_b32 v[58:59], v[86:87], v[98:99] op_sel:[1,0]
	s_nop 0
	v_pk_mul_f32 v[58:59], v[20:21], v[58:59]
	s_nop 0
	v_add_f32_e32 v2, v59, v29
	v_add_f32_e32 v96, v58, v2
	v_pk_mov_b32 v[58:59], v[94:95], v[100:101] op_sel:[1,0]
	s_nop 0
	v_pk_mul_f32 v[58:59], v[84:85], v[58:59]
	s_nop 0
	v_add_f32_e32 v2, v59, v30
	v_add_f32_e32 v97, v58, v2
	v_pk_mov_b32 v[58:59], v[82:83], v[102:103] op_sel:[1,0]
	s_nop 0
	v_pk_mul_f32 v[58:59], v[22:23], v[58:59]
	s_nop 0
	v_add_f32_e32 v2, v59, v31
	v_add_f32_e32 v98, v58, v2
; __device__ __forceinline__ float siluf_(float x) { return x * __builtin_amdgcn_rcpf(1.0f + __expf(-x)); }
; __device__ void conv_prepass(const Params& p, int layer) {
;     ...
; #pragma unroll
;     for (int o = 0; o < 8; ++o) {
;       float y[8];
; #pragma unroll
;       for (int k = 0; k < 8; ++k) y[k] = bv[k];
; #pragma unroll
;       for (int j = 0; j < 4; ++j) {
;         float f[8];
;         unpack8(R[o + j], f);
; #pragma unroll
;         for (int k = 0; k < 8; ++k) y[k] += wv[j][k] * f[k];
;       }
;       u32x4 r;
;       r.x = pack2(siluf_(y[0]), siluf_(y[1])); r.y = pack2(siluf_(y[2]), siluf_(y[3]));
;       r.z = pack2(siluf_(y[4]), siluf_(y[5])); r.w = pack2(siluf_(y[6]), siluf_(y[7]));
;       *(u32x4*)(dst + (long)o * dld) = r;
	v_pk_mov_b32 v[58:59], v[76:77], v[104:105] op_sel:[1,0]
	s_nop 0
	v_pk_mul_f32 v[58:59], v[60:61], v[58:59]
	s_nop 0
	v_add_f32_e32 v2, v59, v24
	v_add_f32_e32 v99, v58, v2
	v_pk_mov_b32 v[58:59], v[80:81], v[106:107] op_sel:[1,0]
	s_nop 0
	v_pk_mul_f32 v[58:59], v[16:17], v[58:59]
	s_nop 0
	v_add_f32_e32 v2, v59, v25
	v_add_f32_e32 v100, v58, v2
	v_pk_mov_b32 v[58:59], v[78:79], v[108:109] op_sel:[1,0]
	s_nop 0
	v_pk_mul_f32 v[58:59], v[64:65], v[58:59]
	s_nop 0
	v_add_f32_e32 v2, v59, v26
	v_add_f32_e32 v102, v58, v2
	v_pk_mov_b32 v[58:59], v[72:73], v[110:111] op_sel:[1,0]
	s_nop 0
	v_pk_mul_f32 v[58:59], v[18:19], v[58:59]
	s_nop 0
	v_add_f32_e32 v2, v59, v27
	v_add_f32_e32 v103, v58, v2
	v_pk_mul_f32 v[58:59], v[0:1], v[92:93]
	v_lshlrev_b32_e32 v2, 1, v90
	v_add_f32_e32 v59, v59, v28
	v_add_f32_e32 v75, v58, v59
	v_pk_mul_f32 v[58:59], v[20:21], v[86:87]
	v_pk_mov_b32 v[90:91], v[70:71], v[92:93] op_sel:[1,0]
	v_add_f32_e32 v59, v59, v29
	v_add_f32_e32 v101, v58, v59
	v_pk_mul_f32 v[58:59], v[84:85], v[94:95]
	v_lshl_add_u64 v[88:89], v[88:89], 0, v[2:3]
	v_add_f32_e32 v59, v59, v30
	v_add_f32_e32 v104, v58, v59
	v_pk_mul_f32 v[58:59], v[22:23], v[82:83]
	s_nop 0
	v_add_f32_e32 v59, v59, v31
	v_add_f32_e32 v105, v58, v59
	v_pk_mul_f32 v[58:59], v[60:61], v[76:77]
	s_nop 0
	v_add_f32_e32 v59, v59, v24
	v_add_f32_e32 v106, v58, v59
	v_pk_mul_f32 v[58:59], v[16:17], v[80:81]
	s_nop 0
	v_add_f32_e32 v59, v59, v25
	v_add_f32_e32 v107, v58, v59
	v_pk_mul_f32 v[58:59], v[64:65], v[78:79]
	s_nop 0
	v_add_f32_e32 v59, v59, v26
	v_add_f32_e32 v108, v58, v59
	v_pk_mul_f32 v[58:59], v[18:19], v[72:73]
	s_nop 0
	v_add_f32_e32 v59, v59, v27
	v_add_f32_e32 v109, v58, v59
	v_pk_mul_f32 v[58:59], v[62:63], v[90:91]
	s_nop 0
	v_add_f32_e32 v59, v59, v74
	v_add_f32_e32 v58, v58, v59
	v_mul_f32_e32 v59, 0xbfb8aa3b, v58
	v_exp_f32_e32 v59, v59
	s_nop 0
	v_add_f32_e32 v59, 1.0, v59
	v_rcp_f32_e32 v59, v59
	s_nop 0
	v_mul_f32_e32 v110, v58, v59
	v_pk_mul_f32 v[58:59], v[62:63], v[70:71]
	s_nop 0
	v_add_f32_e32 v59, v59, v75
	v_add_f32_e32 v111, v58, v59
	v_and_b32_e32 v59, 0xffff0000, v48
	v_and_b32_e32 v58, 0xffff0000, v52
	v_pk_mov_b32 v[92:93], v[58:59], v[86:87] op_sel:[1,0]
	v_lshlrev_b32_e32 v87, 16, v49
	v_pk_mul_f32 v[74:75], v[12:13], v[92:93]
	v_lshlrev_b32_e32 v86, 16, v53
	v_add_f32_e32 v48, v75, v96
	v_add_f32_e32 v48, v74, v48
	v_mul_f32_e32 v52, 0xbfb8aa3b, v48
	v_exp_f32_e32 v52, v52
	v_pk_mul_f32 v[74:75], v[12:13], v[58:59]
	v_pk_mov_b32 v[94:95], v[86:87], v[94:95] op_sel:[1,0]
	v_add_f32_e32 v52, 1.0, v52
	v_rcp_f32_e32 v52, v52
	s_nop 0
	v_mul_f32_e32 v48, v48, v52
	v_add_f32_e32 v52, v75, v101
	v_cvt_pk_bf16_f32 v48, v110, v48
	v_add_f32_e32 v110, v74, v52
	v_pk_mul_f32 v[74:75], v[66:67], v[94:95]
	s_nop 0
	v_add_f32_e32 v52, v75, v97
	v_add_f32_e32 v52, v74, v52
	v_mul_f32_e32 v74, 0xbfb8aa3b, v52
	v_exp_f32_e32 v74, v74
	s_nop 0
	v_add_f32_e32 v74, 1.0, v74
	v_rcp_f32_e32 v74, v74
	s_nop 0
	v_mul_f32_e32 v96, v52, v74
	v_pk_mul_f32 v[74:75], v[66:67], v[86:87]
	s_nop 0
	v_add_f32_e32 v52, v75, v104
	v_add_f32_e32 v104, v74, v52
	v_and_b32_e32 v75, 0xffff0000, v49
	v_and_b32_e32 v74, 0xffff0000, v53
	v_pk_mov_b32 v[52:53], v[74:75], v[82:83] op_sel:[1,0]
	s_nop 0
	v_pk_mul_f32 v[82:83], v[14:15], v[52:53]
	s_nop 0
	v_add_f32_e32 v49, v83, v98
	v_add_f32_e32 v49, v82, v49
	v_mul_f32_e32 v82, 0xbfb8aa3b, v49
	v_exp_f32_e32 v82, v82
	s_nop 0
	v_add_f32_e32 v82, 1.0, v82
	v_rcp_f32_e32 v82, v82
	s_nop 0
	v_mul_f32_e32 v49, v49, v82
	v_pk_mul_f32 v[82:83], v[14:15], v[74:75]
	v_cvt_pk_bf16_f32 v49, v96, v49
	s_nop 0
	v_add_f32_e32 v83, v83, v105
	v_add_f32_e32 v105, v82, v83
	v_lshlrev_b32_e32 v83, 16, v50
	v_lshlrev_b32_e32 v82, 16, v54
	v_pk_mov_b32 v[96:97], v[82:83], v[76:77] op_sel:[1,0]
	s_nop 0
	v_pk_mul_f32 v[76:77], v[56:57], v[96:97]
	s_nop 0
	v_add_f32_e32 v77, v77, v99
	v_add_f32_e32 v76, v76, v77
	v_mul_f32_e32 v77, 0xbfb8aa3b, v76
	v_exp_f32_e32 v77, v77
	s_nop 0
	v_add_f32_e32 v77, 1.0, v77
	v_rcp_f32_e32 v77, v77
	s_nop 0
	v_mul_f32_e32 v101, v76, v77
	v_pk_mul_f32 v[76:77], v[56:57], v[82:83]
	s_nop 0
	v_add_f32_e32 v77, v77, v106
	v_add_f32_e32 v106, v76, v77
	v_and_b32_e32 v77, 0xffff0000, v50
	v_and_b32_e32 v76, 0xffff0000, v54
	v_pk_mov_b32 v[98:99], v[76:77], v[80:81] op_sel:[1,0]
	s_nop 0
	v_pk_mul_f32 v[80:81], v[4:5], v[98:99]
	s_nop 0
	v_add_f32_e32 v50, v81, v100
	v_add_f32_e32 v50, v80, v50
	v_mul_f32_e32 v54, 0xbfb8aa3b, v50
	v_exp_f32_e32 v54, v54
	v_pk_mul_f32 v[80:81], v[4:5], v[76:77]
	v_add_f32_e32 v54, 1.0, v54
	v_rcp_f32_e32 v54, v54
	s_nop 0
	v_mul_f32_e32 v50, v50, v54
	v_add_f32_e32 v54, v81, v107
	v_add_f32_e32 v107, v80, v54
	v_lshlrev_b32_e32 v81, 16, v51
	v_lshlrev_b32_e32 v80, 16, v55
	v_cvt_pk_bf16_f32 v50, v101, v50
	v_pk_mov_b32 v[100:101], v[80:81], v[78:79] op_sel:[1,0]
	s_nop 0
	v_pk_mul_f32 v[78:79], v[68:69], v[100:101]
	s_nop 0
	v_add_f32_e32 v54, v79, v102
	v_add_f32_e32 v54, v78, v54
	v_mul_f32_e32 v78, 0xbfb8aa3b, v54
	v_exp_f32_e32 v78, v78
	s_nop 0
	v_add_f32_e32 v78, 1.0, v78
	v_rcp_f32_e32 v78, v78
	s_nop 0
	v_mul_f32_e32 v102, v54, v78
	v_pk_mul_f32 v[78:79], v[68:69], v[80:81]
	s_nop 0
	v_add_f32_e32 v54, v79, v108
	v_add_f32_e32 v108, v78, v54
	v_and_b32_e32 v79, 0xffff0000, v51
	v_and_b32_e32 v78, 0xffff0000, v55
	v_pk_mov_b32 v[54:55], v[78:79], v[72:73] op_sel:[1,0]
	s_nop 0
	v_pk_mul_f32 v[72:73], v[6:7], v[54:55]
	s_nop 0
	v_add_f32_e32 v51, v73, v103
	v_add_f32_e32 v51, v72, v51
	v_mul_f32_e32 v72, 0xbfb8aa3b, v51
	v_exp_f32_e32 v72, v72
	s_nop 0
	v_add_f32_e32 v72, 1.0, v72
	v_rcp_f32_e32 v72, v72
	s_nop 0
	v_mul_f32_e32 v51, v51, v72
	v_cvt_pk_bf16_f32 v51, v102, v51
; __device__ __forceinline__ float siluf_(float x) { return x * __builtin_amdgcn_rcpf(1.0f + __expf(-x)); }
; __device__ void conv_prepass(const Params& p, int layer) {
;     ...
; #pragma unroll
;     for (int o = 0; o < 8; ++o) {
;       float y[8];
; #pragma unroll
;       for (int k = 0; k < 8; ++k) y[k] = bv[k];
; #pragma unroll
;       for (int j = 0; j < 4; ++j) {
;         float f[8];
;         unpack8(R[o + j], f);
; #pragma unroll
;         for (int k = 0; k < 8; ++k) y[k] += wv[j][k] * f[k];
;       }
;       u32x4 r;
;       r.x = pack2(siluf_(y[0]), siluf_(y[1])); r.y = pack2(siluf_(y[2]), siluf_(y[3]));
;       r.z = pack2(siluf_(y[4]), siluf_(y[5])); r.w = pack2(siluf_(y[6]), siluf_(y[7]));
;       *(u32x4*)(dst + (long)o * dld) = r;
	global_store_dwordx4 v[88:89], v[48:51], off
	v_pk_mul_f32 v[72:73], v[6:7], v[78:79]
	s_nop 0
	v_mul_f32_e32 v48, 0xbfb8aa3b, v111
	v_mul_f32_e32 v49, 0xbfb8aa3b, v110
	v_exp_f32_e32 v48, v48
	v_exp_f32_e32 v49, v49
	v_mul_f32_e32 v50, 0xbfb8aa3b, v105
	v_exp_f32_e32 v50, v50
	v_add_f32_e32 v48, 1.0, v48
	v_add_f32_e32 v49, 1.0, v49
	v_rcp_f32_e32 v48, v48
	v_rcp_f32_e32 v49, v49
	v_add_f32_e32 v50, 1.0, v50
	v_rcp_f32_e32 v50, v50
	v_mul_f32_e32 v48, v111, v48
	v_mul_f32_e32 v49, v110, v49
	v_cvt_pk_bf16_f32 v48, v48, v49
	v_mul_f32_e32 v49, 0xbfb8aa3b, v104
	v_exp_f32_e32 v49, v49
	v_add_f32_e32 v73, v73, v109
	v_mul_f32_e32 v50, v105, v50
	v_add_f32_e32 v51, v72, v73
	v_add_f32_e32 v49, 1.0, v49
	v_rcp_f32_e32 v49, v49
	v_mul_f32_e32 v72, 0xbfb8aa3b, v107
	v_exp_f32_e32 v72, v72
	v_mul_f32_e32 v73, 0xbfb8aa3b, v51
	v_mul_f32_e32 v49, v104, v49
	v_cvt_pk_bf16_f32 v49, v49, v50
	v_mul_f32_e32 v50, 0xbfb8aa3b, v106
	v_exp_f32_e32 v50, v50
	v_add_f32_e32 v72, 1.0, v72
	v_rcp_f32_e32 v72, v72
	v_exp_f32_e32 v73, v73
	v_add_f32_e32 v50, 1.0, v50
	v_rcp_f32_e32 v50, v50
	v_mul_f32_e32 v72, v107, v72
	v_add_f32_e32 v73, 1.0, v73
	v_rcp_f32_e32 v73, v73
	v_mul_f32_e32 v50, v106, v50
	v_cvt_pk_bf16_f32 v50, v50, v72
	v_mul_f32_e32 v72, 0xbfb8aa3b, v108
	v_exp_f32_e32 v72, v72
	v_mul_f32_e32 v51, v51, v73
	v_add_f32_e32 v72, 1.0, v72
	v_rcp_f32_e32 v72, v72
	s_nop 0
	v_mul_f32_e32 v72, v108, v72
	v_cvt_pk_bf16_f32 v51, v72, v51
	v_lshl_add_u64 v[72:73], v[88:89], 0, v[2:3]
	global_store_dwordx4 v[72:73], v[48:51], off
	v_lshl_add_u64 v[88:89], v[72:73], 0, v[2:3]
	v_lshlrev_b32_e32 v73, 16, v40
	v_pk_mul_f32 v[48:49], v[0:1], v[90:91]
	v_lshlrev_b32_e32 v72, 16, v44
	v_add_f32_e32 v49, v49, v28
	v_add_f32_e32 v50, v48, v49
	v_pk_mul_f32 v[48:49], v[20:21], v[92:93]
	v_pk_mov_b32 v[90:91], v[72:73], v[70:71] op_sel:[1,0]
	v_add_f32_e32 v49, v49, v29
	v_add_f32_e32 v51, v48, v49
	v_pk_mul_f32 v[48:49], v[84:85], v[94:95]
	s_nop 0
	v_add_f32_e32 v49, v49, v30
	v_add_f32_e32 v94, v48, v49
	v_pk_mul_f32 v[48:49], v[22:23], v[52:53]
	s_nop 0
	v_add_f32_e32 v49, v49, v31
	v_add_f32_e32 v52, v48, v49
	v_pk_mul_f32 v[48:49], v[60:61], v[96:97]
	s_nop 0
	v_add_f32_e32 v49, v49, v24
	v_add_f32_e32 v95, v48, v49
	v_pk_mul_f32 v[48:49], v[16:17], v[98:99]
	s_nop 0
	v_add_f32_e32 v49, v49, v25
	v_add_f32_e32 v96, v48, v49
	v_pk_mul_f32 v[48:49], v[64:65], v[100:101]
	s_nop 0
	v_add_f32_e32 v49, v49, v26
	v_add_f32_e32 v97, v48, v49
	v_pk_mul_f32 v[48:49], v[18:19], v[54:55]
	s_nop 0
	v_add_f32_e32 v49, v49, v27
	v_add_f32_e32 v98, v48, v49
	v_pk_mul_f32 v[48:49], v[0:1], v[70:71]
	v_and_b32_e32 v71, 0xffff0000, v40
	v_add_f32_e32 v49, v49, v28
	v_add_f32_e32 v53, v48, v49
	v_pk_mul_f32 v[48:49], v[20:21], v[58:59]
	v_and_b32_e32 v70, 0xffff0000, v44
	v_add_f32_e32 v49, v49, v29
	v_add_f32_e32 v54, v48, v49
	v_pk_mul_f32 v[48:49], v[84:85], v[86:87]
	v_pk_mov_b32 v[92:93], v[70:71], v[58:59] op_sel:[1,0]
	v_add_f32_e32 v49, v49, v30
	v_add_f32_e32 v55, v48, v49
	v_pk_mul_f32 v[48:49], v[22:23], v[74:75]
	v_lshlrev_b32_e32 v59, 16, v41
	v_add_f32_e32 v49, v49, v31
	v_add_f32_e32 v99, v48, v49
	v_pk_mul_f32 v[48:49], v[60:61], v[82:83]
	v_lshlrev_b32_e32 v58, 16, v45
	v_add_f32_e32 v49, v49, v24
	v_add_f32_e32 v100, v48, v49
	v_pk_mul_f32 v[48:49], v[16:17], v[76:77]
	v_pk_mov_b32 v[86:87], v[58:59], v[86:87] op_sel:[1,0]
	v_add_f32_e32 v49, v49, v25
	v_add_f32_e32 v101, v48, v49
	v_pk_mul_f32 v[48:49], v[64:65], v[80:81]
	s_nop 0
	v_add_f32_e32 v49, v49, v26
	v_add_f32_e32 v102, v48, v49
	v_pk_mul_f32 v[48:49], v[18:19], v[78:79]
	s_nop 0
	v_add_f32_e32 v49, v49, v27
	v_add_f32_e32 v103, v48, v49
	v_pk_mul_f32 v[48:49], v[62:63], v[90:91]
	s_nop 0
	v_add_f32_e32 v49, v49, v50
	v_add_f32_e32 v48, v48, v49
	v_mul_f32_e32 v49, 0xbfb8aa3b, v48
	v_exp_f32_e32 v49, v49
	s_nop 0
	v_add_f32_e32 v49, 1.0, v49
	v_rcp_f32_e32 v49, v49
	s_nop 0
	v_mul_f32_e32 v50, v48, v49
	v_pk_mul_f32 v[48:49], v[62:63], v[72:73]
	s_nop 0
	v_add_f32_e32 v49, v49, v53
	v_add_f32_e32 v104, v48, v49
	v_pk_mul_f32 v[48:49], v[12:13], v[92:93]
	v_lshlrev_b32_e32 v53, 16, v42
	v_add_f32_e32 v40, v49, v51
	v_add_f32_e32 v40, v48, v40
	v_mul_f32_e32 v44, 0xbfb8aa3b, v40
	v_exp_f32_e32 v44, v44
	v_pk_mul_f32 v[48:49], v[12:13], v[70:71]
	v_and_b32_e32 v51, 0xffff0000, v42
	v_add_f32_e32 v44, 1.0, v44
	v_rcp_f32_e32 v44, v44
	s_nop 0
	v_mul_f32_e32 v40, v40, v44
	v_add_f32_e32 v44, v49, v54
	v_add_f32_e32 v105, v48, v44
	v_pk_mul_f32 v[48:49], v[66:67], v[86:87]
	v_cvt_pk_bf16_f32 v40, v50, v40
	v_and_b32_e32 v54, 0xffff0000, v45
	v_add_f32_e32 v44, v49, v94
	v_add_f32_e32 v44, v48, v44
	v_mul_f32_e32 v48, 0xbfb8aa3b, v44
	v_exp_f32_e32 v48, v48
	s_nop 0
	v_add_f32_e32 v48, 1.0, v48
	v_rcp_f32_e32 v48, v48
	s_nop 0
	v_mul_f32_e32 v50, v44, v48
	v_pk_mul_f32 v[48:49], v[66:67], v[58:59]
	s_nop 0
	v_add_f32_e32 v44, v49, v55
	v_and_b32_e32 v55, 0xffff0000, v41
	v_pk_mov_b32 v[74:75], v[54:55], v[74:75] op_sel:[1,0]
	v_add_f32_e32 v94, v48, v44
	v_pk_mul_f32 v[44:45], v[14:15], v[74:75]
	v_lshlrev_b32_e32 v49, 16, v43
	v_add_f32_e32 v41, v45, v52
	v_add_f32_e32 v41, v44, v41
	v_mul_f32_e32 v44, 0xbfb8aa3b, v41
	v_exp_f32_e32 v44, v44
	v_lshlrev_b32_e32 v52, 16, v46
	v_pk_mov_b32 v[82:83], v[52:53], v[82:83] op_sel:[1,0]
	v_add_f32_e32 v44, 1.0, v44
	v_rcp_f32_e32 v44, v44
	s_nop 0
	v_mul_f32_e32 v41, v41, v44
	v_pk_mul_f32 v[44:45], v[14:15], v[54:55]
	v_cvt_pk_bf16_f32 v41, v50, v41
	v_and_b32_e32 v50, 0xffff0000, v46
	v_add_f32_e32 v45, v45, v99
	v_add_f32_e32 v99, v44, v45
	v_pk_mul_f32 v[44:45], v[56:57], v[82:83]
	v_pk_mov_b32 v[76:77], v[50:51], v[76:77] op_sel:[1,0]
	v_add_f32_e32 v45, v45, v95
; __device__ __forceinline__ float siluf_(float x) { return x * __builtin_amdgcn_rcpf(1.0f + __expf(-x)); }
; __device__ void conv_prepass(const Params& p, int layer) {
;     ...
; #pragma unroll
;     for (int o = 0; o < 8; ++o) {
;       float y[8];
; #pragma unroll
;       for (int k = 0; k < 8; ++k) y[k] = bv[k];
; #pragma unroll
;       for (int j = 0; j < 4; ++j) {
;         float f[8];
;         unpack8(R[o + j], f);
; #pragma unroll
;         for (int k = 0; k < 8; ++k) y[k] += wv[j][k] * f[k];
;       }
;       u32x4 r;
;       r.x = pack2(siluf_(y[0]), siluf_(y[1])); r.y = pack2(siluf_(y[2]), siluf_(y[3]));
;       r.z = pack2(siluf_(y[4]), siluf_(y[5])); r.w = pack2(siluf_(y[6]), siluf_(y[7]));
;       *(u32x4*)(dst + (long)o * dld) = r;
	v_add_f32_e32 v44, v44, v45
	v_mul_f32_e32 v45, 0xbfb8aa3b, v44
	v_exp_f32_e32 v45, v45
	s_nop 0
	v_add_f32_e32 v45, 1.0, v45
	v_rcp_f32_e32 v45, v45
	s_nop 0
	v_mul_f32_e32 v48, v44, v45
	v_pk_mul_f32 v[44:45], v[56:57], v[52:53]
	s_nop 0
	v_add_f32_e32 v45, v45, v100
	v_add_f32_e32 v95, v44, v45
	v_pk_mul_f32 v[44:45], v[4:5], v[76:77]
	s_nop 0
	v_add_f32_e32 v42, v45, v96
	v_add_f32_e32 v42, v44, v42
	v_mul_f32_e32 v44, 0xbfb8aa3b, v42
	v_exp_f32_e32 v44, v44
	s_nop 0
	v_add_f32_e32 v44, 1.0, v44
	v_rcp_f32_e32 v44, v44
	s_nop 0
	v_mul_f32_e32 v42, v42, v44
	v_pk_mul_f32 v[44:45], v[4:5], v[50:51]
	v_cvt_pk_bf16_f32 v42, v48, v42
	v_lshlrev_b32_e32 v48, 16, v47
	v_add_f32_e32 v45, v45, v101
	v_pk_mov_b32 v[80:81], v[48:49], v[80:81] op_sel:[1,0]
	v_add_f32_e32 v96, v44, v45
	v_pk_mul_f32 v[44:45], v[68:69], v[80:81]
	s_nop 0
	v_add_f32_e32 v45, v45, v97
	v_add_f32_e32 v44, v44, v45
	v_mul_f32_e32 v45, 0xbfb8aa3b, v44
	v_exp_f32_e32 v45, v45
	s_nop 0
	v_add_f32_e32 v45, 1.0, v45
	v_rcp_f32_e32 v45, v45
	s_nop 0
	v_mul_f32_e32 v97, v44, v45
	v_pk_mul_f32 v[44:45], v[68:69], v[48:49]
	s_nop 0
	v_add_f32_e32 v45, v45, v102
	v_add_f32_e32 v100, v44, v45
	v_and_b32_e32 v45, 0xffff0000, v43
	v_and_b32_e32 v44, 0xffff0000, v47
	v_pk_mov_b32 v[46:47], v[44:45], v[78:79] op_sel:[1,0]
	s_nop 0
	v_pk_mul_f32 v[78:79], v[6:7], v[46:47]
	s_nop 0
	v_add_f32_e32 v43, v79, v98
	v_add_f32_e32 v43, v78, v43
	v_mul_f32_e32 v78, 0xbfb8aa3b, v43
	v_exp_f32_e32 v78, v78
	s_nop 0
	v_add_f32_e32 v78, 1.0, v78
	v_rcp_f32_e32 v78, v78
	s_nop 0
	v_mul_f32_e32 v43, v43, v78
	v_cvt_pk_bf16_f32 v43, v97, v43
	global_store_dwordx4 v[88:89], v[40:43], off
	v_pk_mul_f32 v[78:79], v[6:7], v[44:45]
	s_nop 0
	v_mul_f32_e32 v40, 0xbfb8aa3b, v104
	v_mul_f32_e32 v41, 0xbfb8aa3b, v105
	v_exp_f32_e32 v40, v40
	v_exp_f32_e32 v41, v41
	v_mul_f32_e32 v42, 0xbfb8aa3b, v99
	v_exp_f32_e32 v42, v42
	v_add_f32_e32 v40, 1.0, v40
	v_add_f32_e32 v41, 1.0, v41
	v_rcp_f32_e32 v40, v40
	v_rcp_f32_e32 v41, v41
	v_add_f32_e32 v42, 1.0, v42
	v_rcp_f32_e32 v42, v42
	v_mul_f32_e32 v40, v104, v40
	v_mul_f32_e32 v41, v105, v41
	v_cvt_pk_bf16_f32 v40, v40, v41
	v_mul_f32_e32 v41, 0xbfb8aa3b, v94
	v_exp_f32_e32 v41, v41
	v_add_f32_e32 v79, v79, v103
	v_mul_f32_e32 v42, v99, v42
	v_add_f32_e32 v43, v78, v79
	v_add_f32_e32 v41, 1.0, v41
	v_rcp_f32_e32 v41, v41
	v_mul_f32_e32 v78, 0xbfb8aa3b, v96
	v_exp_f32_e32 v78, v78
	v_mul_f32_e32 v79, 0xbfb8aa3b, v43
	v_mul_f32_e32 v41, v94, v41
	v_cvt_pk_bf16_f32 v41, v41, v42
	v_mul_f32_e32 v42, 0xbfb8aa3b, v95
	v_exp_f32_e32 v42, v42
	v_add_f32_e32 v78, 1.0, v78
	v_rcp_f32_e32 v78, v78
	v_exp_f32_e32 v79, v79
	v_add_f32_e32 v42, 1.0, v42
	v_rcp_f32_e32 v42, v42
	v_mul_f32_e32 v78, v96, v78
	v_add_f32_e32 v79, 1.0, v79
	v_rcp_f32_e32 v79, v79
	v_mul_f32_e32 v42, v95, v42
	v_cvt_pk_bf16_f32 v42, v42, v78
	v_mul_f32_e32 v78, 0xbfb8aa3b, v100
	v_exp_f32_e32 v78, v78
	v_mul_f32_e32 v43, v43, v79
	v_add_f32_e32 v78, 1.0, v78
	v_rcp_f32_e32 v78, v78
	s_nop 0
	v_mul_f32_e32 v78, v100, v78
	v_cvt_pk_bf16_f32 v43, v78, v43
	v_lshl_add_u64 v[78:79], v[88:89], 0, v[2:3]
	global_store_dwordx4 v[78:79], v[40:43], off
	s_nop 1
	v_pk_mul_f32 v[40:41], v[0:1], v[90:91]
	v_pk_mul_f32 v[42:43], v[0:1], v[72:73]
	v_add_f32_e32 v41, v41, v28
	v_add_f32_e32 v88, v40, v41
	v_pk_mul_f32 v[40:41], v[20:21], v[92:93]
	v_add_f32_e32 v43, v43, v28
	v_add_f32_e32 v41, v41, v29
	v_add_f32_e32 v89, v40, v41
	v_pk_mul_f32 v[40:41], v[84:85], v[86:87]
	s_nop 0
	v_add_f32_e32 v41, v41, v30
	v_add_f32_e32 v86, v40, v41
	v_pk_mul_f32 v[40:41], v[22:23], v[74:75]
	v_add_f32_e32 v74, v42, v43
	v_add_f32_e32 v41, v41, v31
	v_add_f32_e32 v87, v40, v41
	v_pk_mul_f32 v[40:41], v[60:61], v[82:83]
	v_pk_mul_f32 v[42:43], v[20:21], v[70:71]
	v_add_f32_e32 v41, v41, v24
	v_add_f32_e32 v82, v40, v41
	v_pk_mul_f32 v[40:41], v[16:17], v[76:77]
	v_add_f32_e32 v43, v43, v29
	v_add_f32_e32 v41, v41, v25
	v_add_f32_e32 v83, v40, v41
	v_pk_mul_f32 v[40:41], v[64:65], v[80:81]
	v_add_f32_e32 v76, v42, v43
	v_add_f32_e32 v41, v41, v26
	v_add_f32_e32 v90, v40, v41
	v_pk_mul_f32 v[40:41], v[18:19], v[46:47]
	v_pk_mul_f32 v[42:43], v[84:85], v[58:59]
	v_add_f32_e32 v41, v41, v27
	v_add_f32_e32 v43, v43, v30
	v_add_f32_e32 v91, v40, v41
	v_lshl_add_u64 v[40:41], v[78:79], 0, v[2:3]
	v_add_f32_e32 v78, v42, v43
	v_pk_mul_f32 v[42:43], v[22:23], v[54:55]
	s_nop 0
	v_add_f32_e32 v43, v43, v31
	v_add_f32_e32 v79, v42, v43
	v_pk_mul_f32 v[42:43], v[60:61], v[52:53]
	s_nop 0
	v_add_f32_e32 v43, v43, v24
	v_add_f32_e32 v80, v42, v43
	v_pk_mul_f32 v[42:43], v[16:17], v[50:51]
	s_nop 0
	v_add_f32_e32 v43, v43, v25
	v_add_f32_e32 v92, v42, v43
	v_pk_mul_f32 v[42:43], v[64:65], v[48:49]
	s_nop 0
	v_add_f32_e32 v43, v43, v26
	v_add_f32_e32 v93, v42, v43
	v_pk_mul_f32 v[42:43], v[18:19], v[44:45]
	s_nop 0
	v_add_f32_e32 v43, v43, v27
	v_add_f32_e32 v94, v42, v43
	v_lshlrev_b32_e32 v43, 16, v32
	v_lshlrev_b32_e32 v42, 16, v36
	v_pk_mov_b32 v[46:47], v[42:43], v[72:73] op_sel:[1,0]
	s_nop 0
	v_pk_mul_f32 v[72:73], v[62:63], v[46:47]
	v_pk_mul_f32 v[0:1], v[0:1], v[46:47]
	v_add_f32_e32 v73, v73, v88
	v_add_f32_e32 v72, v72, v73
	v_mul_f32_e32 v73, 0xbfb8aa3b, v72
	v_exp_f32_e32 v73, v73
	v_add_f32_e32 v1, v1, v28
	v_add_f32_e32 v28, v0, v1
	v_add_f32_e32 v73, 1.0, v73
	v_rcp_f32_e32 v73, v73
	s_nop 0
	v_mul_f32_e32 v77, v72, v73
	v_pk_mul_f32 v[72:73], v[62:63], v[42:43]
	s_nop 0
	v_add_f32_e32 v43, v73, v74
	v_add_f32_e32 v43, v72, v43
	v_and_b32_e32 v73, 0xffff0000, v32
	v_and_b32_e32 v72, 0xffff0000, v36
	v_pk_mov_b32 v[70:71], v[72:73], v[70:71] op_sel:[1,0]
	s_nop 0
	v_pk_mul_f32 v[74:75], v[12:13], v[70:71]
; __device__ __forceinline__ float siluf_(float x) { return x * __builtin_amdgcn_rcpf(1.0f + __expf(-x)); }
; __device__ void conv_prepass(const Params& p, int layer) {
;     ...
; #pragma unroll
;     for (int o = 0; o < 8; ++o) {
;       float y[8];
; #pragma unroll
;       for (int k = 0; k < 8; ++k) y[k] = bv[k];
; #pragma unroll
;       for (int j = 0; j < 4; ++j) {
;         float f[8];
;         unpack8(R[o + j], f);
; #pragma unroll
;         for (int k = 0; k < 8; ++k) y[k] += wv[j][k] * f[k];
;       }
;       u32x4 r;
;       r.x = pack2(siluf_(y[0]), siluf_(y[1])); r.y = pack2(siluf_(y[2]), siluf_(y[3]));
;       r.z = pack2(siluf_(y[4]), siluf_(y[5])); r.w = pack2(siluf_(y[6]), siluf_(y[7]));
;       *(u32x4*)(dst + (long)o * dld) = r;
	v_pk_mul_f32 v[0:1], v[20:21], v[70:71]
	v_add_f32_e32 v32, v75, v89
	v_add_f32_e32 v32, v74, v32
	v_mul_f32_e32 v36, 0xbfb8aa3b, v32
	v_exp_f32_e32 v36, v36
	v_pk_mul_f32 v[74:75], v[12:13], v[72:73]
	v_add_f32_e32 v1, v1, v29
	v_add_f32_e32 v21, v0, v1
	v_add_f32_e32 v36, 1.0, v36
	v_rcp_f32_e32 v36, v36
	v_lshlrev_b32_e32 v20, 16, v10
	v_and_b32_e32 v10, 0xffff0000, v10
	v_mul_f32_e32 v32, v32, v36
	v_add_f32_e32 v36, v75, v76
	v_add_f32_e32 v73, v74, v36
	v_lshlrev_b32_e32 v75, 16, v33
	v_lshlrev_b32_e32 v74, 16, v37
	v_cvt_pk_bf16_f32 v32, v77, v32
	v_pk_mov_b32 v[76:77], v[74:75], v[58:59] op_sel:[1,0]
	s_nop 0
	v_pk_mul_f32 v[58:59], v[66:67], v[76:77]
	v_pk_mul_f32 v[0:1], v[84:85], v[76:77]
	v_add_f32_e32 v36, v59, v86
	v_add_f32_e32 v36, v58, v36
	v_mul_f32_e32 v58, 0xbfb8aa3b, v36
	v_exp_f32_e32 v58, v58
	v_add_f32_e32 v1, v1, v30
	v_add_f32_e32 v29, v0, v1
	v_add_f32_e32 v58, 1.0, v58
	v_rcp_f32_e32 v58, v58
	s_nop 0
	v_mul_f32_e32 v81, v36, v58
	v_pk_mul_f32 v[58:59], v[66:67], v[74:75]
	s_nop 0
	v_add_f32_e32 v36, v59, v78
	v_add_f32_e32 v75, v58, v36
	v_and_b32_e32 v59, 0xffff0000, v33
	v_and_b32_e32 v58, 0xffff0000, v37
	v_pk_mov_b32 v[36:37], v[58:59], v[54:55] op_sel:[1,0]
	s_nop 0
	v_pk_mul_f32 v[54:55], v[14:15], v[36:37]
	v_pk_mul_f32 v[0:1], v[22:23], v[36:37]
	v_add_f32_e32 v33, v55, v87
	v_add_f32_e32 v33, v54, v33
	v_mul_f32_e32 v54, 0xbfb8aa3b, v33
	v_exp_f32_e32 v54, v54
	v_add_f32_e32 v1, v1, v31
	v_add_f32_e32 v23, v0, v1
	v_lshlrev_b32_e32 v22, 16, v11
	v_add_f32_e32 v54, 1.0, v54
	v_rcp_f32_e32 v54, v54
	s_nop 0
	v_mul_f32_e32 v33, v33, v54
	v_pk_mul_f32 v[54:55], v[14:15], v[58:59]
	v_cvt_pk_bf16_f32 v33, v81, v33
	s_nop 0
	v_add_f32_e32 v55, v55, v79
	v_add_f32_e32 v59, v54, v55
	v_lshlrev_b32_e32 v55, 16, v34
	v_lshlrev_b32_e32 v54, 16, v38
	v_pk_mov_b32 v[52:53], v[54:55], v[52:53] op_sel:[1,0]
	s_nop 0
	v_pk_mul_f32 v[78:79], v[56:57], v[52:53]
	v_pk_mul_f32 v[0:1], v[60:61], v[52:53]
	v_add_f32_e32 v79, v79, v82
	v_add_f32_e32 v78, v78, v79
	v_mul_f32_e32 v79, 0xbfb8aa3b, v78
	v_exp_f32_e32 v79, v79
	v_add_f32_e32 v1, v1, v24
	v_add_f32_e32 v30, v0, v1
	v_and_b32_e32 v24, 0xffff0000, v11
	v_add_f32_e32 v79, 1.0, v79
	v_rcp_f32_e32 v79, v79
	s_nop 0
	v_mul_f32_e32 v82, v78, v79
	v_pk_mul_f32 v[78:79], v[56:57], v[54:55]
	s_nop 0
	v_add_f32_e32 v55, v79, v80
	v_add_f32_e32 v55, v78, v55
	v_and_b32_e32 v79, 0xffff0000, v34
	v_and_b32_e32 v78, 0xffff0000, v38
	v_pk_mov_b32 v[80:81], v[78:79], v[50:51] op_sel:[1,0]
	v_mov_b32_e32 v11, v78
	v_pk_mul_f32 v[50:51], v[4:5], v[80:81]
	v_pk_mul_f32 v[0:1], v[16:17], v[80:81]
	v_add_f32_e32 v34, v51, v83
	v_add_f32_e32 v34, v50, v34
	v_mul_f32_e32 v38, 0xbfb8aa3b, v34
	v_exp_f32_e32 v38, v38
	v_pk_mul_f32 v[50:51], v[4:5], v[78:79]
	v_add_f32_e32 v1, v1, v25
	v_add_f32_e32 v25, v0, v1
	v_add_f32_e32 v38, 1.0, v38
	v_rcp_f32_e32 v38, v38
	v_lshlrev_b32_e32 v16, 16, v9
	v_mov_b32_e32 v17, v74
	v_mul_f32_e32 v34, v34, v38
	v_add_f32_e32 v38, v51, v92
	v_add_f32_e32 v79, v50, v38
	v_lshlrev_b32_e32 v51, 16, v35
	v_lshlrev_b32_e32 v50, 16, v39
	v_cvt_pk_bf16_f32 v34, v82, v34
	v_pk_mov_b32 v[82:83], v[50:51], v[48:49] op_sel:[1,0]
	s_nop 0
	v_pk_mul_f32 v[48:49], v[68:69], v[82:83]
	v_pk_mul_f32 v[0:1], v[64:65], v[82:83]
	v_add_f32_e32 v38, v49, v90
	v_add_f32_e32 v38, v48, v38
	v_mul_f32_e32 v48, 0xbfb8aa3b, v38
	v_exp_f32_e32 v48, v48
	v_add_f32_e32 v1, v1, v26
	v_add_f32_e32 v26, v0, v1
	v_add_f32_e32 v48, 1.0, v48
	v_rcp_f32_e32 v48, v48
	s_nop 0
	v_mul_f32_e32 v86, v38, v48
	v_pk_mul_f32 v[48:49], v[68:69], v[50:51]
	s_nop 0
	v_add_f32_e32 v38, v49, v93
	v_add_f32_e32 v51, v48, v38
	v_and_b32_e32 v49, 0xffff0000, v35
	v_and_b32_e32 v48, 0xffff0000, v39
	v_pk_mov_b32 v[38:39], v[48:49], v[44:45] op_sel:[1,0]
	s_nop 0
	v_pk_mul_f32 v[0:1], v[18:19], v[38:39]
	v_pk_mul_f32 v[44:45], v[6:7], v[38:39]
	v_add_f32_e32 v1, v1, v27
	v_add_f32_e32 v27, v0, v1
	v_lshlrev_b32_e32 v0, 16, v8
	v_mov_b32_e32 v1, v42
	v_pk_mul_f32 v[0:1], v[62:63], v[0:1]
	v_and_b32_e32 v8, 0xffff0000, v8
	v_and_b32_e32 v18, 0xffff0000, v9
	v_add_f32_e32 v1, v1, v28
	v_mov_b32_e32 v9, v72
	v_add_f32_e32 v35, v45, v91
	v_add_f32_e32 v28, v0, v1
	v_pk_mul_f32 v[0:1], v[12:13], v[8:9]
	v_add_f32_e32 v35, v44, v35
	v_add_f32_e32 v1, v1, v21
	v_mul_f32_e32 v44, 0xbfb8aa3b, v35
	v_add_f32_e32 v8, v0, v1
	v_pk_mul_f32 v[0:1], v[66:67], v[16:17]
	v_exp_f32_e32 v44, v44
	v_add_f32_e32 v1, v1, v29
	v_mov_b32_e32 v19, v58
	v_add_f32_e32 v9, v0, v1
	v_pk_mul_f32 v[0:1], v[14:15], v[18:19]
	v_mov_b32_e32 v21, v54
	v_add_f32_e32 v1, v1, v23
	v_add_f32_e32 v12, v0, v1
	v_pk_mul_f32 v[0:1], v[56:57], v[20:21]
	v_add_f32_e32 v44, 1.0, v44
	v_add_f32_e32 v1, v1, v30
	v_rcp_f32_e32 v44, v44
	v_add_f32_e32 v13, v0, v1
	v_pk_mul_f32 v[0:1], v[4:5], v[10:11]
	v_mov_b32_e32 v23, v50
	v_add_f32_e32 v1, v1, v25
	v_add_f32_e32 v10, v0, v1
	v_pk_mul_f32 v[0:1], v[68:69], v[22:23]
	v_mov_b32_e32 v25, v48
	v_add_f32_e32 v1, v1, v26
	v_mul_f32_e32 v35, v35, v44
	v_add_f32_e32 v11, v0, v1
	v_pk_mul_f32 v[0:1], v[6:7], v[24:25]
	v_cvt_pk_bf16_f32 v35, v86, v35
	global_store_dwordx4 v[40:41], v[32:35], off
	v_add_f32_e32 v1, v1, v27
	v_add_f32_e32 v0, v0, v1
	v_mul_f32_e32 v33, 0xbfb8aa3b, v43
	v_mul_f32_e32 v34, 0xbfb8aa3b, v73
	v_exp_f32_e32 v33, v33
	v_exp_f32_e32 v34, v34
	v_mul_f32_e32 v1, 0xbfb8aa3b, v28
	v_mul_f32_e32 v4, 0xbfb8aa3b, v8
	v_exp_f32_e32 v1, v1
	v_exp_f32_e32 v4, v4
	v_add_f32_e32 v33, 1.0, v33
	v_add_f32_e32 v34, 1.0, v34
	v_rcp_f32_e32 v33, v33
	v_rcp_f32_e32 v34, v34
	v_add_f32_e32 v1, 1.0, v1
	v_add_f32_e32 v4, 1.0, v4
	v_rcp_f32_e32 v1, v1
	v_rcp_f32_e32 v4, v4
	v_mul_f32_e32 v33, v43, v33
; __device__ __forceinline__ size_t pidx(size_t row, int col) { return ((size_t)(col >> 8) * MTOK + row) * PLD + (col & 255); }
; __device__ void conv_prepass(const Params& p, int layer) {
;     ...
;   for (int u = blockIdx.x * 512 + tid; u < total; u += gridDim.x * 512) {
;     const int cgp = u % 384, rb = u / 384;
;     const int ch = cgp * 8, row0 = rb * 8, tseq = row0 & (SEQ - 1);
;     const bf16_t* src = proj + pidx(row0, ch < 2048 ? 4096 + ch : 6144 + ch);
;     u32x4 R[11];
; #pragma unroll
;     for (int i = 0; i < 11; ++i) {
;       if (tseq - 3 + i >= 0) R[i] = *(const u32x4*)(src + (long)(i - 3) * PLD);
;       else R[i] = (u32x4){0u, 0u, 0u, 0u};
;     }
;     float wv[4][8], bv[8];
; #pragma unroll
;     for (int j = 0; j < 4; ++j) {
;       const f32x4 a = *(const f32x4*)(cw + j * 3072 + ch), b2 = *(const f32x4*)(cw + j * 3072 + ch + 4);
;       wv[j][0] = a[0]; wv[j][1] = a[1]; wv[j][2] = a[2]; wv[j][3] = a[3];
;       wv[j][4] = b2[0]; wv[j][5] = b2[1]; wv[j][6] = b2[2]; wv[j][7] = b2[3];
;     }
;     {
;       const f32x4 a = *(const f32x4*)(cb + ch), b2 = *(const f32x4*)(cb + ch + 4);
;       bv[0] = a[0]; bv[1] = a[1]; bv[2] = a[2]; bv[3] = a[3]; bv[4] = b2[0]; bv[5] = b2[1]; bv[6] = b2[2]; bv[7] = b2[3];
;     }
;     bf16_t* dst = (ch < 2048) ? xconv + (size_t)row0 * DM + ch : bcconv + (size_t)row0 * 1024 + (ch - 2048);
;     const long dld = (ch < 2048) ? DM : 1024;
;     ...
;       *(u32x4*)(dst + (long)o * dld) = r;
	v_mul_f32_e32 v34, v73, v34
	v_cvt_pk_bf16_f32 v86, v33, v34
	v_mul_f32_e32 v33, 0xbfb8aa3b, v75
	v_mul_f32_e32 v34, 0xbfb8aa3b, v59
	v_mul_f32_e32 v1, v28, v1
	v_mul_f32_e32 v4, v8, v4
	v_exp_f32_e32 v33, v33
	v_exp_f32_e32 v34, v34
	v_cvt_pk_bf16_f32 v4, v1, v4
	v_mul_f32_e32 v1, 0xbfb8aa3b, v9
	v_mul_f32_e32 v5, 0xbfb8aa3b, v12
	v_exp_f32_e32 v1, v1
	v_exp_f32_e32 v5, v5
	v_add_f32_e32 v33, 1.0, v33
	v_add_f32_e32 v34, 1.0, v34
	v_rcp_f32_e32 v33, v33
	v_rcp_f32_e32 v34, v34
	v_add_f32_e32 v1, 1.0, v1
	v_add_f32_e32 v5, 1.0, v5
	v_rcp_f32_e32 v1, v1
	v_rcp_f32_e32 v5, v5
	v_mul_f32_e32 v33, v75, v33
	v_mul_f32_e32 v34, v59, v34
	v_cvt_pk_bf16_f32 v87, v33, v34
	v_mul_f32_e32 v33, 0xbfb8aa3b, v55
	v_mul_f32_e32 v34, 0xbfb8aa3b, v79
	v_mul_f32_e32 v1, v9, v1
	v_mul_f32_e32 v5, v12, v5
	v_pk_mul_f32 v[44:45], v[6:7], v[48:49]
	v_exp_f32_e32 v33, v33
	v_exp_f32_e32 v34, v34
	v_cvt_pk_bf16_f32 v5, v1, v5
	v_mul_f32_e32 v1, 0xbfb8aa3b, v13
	v_mul_f32_e32 v6, 0xbfb8aa3b, v10
	v_exp_f32_e32 v1, v1
	v_exp_f32_e32 v6, v6
	v_add_f32_e32 v33, 1.0, v33
	v_add_f32_e32 v34, 1.0, v34
	v_rcp_f32_e32 v33, v33
	v_rcp_f32_e32 v34, v34
	v_add_f32_e32 v1, 1.0, v1
	v_add_f32_e32 v6, 1.0, v6
	v_rcp_f32_e32 v1, v1
	v_rcp_f32_e32 v6, v6
	v_add_f32_e32 v45, v45, v94
	v_add_f32_e32 v32, v44, v45
	v_mul_f32_e32 v33, v55, v33
	v_mul_f32_e32 v34, v79, v34
	v_cvt_pk_bf16_f32 v88, v33, v34
	v_mul_f32_e32 v33, 0xbfb8aa3b, v51
	v_mul_f32_e32 v34, 0xbfb8aa3b, v32
	v_mul_f32_e32 v1, v13, v1
	v_mul_f32_e32 v6, v10, v6
	v_exp_f32_e32 v33, v33
	v_exp_f32_e32 v34, v34
	v_cvt_pk_bf16_f32 v6, v1, v6
	v_mul_f32_e32 v1, 0xbfb8aa3b, v11
	v_mul_f32_e32 v7, 0xbfb8aa3b, v0
	v_exp_f32_e32 v1, v1
	v_exp_f32_e32 v7, v7
	v_add_f32_e32 v33, 1.0, v33
	v_add_f32_e32 v34, 1.0, v34
	v_rcp_f32_e32 v33, v33
	v_rcp_f32_e32 v34, v34
	v_add_f32_e32 v1, 1.0, v1
	v_add_f32_e32 v7, 1.0, v7
	v_rcp_f32_e32 v1, v1
	v_rcp_f32_e32 v7, v7
	v_mul_f32_e32 v33, v51, v33
	v_mul_f32_e32 v32, v32, v34
	v_cvt_pk_bf16_f32 v89, v33, v32
	v_lshl_add_u64 v[32:33], v[40:41], 0, v[2:3]
	v_mul_f32_e32 v1, v11, v1
	v_mul_f32_e32 v0, v0, v7
	v_cvt_pk_bf16_f32 v7, v1, v0
	v_lshl_add_u64 v[0:1], v[32:33], 0, v[2:3]
	global_store_dwordx4 v[32:33], v[86:89], off
	global_store_dwordx4 v[0:1], v[4:7], off
	s_andn2_b64 exec, exec, s[14:15]
	s_cbranch_execz .LBB0_171
.LBB0_161:
	s_mov_b32 s8, 0x2aaaaaab
	v_mul_hi_i32 v0, v112, s8
	v_lshrrev_b32_e32 v1, 31, v0
	v_ashrrev_i32_e32 v0, 6, v0
	v_add_u32_e32 v1, v0, v1
	v_mul_i32_i24_e32 v0, 0x180, v1
	v_sub_u32_e32 v2, v112, v0
	s_movk_i32 s16, 0x100
	v_lshlrev_b32_e32 v0, 3, v0
	s_movk_i32 s8, 0xff
	v_cmp_gt_i32_e32 vcc, s16, v2
	v_sub_u32_e32 v0, v113, v0
	v_cmp_lt_i32_e64 s[8:9], s8, v2
	v_cndmask_b32_e32 v2, v202, v203, vcc
	v_add_u32_e32 v2, v0, v2
	v_lshlrev_b32_e32 v92, 3, v1
	v_lshrrev_b32_e32 v2, 8, v2
	v_ashrrev_i32_e32 v93, 31, v92
	v_lshlrev_b64 v[4:5], 23, v[2:3]
	v_and_b32_e32 v8, 0xf8, v0
	v_lshl_add_u64 v[4:5], s[4:5], 0, v[4:5]
	v_lshlrev_b64 v[6:7], 9, v[92:93]
	v_lshl_add_u64 v[4:5], v[4:5], 0, v[6:7]
	v_lshlrev_b32_e32 v2, 1, v8
	v_lshl_add_u64 v[4:5], v[4:5], 0, v[2:3]
	v_mov_b32_e32 v60, 0
	v_cmp_ne_u32_sdwa s[16:17], v1, v3 src0_sel:BYTE_0 src1_sel:DWORD
	v_mov_b32_e32 v64, 0
	v_mov_b32_e32 v65, 0
	v_mov_b32_e32 v66, 0
	v_mov_b32_e32 v67, 0
	s_and_saveexec_b64 s[18:19], s[16:17]
	s_cbranch_execz .LBB0_163
	v_add_co_u32_e32 v6, vcc, 0xfffffa00, v4
	s_nop 1
	v_addc_co_u32_e32 v7, vcc, -1, v5, vcc
	global_load_dwordx4 v[64:67], v[6:7], off
.LBB0_163:
	s_or_b64 exec, exec, s[18:19]
	v_mov_b32_e32 v61, 0
	v_mov_b32_e32 v62, 0
	v_mov_b32_e32 v63, 0
	s_and_saveexec_b64 s[18:19], s[16:17]
	s_cbranch_execz .LBB0_165
	v_add_co_u32_e32 v6, vcc, 0xfffffc00, v4
	s_nop 1
	v_addc_co_u32_e32 v7, vcc, -1, v5, vcc
	global_load_dwordx4 v[60:63], v[6:7], off
.LBB0_165:
	s_or_b64 exec, exec, s[18:19]
	v_mov_b32_e32 v56, 0
	v_mov_b32_e32 v57, 0
	v_mov_b32_e32 v58, 0
	v_mov_b32_e32 v59, 0
	s_and_saveexec_b64 s[18:19], s[16:17]
	s_cbranch_execz .LBB0_167
	v_add_co_u32_e32 v6, vcc, 0xfffffe00, v4
	s_nop 1
	v_addc_co_u32_e32 v7, vcc, -1, v5, vcc
	global_load_dwordx4 v[56:59], v[6:7], off
.LBB0_167:
	s_or_b64 exec, exec, s[18:19]
	v_ashrrev_i32_e32 v1, 31, v0
	v_lshlrev_b64 v[24:25], 2, v[0:1]
	v_lshl_add_u64 v[26:27], s[10:11], 0, v[24:25]
	v_add_co_u32_e32 v6, vcc, 0x3000, v26
	global_load_dwordx4 v[68:71], v[4:5], off
	global_load_dwordx4 v[48:51], v[4:5], off offset:512
	global_load_dwordx4 v[52:55], v[4:5], off offset:1024
	global_load_dwordx4 v[40:43], v[4:5], off offset:1536
	global_load_dwordx4 v[44:47], v[4:5], off offset:2048
	global_load_dwordx4 v[32:35], v[4:5], off offset:2560
	global_load_dwordx4 v[36:39], v[4:5], off offset:3072
	global_load_dwordx4 v[8:11], v[4:5], off offset:3584
	s_mov_b64 s[16:17], 0x3000
	v_addc_co_u32_e32 v7, vcc, 0, v27, vcc
	global_load_dwordx4 v[16:19], v[26:27], off offset:16
	global_load_dwordx4 v[20:23], v[26:27], off
	v_lshl_add_u64 v[4:5], v[26:27], 0, s[16:17]
	global_load_dwordx4 v[84:87], v[6:7], off
	global_load_dwordx4 v[80:83], v[4:5], off offset:16
	s_mov_b64 s[16:17], 0x6000
	v_add_co_u32_e32 v6, vcc, 0x6000, v26
	v_lshl_add_u64 v[4:5], v[26:27], 0, s[16:17]
	s_nop 0
	v_addc_co_u32_e32 v7, vcc, 0, v27, vcc
	s_mov_b64 s[16:17], 0x9000
	v_lshl_add_u64 v[28:29], v[26:27], 0, s[16:17]
	v_add_co_u32_e32 v26, vcc, 0x9000, v26
	global_load_dwordx4 v[12:15], v[6:7], off
	s_nop 0
	global_load_dwordx4 v[4:7], v[4:5], off offset:16
	v_addc_co_u32_e32 v27, vcc, 0, v27, vcc
	global_load_dwordx4 v[76:79], v[26:27], off
	global_load_dwordx4 v[72:75], v[28:29], off offset:16
	v_lshl_add_u64 v[28:29], s[12:13], 0, v[24:25]
	global_load_dwordx4 v[24:27], v[28:29], off offset:16
	s_nop 0
	global_load_dwordx4 v[28:31], v[28:29], off
	s_and_saveexec_b64 s[16:17], s[8:9]
	s_xor_b64 s[8:9], exec, s[16:17]
	v_lshlrev_b64 v[88:89], 11, v[92:93]
	v_lshl_add_u64 v[88:89], s[0:1], 0, v[88:89]
	v_mov_b32_e32 v1, v3
	v_lshl_add_u64 v[0:1], v[0:1], 1, v[88:89]
	s_mov_b64 s[16:17], 0x5b07f000
	v_lshl_add_u64 v[88:89], v[0:1], 0, s[16:17]
	s_or_saveexec_b64 s[8:9], s[8:9]
	v_mov_b64_e32 v[90:91], 0x400
	s_xor_b64 exec, exec, s[8:9]
	s_cbranch_execz .LBB0_160
	v_lshlrev_b64 v[88:89], 12, v[92:93]
	v_lshl_add_u64 v[88:89], s[6:7], 0, v[88:89]
	v_lshl_add_u64 v[88:89], v[0:1], 1, v[88:89]
	v_mov_b64_e32 v[90:91], 0x800
	s_branch .LBB0_160

; __device__ __forceinline__ float softplusf_(float x) { return x > 20.f ? x : log1pf(__expf(x)); }
; __device__ __forceinline__ float mlstm_scalars(const float (&g)[4], float ib, float fb, float m_prev, float* sc, int lane) {
;   const float i0 = g[0] + ib, i1 = g[1] + ib;
;   const float f0 = -softplusf_(-(g[2] + fb));
;   const float f1 = -softplusf_(-(g[3] + fb));
; __device__ void mlstm_item(const Params& p, int layer, int b, int hh, int q4) {
;     ...
;   if (w == 0) { mlstm_gates(small, row_b, hh, lane0, gpre); m_run = mlstm_scalars(gpre, ib, fb, 0.f, scal, lane0); mlstm_gates(small, row_b + 128, hh, lane0, gpre); }
.LBB0_182:
	s_or_b64 exec, exec, s[4:5]
	s_lshl_b32 s6, s14, 3
	s_and_b32 s4, s6, 56
	s_add_i32 s4, s4, s8
	s_ashr_i32 s8, s4, 3
	s_ashr_i32 s9, s8, 31
	s_lshl_b64 s[16:17], s[8:9], 11
	v_and_b32_e32 v6, 63, v122
	s_cmp_gt_u32 s13, 63
	s_cselect_b64 s[18:19], -1, 0
	s_cmp_lt_u32 s13, 64
	v_lshlrev_b32_e32 v124, 1, v6
	s_cbranch_scc0 .LBB0_190
	v_or_b32_e32 v0, s16, v124
	v_mov_b32_e32 v1, s17
	v_lshlrev_b64 v[0:1], 8, v[0:1]
	v_lshl_add_u64 v[0:1], s[0:1], 0, v[0:1]
	s_mov_b64 s[4:5], 0x42c80000
	v_lshl_add_u64 v[4:5], v[0:1], 0, s[4:5]
	s_lshl_b32 s72, s12, 2
	v_lshl_add_u64 v[10:11], v[4:5], 0, s[72:73]
	global_load_dword v2, v[10:11], off offset:160
	global_load_dword v7, v[10:11], off offset:416
	global_load_dword v1, v[10:11], off offset:384
	global_load_dword v0, v[10:11], off offset:128
	s_mov_b32 s4, 0xc1a00000
	s_waitcnt vmcnt(0) lgkmcnt(0)
	v_add_f32_e32 v9, v123, v2
	v_xor_b32_e32 v2, 0x80000000, v9
	v_cmp_ngt_f32_e32 vcc, s4, v9
	s_and_saveexec_b64 s[4:5], vcc
	s_cbranch_execz .LBB0_185
	v_mul_f32_e32 v2, 0xbfb8aa3b, v9
	v_exp_f32_e32 v2, v2
	s_mov_b32 s7, 0x3f2aaaab
	v_add_f32_e32 v9, 1.0, v2
	v_frexp_mant_f32_e32 v13, v9
	v_cvt_f64_f32_e32 v[10:11], v9
	v_add_f32_e32 v12, -1.0, v9
	v_frexp_exp_i32_f64_e32 v10, v[10:11]
	v_cmp_gt_f32_e32 vcc, s7, v13
	v_sub_f32_e32 v14, v12, v9
	v_sub_f32_e32 v12, v2, v12
	v_subbrev_co_u32_e32 v18, vcc, 0, v10, vcc
	v_add_f32_e32 v14, 1.0, v14
	v_sub_u32_e32 v10, 0, v18
	v_add_f32_e32 v12, v12, v14
	v_ldexp_f32 v9, v9, v10
	v_ldexp_f32 v10, v12, v10
	v_add_f32_e32 v12, -1.0, v9
	v_add_f32_e32 v11, 1.0, v12
	v_sub_f32_e32 v11, v9, v11
	v_add_f32_e32 v13, v10, v11
	v_add_f32_e32 v11, 1.0, v9
	v_add_f32_e32 v14, -1.0, v11
	v_sub_f32_e32 v9, v9, v14
	v_add_f32_e32 v9, v10, v9
	v_add_f32_e32 v19, v11, v9
	v_rcp_f32_e32 v20, v19
	v_sub_f32_e32 v10, v19, v11
	v_add_f32_e32 v11, v12, v13
	v_sub_f32_e32 v9, v9, v10
	v_mul_f32_e32 v22, v11, v20
	v_sub_f32_e32 v10, v11, v12
	v_mul_f32_e32 v12, v19, v22
	v_fma_f32 v14, v22, v19, -v12
	v_fmac_f32_e32 v14, v22, v9
	v_sub_f32_e32 v21, v13, v10
	v_add_f32_e32 v10, v12, v14
	v_sub_f32_e32 v13, v11, v10
	v_pk_add_f32 v[16:17], v[10:11], v[12:13] neg_lo:[0,1] neg_hi:[0,1]
	v_mov_b32_e32 v15, v10
	v_pk_add_f32 v[10:11], v[16:17], v[14:15] neg_lo:[0,1] neg_hi:[0,1]
	s_mov_b32 s7, 0x3f317218
	v_add_f32_e32 v11, v21, v11
	v_add_f32_e32 v10, v10, v11
	v_add_f32_e32 v11, v13, v10
	v_mul_f32_e32 v21, v20, v11
	v_mul_f32_e32 v12, v19, v21
	v_fma_f32 v14, v21, v19, -v12
	v_fmac_f32_e32 v14, v21, v9
	v_sub_f32_e32 v9, v13, v11
	v_add_f32_e32 v9, v10, v9
	v_add_f32_e32 v10, v12, v14
	v_sub_f32_e32 v13, v11, v10
	v_pk_add_f32 v[16:17], v[10:11], v[12:13] neg_lo:[0,1] neg_hi:[0,1]
	v_mov_b32_e32 v15, v10
	v_pk_add_f32 v[10:11], v[16:17], v[14:15] neg_lo:[0,1] neg_hi:[0,1]
	s_nop 0
	v_add_f32_e32 v9, v9, v11
	v_add_f32_e32 v9, v10, v9
	v_add_f32_e32 v11, v22, v21
	v_add_f32_e32 v9, v13, v9
	v_sub_f32_e32 v10, v11, v22
	v_mul_f32_e32 v9, v20, v9
	v_sub_f32_e32 v10, v21, v10
	v_add_f32_e32 v9, v10, v9
	v_add_f32_e32 v12, v11, v9
	v_mul_f32_e32 v14, v12, v12
	v_fmamk_f32 v10, v14, 0x3e9b6dac, v199
	v_fmaak_f32 v167, v14, v10, 0x3f2aaada
	v_cvt_f32_i32_e32 v10, v18
	v_sub_f32_e32 v11, v12, v11
	v_sub_f32_e32 v9, v9, v11
	v_mul_f32_e32 v11, v12, v14
	v_pk_mul_f32 v[14:15], v[10:11], v[166:167]
	v_ldexp_f32 v13, v12, 1
	v_fma_f32 v12, v10, s7, -v14
	v_fmac_f32_e32 v12, 0xb102e308, v10
	v_pk_add_f32 v[10:11], v[14:15], v[12:13]
	v_ldexp_f32 v9, v9, 1
	v_sub_f32_e32 v13, v11, v13
	v_sub_f32_e32 v13, v15, v13
	v_add_f32_e32 v17, v9, v13
	v_mov_b32_e32 v16, v14
	v_pk_add_f32 v[14:15], v[10:11], v[14:15] neg_lo:[0,1] neg_hi:[0,1]
	v_pk_add_f32 v[18:19], v[10:11], v[16:17]
	v_mov_b32_e32 v13, v10
	v_mov_b32_e32 v15, v19
	v_pk_add_f32 v[20:21], v[12:13], v[14:15] neg_lo:[0,1] neg_hi:[0,1]
	v_pk_add_f32 v[12:13], v[12:13], v[14:15]
	v_mov_b32_e32 v16, v17
	v_pk_add_f32 v[14:15], v[12:13], v[10:11] op_sel:[1,0] op_sel_hi:[0,1] neg_lo:[0,1] neg_hi:[0,1]
	v_pk_add_f32 v[22:23], v[18:19], v[14:15] op_sel_hi:[1,0] neg_lo:[0,1] neg_hi:[0,1]
	v_mov_b32_e32 v18, v19
	v_mov_b32_e32 v19, v13
	v_pk_mov_b32 v[14:15], v[10:11], v[14:15] op_sel:[1,0]
	v_mov_b32_e32 v17, v10
	v_pk_add_f32 v[14:15], v[18:19], v[14:15] neg_lo:[0,1] neg_hi:[0,1]
	v_mov_b32_e32 v22, v20
	v_pk_add_f32 v[10:11], v[16:17], v[14:15] neg_lo:[0,1] neg_hi:[0,1]
	v_mov_b32_e32 v21, v13
	v_pk_add_f32 v[14:15], v[22:23], v[10:11]
	s_mov_b32 s7, 0x7f800000
	v_pk_add_f32 v[16:17], v[14:15], v[14:15] op_sel:[0,1] op_sel_hi:[1,0]
	v_cmp_neq_f32_e32 vcc, s7, v2
	v_pk_add_f32 v[12:13], v[12:13], v[16:17] op_sel:[1,0] op_sel_hi:[0,1]
	v_mov_b32_e32 v15, v12
	v_pk_add_f32 v[18:19], v[14:15], v[20:21] neg_lo:[0,1] neg_hi:[0,1]
	v_mov_b32_e32 v11, v16
	v_sub_f32_e32 v9, v14, v18
	v_pk_add_f32 v[10:11], v[10:11], v[18:19] neg_lo:[0,1] neg_hi:[0,1]
	v_sub_f32_e32 v9, v20, v9
	v_add_f32_e32 v9, v10, v9
	v_add_f32_e32 v9, v9, v11
	v_add_f32_e32 v9, v12, v9
	v_cndmask_b32_e32 v9, v204, v9, vcc
	v_cmp_ngt_f32_e32 vcc, -1.0, v2
	s_mov_b32 s7, 0x33800000
	s_nop 0
	v_cndmask_b32_e32 v9, v205, v9, vcc
	v_cmp_neq_f32_e32 vcc, -1.0, v2
	s_nop 1
	v_cndmask_b32_e32 v9, v206, v9, vcc
	v_cmp_lt_f32_e64 vcc, |v2|, s7
	s_nop 1
	v_cndmask_b32_e32 v2, v9, v2, vcc

; __device__ void mlstm_item(const Params& p, int layer, int b, int hh, int q4) {
;     ...
;   if (w == 0) { mlstm_gates(small, row_b, hh, lane0, gpre); m_run = mlstm_scalars(gpre, ib, fb, 0.f, scal, lane0); mlstm_gates(small, row_b + 128, hh, lane0, gpre); }
.LBB0_189:
	s_or_b64 exec, exec, s[4:5]
	s_lshl_b32 s72, s12, 2
	v_lshl_add_u64 v[0:1], v[4:5], 0, s[72:73]
	v_add_co_u32_e32 v4, vcc, 0x8000, v0
	s_mov_b64 s[4:5], 0
	s_nop 0
	v_addc_co_u32_e32 v5, vcc, 0, v1, vcc
	global_load_dword v0, v[4:5], off offset:128
	global_load_dword v1, v[4:5], off offset:384
	global_load_dword v125, v[4:5], off offset:416
	global_load_dword v126, v[4:5], off offset:160
	s_branch .LBB0_191

; __device__ __forceinline__ size_t pidx(size_t row, int col) { return ((size_t)(col >> 8) * MTOK + row) * PLD + (col & 255); }
; #define LAS __attribute__((address_space(3)))
; __device__ void mlstm_item(const Params& p, int layer, int b, int hh, int q4) {
;     ...
;   auto dma_qk = [&](int buf, size_t rb, int dsl, int ln) {
;     const int rr = ln >> 2, jsrc = (ln & 3) ^ (((rr >> 3) & 1) << 1);
; #pragma unroll
;     for (int s2 = 0; s2 < 2; ++s2) {
;       const int st = 2 * w + s2;
;       const size_t row = rb + (st >> 1) * 16 + rr;
;       const int col = hh * 256 + dsl * 64 + (st & 1) * 32 + 8 * jsrc;
;       LAS unsigned char* dq = (LAS unsigned char*)smem + buf * 32768 + st * 1024;
;       __builtin_amdgcn_global_load_lds((const unsigned*)(proj + pidx(row, MQ + col)), (LAS unsigned*)dq, 16, 0, 0);
;       __builtin_amdgcn_global_load_lds((const unsigned*)(proj + pidx(row, MK + col)), (LAS unsigned*)(dq + 16384), 16, 0, 0);
;     }
;   };
;   const int vcp0 = (lane0 & 31) * 2, vl00 = (w * 2 + (lane0 >> 5)) * 8;
;   for (int i = tid0; i < 80 * 256 / 2; i += 512) ((unsigned*)CTe)[i] = 0u;
;   for (int i = tid0; i < 16 * 128 / 2; i += 512) {
;     ((unsigned*)(vTe + 64 * 128))[i] = 0u;
;     ((unsigned*)(vwT + 64 * 128))[i] = 0u;
;   }
;   __syncthreads();
;   if (tid0 < 64) *(unsigned*)(vTe + swz(64, 2 * tid0, LW)) = 0x3F803F80u;
;   f32x4 acc_c[4][3];
; #pragma unroll
;   for (int i = 0; i < 4; ++i)
; #pragma unroll
;     for (int j = 0; j < 3; ++j) acc_c[i][j] = (f32x4){0.f, 0.f, 0.f, 0.f};
;   float m_run = 0.f;
;   float gpre[4] = {0.f, 0.f, 0.f, 0.f};
;   if (w == 0) { mlstm_gates(small, row_b, hh, lane0, gpre); m_run = mlstm_scalars(gpre, ib, fb, 0.f, scal, lane0); mlstm_gates(small, row_b + 128, hh, lane0, gpre); }
;   const int db = w & 3, eb0 = w >> 2;
;   unsigned pfv[8];
; #pragma unroll
;   for (int i = 0; i < 8; ++i) pfv[i] = *(const unsigned*)(proj + pidx(row_b + vl00 + i, MV + hh * 256 + q4 * 64 + vcp0));
;   dma_qk(0, row_b, 0, lane0);
;   __syncthreads();
.LBB0_193:
	s_ashr_i32 s14, s13, 6
	s_add_u32 s20, s2, 0x10c80000
	s_addc_u32 s21, s3, 0
	s_lshl_b32 s86, s14, 4
	v_lshrrev_b32_e32 v2, 2, v122
	v_and_or_b32 v4, v2, 8, s86
	v_ashrrev_i32_e32 v5, 31, v4
	s_and_b32 s50, s6, 0xc0
	s_lshl_b32 s22, s12, 23
	v_lshl_add_u64 v[4:5], s[16:17], 0, v[4:5]
	s_add_u32 s24, s20, s22
	v_and_or_b32 v2, v8, 62, s50
	s_addc_u32 s25, s21, 0
	v_lshlrev_b64 v[4:5], 9, v[4:5]
	v_lshl_add_u64 v[4:5], s[24:25], 0, v[4:5]
	v_lshlrev_b32_e32 v2, 1, v2
	v_lshl_add_u64 v[4:5], v[4:5], 0, v[2:3]
	s_mov_b32 s2, 0x1a000000
	v_add_co_u32_e32 v4, vcc, s2, v4
	s_lshl_b32 s2, s14, 11
	s_nop 0
	v_addc_co_u32_e32 v5, vcc, 0, v5, vcc
	global_load_dword v127, v[4:5], off
	global_load_dword v128, v[4:5], off offset:512
	global_load_dword v129, v[4:5], off offset:1024
	global_load_dword v130, v[4:5], off offset:1536
	global_load_dword v131, v[4:5], off offset:2048
	global_load_dword v132, v[4:5], off offset:2560
	global_load_dword v133, v[4:5], off offset:3072
	global_load_dword v134, v[4:5], off offset:3584
	s_ashr_i32 s3, s13, 8
	v_lshrrev_b32_e32 v2, 2, v6
	v_and_b32_e32 v4, 3, v122
	v_lshrrev_b32_e32 v5, 4, v122
	s_ashr_i32 s6, s86, 31
	s_add_i32 s51, s2, 0
	v_bitop3_b32 v10, v5, v4, 2 bitop3:0x6c
	v_or_b32_e32 v4, s86, v2
	v_mov_b32_e32 v5, s6
	s_add_u32 s26, s24, 0x12000000
	v_lshl_add_u64 v[4:5], v[4:5], 0, s[16:17]
	s_addc_u32 s27, s25, 0
	v_lshlrev_b64 v[4:5], 9, v[4:5]
	s_add_u32 s28, s24, 0x16000000
	v_lshl_add_u64 v[8:9], s[26:27], 0, v[4:5]
	v_lshlrev_b32_e32 v2, 4, v10
	s_addc_u32 s29, s25, 0
	v_lshl_add_u64 v[8:9], v[8:9], 0, v[2:3]
	s_mov_b32 m0, s51
	v_lshl_add_u64 v[4:5], s[28:29], 0, v[4:5]
	s_add_i32 s84, s51, 0x4000
	global_load_lds_dwordx4 v[8:9], off
	v_lshl_add_u64 v[4:5], v[4:5], 0, v[2:3]
	s_mov_b32 m0, s84
	s_add_i32 s85, s51, 0x400
	global_load_lds_dwordx4 v[4:5], off
	v_lshl_add_u64 v[8:9], v[8:9], 0, 64
	s_mov_b32 m0, s85
	s_add_i32 s88, s51, 0x4400
	global_load_lds_dwordx4 v[8:9], off
	v_lshl_add_u64 v[4:5], v[4:5], 0, 64
	s_mov_b32 m0, s88
	s_lshl_b32 s2, s14, 9
	global_load_lds_dwordx4 v[4:5], off
	s_and_b32 s2, s2, 0x400
	s_add_i32 s92, s2, 0
	s_lshl_b32 s2, s14, 12
	s_add_i32 s33, s2, 0
	s_add_i32 s2, s22, 0x12200000
	s_and_b32 s30, s2, 0x17800000
	s_add_i32 s2, s22, 0x16200000
	s_and_b32 s34, s2, 0x1f800000
	s_add_i32 s2, s22, 0x12400000
	s_and_b32 s36, s2, 0x17800000
	s_add_i32 s2, s22, 0x16400000
	s_and_b32 s38, s2, 0x1f800000
	s_add_i32 s2, s22, 0x12600000
	s_and_b32 s46, s2, 0x17800000
	s_add_i32 s2, s22, 0x16600000
	s_bfe_u32 s89, s14, 0x1b0001
	s_bfe_u32 s90, s14, 0x10001
	s_and_b32 s91, s86, 16
	s_add_i32 s92, s92, 0x1a000
	s_and_b32 s2, s2, 0x1f800000
	s_cmp_lt_i32 s3, 5
	s_cselect_b64 s[42:43], -1, 0
	s_lshl_b32 s87, s3, 13
	s_cmp_lt_i32 s3, 3
	s_cselect_b64 s[4:5], -1, 0
	s_cmp_lt_i32 s3, 1
	s_cselect_b64 s[68:69], -1, 0
	s_cmp_gt_i32 s14, -1
	s_cselect_b64 s[10:11], -1, 0
	s_cmp_lt_u32 s13, 64
	s_cselect_b64 s[40:41], -1, 0
	s_cmp_gt_i32 s14, 0
	v_writelane_b32 v243, s40, 22
	s_cselect_b64 s[70:71], -1, 0
	s_cmp_eq_u32 s14, 1
	v_writelane_b32 v243, s41, 23
	s_cselect_b64 s[40:41], -1, 0
	s_cmp_gt_i32 s14, 1
	s_cselect_b64 s[44:45], -1, 0
	s_cmp_eq_u32 s14, 2
	s_cselect_b64 s[82:83], -1, 0
	s_cmp_gt_i32 s14, 2
	s_cselect_b64 s[54:55], -1, 0
	s_cmp_eq_u32 s14, 3
	s_cselect_b64 s[48:49], -1, 0
	s_cmp_gt_i32 s14, 3
	s_cselect_b64 s[94:95], -1, 0
	s_cmp_eq_u32 s14, 4
	s_cselect_b64 s[56:57], -1, 0
	s_cmp_gt_i32 s14, 4
	s_cselect_b64 s[58:59], -1, 0
	s_cmp_eq_u32 s14, 5
	s_cselect_b64 s[60:61], -1, 0
	s_cmp_gt_i32 s14, 5
	s_cselect_b64 s[62:63], -1, 0
	s_cmp_eq_u32 s14, 6
	s_cselect_b64 s[64:65], -1, 0
	s_cmp_gt_i32 s14, 6
	s_cselect_b64 s[66:67], -1, 0
	s_cmp_eq_u32 s14, 7
	s_cselect_b64 s[80:81], -1, 0
	s_lshl_b32 s79, s3, 12
	s_lshl_b64 s[8:9], s[8:9], 19
	s_lshl_b32 s3, s12, 2
	s_add_u32 s0, s0, s3
	s_addc_u32 s1, s1, 0
	s_add_u32 s0, s0, s8
	s_addc_u32 s1, s1, s9
	v_lshlrev_b32_e32 v2, 9, v6
	v_writelane_b32 v243, s40, 24
	v_lshl_add_u64 v[4:5], s[0:1], 0, v[2:3]
	s_mov_b64 s[0:1], 0x42c90080
	s_add_u32 s78, s16, s86
	v_mov_b32_e32 v20, 0
	s_waitcnt vmcnt(0)
	v_mov_b32_e32 v113, v112
	s_mov_b32 s23, s73
	s_mov_b32 s7, 0
	v_writelane_b32 v243, s41, 25
	v_cmp_eq_u32_e64 s[8:9], 0, v6
	s_mov_b32 s31, s73
	s_mov_b32 s35, s73
	s_mov_b32 s37, s73
	s_mov_b32 s39, s73
	s_mov_b32 s47, s73
	s_mov_b32 s97, s73
	s_mov_b32 s3, s73
	v_lshl_add_u64 v[114:115], v[4:5], 0, s[0:1]
	s_addc_u32 s41, s17, s6
	s_mov_b64 s[72:73], 0
	s_add_i32 s96, s51, 0x8400
	v_mov_b32_e32 v21, v20
	v_mov_b32_e32 v22, v20
	v_mov_b32_e32 v23, v20
	v_mov_b32_e32 v24, v20
	v_mov_b32_e32 v25, v20
	v_mov_b32_e32 v26, v20
	v_mov_b32_e32 v27, v20
	v_mov_b32_e32 v28, v20
	v_mov_b32_e32 v29, v20
	v_mov_b32_e32 v30, v20
	v_mov_b32_e32 v31, v20
	v_mov_b32_e32 v32, v20
	v_mov_b32_e32 v33, v20
	v_mov_b32_e32 v34, v20
	v_mov_b32_e32 v35, v20
	v_mov_b32_e32 v36, v20
	v_mov_b32_e32 v37, v20
	v_mov_b32_e32 v38, v20
	v_mov_b32_e32 v39, v20
	v_mov_b32_e32 v40, v20
	v_mov_b32_e32 v41, v20
	v_mov_b32_e32 v42, v20
	v_mov_b32_e32 v43, v20
	v_mov_b32_e32 v44, v20
	v_mov_b32_e32 v45, v20
	v_mov_b32_e32 v46, v20
	v_mov_b32_e32 v47, v20
	v_mov_b32_e32 v48, v20
	v_mov_b32_e32 v49, v20
	v_mov_b32_e32 v50, v20
	v_mov_b32_e32 v51, v20
	v_mov_b32_e32 v52, v20
	v_mov_b32_e32 v53, v20
	v_mov_b32_e32 v54, v20
	v_mov_b32_e32 v55, v20
	v_mov_b32_e32 v8, v20
	v_mov_b32_e32 v9, v20
	v_mov_b32_e32 v10, v20
	v_mov_b32_e32 v11, v20
	v_mov_b32_e32 v12, v20
	v_mov_b32_e32 v13, v20
	v_mov_b32_e32 v14, v20
	v_mov_b32_e32 v15, v20
	v_mov_b32_e32 v16, v20
	v_mov_b32_e32 v17, v20
	v_mov_b32_e32 v18, v20
	v_mov_b32_e32 v19, v20
	s_add_i32 s6, s51, 0xc400
	s_waitcnt lgkmcnt(0)
	s_barrier
	s_branch .LBB0_196

; #define SBAR __builtin_amdgcn_sched_barrier(0)
; #define SBAR __builtin_amdgcn_sched_barrier(0)
; #define LD_PV(dst, kk) do { dst[0] = ldsfrag(Pm, LW, l, (kk) * 32 + fq * 8); \
;         _Pragma("unroll") for (int e_ = 0; e_ < 5; ++e_) dst[1 + e_] = ldsfrag(vTe, LW, e_ * 16 + fr, (kk) * 32 + fq * 8); } while (0)
; #define MM_PV(srcf) _Pragma("unroll") for (int e_ = 0; e_ < 5; ++e_) acc_o[e_] = mfma16(srcf[1 + e_], srcf[0], acc_o[e_])
; __device__ void mlstm_item(const Params& p, int layer, int b, int hh, int q4) {
;     ...
;     asm volatile("s_waitcnt lgkmcnt(0)" ::: "memory");
;     {
;       const float m_prev = sc[515];
;       const float iw = __expf(m_prev - mu_l);
; #pragma unroll
;       for (int eb = 0; eb < 5; ++eb) acc_o[eb] *= iw;
;     ...
;       {
;         bf16x8 u0[6], u1[6], u2[6], u3[6];
;         LD_PV(u0, 0); SBAR;
;         LD_PV(u1, 1); MM_PV(u0); SBAR;
;         LD_PV(u2, 2); MM_PV(u1); SBAR;
;         LD_PV(u3, 3); MM_PV(u2); SBAR;
;         MM_PV(u3); SBAR;
;       }
;     ...
;       const float den = __shfl(acc_o[4][0], fr);
;       const float mt = s_bc[l] + mu_l;
;       const float inv = __builtin_amdgcn_rcpf(fmaxf(fabsf(den), __expf(-mt)));
.LBB0_195:
	s_waitcnt lgkmcnt(0)
	v_mov_b32_e32 v2, s40
	ds_read_b32 v2, v2 offset:2060
	v_add_u32_e32 v4, 0x15000, v136
	s_waitcnt lgkmcnt(0)
	v_sub_f32_e32 v2, v2, v121
	v_mul_f32_e32 v2, 0x3fb8aa3b, v2
	v_exp_f32_e32 v2, v2
	s_nop 0
	v_pk_mul_f32 v[70:71], v[70:71], v[2:3] op_sel_hi:[1,0]
	v_pk_mul_f32 v[68:69], v[68:69], v[2:3] op_sel_hi:[1,0]
	v_pk_mul_f32 v[66:67], v[66:67], v[2:3] op_sel_hi:[1,0]
	v_pk_mul_f32 v[64:65], v[64:65], v[2:3] op_sel_hi:[1,0]
	v_pk_mul_f32 v[62:63], v[62:63], v[2:3] op_sel_hi:[1,0]
	v_pk_mul_f32 v[60:61], v[60:61], v[2:3] op_sel_hi:[1,0]
	v_pk_mul_f32 v[58:59], v[58:59], v[2:3] op_sel_hi:[1,0]
	v_pk_mul_f32 v[56:57], v[56:57], v[2:3] op_sel_hi:[1,0]
	v_pk_mul_f32 v[74:75], v[74:75], v[2:3] op_sel_hi:[1,0]
	v_pk_mul_f32 v[72:73], v[72:73], v[2:3] op_sel_hi:[1,0]
	v_lshl_add_u32 v2, v137, 1, s33
	ds_read_b128 v[86:89], v2 offset:32768
	ds_read_b128 v[90:93], v4
	ds_read_b128 v[94:97], v4 offset:4096
	ds_read_b128 v[98:101], v4 offset:8192
	ds_read_b128 v[102:105], v4 offset:12288
	ds_read_b128 v[106:109], v4 offset:16384
	s_waitcnt lgkmcnt(0)
	v_mfma_f32_16x16x32_bf16 v[68:71], v[90:93], v[86:89], v[68:71]
	v_mfma_f32_16x16x32_bf16 v[64:67], v[94:97], v[86:89], v[64:67]
	ds_read_b128 v[90:93], v2 offset:33792
	ds_read_b128 v[94:97], v4 offset:1024
	v_mfma_f32_16x16x32_bf16 v[60:63], v[98:101], v[86:89], v[60:63]
	v_mfma_f32_16x16x32_bf16 v[56:59], v[102:105], v[86:89], v[56:59]
	ds_read_b128 v[98:101], v4 offset:5120
	ds_read_b128 v[102:105], v4 offset:9216
	ds_read_b128 v[116:119], v4 offset:13312
	ds_read_b128 v[136:139], v4 offset:17408
	v_mfma_f32_16x16x32_bf16 v[72:75], v[106:109], v[86:89], v[72:75]
	s_waitcnt lgkmcnt(0)
	v_mfma_f32_16x16x32_bf16 v[68:71], v[94:97], v[90:93], v[68:71]
	ds_read_b128 v[86:89], v2 offset:34816
	ds_read_b128 v[94:97], v4 offset:2048
	v_mfma_f32_16x16x32_bf16 v[64:67], v[98:101], v[90:93], v[64:67]
	v_mfma_f32_16x16x32_bf16 v[60:63], v[102:105], v[90:93], v[60:63]
	v_mfma_f32_16x16x32_bf16 v[56:59], v[116:119], v[90:93], v[56:59]
	ds_read_b128 v[98:101], v4 offset:6144
	ds_read_b128 v[102:105], v4 offset:10240
	ds_read_b128 v[106:109], v4 offset:14336
	ds_read_b128 v[116:119], v4 offset:18432
	v_mfma_f32_16x16x32_bf16 v[72:75], v[136:139], v[90:93], v[72:75]
	s_waitcnt lgkmcnt(0)
	v_mfma_f32_16x16x32_bf16 v[68:71], v[94:97], v[86:89], v[68:71]
	ds_read_b128 v[90:93], v2 offset:35840
	ds_read_b128 v[94:97], v4 offset:3072
	v_mfma_f32_16x16x32_bf16 v[64:67], v[98:101], v[86:89], v[64:67]
	v_mfma_f32_16x16x32_bf16 v[60:63], v[102:105], v[86:89], v[60:63]
	v_mfma_f32_16x16x32_bf16 v[56:59], v[106:109], v[86:89], v[56:59]
	ds_read_b128 v[98:101], v4 offset:7168
	ds_read_b128 v[102:105], v4 offset:11264
	ds_read_b128 v[106:109], v4 offset:15360
	ds_read_b128 v[136:139], v4 offset:19456
	v_mfma_f32_16x16x32_bf16 v[72:75], v[116:119], v[86:89], v[72:75]
	s_waitcnt lgkmcnt(0)
	v_mfma_f32_16x16x32_bf16 v[68:71], v[94:97], v[90:93], v[68:71]
	v_mfma_f32_16x16x32_bf16 v[64:67], v[98:101], v[90:93], v[64:67]
	v_mfma_f32_16x16x32_bf16 v[60:63], v[102:105], v[90:93], v[60:63]
	v_mfma_f32_16x16x32_bf16 v[56:59], v[106:109], v[90:93], v[56:59]
	v_mfma_f32_16x16x32_bf16 v[72:75], v[136:139], v[90:93], v[72:75]
	ds_read_b32 v4, v120 offset:1024
	v_and_or_b32 v2, v200, 64, v135
	v_lshlrev_b32_e32 v2, 2, v2
	s_nop 4
	ds_bpermute_b32 v2, v2, v72
	s_waitcnt vmcnt(0)
	v_lshlrev_b32_e32 v6, 16, v84
	s_waitcnt lgkmcnt(1)
	v_add_f32_e32 v4, v121, v4
	v_mul_f32_e32 v4, 0xbfb8aa3b, v4
	v_exp_f32_e32 v4, v4
	v_mul_f32_e32 v6, 0xbfb8aa3b, v6
	v_exp_f32_e32 v6, v6
	s_waitcnt lgkmcnt(0)
; __device__ __forceinline__ size_t pidx(size_t row, int col) { return ((size_t)(col >> 8) * MTOK + row) * PLD + (col & 255); }
; __device__ __forceinline__ float bflo(unsigned v) { return __uint_as_float(v << 16); }
; __device__ __forceinline__ float bfhi(unsigned v) { return __uint_as_float(v & 0xffff0000u); }
; __device__ __forceinline__ float sigmoidf_(float x) { return __builtin_amdgcn_rcpf(1.0f + __expf(-x)); }
; __device__ void mlstm_item(const Params& p, int layer, int b, int hh, int q4) {
;     ...
;       bf16_t* orow = proj + pidx(rbase + l, MO + hh * 256 + q4 * 64);
; #pragma unroll
;       for (int eb = 0; eb < 4; ++eb) {
;         const int ec = eb * 16 + fq * 4;
;         f32x4 y;
;         y[0] = acc_o[eb][0] * inv * sigmoidf_(bflo(oo[eb].x));
;         y[1] = acc_o[eb][1] * inv * sigmoidf_(bfhi(oo[eb].x));
;         y[2] = acc_o[eb][2] * inv * sigmoidf_(bflo(oo[eb].y));
;         y[3] = acc_o[eb][3] * inv * sigmoidf_(bfhi(oo[eb].y));
;         *(u32x2*)(orow + ec) = pack4(y);
;       }
;     }
;     __syncthreads();
;   }
	v_max_f32_e64 v2, |v2|, |v2|
	v_max_f32_e32 v2, v2, v4
	v_rcp_f32_e32 v2, v2
	v_add_f32_e32 v6, 1.0, v6
	v_rcp_f32_e32 v6, v6
	v_and_b32_e32 v7, 0xffff0000, v84
	v_mul_f32_e32 v4, v68, v2
	v_mul_f32_e32 v7, 0xbfb8aa3b, v7
	v_lshlrev_b32_e32 v68, 16, v85
	v_mul_f32_e32 v4, v6, v4
	v_mul_f32_e32 v6, v69, v2
	v_exp_f32_e32 v7, v7
	v_mul_f32_e32 v68, 0xbfb8aa3b, v68
	v_and_b32_e32 v69, 0xffff0000, v85
	v_exp_f32_e32 v68, v68
	v_mul_f32_e32 v69, 0xbfb8aa3b, v69
	v_exp_f32_e32 v69, v69
	v_add_f32_e32 v7, 1.0, v7
	v_rcp_f32_e32 v7, v7
	v_add_f32_e32 v68, 1.0, v68
	v_rcp_f32_e32 v68, v68
	v_add_f32_e32 v69, 1.0, v69
	v_rcp_f32_e32 v69, v69
	v_mul_f32_e32 v6, v7, v6
	v_mul_f32_e32 v7, v70, v2
	v_mul_f32_e32 v7, v68, v7
	v_mul_f32_e32 v68, v71, v2
	v_cvt_pk_bf16_f32 v6, v4, v6
	v_mul_f32_e32 v68, v69, v68
	v_cvt_pk_bf16_f32 v7, v7, v68
	global_store_dwordx2 v[76:77], v[6:7], off
	v_lshlrev_b32_e32 v6, 16, v82
	v_mul_f32_e32 v6, 0xbfb8aa3b, v6
	v_exp_f32_e32 v6, v6
	v_and_b32_e32 v7, 0xffff0000, v82
	v_mul_f32_e32 v4, v64, v2
	v_mul_f32_e32 v7, 0xbfb8aa3b, v7
	v_add_f32_e32 v6, 1.0, v6
	v_rcp_f32_e32 v6, v6
	v_lshlrev_b32_e32 v64, 16, v83
	v_exp_f32_e32 v7, v7
	v_mul_f32_e32 v64, 0xbfb8aa3b, v64
	v_mul_f32_e32 v4, v6, v4
	v_mul_f32_e32 v6, v65, v2
	v_and_b32_e32 v65, 0xffff0000, v83
	v_exp_f32_e32 v64, v64
	v_mul_f32_e32 v65, 0xbfb8aa3b, v65
	v_exp_f32_e32 v65, v65
	v_add_f32_e32 v7, 1.0, v7
	v_rcp_f32_e32 v7, v7
	v_add_f32_e32 v64, 1.0, v64
	v_rcp_f32_e32 v64, v64
	v_add_f32_e32 v65, 1.0, v65
	v_rcp_f32_e32 v65, v65
	v_mul_f32_e32 v6, v7, v6
	v_mul_f32_e32 v7, v66, v2
	v_mul_f32_e32 v7, v64, v7
	v_mul_f32_e32 v64, v67, v2
	v_cvt_pk_bf16_f32 v6, v4, v6
	v_mul_f32_e32 v64, v65, v64
	v_cvt_pk_bf16_f32 v7, v7, v64
	global_store_dwordx2 v[76:77], v[6:7], off offset:32
	v_lshlrev_b32_e32 v6, 16, v80
	v_mul_f32_e32 v6, 0xbfb8aa3b, v6
	v_exp_f32_e32 v6, v6
	v_and_b32_e32 v7, 0xffff0000, v80
	v_mul_f32_e32 v4, v60, v2
	v_mul_f32_e32 v7, 0xbfb8aa3b, v7
	v_add_f32_e32 v6, 1.0, v6
	v_rcp_f32_e32 v6, v6
	v_lshlrev_b32_e32 v60, 16, v81
	v_exp_f32_e32 v7, v7
	v_mul_f32_e32 v60, 0xbfb8aa3b, v60
	v_mul_f32_e32 v4, v6, v4
	v_mul_f32_e32 v6, v61, v2
	v_and_b32_e32 v61, 0xffff0000, v81
	v_exp_f32_e32 v60, v60
	v_mul_f32_e32 v61, 0xbfb8aa3b, v61
	v_exp_f32_e32 v61, v61
	v_add_f32_e32 v7, 1.0, v7
	v_rcp_f32_e32 v7, v7
	v_add_f32_e32 v60, 1.0, v60
	v_rcp_f32_e32 v60, v60
	v_add_f32_e32 v61, 1.0, v61
	v_rcp_f32_e32 v61, v61
	v_mul_f32_e32 v6, v7, v6
	v_mul_f32_e32 v7, v62, v2
	v_mul_f32_e32 v7, v60, v7
	v_mul_f32_e32 v60, v63, v2
	v_cvt_pk_bf16_f32 v6, v4, v6
	v_mul_f32_e32 v60, v61, v60
	v_cvt_pk_bf16_f32 v7, v7, v60
	global_store_dwordx2 v[76:77], v[6:7], off offset:64
	v_lshlrev_b32_e32 v6, 16, v78
	v_mul_f32_e32 v6, 0xbfb8aa3b, v6
	v_and_b32_e32 v7, 0xffff0000, v78
	v_mul_f32_e32 v4, v56, v2
	v_exp_f32_e32 v6, v6
	v_mul_f32_e32 v7, 0xbfb8aa3b, v7
	v_lshlrev_b32_e32 v56, 16, v79
	v_exp_f32_e32 v7, v7
	v_mul_f32_e32 v56, 0xbfb8aa3b, v56
	v_exp_f32_e32 v56, v56
	v_add_f32_e32 v6, 1.0, v6
	v_rcp_f32_e32 v6, v6
	v_add_f32_e32 v7, 1.0, v7
	v_rcp_f32_e32 v7, v7
	v_add_f32_e32 v56, 1.0, v56
	v_rcp_f32_e32 v56, v56
	v_mul_f32_e32 v4, v6, v4
	v_mul_f32_e32 v6, v57, v2
	v_mul_f32_e32 v6, v7, v6
	v_mul_f32_e32 v7, v58, v2
	v_mul_f32_e32 v7, v56, v7
	v_and_b32_e32 v56, 0xffff0000, v79
	v_mul_f32_e32 v56, 0xbfb8aa3b, v56
	v_exp_f32_e32 v56, v56
	v_mul_f32_e32 v2, v59, v2
	s_add_u32 s72, s72, 0x80
	s_addc_u32 s73, s73, 0
	v_add_f32_e32 v56, 1.0, v56
	v_rcp_f32_e32 v56, v56
	s_mov_b64 s[0:1], 0x8000
	v_cvt_pk_bf16_f32 v6, v4, v6
	v_lshl_add_u64 v[114:115], v[114:115], 0, s[0:1]
	v_mul_f32_e32 v2, v56, v2
	v_cvt_pk_bf16_f32 v7, v7, v2
	global_store_dwordx2 v[76:77], v[6:7], off offset:96
	s_cmpk_lg_i32 s72, 0x800
	v_mov_b32_e32 v7, v5
	s_mov_b32 s7, s12
	s_waitcnt lgkmcnt(0)
	s_barrier
	s_cbranch_scc0 .LBB0_173

; __device__ void mlstm_item(const Params& p, int layer, int b, int hh, int q4) {
;     ...
; #pragma unroll
;     for (int i = 0; i < 4; ++i)
; #pragma unroll
;       for (int j = 0; j < 3; ++j) acc_c[i][j] *= s_old;
;     {
;       float wg8[8];
; #pragma unroll
;       for (int i = 0; i < 8; ++i) wg8[i] = s_wg[vl0 + i];
;       u32x4 o0, o1, w0, w1;
;       o0.x = (pfv[0] & 0xffffu) | (pfv[1] << 16); o0.y = (pfv[2] & 0xffffu) | (pfv[3] << 16);
;       o0.z = (pfv[4] & 0xffffu) | (pfv[5] << 16); o0.w = (pfv[6] & 0xffffu) | (pfv[7] << 16);
;       o1.x = (pfv[0] >> 16) | (pfv[1] & 0xffff0000u); o1.y = (pfv[2] >> 16) | (pfv[3] & 0xffff0000u);
;       o1.z = (pfv[4] >> 16) | (pfv[5] & 0xffff0000u); o1.w = (pfv[6] >> 16) | (pfv[7] & 0xffff0000u);
;       w0.x = pack2(bflo(pfv[0]) * wg8[0], bflo(pfv[1]) * wg8[1]); w0.y = pack2(bflo(pfv[2]) * wg8[2], bflo(pfv[3]) * wg8[3]);
;       w0.z = pack2(bflo(pfv[4]) * wg8[4], bflo(pfv[5]) * wg8[5]); w0.w = pack2(bflo(pfv[6]) * wg8[6], bflo(pfv[7]) * wg8[7]);
;       w1.x = pack2(bfhi(pfv[0]) * wg8[0], bfhi(pfv[1]) * wg8[1]); w1.y = pack2(bfhi(pfv[2]) * wg8[2], bfhi(pfv[3]) * wg8[3]);
;       w1.z = pack2(bfhi(pfv[4]) * wg8[4], bfhi(pfv[5]) * wg8[5]); w1.w = pack2(bfhi(pfv[6]) * wg8[6], bfhi(pfv[7]) * wg8[7]);
;       *(u32x4*)(vTe + swz((vcp + 0), vl0, LW)) = o0;
;       *(u32x4*)(vTe + swz((vcp + 1), vl0, LW)) = o1;
;       *(u32x4*)(vwT + swz((vcp + 0), vl0, LW)) = w0;
;       *(u32x4*)(vwT + swz((vcp + 1), vl0, LW)) = w1;
;       if (tid < 64) *(unsigned*)(vwT + swz(64, 2 * tid, LW)) = pack2(s_wg[2 * tid], s_wg[2 * tid + 1]);
;     }
;     f32x4 acc_qk[8], acc_o[5];
; #pragma unroll
;     for (int i = 0; i < 8; ++i) acc_qk[i] = (f32x4){0.f, 0.f, 0.f, 0.f};
; #pragma unroll
;     for (int i = 0; i < 5; ++i) acc_o[i] = (f32x4){0.f, 0.f, 0.f, 0.f};
;     u32x2 oo[4];
; #pragma unroll
;     for (int ds = 0; ds < 4; ++ds) {
;       bf16_t* qs = qk0 + (ds & 1) * 16384;
;       bf16_t* ks = qs + 8192;
;       asm volatile("s_waitcnt vmcnt(0)" ::: "memory");
;       __syncthreads();
;       if (ds < 3) dma_qk((ds + 1) & 1, rbase, ds + 1, lane);
;       else if (ch + 1 < SEQ / 128) dma_qk(0, rbase + 128, 0, lane);
;       bf16x8 qf[2];
; #pragma unroll
;       for (int kk = 0; kk < 2; ++kk) qf[kk] = ldsfrag(qs, LQ, w * 16 + fr, kk * 32 + fq * 8);
;     ...
;       {
.LBB0_198:
	s_or_b64 exec, exec, s[0:1]
	s_add_u32 s0, s78, s72
	v_and_b32_e32 v135, 15, v68
	v_bfe_u32 v2, v68, 2, 4
	s_addc_u32 s1, s41, s73
	v_or_b32_e32 v116, s86, v135
	v_pk_mul_f32 v[64:65], v[20:21], v[118:119] op_sel_hi:[1,0]
	v_pk_mul_f32 v[20:21], v[28:29], v[118:119] op_sel_hi:[1,0]
	v_bfe_u32 v138, v68, 4, 2
	v_and_b32_e32 v6, 3, v68
	v_lshl_add_u64 v[28:29], s[0:1], 0, v[2:3]
	v_pk_mul_f32 v[66:67], v[22:23], v[118:119] op_sel_hi:[1,0]
	v_pk_mul_f32 v[26:27], v[26:27], v[118:119] op_sel_hi:[1,0]
	v_pk_mul_f32 v[24:25], v[24:25], v[118:119] op_sel_hi:[1,0]
	v_pk_mul_f32 v[22:23], v[30:31], v[118:119] op_sel_hi:[1,0]
	v_pk_mul_f32 v[62:63], v[34:35], v[118:119] op_sel_hi:[1,0]
	v_pk_mul_f32 v[60:61], v[32:33], v[118:119] op_sel_hi:[1,0]
	v_pk_mul_f32 v[38:39], v[38:39], v[118:119] op_sel_hi:[1,0]
	v_pk_mul_f32 v[36:37], v[36:37], v[118:119] op_sel_hi:[1,0]
	v_pk_mul_f32 v[34:35], v[42:43], v[118:119] op_sel_hi:[1,0]
	v_pk_mul_f32 v[32:33], v[40:41], v[118:119] op_sel_hi:[1,0]
	v_pk_mul_f32 v[58:59], v[46:47], v[118:119] op_sel_hi:[1,0]
	v_pk_mul_f32 v[56:57], v[44:45], v[118:119] op_sel_hi:[1,0]
	v_pk_mul_f32 v[50:51], v[50:51], v[118:119] op_sel_hi:[1,0]
	v_pk_mul_f32 v[48:49], v[48:49], v[118:119] op_sel_hi:[1,0]
	v_pk_mul_f32 v[46:47], v[54:55], v[118:119] op_sel_hi:[1,0]
	v_pk_mul_f32 v[44:45], v[52:53], v[118:119] op_sel_hi:[1,0]
	v_bitop3_b32 v119, v138, v6, 2 bitop3:0x6c
	v_lshlrev_b64 v[120:121], 9, v[28:29]
	v_lshlrev_b32_e32 v6, 1, v116
	v_bfe_u32 v28, v68, 2, 2
	v_lshlrev_b32_e32 v2, 3, v138
	v_lshlrev_b32_e32 v117, 5, v135
	v_and_b32_e32 v6, 16, v6
	v_and_b32_e32 v139, 16, v5
	v_and_or_b32 v28, v69, 24, v28
	v_lshrrev_b32_e32 v29, 4, v68
	v_bitop3_b32 v137, v2, v6, v117 bitop3:0x36
	v_bitop3_b32 v2, v2, v139, v117 bitop3:0x36
	v_and_or_b32 v41, v29, 2, s90
	v_lshlrev_b32_e32 v29, 5, v28
	v_lshl_add_u32 v136, v2, 1, 0
	v_and_b32_e32 v29, 0x160, v29
	v_and_or_b32 v54, v70, 12, s91
	v_and_b32_e32 v55, 16, v68
	v_lshl_add_u32 v140, v2, 1, s12
	v_or_b32_e32 v2, 36, v28
	v_or_b32_e32 v30, v29, v54
	v_bitop3_b32 v43, v29, v55, v54 bitop3:0x36
	v_lshrrev_b32_e32 v29, 3, v2
	v_lshlrev_b32_e32 v2, 5, v2
	v_and_b32_e32 v2, 0x1e0, v2
	v_and_or_b32 v29, v29, 6, s90
	v_bitop3_b32 v42, v2, v55, v54 bitop3:0x36
	v_or_b32_e32 v2, 0x44, v28
	v_lshlrev_b32_e32 v40, 10, v29
	v_lshrrev_b32_e32 v29, 3, v2
	v_lshlrev_b32_e32 v2, 5, v2
	v_and_b32_e32 v2, 0x1e0, v2
	v_bitop3_b32 v31, v2, v55, v54 bitop3:0x36
	v_or_b32_e32 v2, 0x64, v28
	v_lshrrev_b32_e32 v28, 3, v2
	v_lshlrev_b32_e32 v2, 5, v2
	v_lshl_add_u64 v[52:53], s[20:21], 0, v[120:121]
	s_cmpk_eq_i32 s72, 0x780
	s_movk_i32 s0, 0x80
	v_and_or_b32 v29, v29, 10, s90
	v_and_b32_e32 v2, 0x1e0, v2
	s_cselect_b64 s[74:75], -1, 0
	s_cmpk_lg_i32 s72, 0x780
	v_bitop3_b32 v68, v30, v55, s0 bitop3:0x36
	v_lshlrev_b32_e32 v30, 10, v29
	v_bitop3_b32 v29, v2, v55, v54 bitop3:0x36
	v_lshl_add_u64 v[54:55], v[52:53], 0, s[30:31]
	v_lshlrev_b32_e32 v2, 4, v119
	s_cselect_b64 s[76:77], -1, 0
	v_lshl_add_u64 v[54:55], v[54:55], 0, v[2:3]
	s_add_i32 s1, s51, 0x8000
	v_lshl_add_u64 v[70:71], v[54:55], 0, s[52:53]
	s_mov_b32 m0, s1
	s_waitcnt vmcnt(0)
	s_waitcnt lgkmcnt(0)
	s_barrier
	global_load_lds_dwordx4 v[70:71], off
	v_lshl_add_u64 v[70:71], v[52:53], 0, s[34:35]
	v_lshl_add_u64 v[70:71], v[70:71], 0, v[2:3]
	s_add_i32 s0, s51, 0xc000
	v_lshl_add_u64 v[70:71], v[70:71], 0, s[52:53]
	s_mov_b32 m0, s0
	s_mov_b64 s[12:13], 0xc0
	global_load_lds_dwordx4 v[70:71], off
	v_lshl_add_u64 v[54:55], v[54:55], 0, s[12:13]
	s_mov_b32 m0, s96
	s_mov_b64 s[12:13], 0x16000000
	global_load_lds_dwordx4 v[54:55], off
	v_lshl_add_u64 v[54:55], v[52:53], 0, s[22:23]
	v_lshl_add_u64 v[54:55], v[54:55], 0, s[12:13]
	v_or_b32_e32 v70, 0xc0, v2
	v_mov_b32_e32 v71, v3
	v_lshl_add_u64 v[70:71], v[54:55], 0, v[70:71]
	s_mov_b32 m0, s6
	v_lshl_add_u32 v144, v137, 1, s51
	global_load_lds_dwordx4 v[70:71], off
	ds_read_b128 v[70:73], v144
	ds_read_b128 v[74:77], v144 offset:1024
	ds_read_b128 v[78:81], v136 offset:16384
	ds_read_b128 v[82:85], v136 offset:18432
	ds_read_b128 v[86:89], v136 offset:20480
	ds_read_b128 v[90:93], v136 offset:22528
	v_and_or_b32 v28, v28, 14, s90
	v_add_u32_e32 v141, 0x1a000, v136
	v_lshlrev_b32_e32 v28, 10, v28
	ds_read_b128 v[94:97], v141 offset:8192
	ds_read_b128 v[98:101], v141 offset:16384
	ds_read_b128 v[102:105], v141 offset:24576
	ds_read_b128 v[106:109], v141
	ds_read_b128 v[146:149], v141 offset:32768
	s_waitcnt lgkmcnt(0)
	v_mfma_f32_16x16x32_bf16 v[78:81], v[78:81], v[70:73], 0
	v_mfma_f32_16x16x32_bf16 v[82:85], v[82:85], v[70:73], 0
	v_mfma_f32_16x16x32_bf16 v[86:89], v[86:89], v[70:73], 0
	v_mfma_f32_16x16x32_bf16 v[90:93], v[90:93], v[70:73], 0
	ds_read_b128 v[150:153], v136 offset:24576
	ds_read_b128 v[154:157], v136 offset:26624
	ds_read_b128 v[158:161], v136 offset:28672
	ds_read_b128 v[168:171], v136 offset:30720
	v_mfma_f32_16x16x32_bf16 v[106:109], v[106:109], v[70:73], 0
	v_mfma_f32_16x16x32_bf16 v[94:97], v[94:97], v[70:73], 0
	v_mfma_f32_16x16x32_bf16 v[98:101], v[98:101], v[70:73], 0
	v_mfma_f32_16x16x32_bf16 v[102:105], v[102:105], v[70:73], 0
	v_mfma_f32_16x16x32_bf16 v[146:149], v[146:149], v[70:73], 0
	ds_read_b128 v[172:175], v136 offset:17408
	ds_read_b128 v[176:179], v136 offset:19456
	ds_read_b128 v[180:183], v136 offset:21504
	ds_read_b128 v[184:187], v136 offset:23552
	s_waitcnt lgkmcnt(0)
; #define SBAR __builtin_amdgcn_sched_barrier(0)
; #define LD_KF(dst, half, kk) _Pragma("unroll") for (int i_ = 0; i_ < 4; ++i_) dst[i_] = ldsfrag(ks, LQ, ((half) * 4 + i_) * 16 + fr, (kk) * 32 + fq * 8)
; #define MM_KF(srcf, half, kk) _Pragma("unroll") for (int i_ = 0; i_ < 4; ++i_) acc_qk[(half) * 4 + i_] = mfma16(srcf[i_], qf[kk], acc_qk[(half) * 4 + i_])
; #define LD_CF(dst, kk) _Pragma("unroll") for (int i_ = 0; i_ < 5; ++i_) dst[i_] = ldsfrag(CTe, LC, i_ * 16 + fr, ds * 64 + (kk) * 32 + fq * 8)
; #define MM_CF(srcf, kk) _Pragma("unroll") for (int i_ = 0; i_ < 5; ++i_) acc_o[i_] = mfma16(srcf[i_], qf[kk], acc_o[i_])
; #define LD_ST(dst, kk) do { dst[0] = ldsfrag_tr(ks, LQ, (kk) * 32, db * 16, lane); \
;         _Pragma("unroll") for (int j_ = 0; j_ < 3; ++j_) dst[1 + j_] = ldsfrag(vwT, LW, (j_ < 2 ? eb0 + 2 * j_ : 4) * 16 + fr, (kk) * 32 + fq * 8); } while (0)
; #define MM_ST(srcf) _Pragma("unroll") for (int j_ = 0; j_ < 3; ++j_) acc_c[ds][j_] = mfma16(srcf[0], srcf[1 + j_], acc_c[ds][j_])
; #define SBAR __builtin_amdgcn_sched_barrier(0)
; __device__ void mlstm_item(const Params& p, int layer, int b, int hh, int q4) {
;     ...
;     for (int ds = 0; ds < 4; ++ds) {
;       bf16_t* qs = qk0 + (ds & 1) * 16384;
;       bf16_t* ks = qs + 8192;
;       asm volatile("s_waitcnt vmcnt(0)" ::: "memory");
;       __syncthreads();
;       if (ds < 3) dma_qk((ds + 1) & 1, rbase, ds + 1, lane);
;       else if (ch + 1 < SEQ / 128) dma_qk(0, rbase + 128, 0, lane);
;       bf16x8 qf[2];
; #pragma unroll
;       for (int kk = 0; kk < 2; ++kk) qf[kk] = ldsfrag(qs, LQ, w * 16 + fr, kk * 32 + fq * 8);
;     ...
;       {
;         bf16x8 r0[4], r1[5], r2[4], r3[4], r4[5], r5[4], t0[4], t1[4], t2[4], t3[4];
;         LD_KF(r0, 0, 0); SBAR;
;         LD_CF(r1, 0); MM_KF(r0, 0, 0); SBAR;
;         LD_KF(r2, 1, 0); MM_CF(r1, 0); SBAR;
;         LD_KF(r3, 0, 1); MM_KF(r2, 1, 0); SBAR;
;         LD_CF(r4, 1); MM_KF(r3, 0, 1); SBAR;
;         LD_KF(r5, 1, 1); MM_CF(r4, 1); SBAR;
;         LD_ST(t0, 0); MM_KF(r5, 1, 1); SBAR;
;         LD_ST(t1, 1); MM_ST(t0); SBAR;
;         LD_ST(t2, 2); MM_ST(t1); SBAR;
;         LD_ST(t3, 3); MM_ST(t2); SBAR;
;         MM_ST(t3); SBAR;
	v_mfma_f32_16x16x32_bf16 v[150:153], v[150:153], v[70:73], 0
	v_mfma_f32_16x16x32_bf16 v[154:157], v[154:157], v[70:73], 0
	v_mfma_f32_16x16x32_bf16 v[158:161], v[158:161], v[70:73], 0
	v_mfma_f32_16x16x32_bf16 v[70:73], v[168:171], v[70:73], 0
	v_add_u32_e32 v69, 0x1a400, v136
	v_mfma_f32_16x16x32_bf16 v[78:81], v[172:175], v[74:77], v[78:81]
	v_add_u32_e32 v110, 0x1c400, v136
	ds_read_b128 v[168:171], v69
	ds_read_b128 v[172:175], v110
	v_add_u32_e32 v69, 0x1e400, v136
	v_mfma_f32_16x16x32_bf16 v[82:85], v[176:179], v[74:77], v[82:85]
	v_add_u32_e32 v110, 0x20400, v136
	v_mfma_f32_16x16x32_bf16 v[86:89], v[180:183], v[74:77], v[86:89]
	ds_read_b128 v[176:179], v69
	ds_read_b128 v[180:183], v110
	v_add_u32_e32 v69, 0x22400, v136
	ds_read_b128 v[188:191], v69
	v_mfma_f32_16x16x32_bf16 v[90:93], v[184:187], v[74:77], v[90:93]
	s_waitcnt lgkmcnt(0)
	v_mfma_f32_16x16x32_bf16 v[106:109], v[168:171], v[74:77], v[106:109]
	v_mfma_f32_16x16x32_bf16 v[94:97], v[172:175], v[74:77], v[94:97]
	v_mfma_f32_16x16x32_bf16 v[98:101], v[176:179], v[74:77], v[98:101]
	v_mfma_f32_16x16x32_bf16 v[102:105], v[180:183], v[74:77], v[102:105]
	ds_read_b128 v[168:171], v136 offset:25600
	ds_read_b128 v[172:175], v136 offset:27648
	ds_read_b128 v[176:179], v136 offset:29696
	ds_read_b128 v[180:183], v136 offset:31744
	v_mfma_f32_16x16x32_bf16 v[184:187], v[188:191], v[74:77], v[146:149]
	v_lshl_add_u32 v41, v41, 10, 0
	v_lshl_add_u32 v145, v68, 1, v41
	v_add_u32_e32 v143, s79, v140
	s_waitcnt lgkmcnt(0)
	v_mfma_f32_16x16x32_bf16 v[150:153], v[168:171], v[74:77], v[150:153]
	v_lshl_add_u32 v142, v43, 1, v41
	s_nop 0
	ds_read_b64_tr_b16 v[162:163], v145 offset:16384
	ds_read_b128 v[146:149], v143
	v_mfma_f32_16x16x32_bf16 v[154:157], v[172:175], v[74:77], v[154:157]
	v_mfma_f32_16x16x32_bf16 v[168:171], v[176:179], v[74:77], v[158:161]
	ds_read_b128 v[172:175], v143 offset:8192
	s_nop 1
	ds_read_b64_tr_b16 v[160:161], v142 offset:16384
	ds_read_b128 v[176:179], v140 offset:16384
	v_mfma_f32_16x16x32_bf16 v[68:71], v[180:183], v[74:77], v[70:73]
	v_lshlrev_b32_e32 v41, 1, v42
	s_waitcnt lgkmcnt(1)
	v_mfma_f32_16x16x32_bf16 v[64:67], v[160:163], v[146:149], v[64:67]
	v_add3_u32 v146, 0, v40, v41
	ds_read_b64_tr_b16 v[42:43], v146 offset:16384
	ds_read_b128 v[72:75], v143 offset:1024
	v_mfma_f32_16x16x32_bf16 v[24:27], v[160:163], v[172:175], v[24:27]
	ds_read_b128 v[172:175], v143 offset:9216
	ds_read_b64_tr_b16 v[40:41], v142 offset:20480
	ds_read_b128 v[180:183], v140 offset:17408
	s_waitcnt lgkmcnt(5)
	v_mfma_f32_16x16x32_bf16 v[20:23], v[160:163], v[176:179], v[20:23]
	v_lshlrev_b32_e32 v31, 1, v31
	v_add3_u32 v147, 0, v30, v31
	s_waitcnt lgkmcnt(1)
	v_mfma_f32_16x16x32_bf16 v[64:67], v[40:43], v[72:75], v[64:67]
	ds_read_b64_tr_b16 v[74:75], v147 offset:16384
	ds_read_b128 v[158:161], v143 offset:2048
	v_mfma_f32_16x16x32_bf16 v[24:27], v[40:43], v[172:175], v[24:27]
	ds_read_b128 v[172:175], v143 offset:10240
	ds_read_b64_tr_b16 v[72:73], v142 offset:24576
	ds_read_b128 v[176:179], v140 offset:18432
	s_waitcnt lgkmcnt(5)
	v_mfma_f32_16x16x32_bf16 v[20:23], v[40:43], v[180:183], v[20:23]
	v_lshlrev_b32_e32 v29, 1, v29
	v_add3_u32 v148, 0, v28, v29
	s_waitcnt lgkmcnt(1)
	v_mfma_f32_16x16x32_bf16 v[40:43], v[72:75], v[158:161], v[64:67]
	ds_read_b64_tr_b16 v[30:31], v148 offset:16384
	s_nop 1
	ds_read_b128 v[64:67], v143 offset:3072
	v_mfma_f32_16x16x32_bf16 v[24:27], v[72:75], v[172:175], v[24:27]
	ds_read_b128 v[158:161], v143 offset:11264
	ds_read_b64_tr_b16 v[28:29], v142 offset:28672
	ds_read_b128 v[172:175], v140 offset:19456
	s_waitcnt lgkmcnt(5)
	v_mfma_f32_16x16x32_bf16 v[72:75], v[72:75], v[176:179], v[20:23]
	s_waitcnt lgkmcnt(1)
	v_mfma_f32_16x16x32_bf16 v[20:23], v[28:31], v[64:67], v[40:43]
	v_mfma_f32_16x16x32_bf16 v[24:27], v[28:31], v[158:161], v[24:27]
	s_waitcnt lgkmcnt(0)
	v_mfma_f32_16x16x32_bf16 v[28:31], v[28:31], v[172:175], v[72:75]
	v_lshl_add_u64 v[40:41], v[52:53], 0, s[36:37]
	v_lshl_add_u64 v[40:41], v[40:41], 0, v[2:3]
	s_mov_b64 s[12:13], 0x100
	s_mov_b32 m0, s51
	v_lshl_add_u64 v[42:43], v[40:41], 0, s[12:13]
	s_waitcnt vmcnt(0)
	s_barrier
	global_load_lds_dwordx4 v[42:43], off
	v_lshl_add_u64 v[42:43], v[52:53], 0, s[38:39]
	v_lshl_add_u64 v[42:43], v[42:43], 0, v[2:3]
	v_lshl_add_u64 v[42:43], v[42:43], 0, s[12:13]
	s_mov_b32 m0, s84
	s_mov_b64 s[12:13], 0x140
	global_load_lds_dwordx4 v[42:43], off
	v_lshl_add_u64 v[40:41], v[40:41], 0, s[12:13]
	s_mov_b32 m0, s85
	s_nop 0
	global_load_lds_dwordx4 v[40:41], off
	v_or_b32_e32 v40, 0x140, v2
	v_mov_b32_e32 v41, v3
	v_lshl_add_u64 v[40:41], v[54:55], 0, v[40:41]
	s_mov_b32 m0, s88
	s_nop 0
	global_load_lds_dwordx4 v[40:41], off
	ds_read_b128 v[40:43], v144 offset:32768
	ds_read_b128 v[64:67], v144 offset:33792
	ds_read_b128 v[72:75], v136 offset:49152
	ds_read_b128 v[158:161], v136 offset:51200
	ds_read_b128 v[172:175], v136 offset:53248
	ds_read_b128 v[176:179], v136 offset:55296
	s_waitcnt lgkmcnt(0)
	v_mfma_f32_16x16x32_bf16 v[72:75], v[72:75], v[40:43], v[78:81]
	v_mfma_f32_16x16x32_bf16 v[76:79], v[158:161], v[40:43], v[82:85]
	s_nop 2
	ds_read_b128 v[80:83], v141 offset:10240
	ds_read_b128 v[158:161], v141 offset:18432
	v_mfma_f32_16x16x32_bf16 v[84:87], v[172:175], v[40:43], v[86:89]
	ds_read_b128 v[172:175], v141 offset:26624
	ds_read_b128 v[180:183], v141 offset:2048
	ds_read_b128 v[188:191], v141 offset:34816
	v_mfma_f32_16x16x32_bf16 v[88:91], v[176:179], v[40:43], v[90:93]
	s_waitcnt lgkmcnt(0)
; #define SBAR __builtin_amdgcn_sched_barrier(0)
; #define LD_KF(dst, half, kk) _Pragma("unroll") for (int i_ = 0; i_ < 4; ++i_) dst[i_] = ldsfrag(ks, LQ, ((half) * 4 + i_) * 16 + fr, (kk) * 32 + fq * 8)
; #define MM_KF(srcf, half, kk) _Pragma("unroll") for (int i_ = 0; i_ < 4; ++i_) acc_qk[(half) * 4 + i_] = mfma16(srcf[i_], qf[kk], acc_qk[(half) * 4 + i_])
; #define LD_CF(dst, kk) _Pragma("unroll") for (int i_ = 0; i_ < 5; ++i_) dst[i_] = ldsfrag(CTe, LC, i_ * 16 + fr, ds * 64 + (kk) * 32 + fq * 8)
; #define MM_CF(srcf, kk) _Pragma("unroll") for (int i_ = 0; i_ < 5; ++i_) acc_o[i_] = mfma16(srcf[i_], qf[kk], acc_o[i_])
; #define LD_ST(dst, kk) do { dst[0] = ldsfrag_tr(ks, LQ, (kk) * 32, db * 16, lane); \
;         _Pragma("unroll") for (int j_ = 0; j_ < 3; ++j_) dst[1 + j_] = ldsfrag(vwT, LW, (j_ < 2 ? eb0 + 2 * j_ : 4) * 16 + fr, (kk) * 32 + fq * 8); } while (0)
; #define MM_ST(srcf) _Pragma("unroll") for (int j_ = 0; j_ < 3; ++j_) acc_c[ds][j_] = mfma16(srcf[0], srcf[1 + j_], acc_c[ds][j_])
; #define SBAR __builtin_amdgcn_sched_barrier(0)
; __device__ void mlstm_item(const Params& p, int layer, int b, int hh, int q4) {
;     ...
;     for (int ds = 0; ds < 4; ++ds) {
;       bf16_t* qs = qk0 + (ds & 1) * 16384;
;       bf16_t* ks = qs + 8192;
;       asm volatile("s_waitcnt vmcnt(0)" ::: "memory");
;       __syncthreads();
;       if (ds < 3) dma_qk((ds + 1) & 1, rbase, ds + 1, lane);
;       else if (ch + 1 < SEQ / 128) dma_qk(0, rbase + 128, 0, lane);
;       bf16x8 qf[2];
; #pragma unroll
;       for (int kk = 0; kk < 2; ++kk) qf[kk] = ldsfrag(qs, LQ, w * 16 + fr, kk * 32 + fq * 8);
;     ...
;       {
;         bf16x8 r0[4], r1[5], r2[4], r3[4], r4[5], r5[4], t0[4], t1[4], t2[4], t3[4];
;         LD_KF(r0, 0, 0); SBAR;
;         LD_CF(r1, 0); MM_KF(r0, 0, 0); SBAR;
;         LD_KF(r2, 1, 0); MM_CF(r1, 0); SBAR;
;         LD_KF(r3, 0, 1); MM_KF(r2, 1, 0); SBAR;
;         LD_CF(r4, 1); MM_KF(r3, 0, 1); SBAR;
;         LD_KF(r5, 1, 1); MM_CF(r4, 1); SBAR;
;         LD_ST(t0, 0); MM_KF(r5, 1, 1); SBAR;
;         LD_ST(t1, 1); MM_ST(t0); SBAR;
;         LD_ST(t2, 2); MM_ST(t1); SBAR;
;         LD_ST(t3, 3); MM_ST(t2); SBAR;
;         MM_ST(t3); SBAR;
	v_mfma_f32_16x16x32_bf16 v[80:83], v[80:83], v[40:43], v[94:97]
	v_mfma_f32_16x16x32_bf16 v[92:95], v[158:161], v[40:43], v[98:101]
	v_mfma_f32_16x16x32_bf16 v[96:99], v[172:175], v[40:43], v[102:105]
	s_nop 2
	ds_read_b128 v[100:103], v136 offset:57344
	ds_read_b128 v[158:161], v136 offset:59392
	ds_read_b128 v[172:175], v136 offset:61440
	ds_read_b128 v[176:179], v136 offset:63488
	v_mfma_f32_16x16x32_bf16 v[106:109], v[180:183], v[40:43], v[106:109]
	v_mfma_f32_16x16x32_bf16 v[180:183], v[188:191], v[40:43], v[184:187]
	s_waitcnt lgkmcnt(0)
	v_mfma_f32_16x16x32_bf16 v[100:103], v[100:103], v[40:43], v[150:153]
	v_mfma_f32_16x16x32_bf16 v[150:153], v[158:161], v[40:43], v[154:157]
	v_mfma_f32_16x16x32_bf16 v[154:157], v[172:175], v[40:43], v[168:171]
	ds_read_b128 v[158:161], v136 offset:50176
	s_nop 1
	ds_read_b128 v[168:171], v136 offset:52224
	ds_read_b128 v[172:175], v136 offset:54272
	ds_read_b128 v[184:187], v136 offset:56320
	v_mfma_f32_16x16x32_bf16 v[40:43], v[176:179], v[40:43], v[68:71]
	v_add_u32_e32 v104, 0x1ac00, v136
	s_waitcnt lgkmcnt(0)
	v_mfma_f32_16x16x32_bf16 v[68:71], v[158:161], v[64:67], v[72:75]
	v_add_u32_e32 v105, 0x1cc00, v136
	v_mfma_f32_16x16x32_bf16 v[72:75], v[168:171], v[64:67], v[76:79]
	s_nop 2
	ds_read_b128 v[76:79], v104
	ds_read_b128 v[158:161], v105
	v_add_u32_e32 v104, 0x1ec00, v136
	v_add_u32_e32 v105, 0x20c00, v136
	v_mfma_f32_16x16x32_bf16 v[84:87], v[172:175], v[64:67], v[84:87]
	ds_read_b128 v[168:171], v104
	ds_read_b128 v[172:175], v105
	v_add_u32_e32 v104, 0x22c00, v136
	ds_read_b128 v[176:179], v104
	v_mfma_f32_16x16x32_bf16 v[88:91], v[184:187], v[64:67], v[88:91]
	s_waitcnt lgkmcnt(0)
	v_mfma_f32_16x16x32_bf16 v[76:79], v[76:79], v[64:67], v[106:109]
	v_mfma_f32_16x16x32_bf16 v[80:83], v[158:161], v[64:67], v[80:83]
	v_mfma_f32_16x16x32_bf16 v[92:95], v[168:171], v[64:67], v[92:95]
	s_nop 0
	ds_read_b128 v[104:107], v136 offset:58368
	ds_read_b128 v[108:111], v136 offset:60416
	ds_read_b128 v[158:161], v136 offset:62464
	ds_read_b128 v[168:171], v136 offset:64512
	v_mfma_f32_16x16x32_bf16 v[96:99], v[172:175], v[64:67], v[96:99]
	v_mfma_f32_16x16x32_bf16 v[172:175], v[176:179], v[64:67], v[180:183]
	s_waitcnt lgkmcnt(0)
	v_mfma_f32_16x16x32_bf16 v[100:103], v[104:107], v[64:67], v[100:103]
	v_mfma_f32_16x16x32_bf16 v[104:107], v[108:111], v[64:67], v[150:153]
	s_nop 0
	ds_read_b64_tr_b16 v[110:111], v145 offset:49152
	s_nop 0
	ds_read_b128 v[150:153], v143
	v_mfma_f32_16x16x32_bf16 v[154:157], v[158:161], v[64:67], v[154:157]
	ds_read_b128 v[158:161], v143 offset:8192
	ds_read_b64_tr_b16 v[108:109], v142 offset:49152
	ds_read_b128 v[176:179], v140 offset:16384
	v_mfma_f32_16x16x32_bf16 v[64:67], v[168:171], v[64:67], v[40:43]
	s_waitcnt lgkmcnt(1)
	v_mfma_f32_16x16x32_bf16 v[40:43], v[108:111], v[150:153], v[60:63]
	s_nop 2
	ds_read_b64_tr_b16 v[62:63], v146 offset:49152
	ds_read_b128 v[150:153], v143 offset:1024
	v_mfma_f32_16x16x32_bf16 v[36:39], v[108:111], v[158:161], v[36:39]
	ds_read_b128 v[158:161], v143 offset:9216
	ds_read_b64_tr_b16 v[60:61], v142 offset:53248
	ds_read_b128 v[168:171], v140 offset:17408
	s_waitcnt lgkmcnt(5)
	v_mfma_f32_16x16x32_bf16 v[32:35], v[108:111], v[176:179], v[32:35]
	s_waitcnt lgkmcnt(1)
	v_mfma_f32_16x16x32_bf16 v[40:43], v[60:63], v[150:153], v[40:43]
	ds_read_b64_tr_b16 v[110:111], v147 offset:49152
	ds_read_b128 v[150:153], v143 offset:2048
	v_mfma_f32_16x16x32_bf16 v[36:39], v[60:63], v[158:161], v[36:39]
	ds_read_b128 v[158:161], v143 offset:10240
	ds_read_b64_tr_b16 v[108:109], v142 offset:57344
	ds_read_b128 v[176:179], v140 offset:18432
	s_waitcnt lgkmcnt(5)
	v_mfma_f32_16x16x32_bf16 v[32:35], v[60:63], v[168:171], v[32:35]
	s_waitcnt lgkmcnt(1)
	v_mfma_f32_16x16x32_bf16 v[40:43], v[108:111], v[150:153], v[40:43]
	ds_read_b64_tr_b16 v[62:63], v148 offset:49152
	ds_read_b128 v[150:153], v143 offset:3072
	v_mfma_f32_16x16x32_bf16 v[36:39], v[108:111], v[158:161], v[36:39]
	ds_read_b128 v[158:161], v143 offset:11264
	ds_read_b64_tr_b16 v[60:61], v142 offset:61440
	ds_read_b128 v[168:171], v140 offset:19456
	s_waitcnt lgkmcnt(5)
	v_mfma_f32_16x16x32_bf16 v[108:111], v[108:111], v[176:179], v[32:35]
	s_waitcnt lgkmcnt(1)
	v_mfma_f32_16x16x32_bf16 v[32:35], v[60:63], v[150:153], v[40:43]
	v_mfma_f32_16x16x32_bf16 v[36:39], v[60:63], v[158:161], v[36:39]
	s_waitcnt lgkmcnt(0)
	v_mfma_f32_16x16x32_bf16 v[40:43], v[60:63], v[168:171], v[108:111]
	v_lshl_add_u64 v[60:61], v[52:53], 0, s[46:47]
	v_lshl_add_u64 v[60:61], v[60:61], 0, v[2:3]
	s_mov_b64 s[12:13], 0x180
	v_lshl_add_u64 v[52:53], v[52:53], 0, s[2:3]
	s_mov_b32 m0, s1
	v_lshl_add_u64 v[62:63], v[60:61], 0, s[12:13]
	v_lshl_add_u64 v[52:53], v[52:53], 0, v[2:3]
	s_waitcnt vmcnt(0)
	s_barrier
; #define SBAR __builtin_amdgcn_sched_barrier(0)
; #define LD_KF(dst, half, kk) _Pragma("unroll") for (int i_ = 0; i_ < 4; ++i_) dst[i_] = ldsfrag(ks, LQ, ((half) * 4 + i_) * 16 + fr, (kk) * 32 + fq * 8)
; #define MM_KF(srcf, half, kk) _Pragma("unroll") for (int i_ = 0; i_ < 4; ++i_) acc_qk[(half) * 4 + i_] = mfma16(srcf[i_], qf[kk], acc_qk[(half) * 4 + i_])
; #define LD_CF(dst, kk) _Pragma("unroll") for (int i_ = 0; i_ < 5; ++i_) dst[i_] = ldsfrag(CTe, LC, i_ * 16 + fr, ds * 64 + (kk) * 32 + fq * 8)
; #define MM_CF(srcf, kk) _Pragma("unroll") for (int i_ = 0; i_ < 5; ++i_) acc_o[i_] = mfma16(srcf[i_], qf[kk], acc_o[i_])
; #define LD_ST(dst, kk) do { dst[0] = ldsfrag_tr(ks, LQ, (kk) * 32, db * 16, lane); \
;         _Pragma("unroll") for (int j_ = 0; j_ < 3; ++j_) dst[1 + j_] = ldsfrag(vwT, LW, (j_ < 2 ? eb0 + 2 * j_ : 4) * 16 + fr, (kk) * 32 + fq * 8); } while (0)
; #define MM_ST(srcf) _Pragma("unroll") for (int j_ = 0; j_ < 3; ++j_) acc_c[ds][j_] = mfma16(srcf[0], srcf[1 + j_], acc_c[ds][j_])
; #define SBAR __builtin_amdgcn_sched_barrier(0)
; __device__ void mlstm_item(const Params& p, int layer, int b, int hh, int q4) {
;     ...
;     for (int ds = 0; ds < 4; ++ds) {
;       bf16_t* qs = qk0 + (ds & 1) * 16384;
;       bf16_t* ks = qs + 8192;
;       asm volatile("s_waitcnt vmcnt(0)" ::: "memory");
;       __syncthreads();
;       if (ds < 3) dma_qk((ds + 1) & 1, rbase, ds + 1, lane);
;       else if (ch + 1 < SEQ / 128) dma_qk(0, rbase + 128, 0, lane);
;       bf16x8 qf[2];
; #pragma unroll
;       for (int kk = 0; kk < 2; ++kk) qf[kk] = ldsfrag(qs, LQ, w * 16 + fr, kk * 32 + fq * 8);
;     ...
;       {
;         bf16x8 r0[4], r1[5], r2[4], r3[4], r4[5], r5[4], t0[4], t1[4], t2[4], t3[4];
;         LD_KF(r0, 0, 0); SBAR;
;         LD_CF(r1, 0); MM_KF(r0, 0, 0); SBAR;
;         LD_KF(r2, 1, 0); MM_CF(r1, 0); SBAR;
;         LD_KF(r3, 0, 1); MM_KF(r2, 1, 0); SBAR;
;         LD_CF(r4, 1); MM_KF(r3, 0, 1); SBAR;
;         LD_KF(r5, 1, 1); MM_CF(r4, 1); SBAR;
;         LD_ST(t0, 0); MM_KF(r5, 1, 1); SBAR;
;         LD_ST(t1, 1); MM_ST(t0); SBAR;
;         LD_ST(t2, 2); MM_ST(t1); SBAR;
;         LD_ST(t3, 3); MM_ST(t2); SBAR;
;         MM_ST(t3); SBAR;
	global_load_lds_dwordx4 v[62:63], off
	v_lshl_add_u64 v[52:53], v[52:53], 0, s[12:13]
	s_mov_b32 m0, s0
	s_mov_b64 s[0:1], 0x1c0
	global_load_lds_dwordx4 v[52:53], off
	v_lshl_add_u64 v[52:53], v[60:61], 0, s[0:1]
	s_mov_b32 m0, s96
	v_or_b32_e32 v2, 0x1c0, v2
	global_load_lds_dwordx4 v[52:53], off
	v_lshl_add_u64 v[52:53], v[54:55], 0, v[2:3]
	s_mov_b32 m0, s6
	s_nop 0
	global_load_lds_dwordx4 v[52:53], off
	ds_read_b128 v[52:55], v144
	ds_read_b128 v[150:153], v144 offset:1024
	ds_read_b128 v[60:63], v136 offset:16384
	ds_read_b128 v[108:111], v136 offset:18432
	ds_read_b128 v[158:161], v136 offset:20480
	ds_read_b128 v[168:171], v136 offset:22528
	s_waitcnt lgkmcnt(0)
	v_mfma_f32_16x16x32_bf16 v[60:63], v[60:63], v[52:55], v[68:71]
	v_mfma_f32_16x16x32_bf16 v[68:71], v[108:111], v[52:55], v[72:75]
	s_nop 2
	ds_read_b128 v[72:75], v141 offset:12288
	ds_read_b128 v[108:111], v141 offset:20480
	v_mfma_f32_16x16x32_bf16 v[84:87], v[158:161], v[52:55], v[84:87]
	ds_read_b128 v[158:161], v141 offset:28672
	ds_read_b128 v[176:179], v141 offset:4096
	ds_read_b128 v[180:183], v141 offset:36864
	v_mfma_f32_16x16x32_bf16 v[88:91], v[168:171], v[52:55], v[88:91]
	s_waitcnt lgkmcnt(0)
	v_mfma_f32_16x16x32_bf16 v[80:83], v[72:75], v[52:55], v[80:83]
	v_mfma_f32_16x16x32_bf16 v[92:95], v[108:111], v[52:55], v[92:95]
	v_mfma_f32_16x16x32_bf16 v[96:99], v[158:161], v[52:55], v[96:99]
	ds_read_b128 v[72:75], v136 offset:24576
	ds_read_b128 v[108:111], v136 offset:26624
	ds_read_b128 v[158:161], v136 offset:28672
	ds_read_b128 v[168:171], v136 offset:30720
	v_mfma_f32_16x16x32_bf16 v[76:79], v[176:179], v[52:55], v[76:79]
	v_mfma_f32_16x16x32_bf16 v[172:175], v[180:183], v[52:55], v[172:175]
	s_waitcnt lgkmcnt(0)
	v_mfma_f32_16x16x32_bf16 v[100:103], v[72:75], v[52:55], v[100:103]
	v_mfma_f32_16x16x32_bf16 v[104:107], v[108:111], v[52:55], v[104:107]
	v_mfma_f32_16x16x32_bf16 v[108:111], v[158:161], v[52:55], v[154:157]
	ds_read_b128 v[72:75], v136 offset:17408
	s_nop 1
	ds_read_b128 v[154:157], v136 offset:19456
	ds_read_b128 v[158:161], v136 offset:21504
	ds_read_b128 v[176:179], v136 offset:23552
	v_mfma_f32_16x16x32_bf16 v[52:55], v[168:171], v[52:55], v[64:67]
	v_add_u32_e32 v2, 0x1b400, v136
	s_waitcnt lgkmcnt(0)
	v_mfma_f32_16x16x32_bf16 v[60:63], v[72:75], v[150:153], v[60:63]
	v_add_u32_e32 v72, 0x1d400, v136
	v_mfma_f32_16x16x32_bf16 v[64:67], v[154:157], v[150:153], v[68:71]
	ds_read_b128 v[154:157], v2
	ds_read_b128 v[168:171], v72
	v_add_u32_e32 v2, 0x1f400, v136
	v_add_u32_e32 v72, 0x21400, v136
	v_mfma_f32_16x16x32_bf16 v[68:71], v[158:161], v[150:153], v[84:87]
	s_nop 2
	ds_read_b128 v[84:87], v2
	ds_read_b128 v[158:161], v72
	v_add_u32_e32 v2, 0x23400, v136
	ds_read_b128 v[180:183], v2
	v_mfma_f32_16x16x32_bf16 v[72:75], v[176:179], v[150:153], v[88:91]
	s_waitcnt lgkmcnt(0)
	v_mfma_f32_16x16x32_bf16 v[76:79], v[154:157], v[150:153], v[76:79]
	v_mfma_f32_16x16x32_bf16 v[80:83], v[168:171], v[150:153], v[80:83]
	v_mfma_f32_16x16x32_bf16 v[88:91], v[158:161], v[150:153], v[96:99]
	s_nop 2
	ds_read_b128 v[96:99], v136 offset:25600
	ds_read_b128 v[154:157], v136 offset:27648
	ds_read_b128 v[158:161], v136 offset:29696
	ds_read_b128 v[168:171], v136 offset:31744
	v_mfma_f32_16x16x32_bf16 v[84:87], v[84:87], v[150:153], v[92:95]
	v_mfma_f32_16x16x32_bf16 v[92:95], v[180:183], v[150:153], v[172:175]
	s_waitcnt lgkmcnt(0)
	v_mfma_f32_16x16x32_bf16 v[96:99], v[96:99], v[150:153], v[100:103]
	v_mfma_f32_16x16x32_bf16 v[100:103], v[154:157], v[150:153], v[104:107]
	s_nop 0
	ds_read_b64_tr_b16 v[156:157], v145 offset:16384
	ds_read_b128 v[172:175], v143
	v_mfma_f32_16x16x32_bf16 v[108:111], v[158:161], v[150:153], v[108:111]
	ds_read_b128 v[158:161], v143 offset:8192
	ds_read_b64_tr_b16 v[154:155], v142 offset:16384
	ds_read_b128 v[176:179], v140 offset:16384
	v_mfma_f32_16x16x32_bf16 v[104:107], v[168:171], v[150:153], v[52:55]
	s_waitcnt lgkmcnt(1)
	v_mfma_f32_16x16x32_bf16 v[52:55], v[154:157], v[172:175], v[56:59]
	s_nop 2
	ds_read_b64_tr_b16 v[58:59], v146 offset:16384
	ds_read_b128 v[150:153], v143 offset:1024
	v_mfma_f32_16x16x32_bf16 v[48:51], v[154:157], v[158:161], v[48:51]
	ds_read_b128 v[158:161], v143 offset:9216
	ds_read_b64_tr_b16 v[56:57], v142 offset:20480
	ds_read_b128 v[168:171], v140 offset:17408
	s_waitcnt lgkmcnt(5)
	v_mfma_f32_16x16x32_bf16 v[44:47], v[154:157], v[176:179], v[44:47]
	s_waitcnt lgkmcnt(1)
	v_mfma_f32_16x16x32_bf16 v[52:55], v[56:59], v[150:153], v[52:55]
	ds_read_b64_tr_b16 v[152:153], v147 offset:16384
	ds_read_b128 v[154:157], v143 offset:2048
	v_mfma_f32_16x16x32_bf16 v[48:51], v[56:59], v[158:161], v[48:51]
	ds_read_b128 v[158:161], v143 offset:10240
	ds_read_b64_tr_b16 v[150:151], v142 offset:24576
	ds_read_b128 v[172:175], v140 offset:18432
	s_waitcnt lgkmcnt(5)
	v_mfma_f32_16x16x32_bf16 v[44:47], v[56:59], v[168:171], v[44:47]
	s_waitcnt lgkmcnt(1)
	v_mfma_f32_16x16x32_bf16 v[52:55], v[150:153], v[154:157], v[52:55]
	ds_read_b64_tr_b16 v[58:59], v148 offset:16384
	ds_read_b128 v[154:157], v143 offset:3072
	v_mfma_f32_16x16x32_bf16 v[48:51], v[150:153], v[158:161], v[48:51]
	ds_read_b128 v[158:161], v143 offset:11264
	ds_read_b64_tr_b16 v[56:57], v142 offset:28672
	ds_read_b128 v[168:171], v140 offset:19456
	s_waitcnt lgkmcnt(5)
	v_mfma_f32_16x16x32_bf16 v[150:153], v[150:153], v[172:175], v[44:47]
	s_waitcnt lgkmcnt(1)
	v_mfma_f32_16x16x32_bf16 v[44:47], v[56:59], v[154:157], v[52:55]
	v_mfma_f32_16x16x32_bf16 v[48:51], v[56:59], v[158:161], v[48:51]
	s_waitcnt lgkmcnt(0)
	v_mfma_f32_16x16x32_bf16 v[52:55], v[56:59], v[168:171], v[150:153]
	s_waitcnt vmcnt(0)
	s_and_b64 vcc, exec, s[74:75]
	s_barrier
	s_cbranch_vccnz .LBB0_200
	s_mov_b64 s[0:1], 0x10000
	v_lshlrev_b32_e32 v2, 3, v119
	v_lshl_add_u64 v[56:57], v[120:121], 0, s[0:1]
	v_lshl_add_u64 v[58:59], s[28:29], 0, v[56:57]
	v_lshlrev_b32_e32 v2, 1, v2
	v_lshl_add_u64 v[56:57], s[26:27], 0, v[56:57]
	s_mov_b32 m0, s51
	v_lshl_add_u64 v[56:57], v[56:57], 0, v[2:3]
	v_lshl_add_u64 v[58:59], v[58:59], 0, v[2:3]
	global_load_lds_dwordx4 v[56:57], off
	s_mov_b32 m0, s84
	v_lshl_add_u64 v[150:151], v[56:57], 0, 64
	global_load_lds_dwordx4 v[58:59], off
	s_mov_b32 m0, s85
	v_lshl_add_u64 v[120:121], v[58:59], 0, 64
	global_load_lds_dwordx4 v[150:151], off
	s_mov_b32 m0, s88
	s_nop 0
	global_load_lds_dwordx4 v[120:121], off
; #define SBAR __builtin_amdgcn_sched_barrier(0)
; #define LD_KF(dst, half, kk) _Pragma("unroll") for (int i_ = 0; i_ < 4; ++i_) dst[i_] = ldsfrag(ks, LQ, ((half) * 4 + i_) * 16 + fr, (kk) * 32 + fq * 8)
; #define MM_KF(srcf, half, kk) _Pragma("unroll") for (int i_ = 0; i_ < 4; ++i_) acc_qk[(half) * 4 + i_] = mfma16(srcf[i_], qf[kk], acc_qk[(half) * 4 + i_])
; #define LD_CF(dst, kk) _Pragma("unroll") for (int i_ = 0; i_ < 5; ++i_) dst[i_] = ldsfrag(CTe, LC, i_ * 16 + fr, ds * 64 + (kk) * 32 + fq * 8)
; #define MM_CF(srcf, kk) _Pragma("unroll") for (int i_ = 0; i_ < 5; ++i_) acc_o[i_] = mfma16(srcf[i_], qf[kk], acc_o[i_])
; #define LD_ST(dst, kk) do { dst[0] = ldsfrag_tr(ks, LQ, (kk) * 32, db * 16, lane); \
;         _Pragma("unroll") for (int j_ = 0; j_ < 3; ++j_) dst[1 + j_] = ldsfrag(vwT, LW, (j_ < 2 ? eb0 + 2 * j_ : 4) * 16 + fr, (kk) * 32 + fq * 8); } while (0)
; #define MM_ST(srcf) _Pragma("unroll") for (int j_ = 0; j_ < 3; ++j_) acc_c[ds][j_] = mfma16(srcf[0], srcf[1 + j_], acc_c[ds][j_])
; #define SBAR __builtin_amdgcn_sched_barrier(0)
; __device__ void mlstm_item(const Params& p, int layer, int b, int hh, int q4) {
;     ...
;     for (int i = 0; i < 4; ++i)
; #pragma unroll
;       for (int j = 0; j < 3; ++j) acc_c[i][j] *= s_old;
;     ...
;     for (int ds = 0; ds < 4; ++ds) {
;       bf16_t* qs = qk0 + (ds & 1) * 16384;
;       bf16_t* ks = qs + 8192;
;       asm volatile("s_waitcnt vmcnt(0)" ::: "memory");
;       __syncthreads();
;       if (ds < 3) dma_qk((ds + 1) & 1, rbase, ds + 1, lane);
;       else if (ch + 1 < SEQ / 128) dma_qk(0, rbase + 128, 0, lane);
;       bf16x8 qf[2];
; #pragma unroll
;       for (int kk = 0; kk < 2; ++kk) qf[kk] = ldsfrag(qs, LQ, w * 16 + fr, kk * 32 + fq * 8);
;     ...
;       {
;         bf16x8 r0[4], r1[5], r2[4], r3[4], r4[5], r5[4], t0[4], t1[4], t2[4], t3[4];
;         LD_KF(r0, 0, 0); SBAR;
;         LD_CF(r1, 0); MM_KF(r0, 0, 0); SBAR;
;         LD_KF(r2, 1, 0); MM_CF(r1, 0); SBAR;
;         LD_KF(r3, 0, 1); MM_KF(r2, 1, 0); SBAR;
;         LD_CF(r4, 1); MM_KF(r3, 0, 1); SBAR;
;         LD_KF(r5, 1, 1); MM_CF(r4, 1); SBAR;
;         LD_ST(t0, 0); MM_KF(r5, 1, 1); SBAR;
;         LD_ST(t1, 1); MM_ST(t0); SBAR;
;         LD_ST(t2, 2); MM_ST(t1); SBAR;
;         LD_ST(t3, 3); MM_ST(t2); SBAR;
;         MM_ST(t3); SBAR;
;       }
;     ...
;     }
;     __syncthreads();
.LBB0_200:
	v_mov_b32_e32 v119, v118
	v_mov_b32_e32 v56, v118
	v_mov_b32_e32 v57, v118
	v_pk_mul_f32 v[10:11], v[10:11], v[56:57]
	v_pk_mul_f32 v[8:9], v[8:9], v[118:119]
	v_pk_mul_f32 v[14:15], v[14:15], v[56:57]
	v_pk_mul_f32 v[12:13], v[12:13], v[118:119]
	v_pk_mul_f32 v[18:19], v[18:19], v[56:57]
	v_pk_mul_f32 v[16:17], v[16:17], v[118:119]
	ds_read_b128 v[56:59], v144 offset:32768
	ds_read_b128 v[118:121], v144 offset:33792
	ds_read_b128 v[150:153], v136 offset:49152
	ds_read_b128 v[154:157], v136 offset:51200
	ds_read_b128 v[158:161], v136 offset:53248
	ds_read_b128 v[168:171], v136 offset:55296
	s_waitcnt lgkmcnt(0)
	v_mfma_f32_16x16x32_bf16 v[60:63], v[150:153], v[56:59], v[60:63]
	v_mfma_f32_16x16x32_bf16 v[64:67], v[154:157], v[56:59], v[64:67]
	ds_read_b128 v[150:153], v141 offset:14336
	ds_read_b128 v[154:157], v141 offset:22528
	v_mfma_f32_16x16x32_bf16 v[68:71], v[158:161], v[56:59], v[68:71]
	ds_read_b128 v[158:161], v141 offset:30720
	ds_read_b128 v[172:175], v141 offset:6144
	ds_read_b128 v[176:179], v141 offset:38912
	v_mfma_f32_16x16x32_bf16 v[72:75], v[168:171], v[56:59], v[72:75]
	s_waitcnt lgkmcnt(0)
	v_mfma_f32_16x16x32_bf16 v[80:83], v[150:153], v[56:59], v[80:83]
	v_mfma_f32_16x16x32_bf16 v[84:87], v[154:157], v[56:59], v[84:87]
	v_mfma_f32_16x16x32_bf16 v[88:91], v[158:161], v[56:59], v[88:91]
	ds_read_b128 v[150:153], v136 offset:57344
	ds_read_b128 v[154:157], v136 offset:59392
	ds_read_b128 v[158:161], v136 offset:61440
	ds_read_b128 v[168:171], v136 offset:63488
	v_mfma_f32_16x16x32_bf16 v[76:79], v[172:175], v[56:59], v[76:79]
	v_mfma_f32_16x16x32_bf16 v[172:175], v[176:179], v[56:59], v[92:95]
	s_waitcnt lgkmcnt(0)
	v_mfma_f32_16x16x32_bf16 v[150:153], v[150:153], v[56:59], v[96:99]
	v_mfma_f32_16x16x32_bf16 v[108:111], v[158:161], v[56:59], v[108:111]
	ds_read_b128 v[92:95], v136 offset:50176
	s_nop 0
	ds_read_b128 v[96:99], v136 offset:52224
	ds_read_b128 v[158:161], v136 offset:54272
	ds_read_b128 v[176:179], v136 offset:56320
	v_mfma_f32_16x16x32_bf16 v[154:157], v[154:157], v[56:59], v[100:103]
	v_mfma_f32_16x16x32_bf16 v[168:171], v[168:171], v[56:59], v[104:107]
	s_waitcnt lgkmcnt(0)
	v_mfma_f32_16x16x32_bf16 v[104:107], v[92:95], v[118:121], v[60:63]
	v_add_u32_e32 v2, 0x1bc00, v136
	s_nop 1
	v_add_u32_e32 v60, 0x1dc00, v136
	ds_read_b128 v[56:59], v2
	ds_read_b128 v[60:63], v60
	v_add_u32_e32 v2, 0x1fc00, v136
	v_mfma_f32_16x16x32_bf16 v[100:103], v[96:99], v[118:121], v[64:67]
	s_nop 2
	v_add_u32_e32 v64, 0x21c00, v136
	v_mfma_f32_16x16x32_bf16 v[96:99], v[158:161], v[118:121], v[68:71]
	ds_read_b128 v[158:161], v2
	ds_read_b128 v[180:183], v64
	v_add_u32_e32 v2, 0x23c00, v136
	ds_read_b128 v[184:187], v2
	v_mfma_f32_16x16x32_bf16 v[92:95], v[176:179], v[118:121], v[72:75]
	s_waitcnt lgkmcnt(0)
	v_mfma_f32_16x16x32_bf16 v[68:71], v[56:59], v[118:121], v[76:79]
	v_mfma_f32_16x16x32_bf16 v[64:67], v[60:63], v[118:121], v[80:83]
	v_mfma_f32_16x16x32_bf16 v[60:63], v[158:161], v[118:121], v[84:87]
	s_nop 0
	ds_read_b128 v[76:79], v136 offset:58368
	ds_read_b128 v[80:83], v136 offset:60416
	ds_read_b128 v[158:161], v136 offset:62464
	ds_read_b128 v[176:179], v136 offset:64512
	v_mfma_f32_16x16x32_bf16 v[56:59], v[180:183], v[118:121], v[88:91]
	v_mfma_f32_16x16x32_bf16 v[72:75], v[184:187], v[118:121], v[172:175]
	s_waitcnt lgkmcnt(0)
	v_mfma_f32_16x16x32_bf16 v[88:91], v[76:79], v[118:121], v[150:153]
	v_mfma_f32_16x16x32_bf16 v[84:87], v[80:83], v[118:121], v[154:157]
	s_nop 0
	s_nop 0
	ds_read_b64_tr_b16 v[152:153], v145 offset:49152
	ds_read_b128 v[154:157], v143
	v_mfma_f32_16x16x32_bf16 v[80:83], v[158:161], v[118:121], v[108:111]
	s_nop 2
	ds_read_b128 v[108:111], v143 offset:8192
	ds_read_b64_tr_b16 v[150:151], v142 offset:49152
	ds_read_b128 v[158:161], v140 offset:16384
	v_mfma_f32_16x16x32_bf16 v[76:79], v[176:179], v[118:121], v[168:171]
	s_waitcnt lgkmcnt(1)
	v_mfma_f32_16x16x32_bf16 v[8:11], v[150:153], v[154:157], v[8:11]
	ds_read_b64_tr_b16 v[120:121], v146 offset:49152
	ds_read_b128 v[154:157], v143 offset:1024
	v_mfma_f32_16x16x32_bf16 v[12:15], v[150:153], v[108:111], v[12:15]
	ds_read_b128 v[108:111], v143 offset:9216
	ds_read_b64_tr_b16 v[118:119], v142 offset:53248
	ds_read_b128 v[168:171], v140 offset:17408
	s_waitcnt lgkmcnt(5)
	v_mfma_f32_16x16x32_bf16 v[16:19], v[150:153], v[158:161], v[16:19]
	s_waitcnt lgkmcnt(1)
	v_mfma_f32_16x16x32_bf16 v[8:11], v[118:121], v[154:157], v[8:11]
	ds_read_b64_tr_b16 v[146:147], v147 offset:49152
	ds_read_b128 v[150:153], v143 offset:2048
	v_mfma_f32_16x16x32_bf16 v[12:15], v[118:121], v[108:111], v[12:15]
	ds_read_b128 v[108:111], v143 offset:10240
	ds_read_b64_tr_b16 v[144:145], v142 offset:57344
	ds_read_b128 v[154:157], v140 offset:18432
	s_waitcnt lgkmcnt(5)
	v_mfma_f32_16x16x32_bf16 v[16:19], v[118:121], v[168:171], v[16:19]
	s_waitcnt lgkmcnt(1)
	v_mfma_f32_16x16x32_bf16 v[8:11], v[144:147], v[150:153], v[8:11]
	ds_read_b64_tr_b16 v[120:121], v148 offset:49152
	ds_read_b128 v[148:151], v143 offset:3072
	v_mfma_f32_16x16x32_bf16 v[12:15], v[144:147], v[108:111], v[12:15]
	ds_read_b128 v[108:111], v143 offset:11264
	ds_read_b64_tr_b16 v[118:119], v142 offset:61440
	ds_read_b128 v[140:143], v140 offset:19456
	s_waitcnt lgkmcnt(5)
	v_mfma_f32_16x16x32_bf16 v[16:19], v[144:147], v[154:157], v[16:19]
	s_waitcnt lgkmcnt(1)
	v_mfma_f32_16x16x32_bf16 v[8:11], v[118:121], v[148:151], v[8:11]
	v_mfma_f32_16x16x32_bf16 v[12:15], v[118:121], v[108:111], v[12:15]
	s_waitcnt lgkmcnt(0)
	v_mfma_f32_16x16x32_bf16 v[16:19], v[118:121], v[140:143], v[16:19]
	v_lshlrev_b32_e32 v2, 2, v138
	v_or_b32_e32 v108, s91, v117
	v_bitop3_b32 v108, v108, v139, v2 bitop3:0x36
	v_cndmask_b32_e64 v109, 0, 1, s[42:43]
	v_cmp_ne_u32_e64 s[0:1], 1, v109
	s_andn2_b64 vcc, exec, s[42:43]
	v_lshl_add_u32 v108, v108, 1, s92
	s_barrier
	s_cbranch_vccz .LBB0_247
	v_cndmask_b32_e64 v109, 0, 1, s[4:5]
	v_cmp_ne_u32_e64 s[12:13], 1, v109
	s_andn2_b64 vcc, exec, s[4:5]
	s_cbranch_vccz .LBB0_248

; __device__ __forceinline__ size_t pidx(size_t row, int col) { return ((size_t)(col >> 8) * MTOK + row) * PLD + (col & 255); }
; __device__ void mlstm_item(const Params& p, int layer, int b, int hh, int q4) {
;     ...
;         *(u32x2*)(Pm + swz(l, sb * 16 + fq * 4, LW)) = pack4(v);
;       }
;     }
;     (void)rsum;
;     {
;       const bf16_t* orow = proj + pidx(rbase + l, MO + hh * 256 + q4 * 64);
; #pragma unroll
;       for (int eb = 0; eb < 4; ++eb) oo[eb] = *(const u32x2*)(orow + eb * 16 + fq * 4);
;       if (ch + 1 < SEQ / 128) {
; #pragma unroll
;         for (int i = 0; i < 8; ++i)
;           pfv[i] = *(const unsigned*)(proj + pidx(rbase + 128 + vl0 + i, MV + hh * 256 + q4 * 64 + vcp));
;       }
.LBB0_236:
	s_add_u32 s0, s16, s72
	v_cvt_pk_bf16_f32 v76, v84, v85
	v_cvt_pk_bf16_f32 v77, v80, v81
	v_ashrrev_i32_e32 v117, 31, v116
	s_addc_u32 s1, s17, s73
	ds_write_b64 v6, v[76:77] offset:35840
	v_lshl_add_u64 v[76:77], s[0:1], 0, v[116:117]
	v_lshlrev_b64 v[76:77], 9, v[76:77]
	v_lshl_add_u64 v[76:77], s[24:25], 0, v[76:77]
	s_mov_b32 s13, s97
	s_lshl_b32 s12, s50, 1
	v_lshl_add_u64 v[76:77], v[76:77], 0, s[12:13]
	v_lshlrev_b32_e32 v2, 1, v2
	v_lshl_add_u64 v[78:79], v[76:77], 0, v[2:3]
	s_mov_b64 s[12:13], 0x1e000000
	v_lshl_add_u64 v[76:77], v[78:79], 0, s[12:13]
	v_add_co_u32_e32 v78, vcc, 0x1e000000, v78
	s_nop 1
	v_addc_co_u32_e32 v79, vcc, 0, v79, vcc
	global_load_dwordx2 v[84:85], v[78:79], off
	global_load_dwordx2 v[82:83], v[76:77], off offset:32
	global_load_dwordx2 v[80:81], v[76:77], off offset:64
	s_nop 0
	global_load_dwordx2 v[78:79], v[76:77], off offset:96
	s_andn2_b64 vcc, exec, s[76:77]
	s_cbranch_vccnz .LBB0_238
	v_and_b32_e32 v2, 62, v5
	v_ashrrev_i32_e32 v5, 31, v4
	v_lshl_add_u64 v[4:5], s[0:1], 0, v[4:5]
	v_lshlrev_b64 v[4:5], 9, v[4:5]
	s_mov_b64 s[0:1], 0x10000
	v_or_b32_e32 v2, s50, v2
	v_lshl_add_u64 v[4:5], v[4:5], 0, s[0:1]
	v_lshl_add_u64 v[86:87], s[24:25], 0, v[4:5]
	v_lshlrev_b32_e32 v2, 1, v2
	v_lshl_add_u64 v[86:87], v[86:87], 0, v[2:3]
	v_add_co_u32_e32 v86, vcc, 0x1a000000, v86
	s_nop 1
	v_addc_co_u32_e32 v87, vcc, 0, v87, vcc
	global_load_dword v127, v[86:87], off
	v_or_b32_e32 v86, 0x200, v4
	v_mov_b32_e32 v87, v5
	v_lshl_add_u64 v[86:87], s[24:25], 0, v[86:87]
	v_lshl_add_u64 v[86:87], v[86:87], 0, v[2:3]
	v_add_co_u32_e32 v86, vcc, 0x1a000000, v86
	s_nop 1
	v_addc_co_u32_e32 v87, vcc, 0, v87, vcc
	global_load_dword v128, v[86:87], off
	v_or_b32_e32 v86, 0x400, v4
	v_mov_b32_e32 v87, v5
	v_lshl_add_u64 v[86:87], s[24:25], 0, v[86:87]
	v_lshl_add_u64 v[86:87], v[86:87], 0, v[2:3]
	v_add_co_u32_e32 v86, vcc, 0x1a000000, v86
	s_nop 1
	v_addc_co_u32_e32 v87, vcc, 0, v87, vcc
	global_load_dword v129, v[86:87], off
	v_or_b32_e32 v86, 0x600, v4
	v_mov_b32_e32 v87, v5
	v_lshl_add_u64 v[86:87], s[24:25], 0, v[86:87]
	v_lshl_add_u64 v[86:87], v[86:87], 0, v[2:3]
	v_add_co_u32_e32 v86, vcc, 0x1a000000, v86
	s_nop 1
	v_addc_co_u32_e32 v87, vcc, 0, v87, vcc
	global_load_dword v130, v[86:87], off
	v_or_b32_e32 v86, 0x800, v4
	v_mov_b32_e32 v87, v5
	v_lshl_add_u64 v[86:87], s[24:25], 0, v[86:87]
	v_lshl_add_u64 v[86:87], v[86:87], 0, v[2:3]
	v_add_co_u32_e32 v86, vcc, 0x1a000000, v86
	s_nop 1
	v_addc_co_u32_e32 v87, vcc, 0, v87, vcc
	global_load_dword v131, v[86:87], off
	v_or_b32_e32 v86, 0xa00, v4
	v_mov_b32_e32 v87, v5
	v_lshl_add_u64 v[86:87], s[24:25], 0, v[86:87]
	v_lshl_add_u64 v[86:87], v[86:87], 0, v[2:3]
	v_add_co_u32_e32 v86, vcc, 0x1a000000, v86
	s_nop 1
	v_addc_co_u32_e32 v87, vcc, 0, v87, vcc
	global_load_dword v132, v[86:87], off
	v_or_b32_e32 v86, 0xc00, v4
	v_mov_b32_e32 v87, v5
	v_lshl_add_u64 v[86:87], s[24:25], 0, v[86:87]
	v_lshl_add_u64 v[86:87], v[86:87], 0, v[2:3]
	v_or_b32_e32 v4, 0xe00, v4
	v_add_co_u32_e32 v86, vcc, 0x1a000000, v86
	v_lshl_add_u64 v[4:5], s[24:25], 0, v[4:5]
	s_nop 0
	v_addc_co_u32_e32 v87, vcc, 0, v87, vcc
	v_lshl_add_u64 v[4:5], v[4:5], 0, v[2:3]
	v_add_co_u32_e32 v4, vcc, 0x1a000000, v4
	global_load_dword v133, v[86:87], off
	s_nop 0
	v_addc_co_u32_e32 v5, vcc, 0, v5, vcc
	global_load_dword v134, v[4:5], off

; __device__ void mlstm_item(const Params& p, int layer, int b, int hh, int q4) {
;     ...
;     if (w == 0 && ch + 1 < SEQ / 128) {
;       m_run = mlstm_scalars(gpre, ib, fb, m_run, scal + ((ch + 1) & 1) * SCN, lane0);
;       if (ch + 2 < SEQ / 128) mlstm_gates(small, rbase + 256, hh, lane0, gpre);
;     }
.LBB0_245:
	s_or_b64 exec, exec, s[0:1]
	s_cmp_gt_u32 s7, 13
	s_cbranch_scc1 .LBB0_195
	global_load_dword v0, v[114:115], off
	global_load_dword v1, v[114:115], off offset:256
	global_load_dword v125, v[114:115], off offset:288
	global_load_dword v126, v[114:115], off offset:32
	s_branch .LBB0_195

; template <int WIN>
; __device__ __forceinline__ void pool_rows(const bf16_t* __restrict__ src, bf16_t* __restrict__ dst, int tseq) {
;     ...
; #pragma unroll
;   for (int i = 0; i < 8; ++i) {
;     float u[8], o[8];
;     unpack8(U[i], u);
;     if (i - WIN >= 0) unpack8(U[(i - WIN) >= 0 ? (i - WIN) : 0], o);
;     else unpack8(H[i < WIN ? i : 0], o);
; #pragma unroll
;     for (int k = 0; k < 8; ++k) s[k] += u[k] - o[k];
;     const int t = tseq + i;
;     const float inv = __builtin_amdgcn_rcpf((float)min(t + 1, WIN));
;     u32x4 r;
;     r.x = pack2(s[0] * inv - u[0], s[1] * inv - u[1]);
;     r.y = pack2(s[2] * inv - u[2], s[3] * inv - u[3]);
;     r.z = pack2(s[4] * inv - u[4], s[5] * inv - u[5]);
;     r.w = pack2(s[6] * inv - u[6], s[7] * inv - u[7]);
;     *(u32x4*)(dst + (long)i * DM) = r;
;   }
.LBB0_263:
	s_or_b64 exec, exec, s[2:3]
	s_waitcnt vmcnt(0) lgkmcnt(0)
	v_lshlrev_b32_e32 v48, 16, v40
	v_and_b32_e32 v40, 0xffff0000, v40
	v_rcp_f32_e32 v2, v2
	v_lshlrev_b32_e32 v49, 16, v32
	v_add_f32_e32 v50, 0, v48
	v_and_b32_e32 v51, 0xffff0000, v32
	v_add_f32_e32 v32, 0, v40
	v_lshlrev_b32_e32 v60, 16, v36
	v_and_b32_e32 v36, 0xffff0000, v36
	v_sub_f32_e32 v48, v49, v48
	v_sub_f32_e32 v40, v51, v40
	v_lshlrev_b32_e32 v61, 16, v28
	v_add_f32_e32 v50, v50, v60
	v_and_b32_e32 v62, 0xffff0000, v28
	v_add_f32_e32 v28, v32, v36
	v_add_f32_e32 v48, v48, v50
	v_add_f32_e32 v28, v40, v28
	v_lshlrev_b32_e32 v53, 16, v41
	v_and_b32_e32 v41, 0xffff0000, v41
	v_fma_f32 v50, v2, v48, -v49
	v_fma_f32 v32, v2, v28, -v51
	v_lshlrev_b32_e32 v52, 16, v33
	v_add_f32_e32 v54, 0, v53
	v_and_b32_e32 v55, 0xffff0000, v33
	v_add_f32_e32 v33, 0, v41
	v_cvt_pk_bf16_f32 v32, v50, v32
	v_lshlrev_b32_e32 v50, 16, v37
	v_and_b32_e32 v37, 0xffff0000, v37
	v_sub_f32_e32 v53, v52, v53
	v_sub_f32_e32 v41, v55, v41
	v_lshlrev_b32_e32 v40, 16, v29
	v_add_f32_e32 v54, v54, v50
	v_and_b32_e32 v63, 0xffff0000, v29
	v_add_f32_e32 v29, v33, v37
	v_lshlrev_b32_e32 v56, 16, v42
	v_and_b32_e32 v42, 0xffff0000, v42
	v_add_f32_e32 v53, v53, v54
	v_add_f32_e32 v29, v41, v29
	v_lshlrev_b32_e32 v57, 16, v34
	v_add_f32_e32 v58, 0, v56
	v_and_b32_e32 v59, 0xffff0000, v34
	v_add_f32_e32 v34, 0, v42
	v_fma_f32 v54, v2, v53, -v52
	v_fma_f32 v33, v2, v29, -v55
	v_lshlrev_b32_e32 v41, 16, v38
	v_and_b32_e32 v38, 0xffff0000, v38
	v_lshlrev_b32_e32 v44, 16, v43
	v_sub_f32_e32 v56, v57, v56
	v_sub_f32_e32 v42, v59, v42
	v_cvt_pk_bf16_f32 v33, v54, v33
	v_lshlrev_b32_e32 v54, 16, v30
	v_add_f32_e32 v58, v58, v41
	v_and_b32_e32 v64, 0xffff0000, v30
	v_add_f32_e32 v30, v34, v38
	v_and_b32_e32 v43, 0xffff0000, v43
	v_add_f32_e32 v45, 0, v44
	v_lshlrev_b32_e32 v47, 16, v39
	v_add_f32_e32 v56, v56, v58
	v_add_f32_e32 v30, v42, v30
	v_sub_f32_e32 v42, v61, v60
	v_lshlrev_b32_e32 v60, 16, v35
	v_add_f32_e32 v46, 0, v43
	v_and_b32_e32 v39, 0xffff0000, v39
	v_add_f32_e32 v45, v45, v47
	v_fma_f32 v58, v2, v56, -v57
	v_fma_f32 v34, v2, v30, -v59
	v_sub_f32_e32 v44, v60, v44
	v_and_b32_e32 v65, 0xffff0000, v35
	v_add_f32_e32 v46, v46, v39
	v_cvt_pk_bf16_f32 v34, v58, v34
	v_lshlrev_b32_e32 v58, 16, v27
	v_add_f32_e32 v44, v44, v45
	v_and_b32_e32 v66, 0xffff0000, v27
	v_sub_f32_e32 v27, v65, v43
	v_sub_f32_e32 v36, v62, v36
	v_fma_f32 v45, v2, v44, -v60
	v_add_f32_e32 v27, v27, v46
	v_add_f32_e32 v36, v36, v28
	v_sub_f32_e32 v28, v40, v50
	v_fma_f32 v2, v2, v27, -v65
	v_cvt_pk_bf16_f32 v35, v45, v2
	v_and_b32_e32 v45, 0xffff0000, v31
	v_add_f32_e32 v42, v42, v48
	v_add_f32_e32 v48, v28, v53
	v_sub_f32_e32 v28, v63, v37
	global_store_dwordx4 v[0:1], v[32:35], off
	v_and_b32_e32 v46, 0xffff0000, v23
	v_add_f32_e32 v37, v28, v29
	v_lshlrev_b32_e32 v34, 16, v23
	v_lshlrev_b32_e32 v35, 16, v31
	v_sub_f32_e32 v23, v45, v39
	v_sub_f32_e32 v28, v54, v41
	v_sub_f32_e32 v32, v66, v65
	v_sub_f32_e32 v33, v35, v47
	v_add_f32_e32 v23, v23, v27
	s_movk_i32 s0, 0x1000
	v_add_f32_e32 v41, v28, v56
	v_sub_f32_e32 v28, v64, v38
	v_sub_f32_e32 v2, v58, v60
	v_add_f32_e32 v33, v33, v44
	v_fma_f32 v27, v23, 0.5, -v45
	v_add_f32_e32 v23, v32, v23
	v_add_co_u32_e32 v32, vcc, s0, v0
	v_add_f32_e32 v38, v28, v30
	v_fma_f32 v28, v42, 0.5, -v61
	v_fma_f32 v29, v36, 0.5, -v62
	v_fma_f32 v30, v48, 0.5, -v40
	v_fma_f32 v43, v33, 0.5, -v35
	v_add_f32_e32 v2, v2, v33
	v_addc_co_u32_e32 v33, vcc, 0, v1, vcc
	v_fma_f32 v50, v37, 0.5, -v63
	v_fma_f32 v53, v41, 0.5, -v54
	v_fma_f32 v56, v38, 0.5, -v64
	v_cvt_pk_bf16_f32 v28, v28, v29
	v_cvt_pk_bf16_f32 v29, v30, v50
	v_cvt_pk_bf16_f32 v30, v53, v56
	v_cvt_pk_bf16_f32 v31, v43, v27
	global_store_dwordx4 v[32:33], v[28:31], off
	v_sub_f32_e32 v27, v34, v35
	v_and_b32_e32 v33, 0xffff0000, v24
	v_fma_f32 v44, v2, 0.5, -v58
	v_add_f32_e32 v2, v27, v2
	v_sub_f32_e32 v27, v46, v45
	v_lshlrev_b32_e32 v30, 16, v12
	v_lshlrev_b32_e32 v31, 16, v24
	v_and_b32_e32 v35, 0xffff0000, v12
	v_sub_f32_e32 v12, v33, v51
	v_add_f32_e32 v28, v27, v23
	v_sub_f32_e32 v27, v31, v49
	v_add_f32_e32 v36, v12, v36
	v_add_f32_e32 v32, v27, v42
	v_fma_f32 v12, v36, 0.5, -v33
	v_lshlrev_b32_e32 v43, 16, v25
	v_fma_f32 v27, v32, 0.5, -v31
	v_cvt_pk_bf16_f32 v24, v27, v12
	v_sub_f32_e32 v12, v43, v52
	v_and_b32_e32 v47, 0xffff0000, v25
	v_lshlrev_b32_e32 v42, 16, v13
	v_add_f32_e32 v45, v12, v48
	v_and_b32_e32 v48, 0xffff0000, v13
	v_sub_f32_e32 v13, v47, v55
	v_fma_f32 v12, v45, 0.5, -v43
	v_add_f32_e32 v37, v13, v37
	v_lshlrev_b32_e32 v50, 16, v26
	v_fma_f32 v13, v37, 0.5, -v47
	v_cvt_pk_bf16_f32 v25, v12, v13
	v_sub_f32_e32 v12, v50, v57
	v_and_b32_e32 v51, 0xffff0000, v26
	v_add_f32_e32 v41, v12, v41
	v_sub_f32_e32 v13, v51, v59
	v_lshlrev_b32_e32 v49, 16, v14
	v_fma_f32 v12, v41, 0.5, -v50
	v_and_b32_e32 v52, 0xffff0000, v14
	v_add_f32_e32 v14, v13, v38
	v_fma_f32 v39, v23, 0.5, -v66
	v_fma_f32 v13, v14, 0.5, -v51
	v_cvt_pk_bf16_f32 v26, v12, v13
	v_add_co_u32_e32 v12, vcc, s96, v0
	v_cvt_pk_bf16_f32 v27, v44, v39
	v_and_b32_e32 v39, 0xffff0000, v20
	s_nop 0
	v_addc_co_u32_e32 v13, vcc, 0, v1, vcc
	global_store_dwordx4 v[12:13], v[24:27], off
	v_sub_f32_e32 v12, v30, v31
	v_lshlrev_b32_e32 v31, 16, v8
	v_sub_f32_e32 v24, v42, v43
	v_and_b32_e32 v43, 0xffff0000, v8
	v_sub_f32_e32 v8, v39, v62
	v_sub_f32_e32 v13, v35, v33
	v_add_f32_e32 v8, v8, v36
	v_lshlrev_b32_e32 v44, 16, v21
	v_lshlrev_b32_e32 v33, 16, v20
	v_fma_f32 v20, v8, 0.5, -v39
	v_add_f32_e32 v36, v13, v8
	v_sub_f32_e32 v8, v44, v40
	v_sub_f32_e32 v25, v48, v47
	v_sub_f32_e32 v38, v33, v61
	v_add_f32_e32 v8, v8, v45
	v_and_b32_e32 v47, 0xffff0000, v21
; template <int WIN>
; __device__ __forceinline__ void pool_rows(const bf16_t* __restrict__ src, bf16_t* __restrict__ dst, int tseq) {
;     ...
; #pragma unroll
;   for (int i = 0; i < 8; ++i) {
;     float u[8], o[8];
;     unpack8(U[i], u);
;     if (i - WIN >= 0) unpack8(U[(i - WIN) >= 0 ? (i - WIN) : 0], o);
;     else unpack8(H[i < WIN ? i : 0], o);
; #pragma unroll
;     for (int k = 0; k < 8; ++k) s[k] += u[k] - o[k];
;     const int t = tseq + i;
;     const float inv = __builtin_amdgcn_rcpf((float)min(t + 1, WIN));
;     u32x4 r;
;     r.x = pack2(s[0] * inv - u[0], s[1] * inv - u[1]);
;     r.y = pack2(s[2] * inv - u[2], s[3] * inv - u[3]);
;     r.z = pack2(s[4] * inv - u[4], s[5] * inv - u[5]);
;     r.w = pack2(s[6] * inv - u[6], s[7] * inv - u[7]);
;     *(u32x4*)(dst + (long)i * DM) = r;
;   }
; __device__ void phase_mixers_a(const Params& p, int layer) {
;     ...
;   for (int it = blockIdx.x; it < MTOK / 16; it += G) pool_item(p, it);
	v_add_f32_e32 v32, v38, v32
	v_fma_f32 v40, v8, 0.5, -v44
	v_add_f32_e32 v24, v24, v8
	v_sub_f32_e32 v8, v47, v63
	v_sub_f32_e32 v27, v52, v51
	v_fma_f32 v38, v32, 0.5, -v33
	v_add_f32_e32 v8, v8, v37
	v_lshlrev_b32_e32 v51, 16, v22
	v_sub_f32_e32 v26, v49, v50
	v_cvt_pk_bf16_f32 v20, v38, v20
	v_lshlrev_b32_e32 v38, 16, v9
	v_and_b32_e32 v50, 0xffff0000, v9
	v_fma_f32 v9, v8, 0.5, -v47
	v_add_f32_e32 v25, v25, v8
	v_sub_f32_e32 v8, v51, v54
	v_add_f32_e32 v8, v8, v41
	v_and_b32_e32 v53, 0xffff0000, v22
	v_cvt_pk_bf16_f32 v21, v40, v9
	v_fma_f32 v9, v8, 0.5, -v51
	v_add_f32_e32 v26, v26, v8
	v_sub_f32_e32 v8, v53, v64
	v_add_f32_e32 v8, v8, v14
	s_movk_i32 s0, 0x3000
	v_lshlrev_b32_e32 v40, 16, v10
	v_and_b32_e32 v54, 0xffff0000, v10
	v_fma_f32 v10, v8, 0.5, -v53
	v_add_f32_e32 v27, v27, v8
	v_add_co_u32_e32 v8, vcc, s0, v0
	v_fma_f32 v23, v2, 0.5, -v34
	v_cvt_pk_bf16_f32 v22, v9, v10
	s_nop 0
	v_addc_co_u32_e32 v9, vcc, 0, v1, vcc
	v_fma_f32 v29, v28, 0.5, -v46
	v_add_f32_e32 v32, v12, v32
	v_cvt_pk_bf16_f32 v23, v23, v29
	global_store_dwordx4 v[8:9], v[20:23], off
	v_sub_f32_e32 v8, v31, v33
	v_fma_f32 v12, v32, 0.5, -v30
	v_add_f32_e32 v20, v8, v32
	v_sub_f32_e32 v8, v43, v39
	v_add_f32_e32 v21, v8, v36
	v_sub_f32_e32 v8, v38, v44
	v_add_f32_e32 v22, v8, v24
	v_sub_f32_e32 v8, v50, v47
	v_add_f32_e32 v23, v8, v25
	v_sub_f32_e32 v8, v40, v51
	v_fma_f32 v13, v36, 0.5, -v35
	v_fma_f32 v45, v24, 0.5, -v42
	v_add_f32_e32 v24, v8, v26
	v_sub_f32_e32 v8, v54, v53
	v_lshlrev_b32_e32 v44, 16, v15
	v_fma_f32 v37, v25, 0.5, -v48
	v_cvt_pk_bf16_f32 v12, v12, v13
	v_cvt_pk_bf16_f32 v13, v45, v37
	v_add_f32_e32 v25, v8, v27
	v_sub_f32_e32 v8, v44, v58
	v_and_b32_e32 v45, 0xffff0000, v15
	v_add_f32_e32 v2, v8, v2
	v_sub_f32_e32 v9, v45, v66
	v_fma_f32 v8, v2, 0.5, -v44
	v_add_f32_e32 v28, v9, v28
	s_movk_i32 s0, 0x4000
	v_fma_f32 v9, v28, 0.5, -v45
	v_cvt_pk_bf16_f32 v15, v8, v9
	v_add_co_u32_e32 v8, vcc, s0, v0
	v_fma_f32 v14, v27, 0.5, -v52
	v_lshlrev_b32_e32 v36, 16, v16
	v_addc_co_u32_e32 v9, vcc, 0, v1, vcc
	v_fma_f32 v41, v26, 0.5, -v49
	v_cvt_pk_bf16_f32 v14, v41, v14
	v_and_b32_e32 v16, 0xffff0000, v16
	global_store_dwordx4 v[8:9], v[12:15], off
	v_lshlrev_b32_e32 v37, 16, v17
	v_and_b32_e32 v17, 0xffff0000, v17
	v_sub_f32_e32 v12, v36, v30
	v_add_f32_e32 v14, v12, v20
	v_sub_f32_e32 v12, v16, v35
	v_add_f32_e32 v15, v12, v21
	v_sub_f32_e32 v12, v37, v42
	v_fma_f32 v10, v20, 0.5, -v31
	v_fma_f32 v29, v23, 0.5, -v50
	v_lshlrev_b32_e32 v39, 16, v18
	v_add_f32_e32 v20, v12, v22
	v_sub_f32_e32 v12, v17, v48
	v_fma_f32 v26, v21, 0.5, -v43
	v_fma_f32 v27, v22, 0.5, -v38
	v_fma_f32 v33, v25, 0.5, -v54
	v_and_b32_e32 v18, 0xffff0000, v18
	v_cvt_pk_bf16_f32 v9, v27, v29
	v_add_f32_e32 v21, v12, v23
	v_sub_f32_e32 v12, v39, v49
	v_and_b32_e32 v29, 0xffff0000, v11
	v_fma_f32 v32, v24, 0.5, -v40
	v_lshlrev_b32_e32 v41, 16, v19
	v_and_b32_e32 v19, 0xffff0000, v19
	v_cvt_pk_bf16_f32 v8, v10, v26
	v_cvt_pk_bf16_f32 v10, v32, v33
	v_add_f32_e32 v22, v12, v24
	v_sub_f32_e32 v12, v18, v52
	v_sub_f32_e32 v13, v29, v46
	v_lshlrev_b32_e32 v33, 16, v11
	v_add_f32_e32 v23, v12, v25
	v_sub_f32_e32 v12, v19, v45
	v_add_f32_e32 v13, v13, v28
	v_sub_f32_e32 v11, v33, v34
	s_movk_i32 s0, 0x5000
	v_add_f32_e32 v32, v12, v13
	v_add_f32_e32 v2, v11, v2
	v_add_co_u32_e32 v12, vcc, s0, v0
	v_sub_f32_e32 v24, v41, v44
	v_fma_f32 v28, v13, 0.5, -v29
	v_fma_f32 v11, v2, 0.5, -v33
	v_addc_co_u32_e32 v13, vcc, 0, v1, vcc
	s_movk_i32 s0, 0x6000
	v_cvt_pk_bf16_f32 v11, v11, v28
	global_store_dwordx4 v[12:13], v[8:11], off
	v_add_f32_e32 v2, v24, v2
	v_add_co_u32_e32 v12, vcc, s0, v0
	v_fma_f32 v27, v22, 0.5, -v39
	v_fma_f32 v18, v23, 0.5, -v18
	v_cvt_pk_bf16_f32 v10, v27, v18
	v_fma_f32 v11, v2, 0.5, -v41
	v_addc_co_u32_e32 v13, vcc, 0, v1, vcc
	v_fma_f32 v25, v14, 0.5, -v36
	v_fma_f32 v16, v15, 0.5, -v16
	v_fma_f32 v26, v20, 0.5, -v37
	v_fma_f32 v17, v21, 0.5, -v17
	v_and_b32_e32 v30, 0xffff0000, v7
	v_fma_f32 v19, v32, 0.5, -v19
	v_lshlrev_b32_e32 v7, 16, v7
	v_cvt_pk_bf16_f32 v8, v25, v16
	v_cvt_pk_bf16_f32 v9, v26, v17
	v_cvt_pk_bf16_f32 v11, v11, v19
	global_store_dwordx4 v[12:13], v[8:11], off
	v_sub_f32_e32 v17, v7, v33
	v_add_f32_e32 v2, v17, v2
	v_and_b32_e32 v10, 0xffff0000, v4
	v_and_b32_e32 v8, 0xffff0000, v6
	v_lshlrev_b32_e32 v6, 16, v6
	v_and_b32_e32 v9, 0xffff0000, v5
	v_lshlrev_b32_e32 v5, 16, v5
	v_lshlrev_b32_e32 v4, 16, v4
	v_sub_f32_e32 v12, v10, v43
	v_sub_f32_e32 v11, v4, v31
	v_add_f32_e32 v12, v12, v15
	v_sub_f32_e32 v13, v5, v38
	v_sub_f32_e32 v15, v6, v40
	v_sub_f32_e32 v17, v30, v29
	v_add_f32_e32 v11, v11, v14
	v_add_f32_e32 v13, v13, v20
	v_sub_f32_e32 v14, v9, v50
	v_add_f32_e32 v15, v15, v22
	v_sub_f32_e32 v16, v8, v54
	v_add_f32_e32 v17, v17, v32
	v_add_f32_e32 v14, v14, v21
	v_add_f32_e32 v16, v16, v23
	v_fma_f32 v4, v11, 0.5, -v4
	v_fma_f32 v5, v13, 0.5, -v5
	v_fma_f32 v6, v15, 0.5, -v6
	v_fma_f32 v2, v2, 0.5, -v7
	v_fma_f32 v7, v17, 0.5, -v30
	v_fma_f32 v10, v12, 0.5, -v10
	v_cvt_pk_bf16_f32 v4, v4, v10
	v_fma_f32 v9, v14, 0.5, -v9
	v_cvt_pk_bf16_f32 v5, v5, v9
	v_fma_f32 v8, v16, 0.5, -v8
	v_cvt_pk_bf16_f32 v6, v6, v8
	v_cvt_pk_bf16_f32 v7, v2, v7
.LBB0_264:
	v_readlane_b32 s0, v244, 4
	v_add_co_u32_e32 v0, vcc, 0x7000, v0
	s_add_i32 s5, s5, s76
	s_add_i32 s4, s4, s0
	v_addc_co_u32_e32 v1, vcc, 0, v1, vcc
	s_cmpk_lt_i32 s5, 0x400
	global_store_dwordx4 v[0:1], v[4:7], off
	s_cbranch_scc0 .LBB0_260
; __device__ __forceinline__ size_t pidx(size_t row, int col) { return ((size_t)(col >> 8) * MTOK + row) * PLD + (col & 255); }
; template <int WIN>
; __device__ __forceinline__ void pool_rows(const bf16_t* __restrict__ src, bf16_t* __restrict__ dst, int tseq) {
;   u32x4 U[8], H[WIN];
; #pragma unroll
;   for (int i = 0; i < 8; ++i) U[i] = *(const u32x4*)(src + (long)i * PLD);
; #pragma unroll
;   for (int j = 0; j < WIN; ++j) {
;     if (tseq - WIN + j >= 0) H[j] = *(const u32x4*)(src + (long)(j - WIN) * PLD);
;     else H[j] = (u32x4){0u, 0u, 0u, 0u};
;   }
; __device__ void pool_item(const Params& p, int it) {
;   const bf16_t* proj = (const bf16_t*)(ws_of(p) + OFF_PROJ);
;   bf16_t* pooled = (bf16_t*)(ws_of(p) + OFF_POOLED);
;   const int tid = opaque_tid();
;   const int row0 = it * 16 + (tid >> 8) * 8;
;   const int c = (tid & 255) * 8;
;   const int g = __builtin_amdgcn_readfirstlane(c >> 9);
;   const int tseq = row0 & (SEQ - 1);
;   const bf16_t* src = proj + pidx(row0, PU + c);
;   bf16_t* dst = pooled + (size_t)row0 * DM + c;
;   if (g == 0) pool_rows<2>(src, dst, tseq);
;   else if (g == 1) pool_rows<4>(src, dst, tseq);
;   else if (g == 2) pool_rows<8>(src, dst, tseq);
;   else pool_rows<16>(src, dst, tseq);
; }
.LBB0_265:
	s_mov_b64 s[0:1], s[50:51]
	s_mov_b64 s[6:7], s[50:51]
	v_mov_b32_e32 v6, v164
	s_nop 0
	v_ashrrev_i32_e32 v0, 5, v6
	v_and_b32_e32 v0, -8, v0
	v_add_u32_e32 v0, s4, v0
	v_lshlrev_b32_e32 v1, 3, v6
	v_and_b32_e32 v7, 0x7f8, v1
	v_ashrrev_i32_e32 v1, 31, v0
	v_lshlrev_b64 v[4:5], 9, v[0:1]
	v_lshlrev_b32_e32 v2, 18, v6
	v_lshl_add_u64 v[4:5], s[0:1], 0, v[4:5]
	v_and_b32_e32 v2, 0x3800000, v2
	v_lshl_add_u64 v[4:5], v[4:5], 0, v[2:3]
	v_lshlrev_b32_e32 v2, 4, v6
	v_and_b32_e32 v102, 0x7f8, v0
	v_and_b32_e32 v2, 0x1f0, v2
	v_lshlrev_b64 v[0:1], 12, v[0:1]
	v_lshl_add_u64 v[4:5], v[4:5], 0, v[2:3]
	s_mov_b64 s[0:1], 0x10c80000
	v_lshl_add_u64 v[0:1], s[6:7], 0, v[0:1]
	v_lshlrev_b32_e32 v2, 1, v7
	v_readfirstlane_b32 s2, v7
	v_lshl_add_u64 v[100:101], v[4:5], 0, s[0:1]
	v_lshl_add_u64 v[0:1], v[0:1], 0, v[2:3]
	s_mov_b64 s[0:1], 0x4f080000
	v_lshl_add_u64 v[0:1], v[0:1], 0, s[0:1]
	s_cmpk_gt_u32 s2, 0x1ff
	s_mov_b64 s[0:1], -1
	s_cbranch_scc0 .LBB0_331
	s_lshr_b32 s2, s2, 9
	s_cmp_lt_i32 s2, 2
	s_cbranch_scc1 .LBB0_320
	s_cmp_lg_u32 s2, 2
	s_cbranch_scc0 .LBB0_301
	global_load_dwordx4 v[4:7], v[100:101], off
	global_load_dwordx4 v[36:39], v[100:101], off offset:512
	global_load_dwordx4 v[32:35], v[100:101], off offset:1024
	global_load_dwordx4 v[28:31], v[100:101], off offset:1536
	global_load_dwordx4 v[24:27], v[100:101], off offset:2048
	global_load_dwordx4 v[20:23], v[100:101], off offset:2560
	global_load_dwordx4 v[16:19], v[100:101], off offset:3072
	global_load_dwordx4 v[8:11], v[100:101], off offset:3584
	v_cmp_lt_u32_e32 vcc, 15, v102
	v_mov_b32_e32 v40, 0
	v_mov_b32_e32 v64, 0
	v_mov_b32_e32 v65, 0
	v_mov_b32_e32 v66, 0
	v_mov_b32_e32 v67, 0
	s_and_saveexec_b64 s[0:1], vcc
	s_cbranch_execz .LBB0_270
	v_add_co_u32_e32 v12, vcc, 0xffffe000, v100
	s_nop 1
	v_addc_co_u32_e32 v13, vcc, -1, v101, vcc
	global_load_dwordx4 v[64:67], v[12:13], off
.LBB0_270:
	s_or_b64 exec, exec, s[0:1]
	v_cmp_lt_u32_e32 vcc, 14, v102
	v_mov_b32_e32 v41, 0
	v_mov_b32_e32 v42, 0
	v_mov_b32_e32 v43, 0
	s_and_saveexec_b64 s[0:1], vcc
	s_cbranch_execz .LBB0_272
	v_add_co_u32_e32 v12, vcc, 0xffffe200, v100
	s_nop 1
	v_addc_co_u32_e32 v13, vcc, -1, v101, vcc
	global_load_dwordx4 v[40:43], v[12:13], off
.LBB0_272:
	s_or_b64 exec, exec, s[0:1]
	v_cmp_lt_u32_e32 vcc, 13, v102
	v_mov_b32_e32 v44, 0
	v_mov_b32_e32 v52, 0
	v_mov_b32_e32 v53, 0
	v_mov_b32_e32 v54, 0
	v_mov_b32_e32 v55, 0
	s_and_saveexec_b64 s[0:1], vcc
	s_cbranch_execz .LBB0_274
	v_add_co_u32_e32 v12, vcc, 0xffffe400, v100
	s_nop 1
	v_addc_co_u32_e32 v13, vcc, -1, v101, vcc
	global_load_dwordx4 v[52:55], v[12:13], off
.LBB0_274:
	s_or_b64 exec, exec, s[0:1]
	v_cmp_lt_u32_e32 vcc, 12, v102
	v_mov_b32_e32 v45, 0
	v_mov_b32_e32 v46, 0
	v_mov_b32_e32 v47, 0
	s_and_saveexec_b64 s[0:1], vcc
	s_cbranch_execz .LBB0_276
	v_add_co_u32_e32 v12, vcc, 0xffffe600, v100
	s_nop 1
	v_addc_co_u32_e32 v13, vcc, -1, v101, vcc
	global_load_dwordx4 v[44:47], v[12:13], off
.LBB0_276:
	s_or_b64 exec, exec, s[0:1]
	v_cmp_lt_u32_e32 vcc, 11, v102
	v_mov_b32_e32 v48, 0
	v_mov_b32_e32 v56, 0
	v_mov_b32_e32 v57, 0
	v_mov_b32_e32 v58, 0
	v_mov_b32_e32 v59, 0
	s_and_saveexec_b64 s[0:1], vcc
	s_cbranch_execz .LBB0_278
	v_add_co_u32_e32 v12, vcc, 0xffffe800, v100
	s_nop 1
	v_addc_co_u32_e32 v13, vcc, -1, v101, vcc
	global_load_dwordx4 v[56:59], v[12:13], off
.LBB0_278:
	s_or_b64 exec, exec, s[0:1]
	v_cmp_lt_u32_e32 vcc, 10, v102
	v_mov_b32_e32 v49, 0
	v_mov_b32_e32 v50, 0
	v_mov_b32_e32 v51, 0
	s_and_saveexec_b64 s[0:1], vcc
	s_cbranch_execz .LBB0_280
	v_add_co_u32_e32 v12, vcc, 0xffffea00, v100
	s_nop 1
	v_addc_co_u32_e32 v13, vcc, -1, v101, vcc
	global_load_dwordx4 v[48:51], v[12:13], off
.LBB0_280:
	s_or_b64 exec, exec, s[0:1]
	v_cmp_lt_u32_e32 vcc, 9, v102
	v_mov_b32_e32 v12, 0
	v_mov_b32_e32 v60, 0
	v_mov_b32_e32 v61, 0
	v_mov_b32_e32 v62, 0
	v_mov_b32_e32 v63, 0
	s_and_saveexec_b64 s[0:1], vcc
	s_cbranch_execz .LBB0_282
	v_add_co_u32_e32 v14, vcc, 0xffffec00, v100
	s_nop 1
	v_addc_co_u32_e32 v15, vcc, -1, v101, vcc
	global_load_dwordx4 v[60:63], v[14:15], off
.LBB0_282:
	s_or_b64 exec, exec, s[0:1]
	v_cmp_lt_u32_e32 vcc, 8, v102
	v_mov_b32_e32 v13, 0
	v_mov_b32_e32 v14, 0
	v_mov_b32_e32 v15, 0
	s_and_saveexec_b64 s[0:1], vcc
	s_cbranch_execz .LBB0_284
	v_add_co_u32_e32 v12, vcc, 0xffffee00, v100
	s_nop 1
	v_addc_co_u32_e32 v13, vcc, -1, v101, vcc
	global_load_dwordx4 v[12:15], v[12:13], off
.LBB0_284:
	s_or_b64 exec, exec, s[0:1]
	v_mov_b32_e32 v72, 0
	v_cmp_ne_u32_e64 s[8:9], 0, v102
	v_mov_b32_e32 v76, 0
	v_mov_b32_e32 v77, 0
	v_mov_b32_e32 v78, 0
	v_mov_b32_e32 v79, 0
	s_and_saveexec_b64 s[0:1], s[8:9]
	s_cbranch_execz .LBB0_286
	v_add_co_u32_e32 v68, vcc, 0xfffff000, v100
	s_nop 1
	v_addc_co_u32_e32 v69, vcc, -1, v101, vcc
	global_load_dwordx4 v[76:79], v[68:69], off
.LBB0_286:
	s_or_b64 exec, exec, s[0:1]
	v_mov_b32_e32 v73, 0
	v_mov_b32_e32 v74, 0
	v_mov_b32_e32 v75, 0
	s_and_saveexec_b64 s[0:1], s[8:9]
	s_cbranch_execz .LBB0_288
	v_add_co_u32_e32 v68, vcc, 0xfffff200, v100
	s_nop 1
	v_addc_co_u32_e32 v69, vcc, -1, v101, vcc
	global_load_dwordx4 v[72:75], v[68:69], off
.LBB0_288:
	s_or_b64 exec, exec, s[0:1]
	v_mov_b32_e32 v80, 0
	v_mov_b32_e32 v84, 0
	v_mov_b32_e32 v85, 0
	v_mov_b32_e32 v86, 0
	v_mov_b32_e32 v87, 0
	s_and_saveexec_b64 s[0:1], s[8:9]
	s_cbranch_execz .LBB0_290
	v_add_co_u32_e32 v68, vcc, 0xfffff400, v100
	s_nop 1
	v_addc_co_u32_e32 v69, vcc, -1, v101, vcc
	global_load_dwordx4 v[84:87], v[68:69], off
.LBB0_290:
	s_or_b64 exec, exec, s[0:1]
	v_mov_b32_e32 v81, 0
	v_mov_b32_e32 v82, 0
	v_mov_b32_e32 v83, 0
	s_and_saveexec_b64 s[0:1], s[8:9]
	s_cbranch_execz .LBB0_292
	v_add_co_u32_e32 v68, vcc, 0xfffff600, v100
	s_nop 1
	v_addc_co_u32_e32 v69, vcc, -1, v101, vcc
	global_load_dwordx4 v[80:83], v[68:69], off
; template <int WIN>
; __device__ __forceinline__ void pool_rows(const bf16_t* __restrict__ src, bf16_t* __restrict__ dst, int tseq) {
;   u32x4 U[8], H[WIN];
; #pragma unroll
;   for (int i = 0; i < 8; ++i) U[i] = *(const u32x4*)(src + (long)i * PLD);
; #pragma unroll
;   for (int j = 0; j < WIN; ++j) {
;     if (tseq - WIN + j >= 0) H[j] = *(const u32x4*)(src + (long)(j - WIN) * PLD);
;     else H[j] = (u32x4){0u, 0u, 0u, 0u};
;   }
;   float s[8];
; #pragma unroll
;   for (int k = 0; k < 8; ++k) s[k] = 0.f;
; #pragma unroll
;   for (int j = 0; j < WIN; ++j) {
;     float f[8];
;     unpack8(H[j], f);
; #pragma unroll
;     for (int k = 0; k < 8; ++k) s[k] += f[k];
;   }
; #pragma unroll
;   for (int i = 0; i < 8; ++i) {
;     float u[8], o[8];
;     unpack8(U[i], u);
;     if (i - WIN >= 0) unpack8(U[(i - WIN) >= 0 ? (i - WIN) : 0], o);
;     else unpack8(H[i < WIN ? i : 0], o);
; #pragma unroll
;     for (int k = 0; k < 8; ++k) s[k] += u[k] - o[k];
;     const int t = tseq + i;
;     const float inv = __builtin_amdgcn_rcpf((float)min(t + 1, WIN));
.LBB0_292:
	s_or_b64 exec, exec, s[0:1]
	v_mov_b32_e32 v88, 0
	v_mov_b32_e32 v92, 0
	v_mov_b32_e32 v93, 0
	v_mov_b32_e32 v94, 0
	v_mov_b32_e32 v95, 0
	s_and_saveexec_b64 s[0:1], s[8:9]
	s_cbranch_execz .LBB0_294
	v_add_co_u32_e32 v68, vcc, 0xfffff800, v100
	s_nop 1
	v_addc_co_u32_e32 v69, vcc, -1, v101, vcc
	global_load_dwordx4 v[92:95], v[68:69], off
.LBB0_294:
	s_or_b64 exec, exec, s[0:1]
	v_mov_b32_e32 v89, 0
	v_mov_b32_e32 v90, 0
	v_mov_b32_e32 v91, 0
	s_and_saveexec_b64 s[0:1], s[8:9]
	s_cbranch_execz .LBB0_296
	v_add_co_u32_e32 v68, vcc, 0xfffffa00, v100
	s_nop 1
	v_addc_co_u32_e32 v69, vcc, -1, v101, vcc
	global_load_dwordx4 v[88:91], v[68:69], off
.LBB0_296:
	s_or_b64 exec, exec, s[0:1]
	v_mov_b32_e32 v68, 0
	v_mov_b32_e32 v96, 0
	v_mov_b32_e32 v97, 0
	v_mov_b32_e32 v98, 0
	v_mov_b32_e32 v99, 0
	s_and_saveexec_b64 s[0:1], s[8:9]
	s_cbranch_execz .LBB0_298
	v_add_co_u32_e32 v70, vcc, 0xfffffc00, v100
	s_nop 1
	v_addc_co_u32_e32 v71, vcc, -1, v101, vcc
	global_load_dwordx4 v[96:99], v[70:71], off
.LBB0_298:
	s_or_b64 exec, exec, s[0:1]
	v_mov_b32_e32 v69, 0
	v_mov_b32_e32 v70, 0
	v_mov_b32_e32 v71, 0
	s_and_saveexec_b64 s[0:1], s[8:9]
	s_cbranch_execz .LBB0_300
	v_add_co_u32_e32 v68, vcc, 0xfffffe00, v100
	s_nop 1
	v_addc_co_u32_e32 v69, vcc, -1, v101, vcc
	global_load_dwordx4 v[68:71], v[68:69], off
.LBB0_300:
	s_or_b64 exec, exec, s[0:1]
	s_waitcnt vmcnt(0) lgkmcnt(0)
	v_lshlrev_b32_e32 v2, 16, v64
	v_add_f32_e32 v106, 0, v2
	v_lshlrev_b32_e32 v149, 16, v40
	v_add_f32_e32 v106, v106, v149
	v_lshlrev_b32_e32 v158, 16, v52
	v_add_f32_e32 v106, v106, v158
	v_lshlrev_b32_e32 v170, 16, v44
	v_add_f32_e32 v106, v106, v170
	v_lshlrev_b32_e32 v179, 16, v56
	v_add_f32_e32 v106, v106, v179
	v_lshlrev_b32_e32 v188, 16, v48
	v_add_f32_e32 v106, v106, v188
	v_lshlrev_b32_e32 v197, 16, v60
	v_and_b32_e32 v64, 0xffff0000, v64
	v_add_f32_e32 v106, v106, v197
	v_lshlrev_b32_e32 v220, 16, v12
	v_add_f32_e32 v107, 0, v64
	v_lshlrev_b32_e32 v114, 16, v76
	v_and_b32_e32 v40, 0xffff0000, v40
	v_add_f32_e32 v106, v106, v220
	v_lshlrev_b32_e32 v118, 16, v72
	v_add_f32_e32 v107, v107, v40
	v_and_b32_e32 v52, 0xffff0000, v52
	v_add_f32_e32 v106, v106, v114
	v_lshlrev_b32_e32 v122, 16, v84
	v_add_f32_e32 v107, v107, v52
	v_and_b32_e32 v44, 0xffff0000, v44
	v_add_f32_e32 v106, v106, v118
	v_lshlrev_b32_e32 v126, 16, v80
	v_add_f32_e32 v107, v107, v44
	v_and_b32_e32 v56, 0xffff0000, v56
	v_add_f32_e32 v106, v106, v122
	v_lshlrev_b32_e32 v130, 16, v92
	v_add_f32_e32 v107, v107, v56
	v_and_b32_e32 v48, 0xffff0000, v48
	v_add_f32_e32 v106, v106, v126
	v_lshlrev_b32_e32 v134, 16, v88
	v_add_f32_e32 v107, v107, v48
	v_and_b32_e32 v60, 0xffff0000, v60
	v_add_f32_e32 v106, v106, v130
	v_lshlrev_b32_e32 v138, 16, v96
	v_add_f32_e32 v107, v107, v60
	v_add_f32_e32 v106, v106, v134
	v_and_b32_e32 v12, 0xffff0000, v12
	v_and_b32_e32 v76, 0xffff0000, v76
	v_lshlrev_b32_e32 v221, 16, v8
	v_add_f32_e32 v106, v106, v138
	v_and_b32_e32 v138, 0xffff0000, v8
	v_add_f32_e32 v8, v107, v12
	v_and_b32_e32 v72, 0xffff0000, v72
	v_add_f32_e32 v8, v8, v76
	v_and_b32_e32 v84, 0xffff0000, v84
	v_add_f32_e32 v8, v8, v72
	v_and_b32_e32 v80, 0xffff0000, v80
	v_min_u32_e32 v148, 15, v102
	v_add_f32_e32 v8, v8, v84
	v_and_b32_e32 v92, 0xffff0000, v92
	v_add_u32_e32 v148, 1, v148
	v_min_u32_e32 v157, 14, v102
	v_add_f32_e32 v8, v8, v80
	v_and_b32_e32 v88, 0xffff0000, v88
	v_cvt_f32_ubyte0_e32 v148, v148
	v_add_u32_e32 v157, 2, v157
	v_min_u32_e32 v169, 13, v102
	v_add_f32_e32 v8, v8, v92
	v_and_b32_e32 v96, 0xffff0000, v96
	v_rcp_iflag_f32_e32 v148, v148
	v_cvt_f32_ubyte0_e32 v157, v157
	v_add_u32_e32 v169, 3, v169
	v_min_u32_e32 v178, 12, v102
	v_add_f32_e32 v8, v8, v88
	v_lshlrev_b32_e32 v103, 16, v65
	v_lshlrev_b32_e32 v142, 16, v68
	v_lshlrev_b32_e32 v143, 16, v4
	v_and_b32_e32 v68, 0xffff0000, v68
	v_and_b32_e32 v4, 0xffff0000, v4
	v_rcp_iflag_f32_e32 v157, v157
	v_cvt_f32_ubyte0_e32 v169, v169
	v_add_u32_e32 v178, 4, v178
	v_min_u32_e32 v187, 11, v102
	v_add_f32_e32 v8, v8, v96
	v_add_f32_e32 v108, 0, v103
	v_lshlrev_b32_e32 v150, 16, v36
	v_and_b32_e32 v36, 0xffff0000, v36
	v_lshlrev_b32_e32 v152, 16, v41
	v_rcp_iflag_f32_e32 v169, v169
	v_cvt_f32_ubyte0_e32 v178, v178
	v_add_u32_e32 v187, 5, v187
	v_min_u32_e32 v196, 10, v102
	v_add_f32_e32 v8, v8, v68
	v_sub_f32_e32 v64, v4, v64
	v_add_f32_e32 v108, v108, v152
	v_lshlrev_b32_e32 v159, 16, v32
	v_and_b32_e32 v32, 0xffff0000, v32
	v_lshlrev_b32_e32 v161, 16, v53
	v_rcp_iflag_f32_e32 v178, v178
	v_cvt_f32_ubyte0_e32 v187, v187
	v_add_u32_e32 v196, 6, v196
	v_add_f32_e32 v8, v64, v8
	v_sub_f32_e32 v40, v36, v40
	v_add_f32_e32 v108, v108, v161
	v_lshlrev_b32_e32 v171, 16, v28
	v_and_b32_e32 v28, 0xffff0000, v28
	v_lshlrev_b32_e32 v173, 16, v45
	v_rcp_iflag_f32_e32 v187, v187
	v_cvt_f32_ubyte0_e32 v196, v196
	v_fma_f32 v4, v148, v8, -v4
	v_add_f32_e32 v8, v40, v8
	v_sub_f32_e32 v40, v32, v52
	v_add_f32_e32 v108, v108, v173
	v_lshlrev_b32_e32 v180, 16, v24
	v_and_b32_e32 v24, 0xffff0000, v24
	v_lshlrev_b32_e32 v182, 16, v57
	v_rcp_iflag_f32_e32 v196, v196
	v_fma_f32 v36, v157, v8, -v36
	v_add_f32_e32 v8, v40, v8
	v_sub_f32_e32 v40, v28, v44
	v_add_f32_e32 v108, v108, v182
	v_lshlrev_b32_e32 v189, 16, v20
	v_and_b32_e32 v20, 0xffff0000, v20
	v_lshlrev_b32_e32 v191, 16, v49
	v_fma_f32 v32, v169, v8, -v32
	v_add_f32_e32 v8, v40, v8
	v_sub_f32_e32 v40, v24, v56
	v_add_f32_e32 v108, v108, v191
	v_lshlrev_b32_e32 v212, 16, v16
	v_and_b32_e32 v16, 0xffff0000, v16
	v_lshlrev_b32_e32 v214, 16, v61
	v_fma_f32 v28, v178, v8, -v28
	v_add_f32_e32 v8, v40, v8
	v_sub_f32_e32 v40, v20, v48
	v_add_f32_e32 v108, v108, v214
	v_fma_f32 v24, v187, v8, -v24
; template <int WIN>
; __device__ __forceinline__ void pool_rows(const bf16_t* __restrict__ src, bf16_t* __restrict__ dst, int tseq) {
;     ...
; #pragma unroll
;   for (int j = 0; j < WIN; ++j) {
;     float f[8];
;     unpack8(H[j], f);
; #pragma unroll
;     for (int k = 0; k < 8; ++k) s[k] += f[k];
;   }
; #pragma unroll
;   for (int i = 0; i < 8; ++i) {
;     float u[8], o[8];
;     unpack8(U[i], u);
;     if (i - WIN >= 0) unpack8(U[(i - WIN) >= 0 ? (i - WIN) : 0], o);
;     else unpack8(H[i < WIN ? i : 0], o);
; #pragma unroll
;     for (int k = 0; k < 8; ++k) s[k] += u[k] - o[k];
;     const int t = tseq + i;
;     const float inv = __builtin_amdgcn_rcpf((float)min(t + 1, WIN));
	v_add_f32_e32 v8, v40, v8
	v_sub_f32_e32 v40, v16, v60
	v_lshlrev_b32_e32 v48, 16, v13
	v_lshlrev_b32_e32 v115, 16, v77
	v_fma_f32 v20, v196, v8, -v20
	v_add_f32_e32 v40, v40, v8
	v_add_f32_e32 v8, v108, v48
	v_lshlrev_b32_e32 v119, 16, v73
	v_add_f32_e32 v8, v8, v115
	v_lshlrev_b32_e32 v123, 16, v85
	v_add_f32_e32 v8, v8, v119
	v_lshlrev_b32_e32 v127, 16, v81
	v_add_f32_e32 v8, v8, v123
	v_lshlrev_b32_e32 v131, 16, v93
	v_add_f32_e32 v8, v8, v127
	v_lshlrev_b32_e32 v135, 16, v89
	v_add_f32_e32 v8, v8, v131
	v_lshlrev_b32_e32 v139, 16, v97
	v_add_f32_e32 v8, v8, v135
	v_and_b32_e32 v65, 0xffff0000, v65
	v_lshlrev_b32_e32 v144, 16, v69
	v_lshlrev_b32_e32 v145, 16, v5
	v_add_f32_e32 v8, v8, v139
	v_add_f32_e32 v109, 0, v65
	v_lshlrev_b32_e32 v151, 16, v37
	v_and_b32_e32 v41, 0xffff0000, v41
	v_sub_f32_e32 v52, v145, v103
	v_add_f32_e32 v8, v8, v144
	v_add_f32_e32 v109, v109, v41
	v_lshlrev_b32_e32 v160, 16, v33
	v_and_b32_e32 v53, 0xffff0000, v53
	v_add_f32_e32 v8, v52, v8
	v_sub_f32_e32 v56, v151, v152
	v_add_f32_e32 v109, v109, v53
	v_lshlrev_b32_e32 v172, 16, v29
	v_and_b32_e32 v45, 0xffff0000, v45
	v_fma_f32 v52, v148, v8, -v145
	v_add_f32_e32 v8, v56, v8
	v_sub_f32_e32 v60, v160, v161
	v_add_f32_e32 v109, v109, v45
	v_lshlrev_b32_e32 v181, 16, v25
	v_and_b32_e32 v57, 0xffff0000, v57
	v_fma_f32 v56, v157, v8, -v151
	v_add_f32_e32 v8, v60, v8
	v_sub_f32_e32 v64, v172, v173
	v_add_f32_e32 v109, v109, v57
	v_lshlrev_b32_e32 v190, 16, v21
	v_and_b32_e32 v49, 0xffff0000, v49
	v_fma_f32 v60, v169, v8, -v160
	v_add_f32_e32 v8, v64, v8
	v_sub_f32_e32 v68, v181, v182
	v_add_f32_e32 v109, v109, v49
	v_lshlrev_b32_e32 v213, 16, v17
	v_and_b32_e32 v61, 0xffff0000, v61
	v_fma_f32 v64, v178, v8, -v172
	v_add_f32_e32 v8, v68, v8
	v_sub_f32_e32 v72, v190, v191
	v_add_f32_e32 v109, v109, v61
	v_fma_f32 v68, v187, v8, -v181
	v_add_f32_e32 v8, v72, v8
	v_sub_f32_e32 v76, v213, v214
	v_and_b32_e32 v13, 0xffff0000, v13
	v_and_b32_e32 v77, 0xffff0000, v77
	v_fma_f32 v72, v196, v8, -v190
	v_add_f32_e32 v76, v76, v8
	v_add_f32_e32 v8, v109, v13
	v_and_b32_e32 v73, 0xffff0000, v73
	v_add_f32_e32 v8, v8, v77
	v_and_b32_e32 v85, 0xffff0000, v85
	v_add_f32_e32 v8, v8, v73
	v_and_b32_e32 v81, 0xffff0000, v81
	v_add_f32_e32 v8, v8, v85
	v_and_b32_e32 v93, 0xffff0000, v93
	v_add_f32_e32 v8, v8, v81
	v_and_b32_e32 v89, 0xffff0000, v89
	v_add_f32_e32 v8, v8, v93
	v_and_b32_e32 v97, 0xffff0000, v97
	v_add_f32_e32 v8, v8, v89
	v_and_b32_e32 v69, 0xffff0000, v69
	v_and_b32_e32 v5, 0xffff0000, v5
	v_add_f32_e32 v8, v8, v97
	v_lshlrev_b32_e32 v104, 16, v66
	v_and_b32_e32 v37, 0xffff0000, v37
	v_lshlrev_b32_e32 v44, 16, v9
	v_and_b32_e32 v84, 0xffff0000, v9
	v_add_f32_e32 v8, v8, v69
	v_sub_f32_e32 v9, v5, v65
	v_add_f32_e32 v110, 0, v104
	v_lshlrev_b32_e32 v153, 16, v42
	v_add_f32_e32 v8, v9, v8
	v_sub_f32_e32 v9, v37, v41
	v_add_f32_e32 v110, v110, v153
	v_and_b32_e32 v33, 0xffff0000, v33
	v_lshlrev_b32_e32 v162, 16, v54
	v_fma_f32 v5, v148, v8, -v5
	v_add_f32_e32 v8, v9, v8
	v_add_f32_e32 v110, v110, v162
	v_and_b32_e32 v29, 0xffff0000, v29
	v_lshlrev_b32_e32 v174, 16, v46
	v_fma_f32 v9, v157, v8, -v37
	v_sub_f32_e32 v37, v33, v53
	v_add_f32_e32 v110, v110, v174
	v_and_b32_e32 v25, 0xffff0000, v25
	v_lshlrev_b32_e32 v183, 16, v58
	v_add_f32_e32 v8, v37, v8
	v_sub_f32_e32 v37, v29, v45
	v_add_f32_e32 v110, v110, v183
	v_and_b32_e32 v21, 0xffff0000, v21
	v_lshlrev_b32_e32 v192, 16, v50
	v_fma_f32 v33, v169, v8, -v33
	v_add_f32_e32 v8, v37, v8
	v_sub_f32_e32 v37, v25, v57
	v_add_f32_e32 v110, v110, v192
	v_and_b32_e32 v17, 0xffff0000, v17
	v_lshlrev_b32_e32 v215, 16, v62
	v_fma_f32 v29, v178, v8, -v29
	v_add_f32_e32 v8, v37, v8
	v_sub_f32_e32 v37, v21, v49
	v_add_f32_e32 v110, v110, v215
	v_fma_f32 v25, v187, v8, -v25
	v_add_f32_e32 v8, v37, v8
	v_sub_f32_e32 v37, v17, v61
	v_lshlrev_b32_e32 v41, 16, v14
	v_lshlrev_b32_e32 v116, 16, v78
	v_fma_f32 v21, v196, v8, -v21
	v_add_f32_e32 v37, v37, v8
	v_add_f32_e32 v8, v110, v41
	v_lshlrev_b32_e32 v120, 16, v74
	v_add_f32_e32 v8, v8, v116
	v_lshlrev_b32_e32 v124, 16, v86
	v_add_f32_e32 v8, v8, v120
	v_lshlrev_b32_e32 v128, 16, v82
	v_add_f32_e32 v8, v8, v124
	v_lshlrev_b32_e32 v132, 16, v94
	v_add_f32_e32 v8, v8, v128
	v_lshlrev_b32_e32 v136, 16, v90
	v_add_f32_e32 v8, v8, v132
	v_lshlrev_b32_e32 v140, 16, v98
	v_add_f32_e32 v8, v8, v136
	v_and_b32_e32 v66, 0xffff0000, v66
	v_lshlrev_b32_e32 v146, 16, v70
	v_lshlrev_b32_e32 v147, 16, v6
	v_add_f32_e32 v8, v8, v140
	v_add_f32_e32 v111, 0, v66
	v_lshlrev_b32_e32 v154, 16, v38
	v_and_b32_e32 v42, 0xffff0000, v42
	v_add_f32_e32 v8, v8, v146
	v_sub_f32_e32 v49, v147, v104
	v_add_f32_e32 v111, v111, v42
	v_lshlrev_b32_e32 v163, 16, v34
	v_and_b32_e32 v54, 0xffff0000, v54
	v_cvt_pk_bf16_f32 v5, v52, v5
	v_add_f32_e32 v8, v49, v8
	v_sub_f32_e32 v52, v154, v153
	v_add_f32_e32 v111, v111, v54
	v_lshlrev_b32_e32 v175, 16, v30
	v_and_b32_e32 v46, 0xffff0000, v46
	v_fma_f32 v49, v148, v8, -v147
	v_add_f32_e32 v8, v52, v8
	v_sub_f32_e32 v53, v163, v162
	v_add_f32_e32 v111, v111, v46
	v_lshlrev_b32_e32 v184, 16, v26
	v_and_b32_e32 v58, 0xffff0000, v58
	v_fma_f32 v52, v157, v8, -v154
	v_add_f32_e32 v8, v53, v8
	v_sub_f32_e32 v57, v175, v174
	v_add_f32_e32 v111, v111, v58
	v_lshlrev_b32_e32 v193, 16, v22
	v_and_b32_e32 v50, 0xffff0000, v50
	v_fma_f32 v53, v169, v8, -v163
	v_add_f32_e32 v8, v57, v8
	v_sub_f32_e32 v61, v184, v183
	v_add_f32_e32 v111, v111, v50
	v_lshlrev_b32_e32 v216, 16, v18
	v_and_b32_e32 v62, 0xffff0000, v62
	v_fma_f32 v57, v178, v8, -v175
	v_add_f32_e32 v8, v61, v8
	v_sub_f32_e32 v65, v193, v192
	v_add_f32_e32 v111, v111, v62
	v_fma_f32 v61, v187, v8, -v184
	v_add_f32_e32 v8, v65, v8
; template <int WIN>
; __device__ __forceinline__ void pool_rows(const bf16_t* __restrict__ src, bf16_t* __restrict__ dst, int tseq) {
;     ...
; #pragma unroll
;   for (int i = 0; i < 8; ++i) {
;     float u[8], o[8];
;     unpack8(U[i], u);
;     if (i - WIN >= 0) unpack8(U[(i - WIN) >= 0 ? (i - WIN) : 0], o);
;     else unpack8(H[i < WIN ? i : 0], o);
; #pragma unroll
;     for (int k = 0; k < 8; ++k) s[k] += u[k] - o[k];
;     const int t = tseq + i;
;     const float inv = __builtin_amdgcn_rcpf((float)min(t + 1, WIN));
;     u32x4 r;
;     r.x = pack2(s[0] * inv - u[0], s[1] * inv - u[1]);
;     r.y = pack2(s[2] * inv - u[2], s[3] * inv - u[3]);
;     r.z = pack2(s[4] * inv - u[4], s[5] * inv - u[5]);
;     r.w = pack2(s[6] * inv - u[6], s[7] * inv - u[7]);
;     *(u32x4*)(dst + (long)i * DM) = r;
;   }
	v_sub_f32_e32 v69, v216, v215
	v_and_b32_e32 v14, 0xffff0000, v14
	v_and_b32_e32 v78, 0xffff0000, v78
	v_fma_f32 v65, v196, v8, -v193
	v_add_f32_e32 v69, v69, v8
	v_add_f32_e32 v8, v111, v14
	v_and_b32_e32 v74, 0xffff0000, v74
	v_add_f32_e32 v8, v8, v78
	v_and_b32_e32 v86, 0xffff0000, v86
	v_add_f32_e32 v8, v8, v74
	v_and_b32_e32 v82, 0xffff0000, v82
	v_add_f32_e32 v8, v8, v86
	v_and_b32_e32 v94, 0xffff0000, v94
	v_add_f32_e32 v8, v8, v82
	v_and_b32_e32 v90, 0xffff0000, v90
	v_add_f32_e32 v8, v8, v94
	v_and_b32_e32 v98, 0xffff0000, v98
	v_add_f32_e32 v8, v8, v90
	v_lshlrev_b32_e32 v105, 16, v67
	v_and_b32_e32 v70, 0xffff0000, v70
	v_and_b32_e32 v6, 0xffff0000, v6
	v_add_f32_e32 v8, v8, v98
	v_add_f32_e32 v112, 0, v105
	v_and_b32_e32 v38, 0xffff0000, v38
	v_lshlrev_b32_e32 v156, 16, v43
	v_add_f32_e32 v8, v8, v70
	v_sub_f32_e32 v66, v6, v66
	v_add_f32_e32 v112, v112, v156
	v_and_b32_e32 v34, 0xffff0000, v34
	v_lshlrev_b32_e32 v168, 16, v55
	v_add_f32_e32 v8, v66, v8
	v_sub_f32_e32 v42, v38, v42
	v_add_f32_e32 v112, v112, v168
	v_and_b32_e32 v30, 0xffff0000, v30
	v_lshlrev_b32_e32 v177, 16, v47
	v_fma_f32 v6, v148, v8, -v6
	v_add_f32_e32 v8, v42, v8
	v_sub_f32_e32 v42, v34, v54
	v_add_f32_e32 v112, v112, v177
	v_and_b32_e32 v26, 0xffff0000, v26
	v_lshlrev_b32_e32 v186, 16, v59
	v_fma_f32 v38, v157, v8, -v38
	v_add_f32_e32 v8, v42, v8
	v_sub_f32_e32 v42, v30, v46
	v_add_f32_e32 v112, v112, v186
	v_and_b32_e32 v22, 0xffff0000, v22
	v_lshlrev_b32_e32 v195, 16, v51
	v_fma_f32 v34, v169, v8, -v34
	v_add_f32_e32 v8, v42, v8
	v_sub_f32_e32 v42, v26, v58
	v_add_f32_e32 v112, v112, v195
	v_and_b32_e32 v18, 0xffff0000, v18
	v_lshlrev_b32_e32 v218, 16, v63
	v_fma_f32 v30, v178, v8, -v30
	v_add_f32_e32 v8, v42, v8
	v_sub_f32_e32 v42, v22, v50
	v_add_f32_e32 v112, v112, v218
	v_fma_f32 v26, v187, v8, -v26
	v_add_f32_e32 v8, v42, v8
	v_sub_f32_e32 v42, v18, v62
	v_cvt_pk_bf16_f32 v6, v49, v6
	v_lshlrev_b32_e32 v49, 16, v15
	v_lshlrev_b32_e32 v117, 16, v79
	v_fma_f32 v22, v196, v8, -v22
	v_add_f32_e32 v42, v42, v8
	v_add_f32_e32 v8, v112, v49
	v_lshlrev_b32_e32 v121, 16, v75
	v_add_f32_e32 v8, v8, v117
	v_lshlrev_b32_e32 v125, 16, v87
	v_add_f32_e32 v8, v8, v121
	v_lshlrev_b32_e32 v129, 16, v83
	v_add_f32_e32 v8, v8, v125
	v_lshlrev_b32_e32 v133, 16, v95
	v_add_f32_e32 v8, v8, v129
	v_lshlrev_b32_e32 v137, 16, v91
	v_add_f32_e32 v8, v8, v133
	v_lshlrev_b32_e32 v141, 16, v99
	v_add_f32_e32 v8, v8, v137
	v_add_f32_e32 v8, v8, v141
	v_lshlrev_b32_e32 v50, 16, v71
	v_lshlrev_b32_e32 v54, 16, v7
	v_and_b32_e32 v67, 0xffff0000, v67
	v_sub_f32_e32 v58, v54, v105
	v_add_f32_e32 v8, v8, v50
	v_add_f32_e32 v113, 0, v67
	v_lshlrev_b32_e32 v155, 16, v39
	v_and_b32_e32 v43, 0xffff0000, v43
	v_add_f32_e32 v8, v58, v8
	v_add_f32_e32 v113, v113, v43
	v_lshlrev_b32_e32 v167, 16, v35
	v_and_b32_e32 v55, 0xffff0000, v55
	v_fma_f32 v50, v148, v8, -v54
	v_sub_f32_e32 v54, v155, v156
	v_add_f32_e32 v113, v113, v55
	v_lshlrev_b32_e32 v176, 16, v31
	v_and_b32_e32 v47, 0xffff0000, v47
	v_add_f32_e32 v8, v54, v8
	v_sub_f32_e32 v58, v167, v168
	v_add_f32_e32 v113, v113, v47
	v_lshlrev_b32_e32 v185, 16, v27
	v_and_b32_e32 v59, 0xffff0000, v59
	v_fma_f32 v54, v157, v8, -v155
	v_add_f32_e32 v8, v58, v8
	v_sub_f32_e32 v62, v176, v177
	v_add_f32_e32 v113, v113, v59
	v_lshlrev_b32_e32 v194, 16, v23
	v_and_b32_e32 v51, 0xffff0000, v51
	v_fma_f32 v58, v169, v8, -v167
	v_add_f32_e32 v8, v62, v8
	v_sub_f32_e32 v66, v185, v186
	v_add_f32_e32 v113, v113, v51
	v_lshlrev_b32_e32 v217, 16, v19
	v_and_b32_e32 v63, 0xffff0000, v63
	v_fma_f32 v62, v178, v8, -v176
	v_add_f32_e32 v8, v66, v8
	v_sub_f32_e32 v70, v194, v195
	v_add_f32_e32 v113, v113, v63
	v_fma_f32 v66, v187, v8, -v185
	v_add_f32_e32 v8, v70, v8
	v_sub_f32_e32 v74, v217, v218
	v_and_b32_e32 v15, 0xffff0000, v15
	v_and_b32_e32 v79, 0xffff0000, v79
	v_fma_f32 v70, v196, v8, -v194
	v_add_f32_e32 v74, v74, v8
	v_add_f32_e32 v8, v113, v15
	v_and_b32_e32 v75, 0xffff0000, v75
	v_add_f32_e32 v8, v8, v79
	v_and_b32_e32 v87, 0xffff0000, v87
	v_add_f32_e32 v8, v8, v75
	v_and_b32_e32 v83, 0xffff0000, v83
	v_add_f32_e32 v8, v8, v87
	v_and_b32_e32 v95, 0xffff0000, v95
	v_add_f32_e32 v8, v8, v83
	v_and_b32_e32 v91, 0xffff0000, v91
	v_add_f32_e32 v8, v8, v95
	v_and_b32_e32 v99, 0xffff0000, v99
	v_add_f32_e32 v8, v8, v91
	v_add_f32_e32 v8, v8, v99
	v_and_b32_e32 v71, 0xffff0000, v71
	v_and_b32_e32 v7, 0xffff0000, v7
	v_and_b32_e32 v39, 0xffff0000, v39
	v_add_f32_e32 v8, v8, v71
	v_sub_f32_e32 v67, v7, v67
	v_and_b32_e32 v35, 0xffff0000, v35
	v_add_f32_e32 v8, v67, v8
	v_sub_f32_e32 v43, v39, v43
	v_and_b32_e32 v31, 0xffff0000, v31
	v_fma_f32 v7, v148, v8, -v7
	v_add_f32_e32 v8, v43, v8
	v_sub_f32_e32 v43, v35, v55
	v_and_b32_e32 v27, 0xffff0000, v27
	v_fma_f32 v39, v157, v8, -v39
	v_add_f32_e32 v8, v43, v8
	v_sub_f32_e32 v43, v31, v47
	v_and_b32_e32 v23, 0xffff0000, v23
	v_fma_f32 v35, v169, v8, -v35
	v_add_f32_e32 v8, v43, v8
	v_sub_f32_e32 v43, v27, v59
	v_and_b32_e32 v19, 0xffff0000, v19
	v_fma_f32 v31, v178, v8, -v31
	v_add_f32_e32 v8, v43, v8
	v_sub_f32_e32 v43, v23, v51
	v_add_f32_e32 v106, v106, v142
	v_sub_f32_e32 v2, v143, v2
	v_fma_f32 v27, v187, v8, -v27
	v_add_f32_e32 v8, v43, v8
	v_sub_f32_e32 v43, v19, v63
	s_movk_i32 s0, 0x1000
	v_add_f32_e32 v2, v2, v106
	v_sub_f32_e32 v114, v150, v149
	v_fma_f32 v23, v196, v8, -v23
	v_add_f32_e32 v43, v43, v8
	v_add_co_u32_e32 v8, vcc, s0, v0
	v_fma_f32 v106, v148, v2, -v143
	v_add_f32_e32 v2, v114, v2
	v_cvt_pk_bf16_f32 v4, v106, v4
	v_cvt_pk_bf16_f32 v7, v50, v7
	global_store_dwordx4 v[0:1], v[4:7], off
	v_fma_f32 v114, v157, v2, -v150
	v_sub_f32_e32 v118, v159, v158
	v_cvt_pk_bf16_f32 v5, v56, v9
; template <int WIN>
; __device__ __forceinline__ void pool_rows(const bf16_t* __restrict__ src, bf16_t* __restrict__ dst, int tseq) {
;   u32x4 U[8], H[WIN];
; #pragma unroll
;   for (int i = 0; i < 8; ++i) U[i] = *(const u32x4*)(src + (long)i * PLD);
; #pragma unroll
;   for (int j = 0; j < WIN; ++j) {
;     if (tseq - WIN + j >= 0) H[j] = *(const u32x4*)(src + (long)(j - WIN) * PLD);
;     else H[j] = (u32x4){0u, 0u, 0u, 0u};
;   }
;     ...
; #pragma unroll
;   for (int i = 0; i < 8; ++i) {
;     float u[8], o[8];
;     unpack8(U[i], u);
;     if (i - WIN >= 0) unpack8(U[(i - WIN) >= 0 ? (i - WIN) : 0], o);
;     else unpack8(H[i < WIN ? i : 0], o);
; #pragma unroll
;     for (int k = 0; k < 8; ++k) s[k] += u[k] - o[k];
;     const int t = tseq + i;
;     const float inv = __builtin_amdgcn_rcpf((float)min(t + 1, WIN));
;     u32x4 r;
;     r.x = pack2(s[0] * inv - u[0], s[1] * inv - u[1]);
;     r.y = pack2(s[2] * inv - u[2], s[3] * inv - u[3]);
;     r.z = pack2(s[4] * inv - u[4], s[5] * inv - u[5]);
;     r.w = pack2(s[6] * inv - u[6], s[7] * inv - u[7]);
;     *(u32x4*)(dst + (long)i * DM) = r;
;   }
	v_addc_co_u32_e32 v9, vcc, 0, v1, vcc
	v_cvt_pk_bf16_f32 v4, v114, v36
	v_cvt_pk_bf16_f32 v6, v52, v38
	v_cvt_pk_bf16_f32 v7, v54, v39
	global_store_dwordx4 v[8:9], v[4:7], off
	v_add_co_u32_e32 v8, vcc, s96, v0
	v_add_f32_e32 v2, v118, v2
	s_nop 0
	v_addc_co_u32_e32 v9, vcc, 0, v1, vcc
	s_movk_i32 s0, 0x3000
	v_min_u32_e32 v219, 9, v102
	v_fma_f32 v118, v169, v2, -v159
	v_sub_f32_e32 v122, v171, v170
	v_cvt_pk_bf16_f32 v4, v118, v32
	v_cvt_pk_bf16_f32 v5, v60, v33
	v_cvt_pk_bf16_f32 v6, v53, v34
	v_cvt_pk_bf16_f32 v7, v58, v35
	global_store_dwordx4 v[8:9], v[4:7], off
	v_add_co_u32_e32 v8, vcc, s0, v0
	v_add_u32_e32 v219, 7, v219
	v_add_f32_e32 v2, v122, v2
	v_addc_co_u32_e32 v9, vcc, 0, v1, vcc
	s_movk_i32 s0, 0x4000
	v_cvt_f32_ubyte0_e32 v219, v219
	v_fma_f32 v122, v178, v2, -v171
	v_sub_f32_e32 v126, v180, v179
	v_cvt_pk_bf16_f32 v4, v122, v28
	v_cvt_pk_bf16_f32 v5, v64, v29
	v_cvt_pk_bf16_f32 v6, v57, v30
	v_cvt_pk_bf16_f32 v7, v62, v31
	global_store_dwordx4 v[8:9], v[4:7], off
	v_add_co_u32_e32 v8, vcc, s0, v0
	v_rcp_iflag_f32_e32 v219, v219
	v_add_f32_e32 v2, v126, v2
	v_addc_co_u32_e32 v9, vcc, 0, v1, vcc
	s_movk_i32 s0, 0x5000
	v_fma_f32 v126, v187, v2, -v180
	v_sub_f32_e32 v130, v189, v188
	v_cvt_pk_bf16_f32 v4, v126, v24
	v_cvt_pk_bf16_f32 v5, v68, v25
	v_cvt_pk_bf16_f32 v6, v61, v26
	v_cvt_pk_bf16_f32 v7, v66, v27
	global_store_dwordx4 v[8:9], v[4:7], off
	v_add_co_u32_e32 v8, vcc, s0, v0
	v_add_f32_e32 v2, v130, v2
	v_sub_f32_e32 v134, v212, v197
	v_addc_co_u32_e32 v9, vcc, 0, v1, vcc
	s_movk_i32 s0, 0x6000
	v_fma_f32 v130, v196, v2, -v189
	v_add_f32_e32 v2, v134, v2
	v_cvt_pk_bf16_f32 v4, v130, v20
	v_cvt_pk_bf16_f32 v5, v72, v21
	v_cvt_pk_bf16_f32 v6, v65, v22
	v_cvt_pk_bf16_f32 v7, v70, v23
	global_store_dwordx4 v[8:9], v[4:7], off
	v_add_co_u32_e32 v8, vcc, s0, v0
	v_fma_f32 v134, v219, v2, -v212
	v_fma_f32 v16, v219, v40, -v16
	v_cvt_pk_bf16_f32 v4, v134, v16
	v_addc_co_u32_e32 v9, vcc, 0, v1, vcc
	v_fma_f32 v80, v219, v76, -v213
	v_fma_f32 v17, v219, v37, -v17
	v_fma_f32 v73, v219, v69, -v216
	v_fma_f32 v18, v219, v42, -v18
	v_fma_f32 v77, v219, v74, -v217
	v_fma_f32 v19, v219, v43, -v19
	v_cvt_pk_bf16_f32 v5, v80, v17
	v_cvt_pk_bf16_f32 v6, v73, v18
	v_cvt_pk_bf16_f32 v7, v77, v19
	global_store_dwordx4 v[8:9], v[4:7], off
	v_lshlrev_b32_e32 v45, 16, v10
	v_and_b32_e32 v10, 0xffff0000, v10
	v_sub_f32_e32 v4, v221, v220
	v_add_f32_e32 v2, v4, v2
	v_sub_f32_e32 v4, v138, v12
	v_min_u32_e32 v12, 8, v102
	v_add_u32_e32 v12, 8, v12
	v_cvt_f32_ubyte0_e32 v12, v12
	v_rcp_iflag_f32_e32 v12, v12
	v_lshlrev_b32_e32 v46, 16, v11
	v_and_b32_e32 v11, 0xffff0000, v11
	v_add_f32_e32 v4, v4, v40
	v_sub_f32_e32 v5, v44, v48
	v_sub_f32_e32 v6, v84, v13
	v_add_f32_e32 v5, v5, v76
	v_add_f32_e32 v6, v6, v37
	v_sub_f32_e32 v7, v45, v41
	v_sub_f32_e32 v8, v10, v14
	v_sub_f32_e32 v13, v11, v15
	v_fma_f32 v2, v12, v2, -v221
	v_fma_f32 v4, v12, v4, -v138
	v_add_f32_e32 v7, v7, v69
	v_add_f32_e32 v8, v8, v42
	v_sub_f32_e32 v9, v46, v49
	v_add_f32_e32 v13, v13, v43
	v_cvt_pk_bf16_f32 v4, v2, v4
	v_fma_f32 v2, v12, v5, -v44
	v_fma_f32 v5, v12, v6, -v84
	v_add_f32_e32 v9, v9, v74
	v_cvt_pk_bf16_f32 v5, v2, v5
	v_fma_f32 v2, v12, v7, -v45
	v_fma_f32 v6, v12, v8, -v10
	v_fma_f32 v7, v12, v13, -v11
	s_mov_b64 s[0:1], 0
	v_cvt_pk_bf16_f32 v6, v2, v6
	v_fma_f32 v2, v12, v9, -v46
	v_cvt_pk_bf16_f32 v7, v2, v7
.LBB0_301:
	s_and_b64 vcc, exec, s[0:1]
	s_cbranch_vccz .LBB0_319
	global_load_dwordx4 v[44:47], v[100:101], off
	global_load_dwordx4 v[36:39], v[100:101], off offset:512
	global_load_dwordx4 v[32:35], v[100:101], off offset:1024
	global_load_dwordx4 v[24:27], v[100:101], off offset:1536
	global_load_dwordx4 v[20:23], v[100:101], off offset:2048
	global_load_dwordx4 v[12:15], v[100:101], off offset:2560
	global_load_dwordx4 v[8:11], v[100:101], off offset:3072
	global_load_dwordx4 v[4:7], v[100:101], off offset:3584
	v_mov_b32_e32 v40, 0
	v_cmp_ne_u32_e64 s[8:9], 0, v102
	v_mov_b32_e32 v60, 0
	v_mov_b32_e32 v61, 0
	v_mov_b32_e32 v62, 0
	v_mov_b32_e32 v63, 0
	s_and_saveexec_b64 s[0:1], s[8:9]
	s_cbranch_execz .LBB0_304
	v_add_co_u32_e32 v16, vcc, 0xfffff000, v100
	s_nop 1
	v_addc_co_u32_e32 v17, vcc, -1, v101, vcc
	global_load_dwordx4 v[60:63], v[16:17], off
.LBB0_304:
	s_or_b64 exec, exec, s[0:1]
	v_mov_b32_e32 v41, 0
	v_mov_b32_e32 v42, 0
	v_mov_b32_e32 v43, 0
	s_and_saveexec_b64 s[0:1], s[8:9]
	s_cbranch_execz .LBB0_306
	v_add_co_u32_e32 v16, vcc, 0xfffff200, v100
	s_nop 1
	v_addc_co_u32_e32 v17, vcc, -1, v101, vcc
	global_load_dwordx4 v[40:43], v[16:17], off
.LBB0_306:
	s_or_b64 exec, exec, s[0:1]
	v_mov_b32_e32 v48, 0
	v_mov_b32_e32 v56, 0
	v_mov_b32_e32 v57, 0
	v_mov_b32_e32 v58, 0
	v_mov_b32_e32 v59, 0
	s_and_saveexec_b64 s[0:1], s[8:9]
	s_cbranch_execz .LBB0_308
	v_add_co_u32_e32 v16, vcc, 0xfffff400, v100
	s_nop 1
	v_addc_co_u32_e32 v17, vcc, -1, v101, vcc
	global_load_dwordx4 v[56:59], v[16:17], off
.LBB0_308:
	s_or_b64 exec, exec, s[0:1]
	v_mov_b32_e32 v49, 0
	v_mov_b32_e32 v50, 0
	v_mov_b32_e32 v51, 0
	s_and_saveexec_b64 s[0:1], s[8:9]
	s_cbranch_execz .LBB0_310
	v_add_co_u32_e32 v16, vcc, 0xfffff600, v100
	s_nop 1
	v_addc_co_u32_e32 v17, vcc, -1, v101, vcc
	global_load_dwordx4 v[48:51], v[16:17], off
.LBB0_310:
	s_or_b64 exec, exec, s[0:1]
	v_mov_b32_e32 v52, 0
	v_mov_b32_e32 v64, 0
	v_mov_b32_e32 v65, 0
	v_mov_b32_e32 v66, 0
	v_mov_b32_e32 v67, 0
	s_and_saveexec_b64 s[0:1], s[8:9]
	s_cbranch_execz .LBB0_312
	v_add_co_u32_e32 v16, vcc, 0xfffff800, v100
	s_nop 1
	v_addc_co_u32_e32 v17, vcc, -1, v101, vcc
	global_load_dwordx4 v[64:67], v[16:17], off
; template <int WIN>
; __device__ __forceinline__ void pool_rows(const bf16_t* __restrict__ src, bf16_t* __restrict__ dst, int tseq) {
;   u32x4 U[8], H[WIN];
; #pragma unroll
;   for (int i = 0; i < 8; ++i) U[i] = *(const u32x4*)(src + (long)i * PLD);
; #pragma unroll
;   for (int j = 0; j < WIN; ++j) {
;     if (tseq - WIN + j >= 0) H[j] = *(const u32x4*)(src + (long)(j - WIN) * PLD);
;     else H[j] = (u32x4){0u, 0u, 0u, 0u};
;   }
;   float s[8];
; #pragma unroll
;   for (int k = 0; k < 8; ++k) s[k] = 0.f;
; #pragma unroll
;   for (int j = 0; j < WIN; ++j) {
;     float f[8];
;     unpack8(H[j], f);
; #pragma unroll
;     for (int k = 0; k < 8; ++k) s[k] += f[k];
;   }
; #pragma unroll
;   for (int i = 0; i < 8; ++i) {
;     float u[8], o[8];
;     unpack8(U[i], u);
;     if (i - WIN >= 0) unpack8(U[(i - WIN) >= 0 ? (i - WIN) : 0], o);
;     else unpack8(H[i < WIN ? i : 0], o);
; #pragma unroll
;     for (int k = 0; k < 8; ++k) s[k] += u[k] - o[k];
;     const int t = tseq + i;
;     const float inv = __builtin_amdgcn_rcpf((float)min(t + 1, WIN));
.LBB0_312:
	s_or_b64 exec, exec, s[0:1]
	v_mov_b32_e32 v53, 0
	v_mov_b32_e32 v54, 0
	v_mov_b32_e32 v55, 0
	s_and_saveexec_b64 s[0:1], s[8:9]
	s_cbranch_execz .LBB0_314
	v_add_co_u32_e32 v16, vcc, 0xfffffa00, v100
	s_nop 1
	v_addc_co_u32_e32 v17, vcc, -1, v101, vcc
	global_load_dwordx4 v[52:55], v[16:17], off
.LBB0_314:
	s_or_b64 exec, exec, s[0:1]
	v_mov_b32_e32 v16, 0
	v_mov_b32_e32 v28, 0
	v_mov_b32_e32 v29, 0
	v_mov_b32_e32 v30, 0
	v_mov_b32_e32 v31, 0
	s_and_saveexec_b64 s[0:1], s[8:9]
	s_cbranch_execz .LBB0_316
	v_add_co_u32_e32 v18, vcc, 0xfffffc00, v100
	s_nop 1
	v_addc_co_u32_e32 v19, vcc, -1, v101, vcc
	global_load_dwordx4 v[28:31], v[18:19], off
.LBB0_316:
	s_or_b64 exec, exec, s[0:1]
	v_mov_b32_e32 v2, 0x40e00000
	v_mov_b32_e32 v17, 0
	v_mov_b32_e32 v18, 0
	v_mov_b32_e32 v19, 0
	s_and_saveexec_b64 s[0:1], s[8:9]
	s_cbranch_execz .LBB0_318
	v_add_co_u32_e32 v16, vcc, 0xfffffe00, v100
	v_mov_b32_e32 v2, 0x41000000
	s_nop 0
	v_addc_co_u32_e32 v17, vcc, -1, v101, vcc
	global_load_dwordx4 v[16:19], v[16:17], off
.LBB0_318:
	s_or_b64 exec, exec, s[0:1]
	s_waitcnt vmcnt(0) lgkmcnt(0)
	v_lshlrev_b32_e32 v68, 16, v60
	v_add_f32_e32 v71, 0, v68
	v_lshlrev_b32_e32 v88, 16, v40
	v_add_f32_e32 v71, v71, v88
	v_lshlrev_b32_e32 v97, 16, v56
	v_min_u32_e32 v87, 7, v102
	v_add_f32_e32 v71, v71, v97
	v_lshlrev_b32_e32 v109, 16, v48
	v_add_u32_e32 v87, 1, v87
	v_add_f32_e32 v71, v71, v109
	v_lshlrev_b32_e32 v118, 16, v64
	v_and_b32_e32 v60, 0xffff0000, v60
	v_cvt_f32_ubyte0_e32 v87, v87
	v_min_u32_e32 v96, 6, v102
	v_add_f32_e32 v71, v71, v118
	v_lshlrev_b32_e32 v127, 16, v52
	v_add_f32_e32 v72, 0, v60
	v_rcp_iflag_f32_e32 v87, v87
	v_and_b32_e32 v40, 0xffff0000, v40
	v_add_u32_e32 v96, 2, v96
	v_add_f32_e32 v71, v71, v127
	v_lshlrev_b32_e32 v136, 16, v28
	v_lshlrev_b32_e32 v81, 16, v16
	v_lshlrev_b32_e32 v82, 16, v44
	v_add_f32_e32 v72, v72, v40
	v_cvt_f32_ubyte0_e32 v96, v96
	v_and_b32_e32 v56, 0xffff0000, v56
	v_add_f32_e32 v71, v71, v136
	v_rcp_iflag_f32_e32 v96, v96
	v_add_f32_e32 v72, v72, v56
	v_and_b32_e32 v48, 0xffff0000, v48
	v_add_f32_e32 v71, v71, v81
	v_sub_f32_e32 v68, v82, v68
	v_lshlrev_b32_e32 v89, 16, v36
	v_add_f32_e32 v72, v72, v48
	v_and_b32_e32 v64, 0xffff0000, v64
	v_add_f32_e32 v68, v68, v71
	v_min_u32_e32 v108, 5, v102
	v_add_f32_e32 v72, v72, v64
	v_and_b32_e32 v52, 0xffff0000, v52
	v_fma_f32 v71, v87, v68, -v82
	v_sub_f32_e32 v82, v89, v88
	v_add_u32_e32 v108, 3, v108
	v_lshlrev_b32_e32 v110, 16, v24
	v_min_u32_e32 v117, 4, v102
	v_add_f32_e32 v72, v72, v52
	v_add_f32_e32 v68, v82, v68
	v_and_b32_e32 v28, 0xffff0000, v28
	v_lshlrev_b32_e32 v69, 16, v61
	v_and_b32_e32 v61, 0xffff0000, v61
	v_and_b32_e32 v16, 0xffff0000, v16
	v_and_b32_e32 v44, 0xffff0000, v44
	v_cvt_f32_ubyte0_e32 v108, v108
	v_add_u32_e32 v117, 4, v117
	v_min_u32_e32 v126, 3, v102
	v_lshlrev_b32_e32 v137, 16, v8
	v_fma_f32 v82, v96, v68, -v89
	v_sub_f32_e32 v89, v110, v109
	v_and_b32_e32 v109, 0xffff0000, v8
	v_add_f32_e32 v8, v72, v28
	v_add_f32_e32 v73, 0, v69
	v_add_f32_e32 v74, 0, v61
	v_and_b32_e32 v36, 0xffff0000, v36
	v_lshlrev_b32_e32 v91, 16, v41
	v_and_b32_e32 v41, 0xffff0000, v41
	v_rcp_iflag_f32_e32 v108, v108
	v_cvt_f32_ubyte0_e32 v117, v117
	v_add_u32_e32 v126, 5, v126
	v_add_f32_e32 v8, v8, v16
	v_sub_f32_e32 v60, v44, v60
	v_add_f32_e32 v73, v73, v91
	v_add_f32_e32 v74, v74, v41
	v_lshlrev_b32_e32 v98, 16, v32
	v_and_b32_e32 v32, 0xffff0000, v32
	v_lshlrev_b32_e32 v103, 16, v57
	v_and_b32_e32 v57, 0xffff0000, v57
	v_rcp_iflag_f32_e32 v117, v117
	v_cvt_f32_ubyte0_e32 v126, v126
	v_add_f32_e32 v8, v60, v8
	v_sub_f32_e32 v40, v36, v40
	v_add_f32_e32 v73, v73, v103
	v_add_f32_e32 v74, v74, v57
	v_and_b32_e32 v24, 0xffff0000, v24
	v_lshlrev_b32_e32 v112, 16, v49
	v_and_b32_e32 v49, 0xffff0000, v49
	v_rcp_iflag_f32_e32 v126, v126
	v_fma_f32 v44, v87, v8, -v44
	v_add_f32_e32 v8, v40, v8
	v_sub_f32_e32 v40, v32, v56
	v_add_f32_e32 v73, v73, v112
	v_add_f32_e32 v74, v74, v49
	v_lshlrev_b32_e32 v119, 16, v20
	v_and_b32_e32 v20, 0xffff0000, v20
	v_lshlrev_b32_e32 v121, 16, v65
	v_and_b32_e32 v65, 0xffff0000, v65
	v_fma_f32 v36, v96, v8, -v36
	v_add_f32_e32 v8, v40, v8
	v_sub_f32_e32 v40, v24, v48
	v_add_f32_e32 v73, v73, v121
	v_add_f32_e32 v74, v74, v65
	v_lshlrev_b32_e32 v128, 16, v12
	v_and_b32_e32 v12, 0xffff0000, v12
	v_lshlrev_b32_e32 v130, 16, v53
	v_and_b32_e32 v53, 0xffff0000, v53
	v_fma_f32 v32, v108, v8, -v32
	v_add_f32_e32 v8, v40, v8
	v_sub_f32_e32 v40, v20, v64
	v_add_f32_e32 v73, v73, v130
	v_add_f32_e32 v74, v74, v53
	v_fma_f32 v24, v117, v8, -v24
	v_add_f32_e32 v8, v40, v8
	v_sub_f32_e32 v40, v12, v52
	v_lshlrev_b32_e32 v48, 16, v29
	v_and_b32_e32 v29, 0xffff0000, v29
	v_lshlrev_b32_e32 v83, 16, v17
	v_lshlrev_b32_e32 v84, 16, v45
	v_and_b32_e32 v17, 0xffff0000, v17
	v_and_b32_e32 v45, 0xffff0000, v45
	v_fma_f32 v20, v126, v8, -v20
	v_add_f32_e32 v40, v40, v8
	v_cvt_pk_bf16_f32 v8, v71, v44
	v_lshlrev_b32_e32 v44, 16, v9
	v_add_f32_e32 v52, v73, v48
	v_and_b32_e32 v73, 0xffff0000, v9
	v_add_f32_e32 v9, v74, v29
	v_lshlrev_b32_e32 v70, 16, v62
	v_lshlrev_b32_e32 v90, 16, v37
	v_and_b32_e32 v37, 0xffff0000, v37
	v_add_f32_e32 v9, v9, v17
	v_sub_f32_e32 v61, v45, v61
	v_and_b32_e32 v62, 0xffff0000, v62
	v_add_f32_e32 v75, 0, v70
	v_lshlrev_b32_e32 v92, 16, v42
	v_lshlrev_b32_e32 v99, 16, v33
	v_and_b32_e32 v33, 0xffff0000, v33
	v_add_f32_e32 v9, v61, v9
	v_sub_f32_e32 v41, v37, v41
	v_add_f32_e32 v76, 0, v62
	v_add_f32_e32 v75, v75, v92
	v_and_b32_e32 v42, 0xffff0000, v42
	v_lshlrev_b32_e32 v104, 16, v58
	v_lshlrev_b32_e32 v111, 16, v25
	v_and_b32_e32 v25, 0xffff0000, v25
	v_fma_f32 v45, v87, v9, -v45
	v_add_f32_e32 v9, v41, v9
; template <int WIN>
; __device__ __forceinline__ void pool_rows(const bf16_t* __restrict__ src, bf16_t* __restrict__ dst, int tseq) {
;     ...
; #pragma unroll
;   for (int i = 0; i < 8; ++i) {
;     float u[8], o[8];
;     unpack8(U[i], u);
;     if (i - WIN >= 0) unpack8(U[(i - WIN) >= 0 ? (i - WIN) : 0], o);
;     else unpack8(H[i < WIN ? i : 0], o);
; #pragma unroll
;     for (int k = 0; k < 8; ++k) s[k] += u[k] - o[k];
;     const int t = tseq + i;
;     const float inv = __builtin_amdgcn_rcpf((float)min(t + 1, WIN));
	v_sub_f32_e32 v41, v33, v57
	v_add_f32_e32 v76, v76, v42
	v_add_f32_e32 v75, v75, v104
	v_and_b32_e32 v58, 0xffff0000, v58
	v_lshlrev_b32_e32 v113, 16, v50
	v_lshlrev_b32_e32 v120, 16, v21
	v_and_b32_e32 v21, 0xffff0000, v21
	v_fma_f32 v37, v96, v9, -v37
	v_add_f32_e32 v9, v41, v9
	v_sub_f32_e32 v41, v25, v49
	v_add_f32_e32 v76, v76, v58
	v_add_f32_e32 v75, v75, v113
	v_and_b32_e32 v50, 0xffff0000, v50
	v_lshlrev_b32_e32 v122, 16, v66
	v_lshlrev_b32_e32 v129, 16, v13
	v_and_b32_e32 v13, 0xffff0000, v13
	v_sub_f32_e32 v56, v84, v69
	v_add_f32_e32 v52, v52, v83
	v_fma_f32 v33, v108, v9, -v33
	v_add_f32_e32 v9, v41, v9
	v_sub_f32_e32 v41, v21, v65
	v_add_f32_e32 v76, v76, v50
	v_add_f32_e32 v75, v75, v122
	v_and_b32_e32 v66, 0xffff0000, v66
	v_lshlrev_b32_e32 v131, 16, v54
	v_add_f32_e32 v52, v56, v52
	v_fma_f32 v25, v117, v9, -v25
	v_add_f32_e32 v9, v41, v9
	v_sub_f32_e32 v41, v13, v53
	v_add_f32_e32 v76, v76, v66
	v_add_f32_e32 v75, v75, v131
	v_and_b32_e32 v54, 0xffff0000, v54
	v_fma_f32 v56, v87, v52, -v84
	v_fma_f32 v21, v126, v9, -v21
	v_add_f32_e32 v41, v41, v9
	v_cvt_pk_bf16_f32 v9, v56, v45
	v_lshlrev_b32_e32 v45, 16, v30
	v_lshlrev_b32_e32 v78, 16, v63
	v_lshlrev_b32_e32 v85, 16, v18
	v_lshlrev_b32_e32 v86, 16, v46
	v_add_f32_e32 v76, v76, v54
	v_min_u32_e32 v135, 2, v102
	v_add_f32_e32 v53, v75, v45
	v_and_b32_e32 v30, 0xffff0000, v30
	v_add_f32_e32 v79, 0, v78
	v_and_b32_e32 v18, 0xffff0000, v18
	v_and_b32_e32 v46, 0xffff0000, v46
	v_lshlrev_b32_e32 v93, 16, v38
	v_lshlrev_b32_e32 v95, 16, v43
	v_add_u32_e32 v135, 6, v135
	v_lshlrev_b32_e32 v49, 16, v10
	v_add_f32_e32 v53, v53, v85
	v_sub_f32_e32 v56, v86, v70
	v_and_b32_e32 v75, 0xffff0000, v10
	v_add_f32_e32 v10, v76, v30
	v_and_b32_e32 v38, 0xffff0000, v38
	v_add_f32_e32 v79, v79, v95
	v_lshlrev_b32_e32 v105, 16, v34
	v_lshlrev_b32_e32 v107, 16, v59
	v_cvt_f32_ubyte0_e32 v135, v135
	v_add_f32_e32 v53, v56, v53
	v_sub_f32_e32 v57, v93, v92
	v_add_f32_e32 v10, v10, v18
	v_sub_f32_e32 v62, v46, v62
	v_and_b32_e32 v34, 0xffff0000, v34
	v_add_f32_e32 v79, v79, v107
	v_lshlrev_b32_e32 v114, 16, v26
	v_lshlrev_b32_e32 v116, 16, v51
	v_rcp_iflag_f32_e32 v135, v135
	v_fma_f32 v56, v87, v53, -v86
	v_add_f32_e32 v53, v57, v53
	v_sub_f32_e32 v61, v105, v104
	v_add_f32_e32 v10, v62, v10
	v_sub_f32_e32 v42, v38, v42
	v_and_b32_e32 v26, 0xffff0000, v26
	v_add_f32_e32 v79, v79, v116
	v_lshlrev_b32_e32 v123, 16, v22
	v_lshlrev_b32_e32 v125, 16, v67
	v_fma_f32 v57, v96, v53, -v93
	v_add_f32_e32 v53, v61, v53
	v_sub_f32_e32 v65, v114, v113
	v_fma_f32 v46, v87, v10, -v46
	v_add_f32_e32 v10, v42, v10
	v_sub_f32_e32 v42, v34, v58
	v_and_b32_e32 v22, 0xffff0000, v22
	v_add_f32_e32 v79, v79, v125
	v_lshlrev_b32_e32 v132, 16, v14
	v_lshlrev_b32_e32 v134, 16, v55
	v_sub_f32_e32 v88, v98, v97
	v_fma_f32 v61, v108, v53, -v105
	v_add_f32_e32 v53, v65, v53
	v_sub_f32_e32 v70, v123, v122
	v_fma_f32 v38, v96, v10, -v38
	v_add_f32_e32 v10, v42, v10
	v_sub_f32_e32 v42, v26, v50
	v_and_b32_e32 v14, 0xffff0000, v14
	v_add_f32_e32 v79, v79, v134
	v_add_f32_e32 v68, v88, v68
	v_fma_f32 v65, v117, v53, -v114
	v_add_f32_e32 v53, v70, v53
	v_sub_f32_e32 v74, v132, v131
	v_fma_f32 v34, v108, v10, -v34
	v_add_f32_e32 v10, v42, v10
	v_sub_f32_e32 v42, v22, v66
	v_lshlrev_b32_e32 v50, 16, v31
	v_sub_f32_e32 v29, v73, v29
	v_lshlrev_b32_e32 v77, 16, v47
	v_and_b32_e32 v63, 0xffff0000, v63
	v_fma_f32 v88, v108, v68, -v98
	v_add_f32_e32 v68, v89, v68
	v_sub_f32_e32 v97, v119, v118
	v_fma_f32 v13, v135, v41, -v13
	v_fma_f32 v70, v126, v53, -v123
	v_add_f32_e32 v53, v74, v53
	v_fma_f32 v26, v117, v10, -v26
	v_add_f32_e32 v10, v42, v10
	v_sub_f32_e32 v42, v14, v54
	v_add_f32_e32 v54, v79, v50
	v_add_f32_e32 v29, v29, v41
	v_sub_f32_e32 v41, v49, v45
	v_lshlrev_b32_e32 v79, 16, v19
	v_add_f32_e32 v80, 0, v63
	v_sub_f32_e32 v78, v77, v78
	v_lshlrev_b32_e32 v94, 16, v39
	v_and_b32_e32 v43, 0xffff0000, v43
	v_fma_f32 v89, v117, v68, -v110
	v_add_f32_e32 v68, v97, v68
	v_sub_f32_e32 v98, v128, v127
	v_fma_f32 v74, v135, v53, -v132
	v_add_f32_e32 v41, v41, v53
	v_lshlrev_b32_e32 v53, 16, v4
	v_and_b32_e32 v62, 0xffff0000, v4
	v_add_f32_e32 v4, v54, v79
	v_add_f32_e32 v80, v80, v43
	v_sub_f32_e32 v95, v94, v95
	v_lshlrev_b32_e32 v106, 16, v35
	v_and_b32_e32 v59, 0xffff0000, v59
	v_fma_f32 v97, v126, v68, -v119
	v_add_f32_e32 v68, v98, v68
	v_sub_f32_e32 v58, v137, v136
	v_add_f32_e32 v4, v78, v4
	v_add_f32_e32 v80, v80, v59
	v_sub_f32_e32 v107, v106, v107
	v_lshlrev_b32_e32 v115, 16, v27
	v_and_b32_e32 v51, 0xffff0000, v51
	v_fma_f32 v98, v135, v68, -v128
	v_add_f32_e32 v58, v58, v68
	v_lshlrev_b32_e32 v66, 16, v5
	v_and_b32_e32 v68, 0xffff0000, v5
	v_fma_f32 v5, v87, v4, -v77
	v_add_f32_e32 v4, v95, v4
	v_add_f32_e32 v80, v80, v51
	v_sub_f32_e32 v116, v115, v116
	v_lshlrev_b32_e32 v124, 16, v23
	v_and_b32_e32 v67, 0xffff0000, v67
	v_sub_f32_e32 v60, v90, v91
	v_fma_f32 v54, v96, v4, -v94
	v_add_f32_e32 v4, v107, v4
	v_add_f32_e32 v80, v80, v67
	v_sub_f32_e32 v125, v124, v125
	v_lshlrev_b32_e32 v133, 16, v15
	v_and_b32_e32 v55, 0xffff0000, v55
; template <int WIN>
; __device__ __forceinline__ void pool_rows(const bf16_t* __restrict__ src, bf16_t* __restrict__ dst, int tseq) {
;     ...
; #pragma unroll
;   for (int i = 0; i < 8; ++i) {
;     float u[8], o[8];
;     unpack8(U[i], u);
;     if (i - WIN >= 0) unpack8(U[(i - WIN) >= 0 ? (i - WIN) : 0], o);
;     else unpack8(H[i < WIN ? i : 0], o);
; #pragma unroll
;     for (int k = 0; k < 8; ++k) s[k] += u[k] - o[k];
;     const int t = tseq + i;
;     const float inv = __builtin_amdgcn_rcpf((float)min(t + 1, WIN));
;     u32x4 r;
;     r.x = pack2(s[0] * inv - u[0], s[1] * inv - u[1]);
;     r.y = pack2(s[2] * inv - u[2], s[3] * inv - u[3]);
;     r.z = pack2(s[4] * inv - u[4], s[5] * inv - u[5]);
;     r.w = pack2(s[6] * inv - u[6], s[7] * inv - u[7]);
;     *(u32x4*)(dst + (long)i * DM) = r;
;   }
	v_add_f32_e32 v52, v60, v52
	v_sub_f32_e32 v64, v99, v103
	v_fma_f32 v77, v108, v4, -v106
	v_add_f32_e32 v4, v116, v4
	v_add_f32_e32 v80, v80, v55
	v_sub_f32_e32 v134, v133, v134
	v_fma_f32 v60, v96, v52, -v90
	v_add_f32_e32 v52, v64, v52
	v_sub_f32_e32 v69, v111, v112
	v_fma_f32 v22, v126, v10, -v22
	v_add_f32_e32 v42, v42, v10
	v_cvt_pk_bf16_f32 v10, v56, v46
	v_lshlrev_b32_e32 v46, 16, v11
	v_and_b32_e32 v31, 0xffff0000, v31
	v_sub_f32_e32 v30, v75, v30
	v_rcp_f32_e32 v2, v2
	v_fma_f32 v78, v117, v4, -v115
	v_add_f32_e32 v4, v125, v4
	v_and_b32_e32 v47, 0xffff0000, v47
	v_fma_f32 v64, v108, v52, -v99
	v_add_f32_e32 v52, v69, v52
	v_sub_f32_e32 v71, v120, v121
	v_fma_f32 v14, v135, v42, -v14
	v_add_f32_e32 v56, v80, v31
	v_add_f32_e32 v30, v30, v42
	v_sub_f32_e32 v42, v46, v50
	v_fma_f32 v80, v126, v4, -v124
	v_add_f32_e32 v4, v134, v4
	v_and_b32_e32 v19, 0xffff0000, v19
	v_sub_f32_e32 v63, v47, v63
	v_and_b32_e32 v39, 0xffff0000, v39
	v_fma_f32 v69, v117, v52, -v111
	v_add_f32_e32 v52, v71, v52
	v_sub_f32_e32 v72, v129, v130
	v_sub_f32_e32 v28, v109, v28
	v_fma_f32 v84, v135, v4, -v133
	v_add_f32_e32 v42, v42, v4
	v_add_f32_e32 v4, v56, v19
	v_sub_f32_e32 v43, v39, v43
	v_and_b32_e32 v35, 0xffff0000, v35
	v_fma_f32 v12, v135, v40, -v12
	v_fma_f32 v71, v126, v52, -v120
	v_add_f32_e32 v52, v72, v52
	v_add_f32_e32 v28, v28, v40
	v_sub_f32_e32 v40, v44, v48
	v_add_f32_e32 v4, v63, v4
	v_sub_f32_e32 v59, v35, v59
	v_and_b32_e32 v27, 0xffff0000, v27
	v_fma_f32 v72, v135, v52, -v129
	v_add_f32_e32 v40, v40, v52
	v_fma_f32 v50, v2, v29, -v73
	v_fma_f32 v52, v2, v30, -v75
	v_lshlrev_b32_e32 v73, 16, v6
	v_and_b32_e32 v75, 0xffff0000, v6
	v_fma_f32 v6, v87, v4, -v47
	v_add_f32_e32 v4, v43, v4
	v_sub_f32_e32 v51, v27, v51
	v_and_b32_e32 v23, 0xffff0000, v23
	v_lshlrev_b32_e32 v76, 16, v7
	v_and_b32_e32 v86, 0xffff0000, v7
	v_fma_f32 v7, v96, v4, -v39
	v_add_f32_e32 v4, v59, v4
	v_sub_f32_e32 v67, v23, v67
	v_and_b32_e32 v15, 0xffff0000, v15
	v_fma_f32 v35, v108, v4, -v35
	v_add_f32_e32 v4, v51, v4
	v_sub_f32_e32 v55, v15, v55
	v_and_b32_e32 v11, 0xffff0000, v11
	v_fma_f32 v27, v117, v4, -v27
	v_add_f32_e32 v4, v67, v4
	v_sub_f32_e32 v31, v11, v31
	v_fma_f32 v23, v126, v4, -v23
	v_add_f32_e32 v4, v55, v4
	v_add_f32_e32 v31, v31, v4
	s_movk_i32 s0, 0x1000
	v_fma_f32 v45, v2, v58, -v137
	v_fma_f32 v48, v2, v28, -v109
	v_fma_f32 v44, v2, v40, -v44
	v_fma_f32 v49, v2, v41, -v49
	v_fma_f32 v46, v2, v42, -v46
	v_fma_f32 v2, v2, v31, -v11
	v_cvt_pk_bf16_f32 v11, v5, v6
	global_store_dwordx4 v[0:1], v[8:11], off
	v_fma_f32 v15, v135, v4, -v15
	v_cvt_pk_bf16_f32 v4, v82, v36
	v_cvt_pk_bf16_f32 v5, v60, v37
	v_cvt_pk_bf16_f32 v6, v57, v38
	v_cvt_pk_bf16_f32 v7, v54, v7
	s_nop 0
	v_add_co_u32_e32 v8, vcc, s0, v0
	s_movk_i32 s0, 0x3000
	s_nop 0
	v_addc_co_u32_e32 v9, vcc, 0, v1, vcc
	global_store_dwordx4 v[8:9], v[4:7], off
	v_add_co_u32_e32 v8, vcc, s96, v0
	s_nop 0
	v_cvt_pk_bf16_f32 v4, v88, v32
	v_cvt_pk_bf16_f32 v5, v64, v33
	v_cvt_pk_bf16_f32 v6, v61, v34
	v_cvt_pk_bf16_f32 v7, v77, v35
	s_nop 0
	v_addc_co_u32_e32 v9, vcc, 0, v1, vcc
	global_store_dwordx4 v[8:9], v[4:7], off
	v_add_co_u32_e32 v8, vcc, s0, v0
	s_movk_i32 s0, 0x4000
	s_nop 0
	v_addc_co_u32_e32 v9, vcc, 0, v1, vcc
	v_cvt_pk_bf16_f32 v4, v89, v24
	v_cvt_pk_bf16_f32 v5, v69, v25
	v_cvt_pk_bf16_f32 v6, v65, v26
	v_cvt_pk_bf16_f32 v7, v78, v27
	global_store_dwordx4 v[8:9], v[4:7], off
	v_add_co_u32_e32 v8, vcc, s0, v0
	s_movk_i32 s0, 0x5000
	s_nop 0
	v_addc_co_u32_e32 v9, vcc, 0, v1, vcc
	v_cvt_pk_bf16_f32 v4, v97, v20
	v_cvt_pk_bf16_f32 v5, v71, v21
	v_cvt_pk_bf16_f32 v6, v70, v22
	v_cvt_pk_bf16_f32 v7, v80, v23
	global_store_dwordx4 v[8:9], v[4:7], off
	v_add_co_u32_e32 v8, vcc, s0, v0
	s_movk_i32 s0, 0x6000
	s_nop 0
	v_addc_co_u32_e32 v9, vcc, 0, v1, vcc
	v_cvt_pk_bf16_f32 v4, v98, v12
	v_cvt_pk_bf16_f32 v5, v72, v13
	v_cvt_pk_bf16_f32 v6, v74, v14
	v_cvt_pk_bf16_f32 v7, v84, v15
	global_store_dwordx4 v[8:9], v[4:7], off
	v_add_co_u32_e32 v8, vcc, s0, v0
	s_nop 0
	v_cvt_pk_bf16_f32 v4, v45, v48
	v_cvt_pk_bf16_f32 v5, v44, v50
	v_cvt_pk_bf16_f32 v6, v49, v52
	v_cvt_pk_bf16_f32 v7, v46, v2
	s_nop 0
	v_addc_co_u32_e32 v9, vcc, 0, v1, vcc
	global_store_dwordx4 v[8:9], v[4:7], off
	v_sub_f32_e32 v2, v53, v81
	v_add_f32_e32 v2, v2, v58
	v_sub_f32_e32 v4, v62, v16
	v_add_f32_e32 v4, v4, v28
	v_sub_f32_e32 v5, v66, v83
	v_sub_f32_e32 v6, v68, v17
	s_mov_b32 s0, 0x3e000000
	v_add_f32_e32 v5, v5, v40
	v_add_f32_e32 v6, v6, v29
	v_sub_f32_e32 v7, v73, v85
	v_sub_f32_e32 v8, v75, v18
	v_sub_f32_e32 v10, v86, v19
	v_fma_f32 v2, v2, s0, -v53
	v_fma_f32 v4, v4, s0, -v62
	v_add_f32_e32 v7, v7, v41
	v_add_f32_e32 v8, v8, v30
	v_sub_f32_e32 v9, v76, v79
	v_add_f32_e32 v10, v10, v31
	v_cvt_pk_bf16_f32 v4, v2, v4
	v_fma_f32 v2, v5, s0, -v66
	v_fma_f32 v5, v6, s0, -v68
	v_add_f32_e32 v9, v9, v42
	v_cvt_pk_bf16_f32 v5, v2, v5
	v_fma_f32 v2, v7, s0, -v73
	v_fma_f32 v6, v8, s0, -v75
	v_fma_f32 v7, v10, s0, -v86
	v_cvt_pk_bf16_f32 v6, v2, v6
	v_fma_f32 v2, v9, s0, -v76
	v_cvt_pk_bf16_f32 v7, v2, v7

; template <int WIN>
; __device__ __forceinline__ void pool_rows(const bf16_t* __restrict__ src, bf16_t* __restrict__ dst, int tseq) {
;   u32x4 U[8], H[WIN];
; #pragma unroll
;   for (int i = 0; i < 8; ++i) U[i] = *(const u32x4*)(src + (long)i * PLD);
; #pragma unroll
;   for (int j = 0; j < WIN; ++j) {
;     if (tseq - WIN + j >= 0) H[j] = *(const u32x4*)(src + (long)(j - WIN) * PLD);
;     else H[j] = (u32x4){0u, 0u, 0u, 0u};
;   }
;   float s[8];
; #pragma unroll
;   for (int k = 0; k < 8; ++k) s[k] = 0.f;
; #pragma unroll
;   for (int j = 0; j < WIN; ++j) {
;     float f[8];
;     unpack8(H[j], f);
; #pragma unroll
;     for (int k = 0; k < 8; ++k) s[k] += f[k];
;   }
; #pragma unroll
;   for (int i = 0; i < 8; ++i) {
;     float u[8], o[8];
;     unpack8(U[i], u);
;     if (i - WIN >= 0) unpack8(U[(i - WIN) >= 0 ? (i - WIN) : 0], o);
;     else unpack8(H[i < WIN ? i : 0], o);
; #pragma unroll
;     for (int k = 0; k < 8; ++k) s[k] += u[k] - o[k];
;     const int t = tseq + i;
;     const float inv = __builtin_amdgcn_rcpf((float)min(t + 1, WIN));
.LBB0_320:
	s_andn2_b64 vcc, exec, s[0:1]
	s_cbranch_vccnz .LBB0_330
	global_load_dwordx4 v[28:31], v[100:101], off
	global_load_dwordx4 v[20:23], v[100:101], off offset:512
	global_load_dwordx4 v[12:15], v[100:101], off offset:1024
	global_load_dwordx4 v[4:7], v[100:101], off offset:1536
	global_load_dwordx4 v[32:35], v[100:101], off offset:2048
	global_load_dwordx4 v[24:27], v[100:101], off offset:2560
	global_load_dwordx4 v[16:19], v[100:101], off offset:3072
	global_load_dwordx4 v[8:11], v[100:101], off offset:3584
	v_mov_b32_e32 v36, 0
	v_cmp_ne_u32_e64 s[0:1], 0, v102
	v_mov_b32_e32 v44, 0
	v_mov_b32_e32 v45, 0
	v_mov_b32_e32 v46, 0
	v_mov_b32_e32 v47, 0
	s_and_saveexec_b64 s[2:3], s[0:1]
	s_cbranch_execz .LBB0_323
	v_add_co_u32_e32 v38, vcc, 0xfffff800, v100
	s_nop 1
	v_addc_co_u32_e32 v39, vcc, -1, v101, vcc
	global_load_dwordx4 v[44:47], v[38:39], off
.LBB0_323:
	s_or_b64 exec, exec, s[2:3]
	v_mov_b32_e32 v37, 0
	v_mov_b32_e32 v38, 0
	v_mov_b32_e32 v39, 0
	s_and_saveexec_b64 s[2:3], s[0:1]
	s_cbranch_execz .LBB0_325
	v_add_co_u32_e32 v36, vcc, 0xfffffa00, v100
	s_nop 1
	v_addc_co_u32_e32 v37, vcc, -1, v101, vcc
	global_load_dwordx4 v[36:39], v[36:37], off
.LBB0_325:
	s_or_b64 exec, exec, s[2:3]
	v_mov_b32_e32 v48, 0
	v_mov_b32_e32 v40, 0
	v_mov_b32_e32 v41, 0
	v_mov_b32_e32 v42, 0
	v_mov_b32_e32 v43, 0
	s_and_saveexec_b64 s[2:3], s[0:1]
	s_cbranch_execz .LBB0_327
	v_add_co_u32_e32 v40, vcc, 0xfffffc00, v100
	s_nop 1
	v_addc_co_u32_e32 v41, vcc, -1, v101, vcc
	global_load_dwordx4 v[40:43], v[40:41], off
.LBB0_327:
	s_or_b64 exec, exec, s[2:3]
	v_mov_b32_e32 v2, 0x40400000
	v_mov_b32_e32 v49, 0
	v_mov_b32_e32 v50, 0
	v_mov_b32_e32 v51, 0
	s_and_saveexec_b64 s[2:3], s[0:1]
	s_cbranch_execz .LBB0_329
	v_add_co_u32_e32 v48, vcc, 0xfffffe00, v100
	v_mov_b32_e32 v2, 4.0
	s_nop 0
	v_addc_co_u32_e32 v49, vcc, -1, v101, vcc
	global_load_dwordx4 v[48:51], v[48:49], off
.LBB0_329:
	s_or_b64 exec, exec, s[2:3]
	s_waitcnt vmcnt(0) lgkmcnt(0)
	v_lshlrev_b32_e32 v68, 16, v28
	v_and_b32_e32 v69, 0xffff0000, v28
	v_min_u32_e32 v28, 3, v102
	v_add_u32_e32 v28, 1, v28
	v_lshlrev_b32_e32 v52, 16, v44
	v_and_b32_e32 v44, 0xffff0000, v44
	v_cvt_f32_ubyte0_e32 v28, v28
	v_add_f32_e32 v56, 0, v52
	v_add_f32_e32 v57, 0, v44
	v_lshlrev_b32_e32 v74, 16, v30
	v_and_b32_e32 v75, 0xffff0000, v30
	v_rcp_iflag_f32_e32 v76, v28
	v_lshlrev_b32_e32 v28, 16, v36
	v_and_b32_e32 v30, 0xffff0000, v36
	v_lshlrev_b32_e32 v71, 16, v29
	v_and_b32_e32 v72, 0xffff0000, v29
	v_lshlrev_b32_e32 v77, 16, v20
	v_add_f32_e32 v29, v56, v28
	v_and_b32_e32 v36, 0xffff0000, v20
	v_add_f32_e32 v20, v57, v30
	v_lshlrev_b32_e32 v81, 16, v40
	v_and_b32_e32 v40, 0xffff0000, v40
	v_lshlrev_b32_e32 v67, 16, v48
	v_and_b32_e32 v48, 0xffff0000, v48
	v_lshlrev_b32_e32 v82, 16, v12
	v_add_f32_e32 v29, v29, v81
	v_and_b32_e32 v85, 0xffff0000, v12
	v_add_f32_e32 v12, v20, v40
	v_add_f32_e32 v29, v29, v67
	v_sub_f32_e32 v52, v68, v52
	v_add_f32_e32 v12, v12, v48
	v_sub_f32_e32 v20, v69, v44
	v_lshlrev_b32_e32 v53, 16, v45
	v_and_b32_e32 v45, 0xffff0000, v45
	v_add_f32_e32 v29, v52, v29
	v_sub_f32_e32 v28, v77, v28
	v_add_f32_e32 v12, v20, v12
	v_add_f32_e32 v58, 0, v53
	v_add_f32_e32 v59, 0, v45
	v_lshlrev_b32_e32 v57, 16, v37
	v_and_b32_e32 v37, 0xffff0000, v37
	v_add_f32_e32 v83, v28, v29
	v_fma_f32 v20, v76, v12, -v69
	v_sub_f32_e32 v28, v36, v30
	v_lshlrev_b32_e32 v56, 16, v21
	v_add_f32_e32 v58, v58, v57
	v_and_b32_e32 v78, 0xffff0000, v21
	v_add_f32_e32 v21, v59, v37
	v_fma_f32 v52, v76, v29, -v68
	v_add_f32_e32 v12, v28, v12
	v_cvt_pk_bf16_f32 v28, v52, v20
	v_lshlrev_b32_e32 v20, 16, v41
	v_and_b32_e32 v41, 0xffff0000, v41
	v_lshlrev_b32_e32 v70, 16, v49
	v_and_b32_e32 v49, 0xffff0000, v49
	v_lshlrev_b32_e32 v52, 16, v13
	v_add_f32_e32 v29, v58, v20
	v_and_b32_e32 v58, 0xffff0000, v13
	v_add_f32_e32 v13, v21, v41
	v_sub_f32_e32 v30, v71, v53
	v_add_f32_e32 v29, v29, v70
	v_add_f32_e32 v13, v13, v49
	v_sub_f32_e32 v21, v72, v45
	v_lshlrev_b32_e32 v54, 16, v46
	v_and_b32_e32 v46, 0xffff0000, v46
	v_add_f32_e32 v29, v30, v29
	v_sub_f32_e32 v53, v56, v57
	v_add_f32_e32 v13, v21, v13
	v_add_f32_e32 v60, 0, v54
	v_add_f32_e32 v61, 0, v46
	v_lshlrev_b32_e32 v59, 16, v38
	v_and_b32_e32 v38, 0xffff0000, v38
	v_fma_f32 v30, v76, v29, -v71
	v_add_f32_e32 v53, v53, v29
	v_fma_f32 v21, v76, v13, -v72
	v_sub_f32_e32 v29, v78, v37
	v_lshlrev_b32_e32 v79, 16, v22
	v_add_f32_e32 v60, v60, v59
	v_and_b32_e32 v80, 0xffff0000, v22
	v_add_f32_e32 v22, v61, v38
	v_min_u32_e32 v61, 2, v102
	v_add_f32_e32 v13, v29, v13
	v_cvt_pk_bf16_f32 v29, v30, v21
	v_lshlrev_b32_e32 v21, 16, v42
	v_and_b32_e32 v42, 0xffff0000, v42
	v_lshlrev_b32_e32 v73, 16, v50
	v_and_b32_e32 v50, 0xffff0000, v50
	v_add_u32_e32 v61, 2, v61
	v_lshlrev_b32_e32 v45, 16, v14
	v_add_f32_e32 v30, v60, v21
	v_and_b32_e32 v86, 0xffff0000, v14
	v_add_f32_e32 v14, v22, v42
	v_cvt_f32_ubyte0_e32 v61, v61
	v_add_f32_e32 v30, v30, v73
	v_sub_f32_e32 v54, v74, v54
	v_add_f32_e32 v14, v14, v50
	v_sub_f32_e32 v22, v75, v46
	v_rcp_iflag_f32_e32 v61, v61
	v_add_f32_e32 v30, v54, v30
	v_sub_f32_e32 v59, v79, v59
	v_add_f32_e32 v14, v22, v14
	v_fma_f32 v54, v76, v30, -v74
	v_add_f32_e32 v59, v59, v30
	v_fma_f32 v22, v76, v14, -v75
	v_sub_f32_e32 v30, v80, v38
	v_add_f32_e32 v14, v30, v14
	v_cvt_pk_bf16_f32 v30, v54, v22
	v_sub_f32_e32 v22, v82, v81
	v_add_f32_e32 v46, v22, v83
	v_sub_f32_e32 v22, v85, v40
	v_fma_f32 v44, v61, v12, -v36
	v_add_f32_e32 v40, v22, v12
	v_sub_f32_e32 v12, v52, v20
	v_fma_f32 v57, v61, v53, -v56
	v_add_f32_e32 v53, v12, v53
	v_sub_f32_e32 v12, v58, v41
	v_lshlrev_b32_e32 v55, 16, v47
	v_and_b32_e32 v47, 0xffff0000, v47
; template <int WIN>
; __device__ __forceinline__ void pool_rows(const bf16_t* __restrict__ src, bf16_t* __restrict__ dst, int tseq) {
;     ...
; #pragma unroll
;   for (int i = 0; i < 8; ++i) {
;     float u[8], o[8];
;     unpack8(U[i], u);
;     if (i - WIN >= 0) unpack8(U[(i - WIN) >= 0 ? (i - WIN) : 0], o);
;     else unpack8(H[i < WIN ? i : 0], o);
; #pragma unroll
;     for (int k = 0; k < 8; ++k) s[k] += u[k] - o[k];
;     const int t = tseq + i;
;     const float inv = __builtin_amdgcn_rcpf((float)min(t + 1, WIN));
;     u32x4 r;
;     r.x = pack2(s[0] * inv - u[0], s[1] * inv - u[1]);
;     r.y = pack2(s[2] * inv - u[2], s[3] * inv - u[3]);
;     r.z = pack2(s[4] * inv - u[4], s[5] * inv - u[5]);
;     r.w = pack2(s[6] * inv - u[6], s[7] * inv - u[7]);
;     *(u32x4*)(dst + (long)i * DM) = r;
;   }
	v_add_f32_e32 v41, v12, v13
	v_sub_f32_e32 v12, v45, v21
	v_add_f32_e32 v62, 0, v55
	v_add_f32_e32 v63, 0, v47
	v_lshlrev_b32_e32 v64, 16, v39
	v_and_b32_e32 v39, 0xffff0000, v39
	v_add_f32_e32 v54, v12, v59
	v_sub_f32_e32 v12, v86, v42
	v_add_f32_e32 v62, v62, v64
	v_add_f32_e32 v63, v63, v39
	v_lshlrev_b32_e32 v65, 16, v43
	v_and_b32_e32 v43, 0xffff0000, v43
	v_add_f32_e32 v42, v12, v14
	v_lshlrev_b32_e32 v12, 16, v31
	v_add_f32_e32 v62, v62, v65
	v_add_f32_e32 v63, v63, v43
	v_lshlrev_b32_e32 v66, 16, v51
	v_and_b32_e32 v51, 0xffff0000, v51
	v_fma_f32 v37, v61, v13, -v78
	v_sub_f32_e32 v13, v12, v55
	v_and_b32_e32 v55, 0xffff0000, v31
	v_add_f32_e32 v62, v62, v66
	v_add_f32_e32 v63, v63, v51
	v_sub_f32_e32 v21, v55, v47
	v_lshlrev_b32_e32 v89, 16, v32
	v_add_f32_e32 v13, v13, v62
	v_add_f32_e32 v47, v21, v63
	v_and_b32_e32 v32, 0xffff0000, v32
	v_lshlrev_b32_e32 v92, 16, v35
	v_fma_f32 v20, v76, v13, -v12
	v_fma_f32 v21, v76, v47, -v55
	v_cvt_pk_bf16_f32 v31, v20, v21
	global_store_dwordx4 v[0:1], v[28:31], off
	v_fma_f32 v84, v61, v83, -v77
	v_cvt_pk_bf16_f32 v20, v84, v44
	v_sub_f32_e32 v44, v92, v12
	v_sub_f32_e32 v28, v89, v68
	v_lshlrev_b32_e32 v68, 16, v23
	v_sub_f32_e32 v29, v32, v69
	v_sub_f32_e32 v12, v68, v64
	v_and_b32_e32 v69, 0xffff0000, v23
	v_add_f32_e32 v64, v12, v13
	v_sub_f32_e32 v13, v69, v39
	v_fma_f32 v12, v61, v64, -v68
	v_add_f32_e32 v39, v13, v47
	s_movk_i32 s0, 0x1000
	v_fma_f32 v60, v61, v59, -v79
	v_fma_f32 v38, v61, v14, -v80
	v_rcp_f32_e32 v2, v2
	v_lshlrev_b32_e32 v91, 16, v34
	v_and_b32_e32 v34, 0xffff0000, v34
	v_fma_f32 v13, v61, v39, -v69
	v_cvt_pk_bf16_f32 v23, v12, v13
	v_add_co_u32_e32 v12, vcc, s0, v0
	v_cvt_pk_bf16_f32 v22, v60, v38
	v_sub_f32_e32 v38, v34, v75
	v_lshlrev_b32_e32 v60, 16, v25
	v_lshlrev_b32_e32 v63, 16, v27
	v_addc_co_u32_e32 v13, vcc, 0, v1, vcc
	v_lshlrev_b32_e32 v75, 16, v15
	v_cvt_pk_bf16_f32 v21, v57, v37
	global_store_dwordx4 v[12:13], v[20:23], off
	v_lshlrev_b32_e32 v61, 16, v16
	v_fma_f32 v14, v2, v46, -v82
	v_sub_f32_e32 v22, v60, v56
	v_sub_f32_e32 v56, v63, v68
	v_and_b32_e32 v68, 0xffff0000, v16
	v_sub_f32_e32 v16, v75, v65
	v_and_b32_e32 v65, 0xffff0000, v15
	v_add_f32_e32 v64, v16, v64
	v_sub_f32_e32 v15, v65, v43
	v_fma_f32 v16, v2, v64, -v75
	v_add_f32_e32 v39, v15, v39
	v_fma_f32 v59, v2, v40, -v85
	v_fma_f32 v81, v2, v53, -v52
	v_fma_f32 v83, v2, v41, -v58
	v_fma_f32 v87, v2, v54, -v45
	v_fma_f32 v88, v2, v42, -v86
	v_lshlrev_b32_e32 v90, 16, v33
	v_and_b32_e32 v33, 0xffff0000, v33
	v_and_b32_e32 v27, 0xffff0000, v27
	v_fma_f32 v2, v2, v39, -v65
	v_cvt_pk_bf16_f32 v15, v16, v2
	v_add_co_u32_e32 v16, vcc, s96, v0
	v_sub_f32_e32 v30, v90, v71
	v_sub_f32_e32 v31, v33, v72
	v_cvt_pk_bf16_f32 v12, v14, v59
	v_sub_f32_e32 v59, v27, v69
	v_lshlrev_b32_e32 v69, 16, v17
	v_and_b32_e32 v71, 0xffff0000, v17
	v_lshlrev_b32_e32 v72, 16, v18
	v_addc_co_u32_e32 v17, vcc, 0, v1, vcc
	v_cvt_pk_bf16_f32 v13, v81, v83
	v_cvt_pk_bf16_f32 v14, v87, v88
	global_store_dwordx4 v[16:17], v[12:15], off
	v_and_b32_e32 v35, 0xffff0000, v35
	v_sub_f32_e32 v55, v35, v55
	v_sub_f32_e32 v15, v72, v45
	v_and_b32_e32 v45, 0xffff0000, v7
	v_sub_f32_e32 v51, v45, v51
	v_add_f32_e32 v39, v51, v39
	s_mov_b32 s1, 0x3e800000
	v_sub_f32_e32 v37, v91, v74
	v_lshlrev_b32_e32 v74, 16, v19
	v_and_b32_e32 v19, 0xffff0000, v19
	v_fma_f32 v51, v39, s1, -v45
	v_add_f32_e32 v39, v55, v39
	v_sub_f32_e32 v43, v19, v65
	v_fma_f32 v35, v39, s1, -v35
	v_add_f32_e32 v39, v59, v39
	v_fma_f32 v27, v39, s1, -v27
	v_add_f32_e32 v39, v43, v39
	v_lshlrev_b32_e32 v43, 16, v7
	v_sub_f32_e32 v7, v43, v66
	v_add_f32_e32 v7, v7, v64
	v_fma_f32 v55, v7, s1, -v43
	v_add_f32_e32 v7, v44, v7
	v_sub_f32_e32 v17, v74, v75
	v_fma_f32 v44, v7, s1, -v92
	v_add_f32_e32 v7, v56, v7
	v_and_b32_e32 v59, 0xffff0000, v6
	v_fma_f32 v56, v7, s1, -v63
	v_add_f32_e32 v17, v17, v7
	v_sub_f32_e32 v7, v59, v50
	v_add_f32_e32 v7, v7, v42
	v_lshlrev_b32_e32 v62, 16, v26
	v_and_b32_e32 v26, 0xffff0000, v26
	v_fma_f32 v42, v7, s1, -v59
	v_add_f32_e32 v7, v38, v7
	v_lshlrev_b32_e32 v38, 16, v6
	v_sub_f32_e32 v47, v26, v80
	v_and_b32_e32 v18, 0xffff0000, v18
; template <int WIN>
; __device__ __forceinline__ void pool_rows(const bf16_t* __restrict__ src, bf16_t* __restrict__ dst, int tseq) {
;     ...
; #pragma unroll
;   for (int i = 0; i < 8; ++i) {
;     float u[8], o[8];
;     unpack8(U[i], u);
;     if (i - WIN >= 0) unpack8(U[(i - WIN) >= 0 ? (i - WIN) : 0], o);
;     else unpack8(H[i < WIN ? i : 0], o);
; #pragma unroll
;     for (int k = 0; k < 8; ++k) s[k] += u[k] - o[k];
;     const int t = tseq + i;
;     const float inv = __builtin_amdgcn_rcpf((float)min(t + 1, WIN));
;     u32x4 r;
;     r.x = pack2(s[0] * inv - u[0], s[1] * inv - u[1]);
;     r.y = pack2(s[2] * inv - u[2], s[3] * inv - u[3]);
;     r.z = pack2(s[4] * inv - u[4], s[5] * inv - u[5]);
;     r.w = pack2(s[6] * inv - u[6], s[7] * inv - u[7]);
;     *(u32x4*)(dst + (long)i * DM) = r;
;   }
	v_sub_f32_e32 v6, v38, v73
	v_lshlrev_b32_e32 v57, 16, v24
	v_and_b32_e32 v24, 0xffff0000, v24
	v_sub_f32_e32 v16, v18, v86
	v_fma_f32 v34, v7, s1, -v34
	v_add_f32_e32 v7, v47, v7
	v_add_f32_e32 v6, v6, v54
	v_sub_f32_e32 v21, v24, v36
	v_sub_f32_e32 v36, v62, v79
	v_fma_f32 v26, v7, s1, -v26
	v_add_f32_e32 v16, v16, v7
	v_fma_f32 v7, v6, s1, -v38
	v_add_f32_e32 v6, v37, v6
	v_fma_f32 v37, v6, s1, -v91
	v_add_f32_e32 v6, v36, v6
	v_and_b32_e32 v50, 0xffff0000, v5
	v_fma_f32 v36, v6, s1, -v62
	v_add_f32_e32 v15, v15, v6
	v_sub_f32_e32 v6, v50, v49
	v_and_b32_e32 v25, 0xffff0000, v25
	v_add_f32_e32 v6, v6, v41
	v_lshlrev_b32_e32 v49, 16, v5
	v_sub_f32_e32 v23, v25, v78
	v_fma_f32 v41, v6, s1, -v50
	v_add_f32_e32 v6, v31, v6
	v_sub_f32_e32 v5, v49, v70
	v_sub_f32_e32 v14, v71, v58
	v_fma_f32 v31, v6, s1, -v33
	v_add_f32_e32 v6, v23, v6
	v_add_f32_e32 v5, v5, v53
	v_fma_f32 v23, v6, s1, -v25
	v_add_f32_e32 v14, v14, v6
	v_fma_f32 v6, v5, s1, -v49
	v_add_f32_e32 v5, v30, v5
	v_fma_f32 v30, v5, s1, -v90
	v_add_f32_e32 v5, v22, v5
	v_sub_f32_e32 v13, v69, v52
	v_fma_f32 v22, v5, s1, -v60
	v_and_b32_e32 v60, 0xffff0000, v4
	v_add_f32_e32 v13, v13, v5
	v_sub_f32_e32 v5, v60, v48
	v_add_f32_e32 v5, v5, v40
	v_lshlrev_b32_e32 v40, 16, v4
	v_and_b32_e32 v54, 0xffff0000, v9
	v_lshlrev_b32_e32 v33, 16, v9
	v_fma_f32 v9, v5, s1, -v60
	v_add_f32_e32 v5, v29, v5
	v_sub_f32_e32 v4, v40, v67
	v_sub_f32_e32 v12, v68, v85
	v_fma_f32 v29, v5, s1, -v32
	v_add_f32_e32 v5, v21, v5
	v_add_f32_e32 v4, v4, v46
	v_sub_f32_e32 v20, v57, v77
	v_fma_f32 v21, v5, s1, -v24
	v_add_f32_e32 v12, v12, v5
	v_fma_f32 v5, v4, s1, -v40
	v_add_f32_e32 v4, v28, v4
	v_sub_f32_e32 v2, v61, v82
	v_and_b32_e32 v62, 0xffff0000, v8
	v_lshlrev_b32_e32 v32, 16, v8
	v_add_f32_e32 v8, v20, v4
	s_movk_i32 s0, 0x3000
	v_fma_f32 v20, v8, s1, -v57
	v_add_f32_e32 v2, v2, v8
	v_add_co_u32_e32 v8, vcc, s0, v0
	v_fma_f32 v28, v4, s1, -v89
	v_cvt_pk_bf16_f32 v4, v5, v9
	s_nop 0
	v_addc_co_u32_e32 v9, vcc, 0, v1, vcc
	s_movk_i32 s0, 0x4000
	v_cvt_pk_bf16_f32 v5, v6, v41
	v_cvt_pk_bf16_f32 v6, v7, v42
	v_cvt_pk_bf16_f32 v7, v55, v51
	global_store_dwordx4 v[8:9], v[4:7], off
	v_add_co_u32_e32 v8, vcc, s0, v0
	s_movk_i32 s0, 0x5000
	s_nop 0
	v_addc_co_u32_e32 v9, vcc, 0, v1, vcc
	v_cvt_pk_bf16_f32 v4, v28, v29
	v_cvt_pk_bf16_f32 v5, v30, v31
	v_cvt_pk_bf16_f32 v6, v37, v34
	v_cvt_pk_bf16_f32 v7, v44, v35
	global_store_dwordx4 v[8:9], v[4:7], off
	v_add_co_u32_e32 v8, vcc, s0, v0
	s_movk_i32 s0, 0x6000
	s_nop 0
	v_addc_co_u32_e32 v9, vcc, 0, v1, vcc
	v_cvt_pk_bf16_f32 v4, v20, v21
	v_cvt_pk_bf16_f32 v5, v22, v23
	v_cvt_pk_bf16_f32 v6, v36, v26
	v_cvt_pk_bf16_f32 v7, v56, v27
	global_store_dwordx4 v[8:9], v[4:7], off
	v_add_co_u32_e32 v8, vcc, s0, v0
	v_fma_f32 v24, v12, s1, -v68
	v_fma_f32 v46, v2, s1, -v61
	v_cvt_pk_bf16_f32 v4, v46, v24
	v_addc_co_u32_e32 v9, vcc, 0, v1, vcc
	v_fma_f32 v19, v39, s1, -v19
	v_fma_f32 v58, v17, s1, -v74
	v_fma_f32 v18, v16, s1, -v18
	v_fma_f32 v47, v15, s1, -v72
	v_fma_f32 v25, v14, s1, -v71
	v_fma_f32 v53, v13, s1, -v69
	v_cvt_pk_bf16_f32 v5, v53, v25
	v_cvt_pk_bf16_f32 v6, v47, v18
	v_cvt_pk_bf16_f32 v7, v58, v19
	global_store_dwordx4 v[8:9], v[4:7], off
	v_and_b32_e32 v52, 0xffff0000, v11
	v_and_b32_e32 v63, 0xffff0000, v10
	v_sub_f32_e32 v4, v32, v40
	v_add_f32_e32 v2, v4, v2
	v_sub_f32_e32 v4, v62, v60
	v_lshlrev_b32_e32 v10, 16, v10
	v_add_f32_e32 v4, v4, v12
	v_sub_f32_e32 v5, v33, v49
	v_sub_f32_e32 v6, v54, v50
	v_lshlrev_b32_e32 v11, 16, v11
	v_add_f32_e32 v5, v5, v13
	v_add_f32_e32 v6, v6, v14
	v_sub_f32_e32 v7, v10, v38
	v_sub_f32_e32 v8, v63, v59
	v_sub_f32_e32 v12, v52, v45
	v_fma_f32 v2, v2, s1, -v32
	v_fma_f32 v4, v4, s1, -v62
	v_add_f32_e32 v7, v7, v15
	v_add_f32_e32 v8, v8, v16
	v_sub_f32_e32 v9, v11, v43
	v_add_f32_e32 v12, v12, v39
	v_cvt_pk_bf16_f32 v4, v2, v4
	v_fma_f32 v2, v5, s1, -v33
	v_fma_f32 v5, v6, s1, -v54
	v_add_f32_e32 v9, v9, v17
	v_cvt_pk_bf16_f32 v5, v2, v5
	v_fma_f32 v2, v7, s1, -v10
	v_fma_f32 v6, v8, s1, -v63
	v_fma_f32 v7, v12, s1, -v52
	v_cvt_pk_bf16_f32 v6, v2, v6
	v_fma_f32 v2, v9, s1, -v11
	v_cvt_pk_bf16_f32 v7, v2, v7

; template <int WIN>
; __device__ __forceinline__ void pool_rows(const bf16_t* __restrict__ src, bf16_t* __restrict__ dst, int tseq) {
;   u32x4 U[8], H[WIN];
; #pragma unroll
;   for (int i = 0; i < 8; ++i) U[i] = *(const u32x4*)(src + (long)i * PLD);
; #pragma unroll
;   for (int j = 0; j < WIN; ++j) {
;     if (tseq - WIN + j >= 0) H[j] = *(const u32x4*)(src + (long)(j - WIN) * PLD);
;     else H[j] = (u32x4){0u, 0u, 0u, 0u};
;   }
; __device__ void pool_item(const Params& p, int it) {
;     ...
;   if (g == 0) pool_rows<2>(src, dst, tseq);
.LBB0_331:
	s_and_b64 vcc, exec, s[0:1]
	s_cbranch_vccz .LBB0_264
	global_load_dwordx4 v[32:35], v[100:101], off
	global_load_dwordx4 v[28:31], v[100:101], off offset:512
	global_load_dwordx4 v[24:27], v[100:101], off offset:1024
	global_load_dwordx4 v[20:23], v[100:101], off offset:1536
	global_load_dwordx4 v[12:15], v[100:101], off offset:2048
	global_load_dwordx4 v[8:11], v[100:101], off offset:2560
	global_load_dwordx4 v[16:19], v[100:101], off offset:3072
	global_load_dwordx4 v[4:7], v[100:101], off offset:3584
	v_mov_b32_e32 v36, 0
	v_cmp_ne_u32_e64 s[0:1], 0, v102
	v_mov_b32_e32 v40, 0
	v_mov_b32_e32 v41, 0
	v_mov_b32_e32 v42, 0
	v_mov_b32_e32 v43, 0
	s_and_saveexec_b64 s[2:3], s[0:1]
	s_cbranch_execz .LBB0_334
	v_add_co_u32_e32 v38, vcc, 0xfffffc00, v100
	s_nop 1
	v_addc_co_u32_e32 v39, vcc, -1, v101, vcc
	global_load_dwordx4 v[40:43], v[38:39], off
.LBB0_334:
	s_or_b64 exec, exec, s[2:3]
	v_mov_b32_e32 v2, 1.0
	v_mov_b32_e32 v37, 0
	v_mov_b32_e32 v38, 0
	v_mov_b32_e32 v39, 0
	s_and_saveexec_b64 s[2:3], s[0:1]
	s_cbranch_execz .LBB0_263
	v_add_co_u32_e32 v36, vcc, 0xfffffe00, v100
	v_mov_b32_e32 v2, 2.0
	s_nop 0
	v_addc_co_u32_e32 v37, vcc, -1, v101, vcc
	global_load_dwordx4 v[36:39], v[36:37], off
	s_branch .LBB0_263

; __device__ __forceinline__ float softplusf_(float x) { return x > 20.f ? x : log1pf(__expf(x)); }
; __device__ __forceinline__ void ssm_scalars(const float (&g)[2], float dtb, float A_h, float* sc, int lane) {
;   const float d0 = softplusf_(g[0] + dtb);
;   const float d1 = softplusf_(g[1] + dtb);
; __device__ void ssm_item(const Params& p, int layer, int b, int h) {
;     ...
;   const float A_h = -__expf(p.a_log[layer * 32 + h]);
;   const float dtb = p.dt_bias[layer * 32 + h];
;   const float dsk = p.d_skip[layer * 32 + h];
;   const size_t row_b = (size_t)b * SEQ;
;   for (int i = tid0; i < 64 * 128 / 2; i += 512) ((unsigned*)Sb)[i] = 0u;
;   f32x4 acc_s[4];
; #pragma unroll
;   for (int i = 0; i < 4; ++i) acc_s[i] = (f32x4){0.f, 0.f, 0.f, 0.f};
;   float gpre[2] = {0.f, 0.f};
;   if (w == 0) { ssm_gates(small, row_b, h, lane0, gpre); ssm_scalars(gpre, dtb, A_h, scal, lane0); ssm_gates(small, row_b + 128, h, lane0, gpre); }
.LBB0_383:
	s_or_b64 exec, exec, s[0:1]
	s_lshl_b32 s0, s50, 2
	s_and_b32 s0, s0, 28
	s_add_i32 s0, s0, s10
	s_ashr_i32 s46, s0, 2
	s_waitcnt vmcnt(0)
	v_mul_f32_e32 v0, 0x3fb8aa3b, v0
	v_exp_f32_e32 v128, v0
	s_ashr_i32 s47, s46, 31
	s_lshl_b64 s[0:1], s[46:47], 11
	s_cmp_gt_u32 s12, 63
	v_lshlrev_b32_e32 v0, 1, v126
	s_mov_b32 s77, 0x41a00000
	s_cselect_b64 s[2:3], -1, 0
	s_cmp_lt_u32 s12, 64
	v_and_b32_e32 v0, 0x7e, v0
	s_mov_b32 s80, 0x3ffffc
	s_mov_b32 s81, 0x3ffffe
	s_mov_b32 s82, 0x40000
	s_mov_b32 s83, 0x80000
	s_mov_b32 s84, 0x1cc80000
	s_cbranch_scc0 .LBB0_389
	v_or_b32_e32 v4, s0, v0
	v_mov_b32_e32 v5, s1
	v_lshlrev_b64 v[4:5], 8, v[4:5]
	v_lshl_add_u64 v[4:5], s[44:45], 0, v[4:5]
	s_mov_b64 s[10:11], 0x42c80000
	v_lshl_add_u64 v[4:5], v[4:5], 0, s[10:11]
	s_lshl_b32 s72, s48, 2
	v_lshl_add_u64 v[6:7], v[4:5], 0, s[72:73]
	global_load_dword v8, v[6:7], off
	global_load_dword v2, v[6:7], off offset:256
	s_waitcnt vmcnt(0) lgkmcnt(0)
	v_add_f32_e32 v6, v127, v8
	v_cmp_nlt_f32_e32 vcc, s77, v6
	s_and_saveexec_b64 s[10:11], vcc
	s_cbranch_execz .LBB0_386
	v_mul_f32_e32 v6, 0x3fb8aa3b, v6
	v_exp_f32_e32 v20, v6
	s_mov_b32 s14, 0x3f2aaaab
	v_add_f32_e32 v8, 1.0, v20
	v_frexp_mant_f32_e32 v10, v8
	v_cvt_f64_f32_e32 v[6:7], v8
	v_frexp_exp_i32_f64_e32 v6, v[6:7]
	v_cmp_gt_f32_e32 vcc, s14, v10
	v_add_f32_e32 v9, -1.0, v8
	v_sub_f32_e32 v11, v9, v8
	v_subbrev_co_u32_e32 v14, vcc, 0, v6, vcc
	v_sub_u32_e32 v6, 0, v14
	v_sub_f32_e32 v9, v20, v9
	v_add_f32_e32 v11, 1.0, v11
	v_ldexp_f32 v7, v8, v6
	v_add_f32_e32 v9, v9, v11
	v_add_f32_e32 v8, -1.0, v7
	v_add_f32_e32 v10, 1.0, v7
	v_ldexp_f32 v6, v9, v6
	v_add_f32_e32 v9, 1.0, v8
	v_add_f32_e32 v11, -1.0, v10
	v_sub_f32_e32 v9, v7, v9
	v_sub_f32_e32 v7, v7, v11
	v_add_f32_e32 v9, v6, v9
	v_add_f32_e32 v6, v6, v7
	v_add_f32_e32 v15, v10, v6
	v_rcp_f32_e32 v17, v15
	v_sub_f32_e32 v7, v15, v10
	v_sub_f32_e32 v16, v6, v7
	v_add_f32_e32 v7, v8, v9
	v_mul_f32_e32 v19, v7, v17
	v_sub_f32_e32 v6, v7, v8
	v_mul_f32_e32 v8, v15, v19
	v_fma_f32 v10, v19, v15, -v8
	v_fmac_f32_e32 v10, v19, v16
	v_sub_f32_e32 v18, v9, v6
	v_add_f32_e32 v6, v8, v10
	v_sub_f32_e32 v9, v7, v6
	v_pk_add_f32 v[12:13], v[6:7], v[8:9] neg_lo:[0,1] neg_hi:[0,1]
	v_mov_b32_e32 v11, v6
	v_pk_add_f32 v[6:7], v[12:13], v[10:11] neg_lo:[0,1] neg_hi:[0,1]
	s_mov_b32 s14, 0x3f317218
	v_add_f32_e32 v7, v18, v7
	v_add_f32_e32 v6, v6, v7
	v_add_f32_e32 v7, v9, v6
	v_mul_f32_e32 v18, v17, v7
	v_mul_f32_e32 v8, v15, v18
	v_fma_f32 v10, v18, v15, -v8
	v_fmac_f32_e32 v10, v18, v16
	v_sub_f32_e32 v9, v9, v7
	v_add_f32_e32 v15, v6, v9
	v_add_f32_e32 v6, v8, v10
	v_sub_f32_e32 v9, v7, v6
	v_pk_add_f32 v[12:13], v[6:7], v[8:9] neg_lo:[0,1] neg_hi:[0,1]
	v_mov_b32_e32 v11, v6
	v_pk_add_f32 v[6:7], v[12:13], v[10:11] neg_lo:[0,1] neg_hi:[0,1]
	s_nop 0
	v_add_f32_e32 v7, v15, v7
	v_add_f32_e32 v6, v6, v7
	v_add_f32_e32 v7, v19, v18
	v_add_f32_e32 v6, v9, v6
	v_sub_f32_e32 v8, v7, v19
	v_mul_f32_e32 v6, v17, v6
	v_sub_f32_e32 v8, v18, v8
	v_add_f32_e32 v8, v8, v6
	v_add_f32_e32 v10, v7, v8
	v_mul_f32_e32 v11, v10, v10
	v_fmamk_f32 v6, v11, 0x3e9b6dac, v199
	v_fmaak_f32 v167, v11, v6, 0x3f2aaada
	v_cvt_f32_i32_e32 v6, v14
	v_sub_f32_e32 v7, v10, v7
	v_sub_f32_e32 v7, v8, v7
	v_ldexp_f32 v12, v7, 1
	v_mul_f32_e32 v7, v10, v11
	v_ldexp_f32 v9, v10, 1
	v_pk_mul_f32 v[10:11], v[6:7], v[166:167]
	s_nop 0
	v_fma_f32 v8, v6, s14, -v10
	v_fmac_f32_e32 v8, 0xb102e308, v6
	v_pk_add_f32 v[6:7], v[10:11], v[8:9]
	s_mov_b32 s14, 0x7f800000
	v_sub_f32_e32 v9, v7, v9
	v_sub_f32_e32 v9, v11, v9
	v_add_f32_e32 v13, v12, v9
	v_mov_b32_e32 v12, v10
	v_pk_add_f32 v[10:11], v[6:7], v[10:11] neg_lo:[0,1] neg_hi:[0,1]
	v_pk_add_f32 v[14:15], v[6:7], v[12:13]
	v_mov_b32_e32 v9, v6
	v_mov_b32_e32 v11, v15
	v_pk_add_f32 v[16:17], v[8:9], v[10:11] neg_lo:[0,1] neg_hi:[0,1]
	v_pk_add_f32 v[8:9], v[8:9], v[10:11]
	v_mov_b32_e32 v12, v13
	v_pk_add_f32 v[10:11], v[8:9], v[6:7] op_sel:[1,0] op_sel_hi:[0,1] neg_lo:[0,1] neg_hi:[0,1]
	v_pk_add_f32 v[18:19], v[14:15], v[10:11] op_sel_hi:[1,0] neg_lo:[0,1] neg_hi:[0,1]
	v_mov_b32_e32 v14, v15
	v_mov_b32_e32 v15, v9
	v_pk_mov_b32 v[10:11], v[6:7], v[10:11] op_sel:[1,0]
	v_mov_b32_e32 v13, v6
	v_pk_add_f32 v[10:11], v[14:15], v[10:11] neg_lo:[0,1] neg_hi:[0,1]
	v_mov_b32_e32 v18, v16
	v_pk_add_f32 v[6:7], v[12:13], v[10:11] neg_lo:[0,1] neg_hi:[0,1]
	v_mov_b32_e32 v17, v9
	v_pk_add_f32 v[10:11], v[18:19], v[6:7]
	v_cmp_neq_f32_e32 vcc, s14, v20
	v_pk_add_f32 v[12:13], v[10:11], v[10:11] op_sel:[0,1] op_sel_hi:[1,0]
	s_mov_b32 s14, 0x33800000
	v_pk_add_f32 v[8:9], v[8:9], v[12:13] op_sel:[1,0] op_sel_hi:[0,1]
	v_mov_b32_e32 v11, v8
	v_pk_add_f32 v[14:15], v[10:11], v[16:17] neg_lo:[0,1] neg_hi:[0,1]
	v_mov_b32_e32 v7, v12
	v_sub_f32_e32 v9, v10, v14
	v_pk_add_f32 v[6:7], v[6:7], v[14:15] neg_lo:[0,1] neg_hi:[0,1]
	v_sub_f32_e32 v9, v16, v9
	v_add_f32_e32 v6, v6, v9
	v_add_f32_e32 v6, v6, v7
	v_add_f32_e32 v6, v8, v6
	v_cndmask_b32_e32 v6, v204, v6, vcc
	v_cmp_ngt_f32_e32 vcc, -1.0, v20
	s_nop 1
	v_cndmask_b32_e32 v6, v205, v6, vcc
	v_cmp_neq_f32_e32 vcc, -1.0, v20
	s_nop 1
	v_cndmask_b32_e32 v6, v206, v6, vcc
	v_cmp_lt_f32_e64 vcc, |v20|, s14
	s_nop 1
	v_cndmask_b32_e32 v6, v6, v20, vcc

; __device__ __forceinline__ float wave_last(float v) { return __int_as_float(__builtin_amdgcn_readlane(__float_as_int(v), 63)); }
; __device__ __forceinline__ void ssm_scalars(const float (&g)[2], float dtb, float A_h, float* sc, int lane) {
;     ...
;   const float a0 = d0 * A_h, a1 = d1 * A_h;
;   const float S = wave_scan_add(a0 + a1, lane);
;   const float tot = wave_last(S);
;   sc[2 * lane] = d0; sc[2 * lane + 1] = d1;
;   sc[128 + 2 * lane] = S - a1; sc[128 + 2 * lane + 1] = S;
;   sc[256 + 2 * lane] = __expf(tot - (S - a1)); sc[256 + 2 * lane + 1] = __expf(tot - S);
; }
.LBB0_388:
	s_or_b64 exec, exec, s[10:11]
	v_mul_f32_e32 v2, v128, v6
	v_fma_f32 v2, v7, -v128, -v2
	v_mov_b32_e32 v8, v3
	s_lshl_b32 s72, s48, 2
	v_add_f32_dpp v2, v2, v2 row_shr:1 row_mask:0xf bank_mask:0xf bound_ctrl:1
	v_lshl_add_u64 v[4:5], v[4:5], 0, s[72:73]
	v_add_co_u32_e32 v4, vcc, 0x8000, v4
	v_add_f32_dpp v2, v2, v2 row_shr:2 row_mask:0xf bank_mask:0xf bound_ctrl:1
	s_nop 0
	v_addc_co_u32_e32 v5, vcc, 0, v5, vcc
	v_add_f32_dpp v2, v2, v2 row_shr:4 row_mask:0xf bank_mask:0xf bound_ctrl:1
	s_nop 1
	v_add_f32_dpp v2, v2, v2 row_shr:8 row_mask:0xf bank_mask:0xf bound_ctrl:1
	s_nop 1
	v_mov_b32_dpp v8, v2 row_bcast:15 row_mask:0xa bank_mask:0xf
	v_add_f32_e32 v2, v2, v8
	v_mov_b32_e32 v8, v3
	s_nop 1
	v_mov_b32_dpp v8, v2 row_bcast:31 row_mask:0xc bank_mask:0xf
	v_add_f32_e32 v9, v2, v8
	v_lshl_add_u32 v2, v0, 2, 0
	v_readlane_b32 s10, v9, 63
	v_add_u32_e32 v2, 0x20000, v2
	v_fma_f32 v8, v7, v128, v9
	ds_write2st64_b64 v2, v[6:7], v[8:9] offset1:1
	v_sub_f32_e32 v6, s10, v8
	v_sub_f32_e32 v7, s10, v9
	v_mul_f32_e32 v6, 0x3fb8aa3b, v6
	v_mul_f32_e32 v7, 0x3fb8aa3b, v7
	v_exp_f32_e32 v6, v6
	v_exp_f32_e32 v7, v7
	ds_write_b64 v2, v[6:7] offset:1024
	global_load_dword v129, v[4:5], off
	global_load_dword v130, v[4:5], off offset:256
	s_branch .LBB0_391

; __device__ void ssm_item(const Params& p, int layer, int b, int h) {
;     ...
;   u32x4 pfC[4], pfB[4], pfX[2];
; #pragma unroll
;   for (int rep = 0; rep < 4; ++rep) {
;     const int idx = tid0 + rep * 512, row = idx >> 4, seg = idx & 15;
;     const bf16_t* rp = bcconv + (row_b + row) * 1024 + g * 128 + seg * 8;
;     pfB[rep] = *(const u32x4*)rp;
;     pfC[rep] = *(const u32x4*)(rp + 512);
;   }
; #pragma unroll
;   for (int rep = 0; rep < 2; ++rep) {
;     const int idx = tid0 + rep * 512, row = idx >> 3, seg = idx & 7;
;     pfX[rep] = *(const u32x4*)(xconv + (row_b + row) * DM + h * 64 + seg * 8);
;   }
;   __syncthreads();
.LBB0_391:
	s_ashr_i32 s42, s12, 6
	s_lshl_b32 s10, s13, 5
	s_add_u32 s4, s4, s10
	s_addc_u32 s5, s5, 0
	v_ashrrev_i32_e32 v6, 4, v126
	s_add_u32 s4, s4, 0x5b080000
	v_lshlrev_b32_e32 v8, 4, v126
	v_ashrrev_i32_e32 v7, 31, v6
	s_addc_u32 s5, s5, 0
	v_and_b32_e32 v2, 0xf0, v8
	v_lshl_add_u64 v[6:7], s[0:1], 0, v[6:7]
	v_lshl_add_u64 v[4:5], s[4:5], 0, v[2:3]
	v_lshlrev_b64 v[6:7], 11, v[6:7]
	v_lshl_add_u64 v[6:7], v[4:5], 0, v[6:7]
	v_add_u32_e32 v9, 0x200, v126
	global_load_dwordx4 v[60:63], v[6:7], off
	global_load_dwordx4 v[64:67], v[6:7], off offset:1024
	v_ashrrev_i32_e32 v6, 4, v9
	v_ashrrev_i32_e32 v7, 31, v6
	v_lshl_add_u64 v[6:7], s[0:1], 0, v[6:7]
	v_lshlrev_b64 v[6:7], 11, v[6:7]
	v_lshl_add_u64 v[6:7], v[4:5], 0, v[6:7]
	v_add_u32_e32 v2, 0x400, v126
	global_load_dwordx4 v[68:71], v[6:7], off
	global_load_dwordx4 v[72:75], v[6:7], off offset:1024
	v_ashrrev_i32_e32 v6, 4, v2
	v_ashrrev_i32_e32 v7, 31, v6
	v_lshl_add_u64 v[6:7], s[0:1], 0, v[6:7]
	v_lshlrev_b64 v[6:7], 11, v[6:7]
	v_lshl_add_u64 v[6:7], v[4:5], 0, v[6:7]
	v_add_u32_e32 v2, 0x600, v126
	global_load_dwordx4 v[76:79], v[6:7], off
	global_load_dwordx4 v[80:83], v[6:7], off offset:1024
	v_ashrrev_i32_e32 v6, 4, v2
	v_ashrrev_i32_e32 v7, 31, v6
	v_lshl_add_u64 v[6:7], s[0:1], 0, v[6:7]
	s_lshl_b32 s10, s48, 6
	s_lshl_b32 s11, s48, 7
	v_lshlrev_b64 v[6:7], 11, v[6:7]
	s_add_u32 s6, s6, s11
	v_lshl_add_u64 v[4:5], v[4:5], 0, v[6:7]
	s_addc_u32 s7, s7, 0
	v_ashrrev_i32_e32 v6, 3, v126
	s_add_u32 s6, s6, 0x57080000
	v_and_b32_e32 v2, 0x70, v8
	v_ashrrev_i32_e32 v7, 31, v6
	v_ashrrev_i32_e32 v8, 3, v9
	s_addc_u32 s7, s7, 0
	v_lshl_add_u64 v[6:7], s[0:1], 0, v[6:7]
	v_ashrrev_i32_e32 v9, 31, v8
	global_load_dwordx4 v[84:87], v[4:5], off
	global_load_dwordx4 v[88:91], v[4:5], off offset:1024
	v_lshl_add_u64 v[4:5], s[6:7], 0, v[2:3]
	v_lshlrev_b64 v[6:7], 12, v[6:7]
	v_lshl_add_u64 v[8:9], s[0:1], 0, v[8:9]
	v_lshl_add_u64 v[6:7], v[4:5], 0, v[6:7]
	v_lshlrev_b64 v[8:9], 12, v[8:9]
	v_lshl_add_u64 v[4:5], v[4:5], 0, v[8:9]
	global_load_dwordx4 v[92:95], v[6:7], off
	global_load_dwordx4 v[96:99], v[4:5], off
	s_and_b32 s49, s10, 0xc0
	s_lshl_b32 s10, s48, 21
	s_lshl_b32 s51, s42, 4
	s_and_b32 s10, s10, 0x3800000
	s_add_u32 s8, s8, s10
	s_addc_u32 s9, s9, 0
	s_lshl_b32 s10, s42, 12
	s_add_i32 s56, s10, 0
	s_lshl_b32 s10, s42, 9
	s_and_b32 s10, s10, 0xfffffc00
	s_add_i32 s58, s10, 0
	s_add_i32 s10, 0, 0x20000
	v_lshl_add_u32 v131, v0, 2, s10
	s_lshl_b32 s10, s42, 11
	s_add_i32 s59, s10, 0
	s_and_b32 s57, s51, 16
	s_add_i32 s59, s59, 0x10000
	s_add_i32 s60, s58, 0x1c000
	s_cmp_gt_i32 s42, -1
	s_cselect_b64 s[10:11], -1, 0
	s_cmp_lt_u32 s12, 64
	s_cselect_b64 s[12:13], -1, 0
	s_cmp_gt_i32 s42, 0
	s_cselect_b64 s[14:15], -1, 0
	s_cmp_eq_u32 s42, 1
	s_cselect_b64 s[16:17], -1, 0
	s_cmp_gt_i32 s42, 1
	s_cselect_b64 s[18:19], -1, 0
	s_cmp_eq_u32 s42, 2
	s_cselect_b64 s[20:21], -1, 0
	s_cmp_gt_i32 s42, 2
	s_cselect_b64 s[22:23], -1, 0
	s_cmp_eq_u32 s42, 3
	s_cselect_b64 s[24:25], -1, 0
	s_cmp_gt_i32 s42, 3
	s_cselect_b64 s[26:27], -1, 0
	s_cmp_eq_u32 s42, 4
	s_cselect_b64 s[28:29], -1, 0
	s_cmp_gt_i32 s42, 4
	s_cselect_b64 s[30:31], -1, 0
	s_cmp_eq_u32 s42, 5
	s_cselect_b64 s[34:35], -1, 0
	s_cmp_gt_i32 s42, 5
	s_cselect_b64 s[36:37], -1, 0
	s_cmp_eq_u32 s42, 6
	s_cselect_b64 s[38:39], -1, 0
	s_cmp_gt_i32 s42, 6
	s_cselect_b64 s[40:41], -1, 0
	s_cmp_eq_u32 s42, 7
	s_cselect_b64 s[42:43], -1, 0
	s_lshl_b64 s[46:47], s[46:47], 19
	s_lshl_b32 s48, s48, 2
	s_add_u32 s44, s44, s48
	s_addc_u32 s45, s45, 0
	v_and_b32_e32 v0, 63, v126
	s_add_u32 s44, s44, s46
	v_lshlrev_b32_e32 v2, 9, v0
	s_addc_u32 s45, s45, s47
	v_lshl_add_u64 v[4:5], s[44:45], 0, v[2:3]
	s_mov_b64 s[44:45], 0x42c90000
	v_mov_b32_e32 v36, 0
	s_mov_b32 s62, 0
	v_lshl_add_u64 v[108:109], v[4:5], 0, s[44:45]
	s_mov_b64 s[44:45], 0
	s_lshl_b32 s72, s49, 1
	v_mov_b32_e32 v37, v36
	v_mov_b32_e32 v38, v36
	v_mov_b32_e32 v39, v36
	v_mov_b32_e32 v56, v36
	v_mov_b32_e32 v57, v36
	v_mov_b32_e32 v58, v36
	v_mov_b32_e32 v59, v36
	v_mov_b32_e32 v44, v36
	v_mov_b32_e32 v45, v36
	v_mov_b32_e32 v46, v36
	v_mov_b32_e32 v47, v36
	v_mov_b32_e32 v52, v36
	v_mov_b32_e32 v53, v36
	v_mov_b32_e32 v54, v36
	v_mov_b32_e32 v55, v36
	s_waitcnt lgkmcnt(0)
	s_barrier
	s_branch .LBB0_393
; #define SBAR __builtin_amdgcn_sched_barrier(0)
; #define LD_YO(dst, kk) _Pragma("unroll") for (int p_ = 0; p_ < 4; ++p_) dst[p_] = ldsfrag(Sb, LW, p_ * 16 + fr, (kk) * 32 + fq * 8)
; #define MM_YO(srcf, kk) _Pragma("unroll") for (int p_ = 0; p_ < 4; ++p_) acc_y[p_] = mfma16(srcf[p_], cfr[kk], acc_y[p_])
; #define LD_YD(dst, kk) do { dst[0] = ldsfrag(Bm, LW, l, (kk) * 32 + fq * 8); \
;         _Pragma("unroll") for (int p_ = 0; p_ < 4; ++p_) dst[1 + p_] = ldsfrag_tr(Xdt, LX, (kk) * 32, p_ * 16, lane); } while (0)
; #define MM_YD(srcf) _Pragma("unroll") for (int p_ = 0; p_ < 4; ++p_) acc_y[p_] = mfma16(srcf[1 + p_], srcf[0], acc_y[p_])
; #define SBAR __builtin_amdgcn_sched_barrier(0)
; __device__ void ssm_item(const Params& p, int layer, int b, int h) {
;     ...
;     asm volatile("s_waitcnt lgkmcnt(0)" ::: "memory");
;     {
;       f32x4 acc_y[4];
; #pragma unroll
;       for (int pb = 0; pb < 4; ++pb) acc_y[pb] = (f32x4){0.f, 0.f, 0.f, 0.f};
;     ...
;       {
;         const float ea = __expf(s_acs[l]);
;         bf16x8 o0[4], o1[4], o2[4], o3[4], d0[5], d1[5], d2[5], d3[5];
;         LD_YO(o0, 0); SBAR;
;         LD_YO(o1, 1); MM_YO(o0, 0); SBAR;
;         LD_YO(o2, 2); MM_YO(o1, 1); SBAR;
;         LD_YO(o3, 3); MM_YO(o2, 2); SBAR;
;         LD_YD(d0, 0); MM_YO(o3, 3); SBAR;
; #pragma unroll
;         for (int pb = 0; pb < 4; ++pb) acc_y[pb] *= ea;
;         LD_YD(d1, 1); MM_YD(d0); SBAR;
;         LD_YD(d2, 2); MM_YD(d1); SBAR;
;         LD_YD(d3, 3); MM_YD(d2); SBAR;
;         MM_YD(d3); SBAR;
;       }
.LBB0_392:
	v_cvt_pk_bf16_f32 v76, v84, v85
	v_cvt_pk_bf16_f32 v77, v80, v81
	ds_write_b64 v120, v[76:77] offset:35840
	s_waitcnt lgkmcnt(0)
	ds_read_b32 v76, v154 offset:512
	v_add_u32_e32 v105, 0x1c000, v137
	s_waitcnt lgkmcnt(0)
	v_mul_f32_e32 v104, 0x3fb8aa3b, v76
	ds_read_b128 v[76:79], v105
	ds_read_b128 v[80:83], v105 offset:4096
	ds_read_b128 v[84:87], v105 offset:8192
	ds_read_b128 v[88:91], v105 offset:12288
	ds_read_b128 v[92:95], v105 offset:1024
	ds_read_b128 v[96:99], v105 offset:5120
	ds_read_b128 v[100:103], v105 offset:9216
	ds_read_b128 v[120:123], v105 offset:13312
	s_waitcnt lgkmcnt(0)
	v_mfma_f32_16x16x32_bf16 v[76:79], v[76:79], v[72:75], 0
	v_mfma_f32_16x16x32_bf16 v[80:83], v[80:83], v[72:75], 0
	v_mfma_f32_16x16x32_bf16 v[84:87], v[84:87], v[72:75], 0
	v_mfma_f32_16x16x32_bf16 v[72:75], v[88:91], v[72:75], 0
	v_mfma_f32_16x16x32_bf16 v[76:79], v[92:95], v[68:71], v[76:79]
	v_mfma_f32_16x16x32_bf16 v[80:83], v[96:99], v[68:71], v[80:83]
	v_mfma_f32_16x16x32_bf16 v[84:87], v[100:103], v[68:71], v[84:87]
	ds_read_b128 v[88:91], v105 offset:2048
	ds_read_b128 v[92:95], v105 offset:6144
	ds_read_b128 v[96:99], v105 offset:10240
	ds_read_b128 v[100:103], v105 offset:14336
	v_mfma_f32_16x16x32_bf16 v[68:71], v[120:123], v[68:71], v[72:75]
	s_waitcnt lgkmcnt(0)
	v_mfma_f32_16x16x32_bf16 v[72:75], v[88:91], v[64:67], v[76:79]
	v_mfma_f32_16x16x32_bf16 v[76:79], v[92:95], v[64:67], v[80:83]
	v_mfma_f32_16x16x32_bf16 v[80:83], v[96:99], v[64:67], v[84:87]
	s_nop 2
	ds_read_b128 v[84:87], v105 offset:3072
	ds_read_b128 v[88:91], v105 offset:7168
	ds_read_b128 v[92:95], v105 offset:11264
	ds_read_b128 v[96:99], v105 offset:15360
	v_mfma_f32_16x16x32_bf16 v[64:67], v[100:103], v[64:67], v[68:71]
	v_add_u32_e32 v102, s61, v150
	s_waitcnt lgkmcnt(0)
	v_mfma_f32_16x16x32_bf16 v[72:75], v[84:87], v[60:63], v[72:75]
	v_lshl_add_u32 v86, v144, 1, v102
	v_add_u32_e32 v105, v102, v135
	ds_read_b128 v[68:71], v0 offset:32768
	ds_read_b64_tr_b16 v[100:101], v105
	v_add_u32_e32 v107, v102, v2
	v_lshl_add_u32 v120, v146, 1, v102
	v_mfma_f32_16x16x32_bf16 v[76:79], v[88:91], v[60:63], v[76:79]
	ds_read_b64_tr_b16 v[102:103], v86 offset:256
	ds_read_b64_tr_b16 v[84:85], v107
	ds_read_b64_tr_b16 v[90:91], v86 offset:1280
	ds_read_b64_tr_b16 v[88:89], v105 offset:1024
	v_exp_f32_e32 v104, v104
	v_mfma_f32_16x16x32_bf16 v[80:83], v[92:95], v[60:63], v[80:83]
	ds_read_b64_tr_b16 v[86:87], v120
	ds_read_b64_tr_b16 v[94:95], v120 offset:1024
	ds_read_b64_tr_b16 v[92:93], v107 offset:1024
	v_mfma_f32_16x16x32_bf16 v[60:63], v[96:99], v[60:63], v[64:67]
	s_nop 2
	v_mul_f32_e64 v66, v104, v74
	v_mul_f32_e64 v67, v104, v75
	v_pk_mul_f32 v[64:65], v[104:105], v[72:73] op_sel_hi:[0,1]
	v_add_u32_e32 v99, s61, v142
	v_pk_mul_f32 v[74:75], v[104:105], v[78:79] op_sel_hi:[0,1]
	v_pk_mul_f32 v[72:73], v[104:105], v[76:77] op_sel_hi:[0,1]
	v_add_u32_e32 v98, s61, v141
	s_waitcnt lgkmcnt(0)
	v_mfma_f32_16x16x32_bf16 v[64:67], v[100:103], v[68:71], v[64:67]
	v_lshl_add_u32 v100, v138, 1, v99
	v_pk_mul_f32 v[78:79], v[104:105], v[82:83] op_sel_hi:[0,1]
	v_pk_mul_f32 v[76:77], v[104:105], v[80:81] op_sel_hi:[0,1]
	v_pk_mul_f32 v[62:63], v[104:105], v[62:63] op_sel_hi:[0,1]
	v_pk_mul_f32 v[60:61], v[104:105], v[60:61] op_sel_hi:[0,1]
	v_add_u32_e32 v104, v98, v135
	ds_read_b128 v[80:83], v0 offset:33792
	ds_read_b64_tr_b16 v[96:97], v104
	v_add_u32_e32 v105, v98, v2
	v_lshl_add_u32 v107, v143, 1, v99
	v_mfma_f32_16x16x32_bf16 v[72:75], v[84:87], v[68:71], v[72:75]
	ds_read_b64_tr_b16 v[98:99], v100
	ds_read_b64_tr_b16 v[84:85], v105
	ds_read_b64_tr_b16 v[102:103], v100 offset:1024
	ds_read_b64_tr_b16 v[100:101], v104 offset:1024
	v_mfma_f32_16x16x32_bf16 v[76:79], v[88:91], v[68:71], v[76:79]
	ds_read_b64_tr_b16 v[86:87], v107
	ds_read_b64_tr_b16 v[90:91], v107 offset:1024
	ds_read_b64_tr_b16 v[88:89], v105 offset:1024
	v_mfma_f32_16x16x32_bf16 v[60:63], v[92:95], v[68:71], v[60:63]
	v_add_u32_e32 v95, s61, v148
	v_add_u32_e32 v94, s61, v147
	s_waitcnt lgkmcnt(0)
	v_mfma_f32_16x16x32_bf16 v[64:67], v[96:99], v[80:83], v[64:67]
	v_lshl_add_u32 v96, v140, 1, v95
	v_add_u32_e32 v104, v94, v135
	ds_read_b128 v[68:71], v0 offset:34816
	ds_read_b64_tr_b16 v[92:93], v104
	v_add_u32_e32 v105, v94, v2
	v_lshl_add_u32 v107, v149, 1, v95
	v_mfma_f32_16x16x32_bf16 v[72:75], v[84:87], v[80:83], v[72:75]
	ds_read_b64_tr_b16 v[94:95], v96
	ds_read_b64_tr_b16 v[84:85], v105
	ds_read_b64_tr_b16 v[98:99], v96 offset:1024
	ds_read_b64_tr_b16 v[96:97], v104 offset:1024
	v_mfma_f32_16x16x32_bf16 v[76:79], v[100:103], v[80:83], v[76:79]
	ds_read_b64_tr_b16 v[86:87], v107
	ds_read_b64_tr_b16 v[102:103], v107 offset:1024
	ds_read_b64_tr_b16 v[100:101], v105 offset:1024
	v_mfma_f32_16x16x32_bf16 v[60:63], v[88:91], v[80:83], v[60:63]
	v_add_u32_e32 v90, s61, v151
	v_add_u32_e32 v91, s61, v152
	v_add_u32_e32 v104, v90, v135
	ds_read_b128 v[80:83], v0 offset:35840
	ds_read_b64_tr_b16 v[88:89], v104
	v_lshl_add_u32 v0, v145, 1, v91
	s_waitcnt lgkmcnt(0)
	v_mfma_f32_16x16x32_bf16 v[64:67], v[92:95], v[68:71], v[64:67]
	v_add_u32_e32 v2, v90, v2
	v_lshl_add_u32 v105, v153, 1, v91
	v_mfma_f32_16x16x32_bf16 v[72:75], v[84:87], v[68:71], v[72:75]
	ds_read_b64_tr_b16 v[90:91], v0
	ds_read_b64_tr_b16 v[84:85], v2
	ds_read_b64_tr_b16 v[94:95], v0 offset:1024
	ds_read_b64_tr_b16 v[92:93], v104 offset:1024
	v_mfma_f32_16x16x32_bf16 v[76:79], v[96:99], v[68:71], v[76:79]
	ds_read_b64_tr_b16 v[86:87], v105
	ds_read_b64_tr_b16 v[98:99], v105 offset:1024
	ds_read_b64_tr_b16 v[96:97], v2 offset:1024
	v_mfma_f32_16x16x32_bf16 v[60:63], v[100:103], v[68:71], v[60:63]
	s_waitcnt lgkmcnt(0)
; __device__ __forceinline__ float bflo(unsigned v) { return __uint_as_float(v << 16); }
; __device__ __forceinline__ float bfhi(unsigned v) { return __uint_as_float(v & 0xffff0000u); }
; __device__ __forceinline__ float siluf_(float x) { return x * __builtin_amdgcn_rcpf(1.0f + __expf(-x)); }
; #define SBAR __builtin_amdgcn_sched_barrier(0)
; #define LD_YD(dst, kk) do { dst[0] = ldsfrag(Bm, LW, l, (kk) * 32 + fq * 8); \
;         _Pragma("unroll") for (int p_ = 0; p_ < 4; ++p_) dst[1 + p_] = ldsfrag_tr(Xdt, LX, (kk) * 32, p_ * 16, lane); } while (0)
; #define MM_YD(srcf) _Pragma("unroll") for (int p_ = 0; p_ < 4; ++p_) acc_y[p_] = mfma16(srcf[1 + p_], srcf[0], acc_y[p_])
; #define SBAR __builtin_amdgcn_sched_barrier(0)
; __device__ void ssm_item(const Params& p, int layer, int b, int h) {
;     ...
;         LD_YD(d2, 2); MM_YD(d1); SBAR;
;         LD_YD(d3, 3); MM_YD(d2); SBAR;
;         MM_YD(d3); SBAR;
;       }
;     ...
; #pragma unroll
;       for (int pb = 0; pb < 4; ++pb) {
;         const int pc = pb * 16 + fq * 4;
;         const u32x2 xs = *(const u32x2*)(Xs + swz(l, pc, LX));
;         f32x4 y;
;         y[0] = (acc_y[pb][0] + bflo(xs.x) * dsk) * siluf_(bflo(zz[pb].x));
;         y[1] = (acc_y[pb][1] + bfhi(xs.x) * dsk) * siluf_(bfhi(zz[pb].x));
;         y[2] = (acc_y[pb][2] + bflo(xs.y) * dsk) * siluf_(bflo(zz[pb].y));
;         y[3] = (acc_y[pb][3] + bfhi(xs.y) * dsk) * siluf_(bfhi(zz[pb].y));
;         *(u32x2*)(zrow + pc) = pack4(y);
;       }
;     }
;     __syncthreads();
; #pragma unroll
;     for (int pb = 0; pb < 4; ++pb) *(u32x2*)(Sb + swz((pb * 16 + fr), w * 16 + fq * 4, LW)) = pack4(acc_s[pb]);
	v_mfma_f32_16x16x32_bf16 v[88:91], v[88:91], v[80:83], v[64:67]
	v_mfma_f32_16x16x32_bf16 v[68:71], v[84:87], v[80:83], v[72:75]
	v_mfma_f32_16x16x32_bf16 v[64:67], v[92:95], v[80:83], v[76:79]
	v_mfma_f32_16x16x32_bf16 v[60:63], v[96:99], v[80:83], v[60:63]
	v_lshl_add_u32 v0, v139, 1, s59
	v_lshlrev_b32_e32 v2, 1, v133
	v_lshlrev_b32_e32 v72, 1, v134
	s_waitcnt vmcnt(0)
	v_lshlrev_b32_e32 v74, 16, v118
	v_add3_u32 v2, v0, v2, v72
	v_mul_f32_e32 v0, 0xbfb8aa3b, v74
	v_exp_f32_e32 v0, v0
	ds_read_b64 v[72:73], v2
	s_add_u32 s44, s44, 0x80
	s_addc_u32 s45, s45, 0
	v_add_f32_e32 v0, 1.0, v0
	v_rcp_f32_e32 v0, v0
	s_waitcnt lgkmcnt(0)
	v_lshlrev_b32_e32 v75, 16, v72
	s_mov_b64 s[46:47], 0x8000
	v_mov_b64_e32 v[94:95], v[42:43]
	v_pk_mul_f32 v[74:75], v[0:1], v[74:75]
	v_mov_b64_e32 v[98:99], v[50:51]
	v_add_f32_e32 v0, v88, v75
	v_mul_f32_e32 v76, v74, v0
	v_and_b32_e32 v74, 0xffff0000, v118
	v_mul_f32_e32 v0, 0xbfb8aa3b, v74
	v_exp_f32_e32 v0, v0
	v_and_b32_e32 v75, 0xffff0000, v72
	v_and_b32_e32 v72, 0xffff0000, v119
	v_mov_b64_e32 v[86:87], v[34:35]
	v_add_f32_e32 v0, 1.0, v0
	v_rcp_f32_e32 v0, v0
	v_mov_b64_e32 v[82:83], v[22:23]
	v_lshl_add_u64 v[108:109], v[108:109], 0, s[46:47]
	s_cmpk_lg_i32 s44, 0x800
	v_pk_mul_f32 v[74:75], v[0:1], v[74:75]
	v_mov_b64_e32 v[92:93], v[40:41]
	v_add_f32_e32 v0, v89, v75
	v_mul_f32_e32 v77, v74, v0
	v_lshlrev_b32_e32 v74, 16, v119
	v_mul_f32_e32 v0, 0xbfb8aa3b, v74
	v_exp_f32_e32 v0, v0
	v_lshlrev_b32_e32 v75, 16, v73
	v_and_b32_e32 v73, 0xffff0000, v73
	v_mov_b64_e32 v[96:97], v[48:49]
	v_add_f32_e32 v0, 1.0, v0
	v_rcp_f32_e32 v0, v0
	v_mov_b64_e32 v[84:85], v[32:33]
	v_mov_b64_e32 v[80:81], v[20:21]
	s_mov_b32 s62, s48
	v_pk_mul_f32 v[74:75], v[0:1], v[74:75]
	s_nop 0
	v_add_f32_e32 v0, v90, v75
	v_mul_f32_e32 v74, v74, v0
	v_mul_f32_e32 v0, 0xbfb8aa3b, v72
	v_exp_f32_e32 v0, v0
	s_nop 0
	v_add_f32_e32 v0, 1.0, v0
	v_rcp_f32_e32 v0, v0
	s_nop 0
	v_pk_mul_f32 v[72:73], v[0:1], v[72:73]
	s_nop 0
	v_add_f32_e32 v0, v91, v73
	v_mul_f32_e32 v0, v72, v0
	v_cvt_pk_bf16_f32 v73, v74, v0
	v_or_b32_e32 v0, 16, v139
	v_bitop3_b32 v0, v0, v134, v133 bitop3:0x36
	v_cvt_pk_bf16_f32 v72, v76, v77
	global_store_dwordx2 v[110:111], v[72:73], off
	v_lshl_add_u32 v0, v0, 1, s59
	v_lshlrev_b32_e32 v74, 16, v116
	ds_read_b64 v[72:73], v0
	v_mul_f32_e32 v0, 0xbfb8aa3b, v74
	v_exp_f32_e32 v0, v0
	v_mov_b64_e32 v[90:91], v[30:31]
	v_mov_b64_e32 v[88:89], v[28:29]
	s_waitcnt lgkmcnt(0)
	v_lshlrev_b32_e32 v75, 16, v72
	v_add_f32_e32 v0, 1.0, v0
	v_rcp_f32_e32 v0, v0
	s_nop 0
	v_pk_mul_f32 v[74:75], v[0:1], v[74:75]
	s_nop 0
	v_add_f32_e32 v0, v68, v75
	v_mul_f32_e32 v76, v74, v0
	v_and_b32_e32 v74, 0xffff0000, v116
	v_mul_f32_e32 v0, 0xbfb8aa3b, v74
	v_exp_f32_e32 v0, v0
	v_and_b32_e32 v75, 0xffff0000, v72
	v_lshlrev_b32_e32 v68, 16, v117
	v_add_f32_e32 v0, 1.0, v0
	v_rcp_f32_e32 v0, v0
	s_nop 0
	v_pk_mul_f32 v[74:75], v[0:1], v[74:75]
	s_nop 0
	v_add_f32_e32 v0, v69, v75
	v_mul_f32_e32 v72, v74, v0
	v_mul_f32_e32 v0, 0xbfb8aa3b, v68
	v_exp_f32_e32 v0, v0
	v_lshlrev_b32_e32 v69, 16, v73
	v_add_f32_e32 v0, 1.0, v0
	v_rcp_f32_e32 v0, v0
	s_nop 0
	v_pk_mul_f32 v[68:69], v[0:1], v[68:69]
	s_nop 0
	v_add_f32_e32 v0, v70, v69
	v_mul_f32_e32 v70, v68, v0
	v_and_b32_e32 v68, 0xffff0000, v117
	v_mul_f32_e32 v0, 0xbfb8aa3b, v68
	v_exp_f32_e32 v0, v0
	v_and_b32_e32 v69, 0xffff0000, v73
	v_add_f32_e32 v0, 1.0, v0
	v_rcp_f32_e32 v0, v0
	s_nop 0
	v_pk_mul_f32 v[68:69], v[0:1], v[68:69]
	s_nop 0
	v_add_f32_e32 v0, v71, v69
	v_mul_f32_e32 v0, v68, v0
	v_cvt_pk_bf16_f32 v69, v70, v0
	v_lshlrev_b32_e32 v70, 16, v114
	v_mul_f32_e32 v0, 0xbfb8aa3b, v70
	v_exp_f32_e32 v0, v0
	v_cvt_pk_bf16_f32 v68, v76, v72
	global_store_dwordx2 v[110:111], v[68:69], off offset:32
	ds_read_b64 v[68:69], v2 offset:1024
	v_add_f32_e32 v0, 1.0, v0
	v_rcp_f32_e32 v0, v0
	v_mov_b64_e32 v[78:79], v[26:27]
	v_mov_b64_e32 v[74:75], v[14:15]
	s_waitcnt lgkmcnt(0)
	v_lshlrev_b32_e32 v71, 16, v68
	v_pk_mul_f32 v[70:71], v[0:1], v[70:71]
	v_mov_b64_e32 v[76:77], v[24:25]
	v_add_f32_e32 v0, v64, v71
	v_mul_f32_e32 v2, v70, v0
	v_and_b32_e32 v70, 0xffff0000, v114
	v_mul_f32_e32 v0, 0xbfb8aa3b, v70
	v_exp_f32_e32 v0, v0
	v_and_b32_e32 v71, 0xffff0000, v68
	v_lshlrev_b32_e32 v64, 16, v115
	v_mov_b64_e32 v[72:73], v[12:13]
	v_add_f32_e32 v0, 1.0, v0
	v_rcp_f32_e32 v0, v0
	s_nop 0
	v_pk_mul_f32 v[70:71], v[0:1], v[70:71]
	s_nop 0
	v_add_f32_e32 v0, v65, v71
	v_mul_f32_e32 v68, v70, v0
	v_mul_f32_e32 v0, 0xbfb8aa3b, v64
	v_exp_f32_e32 v0, v0
	v_lshlrev_b32_e32 v65, 16, v69
	v_add_f32_e32 v0, 1.0, v0
	v_rcp_f32_e32 v0, v0
	s_nop 0
	v_pk_mul_f32 v[64:65], v[0:1], v[64:65]
	s_nop 0
	v_add_f32_e32 v0, v66, v65
	v_mul_f32_e32 v66, v64, v0
	v_and_b32_e32 v64, 0xffff0000, v115
	v_mul_f32_e32 v0, 0xbfb8aa3b, v64
	v_exp_f32_e32 v0, v0
	v_and_b32_e32 v65, 0xffff0000, v69
	v_add_f32_e32 v0, 1.0, v0
	v_rcp_f32_e32 v0, v0
	s_nop 0
	v_pk_mul_f32 v[64:65], v[0:1], v[64:65]
	s_nop 0
	v_add_f32_e32 v0, v67, v65
	v_mul_f32_e32 v0, v64, v0
	v_cvt_pk_bf16_f32 v65, v66, v0
	v_bitop3_b32 v0, v139, 28, 16 bitop3:0xc8
	v_bitop3_b32 v0, v0, v134, v133 bitop3:0x36
	v_cvt_pk_bf16_f32 v64, v2, v68
	global_store_dwordx2 v[110:111], v[64:65], off offset:64
	v_lshl_add_u32 v0, v0, 1, s59
	v_lshlrev_b32_e32 v66, 16, v112
	ds_read_b64 v[64:65], v0 offset:1024
	v_mul_f32_e32 v0, 0xbfb8aa3b, v66
	v_exp_f32_e32 v0, v0
	v_mov_b64_e32 v[70:71], v[18:19]
	v_mov_b64_e32 v[68:69], v[16:17]
	s_waitcnt lgkmcnt(0)
	v_lshlrev_b32_e32 v67, 16, v64
	v_add_f32_e32 v0, 1.0, v0
	v_rcp_f32_e32 v0, v0
	s_nop 0
	v_pk_mul_f32 v[66:67], v[0:1], v[66:67]
	s_nop 0
	v_add_f32_e32 v0, v60, v67
	v_mul_f32_e32 v2, v66, v0
	v_and_b32_e32 v66, 0xffff0000, v112
	v_mul_f32_e32 v0, 0xbfb8aa3b, v66
	v_exp_f32_e32 v0, v0
	v_and_b32_e32 v67, 0xffff0000, v64
	v_lshlrev_b32_e32 v60, 16, v113
	v_add_f32_e32 v0, 1.0, v0
	v_rcp_f32_e32 v0, v0
	s_nop 0
	v_pk_mul_f32 v[66:67], v[0:1], v[66:67]
	s_nop 0
	v_add_f32_e32 v0, v61, v67
	v_mul_f32_e32 v64, v66, v0
	v_mul_f32_e32 v0, 0xbfb8aa3b, v60
	v_exp_f32_e32 v0, v0
	v_lshlrev_b32_e32 v61, 16, v65
	v_add_f32_e32 v0, 1.0, v0
	v_rcp_f32_e32 v0, v0
	s_nop 0
	v_pk_mul_f32 v[60:61], v[0:1], v[60:61]
	s_nop 0
	v_add_f32_e32 v0, v62, v61
	v_mul_f32_e32 v62, v60, v0
	v_and_b32_e32 v60, 0xffff0000, v113
	v_mul_f32_e32 v0, 0xbfb8aa3b, v60
	v_exp_f32_e32 v0, v0
	v_and_b32_e32 v61, 0xffff0000, v65
	v_add_f32_e32 v0, 1.0, v0
	v_rcp_f32_e32 v0, v0
	s_nop 0
	v_pk_mul_f32 v[60:61], v[0:1], v[60:61]
	s_nop 0
	v_add_f32_e32 v0, v63, v61
	v_mul_f32_e32 v0, v60, v0
	v_cvt_pk_bf16_f32 v60, v2, v64
	v_cvt_pk_bf16_f32 v61, v62, v0
	v_bitop3_b32 v0, v106, v132, s57 bitop3:0x36
	global_store_dwordx2 v[110:111], v[60:61], off offset:96
	v_lshl_add_u32 v0, v0, 1, s60
	v_cvt_pk_bf16_f32 v60, v36, v37
	v_cvt_pk_bf16_f32 v61, v38, v39
	v_cvt_pk_bf16_f32 v62, v56, v57
	v_cvt_pk_bf16_f32 v63, v58, v59
	s_waitcnt lgkmcnt(0)
	s_barrier
; __device__ void ssm_item(const Params& p, int layer, int b, int h) {
;     ...
; #pragma unroll
;     for (int rep = 0; rep < 4; ++rep) {
;       const int idx = tid + rep * 512, row = idx >> 4, seg = idx & 15;
;       *(u32x4*)(Bm + swz(row, seg * 8, LW)) = pfB[rep];
;       *(u32x4*)(Cm + swz(row, seg * 8, LW)) = pfC[rep];
;     }
; #pragma unroll
;     for (int rep = 0; rep < 2; ++rep) {
;       const int idx = tid + rep * 512, row = idx >> 3, seg = idx & 7;
;       float f[8];
;       unpack8(pfX[rep], f);
;       const float dt = s_dt[row], dd = dt * s_dec[row];
;       u32x4 a, d;
;       a.x = pack2(f[0] * dt, f[1] * dt); a.y = pack2(f[2] * dt, f[3] * dt); a.z = pack2(f[4] * dt, f[5] * dt); a.w = pack2(f[6] * dt, f[7] * dt);
;       d.x = pack2(f[0] * dd, f[1] * dd); d.y = pack2(f[2] * dd, f[3] * dd); d.z = pack2(f[4] * dd, f[5] * dd); d.w = pack2(f[6] * dd, f[7] * dd);
;       *(u32x4*)(Xs + swz(row, seg * 8, LX)) = pfX[rep];
;       *(u32x4*)(Xdt + swz(row, seg * 8, LX)) = a;
;       *(u32x4*)(Xdd + swz(row, seg * 8, LX)) = d;
;     }
;     __syncthreads();
;     ...
;     for (int pb = 0; pb < 4; ++pb) *(u32x2*)(Sb + swz((pb * 16 + fr), w * 16 + fq * 4, LW)) = pack4(acc_s[pb]);
	ds_write2st64_b64 v0, v[60:61], v[62:63] offset1:8
	v_cvt_pk_bf16_f32 v60, v44, v45
	v_cvt_pk_bf16_f32 v61, v46, v47
	v_cvt_pk_bf16_f32 v62, v52, v53
	v_cvt_pk_bf16_f32 v63, v54, v55
	ds_write2st64_b64 v0, v[60:61], v[62:63] offset0:16 offset1:24
	v_mov_b64_e32 v[62:63], v[10:11]
	v_mov_b64_e32 v[66:67], v[6:7]
	v_mov_b64_e32 v[60:61], v[8:9]
	v_mov_b64_e32 v[64:65], v[4:5]
	s_cbranch_scc0 .LBB0_379
.LBB0_393:
	v_mov_b32_e32 v122, v126
	s_bitcmp1_b32 s62, 0
	v_ashrrev_i32_e32 v110, 4, v122
	v_lshlrev_b32_e32 v0, 3, v122
	v_lshlrev_b32_e32 v5, 5, v110
	v_lshlrev_b32_e32 v6, 1, v110
	v_and_b32_e32 v12, 24, v0
	v_and_b32_e32 v5, 0x1e0, v5
	v_and_b32_e32 v6, 16, v6
	v_bfe_u32 v2, v0, 5, 2
	v_lshrrev_b32_e32 v4, 2, v110
	v_bitop3_b32 v5, v5, v6, v12 bitop3:0x36
	v_add_u32_e32 v13, 0x200, v122
	v_and_or_b32 v4, v4, s80, v2
	v_lshlrev_b32_e32 v5, 1, v5
	v_ashrrev_i32_e32 v106, 4, v13
	v_lshl_or_b32 v4, v4, 10, v5
	v_lshlrev_b32_e32 v5, 5, v106
	v_lshlrev_b32_e32 v6, 1, v106
	v_add_u32_e32 v4, 0, v4
	v_and_b32_e32 v5, 0x1e0, v5
	v_and_b32_e32 v6, 16, v6
	s_waitcnt vmcnt(0)
	ds_write_b128 v4, v[60:63] offset:32768
	ds_write_b128 v4, v[64:67]
	v_lshrrev_b32_e32 v4, 2, v106
	v_bitop3_b32 v5, v5, v6, v12 bitop3:0x36
	v_and_or_b32 v4, v4, s80, v2
	v_lshlrev_b32_e32 v5, 1, v5
	v_lshl_or_b32 v4, v4, 10, v5
	v_add_u32_e32 v4, 0, v4
	ds_write_b128 v4, v[68:71] offset:32768
	ds_write_b128 v4, v[72:75]
	v_add_u32_e32 v4, 0x400, v122
	v_ashrrev_i32_e32 v104, 4, v4
	v_lshlrev_b32_e32 v5, 5, v104
	v_lshlrev_b32_e32 v6, 1, v104
	v_and_b32_e32 v5, 0x1e0, v5
	v_and_b32_e32 v6, 16, v6
	v_lshrrev_b32_e32 v4, 2, v104
	v_bitop3_b32 v5, v5, v6, v12 bitop3:0x36
	v_and_or_b32 v4, v4, s80, v2
	v_lshlrev_b32_e32 v5, 1, v5
	v_lshl_or_b32 v4, v4, 10, v5
	v_add_u32_e32 v4, 0, v4
	ds_write_b128 v4, v[76:79] offset:32768
	ds_write_b128 v4, v[80:83]
	v_add_u32_e32 v4, 0x600, v122
	v_ashrrev_i32_e32 v102, 4, v4
	v_lshrrev_b32_e32 v4, 2, v102
	v_and_or_b32 v2, v4, s80, v2
	v_lshlrev_b32_e32 v4, 5, v102
	v_lshlrev_b32_e32 v5, 1, v102
	v_and_b32_e32 v4, 0x1e0, v4
	v_and_b32_e32 v5, 16, v5
	v_bitop3_b32 v4, v4, v5, v12 bitop3:0x36
	s_cselect_b32 s46, 0x600, 0
	v_lshlrev_b32_e32 v4, 1, v4
	s_add_i32 s63, s46, 0
	v_lshl_or_b32 v2, v2, 10, v4
	s_add_i32 s63, s63, 0x20000
	v_add_u32_e32 v2, 0, v2
	v_ashrrev_i32_e32 v100, 3, v122
	ds_write_b128 v2, v[84:87] offset:32768
	ds_write_b128 v2, v[88:91]
	v_lshl_add_u32 v4, v100, 2, s63
	ds_read2st64_b32 v[8:9], v4 offset1:4
	v_lshlrev_b32_e32 v10, 16, v92
	v_and_b32_e32 v11, 0xffff0000, v92
	v_lshlrev_b32_e32 v14, 16, v93
	v_and_b32_e32 v15, 0xffff0000, v93
	s_waitcnt lgkmcnt(0)
	v_mul_f32_e32 v4, v8, v10
	v_mul_f32_e32 v5, v8, v11
	v_lshlrev_b32_e32 v16, 16, v94
	v_and_b32_e32 v17, 0xffff0000, v94
	v_cvt_pk_bf16_f32 v4, v4, v5
	v_mul_f32_e32 v5, v8, v14
	v_mul_f32_e32 v6, v8, v15
	v_lshlrev_b32_e32 v18, 16, v95
	v_and_b32_e32 v19, 0xffff0000, v95
	v_cvt_pk_bf16_f32 v5, v5, v6
	v_mul_f32_e32 v6, v8, v16
	v_mul_f32_e32 v7, v8, v17
	v_mul_f32_e32 v20, v8, v9
	v_cvt_pk_bf16_f32 v6, v6, v7
	v_mul_f32_e32 v7, v8, v18
	v_mul_f32_e32 v8, v8, v19
	v_cvt_pk_bf16_f32 v7, v7, v8
	v_mul_f32_e32 v8, v20, v10
	v_mul_f32_e32 v9, v20, v11
	v_cvt_pk_bf16_f32 v8, v8, v9
	v_mul_f32_e32 v9, v20, v14
	v_mul_f32_e32 v10, v20, v15
	v_cvt_pk_bf16_f32 v9, v9, v10
	v_mul_f32_e32 v10, v20, v16
	v_mul_f32_e32 v11, v20, v17
	v_lshlrev_b32_e32 v15, 5, v100
	v_lshlrev_b32_e32 v16, 1, v100
	v_cvt_pk_bf16_f32 v10, v10, v11
	v_mul_f32_e32 v11, v20, v18
	v_mul_f32_e32 v14, v20, v19
	v_and_b32_e32 v15, 0x1e0, v15
	v_and_b32_e32 v16, 16, v16
	v_bfe_u32 v2, v0, 5, 1
	v_cvt_pk_bf16_f32 v11, v11, v14
	v_lshrrev_b32_e32 v14, 3, v100
	v_bitop3_b32 v15, v15, v16, v12 bitop3:0x36
	v_and_or_b32 v14, v14, s81, v2
	v_lshlrev_b32_e32 v15, 1, v15
	v_lshl_or_b32 v14, v14, 10, v15
	s_add_i32 s46, 0, 0x10000
	v_add_u32_e32 v15, s46, v14
	s_add_i32 s61, 0, 0x14000
	ds_write_b128 v15, v[92:95]
	v_add_u32_e32 v15, s61, v14
	s_add_i32 s64, 0, 0x18000
	ds_write_b128 v15, v[4:7]
	v_add_u32_e32 v4, s64, v14
	v_ashrrev_i32_e32 v112, 3, v13
	ds_write_b128 v4, v[8:11]
	v_lshl_add_u32 v4, v112, 2, s63
	ds_read2st64_b32 v[8:9], v4 offset1:4
	v_lshlrev_b32_e32 v10, 16, v96
	v_and_b32_e32 v11, 0xffff0000, v96
	v_lshlrev_b32_e32 v13, 16, v97
	v_and_b32_e32 v14, 0xffff0000, v97
	s_waitcnt lgkmcnt(0)
	v_mul_f32_e32 v4, v8, v10
	v_mul_f32_e32 v5, v8, v11
	v_lshlrev_b32_e32 v15, 16, v98
	v_and_b32_e32 v16, 0xffff0000, v98
	v_cvt_pk_bf16_f32 v4, v4, v5
	v_mul_f32_e32 v5, v8, v13
	v_mul_f32_e32 v6, v8, v14
	v_lshlrev_b32_e32 v17, 16, v99
	v_and_b32_e32 v18, 0xffff0000, v99
	v_cvt_pk_bf16_f32 v5, v5, v6
	v_mul_f32_e32 v6, v8, v15
	v_mul_f32_e32 v7, v8, v16
	v_mul_f32_e32 v19, v8, v9
	v_cvt_pk_bf16_f32 v6, v6, v7
	v_mul_f32_e32 v7, v8, v17
	v_mul_f32_e32 v8, v8, v18
	v_cvt_pk_bf16_f32 v7, v7, v8
	v_mul_f32_e32 v8, v19, v10
	v_mul_f32_e32 v9, v19, v11
	v_cvt_pk_bf16_f32 v8, v8, v9
	v_mul_f32_e32 v9, v19, v13
	v_mul_f32_e32 v10, v19, v14
	v_cvt_pk_bf16_f32 v9, v9, v10
	v_mul_f32_e32 v10, v19, v15
	v_mul_f32_e32 v11, v19, v16
	v_cvt_pk_bf16_f32 v10, v10, v11
	v_mul_f32_e32 v11, v19, v17
	v_mul_f32_e32 v13, v19, v18
	v_cvt_pk_bf16_f32 v11, v11, v13
	v_lshrrev_b32_e32 v13, 3, v112
	v_and_or_b32 v2, v13, s81, v2
	v_lshlrev_b32_e32 v13, 5, v112
	v_lshlrev_b32_e32 v14, 1, v112
	v_and_b32_e32 v13, 0x1e0, v13
	v_and_b32_e32 v14, 16, v14
	v_bitop3_b32 v12, v13, v14, v12 bitop3:0x36
	v_lshlrev_b32_e32 v12, 1, v12
	v_lshl_or_b32 v2, v2, 10, v12
	v_add_u32_e32 v12, s46, v2
	s_cmpk_eq_i32 s44, 0x780
	ds_write_b128 v12, v[96:99]
	v_add_u32_e32 v12, s61, v2
	v_add_u32_e32 v2, s64, v2
	s_cselect_b64 s[46:47], -1, 0
	s_cmpk_lg_i32 s44, 0x780
	s_mov_b64 s[54:55], -1
	ds_write_b128 v12, v[4:7]
	ds_write_b128 v2, v[8:11]
	s_waitcnt lgkmcnt(0)
	s_barrier
; __device__ void ssm_item(const Params& p, int layer, int b, int h) {
;     ...
;     if (ch + 1 < SEQ / 128) {
; #pragma unroll
;       for (int rep = 0; rep < 4; ++rep) {
;         const int idx = tid + rep * 512, row = idx >> 4, seg = idx & 15;
;         const bf16_t* rp = bcconv + (rbase + 128 + row) * 1024 + g * 128 + seg * 8;
;         pfB[rep] = *(const u32x4*)rp;
;         pfC[rep] = *(const u32x4*)(rp + 512);
;       }
; #pragma unroll
;       for (int rep = 0; rep < 2; ++rep) {
;         const int idx = tid + rep * 512, row = idx >> 3, seg = idx & 7;
;         pfX[rep] = *(const u32x4*)(xconv + (rbase + 128 + row) * DM + h * 64 + seg * 8);
;       }
;     }
	s_cbranch_scc0 .LBB0_395
	s_add_u32 s48, s0, s44
	v_and_b32_e32 v2, 0x78, v0
	v_ashrrev_i32_e32 v111, 31, v110
	s_addc_u32 s49, s1, s45
	v_lshlrev_b32_e32 v2, 1, v2
	v_lshl_add_u64 v[4:5], s[48:49], 0, v[110:111]
	v_lshl_add_u64 v[28:29], s[4:5], 0, v[2:3]
	v_lshlrev_b64 v[4:5], 11, v[4:5]
	v_ashrrev_i32_e32 v107, 31, v106
	v_lshl_add_u64 v[4:5], v[28:29], 0, v[4:5]
	s_mov_b64 s[54:55], 0x40000
	v_lshl_add_u64 v[12:13], s[48:49], 0, v[106:107]
	v_lshl_add_u64 v[6:7], v[4:5], 0, s[54:55]
	v_add_co_u32_e32 v4, vcc, s82, v4
	v_lshlrev_b64 v[12:13], 11, v[12:13]
	v_ashrrev_i32_e32 v105, 31, v104
	v_addc_co_u32_e32 v5, vcc, 0, v5, vcc
	v_lshl_add_u64 v[12:13], v[28:29], 0, v[12:13]
	v_lshl_add_u64 v[20:21], s[48:49], 0, v[104:105]
	v_lshl_add_u64 v[14:15], v[12:13], 0, s[54:55]
	v_add_co_u32_e32 v12, vcc, s82, v12
	v_lshlrev_b64 v[20:21], 11, v[20:21]
	v_ashrrev_i32_e32 v103, 31, v102
	v_addc_co_u32_e32 v13, vcc, 0, v13, vcc
	v_lshl_add_u64 v[20:21], v[28:29], 0, v[20:21]
	v_lshl_add_u64 v[30:31], s[48:49], 0, v[102:103]
	v_lshl_add_u64 v[22:23], v[20:21], 0, s[54:55]
	v_add_co_u32_e32 v20, vcc, s82, v20
	v_lshlrev_b64 v[30:31], 11, v[30:31]
	v_and_b32_e32 v0, 56, v0
	v_ashrrev_i32_e32 v101, 31, v100
	v_addc_co_u32_e32 v21, vcc, 0, v21, vcc
	v_lshl_add_u64 v[28:29], v[28:29], 0, v[30:31]
	v_lshlrev_b32_e32 v2, 1, v0
	v_lshl_add_u64 v[42:43], s[48:49], 0, v[100:101]
	v_lshl_add_u64 v[30:31], v[28:29], 0, s[54:55]
	v_add_co_u32_e32 v28, vcc, s82, v28
	v_lshl_add_u64 v[40:41], s[6:7], 0, v[2:3]
	v_lshlrev_b64 v[42:43], 12, v[42:43]
	v_ashrrev_i32_e32 v113, 31, v112
	v_addc_co_u32_e32 v29, vcc, 0, v29, vcc
	v_lshl_add_u64 v[42:43], v[40:41], 0, v[42:43]
	v_lshl_add_u64 v[48:49], s[48:49], 0, v[112:113]
	v_add_co_u32_e32 v42, vcc, s83, v42
	v_lshlrev_b64 v[48:49], 12, v[48:49]
	s_nop 0
	v_addc_co_u32_e32 v43, vcc, 0, v43, vcc
	v_lshl_add_u64 v[40:41], v[40:41], 0, v[48:49]
	v_add_co_u32_e32 v48, vcc, 0x80000, v40
	global_load_dwordx4 v[8:11], v[4:5], off
	s_nop 0
	global_load_dwordx4 v[4:7], v[6:7], off offset:1024
	v_addc_co_u32_e32 v49, vcc, 0, v41, vcc
	global_load_dwordx4 v[16:19], v[12:13], off
	s_nop 0
	global_load_dwordx4 v[12:15], v[14:15], off offset:1024
	s_nop 0
	global_load_dwordx4 v[24:27], v[20:21], off
	s_nop 0
	global_load_dwordx4 v[20:23], v[22:23], off offset:1024
	s_nop 0
	global_load_dwordx4 v[32:35], v[28:29], off
	s_nop 0
	global_load_dwordx4 v[28:31], v[30:31], off offset:1024
	s_nop 0
	global_load_dwordx4 v[40:43], v[42:43], off
	s_nop 0
	global_load_dwordx4 v[48:51], v[48:49], off
	s_mov_b64 s[54:55], 0

; __device__ __forceinline__ size_t pidx(size_t row, int col) { return ((size_t)(col >> 8) * MTOK + row) * PLD + (col & 255); }
; #define SBAR __builtin_amdgcn_sched_barrier(0)
; #define LD_CB(dst, kk) _Pragma("unroll") for (int i_ = 0; i_ < 8; ++i_) dst[i_] = ldsfrag(Bm, LW, i_ * 16 + fr, (kk) * 32 + fq * 8)
; #define MM_CB(srcf, kk) _Pragma("unroll") for (int i_ = 0; i_ < 8; ++i_) acc_cb[i_] = mfma16(srcf[i_], cfr[kk], acc_cb[i_])
; #define LD_SU(dst, kk) do { dst[0] = ldsfrag_tr(Bm, LW, (kk) * 32, w * 16, lane); \
;       _Pragma("unroll") for (int p_ = 0; p_ < 4; ++p_) dst[1 + p_] = ldsfrag_tr(Xdd, LX, (kk) * 32, p_ * 16, lane); } while (0)
; #define SBAR __builtin_amdgcn_sched_barrier(0)
; __device__ void ssm_item(const Params& p, int layer, int b, int h) {
;     ...
;     const int l = w * 16 + fr;
;     bf16_t* zrow = proj + pidx(rbase + l, SZ + h * 64);
;     u32x2 zz[4];
; #pragma unroll
;     for (int pb = 0; pb < 4; ++pb) zz[pb] = *(const u32x2*)(zrow + pb * 16 + fq * 4);
;     f32x4 acc_cb[8];
; #pragma unroll
;     for (int sb = 0; sb < 8; ++sb) acc_cb[sb] = (f32x4){0.f, 0.f, 0.f, 0.f};
;     bf16x8 cfr[4];
; #pragma unroll
;     for (int kk = 0; kk < 4; ++kk) cfr[kk] = ldsfrag(Cm, LW, w * 16 + fr, kk * 32 + fq * 8);
;     ...
;     {
;       const float el = __expf(s_acs[127]);
; #pragma unroll
;       for (int pb = 0; pb < 4; ++pb) acc_s[pb] *= el;
;       bf16x8 c0[8], c1[8], c2[8], c3[8], t0[5], t1[5], t2[5], t3[5];
;       LD_CB(c0, 0); SBAR;
;       LD_CB(c1, 1); MM_CB(c0, 0); SBAR;
;       LD_CB(c2, 2); MM_CB(c1, 1); SBAR;
;       LD_CB(c3, 3); MM_CB(c2, 2); SBAR;
;       LD_SU(t0, 0); MM_CB(c3, 3); SBAR;
.LBB0_397:
	v_and_b32_e32 v136, 15, v122
	v_or_b32_e32 v120, s51, v136
	v_ashrrev_i32_e32 v121, 31, v120
	v_lshl_add_u64 v[60:61], s[48:49], 0, v[120:121]
	v_lshlrev_b64 v[60:61], 9, v[60:61]
	v_bfe_u32 v124, v122, 4, 2
	v_lshl_add_u64 v[60:61], s[8:9], 0, v[60:61]
	v_lshl_add_u64 v[60:61], v[60:61], 0, s[72:73]
	v_lshlrev_b32_e32 v2, 3, v124
	v_lshl_add_u64 v[60:61], v[60:61], 0, v[2:3]
	s_mov_b64 s[48:49], 0x1cc80000
	v_lshl_add_u64 v[110:111], v[60:61], 0, s[48:49]
	v_add_co_u32_e32 v60, vcc, s84, v60
	v_lshlrev_b32_e32 v0, 1, v120
	s_nop 0
	v_addc_co_u32_e32 v61, vcc, 0, v61, vcc
	global_load_dwordx2 v[118:119], v[60:61], off
	global_load_dwordx2 v[116:117], v[110:111], off offset:32
	global_load_dwordx2 v[114:115], v[110:111], off offset:64
	global_load_dwordx2 v[112:113], v[110:111], off offset:96
	v_mov_b32_e32 v60, s63
	ds_read_b32 v60, v60 offset:1020
	v_lshlrev_b32_e32 v61, 1, v122
	v_lshlrev_b32_e32 v133, 5, v136
	v_and_b32_e32 v134, 16, v0
	v_and_b32_e32 v132, 16, v61
	v_bitop3_b32 v0, v2, v134, v133 bitop3:0x36
	v_bitop3_b32 v2, v2, v132, v133 bitop3:0x36
	v_lshl_add_u32 v0, v0, 1, s56
	v_lshl_add_u32 v137, v2, 1, 0
	ds_read_b128 v[76:79], v137 offset:32768
	s_waitcnt lgkmcnt(0)
	v_mul_f32_e32 v2, 0x3fb8aa3b, v60
	ds_read_b128 v[72:75], v0
	ds_read_b128 v[68:71], v0 offset:1024
	ds_read_b128 v[64:67], v0 offset:2048
	ds_read_b128 v[60:63], v0 offset:3072
	ds_read_b128 v[80:83], v137 offset:36864
	ds_read_b128 v[84:87], v137 offset:40960
	ds_read_b128 v[88:91], v137 offset:45056
	ds_read_b128 v[92:95], v137 offset:49152
	ds_read_b128 v[96:99], v137 offset:53248
	ds_read_b128 v[100:103], v137 offset:57344
	ds_read_b128 v[104:107], v137 offset:61440
	v_exp_f32_e32 v2, v2
	s_add_i32 s48, s62, 1
	v_pk_mul_f32 v[38:39], v[38:39], v[2:3] op_sel_hi:[1,0]
	v_pk_mul_f32 v[36:37], v[36:37], v[2:3] op_sel_hi:[1,0]
	v_pk_mul_f32 v[58:59], v[58:59], v[2:3] op_sel_hi:[1,0]
	v_pk_mul_f32 v[56:57], v[56:57], v[2:3] op_sel_hi:[1,0]
	v_pk_mul_f32 v[46:47], v[46:47], v[2:3] op_sel_hi:[1,0]
	v_pk_mul_f32 v[44:45], v[44:45], v[2:3] op_sel_hi:[1,0]
	v_pk_mul_f32 v[54:55], v[54:55], v[2:3] op_sel_hi:[1,0]
	v_pk_mul_f32 v[52:53], v[52:53], v[2:3] op_sel_hi:[1,0]
	ds_read_b128 v[138:141], v137 offset:33792
	ds_read_b128 v[142:145], v137 offset:37888
	ds_read_b128 v[146:149], v137 offset:41984
	ds_read_b128 v[150:153], v137 offset:46080
	ds_read_b128 v[154:157], v137 offset:50176
	ds_read_b128 v[158:161], v137 offset:54272
	ds_read_b128 v[168:171], v137 offset:58368
	ds_read_b128 v[172:175], v137 offset:62464
	s_waitcnt lgkmcnt(0)
	v_mfma_f32_16x16x32_bf16 v[76:79], v[76:79], v[72:75], 0
	v_mfma_f32_16x16x32_bf16 v[80:83], v[80:83], v[72:75], 0
	v_mfma_f32_16x16x32_bf16 v[84:87], v[84:87], v[72:75], 0
	v_mfma_f32_16x16x32_bf16 v[88:91], v[88:91], v[72:75], 0
	v_mfma_f32_16x16x32_bf16 v[92:95], v[92:95], v[72:75], 0
	v_mfma_f32_16x16x32_bf16 v[96:99], v[96:99], v[72:75], 0
	v_mfma_f32_16x16x32_bf16 v[100:103], v[100:103], v[72:75], 0
	v_mfma_f32_16x16x32_bf16 v[104:107], v[104:107], v[72:75], 0
	v_mfma_f32_16x16x32_bf16 v[76:79], v[138:141], v[68:71], v[76:79]
	v_mfma_f32_16x16x32_bf16 v[80:83], v[142:145], v[68:71], v[80:83]
	v_mfma_f32_16x16x32_bf16 v[84:87], v[146:149], v[68:71], v[84:87]
	v_mfma_f32_16x16x32_bf16 v[88:91], v[150:153], v[68:71], v[88:91]
	ds_read_b128 v[138:141], v137 offset:34816
	ds_read_b128 v[142:145], v137 offset:38912
	ds_read_b128 v[146:149], v137 offset:43008
	ds_read_b128 v[150:153], v137 offset:47104
	v_mfma_f32_16x16x32_bf16 v[92:95], v[154:157], v[68:71], v[92:95]
	v_mfma_f32_16x16x32_bf16 v[96:99], v[158:161], v[68:71], v[96:99]
	v_mfma_f32_16x16x32_bf16 v[100:103], v[168:171], v[68:71], v[100:103]
	ds_read_b128 v[154:157], v137 offset:51200
	ds_read_b128 v[158:161], v137 offset:55296
	ds_read_b128 v[168:171], v137 offset:59392
	ds_read_b128 v[176:179], v137 offset:63488
	v_mfma_f32_16x16x32_bf16 v[104:107], v[172:175], v[68:71], v[104:107]
	s_waitcnt lgkmcnt(0)
	v_mfma_f32_16x16x32_bf16 v[76:79], v[138:141], v[64:67], v[76:79]
	v_mfma_f32_16x16x32_bf16 v[80:83], v[142:145], v[64:67], v[80:83]
	v_mfma_f32_16x16x32_bf16 v[84:87], v[146:149], v[64:67], v[84:87]
	v_mfma_f32_16x16x32_bf16 v[88:91], v[150:153], v[64:67], v[88:91]
	v_mfma_f32_16x16x32_bf16 v[138:141], v[154:157], v[64:67], v[92:95]
	v_mfma_f32_16x16x32_bf16 v[146:149], v[158:161], v[64:67], v[96:99]
	s_nop 1
	ds_read_b128 v[92:95], v137 offset:35840
	ds_read_b128 v[96:99], v137 offset:39936
	ds_read_b128 v[142:145], v137 offset:44032
	ds_read_b128 v[152:155], v137 offset:48128
	v_mfma_f32_16x16x32_bf16 v[156:159], v[168:171], v[64:67], v[100:103]
	ds_read_b128 v[160:163], v137 offset:52224
	ds_read_b128 v[168:171], v137 offset:56320
	ds_read_b128 v[172:175], v137 offset:60416
	ds_read_b128 v[180:183], v137 offset:64512
	v_mfma_f32_16x16x32_bf16 v[176:179], v[176:179], v[64:67], v[104:107]
	v_lshrrev_b32_e32 v100, 1, v122
	v_lshrrev_b32_e32 v2, 2, v122
	v_and_b32_e32 v101, 24, v100
	v_and_or_b32 v121, v2, 3, v101
	v_lshlrev_b32_e32 v2, 2, v122
	v_and_b32_e32 v2, 12, v2
	v_bfe_u32 v123, v100, 4, 1
	v_lshlrev_b32_e32 v100, 5, v121
	v_and_b32_e32 v125, 0x160, v100
	v_or_b32_e32 v151, s57, v2
	v_and_b32_e32 v122, 16, v122
	v_bitop3_b32 v100, v125, v122, v151 bitop3:0x36
	s_waitcnt lgkmcnt(0)
; #define SBAR __builtin_amdgcn_sched_barrier(0)
; #define LD_CB(dst, kk) _Pragma("unroll") for (int i_ = 0; i_ < 8; ++i_) dst[i_] = ldsfrag(Bm, LW, i_ * 16 + fr, (kk) * 32 + fq * 8)
; #define MM_CB(srcf, kk) _Pragma("unroll") for (int i_ = 0; i_ < 8; ++i_) acc_cb[i_] = mfma16(srcf[i_], cfr[kk], acc_cb[i_])
; #define LD_SU(dst, kk) do { dst[0] = ldsfrag_tr(Bm, LW, (kk) * 32, w * 16, lane); \
;       _Pragma("unroll") for (int p_ = 0; p_ < 4; ++p_) dst[1 + p_] = ldsfrag_tr(Xdd, LX, (kk) * 32, p_ * 16, lane); } while (0)
; #define MM_SU(srcf) _Pragma("unroll") for (int p_ = 0; p_ < 4; ++p_) acc_s[p_] = mfma16(srcf[0], srcf[1 + p_], acc_s[p_])
; #define SBAR __builtin_amdgcn_sched_barrier(0)
; __device__ void ssm_item(const Params& p, int layer, int b, int h) {
;     ...
;     {
;       const float el = __expf(s_acs[127]);
; #pragma unroll
;       for (int pb = 0; pb < 4; ++pb) acc_s[pb] *= el;
;       bf16x8 c0[8], c1[8], c2[8], c3[8], t0[5], t1[5], t2[5], t3[5];
;       LD_CB(c0, 0); SBAR;
;       LD_CB(c1, 1); MM_CB(c0, 0); SBAR;
;       LD_CB(c2, 2); MM_CB(c1, 1); SBAR;
;       LD_CB(c3, 3); MM_CB(c2, 2); SBAR;
;       LD_SU(t0, 0); MM_CB(c3, 3); SBAR;
;       LD_SU(t1, 1); MM_SU(t0); SBAR;
;       LD_SU(t2, 2); MM_SU(t1); SBAR;
;       LD_SU(t3, 3); MM_SU(t2); SBAR;
;       MM_SU(t3); SBAR;
	v_mfma_f32_16x16x32_bf16 v[104:107], v[92:95], v[60:63], v[76:79]
	v_lshl_add_u32 v101, v123, 12, s58
	v_lshlrev_b32_e32 v167, 1, v100
	v_or_b32_e32 v188, v122, v2
	v_or_b32_e32 v76, 0x80, v125
	v_bitop3_b32 v77, v76, v122, v151 bitop3:0x36
	v_mfma_f32_16x16x32_bf16 v[92:95], v[152:155], v[60:63], v[88:91]
	v_add_u32_e32 v184, v101, v167
	v_lshl_add_u32 v77, v77, 1, v101
	v_lshlrev_b32_e32 v150, 11, v123
	v_mfma_f32_16x16x32_bf16 v[88:91], v[160:163], v[60:63], v[138:141]
	v_add_u32_e32 v78, s64, v150
	s_nop 1
	v_or_b32_e32 v139, 16, v2
	v_mfma_f32_16x16x32_bf16 v[100:103], v[96:99], v[60:63], v[80:83]
	v_bitop3_b32 v2, v125, v122, v139 bitop3:0x36
	v_lshlrev_b32_e32 v2, 1, v2
	v_mfma_f32_16x16x32_bf16 v[96:99], v[142:145], v[60:63], v[84:87]
	v_or_b32_e32 v144, v188, v125
	v_lshlrev_b32_e32 v135, 1, v144
	v_add_u32_e32 v79, v78, v135
	ds_read_b64_tr_b16 v[152:153], v184 offset:32768
	ds_read_b64_tr_b16 v[154:155], v77 offset:32768
	ds_read_b64_tr_b16 v[184:185], v79
	ds_read_b64_tr_b16 v[186:187], v79 offset:256
	v_mfma_f32_16x16x32_bf16 v[84:87], v[168:171], v[60:63], v[146:149]
	v_add_u32_e32 v77, v78, v2
	s_nop 1
	v_bitop3_b32 v146, v76, v122, v139 bitop3:0x36
	v_lshl_add_u32 v76, v146, 1, v78
	v_mfma_f32_16x16x32_bf16 v[80:83], v[172:175], v[60:63], v[156:159]
	s_nop 2
	ds_read_b64_tr_b16 v[156:157], v77
	ds_read_b64_tr_b16 v[160:161], v79 offset:1024
	ds_read_b64_tr_b16 v[168:169], v77 offset:1024
	ds_read_b64_tr_b16 v[162:163], v79 offset:1280
	ds_read_b64_tr_b16 v[158:159], v76
	ds_read_b64_tr_b16 v[170:171], v76 offset:1024
	v_mfma_f32_16x16x32_bf16 v[76:79], v[180:183], v[60:63], v[176:179]
	v_or_b32_e32 v125, 2, v123
	v_lshlrev_b32_e32 v138, 12, v125
	v_add3_u32 v140, s58, v138, v167
	v_or_b32_e32 v138, 36, v121
	v_lshrrev_b32_e32 v142, 4, v138
	v_lshlrev_b32_e32 v138, 5, v138
	v_and_b32_e32 v143, 0x1e0, v138
	v_bitop3_b32 v138, v143, v122, v151 bitop3:0x36
	v_lshlrev_b32_e32 v141, 12, v142
	v_lshlrev_b32_e32 v138, 1, v138
	v_lshlrev_b32_e32 v142, 11, v142
	v_add3_u32 v145, s58, v141, v138
	v_lshlrev_b32_e32 v141, 11, v125
	v_add_u32_e32 v147, s64, v142
	v_or_b32_e32 v138, v143, v188
	v_add_u32_e32 v125, s64, v141
	v_lshl_add_u32 v149, v138, 1, v147
	v_bitop3_b32 v143, v143, v122, v139 bitop3:0x36
	v_add_u32_e32 v148, v125, v135
	v_add_u32_e32 v125, v125, v2
	v_lshl_add_u32 v147, v143, 1, v147
	s_waitcnt lgkmcnt(0)
	v_mfma_f32_16x16x32_bf16 v[56:59], v[152:155], v[156:159], v[56:59]
	ds_read_b64_tr_b16 v[156:157], v140 offset:32768
	ds_read_b64_tr_b16 v[158:159], v145 offset:32768
	ds_read_b64_tr_b16 v[172:173], v148
	ds_read_b64_tr_b16 v[176:177], v148 offset:1024
	v_mfma_f32_16x16x32_bf16 v[44:47], v[152:155], v[160:163], v[44:47]
	ds_read_b64_tr_b16 v[174:175], v149
	ds_read_b64_tr_b16 v[160:161], v125
	ds_read_b64_tr_b16 v[180:181], v125 offset:1024
	ds_read_b64_tr_b16 v[178:179], v149 offset:1024
	ds_read_b64_tr_b16 v[162:163], v147
	ds_read_b64_tr_b16 v[182:183], v147 offset:1024
	v_mfma_f32_16x16x32_bf16 v[36:39], v[152:155], v[184:187], v[36:39]
	v_mfma_f32_16x16x32_bf16 v[52:55], v[152:155], v[168:171], v[52:55]
	v_or_b32_e32 v125, 4, v123
	v_lshlrev_b32_e32 v140, 12, v125
	v_add3_u32 v145, s58, v140, v167
	v_or_b32_e32 v140, 0x44, v121
	v_lshrrev_b32_e32 v148, 4, v140
	v_lshlrev_b32_e32 v140, 5, v140
	v_and_b32_e32 v149, 0x1e0, v140
	v_bitop3_b32 v140, v149, v122, v151 bitop3:0x36
	v_lshlrev_b32_e32 v147, 12, v148
	v_lshlrev_b32_e32 v140, 1, v140
	v_lshlrev_b32_e32 v148, 11, v148
	v_add3_u32 v152, s58, v147, v140
	v_lshlrev_b32_e32 v147, 11, v125
	v_add_u32_e32 v153, s64, v148
	v_or_b32_e32 v140, v149, v188
	v_add_u32_e32 v125, s64, v147
	v_lshl_add_u32 v155, v140, 1, v153
	v_bitop3_b32 v149, v149, v122, v139 bitop3:0x36
	v_add_u32_e32 v154, v125, v135
	s_waitcnt lgkmcnt(0)
	v_mfma_f32_16x16x32_bf16 v[36:39], v[156:159], v[172:175], v[36:39]
	v_add_u32_e32 v125, v125, v2
	v_lshl_add_u32 v153, v149, 1, v153
	v_mfma_f32_16x16x32_bf16 v[56:59], v[156:159], v[160:163], v[56:59]
	ds_read_b64_tr_b16 v[160:161], v145 offset:32768
	ds_read_b64_tr_b16 v[162:163], v152 offset:32768
	ds_read_b64_tr_b16 v[168:169], v154
	ds_read_b64_tr_b16 v[172:173], v154 offset:1024
	v_mfma_f32_16x16x32_bf16 v[44:47], v[156:159], v[176:179], v[44:47]
	ds_read_b64_tr_b16 v[170:171], v155
	ds_read_b64_tr_b16 v[176:177], v125
	ds_read_b64_tr_b16 v[184:185], v125 offset:1024
	ds_read_b64_tr_b16 v[174:175], v155 offset:1024
	ds_read_b64_tr_b16 v[178:179], v153
	ds_read_b64_tr_b16 v[186:187], v153 offset:1024
	v_mfma_f32_16x16x32_bf16 v[52:55], v[156:159], v[180:183], v[52:55]
	v_or_b32_e32 v121, 0x64, v121
	v_lshrrev_b32_e32 v145, 4, v121
	v_lshlrev_b32_e32 v121, 5, v121
	v_and_b32_e32 v121, 0x1e0, v121
	v_bitop3_b32 v151, v121, v122, v151 bitop3:0x36
	v_lshlrev_b32_e32 v152, 12, v145
	v_lshlrev_b32_e32 v151, 1, v151
	v_or_b32_e32 v123, 6, v123
	v_add3_u32 v156, s58, v152, v151
	v_lshlrev_b32_e32 v152, 11, v145
	v_lshlrev_b32_e32 v125, 12, v123
	v_lshlrev_b32_e32 v151, 11, v123
	v_add_u32_e32 v154, s64, v152
	v_or_b32_e32 v145, v121, v188
	v_add3_u32 v125, s58, v125, v167
	v_add_u32_e32 v123, s64, v151
	v_lshl_add_u32 v159, v145, 1, v154
	v_bitop3_b32 v153, v121, v122, v139 bitop3:0x36
	v_add_u32_e32 v158, v123, v135
	s_waitcnt lgkmcnt(0)
	v_mfma_f32_16x16x32_bf16 v[36:39], v[160:163], v[168:171], v[36:39]
	v_add_u32_e32 v123, v123, v2
	v_lshl_add_u32 v121, v153, 1, v154
	v_mfma_f32_16x16x32_bf16 v[56:59], v[160:163], v[176:179], v[56:59]
	ds_read_b64_tr_b16 v[154:155], v125 offset:32768
	ds_read_b64_tr_b16 v[156:157], v156 offset:32768
	ds_read_b64_tr_b16 v[168:169], v158
	ds_read_b64_tr_b16 v[176:177], v158 offset:1024
	v_mfma_f32_16x16x32_bf16 v[44:47], v[160:163], v[172:175], v[44:47]
	ds_read_b64_tr_b16 v[170:171], v159
	ds_read_b64_tr_b16 v[172:173], v123
	ds_read_b64_tr_b16 v[180:181], v123 offset:1024
	ds_read_b64_tr_b16 v[178:179], v159 offset:1024
	ds_read_b64_tr_b16 v[174:175], v121
	ds_read_b64_tr_b16 v[182:183], v121 offset:1024
	v_mfma_f32_16x16x32_bf16 v[52:55], v[160:163], v[184:187], v[52:55]
	s_waitcnt lgkmcnt(0)
	v_mfma_f32_16x16x32_bf16 v[36:39], v[154:157], v[168:171], v[36:39]
	v_mfma_f32_16x16x32_bf16 v[56:59], v[154:157], v[172:175], v[56:59]
	v_mfma_f32_16x16x32_bf16 v[44:47], v[154:157], v[176:179], v[44:47]
	v_mfma_f32_16x16x32_bf16 v[52:55], v[154:157], v[180:183], v[52:55]
	s_or_b64 s[46:47], s[2:3], s[46:47]
	s_and_b64 vcc, exec, s[46:47]
	s_cbranch_vccnz .LBB0_404
; __device__ __forceinline__ float softplusf_(float x) { return x > 20.f ? x : log1pf(__expf(x)); }
; __device__ __forceinline__ void ssm_scalars(const float (&g)[2], float dtb, float A_h, float* sc, int lane) {
;   const float d0 = softplusf_(g[0] + dtb);
;   const float d1 = softplusf_(g[1] + dtb);
; __device__ void ssm_item(const Params& p, int layer, int b, int h) {
;     ...
;     if (w == 0 && ch + 1 < SEQ / 128) {
;       ssm_scalars(gpre, dtb, A_h, scal + ((ch + 1) & 1) * 384, lane0);
;       if (ch + 2 < SEQ / 128) ssm_gates(small, rbase + 256, h, lane0, gpre);
	v_add_f32_e32 v122, v127, v129
	v_cmp_nlt_f32_e32 vcc, s77, v122
	s_and_saveexec_b64 s[46:47], vcc
	s_cbranch_execz .LBB0_400
	v_mul_f32_e32 v121, 0x3fb8aa3b, v122
	v_exp_f32_e32 v121, v121
	s_mov_b32 s49, 0x3f2aaaab
	v_add_f32_e32 v125, 1.0, v121
	v_frexp_mant_f32_e32 v154, v125
	v_cvt_f64_f32_e32 v[122:123], v125
	v_frexp_exp_i32_f64_e32 v122, v[122:123]
	v_cmp_gt_f32_e32 vcc, s49, v154
	v_add_f32_e32 v139, -1.0, v125
	v_sub_f32_e32 v155, v139, v125
	v_subbrev_co_u32_e32 v160, vcc, 0, v122, vcc
	v_sub_u32_e32 v122, 0, v160
	v_sub_f32_e32 v139, v121, v139
	v_add_f32_e32 v155, 1.0, v155
	v_ldexp_f32 v123, v125, v122
	v_add_f32_e32 v139, v139, v155
	v_add_f32_e32 v125, -1.0, v123
	v_add_f32_e32 v154, 1.0, v123
	v_ldexp_f32 v122, v139, v122
	v_add_f32_e32 v139, 1.0, v125
	v_add_f32_e32 v155, -1.0, v154
	v_sub_f32_e32 v139, v123, v139
	v_sub_f32_e32 v123, v123, v155
	v_add_f32_e32 v139, v122, v139
	v_add_f32_e32 v122, v122, v123
	v_add_f32_e32 v161, v154, v122
	v_rcp_f32_e32 v163, v161
	v_sub_f32_e32 v123, v161, v154
	v_sub_f32_e32 v162, v122, v123
	v_add_f32_e32 v123, v125, v139
	v_sub_f32_e32 v122, v123, v125
	v_sub_f32_e32 v125, v139, v122
	v_mul_f32_e32 v139, v123, v163
	v_mul_f32_e32 v154, v161, v139
	v_fma_f32 v156, v139, v161, -v154
	v_fmac_f32_e32 v156, v139, v162
	v_add_f32_e32 v122, v154, v156
	v_sub_f32_e32 v155, v123, v122
	v_pk_add_f32 v[158:159], v[122:123], v[154:155] neg_lo:[0,1] neg_hi:[0,1]
	v_mov_b32_e32 v157, v122
	v_pk_add_f32 v[122:123], v[158:159], v[156:157] neg_lo:[0,1] neg_hi:[0,1]
	s_mov_b32 s49, 0x3f317218
	v_add_f32_e32 v123, v125, v123
	v_add_f32_e32 v122, v122, v123
	v_add_f32_e32 v123, v155, v122
	v_mul_f32_e32 v125, v163, v123
	v_mul_f32_e32 v154, v161, v125
	v_fma_f32 v156, v125, v161, -v154
	v_fmac_f32_e32 v156, v125, v162
	v_sub_f32_e32 v155, v155, v123
	v_add_f32_e32 v161, v122, v155
	v_add_f32_e32 v122, v154, v156
	v_sub_f32_e32 v155, v123, v122
	v_pk_add_f32 v[158:159], v[122:123], v[154:155] neg_lo:[0,1] neg_hi:[0,1]
	v_mov_b32_e32 v157, v122
	v_pk_add_f32 v[122:123], v[158:159], v[156:157] neg_lo:[0,1] neg_hi:[0,1]
	s_nop 0
	v_add_f32_e32 v123, v161, v123
	v_add_f32_e32 v122, v122, v123
	v_add_f32_e32 v123, v139, v125
	v_add_f32_e32 v122, v155, v122
	v_sub_f32_e32 v139, v123, v139
	v_mul_f32_e32 v122, v163, v122
	v_sub_f32_e32 v125, v125, v139
	v_add_f32_e32 v125, v125, v122
	v_add_f32_e32 v139, v123, v125
	v_mul_f32_e32 v154, v139, v139
	v_fmamk_f32 v122, v154, 0x3e9b6dac, v199
	v_fmaak_f32 v167, v154, v122, 0x3f2aaada
	v_cvt_f32_i32_e32 v122, v160
	v_sub_f32_e32 v123, v139, v123
	v_sub_f32_e32 v123, v125, v123
	v_ldexp_f32 v125, v123, 1
	v_mul_f32_e32 v123, v139, v154
	v_pk_mul_f32 v[156:157], v[122:123], v[166:167]
	v_ldexp_f32 v155, v139, 1
	v_fma_f32 v154, v122, s49, -v156
	v_fmac_f32_e32 v154, 0xb102e308, v122
	v_pk_add_f32 v[122:123], v[156:157], v[154:155]
	v_mov_b32_e32 v158, v156
	v_sub_f32_e32 v139, v123, v155
	v_sub_f32_e32 v139, v157, v139
	v_add_f32_e32 v159, v125, v139
	v_pk_add_f32 v[156:157], v[122:123], v[156:157] neg_lo:[0,1] neg_hi:[0,1]
	v_pk_add_f32 v[160:161], v[122:123], v[158:159]
	v_mov_b32_e32 v155, v122
	v_mov_b32_e32 v157, v161
	v_pk_add_f32 v[162:163], v[154:155], v[156:157] neg_lo:[0,1] neg_hi:[0,1]
	v_pk_add_f32 v[154:155], v[154:155], v[156:157]
	v_mov_b32_e32 v158, v159
	v_pk_add_f32 v[156:157], v[154:155], v[122:123] op_sel:[1,0] op_sel_hi:[0,1] neg_lo:[0,1] neg_hi:[0,1]
	v_pk_add_f32 v[168:169], v[160:161], v[156:157] op_sel_hi:[1,0] neg_lo:[0,1] neg_hi:[0,1]
	v_mov_b32_e32 v160, v161
	v_mov_b32_e32 v161, v155
	v_pk_mov_b32 v[156:157], v[122:123], v[156:157] op_sel:[1,0]
	v_mov_b32_e32 v159, v122
	v_pk_add_f32 v[156:157], v[160:161], v[156:157] neg_lo:[0,1] neg_hi:[0,1]
	v_mov_b32_e32 v168, v162
	v_pk_add_f32 v[122:123], v[158:159], v[156:157] neg_lo:[0,1] neg_hi:[0,1]
	v_mov_b32_e32 v163, v155
	v_pk_add_f32 v[156:157], v[168:169], v[122:123]
	s_mov_b32 s49, 0x7f800000
	v_pk_add_f32 v[158:159], v[156:157], v[156:157] op_sel:[0,1] op_sel_hi:[1,0]
	v_cmp_neq_f32_e32 vcc, s49, v121
	v_pk_add_f32 v[154:155], v[154:155], v[158:159] op_sel:[1,0] op_sel_hi:[0,1]
	v_mov_b32_e32 v157, v154
	v_pk_add_f32 v[160:161], v[156:157], v[162:163] neg_lo:[0,1] neg_hi:[0,1]
	v_mov_b32_e32 v123, v158
	v_sub_f32_e32 v125, v156, v160
	v_pk_add_f32 v[122:123], v[122:123], v[160:161] neg_lo:[0,1] neg_hi:[0,1]
	v_sub_f32_e32 v125, v162, v125
	v_add_f32_e32 v122, v122, v125
	v_add_f32_e32 v122, v122, v123
	v_add_f32_e32 v122, v154, v122
	v_cndmask_b32_e32 v122, v204, v122, vcc
	v_cmp_ngt_f32_e32 vcc, -1.0, v121
	s_mov_b32 s49, 0x33800000
	s_nop 0
	v_cndmask_b32_e32 v122, v205, v122, vcc
	v_cmp_neq_f32_e32 vcc, -1.0, v121
	s_nop 1
	v_cndmask_b32_e32 v122, v206, v122, vcc
	v_cmp_lt_f32_e64 vcc, |v121|, s49
	s_nop 1
	v_cndmask_b32_e32 v122, v122, v121, vcc

; __device__ __forceinline__ float wave_last(float v) { return __int_as_float(__builtin_amdgcn_readlane(__float_as_int(v), 63)); }
; __device__ __forceinline__ void ssm_scalars(const float (&g)[2], float dtb, float A_h, float* sc, int lane) {
;     ...
;   const float a0 = d0 * A_h, a1 = d1 * A_h;
;   const float S = wave_scan_add(a0 + a1, lane);
;   const float tot = wave_last(S);
;   sc[2 * lane] = d0; sc[2 * lane + 1] = d1;
;   sc[128 + 2 * lane] = S - a1; sc[128 + 2 * lane + 1] = S;
;   sc[256 + 2 * lane] = __expf(tot - (S - a1)); sc[256 + 2 * lane + 1] = __expf(tot - S);
; }
; __device__ void ssm_item(const Params& p, int layer, int b, int h) {
;     ...
;       if (ch + 2 < SEQ / 128) ssm_gates(small, rbase + 256, h, lane0, gpre);
.LBB0_402:
	s_or_b64 exec, exec, s[46:47]
	v_mul_f32_e32 v121, v128, v122
	v_fma_f32 v121, v123, -v128, -v121
	v_mov_b32_e32 v125, v3
	s_bitcmp1_b32 s48, 0
	v_add_f32_dpp v121, v121, v121 row_shr:1 row_mask:0xf bank_mask:0xf bound_ctrl:1
	s_cselect_b32 s46, 0x600, 0
	s_cmp_gt_u32 s62, 13
	v_add_f32_dpp v121, v121, v121 row_shr:2 row_mask:0xf bank_mask:0xf bound_ctrl:1
	s_nop 1
	v_add_f32_dpp v121, v121, v121 row_shr:4 row_mask:0xf bank_mask:0xf bound_ctrl:1
	s_nop 1
	v_add_f32_dpp v121, v121, v121 row_shr:8 row_mask:0xf bank_mask:0xf bound_ctrl:1
	s_nop 1
	v_mov_b32_dpp v125, v121 row_bcast:15 row_mask:0xa bank_mask:0xf
	v_add_f32_e32 v121, v121, v125
	v_mov_b32_e32 v125, v3
	s_nop 1
	v_mov_b32_dpp v125, v121 row_bcast:31 row_mask:0xc bank_mask:0xf
	v_add_f32_e32 v155, v121, v125
	v_add_u32_e32 v121, s46, v131
	v_readlane_b32 s47, v155, 63
	v_fma_f32 v154, v123, v128, v155
	ds_write2st64_b64 v121, v[122:123], v[154:155] offset1:1
	v_sub_f32_e32 v122, s47, v154
	v_sub_f32_e32 v123, s47, v155
	v_mul_f32_e32 v122, 0x3fb8aa3b, v122
	v_mul_f32_e32 v123, 0x3fb8aa3b, v123
	v_exp_f32_e32 v122, v122
	v_exp_f32_e32 v123, v123
	ds_write_b64 v121, v[122:123] offset:1024
	s_cbranch_scc1 .LBB0_404
	global_load_dword v129, v[108:109], off
	global_load_dword v130, v[108:109], off offset:256

; __device__ __forceinline__ size_t pidx(size_t row, int col) { return ((size_t)(col >> 8) * MTOK + row) * PLD + (col & 255); }
; __device__ void phase_post(const Params& p, int layer) {
;   const bf16_t* proj = (const bf16_t*)(ws_of(p) + OFF_PROJ);
;   bf16_t* y0 = (bf16_t*)(ws_of(p) + OFF_YBR);
;   bf16_t* y1 = y0 + (size_t)MTOK * DM;
;   bf16_t* y2 = y1 + (size_t)MTOK * DM;
;   const int tid = opaque_tid(), w = tid >> 6, lane = tid & 63;
;   const float* nw1 = p.ssm_norm_w + layer * DM;
;   const float* nw2 = p.mlstm_norm_w + layer * DM;
;   u32x4 ns[4], nm[4], nz[4];
;   {
;     const size_t row = (size_t)blockIdx.x * 8 + w;
; #pragma unroll
;     for (int i = 0; i < 4; ++i) {
;       const int c = i * 512 + lane * 8;
;       ns[i] = *(const u32x4*)(proj + pidx(row, SZ + c));
;       nm[i] = *(const u32x4*)(proj + pidx(row, MO + c));
;       nz[i] = *(const u32x4*)(proj + pidx(row, MZ + c));
;     }
;   }
.LBB0_473:
	s_or_b64 exec, exec, s[2:3]
	s_mov_b64 s[2:3], s[50:51]
	v_readlane_b32 s4, v245, 56
	s_waitcnt lgkmcnt(0)
	s_barrier
	s_add_u32 s0, s2, 0x10c80000
	v_readlane_b32 s5, v245, 57
	s_addc_u32 s1, s3, 0
	s_mov_b64 s[12:13], s[50:51]
	v_mov_b32_e32 v4, v164
	s_andn2_b64 vcc, exec, s[4:5]
	s_lshl_b32 s72, s42, 11
	s_cbranch_vccnz .LBB0_478
	v_and_b32_e32 v5, 63, v4
	v_lshlrev_b32_e32 v2, 3, v5
	v_or_b32_e32 v22, 0x400, v2
	v_lshlrev_b32_e32 v6, 14, v22
	v_or_b32_e32 v23, 0x600, v2
	v_ashrrev_i32_e32 v0, 6, v4
	v_add_u32_e32 v7, 0xf000000, v6
	v_add_u32_e32 v6, 0x11000000, v6
	v_lshlrev_b32_e32 v2, 14, v23
	v_ashrrev_i32_e32 v1, 31, v0
	v_and_b32_e32 v17, 0x12400000, v6
	v_add_u32_e32 v6, 0xf000000, v2
	v_and_b32_e32 v16, 0x10400000, v7
	v_and_b32_e32 v14, 0x10c00000, v6
	v_lshlrev_b64 v[6:7], 9, v[0:1]
	v_readlane_b32 s4, v245, 58
	v_add_u32_e32 v2, 0x11000000, v2
	v_lshl_add_u64 v[8:9], s[0:1], 0, v[6:7]
	v_readlane_b32 s5, v245, 59
	v_lshlrev_b32_e32 v24, 4, v5
	v_and_b32_e32 v12, 0x12c00000, v2
	v_lshl_add_u64 v[8:9], v[8:9], 0, s[4:5]
	v_and_b32_e32 v2, 0x1f0, v24
	v_lshl_add_u64 v[10:11], v[8:9], 0, v[2:3]
	v_lshlrev_b32_e32 v12, 1, v12
	v_mov_b32_e32 v13, v3
	v_lshlrev_b32_e32 v14, 1, v14
	v_mov_b32_e32 v15, v3
	v_lshl_add_u64 v[12:13], v[10:11], 0, v[12:13]
	v_lshl_add_u64 v[14:15], v[10:11], 0, v[14:15]
	global_load_dwordx4 v[56:59], v[12:13], off
	global_load_dwordx4 v[52:55], v[14:15], off
	v_lshlrev_b32_e32 v12, 15, v23
	v_lshlrev_b32_e32 v14, 1, v17
	v_mov_b32_e32 v15, v3
	v_and_b32_e32 v12, 0x3800000, v12
	v_mov_b32_e32 v13, v3
	v_lshl_add_u64 v[14:15], v[10:11], 0, v[14:15]
	v_lshlrev_b32_e32 v25, 18, v4
	s_mov_b32 s4, 0x1800000
	v_lshl_add_u64 v[12:13], v[8:9], 0, v[12:13]
	global_load_dwordx4 v[60:63], v[14:15], off
	v_lshlrev_b32_e32 v14, 1, v16
	v_mov_b32_e32 v15, v3
	v_bitop3_b32 v16, v25, s4, v207 bitop3:0xc8
	v_lshl_add_u64 v[12:13], v[12:13], 0, v[2:3]
	s_brev_b32 s5, 48
	v_lshl_add_u64 v[14:15], v[10:11], 0, v[14:15]
	v_or_b32_e32 v18, 0x22000000, v16
	v_mov_b32_e32 v19, v3
	v_mov_b32_e32 v17, v3
	v_add_co_u32_e32 v12, vcc, s5, v12
	global_load_dwordx4 v[64:67], v[14:15], off
	v_lshlrev_b32_e32 v14, 15, v22
	v_lshl_add_u64 v[18:19], v[10:11], 0, v[18:19]
	v_or_b32_e32 v20, 0x1e000000, v16
	v_mov_b32_e32 v21, v3
	v_lshl_add_u64 v[16:17], v[8:9], 0, v[16:17]
	v_addc_co_u32_e32 v13, vcc, 0, v13, vcc
	v_and_b32_e32 v14, 0x2800000, v14
	v_mov_b32_e32 v15, v3
	v_lshl_add_u64 v[20:21], v[10:11], 0, v[20:21]
	global_load_dwordx4 v[72:75], v[18:19], off
	global_load_dwordx4 v[68:71], v[20:21], off
	v_lshl_add_u64 v[16:17], v[16:17], 0, v[2:3]
	v_and_b32_e32 v18, 0x800000, v25
	v_mov_b32_e32 v19, v3
	v_lshl_add_u64 v[14:15], v[8:9], 0, v[14:15]
	v_add_co_u32_e32 v16, vcc, s5, v16
	v_lshl_add_u64 v[8:9], v[8:9], 0, v[18:19]
	s_nop 0
	v_addc_co_u32_e32 v17, vcc, 0, v17, vcc
	v_or_b32_e32 v20, 0x22000000, v18
	v_mov_b32_e32 v21, v3
	v_lshl_add_u64 v[8:9], v[8:9], 0, v[2:3]
	v_lshl_add_u64 v[20:21], v[10:11], 0, v[20:21]
	global_load_dwordx4 v[92:95], v[16:17], off
	global_load_dwordx4 v[80:83], v[20:21], off
	v_or_b32_e32 v16, 0x1e000000, v18
	v_mov_b32_e32 v17, v3
	v_add_co_u32_e32 v8, vcc, s5, v8
	v_lshl_add_u64 v[14:15], v[14:15], 0, v[2:3]
	v_lshl_add_u64 v[10:11], v[10:11], 0, v[16:17]
	v_addc_co_u32_e32 v9, vcc, 0, v9, vcc
	global_load_dwordx4 v[76:79], v[10:11], off
	global_load_dwordx4 v[96:99], v[8:9], off
	v_add_co_u32_e32 v8, vcc, s5, v14
	v_readlane_b32 s16, v245, 28
	s_nop 0
	v_addc_co_u32_e32 v9, vcc, 0, v15, vcc
	global_load_dwordx4 v[88:91], v[8:9], off
	global_load_dwordx4 v[84:87], v[12:13], off
	s_lshl_b64 s[4:5], s[72:73], 2
	v_readlane_b32 s26, v245, 38
	v_readlane_b32 s27, v245, 39
	s_add_u32 s6, s26, s4
	v_readlane_b32 s20, v245, 32
	s_addc_u32 s7, s27, s5
	v_readlane_b32 s21, v245, 33
	s_add_u32 s4, s20, s4
	s_addc_u32 s5, s21, s5
	v_lshlrev_b32_e32 v2, 5, v5
	v_lshlrev_b32_e32 v10, 2, v22
	v_mov_b32_e32 v11, v3
	v_lshlrev_b32_e32 v12, 2, v23
	v_mov_b32_e32 v13, v3
	v_lshlrev_b64 v[8:9], 12, v[0:1]
	v_lshl_add_u64 v[0:1], s[4:5], 0, v[2:3]
	v_lshl_add_u64 v[100:101], s[4:5], 0, v[10:11]
	v_lshl_add_u64 v[102:103], s[4:5], 0, v[12:13]
	v_readlane_b32 s4, v244, 10
	v_readlane_b32 s5, v244, 11
	s_add_u32 s4, s2, s4
	v_cmp_gt_u32_e64 s[8:9], 32, v5
	v_lshl_add_u64 v[104:105], s[6:7], 0, v[2:3]
	v_and_b32_e32 v2, 31, v4
	s_addc_u32 s5, s3, s5
	v_lshl_add_u64 v[4:5], v[18:19], 0, v[6:7]
	v_lshl_add_u64 v[110:111], s[4:5], 0, v[4:5]
	v_or_b32_e32 v4, 0x1000000, v18
	v_mov_b32_e32 v5, v3
	v_lshl_add_u64 v[4:5], v[4:5], 0, v[6:7]
	v_lshl_add_u64 v[112:113], s[4:5], 0, v[4:5]
	v_readlane_b32 s4, v244, 7
	s_add_u32 s4, s2, s4
	v_readlane_b32 s5, v244, 8
	v_or_b32_e32 v4, 0x2000000, v18
	v_mov_b32_e32 v5, v3
	s_addc_u32 s5, s3, s5
	v_lshl_add_u64 v[4:5], v[4:5], 0, v[6:7]
	v_lshl_add_u64 v[114:115], s[4:5], 0, v[4:5]
	v_or_b32_e32 v4, 0x3000000, v18
	v_mov_b32_e32 v5, v3
	v_lshl_add_u64 v[4:5], v[4:5], 0, v[6:7]
	v_lshl_add_u64 v[116:117], s[4:5], 0, v[4:5]
	v_readlane_b32 s4, v244, 9
	s_add_u32 s2, s2, s4
	v_readlane_b32 s4, v244, 12
	v_or_b32_e32 v4, 0x25000000, v18
	v_mov_b32_e32 v5, v3
	s_addc_u32 s3, s3, s4
	v_lshl_add_u64 v[4:5], v[4:5], 0, v[6:7]
	v_lshl_add_u64 v[118:119], s[2:3], 0, v[4:5]
	v_or_b32_e32 v4, 0x21000000, v18
	v_mov_b32_e32 v5, v3
	v_lshl_add_u64 v[4:5], v[4:5], 0, v[6:7]
	v_lshl_add_u64 v[120:121], s[2:3], 0, v[4:5]
	v_or_b32_e32 v4, 0x24000000, v18
	v_mov_b32_e32 v5, v3
	v_lshl_add_u64 v[4:5], v[4:5], 0, v[6:7]
	v_lshl_add_u64 v[122:123], s[2:3], 0, v[4:5]
	v_or_b32_e32 v4, 0x20000000, v18
	v_mov_b32_e32 v5, v3
	v_lshl_add_u64 v[4:5], v[4:5], 0, v[6:7]
	v_lshl_add_u64 v[124:125], s[2:3], 0, v[4:5]
	v_readlane_b32 s2, v244, 13
	s_add_u32 s2, s12, s2
	v_readlane_b32 s3, v244, 14
	s_addc_u32 s3, s13, s3
	v_or_b32_e32 v8, v8, v24
	v_lshl_add_u64 v[106:107], s[6:7], 0, v[10:11]
	v_lshl_add_u64 v[108:109], s[6:7], 0, v[12:13]
	v_lshl_add_u64 v[126:127], s[2:3], 0, v[8:9]
	s_waitcnt vmcnt(0) lgkmcnt(0)
; __device__ __forceinline__ size_t pidx(size_t row, int col) { return ((size_t)(col >> 8) * MTOK + row) * PLD + (col & 255); }
; __device__ __forceinline__ float wave_sum(float v) { return wave_last(wave_scan_add(v, 0)); }
; __device__ void phase_post(const Params& p, int layer) {
;     ...
; #pragma unroll 1
;   for (int it = blockIdx.x; it < MTOK / 8; it += gridDim.x) {
;     const size_t row = (size_t)it * 8 + w;
;     u32x4 vs[4], vm[4], vz[4];
; #pragma unroll
;     for (int i = 0; i < 4; ++i) { vs[i] = ns[i]; vm[i] = nm[i]; vz[i] = nz[i]; }
;     if (it + (int)gridDim.x < MTOK / 8) {
;       const size_t rown = row + (size_t)gridDim.x * 8;
; #pragma unroll
;       for (int i = 0; i < 4; ++i) {
;         const int c = i * 512 + lane * 8;
;         ns[i] = *(const u32x4*)(proj + pidx(rown, SZ + c));
;         nm[i] = *(const u32x4*)(proj + pidx(rown, MO + c));
;         nz[i] = *(const u32x4*)(proj + pidx(rown, MZ + c));
;       }
;     }
;     __builtin_amdgcn_sched_barrier(0);
; #pragma unroll
;     for (int i = 0; i < 4; ++i) {
;       const int c = i * 512 + lane * 8;
;       float f[8];
;       unpack8(vs[i], f);
;       float ss = 0.f;
; #pragma unroll
;       for (int j = 0; j < 8; ++j) ss += f[j] * f[j];
;       ss = wave_sum(ss);
;       const float rs = rsqrtf(ss * (1.0f / 512.0f) + EPS);
;       const f32x4 wa = *(const f32x4*)(nw1 + c), wb = *(const f32x4*)(nw1 + c + 4);
;       u32x4 o;
;       o.x = pack2(f[0] * rs * wa[0], f[1] * rs * wa[1]);
;       o.y = pack2(f[2] * rs * wa[2], f[3] * rs * wa[3]);
;       o.z = pack2(f[4] * rs * wb[0], f[5] * rs * wb[1]);
;       o.w = pack2(f[6] * rs * wb[2], f[7] * rs * wb[3]);
;       *(u32x4*)(y1 + row * DM + c) = o;
;     }
	v_mov_b64_e32 v[12:13], v[80:81]
	v_mov_b64_e32 v[24:25], v[72:73]
	v_mov_b64_e32 v[28:29], v[60:61]
	v_mov_b64_e32 v[40:41], v[56:57]
	v_mov_b64_e32 v[4:5], v[76:77]
	v_mov_b64_e32 v[16:17], v[68:69]
	v_mov_b64_e32 v[32:33], v[64:65]
	v_mov_b64_e32 v[44:45], v[52:53]
	v_mov_b64_e32 v[8:9], v[96:97]
	v_mov_b64_e32 v[20:21], v[92:93]
	v_mov_b64_e32 v[36:37], v[88:89]
	v_mov_b64_e32 v[48:49], v[84:85]
	v_lshlrev_b32_e32 v2, 4, v2
	s_mov_b32 s2, s66
	v_mov_b64_e32 v[14:15], v[82:83]
	v_mov_b64_e32 v[26:27], v[74:75]
	v_mov_b64_e32 v[30:31], v[62:63]
	v_mov_b64_e32 v[42:43], v[58:59]
	v_mov_b64_e32 v[6:7], v[78:79]
	v_mov_b64_e32 v[18:19], v[70:71]
	v_mov_b64_e32 v[34:35], v[66:67]
	v_mov_b64_e32 v[46:47], v[54:55]
	v_mov_b64_e32 v[10:11], v[98:99]
	v_mov_b64_e32 v[22:23], v[94:95]
	v_mov_b64_e32 v[38:39], v[90:91]
	v_mov_b64_e32 v[50:51], v[86:87]
	v_readlane_b32 s17, v245, 29
	v_readlane_b32 s18, v245, 30
	v_readlane_b32 s19, v245, 31
	v_readlane_b32 s22, v245, 34
	v_readlane_b32 s23, v245, 35
	v_readlane_b32 s24, v245, 36
	v_readlane_b32 s25, v245, 37
	v_readlane_b32 s28, v245, 40
	v_readlane_b32 s29, v245, 41
	v_readlane_b32 s30, v245, 42
	v_readlane_b32 s31, v245, 43
	s_branch .LBB0_476
.LBB0_475:
	v_and_b32_e32 v137, 0xffff0000, v96
	v_lshlrev_b32_e32 v136, 16, v96
	v_mul_f32_e32 v128, v137, v137
	v_lshlrev_b32_e32 v138, 16, v97
	v_fmac_f32_e32 v128, v136, v136
	v_and_b32_e32 v139, 0xffff0000, v97
	v_fmac_f32_e32 v128, v138, v138
	v_and_b32_e32 v132, 0xffff0000, v98
	v_lshlrev_b32_e32 v133, 16, v98
	v_fmac_f32_e32 v128, v139, v139
	v_pk_mul_f32 v[96:97], v[132:133], v[132:133]
	v_and_b32_e32 v134, 0xffff0000, v99
	v_add_f32_e32 v97, v97, v128
	v_lshlrev_b32_e32 v135, 16, v99
	v_add_f32_e32 v98, v96, v97
	v_pk_mul_f32 v[96:97], v[134:135], v[134:135]
	s_nop 0
	v_add_f32_e32 v97, v97, v98
	v_add_f32_e32 v96, v96, v97
	v_mov_b32_e32 v97, v3
	s_nop 0
	v_add_f32_dpp v96, v96, v96 row_shr:1 row_mask:0xf bank_mask:0xf bound_ctrl:1
	s_nop 1
	v_add_f32_dpp v96, v96, v96 row_shr:2 row_mask:0xf bank_mask:0xf bound_ctrl:1
	s_nop 1
	v_add_f32_dpp v96, v96, v96 row_shr:4 row_mask:0xf bank_mask:0xf bound_ctrl:1
	s_nop 1
	v_add_f32_dpp v96, v96, v96 row_shr:8 row_mask:0xf bank_mask:0xf bound_ctrl:1
	s_nop 1
	v_mov_b32_dpp v97, v96 row_bcast:15 row_mask:0xa bank_mask:0xf
	v_add_f32_e32 v96, v96, v97
	v_mov_b32_e32 v97, v3
	s_nop 1
	v_mov_b32_dpp v97, v96 row_bcast:31 row_mask:0xc bank_mask:0xf
	v_add_f32_e32 v96, v96, v97
	s_nop 0
	v_readlane_b32 s3, v96, 63
	s_nop 1
	v_fma_f32 v96, s3, v208, v201
	v_cmp_gt_f32_e32 vcc, s43, v96
	v_mul_f32_e32 v97, 0x4b800000, v96
	s_mov_b32 s3, 0xfbfff400
	v_cndmask_b32_e32 v96, v96, v97, vcc
	v_rsq_f32_e32 v96, v96
	s_nop 0
	v_mul_f32_e32 v97, 0x45800000, v96
	v_cndmask_b32_e32 v140, v96, v97, vcc
	global_load_dwordx4 v[128:131], v[0:1], off offset:16
	global_load_dwordx4 v[96:99], v[0:1], off
	v_mul_f32_e32 v136, v140, v136
	s_waitcnt vmcnt(0)
	v_mul_f32_e32 v96, v96, v136
	v_mul_f32_e32 v136, v140, v137
	v_mul_f32_e32 v97, v97, v136
	v_cvt_pk_bf16_f32 v96, v96, v97
	v_mul_f32_e32 v97, v140, v138
	v_mul_f32_e32 v97, v98, v97
	v_mul_f32_e32 v98, v140, v139
	v_mul_f32_e32 v98, v99, v98
	v_cvt_pk_bf16_f32 v97, v97, v98
	v_mul_f32_e32 v98, v140, v133
	v_mul_f32_e32 v99, v140, v132
	v_mul_f32_e32 v98, v128, v98
	v_mul_f32_e32 v99, v129, v99
	v_cvt_pk_bf16_f32 v98, v98, v99
	v_mul_f32_e32 v99, v140, v135
	v_mul_f32_e32 v128, v140, v134
	v_mul_f32_e32 v99, v130, v99
	v_mul_f32_e32 v128, v131, v128
	v_cvt_pk_bf16_f32 v99, v99, v128
	v_add_co_u32_e32 v128, vcc, s3, v126
	v_and_b32_e32 v135, 0xffff0000, v92
	s_nop 0
	v_addc_co_u32_e32 v129, vcc, -1, v127, vcc
	global_store_dwordx4 v[128:129], v[96:99], off
	v_lshlrev_b32_e32 v134, 16, v92
	v_lshlrev_b32_e32 v136, 16, v93
	v_mul_f32_e32 v96, v135, v135
	v_fmac_f32_e32 v96, v134, v134
	v_and_b32_e32 v137, 0xffff0000, v93
	v_fmac_f32_e32 v96, v136, v136
	v_and_b32_e32 v98, 0xffff0000, v94
	v_lshlrev_b32_e32 v99, 16, v94
	v_fmac_f32_e32 v96, v137, v137
	v_pk_mul_f32 v[92:93], v[98:99], v[98:99]
	v_and_b32_e32 v132, 0xffff0000, v95
	v_add_f32_e32 v93, v93, v96
	v_lshlrev_b32_e32 v133, 16, v95
	v_add_f32_e32 v94, v92, v93
	v_pk_mul_f32 v[92:93], v[132:133], v[132:133]
	s_nop 0
	v_add_f32_e32 v93, v93, v94
	global_load_dwordx4 v[94:97], v[0:1], off offset:2064
	global_load_dwordx4 v[128:131], v[0:1], off offset:2048
	v_add_f32_e32 v92, v92, v93
	v_mov_b32_e32 v93, v3
	s_nop 0
	v_add_f32_dpp v92, v92, v92 row_shr:1 row_mask:0xf bank_mask:0xf bound_ctrl:1
	s_nop 1
	v_add_f32_dpp v92, v92, v92 row_shr:2 row_mask:0xf bank_mask:0xf bound_ctrl:1
	s_nop 1
	v_add_f32_dpp v92, v92, v92 row_shr:4 row_mask:0xf bank_mask:0xf bound_ctrl:1
	s_nop 1
	v_add_f32_dpp v92, v92, v92 row_shr:8 row_mask:0xf bank_mask:0xf bound_ctrl:1
	s_nop 1
	v_mov_b32_dpp v93, v92 row_bcast:15 row_mask:0xa bank_mask:0xf
	v_add_f32_e32 v92, v92, v93
	v_mov_b32_e32 v93, v3
	s_nop 1
	v_mov_b32_dpp v93, v92 row_bcast:31 row_mask:0xc bank_mask:0xf
	v_add_f32_e32 v92, v92, v93
	s_nop 0
	v_readlane_b32 s3, v92, 63
	s_nop 1
	v_fma_f32 v92, s3, v208, v201
	v_cmp_gt_f32_e32 vcc, s43, v92
	v_mul_f32_e32 v93, 0x4b800000, v92
	s_mov_b32 s3, 0xfbfff800
	v_cndmask_b32_e32 v92, v92, v93, vcc
	v_rsq_f32_e32 v92, v92
	s_nop 0
	v_mul_f32_e32 v93, 0x45800000, v92
	v_cndmask_b32_e32 v138, v92, v93, vcc
	v_mul_f32_e32 v99, v138, v99
	v_mul_f32_e32 v98, v138, v98
	v_mul_f32_e32 v92, v138, v134
	v_mul_f32_e32 v93, v138, v135
	s_waitcnt vmcnt(0)
; __device__ __forceinline__ float wave_sum(float v) { return wave_last(wave_scan_add(v, 0)); }
; __device__ void phase_post(const Params& p, int layer) {
;     ...
;     for (int i = 0; i < 4; ++i) {
;       const int c = i * 512 + lane * 8;
;       float f[8];
;       unpack8(vs[i], f);
;       float ss = 0.f;
; #pragma unroll
;       for (int j = 0; j < 8; ++j) ss += f[j] * f[j];
;       ss = wave_sum(ss);
;       const float rs = rsqrtf(ss * (1.0f / 512.0f) + EPS);
;       const f32x4 wa = *(const f32x4*)(nw1 + c), wb = *(const f32x4*)(nw1 + c + 4);
;       u32x4 o;
;       o.x = pack2(f[0] * rs * wa[0], f[1] * rs * wa[1]);
;       o.y = pack2(f[2] * rs * wa[2], f[3] * rs * wa[3]);
;       o.z = pack2(f[4] * rs * wb[0], f[5] * rs * wb[1]);
;       o.w = pack2(f[6] * rs * wb[2], f[7] * rs * wb[3]);
;       *(u32x4*)(y1 + row * DM + c) = o;
;     }
	v_mul_f32_e32 v94, v94, v99
	v_mul_f32_e32 v95, v95, v98
	v_cvt_pk_bf16_f32 v94, v94, v95
	v_mul_f32_e32 v95, v138, v133
	v_mul_f32_e32 v95, v96, v95
	v_mul_f32_e32 v96, v138, v132
	v_mul_f32_e32 v92, v128, v92
	v_mul_f32_e32 v93, v129, v93
	v_mul_f32_e32 v96, v97, v96
	v_cvt_pk_bf16_f32 v92, v92, v93
	v_mul_f32_e32 v93, v138, v136
	v_mul_f32_e32 v128, v138, v137
	v_cvt_pk_bf16_f32 v95, v95, v96
	v_add_co_u32_e32 v96, vcc, s3, v126
	v_mul_f32_e32 v93, v130, v93
	v_mul_f32_e32 v128, v131, v128
	v_addc_co_u32_e32 v97, vcc, -1, v127, vcc
	v_and_b32_e32 v129, 0xffff0000, v88
	v_cvt_pk_bf16_f32 v93, v93, v128
	global_store_dwordx4 v[96:97], v[92:95], off
	v_lshlrev_b32_e32 v128, 16, v88
	v_lshlrev_b32_e32 v130, 16, v89
	v_mul_f32_e32 v92, v129, v129
	v_fmac_f32_e32 v92, v128, v128
	v_and_b32_e32 v131, 0xffff0000, v89
	v_fmac_f32_e32 v92, v130, v130
	v_and_b32_e32 v96, 0xffff0000, v90
	v_lshlrev_b32_e32 v97, 16, v90
	v_fmac_f32_e32 v92, v131, v131
	v_pk_mul_f32 v[88:89], v[96:97], v[96:97]
	v_and_b32_e32 v98, 0xffff0000, v91
	v_add_f32_e32 v89, v89, v92
	v_lshlrev_b32_e32 v99, 16, v91
	v_add_f32_e32 v90, v88, v89
	v_pk_mul_f32 v[88:89], v[98:99], v[98:99]
	v_and_b32_e32 v133, 0xffff0000, v78
	v_add_f32_e32 v89, v89, v90
	v_add_f32_e32 v88, v88, v89
	v_mov_b32_e32 v89, v3
	s_nop 0
	v_add_f32_dpp v88, v88, v88 row_shr:1 row_mask:0xf bank_mask:0xf bound_ctrl:1
	s_nop 1
	v_add_f32_dpp v88, v88, v88 row_shr:2 row_mask:0xf bank_mask:0xf bound_ctrl:1
	s_nop 1
	v_add_f32_dpp v88, v88, v88 row_shr:4 row_mask:0xf bank_mask:0xf bound_ctrl:1
	s_nop 1
	v_add_f32_dpp v88, v88, v88 row_shr:8 row_mask:0xf bank_mask:0xf bound_ctrl:1
	s_nop 1
	v_mov_b32_dpp v89, v88 row_bcast:15 row_mask:0xa bank_mask:0xf
	v_add_f32_e32 v88, v88, v89
	v_mov_b32_e32 v89, v3
	s_nop 1
	v_mov_b32_dpp v89, v88 row_bcast:31 row_mask:0xc bank_mask:0xf
	v_add_f32_e32 v88, v88, v89
	s_nop 0
	v_readlane_b32 s3, v88, 63
	s_nop 1
	v_fma_f32 v88, s3, v208, v201
	v_cmp_gt_f32_e32 vcc, s43, v88
	v_mul_f32_e32 v89, 0x4b800000, v88
	s_mov_b32 s3, 0xfbfffc00
	v_cndmask_b32_e32 v88, v88, v89, vcc
	v_rsq_f32_e32 v88, v88
	s_nop 0
	v_mul_f32_e32 v89, 0x45800000, v88
	v_cndmask_b32_e32 v132, v88, v89, vcc
	global_load_dwordx4 v[88:91], v[100:101], off offset:16
	global_load_dwordx4 v[92:95], v[100:101], off
	v_mul_f32_e32 v128, v132, v128
	s_waitcnt vmcnt(0)
	v_mul_f32_e32 v92, v92, v128
	v_mul_f32_e32 v128, v132, v129
	v_mul_f32_e32 v93, v93, v128
	v_cvt_pk_bf16_f32 v92, v92, v93
	v_mul_f32_e32 v93, v132, v130
	v_mul_f32_e32 v93, v94, v93
	v_mul_f32_e32 v94, v132, v131
	v_mul_f32_e32 v94, v95, v94
	v_cvt_pk_bf16_f32 v93, v93, v94
	v_mul_f32_e32 v94, v132, v97
	v_mul_f32_e32 v88, v88, v94
	v_mul_f32_e32 v94, v132, v96
	v_mul_f32_e32 v89, v89, v94
	v_cvt_pk_bf16_f32 v94, v88, v89
	v_mul_f32_e32 v88, v132, v99
	v_mul_f32_e32 v88, v90, v88
	v_mul_f32_e32 v89, v132, v98
	v_mul_f32_e32 v89, v91, v89
	v_cvt_pk_bf16_f32 v95, v88, v89
	v_add_co_u32_e32 v88, vcc, s3, v126
	v_and_b32_e32 v97, 0xffff0000, v84
	s_nop 0
	v_addc_co_u32_e32 v89, vcc, -1, v127, vcc
	global_store_dwordx4 v[88:89], v[92:95], off
	v_lshlrev_b32_e32 v96, 16, v84
	v_mul_f32_e32 v88, v97, v97
	v_lshlrev_b32_e32 v98, 16, v85
	v_fmac_f32_e32 v88, v96, v96
	v_and_b32_e32 v99, 0xffff0000, v85
	v_fmac_f32_e32 v88, v98, v98
	v_and_b32_e32 v92, 0xffff0000, v86
	v_lshlrev_b32_e32 v93, 16, v86
	v_fmac_f32_e32 v88, v99, v99
	v_pk_mul_f32 v[84:85], v[92:93], v[92:93]
	v_and_b32_e32 v94, 0xffff0000, v87
	v_add_f32_e32 v85, v85, v88
	v_lshlrev_b32_e32 v95, 16, v87
	v_add_f32_e32 v86, v84, v85
	v_pk_mul_f32 v[84:85], v[94:95], v[94:95]
	v_lshlrev_b32_e32 v132, 16, v78
	v_add_f32_e32 v85, v85, v86
	v_add_f32_e32 v84, v84, v85
	v_mov_b32_e32 v85, v3
	v_and_b32_e32 v78, 0xffff0000, v80
	v_add_f32_dpp v84, v84, v84 row_shr:1 row_mask:0xf bank_mask:0xf bound_ctrl:1
	s_nop 1
	v_add_f32_dpp v84, v84, v84 row_shr:2 row_mask:0xf bank_mask:0xf bound_ctrl:1
	s_nop 1
	v_add_f32_dpp v84, v84, v84 row_shr:4 row_mask:0xf bank_mask:0xf bound_ctrl:1
	s_nop 1
	v_add_f32_dpp v84, v84, v84 row_shr:8 row_mask:0xf bank_mask:0xf bound_ctrl:1
	s_nop 1
	v_mov_b32_dpp v85, v84 row_bcast:15 row_mask:0xa bank_mask:0xf
	v_add_f32_e32 v84, v84, v85
	v_mov_b32_e32 v85, v3
	s_nop 1
	v_mov_b32_dpp v85, v84 row_bcast:31 row_mask:0xc bank_mask:0xf
	v_add_f32_e32 v84, v84, v85
	s_nop 0
	v_readlane_b32 s3, v84, 63
	s_nop 1
	v_fma_f32 v84, s3, v208, v201
	v_cmp_gt_f32_e32 vcc, s43, v84
	v_mul_f32_e32 v85, 0x4b800000, v84
	s_brev_b32 s3, 63
	v_cndmask_b32_e32 v84, v84, v85, vcc
	v_rsq_f32_e32 v84, v84
	s_nop 0
	v_mul_f32_e32 v85, 0x45800000, v84
	v_cndmask_b32_e32 v128, v84, v85, vcc
	global_load_dwordx4 v[84:87], v[102:103], off offset:16
	global_load_dwordx4 v[88:91], v[102:103], off
	v_mul_f32_e32 v96, v128, v96
	s_waitcnt vmcnt(0)
; __device__ __forceinline__ float siluf_(float x) { return x * __builtin_amdgcn_rcpf(1.0f + __expf(-x)); }
; __device__ __forceinline__ float wave_sum(float v) { return wave_last(wave_scan_add(v, 0)); }
; __device__ void phase_post(const Params& p, int layer) {
;     ...
;     for (int i = 0; i < 4; ++i) {
;       const int c = i * 512 + lane * 8;
;       float f[8];
;       unpack8(vs[i], f);
;       float ss = 0.f;
; #pragma unroll
;       for (int j = 0; j < 8; ++j) ss += f[j] * f[j];
;       ss = wave_sum(ss);
;       const float rs = rsqrtf(ss * (1.0f / 512.0f) + EPS);
;       const f32x4 wa = *(const f32x4*)(nw1 + c), wb = *(const f32x4*)(nw1 + c + 4);
;       u32x4 o;
;       o.x = pack2(f[0] * rs * wa[0], f[1] * rs * wa[1]);
;       o.y = pack2(f[2] * rs * wa[2], f[3] * rs * wa[3]);
;       o.z = pack2(f[4] * rs * wb[0], f[5] * rs * wb[1]);
;       o.w = pack2(f[6] * rs * wb[2], f[7] * rs * wb[3]);
;       *(u32x4*)(y1 + row * DM + c) = o;
;     }
; #pragma unroll
;     for (int i = 0; i < 4; ++i) {
;       const int c = i * 512 + lane * 8;
;       float f[8], zf[8];
;       unpack8(vm[i], f);
;       unpack8(vz[i], zf);
;       float sm = 0.f;
; #pragma unroll
;       for (int j = 0; j < 8; ++j) sm += f[j];
;       sm = half_sum(sm, lane);
;       const float mu = sm * (1.0f / 256.0f);
;       float ss = 0.f;
; #pragma unroll
;       for (int j = 0; j < 8; ++j) { f[j] -= mu; ss += f[j] * f[j]; }
;       ss = half_sum(ss, lane);
;       const float rs = rsqrtf(ss * (1.0f / 256.0f) + EPS);
;       const f32x4 wa = *(const f32x4*)(nw2 + c), wb = *(const f32x4*)(nw2 + c + 4);
;       u32x4 o;
;       o.x = pack2(f[0] * rs * wa[0] * siluf_(zf[0]), f[1] * rs * wa[1] * siluf_(zf[1]));
;       o.y = pack2(f[2] * rs * wa[2] * siluf_(zf[2]), f[3] * rs * wa[3] * siluf_(zf[3]));
;       o.z = pack2(f[4] * rs * wb[0] * siluf_(zf[4]), f[5] * rs * wb[1] * siluf_(zf[5]));
;       o.w = pack2(f[6] * rs * wb[2] * siluf_(zf[6]), f[7] * rs * wb[3] * siluf_(zf[7]));
;       *(u32x4*)(y2 + row * DM + c) = o;
;     }
	v_mul_f32_e32 v88, v88, v96
	v_mul_f32_e32 v96, v128, v97
	v_mul_f32_e32 v89, v89, v96
	v_cvt_pk_bf16_f32 v88, v88, v89
	v_mul_f32_e32 v89, v128, v98
	v_mul_f32_e32 v89, v90, v89
	v_mul_f32_e32 v90, v128, v99
	v_mul_f32_e32 v90, v91, v90
	v_cvt_pk_bf16_f32 v89, v89, v90
	v_mul_f32_e32 v90, v128, v93
	v_mul_f32_e32 v84, v84, v90
	v_mul_f32_e32 v90, v128, v92
	v_mul_f32_e32 v85, v85, v90
	v_cvt_pk_bf16_f32 v90, v84, v85
	v_mul_f32_e32 v84, v128, v95
	v_mul_f32_e32 v84, v86, v84
	v_mul_f32_e32 v85, v128, v94
	v_mul_f32_e32 v85, v87, v85
	v_cvt_pk_bf16_f32 v91, v84, v85
	v_add_co_u32_e32 v84, vcc, s3, v126
	v_and_b32_e32 v87, 0xffff0000, v76
	s_nop 0
	v_addc_co_u32_e32 v85, vcc, -1, v127, vcc
	global_store_dwordx4 v[84:85], v[88:91], off
	v_lshlrev_b32_e32 v85, 16, v76
	v_lshlrev_b32_e32 v93, 16, v79
	v_lshlrev_b32_e32 v89, 16, v77
	v_and_b32_e32 v91, 0xffff0000, v77
	v_add_f32_e32 v77, 0, v85
	v_add_f32_e32 v77, v77, v87
	v_add_f32_e32 v77, v77, v89
	v_add_f32_e32 v77, v77, v91
	v_add_f32_e32 v77, v77, v132
	v_add_f32_e32 v77, v77, v133
	v_and_b32_e32 v92, 0xffff0000, v79
	v_add_f32_e32 v77, v77, v93
	v_add_f32_e32 v77, v77, v92
	v_mov_b32_e32 v79, v3
	v_lshlrev_b32_e32 v84, 16, v80
	v_add_f32_dpp v77, v77, v77 row_shr:1 row_mask:0xf bank_mask:0xf bound_ctrl:1
	v_lshlrev_b32_e32 v90, 16, v82
	v_and_b32_e32 v88, 0xffff0000, v82
	v_add_f32_dpp v77, v77, v77 row_shr:2 row_mask:0xf bank_mask:0xf bound_ctrl:1
	v_lshlrev_b32_e32 v82, 16, v83
	v_and_b32_e32 v80, 0xffff0000, v83
	v_add_f32_dpp v77, v77, v77 row_shr:4 row_mask:0xf bank_mask:0xf bound_ctrl:1
	v_mul_f32_e32 v83, 0xbfb8aa3b, v78
	v_lshlrev_b32_e32 v76, 16, v81
	v_add_f32_dpp v77, v77, v77 row_shr:8 row_mask:0xf bank_mask:0xf bound_ctrl:1
	v_and_b32_e32 v86, 0xffff0000, v81
	v_exp_f32_e32 v83, v83
	v_mov_b32_dpp v79, v77 row_bcast:15 row_mask:0xa bank_mask:0xf
	v_add_f32_e32 v77, v77, v79
	v_add_f32_e32 v83, 1.0, v83
	v_readlane_b32 s3, v77, 31
	v_readlane_b32 s4, v77, 63
	s_nop 0
	v_mov_b32_e32 v79, s3
	v_mov_b32_e32 v77, s4
	v_cndmask_b32_e64 v77, v77, v79, s[8:9]
	v_fmac_f32_e32 v87, 0xbb800000, v77
	v_fmac_f32_e32 v85, 0xbb800000, v77
	v_mul_f32_e32 v79, v87, v87
	v_fmac_f32_e32 v79, v85, v85
	v_fmac_f32_e32 v89, 0xbb800000, v77
	v_fmac_f32_e32 v79, v89, v89
	v_fmac_f32_e32 v91, 0xbb800000, v77
	v_mul_f32_e32 v94, 0x3b800000, v77
	v_fmac_f32_e32 v79, v91, v91
	v_fmac_f32_e32 v132, 0xbb800000, v77
	v_fmac_f32_e32 v79, v132, v132
	v_fmac_f32_e32 v133, 0xbb800000, v77
	v_pk_add_f32 v[128:129], v[92:93], v[94:95] op_sel_hi:[1,0] neg_lo:[0,1] neg_hi:[0,1]
	v_fmac_f32_e32 v79, v133, v133
	v_pk_mul_f32 v[92:93], v[128:129], v[128:129]
	s_nop 0
	v_add_f32_e32 v77, v93, v79
	v_add_f32_e32 v77, v92, v77
	global_load_dwordx4 v[92:95], v[104:105], off offset:16
	global_load_dwordx4 v[96:99], v[104:105], off
	v_add_f32_dpp v77, v77, v77 row_shr:1 row_mask:0xf bank_mask:0xf bound_ctrl:1
	v_mov_b32_e32 v79, v3
	s_waitcnt vmcnt(0)
	v_mov_b32_e32 v131, v96
	v_add_f32_dpp v77, v77, v77 row_shr:2 row_mask:0xf bank_mask:0xf bound_ctrl:1
	v_rcp_f32_e32 v96, v83
	s_nop 0
	v_add_f32_dpp v77, v77, v77 row_shr:4 row_mask:0xf bank_mask:0xf bound_ctrl:1
	s_nop 1
	v_add_f32_dpp v77, v77, v77 row_shr:8 row_mask:0xf bank_mask:0xf bound_ctrl:1
	s_nop 1
	v_mov_b32_dpp v79, v77 row_bcast:15 row_mask:0xa bank_mask:0xf
	v_add_f32_e32 v77, v77, v79
	s_nop 0
	v_readlane_b32 s3, v77, 31
	v_readlane_b32 s4, v77, 63
	s_nop 0
	v_mov_b32_e32 v79, s3
	v_mov_b32_e32 v77, s4
	v_cndmask_b32_e64 v77, v77, v79, s[8:9]
	v_fmamk_f32 v77, v77, 0x3b800000, v201
	v_cmp_gt_f32_e32 vcc, s43, v77
	v_mul_f32_e32 v79, 0x4b800000, v77
	s_movk_i32 s3, 0xf400
	v_cndmask_b32_e32 v77, v77, v79, vcc
	v_rsq_f32_e32 v77, v77
	s_nop 0
	v_mul_f32_e32 v79, 0x45800000, v77
	v_cndmask_b32_e32 v81, v77, v79, vcc
	v_mul_f32_e32 v77, 0xbfb8aa3b, v84
	v_exp_f32_e32 v77, v77
	v_mul_f32_e32 v79, v87, v81
	v_mul_f32_e32 v85, v85, v81
	v_pk_mul_f32 v[78:79], v[96:97], v[78:79]
	v_add_f32_e32 v77, 1.0, v77
	v_rcp_f32_e32 v130, v77
	v_mul_f32_e32 v78, v78, v79
	v_mov_b32_e32 v79, v98
	v_mul_f32_e32 v87, v91, v81
	v_pk_mul_f32 v[84:85], v[130:131], v[84:85]
	v_mul_f32_e32 v91, v132, v81
	v_mul_f32_e32 v77, v84, v85
	v_cvt_pk_bf16_f32 v84, v77, v78
	v_mul_f32_e32 v78, 0xbfb8aa3b, v76
	v_exp_f32_e32 v78, v78
	v_mul_f32_e32 v77, v89, v81
	v_mul_f32_e32 v89, v133, v81
	v_mul_f32_e32 v83, v129, v81
	v_add_f32_e32 v78, 1.0, v78
	v_rcp_f32_e32 v78, v78
	v_mul_f32_e32 v81, v128, v81
	v_pk_mul_f32 v[76:77], v[78:79], v[76:77]
	s_nop 0
	v_mul_f32_e32 v78, v76, v77
	v_mul_f32_e32 v76, 0xbfb8aa3b, v86
	v_exp_f32_e32 v76, v76
	v_and_b32_e32 v79, 0xffff0000, v70
	v_add_f32_e32 v76, 1.0, v76
	v_rcp_f32_e32 v98, v76
	s_nop 0
	v_pk_mul_f32 v[76:77], v[98:99], v[86:87]
	s_nop 0
	v_mul_f32_e32 v76, v76, v77
	v_cvt_pk_bf16_f32 v85, v78, v76
	v_mul_f32_e32 v76, 0xbfb8aa3b, v90
	v_exp_f32_e32 v76, v76
	v_mov_b32_e32 v77, v92
	v_add_f32_e32 v76, 1.0, v76
	v_rcp_f32_e32 v76, v76
	s_nop 0
	v_pk_mul_f32 v[76:77], v[76:77], v[90:91]
	s_nop 0
	v_mul_f32_e32 v78, v76, v77
	v_mul_f32_e32 v76, 0xbfb8aa3b, v88
	v_exp_f32_e32 v76, v76
	v_and_b32_e32 v90, 0xffff0000, v68
	v_add_f32_e32 v76, 1.0, v76
	v_rcp_f32_e32 v92, v76
	s_nop 0
	v_pk_mul_f32 v[76:77], v[92:93], v[88:89]
	s_nop 0
	v_mul_f32_e32 v76, v76, v77
	v_cvt_pk_bf16_f32 v86, v78, v76
	v_mul_f32_e32 v76, 0xbfb8aa3b, v82
	v_exp_f32_e32 v76, v76
	v_mov_b32_e32 v77, v94
	v_lshlrev_b32_e32 v89, 16, v68
	v_add_f32_e32 v68, 0, v89
	v_add_f32_e32 v76, 1.0, v76
	v_rcp_f32_e32 v76, v76
	v_add_f32_e32 v68, v68, v90
	v_lshlrev_b32_e32 v88, 16, v72
	v_and_b32_e32 v72, 0xffff0000, v72
	v_pk_mul_f32 v[76:77], v[76:77], v[82:83]
	v_lshlrev_b32_e32 v83, 16, v70
; __device__ __forceinline__ float siluf_(float x) { return x * __builtin_amdgcn_rcpf(1.0f + __expf(-x)); }
; __device__ void phase_post(const Params& p, int layer) {
;     ...
; #pragma unroll
;     for (int i = 0; i < 4; ++i) {
;       const int c = i * 512 + lane * 8;
;       float f[8], zf[8];
;       unpack8(vm[i], f);
;       unpack8(vz[i], zf);
;       float sm = 0.f;
; #pragma unroll
;       for (int j = 0; j < 8; ++j) sm += f[j];
;       sm = half_sum(sm, lane);
;       const float mu = sm * (1.0f / 256.0f);
;       float ss = 0.f;
; #pragma unroll
;       for (int j = 0; j < 8; ++j) { f[j] -= mu; ss += f[j] * f[j]; }
;       ss = half_sum(ss, lane);
;       const float rs = rsqrtf(ss * (1.0f / 256.0f) + EPS);
;       const f32x4 wa = *(const f32x4*)(nw2 + c), wb = *(const f32x4*)(nw2 + c + 4);
;       u32x4 o;
;       o.x = pack2(f[0] * rs * wa[0] * siluf_(zf[0]), f[1] * rs * wa[1] * siluf_(zf[1]));
;       o.y = pack2(f[2] * rs * wa[2] * siluf_(zf[2]), f[3] * rs * wa[3] * siluf_(zf[3]));
;       o.z = pack2(f[4] * rs * wb[0] * siluf_(zf[4]), f[5] * rs * wb[1] * siluf_(zf[5]));
;       o.w = pack2(f[6] * rs * wb[2] * siluf_(zf[6]), f[7] * rs * wb[3] * siluf_(zf[7]));
;       *(u32x4*)(y2 + row * DM + c) = o;
;     }
	v_mul_f32_e32 v78, v76, v77
	v_mul_f32_e32 v76, 0xbfb8aa3b, v80
	v_exp_f32_e32 v76, v76
	v_lshlrev_b32_e32 v82, 16, v74
	v_and_b32_e32 v74, 0xffff0000, v74
	v_add_f32_e32 v76, 1.0, v76
	v_rcp_f32_e32 v94, v76
	s_nop 0
	v_pk_mul_f32 v[76:77], v[94:95], v[80:81]
	s_nop 0
	v_mul_f32_e32 v76, v76, v77
	v_cvt_pk_bf16_f32 v87, v78, v76
	v_add_co_u32_e32 v76, vcc, s3, v126
	v_lshlrev_b32_e32 v78, 16, v75
	s_nop 0
	v_addc_co_u32_e32 v77, vcc, -1, v127, vcc
	global_store_dwordx4 v[76:77], v[84:87], off
	v_and_b32_e32 v76, 0xffff0000, v75
	s_nop 0
	v_lshlrev_b32_e32 v87, 16, v69
	v_and_b32_e32 v85, 0xffff0000, v69
	v_add_f32_e32 v68, v68, v87
	v_add_f32_e32 v68, v68, v85
	v_add_f32_e32 v68, v68, v83
	v_add_f32_e32 v70, v68, v79
	v_lshlrev_b32_e32 v69, 16, v71
	v_and_b32_e32 v68, 0xffff0000, v71
	v_add_f32_e32 v70, v70, v69
	v_add_f32_e32 v70, v70, v68
	v_mov_b32_e32 v71, v3
	v_lshlrev_b32_e32 v86, 16, v73
	v_add_f32_dpp v70, v70, v70 row_shr:1 row_mask:0xf bank_mask:0xf bound_ctrl:1
	v_and_b32_e32 v84, 0xffff0000, v73
	s_nop 0
	v_add_f32_dpp v70, v70, v70 row_shr:2 row_mask:0xf bank_mask:0xf bound_ctrl:1
	s_nop 1
	v_add_f32_dpp v70, v70, v70 row_shr:4 row_mask:0xf bank_mask:0xf bound_ctrl:1
	s_nop 1
	v_add_f32_dpp v70, v70, v70 row_shr:8 row_mask:0xf bank_mask:0xf bound_ctrl:1
	s_nop 1
	v_mov_b32_dpp v71, v70 row_bcast:15 row_mask:0xa bank_mask:0xf
	v_add_f32_e32 v70, v70, v71
	s_nop 0
	v_readlane_b32 s3, v70, 31
	v_readlane_b32 s4, v70, 63
	s_nop 0
	v_mov_b32_e32 v71, s3
	v_mov_b32_e32 v70, s4
	v_cndmask_b32_e64 v71, v70, v71, s[8:9]
	v_fmac_f32_e32 v90, 0xbb800000, v71
	v_fmac_f32_e32 v89, 0xbb800000, v71
	v_mul_f32_e32 v73, v90, v90
	v_fmac_f32_e32 v73, v89, v89
	v_fmac_f32_e32 v87, 0xbb800000, v71
	v_fmac_f32_e32 v73, v87, v87
	v_fmac_f32_e32 v85, 0xbb800000, v71
	v_mul_f32_e32 v70, 0x3b800000, v71
	v_fmac_f32_e32 v73, v85, v85
	v_fmac_f32_e32 v83, 0xbb800000, v71
	v_fmac_f32_e32 v73, v83, v83
	v_fmac_f32_e32 v79, 0xbb800000, v71
	v_pk_add_f32 v[80:81], v[68:69], v[70:71] op_sel_hi:[1,0] neg_lo:[0,1] neg_hi:[0,1]
	v_fmac_f32_e32 v73, v79, v79
	v_pk_mul_f32 v[68:69], v[80:81], v[80:81]
	s_nop 0
	v_add_f32_e32 v69, v69, v73
	v_add_f32_e32 v68, v68, v69
	v_mov_b32_e32 v69, v3
	v_mul_f32_e32 v73, 0xbfb8aa3b, v88
	v_add_f32_dpp v68, v68, v68 row_shr:1 row_mask:0xf bank_mask:0xf bound_ctrl:1
	v_exp_f32_e32 v73, v73
	s_nop 0
	v_add_f32_dpp v68, v68, v68 row_shr:2 row_mask:0xf bank_mask:0xf bound_ctrl:1
	v_add_f32_e32 v73, 1.0, v73
	s_nop 0
	v_add_f32_dpp v68, v68, v68 row_shr:4 row_mask:0xf bank_mask:0xf bound_ctrl:1
	v_rcp_f32_e32 v96, v73
	s_nop 0
	v_add_f32_dpp v68, v68, v68 row_shr:8 row_mask:0xf bank_mask:0xf bound_ctrl:1
	s_nop 1
	v_mov_b32_dpp v69, v68 row_bcast:15 row_mask:0xa bank_mask:0xf
	v_add_f32_e32 v68, v68, v69
	s_nop 0
	v_readlane_b32 s3, v68, 31
	v_readlane_b32 s4, v68, 63
	s_nop 0
	v_mov_b32_e32 v69, s3
	v_mov_b32_e32 v68, s4
	v_cndmask_b32_e64 v68, v68, v69, s[8:9]
	v_fmamk_f32 v68, v68, 0x3b800000, v201
	v_cmp_gt_f32_e32 vcc, s43, v68
	v_mul_f32_e32 v69, 0x4b800000, v68
	s_movk_i32 s3, 0xf800
	v_cndmask_b32_e32 v68, v68, v69, vcc
	v_rsq_f32_e32 v68, v68
	s_nop 0
	v_mul_f32_e32 v69, 0x45800000, v68
	v_cndmask_b32_e32 v77, v68, v69, vcc
	global_load_dwordx4 v[68:71], v[104:105], off offset:2064
	global_load_dwordx4 v[92:95], v[104:105], off offset:2048
	v_mul_f32_e32 v89, v89, v77
	v_mul_f32_e32 v73, v90, v77
	v_mul_f32_e32 v87, v87, v77
	v_mul_f32_e32 v85, v85, v77
	v_mul_f32_e32 v83, v83, v77
	s_waitcnt vmcnt(0)
	v_mov_b32_e32 v97, v92
	v_pk_mul_f32 v[88:89], v[96:97], v[88:89]
	s_waitcnt lgkmcnt(0)
	v_mov_b64_e32 v[98:99], v[10:11]
	v_mul_f32_e32 v75, v88, v89
	v_mul_f32_e32 v88, 0xbfb8aa3b, v72
	v_exp_f32_e32 v88, v88
	v_mov_b32_e32 v89, v94
	v_mov_b64_e32 v[96:97], v[8:9]
	v_add_f32_e32 v88, 1.0, v88
	v_rcp_f32_e32 v92, v88
	s_nop 0
	v_pk_mul_f32 v[72:73], v[92:93], v[72:73]
	s_nop 0
	v_mul_f32_e32 v72, v72, v73
	v_cvt_pk_bf16_f32 v72, v75, v72
	v_mul_f32_e32 v73, 0xbfb8aa3b, v86
	v_mul_f32_e32 v75, 0xbfb8aa3b, v84
	v_exp_f32_e32 v73, v73
	v_exp_f32_e32 v75, v75
	v_add_f32_e32 v73, 1.0, v73
	v_add_f32_e32 v75, 1.0, v75
	v_rcp_f32_e32 v88, v73
	v_rcp_f32_e32 v94, v75
	v_pk_mul_f32 v[86:87], v[88:89], v[86:87]
	v_pk_mul_f32 v[84:85], v[94:95], v[84:85]
	v_mul_f32_e32 v73, v86, v87
	v_mul_f32_e32 v75, v84, v85
	v_mov_b32_e32 v85, v68
	v_mul_f32_e32 v68, 0xbfb8aa3b, v74
	v_cvt_pk_bf16_f32 v73, v73, v75
	v_mul_f32_e32 v75, 0xbfb8aa3b, v82
	v_exp_f32_e32 v68, v68
	v_exp_f32_e32 v75, v75
	v_mov_b64_e32 v[94:95], v[22:23]
	v_mov_b64_e32 v[90:91], v[38:39]
	v_add_f32_e32 v68, 1.0, v68
	v_add_f32_e32 v75, 1.0, v75
	v_rcp_f32_e32 v68, v68
	v_rcp_f32_e32 v84, v75
	v_mul_f32_e32 v75, v79, v77
	v_mul_f32_e32 v79, v81, v77
	v_pk_mul_f32 v[68:69], v[68:69], v[74:75]
	v_pk_mul_f32 v[82:83], v[84:85], v[82:83]
	v_mul_f32_e32 v68, v68, v69
	v_mul_f32_e32 v82, v82, v83
	v_cvt_pk_bf16_f32 v74, v82, v68
	v_mul_f32_e32 v68, 0xbfb8aa3b, v78
	v_exp_f32_e32 v68, v68
	v_mov_b32_e32 v69, v70
	v_mul_f32_e32 v77, v80, v77
	v_lshlrev_b32_e32 v83, 16, v64
	v_add_f32_e32 v68, 1.0, v68
	v_rcp_f32_e32 v68, v68
	v_and_b32_e32 v81, 0xffff0000, v64
	v_lshlrev_b32_e32 v84, 16, v60
	v_and_b32_e32 v82, 0xffff0000, v60
	v_pk_mul_f32 v[68:69], v[68:69], v[78:79]
	v_add_f32_e32 v60, 0, v83
	v_mul_f32_e32 v75, v68, v69
	v_mul_f32_e32 v68, 0xbfb8aa3b, v76
	v_exp_f32_e32 v68, v68
	v_lshlrev_b32_e32 v79, 16, v65
	v_add_f32_e32 v60, v60, v81
	v_add_f32_e32 v60, v60, v79
	v_add_f32_e32 v68, 1.0, v68
	v_rcp_f32_e32 v70, v68
	v_lshlrev_b32_e32 v80, 16, v61
	v_and_b32_e32 v78, 0xffff0000, v61
	v_lshlrev_b32_e32 v61, 16, v67
	v_pk_mul_f32 v[68:69], v[70:71], v[76:77]
; __device__ __forceinline__ float siluf_(float x) { return x * __builtin_amdgcn_rcpf(1.0f + __expf(-x)); }
; __device__ void phase_post(const Params& p, int layer) {
;     ...
; #pragma unroll
;     for (int i = 0; i < 4; ++i) {
;       const int c = i * 512 + lane * 8;
;       float f[8], zf[8];
;       unpack8(vm[i], f);
;       unpack8(vz[i], zf);
;       float sm = 0.f;
; #pragma unroll
;       for (int j = 0; j < 8; ++j) sm += f[j];
;       sm = half_sum(sm, lane);
;       const float mu = sm * (1.0f / 256.0f);
;       float ss = 0.f;
; #pragma unroll
;       for (int j = 0; j < 8; ++j) { f[j] -= mu; ss += f[j] * f[j]; }
;       ss = half_sum(ss, lane);
;       const float rs = rsqrtf(ss * (1.0f / 256.0f) + EPS);
;       const f32x4 wa = *(const f32x4*)(nw2 + c), wb = *(const f32x4*)(nw2 + c + 4);
;       u32x4 o;
;       o.x = pack2(f[0] * rs * wa[0] * siluf_(zf[0]), f[1] * rs * wa[1] * siluf_(zf[1]));
;       o.y = pack2(f[2] * rs * wa[2] * siluf_(zf[2]), f[3] * rs * wa[3] * siluf_(zf[3]));
;       o.z = pack2(f[4] * rs * wb[0] * siluf_(zf[4]), f[5] * rs * wb[1] * siluf_(zf[5]));
;       o.w = pack2(f[6] * rs * wb[2] * siluf_(zf[6]), f[7] * rs * wb[3] * siluf_(zf[7]));
;       *(u32x4*)(y2 + row * DM + c) = o;
;     }
	v_and_b32_e32 v77, 0xffff0000, v65
	v_mul_f32_e32 v68, v68, v69
	v_cvt_pk_bf16_f32 v75, v75, v68
	v_add_co_u32_e32 v68, vcc, s3, v126
	v_add_f32_e32 v60, v60, v77
	s_nop 0
	v_addc_co_u32_e32 v69, vcc, -1, v127, vcc
	global_store_dwordx4 v[68:69], v[72:75], off
	v_and_b32_e32 v71, 0xffff0000, v66
	v_lshlrev_b32_e32 v76, 16, v62
	v_lshlrev_b32_e32 v73, 16, v66
	v_add_f32_e32 v60, v60, v73
	v_and_b32_e32 v72, 0xffff0000, v62
	v_add_f32_e32 v62, v60, v71
	v_and_b32_e32 v60, 0xffff0000, v67
	v_add_f32_e32 v62, v62, v61
	v_add_f32_e32 v62, v62, v60
	v_lshlrev_b32_e32 v70, 16, v63
	v_and_b32_e32 v68, 0xffff0000, v63
	v_add_f32_dpp v62, v62, v62 row_shr:1 row_mask:0xf bank_mask:0xf bound_ctrl:1
	v_mov_b32_e32 v63, v3
	v_mov_b64_e32 v[92:93], v[20:21]
	v_add_f32_dpp v62, v62, v62 row_shr:2 row_mask:0xf bank_mask:0xf bound_ctrl:1
	v_mov_b64_e32 v[88:89], v[36:37]
	s_nop 0
	v_add_f32_dpp v62, v62, v62 row_shr:4 row_mask:0xf bank_mask:0xf bound_ctrl:1
	s_nop 1
	v_add_f32_dpp v62, v62, v62 row_shr:8 row_mask:0xf bank_mask:0xf bound_ctrl:1
	s_nop 1
	v_mov_b32_dpp v63, v62 row_bcast:15 row_mask:0xa bank_mask:0xf
	v_add_f32_e32 v62, v62, v63
	s_nop 0
	v_readlane_b32 s3, v62, 31
	v_readlane_b32 s4, v62, 63
	s_nop 0
	v_mov_b32_e32 v63, s3
	v_mov_b32_e32 v62, s4
	v_cndmask_b32_e64 v63, v62, v63, s[8:9]
	v_fmac_f32_e32 v81, 0xbb800000, v63
	v_fmac_f32_e32 v83, 0xbb800000, v63
	v_mul_f32_e32 v64, v81, v81
	v_fmac_f32_e32 v64, v83, v83
	v_fmac_f32_e32 v79, 0xbb800000, v63
	v_fmac_f32_e32 v64, v79, v79
	v_fmac_f32_e32 v77, 0xbb800000, v63
	v_mul_f32_e32 v62, 0x3b800000, v63
	v_fmac_f32_e32 v64, v77, v77
	v_fmac_f32_e32 v73, 0xbb800000, v63
	v_fmac_f32_e32 v64, v73, v73
	v_fmac_f32_e32 v71, 0xbb800000, v63
	v_pk_add_f32 v[74:75], v[60:61], v[62:63] op_sel_hi:[1,0] neg_lo:[0,1] neg_hi:[0,1]
	v_fmac_f32_e32 v64, v71, v71
	v_pk_mul_f32 v[60:61], v[74:75], v[74:75]
	s_nop 0
	v_add_f32_e32 v61, v61, v64
	v_add_f32_e32 v60, v60, v61
	v_mov_b32_e32 v61, v3
	s_nop 0
	v_add_f32_dpp v60, v60, v60 row_shr:1 row_mask:0xf bank_mask:0xf bound_ctrl:1
	s_nop 1
	v_add_f32_dpp v60, v60, v60 row_shr:2 row_mask:0xf bank_mask:0xf bound_ctrl:1
	s_nop 1
	v_add_f32_dpp v60, v60, v60 row_shr:4 row_mask:0xf bank_mask:0xf bound_ctrl:1
	s_nop 1
	v_add_f32_dpp v60, v60, v60 row_shr:8 row_mask:0xf bank_mask:0xf bound_ctrl:1
	s_nop 1
	v_mov_b32_dpp v61, v60 row_bcast:15 row_mask:0xa bank_mask:0xf
	v_add_f32_e32 v60, v60, v61
	s_nop 0
	v_readlane_b32 s3, v60, 31
	v_readlane_b32 s4, v60, 63
	s_nop 0
	v_mov_b32_e32 v61, s3
	v_mov_b32_e32 v60, s4
	v_cndmask_b32_e64 v60, v60, v61, s[8:9]
	v_fmamk_f32 v60, v60, 0x3b800000, v201
	v_cmp_gt_f32_e32 vcc, s43, v60
	v_mul_f32_e32 v61, 0x4b800000, v60
	s_movk_i32 s3, 0xfc00
	v_cndmask_b32_e32 v60, v60, v61, vcc
	v_rsq_f32_e32 v60, v60
	s_nop 0
	v_mul_f32_e32 v61, 0x45800000, v60
	v_cndmask_b32_e32 v69, v60, v61, vcc
	global_load_dwordx4 v[60:63], v[106:107], off offset:16
	global_load_dwordx4 v[64:67], v[106:107], off
	v_mul_f32_e32 v85, v83, v69
	v_mul_f32_e32 v83, 0xbfb8aa3b, v84
	v_exp_f32_e32 v83, v83
	s_waitcnt vmcnt(0)
	v_mov_b32_e32 v87, v64
	v_mul_f32_e32 v64, 0xbfb8aa3b, v82
	v_exp_f32_e32 v64, v64
	v_add_f32_e32 v83, 1.0, v83
	v_rcp_f32_e32 v86, v83
	v_mul_f32_e32 v83, v81, v69
	v_add_f32_e32 v64, 1.0, v64
	v_rcp_f32_e32 v64, v64
	v_mul_f32_e32 v81, v79, v69
	v_mul_f32_e32 v79, v77, v69
	v_mul_f32_e32 v77, v73, v69
	v_pk_mul_f32 v[64:65], v[64:65], v[82:83]
	v_mov_b32_e32 v83, v66
	v_mul_f32_e32 v64, v64, v65
	v_mul_f32_e32 v65, 0xbfb8aa3b, v80
	v_mul_f32_e32 v66, 0xbfb8aa3b, v78
	v_exp_f32_e32 v65, v65
	v_exp_f32_e32 v66, v66
	v_mul_f32_e32 v73, v71, v69
	v_mul_f32_e32 v71, v75, v69
	v_add_f32_e32 v65, 1.0, v65
	v_add_f32_e32 v66, 1.0, v66
	v_rcp_f32_e32 v82, v65
	v_rcp_f32_e32 v66, v66
	v_mul_f32_e32 v69, v74, v69
	v_lshlrev_b32_e32 v75, 16, v52
	v_pk_mul_f32 v[80:81], v[82:83], v[80:81]
	v_pk_mul_f32 v[66:67], v[66:67], v[78:79]
	v_mul_f32_e32 v65, v80, v81
	v_mul_f32_e32 v66, v66, v67
	v_cvt_pk_bf16_f32 v65, v65, v66
	v_mul_f32_e32 v66, 0xbfb8aa3b, v76
	v_mov_b32_e32 v67, v60
	v_mul_f32_e32 v60, 0xbfb8aa3b, v72
	v_exp_f32_e32 v66, v66
	v_exp_f32_e32 v60, v60
	v_pk_mul_f32 v[84:85], v[86:87], v[84:85]
	v_and_b32_e32 v74, 0xffff0000, v56
	v_add_f32_e32 v66, 1.0, v66
	v_add_f32_e32 v60, 1.0, v60
	v_rcp_f32_e32 v66, v66
	v_rcp_f32_e32 v60, v60
	v_mul_f32_e32 v84, v84, v85
	v_cvt_pk_bf16_f32 v64, v84, v64
	v_pk_mul_f32 v[66:67], v[66:67], v[76:77]
	v_pk_mul_f32 v[60:61], v[60:61], v[72:73]
	v_mul_f32_e32 v66, v66, v67
	v_mul_f32_e32 v60, v60, v61
	v_cvt_pk_bf16_f32 v66, v66, v60
	v_mul_f32_e32 v60, 0xbfb8aa3b, v70
	v_exp_f32_e32 v60, v60
	v_mov_b32_e32 v61, v62
	v_and_b32_e32 v73, 0xffff0000, v52
	v_add_f32_e32 v52, 0, v75
	v_add_f32_e32 v60, 1.0, v60
	v_rcp_f32_e32 v60, v60
	v_add_f32_e32 v52, v52, v73
	v_lshlrev_b32_e32 v76, 16, v56
	v_lshlrev_b32_e32 v72, 16, v57
	v_pk_mul_f32 v[60:61], v[60:61], v[70:71]
	v_lshlrev_b32_e32 v71, 16, v53
	v_mul_f32_e32 v67, v60, v61
	v_mul_f32_e32 v60, 0xbfb8aa3b, v68
	v_exp_f32_e32 v60, v60
	v_add_f32_e32 v52, v52, v71
	v_and_b32_e32 v70, 0xffff0000, v57
	v_mov_b64_e32 v[82:83], v[14:15]
	v_add_f32_e32 v60, 1.0, v60
	v_rcp_f32_e32 v62, v60
	v_mov_b64_e32 v[86:87], v[50:51]
	v_mov_b64_e32 v[80:81], v[12:13]
	v_mov_b64_e32 v[84:85], v[48:49]
	v_pk_mul_f32 v[60:61], v[62:63], v[68:69]
	v_and_b32_e32 v69, 0xffff0000, v53
	v_mul_f32_e32 v60, v60, v61
	v_cvt_pk_bf16_f32 v67, v67, v60
	v_add_co_u32_e32 v60, vcc, s3, v126
	v_add_f32_e32 v52, v52, v69
	s_nop 0
	v_addc_co_u32_e32 v61, vcc, -1, v127, vcc
	global_store_dwordx4 v[60:61], v[64:67], off
	v_and_b32_e32 v63, 0xffff0000, v54
	v_lshlrev_b32_e32 v53, 16, v55
; __device__ __forceinline__ float siluf_(float x) { return x * __builtin_amdgcn_rcpf(1.0f + __expf(-x)); }
; __device__ void phase_post(const Params& p, int layer) {
;     ...
; #pragma unroll
;     for (int i = 0; i < 4; ++i) {
;       const int c = i * 512 + lane * 8;
;       float f[8], zf[8];
;       unpack8(vm[i], f);
;       unpack8(vz[i], zf);
;       float sm = 0.f;
; #pragma unroll
;       for (int j = 0; j < 8; ++j) sm += f[j];
;       sm = half_sum(sm, lane);
;       const float mu = sm * (1.0f / 256.0f);
;       float ss = 0.f;
; #pragma unroll
;       for (int j = 0; j < 8; ++j) { f[j] -= mu; ss += f[j] * f[j]; }
;       ss = half_sum(ss, lane);
;       const float rs = rsqrtf(ss * (1.0f / 256.0f) + EPS);
;       const f32x4 wa = *(const f32x4*)(nw2 + c), wb = *(const f32x4*)(nw2 + c + 4);
;       u32x4 o;
;       o.x = pack2(f[0] * rs * wa[0] * siluf_(zf[0]), f[1] * rs * wa[1] * siluf_(zf[1]));
;       o.y = pack2(f[2] * rs * wa[2] * siluf_(zf[2]), f[3] * rs * wa[3] * siluf_(zf[3]));
;       o.z = pack2(f[4] * rs * wb[0] * siluf_(zf[4]), f[5] * rs * wb[1] * siluf_(zf[5]));
;       o.w = pack2(f[6] * rs * wb[2] * siluf_(zf[6]), f[7] * rs * wb[3] * siluf_(zf[7]));
;       *(u32x4*)(y2 + row * DM + c) = o;
;     }
	v_lshlrev_b32_e32 v65, 16, v54
	v_add_f32_e32 v52, v52, v65
	v_add_f32_e32 v54, v52, v63
	v_and_b32_e32 v52, 0xffff0000, v55
	v_add_f32_e32 v54, v54, v53
	v_add_f32_e32 v54, v54, v52
	v_mov_b32_e32 v55, v3
	v_lshlrev_b32_e32 v68, 16, v58
	v_add_f32_dpp v54, v54, v54 row_shr:1 row_mask:0xf bank_mask:0xf bound_ctrl:1
	v_and_b32_e32 v64, 0xffff0000, v58
	v_lshlrev_b32_e32 v62, 16, v59
	v_add_f32_dpp v54, v54, v54 row_shr:2 row_mask:0xf bank_mask:0xf bound_ctrl:1
	v_and_b32_e32 v60, 0xffff0000, v59
	s_nop 0
	v_add_f32_dpp v54, v54, v54 row_shr:4 row_mask:0xf bank_mask:0xf bound_ctrl:1
	s_nop 1
	v_add_f32_dpp v54, v54, v54 row_shr:8 row_mask:0xf bank_mask:0xf bound_ctrl:1
	s_nop 1
	v_mov_b32_dpp v55, v54 row_bcast:15 row_mask:0xa bank_mask:0xf
	v_add_f32_e32 v54, v54, v55
	s_nop 0
	v_readlane_b32 s3, v54, 31
	v_readlane_b32 s4, v54, 63
	s_nop 0
	v_mov_b32_e32 v55, s3
	v_mov_b32_e32 v54, s4
	v_cndmask_b32_e64 v55, v54, v55, s[8:9]
	v_fmac_f32_e32 v73, 0xbb800000, v55
	v_fmac_f32_e32 v75, 0xbb800000, v55
	v_mul_f32_e32 v56, v73, v73
	v_fmac_f32_e32 v56, v75, v75
	v_fmac_f32_e32 v71, 0xbb800000, v55
	v_fmac_f32_e32 v56, v71, v71
	v_fmac_f32_e32 v69, 0xbb800000, v55
	v_mul_f32_e32 v54, 0x3b800000, v55
	v_fmac_f32_e32 v56, v69, v69
	v_fmac_f32_e32 v65, 0xbb800000, v55
	v_fmac_f32_e32 v56, v65, v65
	v_fmac_f32_e32 v63, 0xbb800000, v55
	v_pk_add_f32 v[66:67], v[52:53], v[54:55] op_sel_hi:[1,0] neg_lo:[0,1] neg_hi:[0,1]
	v_fmac_f32_e32 v56, v63, v63
	v_pk_mul_f32 v[52:53], v[66:67], v[66:67]
	s_nop 0
	v_add_f32_e32 v53, v53, v56
	v_add_f32_e32 v52, v52, v53
	v_mov_b32_e32 v53, v3
	s_nop 0
	v_add_f32_dpp v52, v52, v52 row_shr:1 row_mask:0xf bank_mask:0xf bound_ctrl:1
	s_nop 1
	v_add_f32_dpp v52, v52, v52 row_shr:2 row_mask:0xf bank_mask:0xf bound_ctrl:1
	s_nop 1
	v_add_f32_dpp v52, v52, v52 row_shr:4 row_mask:0xf bank_mask:0xf bound_ctrl:1
	s_nop 1
	v_add_f32_dpp v52, v52, v52 row_shr:8 row_mask:0xf bank_mask:0xf bound_ctrl:1
	s_nop 1
	v_mov_b32_dpp v53, v52 row_bcast:15 row_mask:0xa bank_mask:0xf
	v_add_f32_e32 v52, v52, v53
	s_nop 0
	v_readlane_b32 s3, v52, 31
	v_readlane_b32 s4, v52, 63
	s_nop 0
	v_mov_b32_e32 v53, s3
	v_mov_b32_e32 v52, s4
	v_cndmask_b32_e64 v52, v52, v53, s[8:9]
	v_fmamk_f32 v52, v52, 0x3b800000, v201
	v_cmp_gt_f32_e32 vcc, s43, v52
	v_mul_f32_e32 v53, 0x4b800000, v52
	v_readlane_b32 s4, v244, 5
	v_cndmask_b32_e32 v52, v52, v53, vcc
	v_rsq_f32_e32 v52, v52
	v_readlane_b32 s5, v244, 6
	v_mul_f32_e32 v53, 0x45800000, v52
	v_cndmask_b32_e32 v61, v52, v53, vcc
	global_load_dwordx4 v[52:55], v[108:109], off offset:16
	global_load_dwordx4 v[56:59], v[108:109], off
	v_mul_f32_e32 v77, v75, v61
	v_mul_f32_e32 v75, 0xbfb8aa3b, v76
	v_exp_f32_e32 v75, v75
	v_lshl_add_u64 v[110:111], v[110:111], 0, s[4:5]
	v_lshl_add_u64 v[112:113], v[112:113], 0, s[4:5]
	v_lshl_add_u64 v[114:115], v[114:115], 0, s[4:5]
	v_add_f32_e32 v75, 1.0, v75
	v_rcp_f32_e32 v78, v75
	v_mul_f32_e32 v75, v73, v61
	v_mul_f32_e32 v73, v71, v61
	v_mul_f32_e32 v71, v69, v61
	v_mul_f32_e32 v69, v65, v61
	v_mul_f32_e32 v65, v63, v61
	v_mul_f32_e32 v63, v67, v61
	v_mul_f32_e32 v61, v66, v61
	v_lshl_add_u64 v[116:117], v[116:117], 0, s[4:5]
	v_lshl_add_u64 v[118:119], v[118:119], 0, s[4:5]
	v_lshl_add_u64 v[120:121], v[120:121], 0, s[4:5]
	v_lshl_add_u64 v[122:123], v[122:123], 0, s[4:5]
	v_lshl_add_u64 v[124:125], v[124:125], 0, s[4:5]
	v_readlane_b32 s4, v244, 15
	v_readlane_b32 s5, v244, 16
	s_and_b64 vcc, exec, s[14:15]
	s_waitcnt vmcnt(0)
	v_mov_b32_e32 v79, v56
	v_mul_f32_e32 v56, 0xbfb8aa3b, v74
	v_exp_f32_e32 v56, v56
	v_pk_mul_f32 v[76:77], v[78:79], v[76:77]
	v_add_f32_e32 v56, 1.0, v56
	v_rcp_f32_e32 v56, v56
	v_mul_f32_e32 v76, v76, v77
	v_pk_mul_f32 v[56:57], v[56:57], v[74:75]
	s_nop 0
	v_mul_f32_e32 v56, v56, v57
	v_mul_f32_e32 v57, 0xbfb8aa3b, v72
	v_mov_b32_e32 v75, v58
	v_mul_f32_e32 v58, 0xbfb8aa3b, v70
	v_exp_f32_e32 v57, v57
	v_exp_f32_e32 v58, v58
	v_cvt_pk_bf16_f32 v56, v76, v56
	v_mov_b64_e32 v[78:79], v[6:7]
	v_add_f32_e32 v57, 1.0, v57
	v_add_f32_e32 v58, 1.0, v58
	v_rcp_f32_e32 v74, v57
	v_rcp_f32_e32 v58, v58
	v_mov_b64_e32 v[76:77], v[4:5]
	v_pk_mul_f32 v[72:73], v[74:75], v[72:73]
	v_pk_mul_f32 v[58:59], v[58:59], v[70:71]
	v_mul_f32_e32 v57, v72, v73
	v_mul_f32_e32 v58, v58, v59
	v_cvt_pk_bf16_f32 v57, v57, v58
	v_mul_f32_e32 v58, 0xbfb8aa3b, v68
	v_mov_b32_e32 v59, v52
	v_mul_f32_e32 v52, 0xbfb8aa3b, v64
	v_exp_f32_e32 v58, v58
	v_exp_f32_e32 v52, v52
	v_mov_b64_e32 v[74:75], v[26:27]
	v_mov_b64_e32 v[72:73], v[24:25]
	v_add_f32_e32 v58, 1.0, v58
	v_add_f32_e32 v52, 1.0, v52
	v_rcp_f32_e32 v58, v58
	v_rcp_f32_e32 v52, v52
	v_pk_mul_f32 v[58:59], v[58:59], v[68:69]
	v_pk_mul_f32 v[52:53], v[52:53], v[64:65]
	v_mul_f32_e32 v58, v58, v59
	v_mul_f32_e32 v52, v52, v53
	v_cvt_pk_bf16_f32 v58, v58, v52
	v_mul_f32_e32 v52, 0xbfb8aa3b, v62
	v_exp_f32_e32 v52, v52
	v_mov_b32_e32 v53, v54
	v_mov_b64_e32 v[70:71], v[18:19]
	v_mov_b64_e32 v[66:67], v[34:35]
	v_add_f32_e32 v52, 1.0, v52
	v_rcp_f32_e32 v52, v52
	v_mov_b64_e32 v[68:69], v[16:17]
	v_mov_b64_e32 v[64:65], v[32:33]
	v_pk_mul_f32 v[52:53], v[52:53], v[62:63]
	s_nop 0
	v_mul_f32_e32 v59, v52, v53
	v_mul_f32_e32 v52, 0xbfb8aa3b, v60
	v_exp_f32_e32 v52, v52
	s_nop 0
	v_add_f32_e32 v52, 1.0, v52
	v_rcp_f32_e32 v54, v52
	s_nop 0
	v_pk_mul_f32 v[52:53], v[54:55], v[60:61]
	s_nop 0
	v_mul_f32_e32 v52, v52, v53
	v_cvt_pk_bf16_f32 v59, v59, v52
	global_store_dwordx4 v[126:127], v[56:59], off
	v_mov_b64_e32 v[62:63], v[30:31]
	v_mov_b64_e32 v[54:55], v[46:47]
	v_mov_b64_e32 v[58:59], v[42:43]
	v_lshl_add_u64 v[126:127], v[126:127], 0, s[4:5]
	v_mov_b64_e32 v[60:61], v[28:29]
	v_mov_b64_e32 v[56:57], v[40:41]
	v_mov_b64_e32 v[52:53], v[44:45]
	s_cbranch_vccnz .LBB0_478
; __device__ __forceinline__ size_t pidx(size_t row, int col) { return ((size_t)(col >> 8) * MTOK + row) * PLD + (col & 255); }
; __device__ void phase_post(const Params& p, int layer) {
;     ...
;   for (int it = blockIdx.x; it < MTOK / 8; it += gridDim.x) {
;     const size_t row = (size_t)it * 8 + w;
;     u32x4 vs[4], vm[4], vz[4];
; #pragma unroll
;     for (int i = 0; i < 4; ++i) { vs[i] = ns[i]; vm[i] = nm[i]; vz[i] = nz[i]; }
;     if (it + (int)gridDim.x < MTOK / 8) {
;       const size_t rown = row + (size_t)gridDim.x * 8;
; #pragma unroll
;       for (int i = 0; i < 4; ++i) {
;         const int c = i * 512 + lane * 8;
;         ns[i] = *(const u32x4*)(proj + pidx(rown, SZ + c));
;         nm[i] = *(const u32x4*)(proj + pidx(rown, MO + c));
;         nz[i] = *(const u32x4*)(proj + pidx(rown, MZ + c));
;       }
;     }
.LBB0_476:
	s_add_i32 s2, s2, s76
	s_cmpk_gt_i32 s2, 0x7ff
	s_cselect_b64 s[14:15], -1, 0
	s_and_b64 vcc, exec, s[14:15]
	s_cbranch_vccnz .LBB0_475
	v_lshl_add_u64 v[12:13], v[110:111], 0, v[2:3]
	v_add_co_u32_e32 v4, vcc, 0x1cc80000, v12
	v_lshl_add_u64 v[24:25], v[112:113], 0, v[2:3]
	s_nop 0
	v_addc_co_u32_e32 v5, vcc, 0, v13, vcc
	v_add_co_u32_e32 v6, vcc, 0x2ec80000, v12
	s_mov_b32 s3, 0x1cc80000
	s_nop 0
	v_addc_co_u32_e32 v7, vcc, 0, v13, vcc
	v_add_co_u32_e32 v12, vcc, 0x32c80000, v12
	v_lshl_add_u64 v[28:29], v[114:115], 0, v[2:3]
	s_nop 0
	v_addc_co_u32_e32 v13, vcc, 0, v13, vcc
	v_add_co_u32_e32 v16, vcc, s3, v24
	v_lshl_add_u64 v[40:41], v[116:117], 0, v[2:3]
	s_nop 0
	v_addc_co_u32_e32 v17, vcc, 0, v25, vcc
	v_add_co_u32_e32 v18, vcc, 0x2ec80000, v24
	global_load_dwordx4 v[8:11], v[4:5], off
	s_nop 0
	global_load_dwordx4 v[4:7], v[6:7], off
	v_addc_co_u32_e32 v19, vcc, 0, v25, vcc
	global_load_dwordx4 v[12:15], v[12:13], off
	s_nop 0
	global_load_dwordx4 v[20:23], v[16:17], off
	s_nop 0
	global_load_dwordx4 v[16:19], v[18:19], off
	v_add_co_u32_e32 v24, vcc, 0x32c80000, v24
	global_load_dwordx4 v[36:39], v[28:29], off
	v_lshl_add_u64 v[28:29], v[124:125], 0, v[2:3]
	global_load_dwordx4 v[48:51], v[40:41], off
	v_lshl_add_u64 v[40:41], v[120:121], 0, v[2:3]
	v_addc_co_u32_e32 v25, vcc, 0, v25, vcc
	global_load_dwordx4 v[32:35], v[28:29], off
	v_lshl_add_u64 v[28:29], v[122:123], 0, v[2:3]
	global_load_dwordx4 v[44:47], v[40:41], off
	v_lshl_add_u64 v[40:41], v[118:119], 0, v[2:3]
	global_load_dwordx4 v[24:27], v[24:25], off
	s_nop 0
	global_load_dwordx4 v[28:31], v[28:29], off
	s_nop 0
	global_load_dwordx4 v[40:43], v[40:41], off
	s_branch .LBB0_475

; #define PG8_WAIT_V(n) asm volatile("s_waitcnt vmcnt(" #n ")" ::: "memory")
; #define PG8_WAIT_L(n) asm volatile("s_waitcnt lgkmcnt(" #n ")" ::: "memory")
; #define PG8_BAR __builtin_amdgcn_s_barrier()
; #define PG8_SCHED __builtin_amdgcn_sched_barrier(0)
; template <class Epi, class AddrA, class AddrB>
; __device__ __forceinline__ void gemm_phase(const Sched S, const int lda, const int ldb, const int K, const AddrA addrA,
;                                            const AddrB addrB, const Epi E) {
;     ...
;       PG8_LDB(B0, 0, 0); PG8_SCHED; PG8_LDA(At, 0, 0); PG8_STAGE(PG8_SA(1, 1), a1 + hstepA, voffA);
;       PG8_WAIT_L(8); PG8_BAR; PG8_WAIT_L(0); PG8_MMA(0, 0, At, B0); PG8_BAR; PG8_SCHED;
;       PG8_LDB(B1, 0, 1); PG8_STAGE(PG8_SB(0, 0), b2, voffB);
;       PG8_BAR; PG8_WAIT_L(0); PG8_MMA(0, 1, At, B1); PG8_BAR;
;       PG8_LDA(At, 0, 1); PG8_STAGE(PG8_SA(0, 0), a2, voffA);
;       PG8_BAR; PG8_WAIT_L(0); PG8_MMA(1, 0, At, B0); PG8_BAR; PG8_SCHED;
;       PG8_STAGE(PG8_SB(0, 1), b2 + hstepB, voffB);
;       PG8_WAIT_V(6); PG8_BAR; PG8_MMA(1, 1, At, B1); PG8_BAR;
.LBB0_485:
	s_add_u32 s6, s4, 0xfff80080
	s_addc_u32 s7, s5, -1
	s_add_i32 s44, 0, 0x10000
	v_add_u32_e32 v2, s44, v167
	ds_read_b128 v[92:95], v2
	ds_read_b128 v[100:103], v2 offset:1024
	ds_read_b128 v[132:135], v2 offset:2048
	ds_read_b128 v[144:147], v2 offset:3072
	s_cmp_eq_u32 s43, 4
	s_cselect_b32 s11, s3, s7
	s_cselect_b32 s10, s15, s6
	s_cselect_b32 s7, s17, s42
	s_cselect_b32 s6, s40, s41
	v_lshl_add_u64 v[196:197], s[4:5], 0, v[172:173]
	s_add_i32 m0, s30, 0xc000
	ds_read_b128 v[148:151], v169
	ds_read_b128 v[152:155], v169 offset:1024
	ds_read_b128 v[176:179], v169 offset:2048
	ds_read_b128 v[180:183], v169 offset:3072
	ds_read_b128 v[184:187], v169 offset:4096
	ds_read_b128 v[188:191], v169 offset:5120
	ds_read_b128 v[192:195], v169 offset:6144
	ds_read_b128 v[212:215], v169 offset:7168
	global_load_lds_dwordx4 v[196:197], off
	v_lshl_add_u64 v[196:197], s[4:5], 0, v[170:171]
	s_add_i32 m0, s30, 0xe000
	s_nop 0
	global_load_lds_dwordx4 v[196:197], off
	s_waitcnt lgkmcnt(8)
	s_barrier
	s_waitcnt lgkmcnt(0)
	s_setprio 1
	s_waitcnt lgkmcnt(0)
	v_mfma_f32_16x16x32_bf16 v[140:143], v[92:95], v[148:151], v[140:143]
	v_mfma_f32_16x16x32_bf16 v[136:139], v[132:135], v[148:151], v[136:139]
	v_mfma_f32_16x16x32_bf16 v[128:131], v[92:95], v[176:179], v[128:131]
	v_mfma_f32_16x16x32_bf16 v[124:127], v[132:135], v[176:179], v[124:127]
	v_mfma_f32_16x16x32_bf16 v[120:123], v[92:95], v[184:187], v[120:123]
	v_mfma_f32_16x16x32_bf16 v[116:119], v[132:135], v[184:187], v[116:119]
	v_mfma_f32_16x16x32_bf16 v[112:115], v[92:95], v[192:195], v[112:115]
	v_mfma_f32_16x16x32_bf16 v[108:111], v[132:135], v[192:195], v[108:111]
	v_mfma_f32_16x16x32_bf16 v[140:143], v[100:103], v[152:155], v[140:143]
	v_mfma_f32_16x16x32_bf16 v[136:139], v[144:147], v[152:155], v[136:139]
	v_mfma_f32_16x16x32_bf16 v[128:131], v[100:103], v[180:183], v[128:131]
	v_mfma_f32_16x16x32_bf16 v[124:127], v[144:147], v[180:183], v[124:127]
	v_mfma_f32_16x16x32_bf16 v[120:123], v[100:103], v[188:191], v[120:123]
	v_mfma_f32_16x16x32_bf16 v[116:119], v[144:147], v[188:191], v[116:119]
	v_mfma_f32_16x16x32_bf16 v[112:115], v[100:103], v[212:215], v[112:115]
	v_mfma_f32_16x16x32_bf16 v[108:111], v[144:147], v[212:215], v[108:111]
	s_setprio 0
	s_barrier
	s_add_i32 s46, 0, 0x14000
	s_add_i32 s44, s44, s29
	v_add_u32_e32 v2, s46, v167
	v_lshl_add_u64 v[196:197], s[6:7], 0, v[158:159]
	s_mov_b32 m0, s44
	ds_read_b128 v[216:219], v2
	ds_read_b128 v[220:223], v2 offset:1024
	ds_read_b128 v[224:227], v2 offset:2048
	ds_read_b128 v[228:231], v2 offset:3072
	global_load_lds_dwordx4 v[196:197], off
	v_lshl_add_u64 v[232:233], s[6:7], 0, v[0:1]
	s_add_i32 m0, s44, 0x2000
	s_nop 0
	global_load_lds_dwordx4 v[232:233], off
	s_barrier
	s_waitcnt lgkmcnt(0)
	s_setprio 1
	s_waitcnt lgkmcnt(0)
	v_mfma_f32_16x16x32_bf16 v[64:67], v[216:219], v[148:151], v[64:67]
	v_mfma_f32_16x16x32_bf16 v[60:63], v[224:227], v[148:151], v[60:63]
	v_mfma_f32_16x16x32_bf16 v[56:59], v[216:219], v[176:179], v[56:59]
	v_mfma_f32_16x16x32_bf16 v[52:55], v[224:227], v[176:179], v[52:55]
	v_mfma_f32_16x16x32_bf16 v[48:51], v[216:219], v[184:187], v[48:51]
	v_mfma_f32_16x16x32_bf16 v[44:47], v[224:227], v[184:187], v[44:47]
	v_mfma_f32_16x16x32_bf16 v[40:43], v[216:219], v[192:195], v[40:43]
	v_mfma_f32_16x16x32_bf16 v[36:39], v[224:227], v[192:195], v[36:39]
	v_mfma_f32_16x16x32_bf16 v[64:67], v[220:223], v[152:155], v[64:67]
	v_mfma_f32_16x16x32_bf16 v[60:63], v[228:231], v[152:155], v[60:63]
	v_mfma_f32_16x16x32_bf16 v[56:59], v[220:223], v[180:183], v[56:59]
	v_mfma_f32_16x16x32_bf16 v[52:55], v[228:231], v[180:183], v[52:55]
	v_mfma_f32_16x16x32_bf16 v[48:51], v[220:223], v[188:191], v[48:51]
	v_mfma_f32_16x16x32_bf16 v[44:47], v[228:231], v[188:191], v[44:47]
	v_mfma_f32_16x16x32_bf16 v[40:43], v[220:223], v[212:215], v[40:43]
	v_mfma_f32_16x16x32_bf16 v[36:39], v[228:231], v[212:215], v[36:39]
	s_setprio 0
	s_mov_b32 m0, s30
	v_lshl_add_u64 v[234:235], s[10:11], 0, v[160:161]
	s_barrier
	ds_read_b128 v[148:151], v169 offset:16384
	ds_read_b128 v[152:155], v169 offset:17408
	ds_read_b128 v[176:179], v169 offset:18432
	ds_read_b128 v[180:183], v169 offset:19456
	ds_read_b128 v[184:187], v169 offset:20480
	ds_read_b128 v[188:191], v169 offset:21504
	ds_read_b128 v[192:195], v169 offset:22528
	ds_read_b128 v[212:215], v169 offset:23552
	global_load_lds_dwordx4 v[234:235], off
	v_lshl_add_u64 v[236:237], s[10:11], 0, v[156:157]
	s_mov_b32 m0, s31
	s_nop 0
	global_load_lds_dwordx4 v[236:237], off
	s_barrier
	s_waitcnt lgkmcnt(0)
	s_setprio 1
	s_waitcnt lgkmcnt(0)
	v_mfma_f32_16x16x32_bf16 v[104:107], v[92:95], v[148:151], v[104:107]
	v_mfma_f32_16x16x32_bf16 v[96:99], v[132:135], v[148:151], v[96:99]
	v_mfma_f32_16x16x32_bf16 v[88:91], v[92:95], v[176:179], v[88:91]
	v_mfma_f32_16x16x32_bf16 v[84:87], v[132:135], v[176:179], v[84:87]
	v_mfma_f32_16x16x32_bf16 v[80:83], v[92:95], v[184:187], v[80:83]
	v_mfma_f32_16x16x32_bf16 v[76:79], v[132:135], v[184:187], v[76:79]
	v_mfma_f32_16x16x32_bf16 v[72:75], v[92:95], v[192:195], v[72:75]
	v_mfma_f32_16x16x32_bf16 v[68:71], v[132:135], v[192:195], v[68:71]
	v_mfma_f32_16x16x32_bf16 v[104:107], v[100:103], v[152:155], v[104:107]
	v_mfma_f32_16x16x32_bf16 v[96:99], v[144:147], v[152:155], v[96:99]
	v_mfma_f32_16x16x32_bf16 v[88:91], v[100:103], v[180:183], v[88:91]
	v_mfma_f32_16x16x32_bf16 v[84:87], v[144:147], v[180:183], v[84:87]
	v_mfma_f32_16x16x32_bf16 v[80:83], v[100:103], v[188:191], v[80:83]
	v_mfma_f32_16x16x32_bf16 v[76:79], v[144:147], v[188:191], v[76:79]
	v_mfma_f32_16x16x32_bf16 v[72:75], v[100:103], v[212:215], v[72:75]
	v_mfma_f32_16x16x32_bf16 v[68:71], v[144:147], v[212:215], v[68:71]
	s_setprio 0
	s_barrier
; #define PG8_WAIT_V(n) asm volatile("s_waitcnt vmcnt(" #n ")" ::: "memory")
; #define PG8_WAIT_L(n) asm volatile("s_waitcnt lgkmcnt(" #n ")" ::: "memory")
; #define PG8_BAR __builtin_amdgcn_s_barrier()
; #define PG8_SCHED __builtin_amdgcn_sched_barrier(0)
; template <class Epi, class AddrA, class AddrB>
; __device__ __forceinline__ void gemm_phase(const Sched S, const int lda, const int ldb, const int K, const AddrA addrA,
;                                            const AddrB addrB, const Epi E) {
;     ...
;       PG8_STAGE(PG8_SB(0, 1), b2 + hstepB, voffB);
;       PG8_WAIT_V(6); PG8_BAR; PG8_MMA(1, 1, At, B1); PG8_BAR;
;       PG8_LDB(B0, 1, 0); PG8_SCHED; PG8_LDA(At, 1, 0); PG8_STAGE(PG8_SA(0, 1), a2 + hstepA, voffA);
;       PG8_WAIT_L(8); PG8_BAR; PG8_WAIT_L(0); PG8_MMA(0, 0, At, B0); PG8_BAR; PG8_SCHED;
;       PG8_LDB(B1, 1, 1); PG8_STAGE(PG8_SB(1, 0), b3, voffB);
;       PG8_BAR; PG8_WAIT_L(0); PG8_MMA(0, 1, At, B1); PG8_BAR;
;       PG8_LDA(At, 1, 1); PG8_STAGE(PG8_SA(1, 0), a3, voffA);
;       PG8_BAR; PG8_WAIT_L(0); PG8_MMA(1, 0, At, B0); PG8_BAR; PG8_SCHED;
	s_add_u32 s44, s6, 0x20000
	s_addc_u32 s45, s7, 0
	s_add_i32 s46, s46, s29
	v_lshl_add_u64 v[92:93], s[44:45], 0, v[158:159]
	s_mov_b32 m0, s46
	s_nop 0
	global_load_lds_dwordx4 v[92:93], off
	v_lshl_add_u64 v[92:93], s[44:45], 0, v[0:1]
	s_add_i32 m0, s46, 0x2000
	s_nop 0
	global_load_lds_dwordx4 v[92:93], off
	s_waitcnt vmcnt(6)
	s_barrier
	s_setprio 1
	v_mfma_f32_16x16x32_bf16 v[32:35], v[216:219], v[148:151], v[32:35]
	v_mfma_f32_16x16x32_bf16 v[28:31], v[224:227], v[148:151], v[28:31]
	v_mfma_f32_16x16x32_bf16 v[24:27], v[216:219], v[176:179], v[24:27]
	v_mfma_f32_16x16x32_bf16 v[20:23], v[224:227], v[176:179], v[20:23]
	v_mfma_f32_16x16x32_bf16 v[16:19], v[216:219], v[184:187], v[16:19]
	v_mfma_f32_16x16x32_bf16 v[12:15], v[224:227], v[184:187], v[12:15]
	v_mfma_f32_16x16x32_bf16 v[8:11], v[216:219], v[192:195], v[8:11]
	v_mfma_f32_16x16x32_bf16 v[4:7], v[224:227], v[192:195], v[4:7]
	v_mfma_f32_16x16x32_bf16 v[32:35], v[220:223], v[152:155], v[32:35]
	v_mfma_f32_16x16x32_bf16 v[28:31], v[228:231], v[152:155], v[28:31]
	v_mfma_f32_16x16x32_bf16 v[24:27], v[220:223], v[180:183], v[24:27]
	v_mfma_f32_16x16x32_bf16 v[20:23], v[228:231], v[180:183], v[20:23]
	v_mfma_f32_16x16x32_bf16 v[16:19], v[220:223], v[188:191], v[16:19]
	v_mfma_f32_16x16x32_bf16 v[12:15], v[228:231], v[188:191], v[12:15]
	v_mfma_f32_16x16x32_bf16 v[8:11], v[220:223], v[212:215], v[8:11]
	v_mfma_f32_16x16x32_bf16 v[4:7], v[228:231], v[212:215], v[4:7]
	s_setprio 0
	s_add_i32 s44, 0, 0x18000
	v_add_u32_e32 v2, s44, v167
	s_barrier
	ds_read_b128 v[92:95], v2
	ds_read_b128 v[100:103], v2 offset:1024
	ds_read_b128 v[132:135], v2 offset:2048
	ds_read_b128 v[144:147], v2 offset:3072
	s_add_u32 s10, s10, 0x80000
	s_addc_u32 s11, s11, 0
	s_mov_b32 m0, s34
	v_lshl_add_u64 v[216:217], s[10:11], 0, v[160:161]
	ds_read_b128 v[148:151], v169 offset:32768
	ds_read_b128 v[152:155], v169 offset:33792
	ds_read_b128 v[176:179], v169 offset:34816
	ds_read_b128 v[180:183], v169 offset:35840
	ds_read_b128 v[184:187], v169 offset:36864
	ds_read_b128 v[188:191], v169 offset:37888
	ds_read_b128 v[192:195], v169 offset:38912
	ds_read_b128 v[212:215], v169 offset:39936
	global_load_lds_dwordx4 v[216:217], off
	v_lshl_add_u64 v[216:217], s[10:11], 0, v[156:157]
	s_mov_b32 m0, s35
	s_nop 0
	global_load_lds_dwordx4 v[216:217], off
	s_waitcnt lgkmcnt(8)
	s_barrier
	s_waitcnt lgkmcnt(0)
	s_setprio 1
	s_waitcnt lgkmcnt(0)
	v_mfma_f32_16x16x32_bf16 v[140:143], v[92:95], v[148:151], v[140:143]
	v_mfma_f32_16x16x32_bf16 v[136:139], v[132:135], v[148:151], v[136:139]
	v_mfma_f32_16x16x32_bf16 v[128:131], v[92:95], v[176:179], v[128:131]
	v_mfma_f32_16x16x32_bf16 v[124:127], v[132:135], v[176:179], v[124:127]
	v_mfma_f32_16x16x32_bf16 v[120:123], v[92:95], v[184:187], v[120:123]
	v_mfma_f32_16x16x32_bf16 v[116:119], v[132:135], v[184:187], v[116:119]
	v_mfma_f32_16x16x32_bf16 v[112:115], v[92:95], v[192:195], v[112:115]
	v_mfma_f32_16x16x32_bf16 v[108:111], v[132:135], v[192:195], v[108:111]
	v_mfma_f32_16x16x32_bf16 v[140:143], v[100:103], v[152:155], v[140:143]
	v_mfma_f32_16x16x32_bf16 v[136:139], v[144:147], v[152:155], v[136:139]
	v_mfma_f32_16x16x32_bf16 v[128:131], v[100:103], v[180:183], v[128:131]
	v_mfma_f32_16x16x32_bf16 v[124:127], v[144:147], v[180:183], v[124:127]
	v_mfma_f32_16x16x32_bf16 v[120:123], v[100:103], v[188:191], v[120:123]
	v_mfma_f32_16x16x32_bf16 v[116:119], v[144:147], v[188:191], v[116:119]
	v_mfma_f32_16x16x32_bf16 v[112:115], v[100:103], v[212:215], v[112:115]
	v_mfma_f32_16x16x32_bf16 v[108:111], v[144:147], v[212:215], v[108:111]
	s_setprio 0
	s_barrier
	s_add_i32 s10, 0, 0x1c000
	s_add_i32 s11, s44, s29
	v_add_u32_e32 v2, s10, v167
	v_lshl_add_u64 v[196:197], v[196:197], 0, s[52:53]
	s_mov_b32 m0, s11
	ds_read_b128 v[216:219], v2
	ds_read_b128 v[220:223], v2 offset:1024
	ds_read_b128 v[224:227], v2 offset:2048
	ds_read_b128 v[228:231], v2 offset:3072
	global_load_lds_dwordx4 v[196:197], off
	v_lshl_add_u64 v[196:197], v[232:233], 0, s[52:53]
	s_add_i32 m0, s11, 0x2000
	s_nop 0
	global_load_lds_dwordx4 v[196:197], off
	s_barrier
	s_waitcnt lgkmcnt(0)
	s_setprio 1
	s_waitcnt lgkmcnt(0)
	v_mfma_f32_16x16x32_bf16 v[64:67], v[216:219], v[148:151], v[64:67]
	v_mfma_f32_16x16x32_bf16 v[60:63], v[224:227], v[148:151], v[60:63]
	v_mfma_f32_16x16x32_bf16 v[56:59], v[216:219], v[176:179], v[56:59]
	v_mfma_f32_16x16x32_bf16 v[52:55], v[224:227], v[176:179], v[52:55]
	v_mfma_f32_16x16x32_bf16 v[48:51], v[216:219], v[184:187], v[48:51]
	v_mfma_f32_16x16x32_bf16 v[44:47], v[224:227], v[184:187], v[44:47]
	v_mfma_f32_16x16x32_bf16 v[40:43], v[216:219], v[192:195], v[40:43]
	v_mfma_f32_16x16x32_bf16 v[36:39], v[224:227], v[192:195], v[36:39]
	v_mfma_f32_16x16x32_bf16 v[64:67], v[220:223], v[152:155], v[64:67]
	v_mfma_f32_16x16x32_bf16 v[60:63], v[228:231], v[152:155], v[60:63]
	v_mfma_f32_16x16x32_bf16 v[56:59], v[220:223], v[180:183], v[56:59]
	v_mfma_f32_16x16x32_bf16 v[52:55], v[228:231], v[180:183], v[52:55]
	v_mfma_f32_16x16x32_bf16 v[48:51], v[220:223], v[188:191], v[48:51]
	v_mfma_f32_16x16x32_bf16 v[44:47], v[228:231], v[188:191], v[44:47]
	v_mfma_f32_16x16x32_bf16 v[40:43], v[220:223], v[212:215], v[40:43]
	v_mfma_f32_16x16x32_bf16 v[36:39], v[228:231], v[212:215], v[36:39]
	s_setprio 0
	s_mov_b32 m0, s37
	v_lshl_add_u64 v[196:197], v[234:235], 0, s[52:53]
	s_barrier
	ds_read_b128 v[148:151], v169 offset:49152
	ds_read_b128 v[152:155], v169 offset:50176
	ds_read_b128 v[176:179], v169 offset:51200
	ds_read_b128 v[180:183], v169 offset:52224
	ds_read_b128 v[184:187], v169 offset:53248
	ds_read_b128 v[188:191], v169 offset:54272
	ds_read_b128 v[192:195], v169 offset:55296
	ds_read_b128 v[212:215], v169 offset:56320
	global_load_lds_dwordx4 v[196:197], off
	v_lshl_add_u64 v[196:197], v[236:237], 0, s[52:53]
	s_mov_b32 m0, s38
	s_nop 0
	global_load_lds_dwordx4 v[196:197], off
	s_barrier
; __device__ __forceinline__ size_t pidx(size_t row, int col) { return ((size_t)(col >> 8) * MTOK + row) * PLD + (col & 255); }
; __device__ __forceinline__ float bflo(unsigned v) { return __uint_as_float(v << 16); }
; __device__ __forceinline__ float bfhi(unsigned v) { return __uint_as_float(v & 0xffff0000u); }
; __device__ __forceinline__ float siluf_(float x) { return x * __builtin_amdgcn_rcpf(1.0f + __expf(-x)); }
; #define PG8_WAIT_V(n) asm volatile("s_waitcnt vmcnt(" #n ")" ::: "memory")
; #define PG8_WAIT_L(n) asm volatile("s_waitcnt lgkmcnt(" #n ")" ::: "memory")
; #define PG8_BAR __builtin_amdgcn_s_barrier()
; #define PG8_SCHED __builtin_amdgcn_sched_barrier(0)
; template <class Epi, class AddrA, class AddrB>
; __device__ __forceinline__ void gemm_phase(const Sched S, const int lda, const int ldb, const int K, const AddrA addrA,
;                                            const AddrB addrB, const Epi E) {
;     ...
;       PG8_BAR; PG8_WAIT_L(0); PG8_MMA(1, 0, At, B0); PG8_BAR; PG8_SCHED;
;       PG8_STAGE(PG8_SB(1, 1), b3 + hstepB, voffB);
;       PG8_WAIT_V(6); PG8_BAR; PG8_MMA(1, 1, At, B1); PG8_BAR;
;   __device__ __forceinline__ void operator()(EPI_ARGS) const {
;     const size_t row0 = (size_t)u.pm * 256 + wr * 64 + fr;
;     const int col0 = u.pn * 256 + wc * 32 + 8 * fq;
; #pragma unroll
;     for (int bj = 0; bj < 2; ++bj) {
;       const int c = col0 + bj * HALF;
;       const f32x4 s0 = *(const f32x4*)(psc + c), s1 = *(const f32x4*)(psc + c + 4);
; #pragma unroll
;       for (int ai = 0; ai < 2; ++ai) {
;         u32x4 z[4];
; #pragma unroll
;         for (int m = 0; m < 4; ++m) z[m] = *(const u32x4*)(proj + pidx(row0 + ai * HALF + m * 16, PZ + c));
;         __builtin_amdgcn_sched_barrier(0);
; #pragma unroll
;         for (int m = 0; m < 4; ++m) {
;           const size_t row = row0 + ai * HALF + m * 16;
;           const f32x4 v0 = acc[ai][bj][m][0], v1 = acc[ai][bj][m][1];
;           u32x4 o;
;           o.x = pack2(v0[0] * s0[0] * siluf_(bflo(z[m].x)), v0[1] * s0[1] * siluf_(bfhi(z[m].x)));
;           o.y = pack2(v0[2] * s0[2] * siluf_(bflo(z[m].y)), v0[3] * s0[3] * siluf_(bfhi(z[m].y)));
;           o.z = pack2(v1[0] * s1[0] * siluf_(bflo(z[m].z)), v1[1] * s1[1] * siluf_(bfhi(z[m].z)));
;           o.w = pack2(v1[2] * s1[2] * siluf_(bflo(z[m].w)), v1[3] * s1[3] * siluf_(bfhi(z[m].w)));
	s_waitcnt lgkmcnt(0)
	s_setprio 1
	s_waitcnt lgkmcnt(0)
	v_mfma_f32_16x16x32_bf16 v[104:107], v[92:95], v[148:151], v[104:107]
	v_mfma_f32_16x16x32_bf16 v[96:99], v[132:135], v[148:151], v[96:99]
	v_mfma_f32_16x16x32_bf16 v[88:91], v[92:95], v[176:179], v[88:91]
	v_mfma_f32_16x16x32_bf16 v[84:87], v[132:135], v[176:179], v[84:87]
	v_mfma_f32_16x16x32_bf16 v[80:83], v[92:95], v[184:187], v[80:83]
	v_mfma_f32_16x16x32_bf16 v[76:79], v[132:135], v[184:187], v[76:79]
	v_mfma_f32_16x16x32_bf16 v[72:75], v[92:95], v[192:195], v[72:75]
	v_mfma_f32_16x16x32_bf16 v[68:71], v[132:135], v[192:195], v[68:71]
	v_mfma_f32_16x16x32_bf16 v[104:107], v[100:103], v[152:155], v[104:107]
	v_mfma_f32_16x16x32_bf16 v[96:99], v[144:147], v[152:155], v[96:99]
	v_mfma_f32_16x16x32_bf16 v[88:91], v[100:103], v[180:183], v[88:91]
	v_mfma_f32_16x16x32_bf16 v[84:87], v[144:147], v[180:183], v[84:87]
	v_mfma_f32_16x16x32_bf16 v[80:83], v[100:103], v[188:191], v[80:83]
	v_mfma_f32_16x16x32_bf16 v[76:79], v[144:147], v[188:191], v[76:79]
	v_mfma_f32_16x16x32_bf16 v[72:75], v[100:103], v[212:215], v[72:75]
	v_mfma_f32_16x16x32_bf16 v[68:71], v[144:147], v[212:215], v[68:71]
	s_setprio 0
	s_barrier
	s_add_u32 s6, s6, 0x20080
	s_addc_u32 s7, s7, 0
	s_add_i32 s10, s10, s29
	v_lshl_add_u64 v[92:93], s[6:7], 0, v[158:159]
	s_mov_b32 m0, s10
	s_nop 0
	global_load_lds_dwordx4 v[92:93], off
	v_lshl_add_u64 v[92:93], s[6:7], 0, v[0:1]
	s_add_i32 m0, s10, 0x2000
	s_nop 0
	global_load_lds_dwordx4 v[92:93], off
	s_waitcnt vmcnt(6)
	s_barrier
	s_setprio 1
	v_mfma_f32_16x16x32_bf16 v[32:35], v[216:219], v[148:151], v[32:35]
	v_mfma_f32_16x16x32_bf16 v[28:31], v[224:227], v[148:151], v[28:31]
	v_mfma_f32_16x16x32_bf16 v[24:27], v[216:219], v[176:179], v[24:27]
	v_mfma_f32_16x16x32_bf16 v[20:23], v[224:227], v[176:179], v[20:23]
	v_mfma_f32_16x16x32_bf16 v[16:19], v[216:219], v[184:187], v[16:19]
	v_mfma_f32_16x16x32_bf16 v[12:15], v[224:227], v[184:187], v[12:15]
	v_mfma_f32_16x16x32_bf16 v[8:11], v[216:219], v[192:195], v[8:11]
	v_mfma_f32_16x16x32_bf16 v[4:7], v[224:227], v[192:195], v[4:7]
	v_mfma_f32_16x16x32_bf16 v[32:35], v[220:223], v[152:155], v[32:35]
	v_mfma_f32_16x16x32_bf16 v[28:31], v[228:231], v[152:155], v[28:31]
	v_mfma_f32_16x16x32_bf16 v[24:27], v[220:223], v[180:183], v[24:27]
	v_mfma_f32_16x16x32_bf16 v[20:23], v[228:231], v[180:183], v[20:23]
	v_mfma_f32_16x16x32_bf16 v[16:19], v[220:223], v[188:191], v[16:19]
	v_mfma_f32_16x16x32_bf16 v[12:15], v[228:231], v[188:191], v[12:15]
	v_mfma_f32_16x16x32_bf16 v[8:11], v[220:223], v[212:215], v[8:11]
	v_mfma_f32_16x16x32_bf16 v[4:7], v[228:231], v[212:215], v[4:7]
	s_setprio 0
	s_add_i32 s43, s43, 2
	s_add_u32 s41, s41, 0x100
	s_addc_u32 s42, s42, 0
	s_add_u32 s4, s4, 0x100
	s_addc_u32 s5, s5, 0
	s_cmp_gt_u32 s43, 5
	s_barrier
	s_cbranch_scc0 .LBB0_485
	s_ashr_i32 s3, s2, 31
	s_lshl_b64 s[2:3], s[2:3], 8
	v_lshl_add_u64 v[186:187], s[2:3], 0, v[162:163]
	s_lshl_b32 s2, s33, 8
	v_or_b32_e32 v196, s2, v168
	s_addk_i32 s2, 0x800
	s_ashr_i32 s2, s2, 8
	s_ashr_i32 s3, s2, 31
	s_lshl_b64 s[2:3], s[2:3], 23
	s_add_u32 s2, s0, s2
	s_addc_u32 s3, s1, s3
	v_lshlrev_b32_e32 v2, 1, v168
	v_or_b32_e32 v194, 16, v186
	v_mov_b32_e32 v195, v187
	v_ashrrev_i32_e32 v197, 31, v196
	v_lshl_add_u64 v[188:189], s[2:3], 0, v[2:3]
	v_lshlrev_b64 v[178:179], 9, v[186:187]
	v_lshlrev_b64 v[180:181], 9, v[194:195]
	v_or_b32_e32 v192, 32, v186
	v_mov_b32_e32 v193, v187
	v_or_b32_e32 v190, 48, v186
	v_mov_b32_e32 v191, v187
	v_lshl_add_u64 v[176:177], v[196:197], 2, s[12:13]
	v_lshl_add_u64 v[132:133], v[188:189], 0, v[178:179]
	v_lshl_add_u64 v[134:135], v[188:189], 0, v[180:181]
	v_lshlrev_b64 v[182:183], 9, v[192:193]
	v_lshlrev_b64 v[184:185], 9, v[190:191]
	global_load_dwordx4 v[92:95], v[176:177], off offset:16
	global_load_dwordx4 v[100:103], v[176:177], off
	global_load_dwordx4 v[152:155], v[132:133], off
	global_load_dwordx4 v[148:151], v[134:135], off
	v_lshl_add_u64 v[132:133], v[188:189], 0, v[182:183]
	v_lshl_add_u64 v[134:135], v[188:189], 0, v[184:185]
	global_load_dwordx4 v[144:147], v[132:133], off
	s_nop 0
	global_load_dwordx4 v[132:135], v[134:135], off
	s_waitcnt vmcnt(0) lgkmcnt(0)
	v_lshlrev_b32_e32 v213, 16, v152
	v_mul_f32_e32 v2, 0xbfb8aa3b, v213
	v_exp_f32_e32 v2, v2
	v_mov_b32_e32 v214, v140
	v_mov_b32_e32 v212, v100
	s_mov_b64 s[4:5], 0x90
	v_add_f32_e32 v2, 1.0, v2
	v_rcp_f32_e32 v215, v2
	s_nop 0
	v_pk_mul_f32 v[212:213], v[214:215], v[212:213]
	s_nop 0
	v_mul_f32_e32 v2, v212, v213
	v_and_b32_e32 v213, 0xffff0000, v152
	v_mul_f32_e32 v140, 0xbfb8aa3b, v213
	v_exp_f32_e32 v140, v140
	v_mov_b32_e32 v214, v141
	v_mov_b32_e32 v212, v101
	v_add_f32_e32 v140, 1.0, v140
	v_rcp_f32_e32 v215, v140
	s_nop 0
	v_pk_mul_f32 v[140:141], v[214:215], v[212:213]
	s_nop 0
	v_mul_f32_e32 v140, v140, v141
	v_lshlrev_b32_e32 v141, 16, v153
	v_cvt_pk_bf16_f32 v152, v2, v140
	v_mul_f32_e32 v2, 0xbfb8aa3b, v141
	v_exp_f32_e32 v2, v2
	v_mov_b32_e32 v212, v142
	v_mov_b32_e32 v140, v102
	v_mov_b32_e32 v142, v136
	v_add_f32_e32 v2, 1.0, v2
	v_rcp_f32_e32 v213, v2
	s_nop 0
	v_pk_mul_f32 v[140:141], v[212:213], v[140:141]
	s_nop 0
	v_mul_f32_e32 v2, v140, v141
	v_and_b32_e32 v141, 0xffff0000, v153
	v_mul_f32_e32 v140, 0xbfb8aa3b, v141
	v_exp_f32_e32 v140, v140
	v_mov_b32_e32 v212, v143
	v_add_f32_e32 v140, 1.0, v140
	v_rcp_f32_e32 v213, v140
	v_mov_b32_e32 v140, v103
	v_pk_mul_f32 v[140:141], v[212:213], v[140:141]
	s_nop 0
	v_mul_f32_e32 v140, v140, v141
	v_lshlrev_b32_e32 v141, 16, v154
	v_cvt_pk_bf16_f32 v153, v2, v140
	v_mul_f32_e32 v2, 0xbfb8aa3b, v141
	v_exp_f32_e32 v2, v2
	v_mov_b32_e32 v140, v92
	v_add_f32_e32 v2, 1.0, v2
	v_rcp_f32_e32 v143, v2
; __device__ __forceinline__ size_t pidx(size_t row, int col) { return ((size_t)(col >> 8) * MTOK + row) * PLD + (col & 255); }
; __device__ __forceinline__ float bflo(unsigned v) { return __uint_as_float(v << 16); }
; __device__ __forceinline__ float bfhi(unsigned v) { return __uint_as_float(v & 0xffff0000u); }
; __device__ __forceinline__ float siluf_(float x) { return x * __builtin_amdgcn_rcpf(1.0f + __expf(-x)); }
;   __device__ __forceinline__ void operator()(EPI_ARGS) const {
;     ...
;     for (int bj = 0; bj < 2; ++bj) {
;       const int c = col0 + bj * HALF;
;       const f32x4 s0 = *(const f32x4*)(psc + c), s1 = *(const f32x4*)(psc + c + 4);
; #pragma unroll
;       for (int ai = 0; ai < 2; ++ai) {
;         u32x4 z[4];
; #pragma unroll
;         for (int m = 0; m < 4; ++m) z[m] = *(const u32x4*)(proj + pidx(row0 + ai * HALF + m * 16, PZ + c));
;         __builtin_amdgcn_sched_barrier(0);
; #pragma unroll
;         for (int m = 0; m < 4; ++m) {
;           const size_t row = row0 + ai * HALF + m * 16;
;           const f32x4 v0 = acc[ai][bj][m][0], v1 = acc[ai][bj][m][1];
;           u32x4 o;
;           o.x = pack2(v0[0] * s0[0] * siluf_(bflo(z[m].x)), v0[1] * s0[1] * siluf_(bfhi(z[m].x)));
;           o.y = pack2(v0[2] * s0[2] * siluf_(bflo(z[m].y)), v0[3] * s0[3] * siluf_(bfhi(z[m].y)));
;           o.z = pack2(v1[0] * s1[0] * siluf_(bflo(z[m].z)), v1[1] * s1[1] * siluf_(bfhi(z[m].z)));
;           o.w = pack2(v1[2] * s1[2] * siluf_(bflo(z[m].w)), v1[3] * s1[3] * siluf_(bfhi(z[m].w)));
;           *(u32x4*)(y0 + row * DM + c) = o;
;         }
	s_nop 0
	v_pk_mul_f32 v[140:141], v[142:143], v[140:141]
	s_nop 0
	v_mul_f32_e32 v2, v140, v141
	v_and_b32_e32 v141, 0xffff0000, v154
	v_mul_f32_e32 v136, 0xbfb8aa3b, v141
	v_exp_f32_e32 v136, v136
	v_mov_b32_e32 v142, v137
	v_mov_b32_e32 v140, v93
	v_add_f32_e32 v136, 1.0, v136
	v_rcp_f32_e32 v143, v136
	s_nop 0
	v_pk_mul_f32 v[136:137], v[142:143], v[140:141]
	s_nop 0
	v_mul_f32_e32 v136, v136, v137
	v_lshlrev_b32_e32 v137, 16, v155
	v_cvt_pk_bf16_f32 v154, v2, v136
	v_mul_f32_e32 v2, 0xbfb8aa3b, v137
	v_exp_f32_e32 v2, v2
	v_mov_b32_e32 v140, v138
	v_mov_b32_e32 v136, v94
	v_mov_b32_e32 v142, v128
	v_add_f32_e32 v2, 1.0, v2
	v_rcp_f32_e32 v141, v2
	v_mov_b32_e32 v138, v100
	v_pk_mul_f32 v[136:137], v[140:141], v[136:137]
	s_nop 0
	v_mul_f32_e32 v2, v136, v137
	v_and_b32_e32 v137, 0xffff0000, v155
	v_mul_f32_e32 v136, 0xbfb8aa3b, v137
	v_exp_f32_e32 v136, v136
	v_mov_b32_e32 v140, v139
	v_lshlrev_b32_e32 v139, 16, v148
	v_add_f32_e32 v136, 1.0, v136
	v_rcp_f32_e32 v141, v136
	v_mov_b32_e32 v136, v95
	v_pk_mul_f32 v[136:137], v[140:141], v[136:137]
	s_nop 0
	v_mul_f32_e32 v136, v136, v137
	v_cvt_pk_bf16_f32 v155, v2, v136
	v_mul_f32_e32 v2, 0xbfb8aa3b, v139
	v_exp_f32_e32 v2, v2
	v_lshlrev_b64 v[140:141], 1, v[196:197]
	v_lshlrev_b64 v[136:137], 12, v[186:187]
	v_lshl_add_u64 v[136:137], s[8:9], 0, v[136:137]
	v_add_f32_e32 v2, 1.0, v2
	v_rcp_f32_e32 v143, v2
	v_lshl_add_u64 v[136:137], v[136:137], 0, v[140:141]
	global_store_dwordx4 v[136:137], v[152:155], off
	v_pk_mul_f32 v[138:139], v[142:143], v[138:139]
	s_nop 0
	v_mul_f32_e32 v2, v138, v139
	v_and_b32_e32 v139, 0xffff0000, v148
	v_mul_f32_e32 v128, 0xbfb8aa3b, v139
	v_exp_f32_e32 v128, v128
	v_mov_b32_e32 v142, v129
	v_mov_b32_e32 v138, v101
	v_add_f32_e32 v128, 1.0, v128
	v_rcp_f32_e32 v143, v128
	s_nop 0
	v_pk_mul_f32 v[128:129], v[142:143], v[138:139]
	s_nop 0
	v_mul_f32_e32 v128, v128, v129
	v_lshlrev_b32_e32 v139, 16, v149
	v_cvt_pk_bf16_f32 v128, v2, v128
	v_mul_f32_e32 v2, 0xbfb8aa3b, v139
	v_exp_f32_e32 v2, v2
	v_mov_b32_e32 v142, v130
	v_mov_b32_e32 v138, v102
	v_add_f32_e32 v2, 1.0, v2
	v_rcp_f32_e32 v143, v2
	s_nop 0
	v_pk_mul_f32 v[138:139], v[142:143], v[138:139]
	s_nop 0
	v_mul_f32_e32 v2, v138, v139
	v_and_b32_e32 v139, 0xffff0000, v149
	v_mul_f32_e32 v129, 0xbfb8aa3b, v139
	v_exp_f32_e32 v129, v129
	v_mov_b32_e32 v142, v131
	v_mov_b32_e32 v138, v103
	v_lshl_add_u64 v[148:149], v[186:187], 0, s[52:53]
	v_add_f32_e32 v129, 1.0, v129
	v_rcp_f32_e32 v143, v129
	s_nop 0
	v_pk_mul_f32 v[130:131], v[142:143], v[138:139]
	s_nop 0
	v_mul_f32_e32 v129, v130, v131
	v_lshlrev_b32_e32 v131, 16, v150
	v_cvt_pk_bf16_f32 v129, v2, v129
	v_mul_f32_e32 v2, 0xbfb8aa3b, v131
	v_exp_f32_e32 v2, v2
	v_mov_b32_e32 v138, v124
	v_mov_b32_e32 v130, v92
	v_add_f32_e32 v2, 1.0, v2
	v_rcp_f32_e32 v139, v2
	s_nop 0
	v_pk_mul_f32 v[130:131], v[138:139], v[130:131]
	s_nop 0
	v_mul_f32_e32 v2, v130, v131
	v_and_b32_e32 v131, 0xffff0000, v150
	v_mul_f32_e32 v124, 0xbfb8aa3b, v131
	v_exp_f32_e32 v124, v124
	v_mov_b32_e32 v138, v125
	v_mov_b32_e32 v130, v93
	v_add_f32_e32 v124, 1.0, v124
	v_rcp_f32_e32 v139, v124
	s_nop 0
	v_pk_mul_f32 v[124:125], v[138:139], v[130:131]
	s_nop 0
	v_mul_f32_e32 v124, v124, v125
	v_lshlrev_b32_e32 v125, 16, v151
	v_cvt_pk_bf16_f32 v130, v2, v124
	v_mul_f32_e32 v2, 0xbfb8aa3b, v125
	v_exp_f32_e32 v2, v2
	v_mov_b32_e32 v138, v126
	v_mov_b32_e32 v124, v94
	v_mov_b32_e32 v126, v100
	v_add_f32_e32 v2, 1.0, v2
	v_rcp_f32_e32 v139, v2
	s_nop 0
	v_pk_mul_f32 v[124:125], v[138:139], v[124:125]
	s_nop 0
	v_mul_f32_e32 v2, v124, v125
	v_and_b32_e32 v125, 0xffff0000, v151
	v_mul_f32_e32 v124, 0xbfb8aa3b, v125
	v_exp_f32_e32 v124, v124
	v_mov_b32_e32 v138, v127
	v_lshlrev_b32_e32 v127, 16, v144
	v_add_f32_e32 v124, 1.0, v124
	v_rcp_f32_e32 v139, v124
	v_mov_b32_e32 v124, v95
	v_pk_mul_f32 v[124:125], v[138:139], v[124:125]
	s_nop 0
	v_mul_f32_e32 v124, v124, v125
	v_cvt_pk_bf16_f32 v131, v2, v124
	v_mul_f32_e32 v2, 0xbfb8aa3b, v127
	v_exp_f32_e32 v2, v2
	v_lshlrev_b64 v[124:125], 12, v[194:195]
	v_lshl_add_u64 v[124:125], s[8:9], 0, v[124:125]
	v_lshl_add_u64 v[124:125], v[124:125], 0, v[140:141]
	v_add_f32_e32 v2, 1.0, v2
	global_store_dwordx4 v[124:125], v[128:131], off
	s_nop 1
	v_rcp_f32_e32 v129, v2
	v_mov_b32_e32 v128, v120
	v_lshlrev_b64 v[130:131], 9, v[148:149]
	v_pk_mul_f32 v[126:127], v[128:129], v[126:127]
	s_nop 0
	v_mul_f32_e32 v2, v126, v127
	v_and_b32_e32 v127, 0xffff0000, v144
	v_mul_f32_e32 v120, 0xbfb8aa3b, v127
	v_exp_f32_e32 v120, v120
	v_mov_b32_e32 v128, v121
	v_mov_b32_e32 v126, v101
	v_add_f32_e32 v120, 1.0, v120
	v_rcp_f32_e32 v129, v120
	s_nop 0
	v_pk_mul_f32 v[120:121], v[128:129], v[126:127]
	s_nop 0
	v_mul_f32_e32 v120, v120, v121
	v_lshlrev_b32_e32 v127, 16, v145
	v_cvt_pk_bf16_f32 v120, v2, v120
	v_mul_f32_e32 v2, 0xbfb8aa3b, v127
	v_exp_f32_e32 v2, v2
	v_mov_b32_e32 v128, v122
	v_mov_b32_e32 v126, v102
	v_add_f32_e32 v2, 1.0, v2
	v_rcp_f32_e32 v129, v2
	s_nop 0
	v_pk_mul_f32 v[126:127], v[128:129], v[126:127]
	s_nop 0
	v_mul_f32_e32 v2, v126, v127
	v_and_b32_e32 v127, 0xffff0000, v145
	v_mul_f32_e32 v121, 0xbfb8aa3b, v127
	v_exp_f32_e32 v121, v121
	v_mov_b32_e32 v128, v123
	v_mov_b32_e32 v126, v103
	v_add_f32_e32 v121, 1.0, v121
	v_rcp_f32_e32 v129, v121
	s_nop 0
	v_pk_mul_f32 v[122:123], v[128:129], v[126:127]
	s_nop 0
	v_mul_f32_e32 v121, v122, v123
	v_lshlrev_b32_e32 v123, 16, v146
	v_cvt_pk_bf16_f32 v121, v2, v121
	v_mul_f32_e32 v2, 0xbfb8aa3b, v123
	v_exp_f32_e32 v2, v2
	v_mov_b32_e32 v126, v116
	v_mov_b32_e32 v122, v92
	v_add_f32_e32 v2, 1.0, v2
	v_rcp_f32_e32 v127, v2
	s_nop 0
	v_pk_mul_f32 v[122:123], v[126:127], v[122:123]
	s_nop 0
; __device__ __forceinline__ size_t pidx(size_t row, int col) { return ((size_t)(col >> 8) * MTOK + row) * PLD + (col & 255); }
; __device__ __forceinline__ float bflo(unsigned v) { return __uint_as_float(v << 16); }
; __device__ __forceinline__ float bfhi(unsigned v) { return __uint_as_float(v & 0xffff0000u); }
; __device__ __forceinline__ float siluf_(float x) { return x * __builtin_amdgcn_rcpf(1.0f + __expf(-x)); }
;   __device__ __forceinline__ void operator()(EPI_ARGS) const {
;     ...
;       for (int ai = 0; ai < 2; ++ai) {
;         u32x4 z[4];
; #pragma unroll
;         for (int m = 0; m < 4; ++m) z[m] = *(const u32x4*)(proj + pidx(row0 + ai * HALF + m * 16, PZ + c));
;         __builtin_amdgcn_sched_barrier(0);
; #pragma unroll
;         for (int m = 0; m < 4; ++m) {
;           const size_t row = row0 + ai * HALF + m * 16;
;           const f32x4 v0 = acc[ai][bj][m][0], v1 = acc[ai][bj][m][1];
;           u32x4 o;
;           o.x = pack2(v0[0] * s0[0] * siluf_(bflo(z[m].x)), v0[1] * s0[1] * siluf_(bfhi(z[m].x)));
;           o.y = pack2(v0[2] * s0[2] * siluf_(bflo(z[m].y)), v0[3] * s0[3] * siluf_(bfhi(z[m].y)));
;           o.z = pack2(v1[0] * s1[0] * siluf_(bflo(z[m].z)), v1[1] * s1[1] * siluf_(bfhi(z[m].z)));
;           o.w = pack2(v1[2] * s1[2] * siluf_(bflo(z[m].w)), v1[3] * s1[3] * siluf_(bfhi(z[m].w)));
;           *(u32x4*)(y0 + row * DM + c) = o;
;         }
	v_mul_f32_e32 v2, v122, v123
	v_and_b32_e32 v123, 0xffff0000, v146
	v_mul_f32_e32 v116, 0xbfb8aa3b, v123
	v_exp_f32_e32 v116, v116
	v_mov_b32_e32 v126, v117
	v_mov_b32_e32 v122, v93
	v_add_f32_e32 v116, 1.0, v116
	v_rcp_f32_e32 v127, v116
	s_nop 0
	v_pk_mul_f32 v[116:117], v[126:127], v[122:123]
	s_nop 0
	v_mul_f32_e32 v116, v116, v117
	v_lshlrev_b32_e32 v117, 16, v147
	v_cvt_pk_bf16_f32 v122, v2, v116
	v_mul_f32_e32 v2, 0xbfb8aa3b, v117
	v_exp_f32_e32 v2, v2
	v_mov_b32_e32 v126, v118
	v_mov_b32_e32 v116, v94
	v_mov_b32_e32 v118, v112
	v_add_f32_e32 v2, 1.0, v2
	v_rcp_f32_e32 v127, v2
	s_nop 0
	v_pk_mul_f32 v[116:117], v[126:127], v[116:117]
	s_nop 0
	v_mul_f32_e32 v2, v116, v117
	v_and_b32_e32 v117, 0xffff0000, v147
	v_mul_f32_e32 v116, 0xbfb8aa3b, v117
	v_exp_f32_e32 v116, v116
	v_mov_b32_e32 v126, v119
	v_lshl_add_u64 v[146:147], v[186:187], 0, s[4:5]
	s_mov_b64 s[4:5], 0xa0
	v_add_f32_e32 v116, 1.0, v116
	v_rcp_f32_e32 v127, v116
	v_mov_b32_e32 v116, v95
	v_lshl_add_u64 v[144:145], v[186:187], 0, s[4:5]
	s_mov_b64 s[4:5], 0xb0
	v_pk_mul_f32 v[116:117], v[126:127], v[116:117]
	v_lshl_add_u64 v[142:143], v[186:187], 0, s[4:5]
	v_mul_f32_e32 v116, v116, v117
	v_cvt_pk_bf16_f32 v123, v2, v116
	v_lshlrev_b64 v[116:117], 12, v[192:193]
	v_lshl_add_u64 v[116:117], s[8:9], 0, v[116:117]
	v_lshl_add_u64 v[128:129], v[116:117], 0, v[140:141]
	v_lshlrev_b32_e32 v117, 16, v132
	v_mul_f32_e32 v2, 0xbfb8aa3b, v117
	v_exp_f32_e32 v2, v2
	v_mov_b32_e32 v116, v100
	global_store_dwordx4 v[128:129], v[120:123], off
	v_lshlrev_b64 v[138:139], 9, v[142:143]
	v_add_f32_e32 v2, 1.0, v2
	v_rcp_f32_e32 v119, v2
	s_nop 0
	v_pk_mul_f32 v[116:117], v[118:119], v[116:117]
	s_nop 0
	v_mul_f32_e32 v2, v116, v117
	v_and_b32_e32 v117, 0xffff0000, v132
	v_mul_f32_e32 v112, 0xbfb8aa3b, v117
	v_exp_f32_e32 v112, v112
	v_mov_b32_e32 v118, v113
	v_mov_b32_e32 v116, v101
	v_add_f32_e32 v112, 1.0, v112
	v_rcp_f32_e32 v119, v112
	s_nop 0
	v_pk_mul_f32 v[112:113], v[118:119], v[116:117]
	s_nop 0
	v_mul_f32_e32 v112, v112, v113
	v_lshlrev_b32_e32 v117, 16, v133
	v_cvt_pk_bf16_f32 v112, v2, v112
	v_mul_f32_e32 v2, 0xbfb8aa3b, v117
	v_exp_f32_e32 v2, v2
	v_mov_b32_e32 v118, v114
	v_mov_b32_e32 v116, v102
	v_add_f32_e32 v2, 1.0, v2
	v_rcp_f32_e32 v119, v2
	s_nop 0
	v_pk_mul_f32 v[116:117], v[118:119], v[116:117]
	s_nop 0
	v_mul_f32_e32 v2, v116, v117
	v_and_b32_e32 v117, 0xffff0000, v133
	v_mul_f32_e32 v113, 0xbfb8aa3b, v117
	v_exp_f32_e32 v113, v113
	v_mov_b32_e32 v118, v115
	v_mov_b32_e32 v116, v103
	v_lshlrev_b64 v[132:133], 9, v[146:147]
	v_add_f32_e32 v113, 1.0, v113
	v_rcp_f32_e32 v119, v113
	s_nop 0
	v_pk_mul_f32 v[114:115], v[118:119], v[116:117]
	s_nop 0
	v_mul_f32_e32 v113, v114, v115
	v_lshlrev_b32_e32 v115, 16, v134
	v_cvt_pk_bf16_f32 v113, v2, v113
	v_mul_f32_e32 v2, 0xbfb8aa3b, v115
	v_exp_f32_e32 v2, v2
	v_mov_b32_e32 v116, v108
	v_mov_b32_e32 v114, v92
	v_add_f32_e32 v2, 1.0, v2
	v_rcp_f32_e32 v117, v2
	s_nop 0
	v_pk_mul_f32 v[114:115], v[116:117], v[114:115]
	s_nop 0
	v_mul_f32_e32 v2, v114, v115
	v_and_b32_e32 v115, 0xffff0000, v134
	v_mul_f32_e32 v108, 0xbfb8aa3b, v115
	v_exp_f32_e32 v108, v108
	v_mov_b32_e32 v116, v109
	v_mov_b32_e32 v114, v93
	v_add_f32_e32 v108, 1.0, v108
	v_rcp_f32_e32 v117, v108
	s_nop 0
	v_pk_mul_f32 v[108:109], v[116:117], v[114:115]
	s_nop 0
	v_mul_f32_e32 v108, v108, v109
	v_lshlrev_b32_e32 v109, 16, v135
	v_cvt_pk_bf16_f32 v114, v2, v108
	v_mul_f32_e32 v2, 0xbfb8aa3b, v109
	v_exp_f32_e32 v2, v2
	v_mov_b32_e32 v116, v110
	v_mov_b32_e32 v108, v94
	v_add_f32_e32 v2, 1.0, v2
	v_rcp_f32_e32 v117, v2
	s_nop 0
	v_pk_mul_f32 v[108:109], v[116:117], v[108:109]
	s_nop 0
	v_mul_f32_e32 v2, v108, v109
	v_and_b32_e32 v109, 0xffff0000, v135
	v_mul_f32_e32 v108, 0xbfb8aa3b, v109
	v_exp_f32_e32 v108, v108
	v_mov_b32_e32 v116, v111
	v_lshlrev_b64 v[134:135], 9, v[144:145]
	v_add_f32_e32 v108, 1.0, v108
	v_rcp_f32_e32 v117, v108
	v_mov_b32_e32 v108, v95
	v_pk_mul_f32 v[108:109], v[116:117], v[108:109]
	s_nop 0
	v_mul_f32_e32 v108, v108, v109
	v_cvt_pk_bf16_f32 v115, v2, v108
	v_lshlrev_b64 v[108:109], 12, v[190:191]
	v_lshl_add_u64 v[108:109], s[8:9], 0, v[108:109]
	v_lshl_add_u64 v[126:127], v[108:109], 0, v[140:141]
	global_store_dwordx4 v[126:127], v[112:115], off
	v_lshl_add_u64 v[108:109], v[188:189], 0, v[130:131]
	global_load_dwordx4 v[120:123], v[108:109], off
	v_lshl_add_u64 v[108:109], v[188:189], 0, v[132:133]
	global_load_dwordx4 v[116:119], v[108:109], off
	v_lshl_add_u64 v[108:109], v[188:189], 0, v[134:135]
	global_load_dwordx4 v[112:115], v[108:109], off
	v_lshl_add_u64 v[108:109], v[188:189], 0, v[138:139]
	global_load_dwordx4 v[108:111], v[108:109], off
	s_waitcnt vmcnt(0) lgkmcnt(0)
; __device__ __forceinline__ float bflo(unsigned v) { return __uint_as_float(v << 16); }
; __device__ __forceinline__ float bfhi(unsigned v) { return __uint_as_float(v & 0xffff0000u); }
; __device__ __forceinline__ float siluf_(float x) { return x * __builtin_amdgcn_rcpf(1.0f + __expf(-x)); }
;   __device__ __forceinline__ void operator()(EPI_ARGS) const {
;     ...
;         for (int m = 0; m < 4; ++m) {
;           const size_t row = row0 + ai * HALF + m * 16;
;           const f32x4 v0 = acc[ai][bj][m][0], v1 = acc[ai][bj][m][1];
;           u32x4 o;
;           o.x = pack2(v0[0] * s0[0] * siluf_(bflo(z[m].x)), v0[1] * s0[1] * siluf_(bfhi(z[m].x)));
;           o.y = pack2(v0[2] * s0[2] * siluf_(bflo(z[m].y)), v0[3] * s0[3] * siluf_(bfhi(z[m].y)));
;           o.z = pack2(v1[0] * s1[0] * siluf_(bflo(z[m].z)), v1[1] * s1[1] * siluf_(bfhi(z[m].z)));
;           o.w = pack2(v1[2] * s1[2] * siluf_(bflo(z[m].w)), v1[3] * s1[3] * siluf_(bfhi(z[m].w)));
;           *(u32x4*)(y0 + row * DM + c) = o;
;         }
	v_lshlrev_b32_e32 v151, 16, v120
	v_mul_f32_e32 v2, 0xbfb8aa3b, v151
	v_exp_f32_e32 v2, v2
	v_mov_b32_e32 v152, v104
	v_mov_b32_e32 v150, v100
	v_mov_b32_e32 v175, v3
	v_add_f32_e32 v2, 1.0, v2
	v_rcp_f32_e32 v153, v2
	s_nop 0
	v_pk_mul_f32 v[150:151], v[152:153], v[150:151]
	s_nop 0
	v_mul_f32_e32 v2, v150, v151
	v_and_b32_e32 v151, 0xffff0000, v120
	v_mul_f32_e32 v104, 0xbfb8aa3b, v151
	v_exp_f32_e32 v104, v104
	v_mov_b32_e32 v152, v105
	v_mov_b32_e32 v150, v101
	v_mov_b32_e32 v120, v103
	v_add_f32_e32 v104, 1.0, v104
	v_rcp_f32_e32 v153, v104
	s_nop 0
	v_pk_mul_f32 v[104:105], v[152:153], v[150:151]
	s_nop 0
	v_mul_f32_e32 v104, v104, v105
	v_lshlrev_b32_e32 v151, 16, v121
	v_cvt_pk_bf16_f32 v104, v2, v104
	v_mul_f32_e32 v2, 0xbfb8aa3b, v151
	v_exp_f32_e32 v2, v2
	v_and_b32_e32 v121, 0xffff0000, v121
	v_mul_f32_e32 v105, 0xbfb8aa3b, v121
	v_exp_f32_e32 v105, v105
	v_add_f32_e32 v2, 1.0, v2
	v_rcp_f32_e32 v153, v2
	v_mov_b32_e32 v152, v106
	v_mov_b32_e32 v150, v102
	v_add_f32_e32 v105, 1.0, v105
	v_pk_mul_f32 v[150:151], v[152:153], v[150:151]
	s_nop 0
	v_mul_f32_e32 v2, v150, v151
	v_rcp_f32_e32 v151, v105
	v_mov_b32_e32 v150, v107
	v_pk_mul_f32 v[106:107], v[150:151], v[120:121]
	s_nop 0
	v_mul_f32_e32 v105, v106, v107
	v_lshlrev_b32_e32 v107, 16, v122
	v_cvt_pk_bf16_f32 v105, v2, v105
	v_mul_f32_e32 v2, 0xbfb8aa3b, v107
	v_exp_f32_e32 v2, v2
	v_mov_b32_e32 v120, v96
	v_mov_b32_e32 v106, v92
	v_add_f32_e32 v2, 1.0, v2
	v_rcp_f32_e32 v121, v2
	s_nop 0
	v_pk_mul_f32 v[106:107], v[120:121], v[106:107]
	s_nop 0
	v_mul_f32_e32 v2, v106, v107
	v_and_b32_e32 v107, 0xffff0000, v122
	v_mul_f32_e32 v96, 0xbfb8aa3b, v107
	v_exp_f32_e32 v96, v96
	v_mov_b32_e32 v120, v97
	v_mov_b32_e32 v106, v93
	v_add_f32_e32 v96, 1.0, v96
	v_rcp_f32_e32 v121, v96
	s_nop 0
	v_pk_mul_f32 v[96:97], v[120:121], v[106:107]
	s_nop 0
	v_mul_f32_e32 v96, v96, v97
	v_lshlrev_b32_e32 v97, 16, v123
	v_cvt_pk_bf16_f32 v106, v2, v96
	v_mul_f32_e32 v2, 0xbfb8aa3b, v97
	v_exp_f32_e32 v2, v2
	v_mov_b32_e32 v120, v98
	v_mov_b32_e32 v96, v94
	v_mov_b32_e32 v98, v100
	v_add_f32_e32 v2, 1.0, v2
	v_rcp_f32_e32 v121, v2
	s_nop 0
	v_pk_mul_f32 v[96:97], v[120:121], v[96:97]
	s_nop 0
	v_mul_f32_e32 v2, v96, v97
	v_and_b32_e32 v97, 0xffff0000, v123
	v_mul_f32_e32 v96, 0xbfb8aa3b, v97
	v_exp_f32_e32 v96, v96
	v_mov_b32_e32 v120, v99
	v_lshlrev_b32_e32 v99, 16, v116
	v_add_f32_e32 v96, 1.0, v96
	v_rcp_f32_e32 v121, v96
	v_mov_b32_e32 v96, v95
	v_pk_mul_f32 v[96:97], v[120:121], v[96:97]
	s_nop 0
	v_mul_f32_e32 v96, v96, v97
	v_cvt_pk_bf16_f32 v107, v2, v96
	v_mul_f32_e32 v2, 0xbfb8aa3b, v99
	v_exp_f32_e32 v2, v2
	v_lshlrev_b64 v[96:97], 12, v[148:149]
	v_lshl_add_u64 v[96:97], s[8:9], 0, v[96:97]
	v_lshl_add_u64 v[96:97], v[96:97], 0, v[140:141]
	v_add_f32_e32 v2, 1.0, v2
	global_store_dwordx4 v[96:97], v[104:107], off
	s_nop 1
	v_rcp_f32_e32 v105, v2
	v_mov_b32_e32 v104, v88
	v_pk_mul_f32 v[98:99], v[104:105], v[98:99]
	s_nop 0
	v_mul_f32_e32 v2, v98, v99
	v_and_b32_e32 v99, 0xffff0000, v116
	v_mul_f32_e32 v88, 0xbfb8aa3b, v99
	v_exp_f32_e32 v88, v88
	v_mov_b32_e32 v104, v89
	v_mov_b32_e32 v98, v101
	v_add_f32_e32 v88, 1.0, v88
	v_rcp_f32_e32 v105, v88
	s_nop 0
	v_pk_mul_f32 v[88:89], v[104:105], v[98:99]
	s_nop 0
	v_mul_f32_e32 v88, v88, v89
	v_lshlrev_b32_e32 v99, 16, v117
	v_cvt_pk_bf16_f32 v88, v2, v88
	v_mul_f32_e32 v2, 0xbfb8aa3b, v99
	v_exp_f32_e32 v2, v2
	v_mov_b32_e32 v104, v90
	v_mov_b32_e32 v98, v102
	v_add_f32_e32 v2, 1.0, v2
	v_rcp_f32_e32 v105, v2
	s_nop 0
	v_pk_mul_f32 v[98:99], v[104:105], v[98:99]
	s_nop 0
	v_mul_f32_e32 v2, v98, v99
	v_and_b32_e32 v99, 0xffff0000, v117
	v_mul_f32_e32 v89, 0xbfb8aa3b, v99
	v_exp_f32_e32 v89, v89
	v_mov_b32_e32 v104, v91
	v_mov_b32_e32 v98, v103
	v_add_f32_e32 v89, 1.0, v89
	v_rcp_f32_e32 v105, v89
	s_nop 0
	v_pk_mul_f32 v[90:91], v[104:105], v[98:99]
	s_nop 0
	v_mul_f32_e32 v89, v90, v91
	v_lshlrev_b32_e32 v91, 16, v118
	v_cvt_pk_bf16_f32 v89, v2, v89
	v_mul_f32_e32 v2, 0xbfb8aa3b, v91
	v_exp_f32_e32 v2, v2
	v_mov_b32_e32 v98, v84
	v_mov_b32_e32 v90, v92
	v_add_f32_e32 v2, 1.0, v2
	v_rcp_f32_e32 v99, v2
	s_nop 0
	v_pk_mul_f32 v[90:91], v[98:99], v[90:91]
	s_nop 0
	v_mul_f32_e32 v2, v90, v91
	v_and_b32_e32 v91, 0xffff0000, v118
	v_mul_f32_e32 v84, 0xbfb8aa3b, v91
	v_exp_f32_e32 v84, v84
	v_mov_b32_e32 v98, v85
	v_mov_b32_e32 v90, v93
	v_add_f32_e32 v84, 1.0, v84
	v_rcp_f32_e32 v99, v84
	s_nop 0
	v_pk_mul_f32 v[84:85], v[98:99], v[90:91]
	s_nop 0
	v_mul_f32_e32 v84, v84, v85
	v_lshlrev_b32_e32 v85, 16, v119
	v_cvt_pk_bf16_f32 v90, v2, v84
	v_mul_f32_e32 v2, 0xbfb8aa3b, v85
	v_exp_f32_e32 v2, v2
	v_mov_b32_e32 v98, v86
	v_mov_b32_e32 v84, v94
	v_mov_b32_e32 v86, v80
	v_add_f32_e32 v2, 1.0, v2
	v_rcp_f32_e32 v99, v2
	s_nop 0
	v_pk_mul_f32 v[84:85], v[98:99], v[84:85]
	s_nop 0
	v_mul_f32_e32 v2, v84, v85
	v_and_b32_e32 v85, 0xffff0000, v119
	v_mul_f32_e32 v84, 0xbfb8aa3b, v85
	v_exp_f32_e32 v84, v84
	v_mov_b32_e32 v98, v87
	v_add_f32_e32 v84, 1.0, v84
	v_rcp_f32_e32 v99, v84
	v_mov_b32_e32 v84, v95
	v_pk_mul_f32 v[84:85], v[98:99], v[84:85]
	s_nop 0
	v_mul_f32_e32 v84, v84, v85
	v_cvt_pk_bf16_f32 v91, v2, v84
	v_lshlrev_b64 v[84:85], 12, v[146:147]
	v_lshl_add_u64 v[84:85], s[8:9], 0, v[84:85]
	v_lshl_add_u64 v[98:99], v[84:85], 0, v[140:141]
	v_lshlrev_b32_e32 v85, 16, v112
	v_mul_f32_e32 v2, 0xbfb8aa3b, v85
	v_exp_f32_e32 v2, v2
	v_mov_b32_e32 v84, v100
	global_store_dwordx4 v[98:99], v[88:91], off
	v_add_f32_e32 v2, 1.0, v2
	v_rcp_f32_e32 v87, v2
	s_nop 0
	v_pk_mul_f32 v[84:85], v[86:87], v[84:85]
	s_nop 0
	v_mul_f32_e32 v2, v84, v85
	v_and_b32_e32 v85, 0xffff0000, v112
	v_mul_f32_e32 v80, 0xbfb8aa3b, v85
	v_exp_f32_e32 v80, v80
; __device__ __forceinline__ size_t pidx(size_t row, int col) { return ((size_t)(col >> 8) * MTOK + row) * PLD + (col & 255); }
; __device__ __forceinline__ float bflo(unsigned v) { return __uint_as_float(v << 16); }
; __device__ __forceinline__ float bfhi(unsigned v) { return __uint_as_float(v & 0xffff0000u); }
; __device__ __forceinline__ float siluf_(float x) { return x * __builtin_amdgcn_rcpf(1.0f + __expf(-x)); }
;   __device__ __forceinline__ void operator()(EPI_ARGS) const {
;     ...
;       const f32x4 s0 = *(const f32x4*)(psc + c), s1 = *(const f32x4*)(psc + c + 4);
; #pragma unroll
;       for (int ai = 0; ai < 2; ++ai) {
;         u32x4 z[4];
; #pragma unroll
;         for (int m = 0; m < 4; ++m) z[m] = *(const u32x4*)(proj + pidx(row0 + ai * HALF + m * 16, PZ + c));
;         __builtin_amdgcn_sched_barrier(0);
; #pragma unroll
;         for (int m = 0; m < 4; ++m) {
;           const size_t row = row0 + ai * HALF + m * 16;
;           const f32x4 v0 = acc[ai][bj][m][0], v1 = acc[ai][bj][m][1];
;           u32x4 o;
;           o.x = pack2(v0[0] * s0[0] * siluf_(bflo(z[m].x)), v0[1] * s0[1] * siluf_(bfhi(z[m].x)));
;           o.y = pack2(v0[2] * s0[2] * siluf_(bflo(z[m].y)), v0[3] * s0[3] * siluf_(bfhi(z[m].y)));
;           o.z = pack2(v1[0] * s1[0] * siluf_(bflo(z[m].z)), v1[1] * s1[1] * siluf_(bfhi(z[m].z)));
;           o.w = pack2(v1[2] * s1[2] * siluf_(bflo(z[m].w)), v1[3] * s1[3] * siluf_(bfhi(z[m].w)));
;           *(u32x4*)(y0 + row * DM + c) = o;
	v_mov_b32_e32 v86, v81
	v_mov_b32_e32 v84, v101
	v_add_f32_e32 v80, 1.0, v80
	v_rcp_f32_e32 v87, v80
	s_nop 0
	v_pk_mul_f32 v[80:81], v[86:87], v[84:85]
	s_nop 0
	v_mul_f32_e32 v80, v80, v81
	v_lshlrev_b32_e32 v85, 16, v113
	v_cvt_pk_bf16_f32 v80, v2, v80
	v_mul_f32_e32 v2, 0xbfb8aa3b, v85
	v_exp_f32_e32 v2, v2
	v_mov_b32_e32 v86, v82
	v_mov_b32_e32 v84, v102
	v_add_f32_e32 v2, 1.0, v2
	v_rcp_f32_e32 v87, v2
	s_nop 0
	v_pk_mul_f32 v[84:85], v[86:87], v[84:85]
	s_nop 0
	v_mul_f32_e32 v2, v84, v85
	v_and_b32_e32 v85, 0xffff0000, v113
	v_mul_f32_e32 v81, 0xbfb8aa3b, v85
	v_exp_f32_e32 v81, v81
	v_mov_b32_e32 v86, v83
	v_mov_b32_e32 v84, v103
	v_add_f32_e32 v81, 1.0, v81
	v_rcp_f32_e32 v87, v81
	s_nop 0
	v_pk_mul_f32 v[82:83], v[86:87], v[84:85]
	s_nop 0
	v_mul_f32_e32 v81, v82, v83
	v_lshlrev_b32_e32 v83, 16, v114
	v_cvt_pk_bf16_f32 v81, v2, v81
	v_mul_f32_e32 v2, 0xbfb8aa3b, v83
	v_exp_f32_e32 v2, v2
	v_mov_b32_e32 v84, v76
	v_mov_b32_e32 v82, v92
	v_add_f32_e32 v2, 1.0, v2
	v_rcp_f32_e32 v85, v2
	s_nop 0
	v_pk_mul_f32 v[82:83], v[84:85], v[82:83]
	s_nop 0
	v_mul_f32_e32 v2, v82, v83
	v_and_b32_e32 v83, 0xffff0000, v114
	v_mul_f32_e32 v76, 0xbfb8aa3b, v83
	v_exp_f32_e32 v76, v76
	v_mov_b32_e32 v84, v77
	v_mov_b32_e32 v82, v93
	v_add_f32_e32 v76, 1.0, v76
	v_rcp_f32_e32 v85, v76
	s_nop 0
	v_pk_mul_f32 v[76:77], v[84:85], v[82:83]
	s_nop 0
	v_mul_f32_e32 v76, v76, v77
	v_lshlrev_b32_e32 v77, 16, v115
	v_cvt_pk_bf16_f32 v82, v2, v76
	v_mul_f32_e32 v2, 0xbfb8aa3b, v77
	v_exp_f32_e32 v2, v2
	v_mov_b32_e32 v84, v78
	v_mov_b32_e32 v76, v94
	v_mov_b32_e32 v78, v72
	v_add_f32_e32 v2, 1.0, v2
	v_rcp_f32_e32 v85, v2
	s_nop 0
	v_pk_mul_f32 v[76:77], v[84:85], v[76:77]
	s_nop 0
	v_mul_f32_e32 v2, v76, v77
	v_and_b32_e32 v77, 0xffff0000, v115
	v_mul_f32_e32 v76, 0xbfb8aa3b, v77
	v_exp_f32_e32 v76, v76
	v_mov_b32_e32 v84, v79
	v_add_f32_e32 v76, 1.0, v76
	v_rcp_f32_e32 v85, v76
	v_mov_b32_e32 v76, v95
	v_pk_mul_f32 v[76:77], v[84:85], v[76:77]
	s_nop 0
	v_mul_f32_e32 v76, v76, v77
	v_cvt_pk_bf16_f32 v83, v2, v76
	v_lshlrev_b64 v[76:77], 12, v[144:145]
	v_lshl_add_u64 v[76:77], s[8:9], 0, v[76:77]
	v_lshl_add_u64 v[104:105], v[76:77], 0, v[140:141]
	v_lshlrev_b32_e32 v77, 16, v108
	v_mul_f32_e32 v2, 0xbfb8aa3b, v77
	v_exp_f32_e32 v2, v2
	v_mov_b32_e32 v76, v100
	global_store_dwordx4 v[104:105], v[80:83], off
	v_add_f32_e32 v2, 1.0, v2
	v_rcp_f32_e32 v79, v2
	s_nop 0
	v_pk_mul_f32 v[76:77], v[78:79], v[76:77]
	s_nop 0
	v_mul_f32_e32 v2, v76, v77
	v_and_b32_e32 v77, 0xffff0000, v108
	v_mul_f32_e32 v72, 0xbfb8aa3b, v77
	v_exp_f32_e32 v72, v72
	v_mov_b32_e32 v78, v73
	v_mov_b32_e32 v76, v101
	v_add_f32_e32 v72, 1.0, v72
	v_rcp_f32_e32 v79, v72
	s_nop 0
	v_pk_mul_f32 v[72:73], v[78:79], v[76:77]
	s_nop 0
	v_mul_f32_e32 v72, v72, v73
	v_lshlrev_b32_e32 v77, 16, v109
	v_cvt_pk_bf16_f32 v72, v2, v72
	v_mul_f32_e32 v2, 0xbfb8aa3b, v77
	v_exp_f32_e32 v2, v2
	v_mov_b32_e32 v78, v74
	v_mov_b32_e32 v76, v102
	v_add_f32_e32 v2, 1.0, v2
	v_rcp_f32_e32 v79, v2
	s_nop 0
	v_pk_mul_f32 v[76:77], v[78:79], v[76:77]
	s_nop 0
	v_mul_f32_e32 v2, v76, v77
	v_and_b32_e32 v77, 0xffff0000, v109
	v_mul_f32_e32 v73, 0xbfb8aa3b, v77
	v_exp_f32_e32 v73, v73
	v_mov_b32_e32 v78, v75
	v_mov_b32_e32 v76, v103
	v_add_f32_e32 v73, 1.0, v73
	v_rcp_f32_e32 v79, v73
	s_nop 0
	v_pk_mul_f32 v[74:75], v[78:79], v[76:77]
	s_nop 0
	v_mul_f32_e32 v73, v74, v75
	v_lshlrev_b32_e32 v75, 16, v110
	v_cvt_pk_bf16_f32 v73, v2, v73
	v_mul_f32_e32 v2, 0xbfb8aa3b, v75
	v_exp_f32_e32 v2, v2
	v_mov_b32_e32 v76, v68
	v_mov_b32_e32 v74, v92
	v_add_f32_e32 v2, 1.0, v2
	v_rcp_f32_e32 v77, v2
	s_nop 0
	v_pk_mul_f32 v[74:75], v[76:77], v[74:75]
	s_nop 0
	v_mul_f32_e32 v2, v74, v75
	v_and_b32_e32 v75, 0xffff0000, v110
	v_mul_f32_e32 v68, 0xbfb8aa3b, v75
	v_exp_f32_e32 v68, v68
	v_mov_b32_e32 v76, v69
	v_mov_b32_e32 v74, v93
	v_add_f32_e32 v68, 1.0, v68
	v_rcp_f32_e32 v77, v68
	s_nop 0
	v_pk_mul_f32 v[68:69], v[76:77], v[74:75]
	s_nop 0
	v_mul_f32_e32 v68, v68, v69
	v_lshlrev_b32_e32 v69, 16, v111
	v_cvt_pk_bf16_f32 v74, v2, v68
	v_mul_f32_e32 v2, 0xbfb8aa3b, v69
	v_exp_f32_e32 v2, v2
	v_mov_b32_e32 v76, v70
	v_mov_b32_e32 v68, v94
	v_add_f32_e32 v2, 1.0, v2
	v_rcp_f32_e32 v77, v2
	s_nop 0
	v_pk_mul_f32 v[68:69], v[76:77], v[68:69]
	s_nop 0
	v_mul_f32_e32 v2, v68, v69
	v_and_b32_e32 v69, 0xffff0000, v111
	v_mul_f32_e32 v68, 0xbfb8aa3b, v69
	v_exp_f32_e32 v68, v68
	v_mov_b32_e32 v76, v71
	v_add_f32_e32 v68, 1.0, v68
	v_rcp_f32_e32 v77, v68
	v_mov_b32_e32 v68, v95
	v_lshl_add_u64 v[94:95], s[2:3], 0, v[174:175]
	v_pk_mul_f32 v[68:69], v[76:77], v[68:69]
	s_nop 0
	v_mul_f32_e32 v68, v68, v69
	v_cvt_pk_bf16_f32 v75, v2, v68
	v_lshlrev_b64 v[68:69], 12, v[142:143]
	v_lshl_add_u64 v[68:69], s[8:9], 0, v[68:69]
	v_lshl_add_u64 v[92:93], v[68:69], 0, v[140:141]
	global_store_dwordx4 v[92:93], v[72:75], off
	v_lshl_add_u64 v[76:77], v[94:95], 0, v[178:179]
	global_load_dwordx4 v[68:71], v[176:177], off offset:528
	global_load_dwordx4 v[72:75], v[176:177], off offset:512
	global_load_dwordx4 v[88:91], v[76:77], off
	v_lshl_add_u64 v[76:77], v[94:95], 0, v[180:181]
	global_load_dwordx4 v[84:87], v[76:77], off
	v_lshl_add_u64 v[76:77], v[94:95], 0, v[182:183]
	global_load_dwordx4 v[80:83], v[76:77], off
	v_lshl_add_u64 v[76:77], v[94:95], 0, v[184:185]
	global_load_dwordx4 v[76:79], v[76:77], off
	s_waitcnt vmcnt(0) lgkmcnt(0)
; __device__ __forceinline__ float bflo(unsigned v) { return __uint_as_float(v << 16); }
; __device__ __forceinline__ float bfhi(unsigned v) { return __uint_as_float(v & 0xffff0000u); }
; __device__ __forceinline__ float siluf_(float x) { return x * __builtin_amdgcn_rcpf(1.0f + __expf(-x)); }
;   __device__ __forceinline__ void operator()(EPI_ARGS) const {
;     ...
;         for (int m = 0; m < 4; ++m) {
;           const size_t row = row0 + ai * HALF + m * 16;
;           const f32x4 v0 = acc[ai][bj][m][0], v1 = acc[ai][bj][m][1];
;           u32x4 o;
;           o.x = pack2(v0[0] * s0[0] * siluf_(bflo(z[m].x)), v0[1] * s0[1] * siluf_(bfhi(z[m].x)));
;           o.y = pack2(v0[2] * s0[2] * siluf_(bflo(z[m].y)), v0[3] * s0[3] * siluf_(bfhi(z[m].y)));
;           o.z = pack2(v1[0] * s1[0] * siluf_(bflo(z[m].z)), v1[1] * s1[1] * siluf_(bfhi(z[m].z)));
;           o.w = pack2(v1[2] * s1[2] * siluf_(bflo(z[m].w)), v1[3] * s1[3] * siluf_(bfhi(z[m].w)));
;           *(u32x4*)(y0 + row * DM + c) = o;
;         }
	v_lshlrev_b32_e32 v101, 16, v88
	v_mul_f32_e32 v2, 0xbfb8aa3b, v101
	v_exp_f32_e32 v2, v2
	v_mov_b32_e32 v102, v64
	v_mov_b32_e32 v100, v72
	v_add_f32_e32 v2, 1.0, v2
	v_rcp_f32_e32 v103, v2
	s_nop 0
	v_pk_mul_f32 v[100:101], v[102:103], v[100:101]
	s_nop 0
	v_mul_f32_e32 v2, v100, v101
	v_and_b32_e32 v101, 0xffff0000, v88
	v_mul_f32_e32 v64, 0xbfb8aa3b, v101
	v_exp_f32_e32 v64, v64
	v_mov_b32_e32 v102, v65
	v_mov_b32_e32 v100, v73
	v_mov_b32_e32 v88, v75
	v_add_f32_e32 v64, 1.0, v64
	v_rcp_f32_e32 v103, v64
	s_nop 0
	v_pk_mul_f32 v[64:65], v[102:103], v[100:101]
	s_nop 0
	v_mul_f32_e32 v64, v64, v65
	v_lshlrev_b32_e32 v101, 16, v89
	v_cvt_pk_bf16_f32 v64, v2, v64
	v_mul_f32_e32 v2, 0xbfb8aa3b, v101
	v_exp_f32_e32 v2, v2
	v_and_b32_e32 v89, 0xffff0000, v89
	v_mul_f32_e32 v65, 0xbfb8aa3b, v89
	v_exp_f32_e32 v65, v65
	v_add_f32_e32 v2, 1.0, v2
	v_rcp_f32_e32 v103, v2
	v_mov_b32_e32 v102, v66
	v_mov_b32_e32 v100, v74
	v_add_f32_e32 v65, 1.0, v65
	v_pk_mul_f32 v[100:101], v[102:103], v[100:101]
	s_nop 0
	v_mul_f32_e32 v2, v100, v101
	v_rcp_f32_e32 v101, v65
	v_mov_b32_e32 v100, v67
	v_pk_mul_f32 v[66:67], v[100:101], v[88:89]
	s_nop 0
	v_mul_f32_e32 v65, v66, v67
	v_lshlrev_b32_e32 v67, 16, v90
	v_cvt_pk_bf16_f32 v65, v2, v65
	v_mul_f32_e32 v2, 0xbfb8aa3b, v67
	v_exp_f32_e32 v2, v2
	v_mov_b32_e32 v88, v60
	v_mov_b32_e32 v66, v68
	v_add_f32_e32 v2, 1.0, v2
	v_rcp_f32_e32 v89, v2
	s_nop 0
	v_pk_mul_f32 v[66:67], v[88:89], v[66:67]
	s_nop 0
	v_mul_f32_e32 v2, v66, v67
	v_and_b32_e32 v67, 0xffff0000, v90
	v_mul_f32_e32 v60, 0xbfb8aa3b, v67
	v_exp_f32_e32 v60, v60
	v_mov_b32_e32 v88, v61
	v_mov_b32_e32 v66, v69
	v_add_f32_e32 v60, 1.0, v60
	v_rcp_f32_e32 v89, v60
	s_nop 0
	v_pk_mul_f32 v[60:61], v[88:89], v[66:67]
	s_nop 0
	v_mul_f32_e32 v60, v60, v61
	v_lshlrev_b32_e32 v61, 16, v91
	v_cvt_pk_bf16_f32 v66, v2, v60
	v_mul_f32_e32 v2, 0xbfb8aa3b, v61
	v_exp_f32_e32 v2, v2
	v_mov_b32_e32 v88, v62
	v_mov_b32_e32 v60, v70
	v_mov_b32_e32 v62, v56
	v_add_f32_e32 v2, 1.0, v2
	v_rcp_f32_e32 v89, v2
	s_nop 0
	v_pk_mul_f32 v[60:61], v[88:89], v[60:61]
	s_nop 0
	v_mul_f32_e32 v2, v60, v61
	v_and_b32_e32 v61, 0xffff0000, v91
	v_mul_f32_e32 v60, 0xbfb8aa3b, v61
	v_exp_f32_e32 v60, v60
	v_mov_b32_e32 v88, v63
	v_add_f32_e32 v60, 1.0, v60
	v_rcp_f32_e32 v89, v60
	v_mov_b32_e32 v60, v71
	v_pk_mul_f32 v[60:61], v[88:89], v[60:61]
	s_nop 0
	v_mul_f32_e32 v60, v60, v61
	v_lshlrev_b32_e32 v61, 16, v84
	v_cvt_pk_bf16_f32 v67, v2, v60
	v_mul_f32_e32 v2, 0xbfb8aa3b, v61
	v_exp_f32_e32 v2, v2
	v_mov_b32_e32 v60, v72
	global_store_dwordx4 v[136:137], v[64:67], off offset:256
	v_add_f32_e32 v2, 1.0, v2
	v_rcp_f32_e32 v63, v2
	s_nop 0
	v_pk_mul_f32 v[60:61], v[62:63], v[60:61]
	s_nop 0
	v_mul_f32_e32 v2, v60, v61
	v_and_b32_e32 v61, 0xffff0000, v84
	v_mul_f32_e32 v56, 0xbfb8aa3b, v61
	v_exp_f32_e32 v56, v56
	v_mov_b32_e32 v62, v57
	v_mov_b32_e32 v60, v73
	v_add_f32_e32 v56, 1.0, v56
	v_rcp_f32_e32 v63, v56
	s_nop 0
	v_pk_mul_f32 v[56:57], v[62:63], v[60:61]
	s_nop 0
	v_mul_f32_e32 v56, v56, v57
	v_lshlrev_b32_e32 v61, 16, v85
	v_cvt_pk_bf16_f32 v56, v2, v56
	v_mul_f32_e32 v2, 0xbfb8aa3b, v61
	v_exp_f32_e32 v2, v2
	v_mov_b32_e32 v62, v58
	v_mov_b32_e32 v60, v74
	v_add_f32_e32 v2, 1.0, v2
	v_rcp_f32_e32 v63, v2
	s_nop 0
	v_pk_mul_f32 v[60:61], v[62:63], v[60:61]
	s_nop 0
	v_mul_f32_e32 v2, v60, v61
	v_and_b32_e32 v61, 0xffff0000, v85
	v_mul_f32_e32 v57, 0xbfb8aa3b, v61
	v_exp_f32_e32 v57, v57
	v_mov_b32_e32 v62, v59
	v_mov_b32_e32 v60, v75
	v_add_f32_e32 v57, 1.0, v57
	v_rcp_f32_e32 v63, v57
	s_nop 0
	v_pk_mul_f32 v[58:59], v[62:63], v[60:61]
	s_nop 0
	v_mul_f32_e32 v57, v58, v59
	v_lshlrev_b32_e32 v59, 16, v86
	v_cvt_pk_bf16_f32 v57, v2, v57
	v_mul_f32_e32 v2, 0xbfb8aa3b, v59
	v_exp_f32_e32 v2, v2
	v_mov_b32_e32 v60, v52
	v_mov_b32_e32 v58, v68
	v_add_f32_e32 v2, 1.0, v2
	v_rcp_f32_e32 v61, v2
	s_nop 0
	v_pk_mul_f32 v[58:59], v[60:61], v[58:59]
	s_nop 0
	v_mul_f32_e32 v2, v58, v59
	v_and_b32_e32 v59, 0xffff0000, v86
	v_mul_f32_e32 v52, 0xbfb8aa3b, v59
	v_exp_f32_e32 v52, v52
	v_mov_b32_e32 v60, v53
	v_mov_b32_e32 v58, v69
	v_add_f32_e32 v52, 1.0, v52
	v_rcp_f32_e32 v61, v52
	s_nop 0
	v_pk_mul_f32 v[52:53], v[60:61], v[58:59]
	s_nop 0
	v_mul_f32_e32 v52, v52, v53
	v_lshlrev_b32_e32 v53, 16, v87
	v_cvt_pk_bf16_f32 v58, v2, v52
	v_mul_f32_e32 v2, 0xbfb8aa3b, v53
	v_exp_f32_e32 v2, v2
	v_mov_b32_e32 v60, v54
	v_mov_b32_e32 v52, v70
	v_mov_b32_e32 v54, v48
	v_add_f32_e32 v2, 1.0, v2
	v_rcp_f32_e32 v61, v2
	s_nop 0
	v_pk_mul_f32 v[52:53], v[60:61], v[52:53]
	s_nop 0
	v_mul_f32_e32 v2, v52, v53
	v_and_b32_e32 v53, 0xffff0000, v87
	v_mul_f32_e32 v52, 0xbfb8aa3b, v53
	v_exp_f32_e32 v52, v52
	v_mov_b32_e32 v60, v55
	v_add_f32_e32 v52, 1.0, v52
	v_rcp_f32_e32 v61, v52
	v_mov_b32_e32 v52, v71
	v_pk_mul_f32 v[52:53], v[60:61], v[52:53]
	s_nop 0
	v_mul_f32_e32 v52, v52, v53
	v_lshlrev_b32_e32 v53, 16, v80
	v_cvt_pk_bf16_f32 v59, v2, v52
	v_mul_f32_e32 v2, 0xbfb8aa3b, v53
	v_exp_f32_e32 v2, v2
	v_mov_b32_e32 v52, v72
	global_store_dwordx4 v[124:125], v[56:59], off offset:256
	v_add_f32_e32 v2, 1.0, v2
	v_rcp_f32_e32 v55, v2
	s_nop 0
	v_pk_mul_f32 v[52:53], v[54:55], v[52:53]
	s_nop 0
	v_mul_f32_e32 v2, v52, v53
	v_and_b32_e32 v53, 0xffff0000, v80
	v_mul_f32_e32 v48, 0xbfb8aa3b, v53
	v_exp_f32_e32 v48, v48
	v_mov_b32_e32 v54, v49
	v_mov_b32_e32 v52, v73
	v_add_f32_e32 v48, 1.0, v48
	v_rcp_f32_e32 v55, v48
	s_nop 0
	v_pk_mul_f32 v[48:49], v[54:55], v[52:53]
	s_nop 0
	v_mul_f32_e32 v48, v48, v49
	v_lshlrev_b32_e32 v53, 16, v81
	v_cvt_pk_bf16_f32 v48, v2, v48
	v_mul_f32_e32 v2, 0xbfb8aa3b, v53
	v_exp_f32_e32 v2, v2
	v_mov_b32_e32 v54, v50
	v_mov_b32_e32 v52, v74
	v_add_f32_e32 v2, 1.0, v2
; __device__ __forceinline__ size_t pidx(size_t row, int col) { return ((size_t)(col >> 8) * MTOK + row) * PLD + (col & 255); }
; __device__ __forceinline__ float bflo(unsigned v) { return __uint_as_float(v << 16); }
; __device__ __forceinline__ float bfhi(unsigned v) { return __uint_as_float(v & 0xffff0000u); }
; __device__ __forceinline__ float siluf_(float x) { return x * __builtin_amdgcn_rcpf(1.0f + __expf(-x)); }
;   __device__ __forceinline__ void operator()(EPI_ARGS) const {
;     ...
;         for (int m = 0; m < 4; ++m) z[m] = *(const u32x4*)(proj + pidx(row0 + ai * HALF + m * 16, PZ + c));
;         __builtin_amdgcn_sched_barrier(0);
; #pragma unroll
;         for (int m = 0; m < 4; ++m) {
;           const size_t row = row0 + ai * HALF + m * 16;
;           const f32x4 v0 = acc[ai][bj][m][0], v1 = acc[ai][bj][m][1];
;           u32x4 o;
;           o.x = pack2(v0[0] * s0[0] * siluf_(bflo(z[m].x)), v0[1] * s0[1] * siluf_(bfhi(z[m].x)));
;           o.y = pack2(v0[2] * s0[2] * siluf_(bflo(z[m].y)), v0[3] * s0[3] * siluf_(bfhi(z[m].y)));
;           o.z = pack2(v1[0] * s1[0] * siluf_(bflo(z[m].z)), v1[1] * s1[1] * siluf_(bfhi(z[m].z)));
;           o.w = pack2(v1[2] * s1[2] * siluf_(bflo(z[m].w)), v1[3] * s1[3] * siluf_(bfhi(z[m].w)));
;           *(u32x4*)(y0 + row * DM + c) = o;
;         }
	v_rcp_f32_e32 v55, v2
	s_nop 0
	v_pk_mul_f32 v[52:53], v[54:55], v[52:53]
	s_nop 0
	v_mul_f32_e32 v2, v52, v53
	v_and_b32_e32 v53, 0xffff0000, v81
	v_mul_f32_e32 v49, 0xbfb8aa3b, v53
	v_exp_f32_e32 v49, v49
	v_mov_b32_e32 v54, v51
	v_mov_b32_e32 v52, v75
	v_add_f32_e32 v49, 1.0, v49
	v_rcp_f32_e32 v55, v49
	s_nop 0
	v_pk_mul_f32 v[50:51], v[54:55], v[52:53]
	s_nop 0
	v_mul_f32_e32 v49, v50, v51
	v_lshlrev_b32_e32 v51, 16, v82
	v_cvt_pk_bf16_f32 v49, v2, v49
	v_mul_f32_e32 v2, 0xbfb8aa3b, v51
	v_exp_f32_e32 v2, v2
	v_mov_b32_e32 v52, v44
	v_mov_b32_e32 v50, v68
	v_add_f32_e32 v2, 1.0, v2
	v_rcp_f32_e32 v53, v2
	s_nop 0
	v_pk_mul_f32 v[50:51], v[52:53], v[50:51]
	s_nop 0
	v_mul_f32_e32 v2, v50, v51
	v_and_b32_e32 v51, 0xffff0000, v82
	v_mul_f32_e32 v44, 0xbfb8aa3b, v51
	v_exp_f32_e32 v44, v44
	v_mov_b32_e32 v52, v45
	v_mov_b32_e32 v50, v69
	v_add_f32_e32 v44, 1.0, v44
	v_rcp_f32_e32 v53, v44
	s_nop 0
	v_pk_mul_f32 v[44:45], v[52:53], v[50:51]
	s_nop 0
	v_mul_f32_e32 v44, v44, v45
	v_lshlrev_b32_e32 v45, 16, v83
	v_cvt_pk_bf16_f32 v50, v2, v44
	v_mul_f32_e32 v2, 0xbfb8aa3b, v45
	v_exp_f32_e32 v2, v2
	v_mov_b32_e32 v52, v46
	v_mov_b32_e32 v44, v70
	v_mov_b32_e32 v46, v40
	v_add_f32_e32 v2, 1.0, v2
	v_rcp_f32_e32 v53, v2
	s_nop 0
	v_pk_mul_f32 v[44:45], v[52:53], v[44:45]
	s_nop 0
	v_mul_f32_e32 v2, v44, v45
	v_and_b32_e32 v45, 0xffff0000, v83
	v_mul_f32_e32 v44, 0xbfb8aa3b, v45
	v_exp_f32_e32 v44, v44
	v_mov_b32_e32 v52, v47
	v_add_f32_e32 v44, 1.0, v44
	v_rcp_f32_e32 v53, v44
	v_mov_b32_e32 v44, v71
	v_pk_mul_f32 v[44:45], v[52:53], v[44:45]
	s_nop 0
	v_mul_f32_e32 v44, v44, v45
	v_lshlrev_b32_e32 v45, 16, v76
	v_cvt_pk_bf16_f32 v51, v2, v44
	v_mul_f32_e32 v2, 0xbfb8aa3b, v45
	v_exp_f32_e32 v2, v2
	v_mov_b32_e32 v44, v72
	global_store_dwordx4 v[128:129], v[48:51], off offset:256
	v_add_f32_e32 v2, 1.0, v2
	v_rcp_f32_e32 v47, v2
	s_nop 0
	v_pk_mul_f32 v[44:45], v[46:47], v[44:45]
	s_nop 0
	v_mul_f32_e32 v2, v44, v45
	v_and_b32_e32 v45, 0xffff0000, v76
	v_mul_f32_e32 v40, 0xbfb8aa3b, v45
	v_exp_f32_e32 v40, v40
	v_mov_b32_e32 v46, v41
	v_mov_b32_e32 v44, v73
	v_add_f32_e32 v40, 1.0, v40
	v_rcp_f32_e32 v47, v40
	s_nop 0
	v_pk_mul_f32 v[40:41], v[46:47], v[44:45]
	s_nop 0
	v_mul_f32_e32 v40, v40, v41
	v_lshlrev_b32_e32 v45, 16, v77
	v_cvt_pk_bf16_f32 v40, v2, v40
	v_mul_f32_e32 v2, 0xbfb8aa3b, v45
	v_exp_f32_e32 v2, v2
	v_mov_b32_e32 v46, v42
	v_mov_b32_e32 v44, v74
	v_add_f32_e32 v2, 1.0, v2
	v_rcp_f32_e32 v47, v2
	s_nop 0
	v_pk_mul_f32 v[44:45], v[46:47], v[44:45]
	s_nop 0
	v_mul_f32_e32 v2, v44, v45
	v_and_b32_e32 v45, 0xffff0000, v77
	v_mul_f32_e32 v41, 0xbfb8aa3b, v45
	v_exp_f32_e32 v41, v41
	v_mov_b32_e32 v46, v43
	v_mov_b32_e32 v44, v75
	v_add_f32_e32 v41, 1.0, v41
	v_rcp_f32_e32 v47, v41
	s_nop 0
	v_pk_mul_f32 v[42:43], v[46:47], v[44:45]
	s_nop 0
	v_mul_f32_e32 v41, v42, v43
	v_lshlrev_b32_e32 v43, 16, v78
	v_cvt_pk_bf16_f32 v41, v2, v41
	v_mul_f32_e32 v2, 0xbfb8aa3b, v43
	v_exp_f32_e32 v2, v2
	v_mov_b32_e32 v44, v36
	v_mov_b32_e32 v42, v68
	v_add_f32_e32 v2, 1.0, v2
	v_rcp_f32_e32 v45, v2
	s_nop 0
	v_pk_mul_f32 v[42:43], v[44:45], v[42:43]
	s_nop 0
	v_mul_f32_e32 v2, v42, v43
	v_and_b32_e32 v43, 0xffff0000, v78
	v_mul_f32_e32 v36, 0xbfb8aa3b, v43
	v_exp_f32_e32 v36, v36
	v_mov_b32_e32 v44, v37
	v_mov_b32_e32 v42, v69
	v_add_f32_e32 v36, 1.0, v36
	v_rcp_f32_e32 v45, v36
	s_nop 0
	v_pk_mul_f32 v[36:37], v[44:45], v[42:43]
	s_nop 0
	v_mul_f32_e32 v36, v36, v37
	v_lshlrev_b32_e32 v37, 16, v79
	v_cvt_pk_bf16_f32 v42, v2, v36
	v_mul_f32_e32 v2, 0xbfb8aa3b, v37
	v_exp_f32_e32 v2, v2
	v_mov_b32_e32 v44, v38
	v_mov_b32_e32 v36, v70
	v_add_f32_e32 v2, 1.0, v2
	v_rcp_f32_e32 v45, v2
	s_nop 0
	v_pk_mul_f32 v[36:37], v[44:45], v[36:37]
	s_nop 0
	v_mul_f32_e32 v2, v36, v37
	v_and_b32_e32 v37, 0xffff0000, v79
	v_mul_f32_e32 v36, 0xbfb8aa3b, v37
	v_exp_f32_e32 v36, v36
	v_mov_b32_e32 v44, v39
	v_add_f32_e32 v36, 1.0, v36
	v_rcp_f32_e32 v45, v36
	v_mov_b32_e32 v36, v71
	v_pk_mul_f32 v[36:37], v[44:45], v[36:37]
	s_nop 0
	v_mul_f32_e32 v36, v36, v37
	v_cvt_pk_bf16_f32 v43, v2, v36
	global_store_dwordx4 v[126:127], v[40:43], off offset:256
	v_lshl_add_u64 v[36:37], v[94:95], 0, v[130:131]
	global_load_dwordx4 v[48:51], v[36:37], off
	v_lshl_add_u64 v[36:37], v[94:95], 0, v[132:133]
	global_load_dwordx4 v[44:47], v[36:37], off
	v_lshl_add_u64 v[36:37], v[94:95], 0, v[134:135]
	global_load_dwordx4 v[40:43], v[36:37], off
	v_lshl_add_u64 v[36:37], v[94:95], 0, v[138:139]
	global_load_dwordx4 v[36:39], v[36:37], off
	s_waitcnt vmcnt(0) lgkmcnt(0)
; __device__ __forceinline__ float bflo(unsigned v) { return __uint_as_float(v << 16); }
; __device__ __forceinline__ float bfhi(unsigned v) { return __uint_as_float(v & 0xffff0000u); }
; __device__ __forceinline__ float siluf_(float x) { return x * __builtin_amdgcn_rcpf(1.0f + __expf(-x)); }
;   __device__ __forceinline__ void operator()(EPI_ARGS) const {
;     ...
;         for (int m = 0; m < 4; ++m) {
;           const size_t row = row0 + ai * HALF + m * 16;
;           const f32x4 v0 = acc[ai][bj][m][0], v1 = acc[ai][bj][m][1];
;           u32x4 o;
;           o.x = pack2(v0[0] * s0[0] * siluf_(bflo(z[m].x)), v0[1] * s0[1] * siluf_(bfhi(z[m].x)));
;           o.y = pack2(v0[2] * s0[2] * siluf_(bflo(z[m].y)), v0[3] * s0[3] * siluf_(bfhi(z[m].y)));
;           o.z = pack2(v1[0] * s1[0] * siluf_(bflo(z[m].z)), v1[1] * s1[1] * siluf_(bfhi(z[m].z)));
;           o.w = pack2(v1[2] * s1[2] * siluf_(bflo(z[m].w)), v1[3] * s1[3] * siluf_(bfhi(z[m].w)));
;           *(u32x4*)(y0 + row * DM + c) = o;
;         }
	v_lshlrev_b32_e32 v53, 16, v48
	v_mul_f32_e32 v2, 0xbfb8aa3b, v53
	v_exp_f32_e32 v2, v2
	v_mov_b32_e32 v54, v32
	v_mov_b32_e32 v52, v72
	s_and_b64 vcc, exec, s[18:19]
	v_add_f32_e32 v2, 1.0, v2
	v_rcp_f32_e32 v55, v2
	s_mov_b32 s33, s16
	s_mov_b32 s2, s14
	s_mov_b64 s[4:5], s[22:23]
	v_pk_mul_f32 v[52:53], v[54:55], v[52:53]
	v_mov_b32_e32 v54, v33
	v_mul_f32_e32 v2, v52, v53
	v_and_b32_e32 v53, 0xffff0000, v48
	v_mul_f32_e32 v32, 0xbfb8aa3b, v53
	v_exp_f32_e32 v32, v32
	v_mov_b32_e32 v52, v73
	v_mov_b32_e32 v48, v75
	s_mov_b64 s[6:7], s[20:21]
	v_add_f32_e32 v32, 1.0, v32
	v_rcp_f32_e32 v55, v32
	s_nop 0
	v_pk_mul_f32 v[32:33], v[54:55], v[52:53]
	s_nop 0
	v_mul_f32_e32 v32, v32, v33
	v_lshlrev_b32_e32 v53, 16, v49
	v_cvt_pk_bf16_f32 v32, v2, v32
	v_mul_f32_e32 v2, 0xbfb8aa3b, v53
	v_exp_f32_e32 v2, v2
	v_and_b32_e32 v49, 0xffff0000, v49
	v_mul_f32_e32 v33, 0xbfb8aa3b, v49
	v_exp_f32_e32 v33, v33
	v_add_f32_e32 v2, 1.0, v2
	v_rcp_f32_e32 v55, v2
	v_mov_b32_e32 v54, v34
	v_mov_b32_e32 v52, v74
	v_add_f32_e32 v33, 1.0, v33
	v_pk_mul_f32 v[52:53], v[54:55], v[52:53]
	s_nop 0
	v_mul_f32_e32 v2, v52, v53
	v_rcp_f32_e32 v53, v33
	v_mov_b32_e32 v52, v35
	v_pk_mul_f32 v[34:35], v[52:53], v[48:49]
	s_nop 0
	v_mul_f32_e32 v33, v34, v35
	v_lshlrev_b32_e32 v35, 16, v50
	v_cvt_pk_bf16_f32 v33, v2, v33
	v_mul_f32_e32 v2, 0xbfb8aa3b, v35
	v_exp_f32_e32 v2, v2
	v_mov_b32_e32 v48, v28
	v_mov_b32_e32 v34, v68
	v_add_f32_e32 v2, 1.0, v2
	v_rcp_f32_e32 v49, v2
	s_nop 0
	v_pk_mul_f32 v[34:35], v[48:49], v[34:35]
	s_nop 0
	v_mul_f32_e32 v2, v34, v35
	v_and_b32_e32 v35, 0xffff0000, v50
	v_mul_f32_e32 v28, 0xbfb8aa3b, v35
	v_exp_f32_e32 v28, v28
	v_mov_b32_e32 v48, v29
	v_mov_b32_e32 v34, v69
	v_add_f32_e32 v28, 1.0, v28
	v_rcp_f32_e32 v49, v28
	s_nop 0
	v_pk_mul_f32 v[28:29], v[48:49], v[34:35]
	s_nop 0
	v_mul_f32_e32 v28, v28, v29
	v_lshlrev_b32_e32 v29, 16, v51
	v_cvt_pk_bf16_f32 v34, v2, v28
	v_mul_f32_e32 v2, 0xbfb8aa3b, v29
	v_exp_f32_e32 v2, v2
	v_mov_b32_e32 v48, v30
	v_mov_b32_e32 v28, v70
	v_mov_b32_e32 v30, v24
	v_add_f32_e32 v2, 1.0, v2
	v_rcp_f32_e32 v49, v2
	s_nop 0
	v_pk_mul_f32 v[28:29], v[48:49], v[28:29]
	s_nop 0
	v_mul_f32_e32 v2, v28, v29
	v_and_b32_e32 v29, 0xffff0000, v51
	v_mul_f32_e32 v28, 0xbfb8aa3b, v29
	v_exp_f32_e32 v28, v28
	v_mov_b32_e32 v48, v31
	v_add_f32_e32 v28, 1.0, v28
	v_rcp_f32_e32 v49, v28
	v_mov_b32_e32 v28, v71
	v_pk_mul_f32 v[28:29], v[48:49], v[28:29]
	s_nop 0
	v_mul_f32_e32 v28, v28, v29
	v_lshlrev_b32_e32 v29, 16, v44
	v_cvt_pk_bf16_f32 v35, v2, v28
	v_mul_f32_e32 v2, 0xbfb8aa3b, v29
	v_exp_f32_e32 v2, v2
	v_mov_b32_e32 v28, v72
	global_store_dwordx4 v[96:97], v[32:35], off offset:256
	v_add_f32_e32 v2, 1.0, v2
	v_rcp_f32_e32 v31, v2
	s_nop 0
	v_pk_mul_f32 v[28:29], v[30:31], v[28:29]
	s_nop 0
	v_mul_f32_e32 v2, v28, v29
	v_and_b32_e32 v29, 0xffff0000, v44
	v_mul_f32_e32 v24, 0xbfb8aa3b, v29
	v_exp_f32_e32 v24, v24
	v_mov_b32_e32 v30, v25
	v_mov_b32_e32 v28, v73
	v_add_f32_e32 v24, 1.0, v24
	v_rcp_f32_e32 v31, v24
	s_nop 0
	v_pk_mul_f32 v[24:25], v[30:31], v[28:29]
	s_nop 0
	v_mul_f32_e32 v24, v24, v25
	v_lshlrev_b32_e32 v29, 16, v45
	v_cvt_pk_bf16_f32 v24, v2, v24
	v_mul_f32_e32 v2, 0xbfb8aa3b, v29
	v_exp_f32_e32 v2, v2
	v_mov_b32_e32 v30, v26
	v_mov_b32_e32 v28, v74
	v_add_f32_e32 v2, 1.0, v2
	v_rcp_f32_e32 v31, v2
	s_nop 0
	v_pk_mul_f32 v[28:29], v[30:31], v[28:29]
	s_nop 0
	v_mul_f32_e32 v2, v28, v29
	v_and_b32_e32 v29, 0xffff0000, v45
	v_mul_f32_e32 v25, 0xbfb8aa3b, v29
	v_exp_f32_e32 v25, v25
	v_mov_b32_e32 v30, v27
	v_mov_b32_e32 v28, v75
	v_add_f32_e32 v25, 1.0, v25
	v_rcp_f32_e32 v31, v25
	s_nop 0
	v_pk_mul_f32 v[26:27], v[30:31], v[28:29]
	s_nop 0
	v_mul_f32_e32 v25, v26, v27
	v_lshlrev_b32_e32 v27, 16, v46
	v_cvt_pk_bf16_f32 v25, v2, v25
	v_mul_f32_e32 v2, 0xbfb8aa3b, v27
	v_exp_f32_e32 v2, v2
	v_mov_b32_e32 v28, v20
	v_mov_b32_e32 v26, v68
	v_add_f32_e32 v2, 1.0, v2
	v_rcp_f32_e32 v29, v2
	s_nop 0
	v_pk_mul_f32 v[26:27], v[28:29], v[26:27]
	s_nop 0
	v_mul_f32_e32 v2, v26, v27
	v_and_b32_e32 v27, 0xffff0000, v46
	v_mul_f32_e32 v20, 0xbfb8aa3b, v27
	v_exp_f32_e32 v20, v20
	v_mov_b32_e32 v28, v21
	v_mov_b32_e32 v26, v69
	v_add_f32_e32 v20, 1.0, v20
	v_rcp_f32_e32 v29, v20
	s_nop 0
	v_pk_mul_f32 v[20:21], v[28:29], v[26:27]
	s_nop 0
	v_mul_f32_e32 v20, v20, v21
	v_lshlrev_b32_e32 v21, 16, v47
	v_cvt_pk_bf16_f32 v26, v2, v20
	v_mul_f32_e32 v2, 0xbfb8aa3b, v21
	v_exp_f32_e32 v2, v2
	v_mov_b32_e32 v28, v22
	v_mov_b32_e32 v20, v70
	v_mov_b32_e32 v22, v16
	v_add_f32_e32 v2, 1.0, v2
	v_rcp_f32_e32 v29, v2
	s_nop 0
	v_pk_mul_f32 v[20:21], v[28:29], v[20:21]
	s_nop 0
	v_mul_f32_e32 v2, v20, v21
	v_and_b32_e32 v21, 0xffff0000, v47
	v_mul_f32_e32 v20, 0xbfb8aa3b, v21
	v_exp_f32_e32 v20, v20
	v_mov_b32_e32 v28, v23
	v_add_f32_e32 v20, 1.0, v20
	v_rcp_f32_e32 v29, v20
	v_mov_b32_e32 v20, v71
	v_pk_mul_f32 v[20:21], v[28:29], v[20:21]
	s_nop 0
	v_mul_f32_e32 v20, v20, v21
	v_lshlrev_b32_e32 v21, 16, v40
	v_cvt_pk_bf16_f32 v27, v2, v20
	v_mul_f32_e32 v2, 0xbfb8aa3b, v21
	v_exp_f32_e32 v2, v2
	v_mov_b32_e32 v20, v72
	global_store_dwordx4 v[98:99], v[24:27], off offset:256
; __device__ __forceinline__ float bflo(unsigned v) { return __uint_as_float(v << 16); }
; __device__ __forceinline__ float bfhi(unsigned v) { return __uint_as_float(v & 0xffff0000u); }
; __device__ __forceinline__ float siluf_(float x) { return x * __builtin_amdgcn_rcpf(1.0f + __expf(-x)); }
; #define PG8_WAIT_V(n) asm volatile("s_waitcnt vmcnt(" #n ")" ::: "memory")
; #define PG8_BAR __builtin_amdgcn_s_barrier()
; template <class Epi, class AddrA, class AddrB>
; __device__ __forceinline__ void gemm_phase(const Sched S, const int lda, const int ldb, const int K, const AddrA addrA,
;                                            const AddrB addrB, const Epi E) {
;     ...
;     if (!has_next) break;
;     if (!(Epi::KEEP && cur.br + 1 < S.nbr)) {
; #pragma unroll
;       for (int a = 0; a < 2; ++a)
; #pragma unroll
;         for (int b = 0; b < 2; ++b)
; #pragma unroll
;           for (int m = 0; m < 4; ++m)
; #pragma unroll
;             for (int n = 0; n < 2; ++n) acc[a][b][m][n] = (f32x4){0.f, 0.f, 0.f, 0.f};
;     }
;     cur = nxt; cA = nA; cB = nB; ++ui;
;   }
;   PG8_WAIT_V(0);
;   if (wr == 0) PG8_BAR;
;   PG8_BAR;
;   __device__ __forceinline__ void operator()(EPI_ARGS) const {
;     ...
;         for (int m = 0; m < 4; ++m) {
;           const size_t row = row0 + ai * HALF + m * 16;
;           const f32x4 v0 = acc[ai][bj][m][0], v1 = acc[ai][bj][m][1];
;           u32x4 o;
;           o.x = pack2(v0[0] * s0[0] * siluf_(bflo(z[m].x)), v0[1] * s0[1] * siluf_(bfhi(z[m].x)));
;           o.y = pack2(v0[2] * s0[2] * siluf_(bflo(z[m].y)), v0[3] * s0[3] * siluf_(bfhi(z[m].y)));
;           o.z = pack2(v1[0] * s1[0] * siluf_(bflo(z[m].z)), v1[1] * s1[1] * siluf_(bfhi(z[m].z)));
;           o.w = pack2(v1[2] * s1[2] * siluf_(bflo(z[m].w)), v1[3] * s1[3] * siluf_(bfhi(z[m].w)));
;           *(u32x4*)(y0 + row * DM + c) = o;
;         }
	v_add_f32_e32 v2, 1.0, v2
	v_rcp_f32_e32 v23, v2
	s_nop 0
	v_pk_mul_f32 v[20:21], v[22:23], v[20:21]
	s_nop 0
	v_mul_f32_e32 v2, v20, v21
	v_and_b32_e32 v21, 0xffff0000, v40
	v_mul_f32_e32 v16, 0xbfb8aa3b, v21
	v_exp_f32_e32 v16, v16
	v_mov_b32_e32 v22, v17
	v_mov_b32_e32 v20, v73
	v_add_f32_e32 v16, 1.0, v16
	v_rcp_f32_e32 v23, v16
	s_nop 0
	v_pk_mul_f32 v[16:17], v[22:23], v[20:21]
	s_nop 0
	v_mul_f32_e32 v16, v16, v17
	v_lshlrev_b32_e32 v21, 16, v41
	v_cvt_pk_bf16_f32 v16, v2, v16
	v_mul_f32_e32 v2, 0xbfb8aa3b, v21
	v_exp_f32_e32 v2, v2
	v_mov_b32_e32 v22, v18
	v_mov_b32_e32 v20, v74
	v_add_f32_e32 v2, 1.0, v2
	v_rcp_f32_e32 v23, v2
	s_nop 0
	v_pk_mul_f32 v[20:21], v[22:23], v[20:21]
	s_nop 0
	v_mul_f32_e32 v2, v20, v21
	v_and_b32_e32 v21, 0xffff0000, v41
	v_mul_f32_e32 v17, 0xbfb8aa3b, v21
	v_exp_f32_e32 v17, v17
	v_mov_b32_e32 v22, v19
	v_mov_b32_e32 v20, v75
	v_add_f32_e32 v17, 1.0, v17
	v_rcp_f32_e32 v23, v17
	s_nop 0
	v_pk_mul_f32 v[18:19], v[22:23], v[20:21]
	s_nop 0
	v_mul_f32_e32 v17, v18, v19
	v_lshlrev_b32_e32 v19, 16, v42
	v_cvt_pk_bf16_f32 v17, v2, v17
	v_mul_f32_e32 v2, 0xbfb8aa3b, v19
	v_exp_f32_e32 v2, v2
	v_mov_b32_e32 v20, v12
	v_mov_b32_e32 v18, v68
	v_add_f32_e32 v2, 1.0, v2
	v_rcp_f32_e32 v21, v2
	s_nop 0
	v_pk_mul_f32 v[18:19], v[20:21], v[18:19]
	s_nop 0
	v_mul_f32_e32 v2, v18, v19
	v_and_b32_e32 v19, 0xffff0000, v42
	v_mul_f32_e32 v12, 0xbfb8aa3b, v19
	v_exp_f32_e32 v12, v12
	v_mov_b32_e32 v20, v13
	v_mov_b32_e32 v18, v69
	v_add_f32_e32 v12, 1.0, v12
	v_rcp_f32_e32 v21, v12
	s_nop 0
	v_pk_mul_f32 v[12:13], v[20:21], v[18:19]
	s_nop 0
	v_mul_f32_e32 v12, v12, v13
	v_lshlrev_b32_e32 v13, 16, v43
	v_cvt_pk_bf16_f32 v18, v2, v12
	v_mul_f32_e32 v2, 0xbfb8aa3b, v13
	v_exp_f32_e32 v2, v2
	v_mov_b32_e32 v20, v14
	v_mov_b32_e32 v12, v70
	v_mov_b32_e32 v14, v8
	v_add_f32_e32 v2, 1.0, v2
	v_rcp_f32_e32 v21, v2
	s_nop 0
	v_pk_mul_f32 v[12:13], v[20:21], v[12:13]
	s_nop 0
	v_mul_f32_e32 v2, v12, v13
	v_and_b32_e32 v13, 0xffff0000, v43
	v_mul_f32_e32 v12, 0xbfb8aa3b, v13
	v_exp_f32_e32 v12, v12
	v_mov_b32_e32 v20, v15
	v_add_f32_e32 v12, 1.0, v12
	v_rcp_f32_e32 v21, v12
	v_mov_b32_e32 v12, v71
	v_pk_mul_f32 v[12:13], v[20:21], v[12:13]
	s_nop 0
	v_mul_f32_e32 v12, v12, v13
	v_lshlrev_b32_e32 v13, 16, v36
	v_cvt_pk_bf16_f32 v19, v2, v12
	v_mul_f32_e32 v2, 0xbfb8aa3b, v13
	v_exp_f32_e32 v2, v2
	v_mov_b32_e32 v12, v72
	global_store_dwordx4 v[104:105], v[16:19], off offset:256
	v_add_f32_e32 v2, 1.0, v2
	v_rcp_f32_e32 v15, v2
	s_nop 0
	v_pk_mul_f32 v[12:13], v[14:15], v[12:13]
	s_nop 0
	v_mul_f32_e32 v2, v12, v13
	v_and_b32_e32 v13, 0xffff0000, v36
	v_mul_f32_e32 v8, 0xbfb8aa3b, v13
	v_exp_f32_e32 v8, v8
	v_mov_b32_e32 v14, v9
	v_mov_b32_e32 v12, v73
	v_add_f32_e32 v8, 1.0, v8
	v_rcp_f32_e32 v15, v8
	s_nop 0
	v_pk_mul_f32 v[8:9], v[14:15], v[12:13]
	s_nop 0
	v_mul_f32_e32 v8, v8, v9
	v_lshlrev_b32_e32 v13, 16, v37
	v_cvt_pk_bf16_f32 v8, v2, v8
	v_mul_f32_e32 v2, 0xbfb8aa3b, v13
	v_exp_f32_e32 v2, v2
	v_mov_b32_e32 v14, v10
	v_mov_b32_e32 v12, v74
	v_add_f32_e32 v2, 1.0, v2
	v_rcp_f32_e32 v15, v2
	s_nop 0
	v_pk_mul_f32 v[12:13], v[14:15], v[12:13]
	s_nop 0
	v_mul_f32_e32 v2, v12, v13
	v_and_b32_e32 v13, 0xffff0000, v37
	v_mul_f32_e32 v9, 0xbfb8aa3b, v13
	v_exp_f32_e32 v9, v9
	v_mov_b32_e32 v14, v11
	v_mov_b32_e32 v12, v75
	v_add_f32_e32 v9, 1.0, v9
	v_rcp_f32_e32 v15, v9
	s_nop 0
	v_pk_mul_f32 v[10:11], v[14:15], v[12:13]
	s_nop 0
	v_mul_f32_e32 v9, v10, v11
	v_lshlrev_b32_e32 v11, 16, v38
	v_cvt_pk_bf16_f32 v9, v2, v9
	v_mul_f32_e32 v2, 0xbfb8aa3b, v11
	v_exp_f32_e32 v2, v2
	v_mov_b32_e32 v12, v4
	v_mov_b32_e32 v10, v68
	v_add_f32_e32 v2, 1.0, v2
	v_rcp_f32_e32 v13, v2
	s_nop 0
	v_pk_mul_f32 v[10:11], v[12:13], v[10:11]
	s_nop 0
	v_mul_f32_e32 v2, v10, v11
	v_and_b32_e32 v11, 0xffff0000, v38
	v_mul_f32_e32 v4, 0xbfb8aa3b, v11
	v_exp_f32_e32 v4, v4
	v_mov_b32_e32 v12, v5
	v_mov_b32_e32 v10, v69
	v_add_f32_e32 v4, 1.0, v4
	v_rcp_f32_e32 v13, v4
	s_nop 0
	v_pk_mul_f32 v[4:5], v[12:13], v[10:11]
	s_nop 0
	v_mul_f32_e32 v4, v4, v5
	v_lshlrev_b32_e32 v5, 16, v39
	v_cvt_pk_bf16_f32 v10, v2, v4
	v_mul_f32_e32 v2, 0xbfb8aa3b, v5
	v_exp_f32_e32 v2, v2
	v_mov_b32_e32 v12, v6
	v_mov_b32_e32 v4, v70
	v_add_f32_e32 v2, 1.0, v2
	v_rcp_f32_e32 v13, v2
	s_nop 0
	v_pk_mul_f32 v[4:5], v[12:13], v[4:5]
	s_nop 0
	v_mul_f32_e32 v2, v4, v5
	v_and_b32_e32 v5, 0xffff0000, v39
	v_mul_f32_e32 v4, 0xbfb8aa3b, v5
	v_exp_f32_e32 v4, v4
	v_mov_b32_e32 v12, v7
	v_add_f32_e32 v4, 1.0, v4
	v_rcp_f32_e32 v13, v4
	v_mov_b32_e32 v4, v71
	v_pk_mul_f32 v[4:5], v[12:13], v[4:5]
	s_nop 0
	v_mul_f32_e32 v4, v4, v5
	v_cvt_pk_bf16_f32 v11, v2, v4
	global_store_dwordx4 v[92:93], v[8:11], off offset:256
	s_cbranch_vccz .LBB0_482
	s_waitcnt vmcnt(0)
	v_readlane_b32 s44, v244, 59
	v_readlane_b32 s40, v243, 18
	s_cmpk_gt_u32 s24, 0xff
	s_mov_b32 s43, 0x800000
	v_readlane_b32 s45, v244, 60
	v_readlane_b32 s46, v244, 61
	v_readlane_b32 s47, v244, 62
	v_readlane_b32 s48, v244, 63
	v_readlane_b32 s49, v243, 0
	v_readlane_b32 s50, v243, 1
	v_readlane_b32 s51, v243, 2
	v_readlane_b32 s41, v243, 19
	s_cbranch_scc1 .LBB0_489
	s_barrier

; __device__ __forceinline__ unsigned xb_ld(unsigned* p) { return __hip_atomic_load(p, __ATOMIC_RELAXED, __HIP_MEMORY_SCOPE_AGENT); }
; __device__ __forceinline__ unsigned xb_add(unsigned* p, unsigned v) { return __hip_atomic_fetch_add(p, v, __ATOMIC_RELAXED, __HIP_MEMORY_SCOPE_AGENT); }
; #define XB_SPIN(cond, bar) do { unsigned _sp = 0; while (cond) { __builtin_amdgcn_s_sleep(1); \
;     if ((++_sp & 255u) == 0u) { if (xb_ld(&(bar)[XB_TMO])) break; if (_sp > XB_SPIN_CAP) { atomicAdd(&(bar)[XB_TMO], 1u); break; } } } } while (0)
; __device__ __forceinline__ void xcd_barrier(const XcdBarrier& b) {
;     ...
;     const unsigned old = xb_add(&bar[XB_XSUB(bx)], 1u);
;     const unsigned gen = old / nloc;
;     if (old + 1u == (gen + 1u) * nloc) {
;       __builtin_amdgcn_fence(__ATOMIC_RELEASE, "agent");
;       asm volatile("s_waitcnt vmcnt(0)" ::: "memory");
;       const unsigned og = xb_add(&bar[XB_TOP], 1u);
;       const unsigned tg = og / nx;
;       if (og + 1u == (tg + 1u) * nx) xb_add(&bar[XB_TOPGEN], 1u);
;       else XB_SPIN(xb_ld(&bar[XB_TOPGEN]) == tg, bar);
;       __builtin_amdgcn_fence(__ATOMIC_ACQUIRE, "agent");
;       xb_add(&bar[XB_XGEN(bx)], 1u);
;       asm volatile("s_waitcnt vmcnt(0)" ::: "memory");
;     } else {
;       XB_SPIN(xb_ld(&bar[XB_XGEN(bx)]) == gen, bar);
.LBB0_505:
	s_lshl_b32 s22, s33, 6
	s_add_i32 s0, s22, 0x500
	s_mov_b32 s1, s73
	s_lshl_b64 s[0:1], s[0:1], 2
	v_readlane_b32 s4, v245, 20
	s_add_u32 s0, s4, s0
	v_readlane_b32 s4, v245, 21
	s_addc_u32 s1, s4, s1
	v_mov_b64_e32 v[4:5], s[0:1]
	global_atomic_add v4, v[4:5], v165, off sc0
	v_cvt_f32_u32_e32 v1, v2
	v_sub_u32_e32 v5, 0, v2
	v_rcp_iflag_f32_e32 v1, v1
	s_nop 0
	v_mul_f32_e32 v1, 0x4f7ffffe, v1
	v_cvt_u32_f32_e32 v1, v1
	v_mul_lo_u32 v5, v5, v1
	v_mul_hi_u32 v5, v1, v5
	v_add_u32_e32 v1, v1, v5
	s_waitcnt vmcnt(0) lgkmcnt(0)
	v_mul_hi_u32 v1, v4, v1
	v_mul_lo_u32 v5, v1, v2
	v_sub_u32_e32 v5, v4, v5
	v_cmp_ge_u32_e32 vcc, v5, v2
	v_add_u32_e32 v6, 1, v1
	s_nop 0
	v_cndmask_b32_e32 v1, v1, v6, vcc
	v_sub_u32_e32 v6, v5, v2
	v_cndmask_b32_e32 v5, v5, v6, vcc
	v_cmp_ge_u32_e32 vcc, v5, v2
	v_add_u32_e32 v5, 1, v1
	v_add_u32_e32 v6, 1, v4
	v_cndmask_b32_e32 v1, v1, v5, vcc
	v_mad_u64_u32 v[4:5], s[0:1], v2, v1, v[2:3]
	v_cmp_ne_u32_e32 vcc, v6, v4
	s_and_saveexec_b64 s[0:1], vcc
	s_xor_b64 s[0:1], exec, s[0:1]
	s_cbranch_execz .LBB0_518
	s_add_i32 s4, s22, 0x900
	s_mov_b32 s5, s73
	s_lshl_b64 s[4:5], s[4:5], 2
	v_readlane_b32 s6, v245, 20
	s_add_u32 s6, s6, s4
	v_readlane_b32 s4, v245, 21
	s_addc_u32 s7, s4, s5
	v_mov_b64_e32 v[4:5], s[6:7]
	global_load_dword v0, v[4:5], off sc1
	s_waitcnt vmcnt(0) lgkmcnt(0)
	v_cmp_eq_u32_e32 vcc, v0, v1
	s_and_saveexec_b64 s[4:5], vcc
	s_cbranch_execz .LBB0_517
	s_mov_b32 s23, 1
	s_mov_b64 s[8:9], 0
	s_branch .LBB0_509

; __device__ __forceinline__ unsigned xb_add(unsigned* p, unsigned v) { return __hip_atomic_fetch_add(p, v, __ATOMIC_RELAXED, __HIP_MEMORY_SCOPE_AGENT); }
; __device__ __forceinline__ void xcd_barrier(const XcdBarrier& b) {
;     ...
;       __builtin_amdgcn_fence(__ATOMIC_ACQUIRE, "agent");
;       xb_add(&bar[XB_XGEN(bx)], 1u);
;       asm volatile("s_waitcnt vmcnt(0)" ::: "memory");
.LBB0_533:
	s_or_b64 exec, exec, s[0:1]
	s_add_i32 s0, s22, 0x900
	s_mov_b32 s1, s73
	s_lshl_b64 s[0:1], s[0:1], 2
	v_readlane_b32 s4, v245, 20
	s_add_u32 s0, s4, s0
	v_readlane_b32 s4, v245, 21
	s_addc_u32 s1, s4, s1
	v_mov_b64_e32 v[0:1], s[0:1]
	s_waitcnt vmcnt(0) lgkmcnt(0)
	buffer_inv sc1
	global_atomic_add v[0:1], v165, off
	s_waitcnt vmcnt(0)

; #define PG8_WAIT_V(n) asm volatile("s_waitcnt vmcnt(" #n ")" ::: "memory")
; #define PG8_WAIT_L(n) asm volatile("s_waitcnt lgkmcnt(" #n ")" ::: "memory")
; #define PG8_BAR __builtin_amdgcn_s_barrier()
; #define PG8_SCHED __builtin_amdgcn_sched_barrier(0)
; template <class Epi, class AddrA, class AddrB>
; __device__ __forceinline__ void gemm_phase(const Sched S, const int lda, const int ldb, const int K, const AddrA addrA,
;                                            const AddrB addrB, const Epi E) {
;     ...
;       PG8_LDB(B0, 0, 0); PG8_SCHED; PG8_LDA(At, 0, 0); PG8_STAGE(PG8_SA(1, 1), a1 + hstepA, voffA);
;       PG8_WAIT_L(8); PG8_BAR; PG8_WAIT_L(0); PG8_MMA(0, 0, At, B0); PG8_BAR; PG8_SCHED;
;       PG8_LDB(B1, 0, 1); PG8_STAGE(PG8_SB(0, 0), b2, voffB);
;       PG8_BAR; PG8_WAIT_L(0); PG8_MMA(0, 1, At, B1); PG8_BAR;
;       PG8_LDA(At, 0, 1); PG8_STAGE(PG8_SA(0, 0), a2, voffA);
;       PG8_BAR; PG8_WAIT_L(0); PG8_MMA(1, 0, At, B0); PG8_BAR; PG8_SCHED;
;       PG8_STAGE(PG8_SB(0, 1), b2 + hstepB, voffB);
;       PG8_WAIT_V(6); PG8_BAR; PG8_MMA(1, 1, At, B1); PG8_BAR;
;       PG8_LDB(B0, 1, 0); PG8_SCHED; PG8_LDA(At, 1, 0); PG8_STAGE(PG8_SA(0, 1), a2 + hstepA, voffA);
;       PG8_WAIT_L(8); PG8_BAR; PG8_WAIT_L(0); PG8_MMA(0, 0, At, B0); PG8_BAR; PG8_SCHED;
;       PG8_LDB(B1, 1, 1); PG8_STAGE(PG8_SB(1, 0), b3, voffB);
;       PG8_BAR; PG8_WAIT_L(0); PG8_MMA(0, 1, At, B1); PG8_BAR;
;       PG8_LDA(At, 1, 1); PG8_STAGE(PG8_SA(1, 0), a3, voffA);
;       PG8_BAR; PG8_WAIT_L(0); PG8_MMA(1, 0, At, B0); PG8_BAR; PG8_SCHED;
;       PG8_STAGE(PG8_SB(1, 1), b3 + hstepB, voffB);
;       PG8_WAIT_V(6); PG8_BAR; PG8_MMA(1, 1, At, B1); PG8_BAR;
.LBB0_543:
	s_add_u32 s4, s2, 0xfff80080
	s_addc_u32 s5, s3, -1
	s_add_i32 s43, 0, 0x10000
	v_add_u32_e32 v0, s43, v167
	ds_read_b128 v[132:135], v0
	ds_read_b128 v[136:139], v0 offset:1024
	ds_read_b128 v[140:143], v0 offset:2048
	ds_read_b128 v[144:147], v0 offset:3072
	s_cmp_eq_u32 s42, 28
	s_cselect_b32 s7, s1, s5
	s_cselect_b32 s6, s9, s4
	s_cselect_b32 s5, s13, s41
	s_cselect_b32 s4, s15, s33
	v_lshl_add_u64 v[0:1], s[2:3], 0, v[180:181]
	s_add_i32 m0, s28, 0xc000
	ds_read_b128 v[148:151], v188
	ds_read_b128 v[152:155], v188 offset:1024
	ds_read_b128 v[156:159], v188 offset:2048
	ds_read_b128 v[160:163], v188 offset:3072
	ds_read_b128 v[182:185], v188 offset:4096
	ds_read_b128 v[190:193], v188 offset:5120
	ds_read_b128 v[194:197], v188 offset:6144
	ds_read_b128 v[212:215], v188 offset:7168
	global_load_lds_dwordx4 v[0:1], off
	v_lshl_add_u64 v[0:1], s[2:3], 0, v[178:179]
	s_add_i32 m0, s28, 0xe000
	s_nop 0
	global_load_lds_dwordx4 v[0:1], off
	s_waitcnt lgkmcnt(8)
	s_barrier
	s_waitcnt lgkmcnt(0)
	s_setprio 1
	s_waitcnt lgkmcnt(0)
	v_mfma_f32_16x16x32_bf16 v[128:131], v[132:135], v[148:151], v[128:131]
	v_mfma_f32_16x16x32_bf16 v[124:127], v[140:143], v[148:151], v[124:127]
	v_mfma_f32_16x16x32_bf16 v[120:123], v[132:135], v[156:159], v[120:123]
	v_mfma_f32_16x16x32_bf16 v[116:119], v[140:143], v[156:159], v[116:119]
	v_mfma_f32_16x16x32_bf16 v[112:115], v[132:135], v[182:185], v[112:115]
	v_mfma_f32_16x16x32_bf16 v[108:111], v[140:143], v[182:185], v[108:111]
	v_mfma_f32_16x16x32_bf16 v[104:107], v[132:135], v[194:197], v[104:107]
	v_mfma_f32_16x16x32_bf16 v[100:103], v[140:143], v[194:197], v[100:103]
	v_mfma_f32_16x16x32_bf16 v[128:131], v[136:139], v[152:155], v[128:131]
	v_mfma_f32_16x16x32_bf16 v[124:127], v[144:147], v[152:155], v[124:127]
	v_mfma_f32_16x16x32_bf16 v[120:123], v[136:139], v[160:163], v[120:123]
	v_mfma_f32_16x16x32_bf16 v[116:119], v[144:147], v[160:163], v[116:119]
	v_mfma_f32_16x16x32_bf16 v[112:115], v[136:139], v[190:193], v[112:115]
	v_mfma_f32_16x16x32_bf16 v[108:111], v[144:147], v[190:193], v[108:111]
	v_mfma_f32_16x16x32_bf16 v[104:107], v[136:139], v[212:215], v[104:107]
	v_mfma_f32_16x16x32_bf16 v[100:103], v[144:147], v[212:215], v[100:103]
	s_setprio 0
	s_barrier
	s_add_i32 s46, 0, 0x14000
	v_add_u32_e32 v0, s46, v167
	s_add_i32 s43, s43, s27
	ds_read_b128 v[216:219], v0
	ds_read_b128 v[220:223], v0 offset:1024
	ds_read_b128 v[224:227], v0 offset:2048
	ds_read_b128 v[228:231], v0 offset:3072
	v_lshl_add_u64 v[0:1], s[4:5], 0, v[172:173]
	s_mov_b32 m0, s43
	v_lshl_add_u64 v[232:233], s[4:5], 0, v[168:169]
	global_load_lds_dwordx4 v[0:1], off
	s_add_i32 m0, s43, 0x2000
	s_nop 0
	global_load_lds_dwordx4 v[232:233], off
	s_barrier
	s_waitcnt lgkmcnt(0)
	s_setprio 1
	s_waitcnt lgkmcnt(0)
	v_mfma_f32_16x16x32_bf16 v[96:99], v[216:219], v[148:151], v[96:99]
	v_mfma_f32_16x16x32_bf16 v[92:95], v[224:227], v[148:151], v[92:95]
	v_mfma_f32_16x16x32_bf16 v[88:91], v[216:219], v[156:159], v[88:91]
	v_mfma_f32_16x16x32_bf16 v[84:87], v[224:227], v[156:159], v[84:87]
	v_mfma_f32_16x16x32_bf16 v[80:83], v[216:219], v[182:185], v[80:83]
	v_mfma_f32_16x16x32_bf16 v[76:79], v[224:227], v[182:185], v[76:79]
	v_mfma_f32_16x16x32_bf16 v[72:75], v[216:219], v[194:197], v[72:75]
	v_mfma_f32_16x16x32_bf16 v[68:71], v[224:227], v[194:197], v[68:71]
	v_mfma_f32_16x16x32_bf16 v[96:99], v[220:223], v[152:155], v[96:99]
	v_mfma_f32_16x16x32_bf16 v[92:95], v[228:231], v[152:155], v[92:95]
	v_mfma_f32_16x16x32_bf16 v[88:91], v[220:223], v[160:163], v[88:91]
	v_mfma_f32_16x16x32_bf16 v[84:87], v[228:231], v[160:163], v[84:87]
	v_mfma_f32_16x16x32_bf16 v[80:83], v[220:223], v[190:193], v[80:83]
	v_mfma_f32_16x16x32_bf16 v[76:79], v[228:231], v[190:193], v[76:79]
	v_mfma_f32_16x16x32_bf16 v[72:75], v[220:223], v[212:215], v[72:75]
	v_mfma_f32_16x16x32_bf16 v[68:71], v[228:231], v[212:215], v[68:71]
	s_setprio 0
	s_mov_b32 m0, s28
	v_lshl_add_u64 v[234:235], s[6:7], 0, v[174:175]
	s_barrier
	ds_read_b128 v[148:151], v188 offset:16384
	ds_read_b128 v[152:155], v188 offset:17408
	ds_read_b128 v[156:159], v188 offset:18432
	ds_read_b128 v[160:163], v188 offset:19456
	ds_read_b128 v[182:185], v188 offset:20480
	ds_read_b128 v[190:193], v188 offset:21504
	ds_read_b128 v[194:197], v188 offset:22528
	ds_read_b128 v[212:215], v188 offset:23552
	global_load_lds_dwordx4 v[234:235], off
	v_lshl_add_u64 v[236:237], s[6:7], 0, v[170:171]
	s_mov_b32 m0, s29
	s_nop 0
	global_load_lds_dwordx4 v[236:237], off
	s_barrier
	s_waitcnt lgkmcnt(0)
	s_setprio 1
	s_waitcnt lgkmcnt(0)
	v_mfma_f32_16x16x32_bf16 v[64:67], v[132:135], v[148:151], v[64:67]
	v_mfma_f32_16x16x32_bf16 v[60:63], v[140:143], v[148:151], v[60:63]
	v_mfma_f32_16x16x32_bf16 v[56:59], v[132:135], v[156:159], v[56:59]
	v_mfma_f32_16x16x32_bf16 v[52:55], v[140:143], v[156:159], v[52:55]
	v_mfma_f32_16x16x32_bf16 v[48:51], v[132:135], v[182:185], v[48:51]
	v_mfma_f32_16x16x32_bf16 v[44:47], v[140:143], v[182:185], v[44:47]
	v_mfma_f32_16x16x32_bf16 v[40:43], v[132:135], v[194:197], v[40:43]
	v_mfma_f32_16x16x32_bf16 v[36:39], v[140:143], v[194:197], v[36:39]
	v_mfma_f32_16x16x32_bf16 v[64:67], v[136:139], v[152:155], v[64:67]
	v_mfma_f32_16x16x32_bf16 v[60:63], v[144:147], v[152:155], v[60:63]
	v_mfma_f32_16x16x32_bf16 v[56:59], v[136:139], v[160:163], v[56:59]
	v_mfma_f32_16x16x32_bf16 v[52:55], v[144:147], v[160:163], v[52:55]
	v_mfma_f32_16x16x32_bf16 v[48:51], v[136:139], v[190:193], v[48:51]
	v_mfma_f32_16x16x32_bf16 v[44:47], v[144:147], v[190:193], v[44:47]
	v_mfma_f32_16x16x32_bf16 v[40:43], v[136:139], v[212:215], v[40:43]
	v_mfma_f32_16x16x32_bf16 v[36:39], v[144:147], v[212:215], v[36:39]
	s_setprio 0
	s_barrier
; #define PG8_WAIT_V(n) asm volatile("s_waitcnt vmcnt(" #n ")" ::: "memory")
; #define PG8_WAIT_L(n) asm volatile("s_waitcnt lgkmcnt(" #n ")" ::: "memory")
; #define PG8_BAR __builtin_amdgcn_s_barrier()
; #define PG8_SCHED __builtin_amdgcn_sched_barrier(0)
; template <class Epi, class AddrA, class AddrB>
; __device__ __forceinline__ void gemm_phase(const Sched S, const int lda, const int ldb, const int K, const AddrA addrA,
;                                            const AddrB addrB, const Epi E) {
;     ...
;       PG8_LDB(B0, 0, 0); PG8_SCHED; PG8_LDA(At, 0, 0); PG8_STAGE(PG8_SA(1, 1), a1 + hstepA, voffA);
;       PG8_WAIT_L(8); PG8_BAR; PG8_WAIT_L(0); PG8_MMA(0, 0, At, B0); PG8_BAR; PG8_SCHED;
;       PG8_LDB(B1, 0, 1); PG8_STAGE(PG8_SB(0, 0), b2, voffB);
;       PG8_BAR; PG8_WAIT_L(0); PG8_MMA(0, 1, At, B1); PG8_BAR;
;       PG8_LDA(At, 0, 1); PG8_STAGE(PG8_SA(0, 0), a2, voffA);
;       PG8_BAR; PG8_WAIT_L(0); PG8_MMA(1, 0, At, B0); PG8_BAR; PG8_SCHED;
;       PG8_STAGE(PG8_SB(0, 1), b2 + hstepB, voffB);
;       PG8_WAIT_V(6); PG8_BAR; PG8_MMA(1, 1, At, B1); PG8_BAR;
;       PG8_LDB(B0, 1, 0); PG8_SCHED; PG8_LDA(At, 1, 0); PG8_STAGE(PG8_SA(0, 1), a2 + hstepA, voffA);
;       PG8_WAIT_L(8); PG8_BAR; PG8_WAIT_L(0); PG8_MMA(0, 0, At, B0); PG8_BAR; PG8_SCHED;
;       PG8_LDB(B1, 1, 1); PG8_STAGE(PG8_SB(1, 0), b3, voffB);
;       PG8_BAR; PG8_WAIT_L(0); PG8_MMA(0, 1, At, B1); PG8_BAR;
;       PG8_LDA(At, 1, 1); PG8_STAGE(PG8_SA(1, 0), a3, voffA);
;       PG8_BAR; PG8_WAIT_L(0); PG8_MMA(1, 0, At, B0); PG8_BAR; PG8_SCHED;
;       PG8_STAGE(PG8_SB(1, 1), b3 + hstepB, voffB);
;       PG8_WAIT_V(6); PG8_BAR; PG8_MMA(1, 1, At, B1); PG8_BAR;
	s_add_u32 s44, s4, 0x80000
	s_addc_u32 s45, s5, 0
	s_add_i32 s43, s46, s27
	v_lshl_add_u64 v[132:133], s[44:45], 0, v[172:173]
	s_mov_b32 m0, s43
	s_nop 0
	global_load_lds_dwordx4 v[132:133], off
	v_lshl_add_u64 v[132:133], s[44:45], 0, v[168:169]
	s_add_i32 m0, s43, 0x2000
	s_nop 0
	global_load_lds_dwordx4 v[132:133], off
	s_waitcnt vmcnt(6)
	s_barrier
	s_setprio 1
	v_mfma_f32_16x16x32_bf16 v[32:35], v[216:219], v[148:151], v[32:35]
	v_mfma_f32_16x16x32_bf16 v[28:31], v[224:227], v[148:151], v[28:31]
	v_mfma_f32_16x16x32_bf16 v[24:27], v[216:219], v[156:159], v[24:27]
	v_mfma_f32_16x16x32_bf16 v[20:23], v[224:227], v[156:159], v[20:23]
	v_mfma_f32_16x16x32_bf16 v[16:19], v[216:219], v[182:185], v[16:19]
	v_mfma_f32_16x16x32_bf16 v[12:15], v[224:227], v[182:185], v[12:15]
	v_mfma_f32_16x16x32_bf16 v[8:11], v[216:219], v[194:197], v[8:11]
	v_mfma_f32_16x16x32_bf16 v[4:7], v[224:227], v[194:197], v[4:7]
	v_mfma_f32_16x16x32_bf16 v[32:35], v[220:223], v[152:155], v[32:35]
	v_mfma_f32_16x16x32_bf16 v[28:31], v[228:231], v[152:155], v[28:31]
	v_mfma_f32_16x16x32_bf16 v[24:27], v[220:223], v[160:163], v[24:27]
	v_mfma_f32_16x16x32_bf16 v[20:23], v[228:231], v[160:163], v[20:23]
	v_mfma_f32_16x16x32_bf16 v[16:19], v[220:223], v[190:193], v[16:19]
	v_mfma_f32_16x16x32_bf16 v[12:15], v[228:231], v[190:193], v[12:15]
	v_mfma_f32_16x16x32_bf16 v[8:11], v[220:223], v[212:215], v[8:11]
	v_mfma_f32_16x16x32_bf16 v[4:7], v[228:231], v[212:215], v[4:7]
	s_setprio 0
	s_add_i32 s43, 0, 0x18000
	v_add_u32_e32 v2, s43, v167
	s_barrier
	ds_read_b128 v[132:135], v2
	ds_read_b128 v[136:139], v2 offset:1024
	ds_read_b128 v[140:143], v2 offset:2048
	ds_read_b128 v[144:147], v2 offset:3072
	s_add_u32 s6, s6, 0x80000
	s_addc_u32 s7, s7, 0
	s_mov_b32 m0, s30
	v_lshl_add_u64 v[216:217], s[6:7], 0, v[174:175]
	ds_read_b128 v[148:151], v188 offset:32768
	ds_read_b128 v[152:155], v188 offset:33792
	ds_read_b128 v[156:159], v188 offset:34816
	ds_read_b128 v[160:163], v188 offset:35840
	ds_read_b128 v[182:185], v188 offset:36864
	ds_read_b128 v[190:193], v188 offset:37888
	ds_read_b128 v[194:197], v188 offset:38912
	ds_read_b128 v[212:215], v188 offset:39936
	global_load_lds_dwordx4 v[216:217], off
	v_lshl_add_u64 v[216:217], s[6:7], 0, v[170:171]
	s_mov_b32 m0, s31
	s_nop 0
	global_load_lds_dwordx4 v[216:217], off
	s_waitcnt lgkmcnt(8)
	s_barrier
	s_waitcnt lgkmcnt(0)
	s_setprio 1
	s_waitcnt lgkmcnt(0)
	v_mfma_f32_16x16x32_bf16 v[128:131], v[132:135], v[148:151], v[128:131]
	v_mfma_f32_16x16x32_bf16 v[124:127], v[140:143], v[148:151], v[124:127]
	v_mfma_f32_16x16x32_bf16 v[120:123], v[132:135], v[156:159], v[120:123]
	v_mfma_f32_16x16x32_bf16 v[116:119], v[140:143], v[156:159], v[116:119]
	v_mfma_f32_16x16x32_bf16 v[112:115], v[132:135], v[182:185], v[112:115]
	v_mfma_f32_16x16x32_bf16 v[108:111], v[140:143], v[182:185], v[108:111]
	v_mfma_f32_16x16x32_bf16 v[104:107], v[132:135], v[194:197], v[104:107]
	v_mfma_f32_16x16x32_bf16 v[100:103], v[140:143], v[194:197], v[100:103]
	v_mfma_f32_16x16x32_bf16 v[128:131], v[136:139], v[152:155], v[128:131]
	v_mfma_f32_16x16x32_bf16 v[124:127], v[144:147], v[152:155], v[124:127]
	v_mfma_f32_16x16x32_bf16 v[120:123], v[136:139], v[160:163], v[120:123]
	v_mfma_f32_16x16x32_bf16 v[116:119], v[144:147], v[160:163], v[116:119]
	v_mfma_f32_16x16x32_bf16 v[112:115], v[136:139], v[190:193], v[112:115]
	v_mfma_f32_16x16x32_bf16 v[108:111], v[144:147], v[190:193], v[108:111]
	v_mfma_f32_16x16x32_bf16 v[104:107], v[136:139], v[212:215], v[104:107]
	v_mfma_f32_16x16x32_bf16 v[100:103], v[144:147], v[212:215], v[100:103]
	s_setprio 0
	s_barrier
	s_add_i32 s6, 0, 0x1c000
	s_add_i32 s7, s43, s27
	v_add_u32_e32 v2, s6, v167
	v_lshl_add_u64 v[0:1], v[0:1], 0, s[52:53]
	s_mov_b32 m0, s7
	ds_read_b128 v[216:219], v2
	ds_read_b128 v[220:223], v2 offset:1024
	ds_read_b128 v[224:227], v2 offset:2048
	ds_read_b128 v[228:231], v2 offset:3072
	global_load_lds_dwordx4 v[0:1], off
	v_lshl_add_u64 v[0:1], v[232:233], 0, s[52:53]
	s_add_i32 m0, s7, 0x2000
	s_nop 0
	global_load_lds_dwordx4 v[0:1], off
	s_barrier
	s_waitcnt lgkmcnt(0)
	s_setprio 1
	s_waitcnt lgkmcnt(0)
	v_mfma_f32_16x16x32_bf16 v[96:99], v[216:219], v[148:151], v[96:99]
	v_mfma_f32_16x16x32_bf16 v[92:95], v[224:227], v[148:151], v[92:95]
	v_mfma_f32_16x16x32_bf16 v[88:91], v[216:219], v[156:159], v[88:91]
	v_mfma_f32_16x16x32_bf16 v[84:87], v[224:227], v[156:159], v[84:87]
	v_mfma_f32_16x16x32_bf16 v[80:83], v[216:219], v[182:185], v[80:83]
	v_mfma_f32_16x16x32_bf16 v[76:79], v[224:227], v[182:185], v[76:79]
	v_mfma_f32_16x16x32_bf16 v[72:75], v[216:219], v[194:197], v[72:75]
	v_mfma_f32_16x16x32_bf16 v[68:71], v[224:227], v[194:197], v[68:71]
	v_mfma_f32_16x16x32_bf16 v[96:99], v[220:223], v[152:155], v[96:99]
	v_mfma_f32_16x16x32_bf16 v[92:95], v[228:231], v[152:155], v[92:95]
	v_mfma_f32_16x16x32_bf16 v[88:91], v[220:223], v[160:163], v[88:91]
	v_mfma_f32_16x16x32_bf16 v[84:87], v[228:231], v[160:163], v[84:87]
	v_mfma_f32_16x16x32_bf16 v[80:83], v[220:223], v[190:193], v[80:83]
	v_mfma_f32_16x16x32_bf16 v[76:79], v[228:231], v[190:193], v[76:79]
	v_mfma_f32_16x16x32_bf16 v[72:75], v[220:223], v[212:215], v[72:75]
	v_mfma_f32_16x16x32_bf16 v[68:71], v[228:231], v[212:215], v[68:71]
	s_setprio 0
	s_mov_b32 m0, s38
	v_lshl_add_u64 v[0:1], v[234:235], 0, s[52:53]
	s_barrier
	ds_read_b128 v[148:151], v188 offset:49152
	ds_read_b128 v[152:155], v188 offset:50176
	ds_read_b128 v[156:159], v188 offset:51200
	ds_read_b128 v[160:163], v188 offset:52224
	ds_read_b128 v[182:185], v188 offset:53248
	ds_read_b128 v[190:193], v188 offset:54272
	ds_read_b128 v[194:197], v188 offset:55296
	ds_read_b128 v[212:215], v188 offset:56320
	global_load_lds_dwordx4 v[0:1], off
	v_lshl_add_u64 v[0:1], v[236:237], 0, s[52:53]
	s_mov_b32 m0, s39
	s_nop 0
	global_load_lds_dwordx4 v[0:1], off
	s_barrier
; #define PG8_WAIT_V(n) asm volatile("s_waitcnt vmcnt(" #n ")" ::: "memory")
; template <class Epi, class AddrA, class AddrB>
; __device__ __forceinline__ void gemm_phase(const Sched S, const int lda, const int ldb, const int K, const AddrA addrA,
;                                            const AddrB addrB, const Epi E) {
;     ...
;       PG8_LDB(B0, 0, 0); PG8_SCHED; PG8_LDA(At, 0, 0); PG8_STAGE(PG8_SA(1, 1), a1 + hstepA, voffA);
;       PG8_WAIT_L(8); PG8_BAR; PG8_WAIT_L(0); PG8_MMA(0, 0, At, B0); PG8_BAR; PG8_SCHED;
;       PG8_LDB(B1, 0, 1); PG8_STAGE(PG8_SB(0, 0), b2, voffB);
;       PG8_BAR; PG8_WAIT_L(0); PG8_MMA(0, 1, At, B1); PG8_BAR;
;       PG8_LDA(At, 0, 1); PG8_STAGE(PG8_SA(0, 0), a2, voffA);
;       PG8_BAR; PG8_WAIT_L(0); PG8_MMA(1, 0, At, B0); PG8_BAR; PG8_SCHED;
;       PG8_STAGE(PG8_SB(0, 1), b2 + hstepB, voffB);
;       PG8_WAIT_V(6); PG8_BAR; PG8_MMA(1, 1, At, B1); PG8_BAR;
;       PG8_LDB(B0, 1, 0); PG8_SCHED; PG8_LDA(At, 1, 0); PG8_STAGE(PG8_SA(0, 1), a2 + hstepA, voffA);
;       PG8_WAIT_L(8); PG8_BAR; PG8_WAIT_L(0); PG8_MMA(0, 0, At, B0); PG8_BAR; PG8_SCHED;
;       PG8_LDB(B1, 1, 1); PG8_STAGE(PG8_SB(1, 0), b3, voffB);
;       PG8_BAR; PG8_WAIT_L(0); PG8_MMA(0, 1, At, B1); PG8_BAR;
;       PG8_LDA(At, 1, 1); PG8_STAGE(PG8_SA(1, 0), a3, voffA);
;       PG8_BAR; PG8_WAIT_L(0); PG8_MMA(1, 0, At, B0); PG8_BAR; PG8_SCHED;
;       PG8_STAGE(PG8_SB(1, 1), b3 + hstepB, voffB);
;       PG8_WAIT_V(6); PG8_BAR; PG8_MMA(1, 1, At, B1); PG8_BAR;
;   __device__ __forceinline__ void operator()(EPI_ARGS) const {
;     const int col0 = u.pn * 256 + wc * 32 + 8 * fq;
;     const int br = u.br, brn = br < 2 ? br + 1 : 2;
;     const unsigned loff0 = (unsigned)((wr * 64 + fr) * PLD + wc * 32 + 8 * fq);
;     const bf16_t* pc = proj + ((size_t)((GT + br * DM) / 256 + u.pn) * MTOK + (size_t)u.pm * 256) * PLD;
;     const bf16_t* pn_ = proj + ((size_t)((GT + brn * DM) / 256 + u.pn) * MTOK + (size_t)u.pm * 256) * PLD;
;     bf16_t* mrow = merged + ((size_t)u.pm * 256 + wr * 64 + fr) * DM + col0;
; #pragma unroll
;     for (int bj = 0; bj < 2; ++bj) {
;       const int c = col0 + bj * HALF;
;       float gc[8], gn[8];
;       {
;         const f32x4 a0 = *(const f32x4*)(bg + br * DM + c), a1 = *(const f32x4*)(bg + br * DM + c + 4);
;         const f32x4 b0 = *(const f32x4*)(bg + brn * DM + c), b1 = *(const f32x4*)(bg + brn * DM + c + 4);
; #pragma unroll
	s_waitcnt lgkmcnt(0)
	s_setprio 1
	s_waitcnt lgkmcnt(0)
	v_mfma_f32_16x16x32_bf16 v[64:67], v[132:135], v[148:151], v[64:67]
	v_mfma_f32_16x16x32_bf16 v[60:63], v[140:143], v[148:151], v[60:63]
	v_mfma_f32_16x16x32_bf16 v[56:59], v[132:135], v[156:159], v[56:59]
	v_mfma_f32_16x16x32_bf16 v[52:55], v[140:143], v[156:159], v[52:55]
	v_mfma_f32_16x16x32_bf16 v[48:51], v[132:135], v[182:185], v[48:51]
	v_mfma_f32_16x16x32_bf16 v[44:47], v[140:143], v[182:185], v[44:47]
	v_mfma_f32_16x16x32_bf16 v[40:43], v[132:135], v[194:197], v[40:43]
	v_mfma_f32_16x16x32_bf16 v[36:39], v[140:143], v[194:197], v[36:39]
	v_mfma_f32_16x16x32_bf16 v[64:67], v[136:139], v[152:155], v[64:67]
	v_mfma_f32_16x16x32_bf16 v[60:63], v[144:147], v[152:155], v[60:63]
	v_mfma_f32_16x16x32_bf16 v[56:59], v[136:139], v[160:163], v[56:59]
	v_mfma_f32_16x16x32_bf16 v[52:55], v[144:147], v[160:163], v[52:55]
	v_mfma_f32_16x16x32_bf16 v[48:51], v[136:139], v[190:193], v[48:51]
	v_mfma_f32_16x16x32_bf16 v[44:47], v[144:147], v[190:193], v[44:47]
	v_mfma_f32_16x16x32_bf16 v[40:43], v[136:139], v[212:215], v[40:43]
	v_mfma_f32_16x16x32_bf16 v[36:39], v[144:147], v[212:215], v[36:39]
	s_setprio 0
	s_barrier
	s_add_u32 s4, s4, 0x80080
	s_addc_u32 s5, s5, 0
	s_add_i32 s6, s6, s27
	v_lshl_add_u64 v[0:1], s[4:5], 0, v[172:173]
	s_mov_b32 m0, s6
	s_nop 0
	global_load_lds_dwordx4 v[0:1], off
	v_lshl_add_u64 v[0:1], s[4:5], 0, v[168:169]
	s_add_i32 m0, s6, 0x2000
	s_nop 0
	global_load_lds_dwordx4 v[0:1], off
	s_waitcnt vmcnt(6)
	s_barrier
	s_setprio 1
	v_mfma_f32_16x16x32_bf16 v[32:35], v[216:219], v[148:151], v[32:35]
	v_mfma_f32_16x16x32_bf16 v[28:31], v[224:227], v[148:151], v[28:31]
	v_mfma_f32_16x16x32_bf16 v[24:27], v[216:219], v[156:159], v[24:27]
	v_mfma_f32_16x16x32_bf16 v[20:23], v[224:227], v[156:159], v[20:23]
	v_mfma_f32_16x16x32_bf16 v[16:19], v[216:219], v[182:185], v[16:19]
	v_mfma_f32_16x16x32_bf16 v[12:15], v[224:227], v[182:185], v[12:15]
	v_mfma_f32_16x16x32_bf16 v[8:11], v[216:219], v[194:197], v[8:11]
	v_mfma_f32_16x16x32_bf16 v[4:7], v[224:227], v[194:197], v[4:7]
	v_mfma_f32_16x16x32_bf16 v[32:35], v[220:223], v[152:155], v[32:35]
	v_mfma_f32_16x16x32_bf16 v[28:31], v[228:231], v[152:155], v[28:31]
	v_mfma_f32_16x16x32_bf16 v[24:27], v[220:223], v[160:163], v[24:27]
	v_mfma_f32_16x16x32_bf16 v[20:23], v[228:231], v[160:163], v[20:23]
	v_mfma_f32_16x16x32_bf16 v[16:19], v[220:223], v[190:193], v[16:19]
	v_mfma_f32_16x16x32_bf16 v[12:15], v[228:231], v[190:193], v[12:15]
	v_mfma_f32_16x16x32_bf16 v[8:11], v[220:223], v[212:215], v[8:11]
	v_mfma_f32_16x16x32_bf16 v[4:7], v[228:231], v[212:215], v[4:7]
	s_setprio 0
	s_add_i32 s42, s42, 2
	s_add_u32 s33, s33, 0x100
	s_addc_u32 s41, s41, 0
	s_add_u32 s2, s2, 0x100
	s_addc_u32 s3, s3, 0
	s_cmp_gt_u32 s42, 29
	s_barrier
	s_cbranch_scc0 .LBB0_543
	s_cmp_gt_i32 s10, 1
	s_cselect_b64 s[6:7], -1, 0
	s_lshl_b32 s42, s10, 11
	s_add_i32 s2, s42, 0x4c00
	s_ashr_i32 s2, s2, 8
	s_add_i32 s2, s2, s11
	s_ashr_i32 s3, s2, 31
	s_min_i32 s1, s10, 1
	s_ashr_i32 s9, s8, 31
	s_lshl_b64 s[2:3], s[2:3], 23
	s_add_u32 s2, s34, s2
	s_addc_u32 s3, s35, s3
	s_lshl_b64 s[4:5], s[8:9], 17
	s_add_u32 s2, s2, s4
	s_addc_u32 s3, s3, s5
	s_lshl_b32 s1, s1, 11
	s_add_i32 s44, s1, 0x800
	s_addk_i32 s1, 0x5400
	s_ashr_i32 s1, s1, 8
	s_add_i32 s46, s1, s11
	s_ashr_i32 s47, s46, 31
	s_lshl_b64 s[46:47], s[46:47], 23
	s_add_u32 s1, s34, s46
	v_lshl_or_b32 v132, s11, 8, v187
	s_addc_u32 s11, s35, s47
	s_add_u32 s4, s1, s4
	s_addc_u32 s5, s11, s5
	s_ashr_i32 s43, s42, 31
	s_lshl_b64 s[8:9], s[8:9], 20
	s_ashr_i32 s45, s44, 31
	s_lshl_b64 s[42:43], s[42:43], 2
	s_add_u32 s42, s36, s42
	s_addc_u32 s43, s37, s43
	s_lshl_b64 s[44:45], s[44:45], 2
	s_add_u32 s44, s36, s44
	v_lshl_add_u64 v[0:1], v[176:177], 0, s[8:9]
	v_ashrrev_i32_e32 v133, 31, v132
	s_addc_u32 s45, s37, s45
	v_lshl_add_u64 v[0:1], v[132:133], 1, v[0:1]
	v_lshlrev_b64 v[132:133], 2, v[132:133]
	v_lshl_add_u64 v[182:183], s[42:43], 0, v[132:133]
	v_lshl_add_u64 v[184:185], s[44:45], 0, v[132:133]
	v_mov_b32_e32 v2, v186
	global_load_dwordx4 v[144:147], v[182:183], off
	global_load_dwordx4 v[136:139], v[182:183], off offset:16
	global_load_dwordx4 v[140:143], v[184:185], off
	global_load_dwordx4 v[132:135], v[184:185], off offset:16
	s_cmp_lt_i32 s10, 2
	v_lshlrev_b64 v[148:149], 1, v[2:3]
	v_lshl_add_u64 v[150:151], s[2:3], 0, v[148:149]
	v_lshl_add_u64 v[148:149], s[4:5], 0, v[148:149]
	global_load_dwordx4 v[190:193], v[150:151], off
	global_load_dwordx4 v[160:163], v[148:149], off
	v_add_u32_e32 v148, 0x1000, v2
	v_mov_b32_e32 v149, v3
	v_lshlrev_b64 v[148:149], 1, v[148:149]
	v_lshl_add_u64 v[150:151], s[2:3], 0, v[148:149]
	v_lshl_add_u64 v[148:149], s[4:5], 0, v[148:149]
	global_load_dwordx4 v[194:197], v[150:151], off
	global_load_dwordx4 v[156:159], v[148:149], off
	v_add_u32_e32 v148, 0x2000, v2
	v_mov_b32_e32 v149, v3
	v_lshlrev_b64 v[148:149], 1, v[148:149]
	v_lshl_add_u64 v[150:151], s[2:3], 0, v[148:149]
	v_lshl_add_u64 v[148:149], s[4:5], 0, v[148:149]
	v_add_u32_e32 v2, 0x3000, v2
	global_load_dwordx4 v[234:237], v[150:151], off
	global_load_dwordx4 v[152:155], v[148:149], off
	v_lshlrev_b64 v[148:149], 1, v[2:3]
	v_lshl_add_u64 v[150:151], s[2:3], 0, v[148:149]
	v_lshl_add_u64 v[148:149], s[4:5], 0, v[148:149]
	global_load_dwordx4 v[238:241], v[150:151], off
	s_nop 0
	global_load_dwordx4 v[148:151], v[148:149], off
	s_waitcnt vmcnt(0) lgkmcnt(0)
; __device__ __forceinline__ float sigmoidf_(float x) { return __builtin_amdgcn_rcpf(1.0f + __expf(-x)); }
;   __device__ __forceinline__ void operator()(EPI_ARGS) const {
;     ...
;       for (int ai = 0; ai < 2; ++ai) {
;         unsigned loff = loff0;
;         asm volatile("" : "+v"(loff));
;         u32x4 zc[4], zn[4];
; #pragma unroll
;         for (int m = 0; m < 4; ++m) {
;           const unsigned o = loff + (unsigned)((ai * HALF + m * 16) * PLD + bj * HALF);
;           zc[m] = *(const u32x4*)(pc + o);
;           zn[m] = *(const u32x4*)(pn_ + o);
;         }
;         __builtin_amdgcn_sched_barrier(0);
;         if (br < 2) {
; #pragma unroll
;           for (int m = 0; m < 4; ++m) {
;             float xc[8], xn[8];
;             unpack8(zc[m], xc);
;             unpack8(zn[m], xn);
; #pragma unroll
;             for (int k = 0; k < 8; ++k) {
;               const float ec = __expf(-fmaxf(xc[k] + gc[k], -40.f)), en = __expf(-fmaxf(xn[k] + gn[k], -40.f));
;               const float f = (1.0f + en) * __builtin_amdgcn_rcpf(1.0f + ec);
;               acc[ai][bj][m][k >> 2][k & 3] *= f;
;             }
;           }
;         } else {
; #pragma unroll
;           for (int m = 0; m < 4; ++m) {
;             float xc[8], y[8];
;             unpack8(zc[m], xc);
; #pragma unroll
;             for (int k = 0; k < 8; ++k) y[k] = acc[ai][bj][m][k >> 2][k & 3] * sigmoidf_(fmaxf(xc[k] + gc[k], -40.f));
;             u32x4 o;
;             o.x = pack2(y[0], y[1]); o.y = pack2(y[2], y[3]); o.z = pack2(y[4], y[5]); o.w = pack2(y[6], y[7]);
;             *(u32x4*)(mrow + (size_t)(ai * HALF + m * 16) * DM + bj * HALF) = o;
;           }
	v_lshlrev_b32_e32 v2, 16, v190
	v_and_b32_e32 v189, 0xffff0000, v190
	v_lshlrev_b32_e32 v190, 16, v191
	v_and_b32_e32 v191, 0xffff0000, v191
	v_lshlrev_b32_e32 v212, 16, v192
	v_and_b32_e32 v192, 0xffff0000, v192
	v_lshlrev_b32_e32 v213, 16, v193
	v_and_b32_e32 v193, 0xffff0000, v193
	v_add_f32_e32 v2, v144, v2
	v_add_f32_e32 v189, v145, v189
	v_add_f32_e32 v190, v146, v190
	v_add_f32_e32 v191, v147, v191
	v_add_f32_e32 v212, v136, v212
	v_add_f32_e32 v192, v137, v192
	v_add_f32_e32 v213, v138, v213
	v_add_f32_e32 v193, v139, v193
	s_mov_b64 s[8:9], -1
	v_max_f32_e32 v233, 0xc2200000, v2
	v_max_f32_e32 v232, 0xc2200000, v189
	v_max_f32_e32 v231, 0xc2200000, v190
	v_max_f32_e32 v230, 0xc2200000, v191
	v_max_f32_e32 v229, 0xc2200000, v212
	v_max_f32_e32 v228, 0xc2200000, v192
	v_max_f32_e32 v227, 0xc2200000, v213
	v_max_f32_e32 v226, 0xc2200000, v193
	v_lshlrev_b32_e32 v225, 16, v194
	v_and_b32_e32 v224, 0xffff0000, v194
	v_lshlrev_b32_e32 v223, 16, v195
	v_and_b32_e32 v222, 0xffff0000, v195
	v_lshlrev_b32_e32 v221, 16, v196
	v_and_b32_e32 v220, 0xffff0000, v196
	v_lshlrev_b32_e32 v219, 16, v197
	v_and_b32_e32 v218, 0xffff0000, v197
	v_lshlrev_b32_e32 v217, 16, v234
	v_and_b32_e32 v216, 0xffff0000, v234
	v_lshlrev_b32_e32 v215, 16, v235
	v_and_b32_e32 v214, 0xffff0000, v235
	v_lshlrev_b32_e32 v213, 16, v236
	v_and_b32_e32 v212, 0xffff0000, v236
	v_lshlrev_b32_e32 v197, 16, v237
	v_and_b32_e32 v196, 0xffff0000, v237
	v_lshlrev_b32_e32 v195, 16, v238
	v_and_b32_e32 v194, 0xffff0000, v238
	v_lshlrev_b32_e32 v193, 16, v239
	v_and_b32_e32 v192, 0xffff0000, v239
	v_lshlrev_b32_e32 v191, 16, v240
	v_and_b32_e32 v190, 0xffff0000, v240
	v_lshlrev_b32_e32 v189, 16, v241
	v_and_b32_e32 v2, 0xffff0000, v241
	s_cbranch_scc1 .LBB0_546
	v_mul_f32_e32 v234, 0xbfb8aa3b, v233
	v_mul_f32_e32 v235, 0xbfb8aa3b, v232
	v_mul_f32_e32 v236, 0xbfb8aa3b, v231
	v_exp_f32_e32 v234, v234
	v_exp_f32_e32 v235, v235
	v_exp_f32_e32 v236, v236
	v_mul_f32_e32 v237, 0xbfb8aa3b, v230
	v_exp_f32_e32 v237, v237
	v_mul_f32_e32 v238, 0xbfb8aa3b, v229
	v_mul_f32_e32 v239, 0xbfb8aa3b, v228
	v_add_f32_e32 v234, 1.0, v234
	v_add_f32_e32 v235, 1.0, v235
	v_add_f32_e32 v236, 1.0, v236
	v_exp_f32_e32 v238, v238
	v_exp_f32_e32 v239, v239
	v_mul_f32_e32 v240, 0xbfb8aa3b, v227
	v_mul_f32_e32 v241, 0xbfb8aa3b, v226
	v_rcp_f32_e32 v234, v234
	v_rcp_f32_e32 v235, v235
	v_rcp_f32_e32 v236, v236
	v_add_f32_e32 v237, 1.0, v237
	v_exp_f32_e32 v240, v240
	v_exp_f32_e32 v241, v241
	v_rcp_f32_e32 v237, v237
	v_add_f32_e32 v238, 1.0, v238
	v_add_f32_e32 v239, 1.0, v239
	v_mul_f32_e32 v234, v128, v234
	v_mul_f32_e32 v235, v129, v235
	v_mul_f32_e32 v236, v130, v236
	v_rcp_f32_e32 v238, v238
	v_rcp_f32_e32 v239, v239
	v_add_f32_e32 v240, 1.0, v240
	v_add_f32_e32 v241, 1.0, v241
	v_mul_f32_e32 v237, v131, v237
	v_rcp_f32_e32 v240, v240
	v_rcp_f32_e32 v241, v241
	v_cvt_pk_bf16_f32 v234, v234, v235
	v_cvt_pk_bf16_f32 v235, v236, v237
	v_add_f32_e32 v236, v144, v225
	v_max_f32_e32 v236, 0xc2200000, v236
	v_mul_f32_e32 v236, 0xbfb8aa3b, v236
	v_mul_f32_e32 v238, v124, v238
	v_mul_f32_e32 v239, v125, v239
	v_exp_f32_e32 v242, v236
	v_cvt_pk_bf16_f32 v236, v238, v239
	v_mul_f32_e32 v240, v126, v240
	v_mul_f32_e32 v241, v127, v241
	v_cvt_pk_bf16_f32 v237, v240, v241
	global_store_dwordx4 v[0:1], v[234:237], off
	v_add_f32_e32 v238, v136, v221
	v_max_f32_e32 v238, 0xc2200000, v238
	v_add_f32_e32 v235, v145, v224
	v_add_f32_e32 v236, v146, v223
	v_max_f32_e32 v235, 0xc2200000, v235
	v_max_f32_e32 v236, 0xc2200000, v236
	v_add_f32_e32 v237, v147, v222
	v_add_f32_e32 v239, v137, v220
	v_mul_f32_e32 v235, 0xbfb8aa3b, v235
	v_mul_f32_e32 v236, 0xbfb8aa3b, v236
	v_max_f32_e32 v237, 0xc2200000, v237
	v_mul_f32_e32 v238, 0xbfb8aa3b, v238
	v_max_f32_e32 v239, 0xc2200000, v239
	v_exp_f32_e32 v235, v235
	v_exp_f32_e32 v236, v236
	v_mul_f32_e32 v237, 0xbfb8aa3b, v237
	v_exp_f32_e32 v238, v238
	v_mul_f32_e32 v239, 0xbfb8aa3b, v239
	v_add_f32_e32 v240, v138, v219
	v_exp_f32_e32 v237, v237
	v_exp_f32_e32 v239, v239
	v_max_f32_e32 v240, 0xc2200000, v240
	v_add_f32_e32 v241, v139, v218
	v_mul_f32_e32 v240, 0xbfb8aa3b, v240
	v_max_f32_e32 v241, 0xc2200000, v241
	v_exp_f32_e32 v240, v240
	v_mul_f32_e32 v241, 0xbfb8aa3b, v241
	v_add_f32_e32 v234, 1.0, v242
	v_add_f32_e32 v235, 1.0, v235
	v_add_f32_e32 v236, 1.0, v236
	v_add_f32_e32 v238, 1.0, v238
	v_exp_f32_e32 v241, v241
	v_rcp_f32_e32 v234, v234
	v_rcp_f32_e32 v235, v235
	v_rcp_f32_e32 v236, v236
	v_add_f32_e32 v237, 1.0, v237
	v_rcp_f32_e32 v238, v238
	v_add_f32_e32 v239, 1.0, v239
	v_rcp_f32_e32 v237, v237
	v_rcp_f32_e32 v239, v239
	v_add_f32_e32 v240, 1.0, v240
	v_rcp_f32_e32 v240, v240
	v_add_f32_e32 v241, 1.0, v241
	v_mul_f32_e32 v234, v120, v234
; __device__ __forceinline__ float sigmoidf_(float x) { return __builtin_amdgcn_rcpf(1.0f + __expf(-x)); }
;   __device__ __forceinline__ void operator()(EPI_ARGS) const {
;     ...
;           for (int m = 0; m < 4; ++m) {
;             float xc[8], y[8];
;             unpack8(zc[m], xc);
; #pragma unroll
;             for (int k = 0; k < 8; ++k) y[k] = acc[ai][bj][m][k >> 2][k & 3] * sigmoidf_(fmaxf(xc[k] + gc[k], -40.f));
;             u32x4 o;
;             o.x = pack2(y[0], y[1]); o.y = pack2(y[2], y[3]); o.z = pack2(y[4], y[5]); o.w = pack2(y[6], y[7]);
;             *(u32x4*)(mrow + (size_t)(ai * HALF + m * 16) * DM + bj * HALF) = o;
;           }
	v_mul_f32_e32 v235, v121, v235
	v_mul_f32_e32 v236, v122, v236
	v_rcp_f32_e32 v241, v241
	v_mul_f32_e32 v238, v116, v238
	v_mul_f32_e32 v237, v123, v237
	v_mul_f32_e32 v239, v117, v239
	v_cvt_pk_bf16_f32 v234, v234, v235
	v_cvt_pk_bf16_f32 v235, v236, v237
	v_cvt_pk_bf16_f32 v236, v238, v239
	v_add_f32_e32 v238, v144, v217
	v_max_f32_e32 v238, 0xc2200000, v238
	v_mul_f32_e32 v240, v118, v240
	v_mul_f32_e32 v238, 0xbfb8aa3b, v238
	v_mul_f32_e32 v241, v119, v241
	v_cvt_pk_bf16_f32 v237, v240, v241
	v_exp_f32_e32 v240, v238
	v_add_co_u32_e32 v238, vcc, s67, v0
	v_add_f32_e32 v241, v139, v196
	s_nop 0
	v_addc_co_u32_e32 v239, vcc, 0, v1, vcc
	global_store_dwordx4 v[238:239], v[234:237], off
	v_add_f32_e32 v238, v136, v213
	v_max_f32_e32 v238, 0xc2200000, v238
	v_add_f32_e32 v235, v145, v216
	v_add_f32_e32 v236, v146, v215
	v_max_f32_e32 v235, 0xc2200000, v235
	v_max_f32_e32 v236, 0xc2200000, v236
	v_add_f32_e32 v237, v147, v214
	v_add_f32_e32 v239, v137, v212
	v_mul_f32_e32 v235, 0xbfb8aa3b, v235
	v_mul_f32_e32 v236, 0xbfb8aa3b, v236
	v_max_f32_e32 v237, 0xc2200000, v237
	v_mul_f32_e32 v238, 0xbfb8aa3b, v238
	v_max_f32_e32 v239, 0xc2200000, v239
	v_add_f32_e32 v234, 1.0, v240
	v_exp_f32_e32 v235, v235
	v_exp_f32_e32 v236, v236
	v_mul_f32_e32 v237, 0xbfb8aa3b, v237
	v_exp_f32_e32 v238, v238
	v_mul_f32_e32 v239, 0xbfb8aa3b, v239
	v_add_f32_e32 v240, v138, v197
	v_exp_f32_e32 v237, v237
	v_exp_f32_e32 v239, v239
	v_max_f32_e32 v240, 0xc2200000, v240
	v_mul_f32_e32 v240, 0xbfb8aa3b, v240
	v_max_f32_e32 v241, 0xc2200000, v241
	v_exp_f32_e32 v240, v240
	v_mul_f32_e32 v241, 0xbfb8aa3b, v241
	v_add_f32_e32 v235, 1.0, v235
	v_add_f32_e32 v236, 1.0, v236
	v_add_f32_e32 v238, 1.0, v238
	v_exp_f32_e32 v241, v241
	v_rcp_f32_e32 v234, v234
	v_rcp_f32_e32 v235, v235
	v_rcp_f32_e32 v236, v236
	v_add_f32_e32 v237, 1.0, v237
	v_rcp_f32_e32 v238, v238
	v_add_f32_e32 v239, 1.0, v239
	v_rcp_f32_e32 v237, v237
	v_rcp_f32_e32 v239, v239
	v_add_f32_e32 v240, 1.0, v240
	v_rcp_f32_e32 v240, v240
	v_add_f32_e32 v241, 1.0, v241
	v_mul_f32_e32 v234, v112, v234
	v_mul_f32_e32 v235, v113, v235
	v_mul_f32_e32 v236, v114, v236
	v_rcp_f32_e32 v241, v241
	v_mul_f32_e32 v238, v108, v238
	v_mul_f32_e32 v237, v115, v237
	v_mul_f32_e32 v239, v109, v239
	v_cvt_pk_bf16_f32 v234, v234, v235
	v_cvt_pk_bf16_f32 v235, v236, v237
	v_cvt_pk_bf16_f32 v236, v238, v239
	v_add_f32_e32 v238, v144, v195
	v_max_f32_e32 v238, 0xc2200000, v238
	v_mul_f32_e32 v240, v110, v240
	v_mul_f32_e32 v238, 0xbfb8aa3b, v238
	s_mov_b32 s1, 0x20000
	v_mul_f32_e32 v241, v111, v241
	v_cvt_pk_bf16_f32 v237, v240, v241
	v_exp_f32_e32 v240, v238
	v_add_co_u32_e32 v238, vcc, s1, v0
	v_add_f32_e32 v241, v139, v2
	s_nop 0
	v_addc_co_u32_e32 v239, vcc, 0, v1, vcc
	global_store_dwordx4 v[238:239], v[234:237], off
	v_add_f32_e32 v238, v136, v191
	v_max_f32_e32 v238, 0xc2200000, v238
	v_add_f32_e32 v235, v145, v194
	v_add_f32_e32 v236, v146, v193
	v_max_f32_e32 v235, 0xc2200000, v235
	v_max_f32_e32 v236, 0xc2200000, v236
	v_add_f32_e32 v237, v147, v192
	v_add_f32_e32 v239, v137, v190
	v_mul_f32_e32 v235, 0xbfb8aa3b, v235
	v_mul_f32_e32 v236, 0xbfb8aa3b, v236
	v_max_f32_e32 v237, 0xc2200000, v237
	v_mul_f32_e32 v238, 0xbfb8aa3b, v238
	v_max_f32_e32 v239, 0xc2200000, v239
	v_add_f32_e32 v234, 1.0, v240
	v_exp_f32_e32 v235, v235
	v_exp_f32_e32 v236, v236
	v_mul_f32_e32 v237, 0xbfb8aa3b, v237
	v_exp_f32_e32 v238, v238
	v_mul_f32_e32 v239, 0xbfb8aa3b, v239
	v_add_f32_e32 v240, v138, v189
	v_exp_f32_e32 v237, v237
	v_exp_f32_e32 v239, v239
	v_max_f32_e32 v240, 0xc2200000, v240
	v_max_f32_e32 v241, 0xc2200000, v241
	v_mul_f32_e32 v240, 0xbfb8aa3b, v240
	v_mul_f32_e32 v241, 0xbfb8aa3b, v241
	v_exp_f32_e32 v240, v240
	v_exp_f32_e32 v241, v241
	v_add_f32_e32 v235, 1.0, v235
	v_add_f32_e32 v236, 1.0, v236
	v_add_f32_e32 v238, 1.0, v238
	v_rcp_f32_e32 v234, v234
	v_rcp_f32_e32 v235, v235
	v_rcp_f32_e32 v236, v236
	v_add_f32_e32 v237, 1.0, v237
	v_rcp_f32_e32 v238, v238
	v_add_f32_e32 v239, 1.0, v239
	v_rcp_f32_e32 v237, v237
	v_rcp_f32_e32 v239, v239
	v_add_f32_e32 v240, 1.0, v240
	v_add_f32_e32 v241, 1.0, v241
	v_rcp_f32_e32 v240, v240
	v_rcp_f32_e32 v241, v241
	v_mul_f32_e32 v234, v104, v234
	v_mul_f32_e32 v235, v105, v235
	v_mul_f32_e32 v236, v106, v236
	v_mul_f32_e32 v238, v100, v238
	v_mul_f32_e32 v237, v107, v237
	v_mul_f32_e32 v239, v101, v239
	v_cvt_pk_bf16_f32 v234, v234, v235
	v_cvt_pk_bf16_f32 v235, v236, v237
	v_cvt_pk_bf16_f32 v236, v238, v239
	v_add_co_u32_e32 v238, vcc, 0x30000, v0
	s_mov_b64 s[8:9], 0
	s_nop 0
	v_addc_co_u32_e32 v239, vcc, 0, v1, vcc
	v_mul_f32_e32 v240, v102, v240
	v_mul_f32_e32 v241, v103, v241
	v_cvt_pk_bf16_f32 v237, v240, v241
	global_store_dwordx4 v[238:239], v[234:237], off

; __device__ __forceinline__ float sigmoidf_(float x) { return __builtin_amdgcn_rcpf(1.0f + __expf(-x)); }
;   __device__ __forceinline__ void operator()(EPI_ARGS) const {
;     ...
;       for (int ai = 0; ai < 2; ++ai) {
;         unsigned loff = loff0;
;         asm volatile("" : "+v"(loff));
;         u32x4 zc[4], zn[4];
; #pragma unroll
;         for (int m = 0; m < 4; ++m) {
;           const unsigned o = loff + (unsigned)((ai * HALF + m * 16) * PLD + bj * HALF);
;           zc[m] = *(const u32x4*)(pc + o);
;           zn[m] = *(const u32x4*)(pn_ + o);
;         }
;         __builtin_amdgcn_sched_barrier(0);
;         if (br < 2) {
; #pragma unroll
;           for (int m = 0; m < 4; ++m) {
;             float xc[8], xn[8];
;             unpack8(zc[m], xc);
;             unpack8(zn[m], xn);
; #pragma unroll
;             for (int k = 0; k < 8; ++k) {
;               const float ec = __expf(-fmaxf(xc[k] + gc[k], -40.f)), en = __expf(-fmaxf(xn[k] + gn[k], -40.f));
;               const float f = (1.0f + en) * __builtin_amdgcn_rcpf(1.0f + ec);
;               acc[ai][bj][m][k >> 2][k & 3] *= f;
;             }
;           }
;         } else {
; #pragma unroll
;           for (int m = 0; m < 4; ++m) {
;             float xc[8], y[8];
;             unpack8(zc[m], xc);
; #pragma unroll
;             for (int k = 0; k < 8; ++k) y[k] = acc[ai][bj][m][k >> 2][k & 3] * sigmoidf_(fmaxf(xc[k] + gc[k], -40.f));
;             u32x4 o;
;             o.x = pack2(y[0], y[1]); o.y = pack2(y[2], y[3]); o.z = pack2(y[4], y[5]); o.w = pack2(y[6], y[7]);
;             *(u32x4*)(mrow + (size_t)(ai * HALF + m * 16) * DM + bj * HALF) = o;
;           }
.LBB0_548:
	v_mov_b32_e32 v189, v186
	s_nop 0
	v_add_u32_e32 v2, 0x8000, v189
	v_lshlrev_b64 v[148:149], 1, v[2:3]
	v_lshl_add_u64 v[150:151], s[2:3], 0, v[148:149]
	v_lshl_add_u64 v[148:149], s[4:5], 0, v[148:149]
	v_add_u32_e32 v2, 0x9000, v189
	global_load_dwordx4 v[190:193], v[150:151], off
	global_load_dwordx4 v[160:163], v[148:149], off
	v_lshlrev_b64 v[148:149], 1, v[2:3]
	v_lshl_add_u64 v[150:151], s[2:3], 0, v[148:149]
	v_lshl_add_u64 v[148:149], s[4:5], 0, v[148:149]
	v_add_u32_e32 v2, 0xa000, v189
	global_load_dwordx4 v[194:197], v[150:151], off
	global_load_dwordx4 v[156:159], v[148:149], off
	v_lshlrev_b64 v[148:149], 1, v[2:3]
	v_lshl_add_u64 v[150:151], s[2:3], 0, v[148:149]
	v_lshl_add_u64 v[148:149], s[4:5], 0, v[148:149]
	v_add_u32_e32 v2, 0xb000, v189
	global_load_dwordx4 v[234:237], v[150:151], off
	global_load_dwordx4 v[152:155], v[148:149], off
	v_lshlrev_b64 v[148:149], 1, v[2:3]
	v_lshl_add_u64 v[150:151], s[2:3], 0, v[148:149]
	v_lshl_add_u64 v[148:149], s[4:5], 0, v[148:149]
	global_load_dwordx4 v[238:241], v[150:151], off
	s_nop 0
	global_load_dwordx4 v[148:151], v[148:149], off
	s_waitcnt vmcnt(0) lgkmcnt(0)
	v_lshlrev_b32_e32 v2, 16, v190
	v_and_b32_e32 v189, 0xffff0000, v190
	v_lshlrev_b32_e32 v190, 16, v191
	v_and_b32_e32 v191, 0xffff0000, v191
	v_lshlrev_b32_e32 v212, 16, v192
	v_and_b32_e32 v192, 0xffff0000, v192
	v_lshlrev_b32_e32 v213, 16, v193
	v_and_b32_e32 v193, 0xffff0000, v193
	v_cndmask_b32_e64 v214, 0, 1, s[6:7]
	v_add_f32_e32 v2, v144, v2
	v_add_f32_e32 v189, v145, v189
	v_add_f32_e32 v190, v146, v190
	v_add_f32_e32 v191, v147, v191
	v_add_f32_e32 v212, v136, v212
	v_add_f32_e32 v192, v137, v192
	v_add_f32_e32 v213, v138, v213
	v_add_f32_e32 v193, v139, v193
	s_mov_b64 s[10:11], -1
	v_cmp_ne_u32_e64 s[8:9], 1, v214
	s_andn2_b64 vcc, exec, s[6:7]
	v_max_f32_e32 v233, 0xc2200000, v2
	v_max_f32_e32 v232, 0xc2200000, v189
	v_max_f32_e32 v231, 0xc2200000, v190
	v_max_f32_e32 v230, 0xc2200000, v191
	v_max_f32_e32 v229, 0xc2200000, v212
	v_max_f32_e32 v228, 0xc2200000, v192
	v_max_f32_e32 v227, 0xc2200000, v213
	v_max_f32_e32 v226, 0xc2200000, v193
	v_lshlrev_b32_e32 v225, 16, v194
	v_and_b32_e32 v224, 0xffff0000, v194
	v_lshlrev_b32_e32 v223, 16, v195
	v_and_b32_e32 v222, 0xffff0000, v195
	v_lshlrev_b32_e32 v221, 16, v196
	v_and_b32_e32 v220, 0xffff0000, v196
	v_lshlrev_b32_e32 v219, 16, v197
	v_and_b32_e32 v218, 0xffff0000, v197
	v_lshlrev_b32_e32 v217, 16, v234
	v_and_b32_e32 v216, 0xffff0000, v234
	v_lshlrev_b32_e32 v215, 16, v235
	v_and_b32_e32 v214, 0xffff0000, v235
	v_lshlrev_b32_e32 v213, 16, v236
	v_and_b32_e32 v212, 0xffff0000, v236
	v_lshlrev_b32_e32 v197, 16, v237
	v_and_b32_e32 v196, 0xffff0000, v237
	v_lshlrev_b32_e32 v195, 16, v238
	v_and_b32_e32 v194, 0xffff0000, v238
	v_lshlrev_b32_e32 v193, 16, v239
	v_and_b32_e32 v192, 0xffff0000, v239
	v_lshlrev_b32_e32 v191, 16, v240
	v_and_b32_e32 v190, 0xffff0000, v240
	v_lshlrev_b32_e32 v189, 16, v241
	v_and_b32_e32 v2, 0xffff0000, v241
	s_cbranch_vccnz .LBB0_550
	v_mul_f32_e32 v234, 0xbfb8aa3b, v233
	v_mul_f32_e32 v235, 0xbfb8aa3b, v232
	v_mul_f32_e32 v236, 0xbfb8aa3b, v231
	v_mul_f32_e32 v238, 0xbfb8aa3b, v229
	v_exp_f32_e32 v234, v234
	v_exp_f32_e32 v235, v235
	v_exp_f32_e32 v236, v236
	v_mul_f32_e32 v237, 0xbfb8aa3b, v230
	v_exp_f32_e32 v238, v238
	v_mul_f32_e32 v239, 0xbfb8aa3b, v228
	v_exp_f32_e32 v237, v237
	v_exp_f32_e32 v239, v239
	v_mul_f32_e32 v240, 0xbfb8aa3b, v227
	v_exp_f32_e32 v240, v240
	v_mul_f32_e32 v241, 0xbfb8aa3b, v226
	v_add_f32_e32 v234, 1.0, v234
	v_add_f32_e32 v235, 1.0, v235
	v_add_f32_e32 v236, 1.0, v236
	v_add_f32_e32 v238, 1.0, v238
	v_exp_f32_e32 v241, v241
	v_rcp_f32_e32 v234, v234
	v_rcp_f32_e32 v235, v235
	v_rcp_f32_e32 v236, v236
	v_add_f32_e32 v237, 1.0, v237
	v_rcp_f32_e32 v238, v238
	v_add_f32_e32 v239, 1.0, v239
	v_rcp_f32_e32 v237, v237
	v_rcp_f32_e32 v239, v239
	v_add_f32_e32 v240, 1.0, v240
	v_rcp_f32_e32 v240, v240
	v_add_f32_e32 v241, 1.0, v241
	v_mul_f32_e32 v234, v64, v234
	v_mul_f32_e32 v235, v65, v235
	v_mul_f32_e32 v236, v66, v236
	v_rcp_f32_e32 v241, v241
	v_mul_f32_e32 v238, v60, v238
	v_mul_f32_e32 v237, v67, v237
	v_mul_f32_e32 v239, v61, v239
	v_cvt_pk_bf16_f32 v234, v234, v235
	v_cvt_pk_bf16_f32 v235, v236, v237
	v_cvt_pk_bf16_f32 v236, v238, v239
	v_add_f32_e32 v238, v144, v225
	v_max_f32_e32 v238, 0xc2200000, v238
	v_mul_f32_e32 v240, v62, v240
	v_mul_f32_e32 v238, 0xbfb8aa3b, v238
	s_mov_b32 s1, 0x80000
	v_mul_f32_e32 v241, v63, v241
	v_cvt_pk_bf16_f32 v237, v240, v241
	v_exp_f32_e32 v240, v238
	v_add_co_u32_e32 v238, vcc, s1, v0
	v_add_f32_e32 v241, v139, v218
	s_nop 0
	v_addc_co_u32_e32 v239, vcc, 0, v1, vcc
	global_store_dwordx4 v[238:239], v[234:237], off
	v_add_f32_e32 v238, v136, v221
	v_max_f32_e32 v238, 0xc2200000, v238
	v_add_f32_e32 v235, v145, v224
	v_add_f32_e32 v236, v146, v223
	v_max_f32_e32 v235, 0xc2200000, v235
	v_max_f32_e32 v236, 0xc2200000, v236
	v_add_f32_e32 v237, v147, v222
	v_add_f32_e32 v239, v137, v220
	v_mul_f32_e32 v235, 0xbfb8aa3b, v235
	v_mul_f32_e32 v236, 0xbfb8aa3b, v236
	v_max_f32_e32 v237, 0xc2200000, v237
	v_mul_f32_e32 v238, 0xbfb8aa3b, v238
	v_max_f32_e32 v239, 0xc2200000, v239
	v_add_f32_e32 v234, 1.0, v240
	v_exp_f32_e32 v235, v235
	v_exp_f32_e32 v236, v236
	v_mul_f32_e32 v237, 0xbfb8aa3b, v237
	v_exp_f32_e32 v238, v238
	v_mul_f32_e32 v239, 0xbfb8aa3b, v239
	v_add_f32_e32 v240, v138, v219
; __device__ __forceinline__ float sigmoidf_(float x) { return __builtin_amdgcn_rcpf(1.0f + __expf(-x)); }
;   __device__ __forceinline__ void operator()(EPI_ARGS) const {
;     ...
;           for (int m = 0; m < 4; ++m) {
;             float xc[8], y[8];
;             unpack8(zc[m], xc);
; #pragma unroll
;             for (int k = 0; k < 8; ++k) y[k] = acc[ai][bj][m][k >> 2][k & 3] * sigmoidf_(fmaxf(xc[k] + gc[k], -40.f));
;             u32x4 o;
;             o.x = pack2(y[0], y[1]); o.y = pack2(y[2], y[3]); o.z = pack2(y[4], y[5]); o.w = pack2(y[6], y[7]);
;             *(u32x4*)(mrow + (size_t)(ai * HALF + m * 16) * DM + bj * HALF) = o;
;           }
	v_exp_f32_e32 v237, v237
	v_exp_f32_e32 v239, v239
	v_max_f32_e32 v240, 0xc2200000, v240
	v_mul_f32_e32 v240, 0xbfb8aa3b, v240
	v_max_f32_e32 v241, 0xc2200000, v241
	v_exp_f32_e32 v240, v240
	v_mul_f32_e32 v241, 0xbfb8aa3b, v241
	v_add_f32_e32 v235, 1.0, v235
	v_add_f32_e32 v236, 1.0, v236
	v_add_f32_e32 v238, 1.0, v238
	v_exp_f32_e32 v241, v241
	v_rcp_f32_e32 v234, v234
	v_rcp_f32_e32 v235, v235
	v_rcp_f32_e32 v236, v236
	v_add_f32_e32 v237, 1.0, v237
	v_rcp_f32_e32 v238, v238
	v_add_f32_e32 v239, 1.0, v239
	v_rcp_f32_e32 v237, v237
	v_rcp_f32_e32 v239, v239
	v_add_f32_e32 v240, 1.0, v240
	v_rcp_f32_e32 v240, v240
	v_add_f32_e32 v241, 1.0, v241
	v_mul_f32_e32 v234, v56, v234
	v_mul_f32_e32 v235, v57, v235
	v_mul_f32_e32 v236, v58, v236
	v_rcp_f32_e32 v241, v241
	v_mul_f32_e32 v238, v52, v238
	v_mul_f32_e32 v237, v59, v237
	v_mul_f32_e32 v239, v53, v239
	v_cvt_pk_bf16_f32 v234, v234, v235
	v_cvt_pk_bf16_f32 v235, v236, v237
	v_cvt_pk_bf16_f32 v236, v238, v239
	v_add_f32_e32 v238, v144, v217
	v_max_f32_e32 v238, 0xc2200000, v238
	v_mul_f32_e32 v240, v54, v240
	v_mul_f32_e32 v238, 0xbfb8aa3b, v238
	s_mov_b32 s1, 0x90000
	v_mul_f32_e32 v241, v55, v241
	v_cvt_pk_bf16_f32 v237, v240, v241
	v_exp_f32_e32 v240, v238
	v_add_co_u32_e32 v238, vcc, s1, v0
	v_add_f32_e32 v241, v139, v196
	s_nop 0
	v_addc_co_u32_e32 v239, vcc, 0, v1, vcc
	global_store_dwordx4 v[238:239], v[234:237], off
	v_add_f32_e32 v238, v136, v213
	v_max_f32_e32 v238, 0xc2200000, v238
	v_add_f32_e32 v235, v145, v216
	v_add_f32_e32 v236, v146, v215
	v_max_f32_e32 v235, 0xc2200000, v235
	v_max_f32_e32 v236, 0xc2200000, v236
	v_add_f32_e32 v237, v147, v214
	v_add_f32_e32 v239, v137, v212
	v_mul_f32_e32 v235, 0xbfb8aa3b, v235
	v_mul_f32_e32 v236, 0xbfb8aa3b, v236
	v_max_f32_e32 v237, 0xc2200000, v237
	v_mul_f32_e32 v238, 0xbfb8aa3b, v238
	v_max_f32_e32 v239, 0xc2200000, v239
	v_add_f32_e32 v234, 1.0, v240
	v_exp_f32_e32 v235, v235
	v_exp_f32_e32 v236, v236
	v_mul_f32_e32 v237, 0xbfb8aa3b, v237
	v_exp_f32_e32 v238, v238
	v_mul_f32_e32 v239, 0xbfb8aa3b, v239
	v_add_f32_e32 v240, v138, v197
	v_exp_f32_e32 v237, v237
	v_exp_f32_e32 v239, v239
	v_max_f32_e32 v240, 0xc2200000, v240
	v_mul_f32_e32 v240, 0xbfb8aa3b, v240
	v_max_f32_e32 v241, 0xc2200000, v241
	v_exp_f32_e32 v240, v240
	v_mul_f32_e32 v241, 0xbfb8aa3b, v241
	v_add_f32_e32 v235, 1.0, v235
	v_add_f32_e32 v236, 1.0, v236
	v_add_f32_e32 v238, 1.0, v238
	v_exp_f32_e32 v241, v241
	v_rcp_f32_e32 v234, v234
	v_rcp_f32_e32 v235, v235
	v_rcp_f32_e32 v236, v236
	v_add_f32_e32 v237, 1.0, v237
	v_rcp_f32_e32 v238, v238
	v_add_f32_e32 v239, 1.0, v239
	v_rcp_f32_e32 v237, v237
	v_rcp_f32_e32 v239, v239
	v_add_f32_e32 v240, 1.0, v240
	v_rcp_f32_e32 v240, v240
	v_add_f32_e32 v241, 1.0, v241
	v_mul_f32_e32 v234, v48, v234
	v_mul_f32_e32 v235, v49, v235
	v_mul_f32_e32 v236, v50, v236
	v_rcp_f32_e32 v241, v241
	v_mul_f32_e32 v238, v44, v238
	v_mul_f32_e32 v237, v51, v237
	v_mul_f32_e32 v239, v45, v239
	v_cvt_pk_bf16_f32 v234, v234, v235
	v_cvt_pk_bf16_f32 v235, v236, v237
	v_cvt_pk_bf16_f32 v236, v238, v239
	v_add_f32_e32 v238, v144, v195
	v_max_f32_e32 v238, 0xc2200000, v238
	v_mul_f32_e32 v240, v46, v240
	v_mul_f32_e32 v238, 0xbfb8aa3b, v238
	s_mov_b32 s1, 0xa0000
	v_mul_f32_e32 v241, v47, v241
	v_cvt_pk_bf16_f32 v237, v240, v241
	v_exp_f32_e32 v240, v238
	v_add_co_u32_e32 v238, vcc, s1, v0
	v_add_f32_e32 v241, v139, v2
	s_nop 0
	v_addc_co_u32_e32 v239, vcc, 0, v1, vcc
	global_store_dwordx4 v[238:239], v[234:237], off
	v_add_f32_e32 v238, v136, v191
	v_max_f32_e32 v238, 0xc2200000, v238
	v_add_f32_e32 v235, v145, v194
	v_add_f32_e32 v236, v146, v193
	v_max_f32_e32 v235, 0xc2200000, v235
	v_max_f32_e32 v236, 0xc2200000, v236
	v_add_f32_e32 v237, v147, v192
	v_add_f32_e32 v239, v137, v190
	v_mul_f32_e32 v235, 0xbfb8aa3b, v235
	v_mul_f32_e32 v236, 0xbfb8aa3b, v236
	v_max_f32_e32 v237, 0xc2200000, v237
	v_mul_f32_e32 v238, 0xbfb8aa3b, v238
	v_max_f32_e32 v239, 0xc2200000, v239
	v_add_f32_e32 v234, 1.0, v240
	v_exp_f32_e32 v235, v235
	v_exp_f32_e32 v236, v236
	v_mul_f32_e32 v237, 0xbfb8aa3b, v237
	v_exp_f32_e32 v238, v238
	v_mul_f32_e32 v239, 0xbfb8aa3b, v239
	v_add_f32_e32 v240, v138, v189
	v_exp_f32_e32 v237, v237
	v_exp_f32_e32 v239, v239
	v_max_f32_e32 v240, 0xc2200000, v240
	v_max_f32_e32 v241, 0xc2200000, v241
	v_mul_f32_e32 v240, 0xbfb8aa3b, v240
	v_mul_f32_e32 v241, 0xbfb8aa3b, v241
	v_exp_f32_e32 v240, v240
	v_exp_f32_e32 v241, v241
	v_add_f32_e32 v235, 1.0, v235
	v_add_f32_e32 v236, 1.0, v236
	v_add_f32_e32 v238, 1.0, v238
	v_rcp_f32_e32 v234, v234
	v_rcp_f32_e32 v235, v235
	v_rcp_f32_e32 v236, v236
	v_add_f32_e32 v237, 1.0, v237
	v_rcp_f32_e32 v238, v238
	v_add_f32_e32 v239, 1.0, v239
	v_rcp_f32_e32 v237, v237
	v_rcp_f32_e32 v239, v239
	v_add_f32_e32 v240, 1.0, v240
	v_add_f32_e32 v241, 1.0, v241
	v_rcp_f32_e32 v240, v240
	v_rcp_f32_e32 v241, v241
	v_mul_f32_e32 v234, v40, v234
	v_mul_f32_e32 v235, v41, v235
	v_mul_f32_e32 v236, v42, v236
	v_mul_f32_e32 v238, v36, v238
	v_mul_f32_e32 v237, v43, v237
	v_mul_f32_e32 v239, v37, v239
	v_cvt_pk_bf16_f32 v234, v234, v235
	v_cvt_pk_bf16_f32 v235, v236, v237
	v_cvt_pk_bf16_f32 v236, v238, v239
	v_add_co_u32_e32 v238, vcc, 0xb0000, v0
	s_mov_b64 s[10:11], 0
	s_nop 0
	v_addc_co_u32_e32 v239, vcc, 0, v1, vcc
	v_mul_f32_e32 v240, v38, v240
	v_mul_f32_e32 v241, v39, v241
	v_cvt_pk_bf16_f32 v237, v240, v241
	global_store_dwordx4 v[238:239], v[234:237], off

; __device__ __forceinline__ float sigmoidf_(float x) { return __builtin_amdgcn_rcpf(1.0f + __expf(-x)); }
;   __device__ __forceinline__ void operator()(EPI_ARGS) const {
;     ...
;     for (int bj = 0; bj < 2; ++bj) {
;       const int c = col0 + bj * HALF;
;       float gc[8], gn[8];
;       {
;         const f32x4 a0 = *(const f32x4*)(bg + br * DM + c), a1 = *(const f32x4*)(bg + br * DM + c + 4);
;         const f32x4 b0 = *(const f32x4*)(bg + brn * DM + c), b1 = *(const f32x4*)(bg + brn * DM + c + 4);
; #pragma unroll
;         for (int k = 0; k < 4; ++k) { gc[k] = a0[k]; gc[4 + k] = a1[k]; gn[k] = b0[k]; gn[4 + k] = b1[k]; }
;       }
; #pragma unroll
;       for (int ai = 0; ai < 2; ++ai) {
;         unsigned loff = loff0;
;         asm volatile("" : "+v"(loff));
;         u32x4 zc[4], zn[4];
; #pragma unroll
;         for (int m = 0; m < 4; ++m) {
;           const unsigned o = loff + (unsigned)((ai * HALF + m * 16) * PLD + bj * HALF);
;           zc[m] = *(const u32x4*)(pc + o);
;           zn[m] = *(const u32x4*)(pn_ + o);
;         }
;         __builtin_amdgcn_sched_barrier(0);
;         if (br < 2) {
; #pragma unroll
;           for (int m = 0; m < 4; ++m) {
;             float xc[8], xn[8];
;             unpack8(zc[m], xc);
;             unpack8(zn[m], xn);
; #pragma unroll
;             for (int k = 0; k < 8; ++k) {
;               const float ec = __expf(-fmaxf(xc[k] + gc[k], -40.f)), en = __expf(-fmaxf(xn[k] + gn[k], -40.f));
;               const float f = (1.0f + en) * __builtin_amdgcn_rcpf(1.0f + ec);
;               acc[ai][bj][m][k >> 2][k & 3] *= f;
;             }
;           }
;         } else {
; #pragma unroll
;           for (int m = 0; m < 4; ++m) {
;             float xc[8], y[8];
;             unpack8(zc[m], xc);
; #pragma unroll
;             for (int k = 0; k < 8; ++k) y[k] = acc[ai][bj][m][k >> 2][k & 3] * sigmoidf_(fmaxf(xc[k] + gc[k], -40.f));
;             u32x4 o;
;             o.x = pack2(y[0], y[1]); o.y = pack2(y[2], y[3]); o.z = pack2(y[4], y[5]); o.w = pack2(y[6], y[7]);
;             *(u32x4*)(mrow + (size_t)(ai * HALF + m * 16) * DM + bj * HALF) = o;
;           }
.LBB0_552:
	v_mov_b32_e32 v189, v186
	global_load_dwordx4 v[144:147], v[182:183], off offset:512
	global_load_dwordx4 v[136:139], v[182:183], off offset:528
	global_load_dwordx4 v[140:143], v[184:185], off offset:512
	global_load_dwordx4 v[132:135], v[184:185], off offset:528
	s_nop 0
	v_add_u32_e32 v2, 0x80, v189
	v_lshlrev_b64 v[148:149], 1, v[2:3]
	v_lshl_add_u64 v[150:151], s[2:3], 0, v[148:149]
	v_lshl_add_u64 v[148:149], s[4:5], 0, v[148:149]
	v_add_u32_e32 v2, 0x1080, v189
	global_load_dwordx4 v[182:185], v[150:151], off
	global_load_dwordx4 v[160:163], v[148:149], off
	v_lshlrev_b64 v[148:149], 1, v[2:3]
	v_lshl_add_u64 v[150:151], s[2:3], 0, v[148:149]
	v_lshl_add_u64 v[148:149], s[4:5], 0, v[148:149]
	v_add_u32_e32 v2, 0x2080, v189
	global_load_dwordx4 v[190:193], v[150:151], off
	global_load_dwordx4 v[156:159], v[148:149], off
	v_lshlrev_b64 v[148:149], 1, v[2:3]
	v_lshl_add_u64 v[150:151], s[2:3], 0, v[148:149]
	v_lshl_add_u64 v[148:149], s[4:5], 0, v[148:149]
	v_add_u32_e32 v2, 0x3080, v189
	global_load_dwordx4 v[230:233], v[150:151], off
	global_load_dwordx4 v[152:155], v[148:149], off
	v_lshlrev_b64 v[148:149], 1, v[2:3]
	v_lshl_add_u64 v[150:151], s[2:3], 0, v[148:149]
	v_lshl_add_u64 v[148:149], s[4:5], 0, v[148:149]
	global_load_dwordx4 v[234:237], v[150:151], off
	s_nop 0
	global_load_dwordx4 v[148:151], v[148:149], off
	s_mov_b64 s[6:7], -1
	s_and_b64 vcc, exec, s[8:9]
	s_waitcnt vmcnt(0) lgkmcnt(0)
	v_lshlrev_b32_e32 v229, 16, v182
	v_and_b32_e32 v228, 0xffff0000, v182
	v_lshlrev_b32_e32 v227, 16, v183
	v_and_b32_e32 v226, 0xffff0000, v183
	v_lshlrev_b32_e32 v225, 16, v184
	v_and_b32_e32 v224, 0xffff0000, v184
	v_lshlrev_b32_e32 v223, 16, v185
	v_and_b32_e32 v222, 0xffff0000, v185
	v_lshlrev_b32_e32 v221, 16, v190
	v_and_b32_e32 v220, 0xffff0000, v190
	v_lshlrev_b32_e32 v219, 16, v191
	v_and_b32_e32 v218, 0xffff0000, v191
	v_lshlrev_b32_e32 v217, 16, v192
	v_and_b32_e32 v216, 0xffff0000, v192
	v_lshlrev_b32_e32 v215, 16, v193
	v_and_b32_e32 v214, 0xffff0000, v193
	v_lshlrev_b32_e32 v213, 16, v230
	v_and_b32_e32 v212, 0xffff0000, v230
	v_lshlrev_b32_e32 v197, 16, v231
	v_and_b32_e32 v196, 0xffff0000, v231
	v_lshlrev_b32_e32 v195, 16, v232
	v_and_b32_e32 v194, 0xffff0000, v232
	v_lshlrev_b32_e32 v193, 16, v233
	v_and_b32_e32 v192, 0xffff0000, v233
	v_lshlrev_b32_e32 v191, 16, v234
	v_and_b32_e32 v190, 0xffff0000, v234
	v_lshlrev_b32_e32 v189, 16, v235
	v_and_b32_e32 v185, 0xffff0000, v235
	v_lshlrev_b32_e32 v184, 16, v236
	v_and_b32_e32 v183, 0xffff0000, v236
	v_lshlrev_b32_e32 v182, 16, v237
	v_and_b32_e32 v2, 0xffff0000, v237
	s_cbranch_vccnz .LBB0_554
	v_add_f32_e32 v230, v144, v229
	v_add_f32_e32 v231, v145, v228
	v_add_f32_e32 v232, v146, v227
	v_max_f32_e32 v230, 0xc2200000, v230
	v_max_f32_e32 v231, 0xc2200000, v231
	v_max_f32_e32 v232, 0xc2200000, v232
	v_add_f32_e32 v233, v147, v226
	v_mul_f32_e32 v230, 0xbfb8aa3b, v230
	v_mul_f32_e32 v231, 0xbfb8aa3b, v231
	v_mul_f32_e32 v232, 0xbfb8aa3b, v232
	v_max_f32_e32 v233, 0xc2200000, v233
	v_exp_f32_e32 v230, v230
	v_exp_f32_e32 v231, v231
	v_exp_f32_e32 v232, v232
	v_mul_f32_e32 v233, 0xbfb8aa3b, v233
	v_exp_f32_e32 v233, v233
	v_add_f32_e32 v234, v136, v225
	v_add_f32_e32 v235, v137, v224
	v_max_f32_e32 v234, 0xc2200000, v234
	v_max_f32_e32 v235, 0xc2200000, v235
	v_add_f32_e32 v236, v138, v223
	v_add_f32_e32 v237, v139, v222
	v_mul_f32_e32 v234, 0xbfb8aa3b, v234
	v_mul_f32_e32 v235, 0xbfb8aa3b, v235
	v_max_f32_e32 v236, 0xc2200000, v236
	v_max_f32_e32 v237, 0xc2200000, v237
	v_add_f32_e32 v230, 1.0, v230
	v_add_f32_e32 v231, 1.0, v231
	v_add_f32_e32 v232, 1.0, v232
	v_exp_f32_e32 v234, v234
	v_exp_f32_e32 v235, v235
	v_mul_f32_e32 v236, 0xbfb8aa3b, v236
	v_mul_f32_e32 v237, 0xbfb8aa3b, v237
	v_rcp_f32_e32 v230, v230
	v_rcp_f32_e32 v231, v231
	v_rcp_f32_e32 v232, v232
	v_add_f32_e32 v233, 1.0, v233
	v_exp_f32_e32 v236, v236
	v_exp_f32_e32 v237, v237
	v_rcp_f32_e32 v233, v233
	v_add_f32_e32 v234, 1.0, v234
	v_add_f32_e32 v235, 1.0, v235
	v_mul_f32_e32 v230, v96, v230
	v_mul_f32_e32 v231, v97, v231
	v_mul_f32_e32 v232, v98, v232
	v_rcp_f32_e32 v234, v234
	v_rcp_f32_e32 v235, v235
	v_add_f32_e32 v236, 1.0, v236
	v_add_f32_e32 v237, 1.0, v237
	v_mul_f32_e32 v233, v99, v233
	v_rcp_f32_e32 v236, v236
	v_rcp_f32_e32 v237, v237
	v_cvt_pk_bf16_f32 v230, v230, v231
	v_cvt_pk_bf16_f32 v231, v232, v233
	v_add_f32_e32 v232, v144, v221
	v_max_f32_e32 v232, 0xc2200000, v232
	v_mul_f32_e32 v232, 0xbfb8aa3b, v232
	v_mul_f32_e32 v234, v92, v234
	v_mul_f32_e32 v235, v93, v235
	v_exp_f32_e32 v238, v232
	v_cvt_pk_bf16_f32 v232, v234, v235
	v_mul_f32_e32 v236, v94, v236
	v_mul_f32_e32 v237, v95, v237
	v_cvt_pk_bf16_f32 v233, v236, v237
	global_store_dwordx4 v[0:1], v[230:233], off offset:256
	v_add_f32_e32 v234, v136, v217
	v_max_f32_e32 v234, 0xc2200000, v234
	v_add_f32_e32 v231, v145, v220
	v_add_f32_e32 v232, v146, v219
	v_max_f32_e32 v231, 0xc2200000, v231
	v_max_f32_e32 v232, 0xc2200000, v232
	v_add_f32_e32 v233, v147, v218
	v_add_f32_e32 v235, v137, v216
	v_mul_f32_e32 v231, 0xbfb8aa3b, v231
	v_mul_f32_e32 v232, 0xbfb8aa3b, v232
	v_max_f32_e32 v233, 0xc2200000, v233
	v_mul_f32_e32 v234, 0xbfb8aa3b, v234
	v_max_f32_e32 v235, 0xc2200000, v235
	v_exp_f32_e32 v231, v231
	v_exp_f32_e32 v232, v232
	v_mul_f32_e32 v233, 0xbfb8aa3b, v233
	v_exp_f32_e32 v234, v234
	v_mul_f32_e32 v235, 0xbfb8aa3b, v235
	v_add_f32_e32 v236, v138, v215
	v_exp_f32_e32 v233, v233
	v_exp_f32_e32 v235, v235
; __device__ __forceinline__ float sigmoidf_(float x) { return __builtin_amdgcn_rcpf(1.0f + __expf(-x)); }
;   __device__ __forceinline__ void operator()(EPI_ARGS) const {
;     ...
;           for (int m = 0; m < 4; ++m) {
;             float xc[8], y[8];
;             unpack8(zc[m], xc);
; #pragma unroll
;             for (int k = 0; k < 8; ++k) y[k] = acc[ai][bj][m][k >> 2][k & 3] * sigmoidf_(fmaxf(xc[k] + gc[k], -40.f));
;             u32x4 o;
;             o.x = pack2(y[0], y[1]); o.y = pack2(y[2], y[3]); o.z = pack2(y[4], y[5]); o.w = pack2(y[6], y[7]);
;             *(u32x4*)(mrow + (size_t)(ai * HALF + m * 16) * DM + bj * HALF) = o;
;           }
	v_max_f32_e32 v236, 0xc2200000, v236
	v_add_f32_e32 v237, v139, v214
	v_mul_f32_e32 v236, 0xbfb8aa3b, v236
	v_max_f32_e32 v237, 0xc2200000, v237
	v_exp_f32_e32 v236, v236
	v_mul_f32_e32 v237, 0xbfb8aa3b, v237
	v_add_f32_e32 v230, 1.0, v238
	v_add_f32_e32 v231, 1.0, v231
	v_add_f32_e32 v232, 1.0, v232
	v_add_f32_e32 v234, 1.0, v234
	v_exp_f32_e32 v237, v237
	v_rcp_f32_e32 v230, v230
	v_rcp_f32_e32 v231, v231
	v_rcp_f32_e32 v232, v232
	v_add_f32_e32 v233, 1.0, v233
	v_rcp_f32_e32 v234, v234
	v_add_f32_e32 v235, 1.0, v235
	v_rcp_f32_e32 v233, v233
	v_rcp_f32_e32 v235, v235
	v_add_f32_e32 v236, 1.0, v236
	v_rcp_f32_e32 v236, v236
	v_add_f32_e32 v237, 1.0, v237
	v_mul_f32_e32 v230, v88, v230
	v_mul_f32_e32 v231, v89, v231
	v_mul_f32_e32 v232, v90, v232
	v_rcp_f32_e32 v237, v237
	v_mul_f32_e32 v234, v84, v234
	v_mul_f32_e32 v233, v91, v233
	v_mul_f32_e32 v235, v85, v235
	v_cvt_pk_bf16_f32 v230, v230, v231
	v_cvt_pk_bf16_f32 v231, v232, v233
	v_cvt_pk_bf16_f32 v232, v234, v235
	v_add_f32_e32 v234, v144, v213
	v_max_f32_e32 v234, 0xc2200000, v234
	v_mul_f32_e32 v236, v86, v236
	v_mul_f32_e32 v234, 0xbfb8aa3b, v234
	v_mul_f32_e32 v237, v87, v237
	v_cvt_pk_bf16_f32 v233, v236, v237
	v_exp_f32_e32 v236, v234
	v_add_co_u32_e32 v234, vcc, s67, v0
	v_add_f32_e32 v237, v139, v192
	s_nop 0
	v_addc_co_u32_e32 v235, vcc, 0, v1, vcc
	global_store_dwordx4 v[234:235], v[230:233], off offset:256
	v_add_f32_e32 v234, v136, v195
	v_max_f32_e32 v234, 0xc2200000, v234
	v_add_f32_e32 v231, v145, v212
	v_add_f32_e32 v232, v146, v197
	v_max_f32_e32 v231, 0xc2200000, v231
	v_max_f32_e32 v232, 0xc2200000, v232
	v_add_f32_e32 v233, v147, v196
	v_add_f32_e32 v235, v137, v194
	v_mul_f32_e32 v231, 0xbfb8aa3b, v231
	v_mul_f32_e32 v232, 0xbfb8aa3b, v232
	v_max_f32_e32 v233, 0xc2200000, v233
	v_mul_f32_e32 v234, 0xbfb8aa3b, v234
	v_max_f32_e32 v235, 0xc2200000, v235
	v_add_f32_e32 v230, 1.0, v236
	v_exp_f32_e32 v231, v231
	v_exp_f32_e32 v232, v232
	v_mul_f32_e32 v233, 0xbfb8aa3b, v233
	v_exp_f32_e32 v234, v234
	v_mul_f32_e32 v235, 0xbfb8aa3b, v235
	v_add_f32_e32 v236, v138, v193
	v_exp_f32_e32 v233, v233
	v_exp_f32_e32 v235, v235
	v_max_f32_e32 v236, 0xc2200000, v236
	v_mul_f32_e32 v236, 0xbfb8aa3b, v236
	v_max_f32_e32 v237, 0xc2200000, v237
	v_exp_f32_e32 v236, v236
	v_mul_f32_e32 v237, 0xbfb8aa3b, v237
	v_add_f32_e32 v231, 1.0, v231
	v_add_f32_e32 v232, 1.0, v232
	v_add_f32_e32 v234, 1.0, v234
	v_exp_f32_e32 v237, v237
	v_rcp_f32_e32 v230, v230
	v_rcp_f32_e32 v231, v231
	v_rcp_f32_e32 v232, v232
	v_add_f32_e32 v233, 1.0, v233
	v_rcp_f32_e32 v234, v234
	v_add_f32_e32 v235, 1.0, v235
	v_rcp_f32_e32 v233, v233
	v_rcp_f32_e32 v235, v235
	v_add_f32_e32 v236, 1.0, v236
	v_rcp_f32_e32 v236, v236
	v_add_f32_e32 v237, 1.0, v237
	v_mul_f32_e32 v230, v80, v230
	v_mul_f32_e32 v231, v81, v231
	v_mul_f32_e32 v232, v82, v232
	v_rcp_f32_e32 v237, v237
	v_mul_f32_e32 v234, v76, v234
	v_mul_f32_e32 v233, v83, v233
	v_mul_f32_e32 v235, v77, v235
	v_cvt_pk_bf16_f32 v230, v230, v231
	v_cvt_pk_bf16_f32 v231, v232, v233
	v_cvt_pk_bf16_f32 v232, v234, v235
	v_add_f32_e32 v234, v144, v191
	v_max_f32_e32 v234, 0xc2200000, v234
	v_mul_f32_e32 v236, v78, v236
	v_mul_f32_e32 v234, 0xbfb8aa3b, v234
	s_mov_b32 s1, 0x20000
	v_mul_f32_e32 v237, v79, v237
	v_cvt_pk_bf16_f32 v233, v236, v237
	v_exp_f32_e32 v236, v234
	v_add_co_u32_e32 v234, vcc, s1, v0
	v_add_f32_e32 v237, v139, v2
	s_nop 0
	v_addc_co_u32_e32 v235, vcc, 0, v1, vcc
	global_store_dwordx4 v[234:235], v[230:233], off offset:256
	v_add_f32_e32 v234, v136, v184
	v_max_f32_e32 v234, 0xc2200000, v234
	v_add_f32_e32 v231, v145, v190
	v_add_f32_e32 v232, v146, v189
	v_max_f32_e32 v231, 0xc2200000, v231
	v_max_f32_e32 v232, 0xc2200000, v232
	v_add_f32_e32 v233, v147, v185
	v_add_f32_e32 v235, v137, v183
	v_mul_f32_e32 v231, 0xbfb8aa3b, v231
	v_mul_f32_e32 v232, 0xbfb8aa3b, v232
	v_max_f32_e32 v233, 0xc2200000, v233
	v_mul_f32_e32 v234, 0xbfb8aa3b, v234
	v_max_f32_e32 v235, 0xc2200000, v235
	v_add_f32_e32 v230, 1.0, v236
	v_exp_f32_e32 v231, v231
	v_exp_f32_e32 v232, v232
	v_mul_f32_e32 v233, 0xbfb8aa3b, v233
	v_exp_f32_e32 v234, v234
	v_mul_f32_e32 v235, 0xbfb8aa3b, v235
	v_add_f32_e32 v236, v138, v182
	v_exp_f32_e32 v233, v233
	v_exp_f32_e32 v235, v235
	v_max_f32_e32 v236, 0xc2200000, v236
	v_max_f32_e32 v237, 0xc2200000, v237
	v_mul_f32_e32 v236, 0xbfb8aa3b, v236
	v_mul_f32_e32 v237, 0xbfb8aa3b, v237
	v_exp_f32_e32 v236, v236
	v_exp_f32_e32 v237, v237
	v_add_f32_e32 v231, 1.0, v231
	v_add_f32_e32 v232, 1.0, v232
	v_add_f32_e32 v234, 1.0, v234
	v_rcp_f32_e32 v230, v230
	v_rcp_f32_e32 v231, v231
	v_rcp_f32_e32 v232, v232
	v_add_f32_e32 v233, 1.0, v233
	v_rcp_f32_e32 v234, v234
	v_add_f32_e32 v235, 1.0, v235
	v_rcp_f32_e32 v233, v233
	v_rcp_f32_e32 v235, v235
	v_add_f32_e32 v236, 1.0, v236
	v_add_f32_e32 v237, 1.0, v237
	v_rcp_f32_e32 v236, v236
	v_rcp_f32_e32 v237, v237
	v_mul_f32_e32 v230, v72, v230
	v_mul_f32_e32 v231, v73, v231
	v_mul_f32_e32 v232, v74, v232
	v_mul_f32_e32 v234, v68, v234
	v_mul_f32_e32 v233, v75, v233
	v_mul_f32_e32 v235, v69, v235
	v_cvt_pk_bf16_f32 v230, v230, v231
	v_cvt_pk_bf16_f32 v231, v232, v233
	v_cvt_pk_bf16_f32 v232, v234, v235
	v_add_co_u32_e32 v234, vcc, 0x30000, v0
	s_mov_b64 s[6:7], 0
	s_nop 0
	v_addc_co_u32_e32 v235, vcc, 0, v1, vcc
	v_mul_f32_e32 v236, v70, v236
	v_mul_f32_e32 v237, v71, v237
	v_cvt_pk_bf16_f32 v233, v236, v237
	global_store_dwordx4 v[234:235], v[230:233], off offset:256

;   __device__ __forceinline__ void operator()(EPI_ARGS) const {
;     ...
;       for (int ai = 0; ai < 2; ++ai) {
;         unsigned loff = loff0;
;         asm volatile("" : "+v"(loff));
;         u32x4 zc[4], zn[4];
; #pragma unroll
;         for (int m = 0; m < 4; ++m) {
;           const unsigned o = loff + (unsigned)((ai * HALF + m * 16) * PLD + bj * HALF);
;           zc[m] = *(const u32x4*)(pc + o);
;           zn[m] = *(const u32x4*)(pn_ + o);
;         }
;         __builtin_amdgcn_sched_barrier(0);
;         if (br < 2) {
.LBB0_556:
	v_mov_b32_e32 v189, v186
	s_nop 0
	v_add_u32_e32 v2, 0x8080, v189
	v_lshlrev_b64 v[148:149], 1, v[2:3]
	v_lshl_add_u64 v[150:151], s[2:3], 0, v[148:149]
	v_lshl_add_u64 v[148:149], s[4:5], 0, v[148:149]
	v_add_u32_e32 v2, 0x9080, v189
	global_load_dwordx4 v[182:185], v[150:151], off
	global_load_dwordx4 v[160:163], v[148:149], off
	v_lshlrev_b64 v[148:149], 1, v[2:3]
	v_lshl_add_u64 v[150:151], s[2:3], 0, v[148:149]
	v_lshl_add_u64 v[148:149], s[4:5], 0, v[148:149]
	v_add_u32_e32 v2, 0xa080, v189
	global_load_dwordx4 v[190:193], v[150:151], off
	global_load_dwordx4 v[156:159], v[148:149], off
	v_lshlrev_b64 v[148:149], 1, v[2:3]
	v_lshl_add_u64 v[150:151], s[2:3], 0, v[148:149]
	v_lshl_add_u64 v[148:149], s[4:5], 0, v[148:149]
	v_add_u32_e32 v2, 0xb080, v189
	global_load_dwordx4 v[230:233], v[150:151], off
	global_load_dwordx4 v[152:155], v[148:149], off
	v_lshlrev_b64 v[148:149], 1, v[2:3]
	v_lshl_add_u64 v[150:151], s[2:3], 0, v[148:149]
	v_lshl_add_u64 v[148:149], s[4:5], 0, v[148:149]
	global_load_dwordx4 v[234:237], v[150:151], off
	s_nop 0
	global_load_dwordx4 v[148:151], v[148:149], off
	s_waitcnt vmcnt(0) lgkmcnt(0)
	v_lshlrev_b32_e32 v2, 16, v182
	v_and_b32_e32 v182, 0xffff0000, v182
	v_lshlrev_b32_e32 v189, 16, v183
	v_and_b32_e32 v183, 0xffff0000, v183
	v_lshlrev_b32_e32 v194, 16, v184
	v_and_b32_e32 v184, 0xffff0000, v184
	v_lshlrev_b32_e32 v195, 16, v185
	v_and_b32_e32 v185, 0xffff0000, v185
	v_add_f32_e32 v2, v144, v2
	v_add_f32_e32 v182, v145, v182
	v_add_f32_e32 v189, v146, v189
	v_add_f32_e32 v183, v147, v183
	v_add_f32_e32 v194, v136, v194
	v_add_f32_e32 v184, v137, v184
	v_add_f32_e32 v195, v138, v195
	v_add_f32_e32 v185, v139, v185
	s_mov_b64 s[2:3], -1
	s_and_b64 vcc, exec, s[8:9]
	v_max_f32_e32 v229, 0xc2200000, v2
	v_max_f32_e32 v228, 0xc2200000, v182
	v_max_f32_e32 v227, 0xc2200000, v189
	v_max_f32_e32 v226, 0xc2200000, v183
	v_max_f32_e32 v225, 0xc2200000, v194
	v_max_f32_e32 v224, 0xc2200000, v184
	v_max_f32_e32 v223, 0xc2200000, v195
	v_max_f32_e32 v222, 0xc2200000, v185
	v_lshlrev_b32_e32 v221, 16, v190
	v_and_b32_e32 v220, 0xffff0000, v190
	v_lshlrev_b32_e32 v219, 16, v191
	v_and_b32_e32 v218, 0xffff0000, v191
	v_lshlrev_b32_e32 v217, 16, v192
	v_and_b32_e32 v216, 0xffff0000, v192
	v_lshlrev_b32_e32 v215, 16, v193
	v_and_b32_e32 v214, 0xffff0000, v193
	v_lshlrev_b32_e32 v213, 16, v230
	v_and_b32_e32 v212, 0xffff0000, v230
	v_lshlrev_b32_e32 v197, 16, v231
	v_and_b32_e32 v196, 0xffff0000, v231
	v_lshlrev_b32_e32 v195, 16, v232
	v_and_b32_e32 v194, 0xffff0000, v232
	v_lshlrev_b32_e32 v193, 16, v233
	v_and_b32_e32 v192, 0xffff0000, v233
	v_lshlrev_b32_e32 v191, 16, v234
	v_and_b32_e32 v190, 0xffff0000, v234
	v_lshlrev_b32_e32 v189, 16, v235
	v_and_b32_e32 v185, 0xffff0000, v235
	v_lshlrev_b32_e32 v184, 16, v236
	v_and_b32_e32 v183, 0xffff0000, v236
	v_lshlrev_b32_e32 v182, 16, v237
	v_and_b32_e32 v2, 0xffff0000, v237
	s_cbranch_vccz .LBB0_559
	s_andn2_b64 vcc, exec, s[2:3]
	s_cbranch_vccz .LBB0_560

; __device__ __forceinline__ float sigmoidf_(float x) { return __builtin_amdgcn_rcpf(1.0f + __expf(-x)); }
;   __device__ __forceinline__ void operator()(EPI_ARGS) const {
;     ...
;           for (int m = 0; m < 4; ++m) {
;             float xc[8], y[8];
;             unpack8(zc[m], xc);
; #pragma unroll
;             for (int k = 0; k < 8; ++k) y[k] = acc[ai][bj][m][k >> 2][k & 3] * sigmoidf_(fmaxf(xc[k] + gc[k], -40.f));
;             u32x4 o;
;             o.x = pack2(y[0], y[1]); o.y = pack2(y[2], y[3]); o.z = pack2(y[4], y[5]); o.w = pack2(y[6], y[7]);
;             *(u32x4*)(mrow + (size_t)(ai * HALF + m * 16) * DM + bj * HALF) = o;
;           }
.LBB0_559:
	v_mul_f32_e32 v230, 0xbfb8aa3b, v229
	v_mul_f32_e32 v231, 0xbfb8aa3b, v228
	v_mul_f32_e32 v232, 0xbfb8aa3b, v227
	v_mul_f32_e32 v234, 0xbfb8aa3b, v225
	v_exp_f32_e32 v230, v230
	v_exp_f32_e32 v231, v231
	v_exp_f32_e32 v232, v232
	v_mul_f32_e32 v233, 0xbfb8aa3b, v226
	v_exp_f32_e32 v234, v234
	v_mul_f32_e32 v235, 0xbfb8aa3b, v224
	v_exp_f32_e32 v233, v233
	v_exp_f32_e32 v235, v235
	v_mul_f32_e32 v236, 0xbfb8aa3b, v223
	v_exp_f32_e32 v236, v236
	v_mul_f32_e32 v237, 0xbfb8aa3b, v222
	v_add_f32_e32 v230, 1.0, v230
	v_add_f32_e32 v231, 1.0, v231
	v_add_f32_e32 v232, 1.0, v232
	v_add_f32_e32 v234, 1.0, v234
	v_exp_f32_e32 v237, v237
	v_rcp_f32_e32 v230, v230
	v_rcp_f32_e32 v231, v231
	v_rcp_f32_e32 v232, v232
	v_add_f32_e32 v233, 1.0, v233
	v_rcp_f32_e32 v234, v234
	v_add_f32_e32 v235, 1.0, v235
	v_rcp_f32_e32 v233, v233
	v_rcp_f32_e32 v235, v235
	v_add_f32_e32 v236, 1.0, v236
	v_rcp_f32_e32 v236, v236
	v_add_f32_e32 v237, 1.0, v237
	v_mul_f32_e32 v230, v32, v230
	v_mul_f32_e32 v231, v33, v231
	v_mul_f32_e32 v232, v34, v232
	v_rcp_f32_e32 v237, v237
	v_mul_f32_e32 v234, v28, v234
	v_mul_f32_e32 v233, v35, v233
	v_mul_f32_e32 v235, v29, v235
	v_cvt_pk_bf16_f32 v230, v230, v231
	v_cvt_pk_bf16_f32 v231, v232, v233
	v_cvt_pk_bf16_f32 v232, v234, v235
	v_add_f32_e32 v234, v144, v221
	v_max_f32_e32 v234, 0xc2200000, v234
	v_mul_f32_e32 v236, v30, v236
	v_mul_f32_e32 v234, 0xbfb8aa3b, v234
	s_mov_b32 s1, 0x80000
	v_mul_f32_e32 v237, v31, v237
	v_cvt_pk_bf16_f32 v233, v236, v237
	v_exp_f32_e32 v236, v234
	v_add_co_u32_e32 v234, vcc, s1, v0
	v_add_f32_e32 v237, v139, v214
	s_nop 0
	v_addc_co_u32_e32 v235, vcc, 0, v1, vcc
	global_store_dwordx4 v[234:235], v[230:233], off offset:256
	v_add_f32_e32 v234, v136, v217
	v_max_f32_e32 v234, 0xc2200000, v234
	v_add_f32_e32 v231, v145, v220
	v_add_f32_e32 v232, v146, v219
	v_max_f32_e32 v231, 0xc2200000, v231
	v_max_f32_e32 v232, 0xc2200000, v232
	v_add_f32_e32 v233, v147, v218
	v_add_f32_e32 v235, v137, v216
	v_mul_f32_e32 v231, 0xbfb8aa3b, v231
	v_mul_f32_e32 v232, 0xbfb8aa3b, v232
	v_max_f32_e32 v233, 0xc2200000, v233
	v_mul_f32_e32 v234, 0xbfb8aa3b, v234
	v_max_f32_e32 v235, 0xc2200000, v235
	v_add_f32_e32 v230, 1.0, v236
	v_exp_f32_e32 v231, v231
	v_exp_f32_e32 v232, v232
	v_mul_f32_e32 v233, 0xbfb8aa3b, v233
	v_exp_f32_e32 v234, v234
	v_mul_f32_e32 v235, 0xbfb8aa3b, v235
	v_add_f32_e32 v236, v138, v215
	v_exp_f32_e32 v233, v233
	v_exp_f32_e32 v235, v235
	v_max_f32_e32 v236, 0xc2200000, v236
	v_mul_f32_e32 v236, 0xbfb8aa3b, v236
	v_max_f32_e32 v237, 0xc2200000, v237
	v_exp_f32_e32 v236, v236
	v_mul_f32_e32 v237, 0xbfb8aa3b, v237
	v_add_f32_e32 v231, 1.0, v231
	v_add_f32_e32 v232, 1.0, v232
	v_add_f32_e32 v234, 1.0, v234
	v_exp_f32_e32 v237, v237
	v_rcp_f32_e32 v230, v230
	v_rcp_f32_e32 v231, v231
	v_rcp_f32_e32 v232, v232
	v_add_f32_e32 v233, 1.0, v233
	v_rcp_f32_e32 v234, v234
	v_add_f32_e32 v235, 1.0, v235
	v_rcp_f32_e32 v233, v233
	v_rcp_f32_e32 v235, v235
	v_add_f32_e32 v236, 1.0, v236
	v_rcp_f32_e32 v236, v236
	v_add_f32_e32 v237, 1.0, v237
	v_mul_f32_e32 v230, v24, v230
	v_mul_f32_e32 v231, v25, v231
	v_mul_f32_e32 v232, v26, v232
	v_rcp_f32_e32 v237, v237
	v_mul_f32_e32 v234, v20, v234
	v_mul_f32_e32 v233, v27, v233
	v_mul_f32_e32 v235, v21, v235
	v_cvt_pk_bf16_f32 v230, v230, v231
	v_cvt_pk_bf16_f32 v231, v232, v233
	v_cvt_pk_bf16_f32 v232, v234, v235
	v_add_f32_e32 v234, v144, v213
	v_max_f32_e32 v234, 0xc2200000, v234
	v_mul_f32_e32 v236, v22, v236
	v_mul_f32_e32 v234, 0xbfb8aa3b, v234
	s_mov_b32 s1, 0x90000
	v_mul_f32_e32 v237, v23, v237
	v_cvt_pk_bf16_f32 v233, v236, v237
	v_exp_f32_e32 v236, v234
	v_add_co_u32_e32 v234, vcc, s1, v0
	v_add_f32_e32 v237, v139, v192
	s_nop 0
	v_addc_co_u32_e32 v235, vcc, 0, v1, vcc
	global_store_dwordx4 v[234:235], v[230:233], off offset:256
	v_add_f32_e32 v234, v136, v195
	v_max_f32_e32 v234, 0xc2200000, v234
	v_add_f32_e32 v231, v145, v212
; __device__ __forceinline__ float sigmoidf_(float x) { return __builtin_amdgcn_rcpf(1.0f + __expf(-x)); }
;   __device__ __forceinline__ void operator()(EPI_ARGS) const {
;     ...
;           for (int m = 0; m < 4; ++m) {
;             float xc[8], y[8];
;             unpack8(zc[m], xc);
; #pragma unroll
;             for (int k = 0; k < 8; ++k) y[k] = acc[ai][bj][m][k >> 2][k & 3] * sigmoidf_(fmaxf(xc[k] + gc[k], -40.f));
;             u32x4 o;
;             o.x = pack2(y[0], y[1]); o.y = pack2(y[2], y[3]); o.z = pack2(y[4], y[5]); o.w = pack2(y[6], y[7]);
;             *(u32x4*)(mrow + (size_t)(ai * HALF + m * 16) * DM + bj * HALF) = o;
;           }
	v_add_f32_e32 v232, v146, v197
	v_max_f32_e32 v231, 0xc2200000, v231
	v_max_f32_e32 v232, 0xc2200000, v232
	v_add_f32_e32 v233, v147, v196
	v_add_f32_e32 v235, v137, v194
	v_mul_f32_e32 v231, 0xbfb8aa3b, v231
	v_mul_f32_e32 v232, 0xbfb8aa3b, v232
	v_max_f32_e32 v233, 0xc2200000, v233
	v_mul_f32_e32 v234, 0xbfb8aa3b, v234
	v_max_f32_e32 v235, 0xc2200000, v235
	v_add_f32_e32 v230, 1.0, v236
	v_exp_f32_e32 v231, v231
	v_exp_f32_e32 v232, v232
	v_mul_f32_e32 v233, 0xbfb8aa3b, v233
	v_exp_f32_e32 v234, v234
	v_mul_f32_e32 v235, 0xbfb8aa3b, v235
	v_add_f32_e32 v236, v138, v193
	v_exp_f32_e32 v233, v233
	v_exp_f32_e32 v235, v235
	v_max_f32_e32 v236, 0xc2200000, v236
	v_mul_f32_e32 v236, 0xbfb8aa3b, v236
	v_max_f32_e32 v237, 0xc2200000, v237
	v_exp_f32_e32 v236, v236
	v_mul_f32_e32 v237, 0xbfb8aa3b, v237
	v_add_f32_e32 v231, 1.0, v231
	v_add_f32_e32 v232, 1.0, v232
	v_add_f32_e32 v234, 1.0, v234
	v_exp_f32_e32 v237, v237
	v_rcp_f32_e32 v230, v230
	v_rcp_f32_e32 v231, v231
	v_rcp_f32_e32 v232, v232
	v_add_f32_e32 v233, 1.0, v233
	v_rcp_f32_e32 v234, v234
	v_add_f32_e32 v235, 1.0, v235
	v_rcp_f32_e32 v233, v233
	v_rcp_f32_e32 v235, v235
	v_add_f32_e32 v236, 1.0, v236
	v_rcp_f32_e32 v236, v236
	v_add_f32_e32 v237, 1.0, v237
	v_mul_f32_e32 v230, v16, v230
	v_mul_f32_e32 v231, v17, v231
	v_mul_f32_e32 v232, v18, v232
	v_rcp_f32_e32 v237, v237
	v_mul_f32_e32 v234, v12, v234
	v_mul_f32_e32 v233, v19, v233
	v_mul_f32_e32 v235, v13, v235
	v_cvt_pk_bf16_f32 v230, v230, v231
	v_cvt_pk_bf16_f32 v231, v232, v233
	v_cvt_pk_bf16_f32 v232, v234, v235
	v_add_f32_e32 v234, v144, v191
	v_max_f32_e32 v234, 0xc2200000, v234
	v_mul_f32_e32 v236, v14, v236
	v_mul_f32_e32 v234, 0xbfb8aa3b, v234
	v_mul_f32_e32 v237, v15, v237
	v_cvt_pk_bf16_f32 v233, v236, v237
	v_exp_f32_e32 v236, v234
	s_mov_b32 s1, 0xa0000
	v_add_co_u32_e32 v234, vcc, s1, v0
	v_add_f32_e32 v237, v139, v2
	s_nop 0
	v_addc_co_u32_e32 v235, vcc, 0, v1, vcc
	global_store_dwordx4 v[234:235], v[230:233], off offset:256
	v_add_f32_e32 v234, v136, v184
	v_add_f32_e32 v235, v137, v183
	v_add_f32_e32 v231, v145, v190
	v_add_f32_e32 v232, v146, v189
	v_add_f32_e32 v233, v147, v185
	v_add_f32_e32 v230, 1.0, v236
	v_max_f32_e32 v231, 0xc2200000, v231
	v_max_f32_e32 v232, 0xc2200000, v232
	v_max_f32_e32 v233, 0xc2200000, v233
	v_add_f32_e32 v236, v138, v182
	v_mul_f32_e32 v231, 0xbfb8aa3b, v231
	v_mul_f32_e32 v232, 0xbfb8aa3b, v232
	v_mul_f32_e32 v233, 0xbfb8aa3b, v233
	v_max_f32_e32 v234, 0xc2200000, v234
	v_max_f32_e32 v235, 0xc2200000, v235
	v_max_f32_e32 v236, 0xc2200000, v236
	v_max_f32_e32 v237, 0xc2200000, v237
	v_exp_f32_e32 v231, v231
	v_exp_f32_e32 v232, v232
	v_exp_f32_e32 v233, v233
	v_mul_f32_e32 v234, 0xbfb8aa3b, v234
	v_mul_f32_e32 v235, 0xbfb8aa3b, v235
	v_mul_f32_e32 v236, 0xbfb8aa3b, v236
	v_mul_f32_e32 v237, 0xbfb8aa3b, v237
	v_exp_f32_e32 v234, v234
	v_exp_f32_e32 v235, v235
	v_exp_f32_e32 v236, v236
	v_exp_f32_e32 v237, v237
	v_add_f32_e32 v231, 1.0, v231
	v_add_f32_e32 v232, 1.0, v232
	v_add_f32_e32 v233, 1.0, v233
	v_rcp_f32_e32 v230, v230
	v_rcp_f32_e32 v231, v231
	v_rcp_f32_e32 v232, v232
	v_rcp_f32_e32 v233, v233
	v_add_f32_e32 v234, 1.0, v234
	v_add_f32_e32 v235, 1.0, v235
	v_add_f32_e32 v236, 1.0, v236
	v_add_f32_e32 v237, 1.0, v237
	v_rcp_f32_e32 v234, v234
	v_rcp_f32_e32 v235, v235
	v_rcp_f32_e32 v236, v236
	v_rcp_f32_e32 v237, v237
	v_add_co_u32_e32 v0, vcc, 0xb0000, v0
	v_mul_f32_e32 v230, v8, v230
	v_mul_f32_e32 v231, v9, v231
	v_mul_f32_e32 v232, v10, v232
	v_mul_f32_e32 v233, v11, v233
	v_addc_co_u32_e32 v1, vcc, 0, v1, vcc
	v_mul_f32_e32 v234, v4, v234
	v_mul_f32_e32 v235, v5, v235
	v_mul_f32_e32 v236, v6, v236
	v_mul_f32_e32 v237, v7, v237
	v_cvt_pk_bf16_f32 v230, v230, v231
	v_cvt_pk_bf16_f32 v231, v232, v233
	v_cvt_pk_bf16_f32 v232, v234, v235
	v_cvt_pk_bf16_f32 v233, v236, v237
	global_store_dwordx4 v[0:1], v[230:233], off offset:256
	s_cbranch_execnz .LBB0_558

; #define PG8_WAIT_V(n) asm volatile("s_waitcnt vmcnt(" #n ")" ::: "memory")
; #define PG8_WAIT_L(n) asm volatile("s_waitcnt lgkmcnt(" #n ")" ::: "memory")
; #define PG8_BAR __builtin_amdgcn_s_barrier()
; #define PG8_SCHED __builtin_amdgcn_sched_barrier(0)
; template <class Epi, class AddrA, class AddrB>
; __device__ __forceinline__ void gemm_phase(const Sched S, const int lda, const int ldb, const int K, const AddrA addrA,
;                                            const AddrB addrB, const Epi E) {
;     ...
;       PG8_LDB(B0, 0, 0); PG8_SCHED; PG8_LDA(At, 0, 0); PG8_STAGE(PG8_SA(1, 1), a1 + hstepA, voffA);
;       PG8_WAIT_L(8); PG8_BAR; PG8_WAIT_L(0); PG8_MMA(0, 0, At, B0); PG8_BAR; PG8_SCHED;
;       PG8_LDB(B1, 0, 1); PG8_STAGE(PG8_SB(0, 0), b2, voffB);
;       PG8_BAR; PG8_WAIT_L(0); PG8_MMA(0, 1, At, B1); PG8_BAR;
;       PG8_LDA(At, 0, 1); PG8_STAGE(PG8_SA(0, 0), a2, voffA);
;       PG8_BAR; PG8_WAIT_L(0); PG8_MMA(1, 0, At, B0); PG8_BAR; PG8_SCHED;
;       PG8_STAGE(PG8_SB(0, 1), b2 + hstepB, voffB);
;       PG8_WAIT_V(6); PG8_BAR; PG8_MMA(1, 1, At, B1); PG8_BAR;
;       PG8_LDB(B0, 1, 0); PG8_SCHED; PG8_LDA(At, 1, 0); PG8_STAGE(PG8_SA(0, 1), a2 + hstepA, voffA);
;       PG8_WAIT_L(8); PG8_BAR; PG8_WAIT_L(0); PG8_MMA(0, 0, At, B0); PG8_BAR; PG8_SCHED;
;       PG8_LDB(B1, 1, 1); PG8_STAGE(PG8_SB(1, 0), b3, voffB);
;       PG8_BAR; PG8_WAIT_L(0); PG8_MMA(0, 1, At, B1); PG8_BAR;
;       PG8_LDA(At, 1, 1); PG8_STAGE(PG8_SA(1, 0), a3, voffA);
;       PG8_BAR; PG8_WAIT_L(0); PG8_MMA(1, 0, At, B0); PG8_BAR; PG8_SCHED;
;       PG8_STAGE(PG8_SB(1, 1), b3 + hstepB, voffB);
;       PG8_WAIT_V(6); PG8_BAR; PG8_MMA(1, 1, At, B1); PG8_BAR;
.LBB0_619:
	s_add_u32 s16, s14, 0xfff80080
	s_addc_u32 s17, s15, -1
	s_add_i32 s39, 0, 0x10000
	v_add_u32_e32 v142, s39, v144
	ds_read_b128 v[148:151], v142
	ds_read_b128 v[152:155], v142 offset:1024
	ds_read_b128 v[156:159], v142 offset:2048
	ds_read_b128 v[160:163], v142 offset:3072
	s_cmp_eq_u32 s38, 28
	s_cselect_b32 s19, s3, s17
	s_cselect_b32 s18, s13, s16
	s_cselect_b32 s17, s5, s37
	s_cselect_b32 s16, s35, s36
	v_lshl_add_u64 v[142:143], s[14:15], 0, v[140:141]
	s_add_i32 m0, s26, 0xc000
	ds_read_b128 v[168:171], v146
	ds_read_b128 v[172:175], v146 offset:1024
	ds_read_b128 v[176:179], v146 offset:2048
	ds_read_b128 v[180:183], v146 offset:3072
	ds_read_b128 v[184:187], v146 offset:4096
	ds_read_b128 v[188:191], v146 offset:5120
	ds_read_b128 v[192:195], v146 offset:6144
	ds_read_b128 v[212:215], v146 offset:7168
	global_load_lds_dwordx4 v[142:143], off
	v_lshl_add_u64 v[142:143], s[14:15], 0, v[138:139]
	s_add_i32 m0, s26, 0xe000
	s_nop 0
	global_load_lds_dwordx4 v[142:143], off
	s_waitcnt lgkmcnt(8)
	s_barrier
	s_waitcnt lgkmcnt(0)
	s_setprio 1
	s_waitcnt lgkmcnt(0)
	v_mfma_f32_16x16x32_bf16 v[128:131], v[148:151], v[168:171], v[128:131]
	v_mfma_f32_16x16x32_bf16 v[124:127], v[156:159], v[168:171], v[124:127]
	v_mfma_f32_16x16x32_bf16 v[120:123], v[148:151], v[176:179], v[120:123]
	v_mfma_f32_16x16x32_bf16 v[116:119], v[156:159], v[176:179], v[116:119]
	v_mfma_f32_16x16x32_bf16 v[112:115], v[148:151], v[184:187], v[112:115]
	v_mfma_f32_16x16x32_bf16 v[108:111], v[156:159], v[184:187], v[108:111]
	v_mfma_f32_16x16x32_bf16 v[104:107], v[148:151], v[192:195], v[104:107]
	v_mfma_f32_16x16x32_bf16 v[100:103], v[156:159], v[192:195], v[100:103]
	v_mfma_f32_16x16x32_bf16 v[128:131], v[152:155], v[172:175], v[128:131]
	v_mfma_f32_16x16x32_bf16 v[124:127], v[160:163], v[172:175], v[124:127]
	v_mfma_f32_16x16x32_bf16 v[120:123], v[152:155], v[180:183], v[120:123]
	v_mfma_f32_16x16x32_bf16 v[116:119], v[160:163], v[180:183], v[116:119]
	v_mfma_f32_16x16x32_bf16 v[112:115], v[152:155], v[188:191], v[112:115]
	v_mfma_f32_16x16x32_bf16 v[108:111], v[160:163], v[188:191], v[108:111]
	v_mfma_f32_16x16x32_bf16 v[104:107], v[152:155], v[212:215], v[104:107]
	v_mfma_f32_16x16x32_bf16 v[100:103], v[160:163], v[212:215], v[100:103]
	s_setprio 0
	s_barrier
	s_add_i32 s42, 0, 0x14000
	v_add_u32_e32 v142, s42, v144
	s_add_i32 s39, s39, s25
	ds_read_b128 v[216:219], v142
	ds_read_b128 v[220:223], v142 offset:1024
	ds_read_b128 v[224:227], v142 offset:2048
	ds_read_b128 v[228:231], v142 offset:3072
	v_lshl_add_u64 v[142:143], s[16:17], 0, v[2:3]
	s_mov_b32 m0, s39
	v_lshl_add_u64 v[196:197], s[16:17], 0, v[0:1]
	global_load_lds_dwordx4 v[142:143], off
	s_add_i32 m0, s39, 0x2000
	s_nop 0
	global_load_lds_dwordx4 v[196:197], off
	s_barrier
	s_waitcnt lgkmcnt(0)
	s_setprio 1
	s_waitcnt lgkmcnt(0)
	v_mfma_f32_16x16x32_bf16 v[96:99], v[216:219], v[168:171], v[96:99]
	v_mfma_f32_16x16x32_bf16 v[92:95], v[224:227], v[168:171], v[92:95]
	v_mfma_f32_16x16x32_bf16 v[88:91], v[216:219], v[176:179], v[88:91]
	v_mfma_f32_16x16x32_bf16 v[84:87], v[224:227], v[176:179], v[84:87]
	v_mfma_f32_16x16x32_bf16 v[80:83], v[216:219], v[184:187], v[80:83]
	v_mfma_f32_16x16x32_bf16 v[76:79], v[224:227], v[184:187], v[76:79]
	v_mfma_f32_16x16x32_bf16 v[72:75], v[216:219], v[192:195], v[72:75]
	v_mfma_f32_16x16x32_bf16 v[68:71], v[224:227], v[192:195], v[68:71]
	v_mfma_f32_16x16x32_bf16 v[96:99], v[220:223], v[172:175], v[96:99]
	v_mfma_f32_16x16x32_bf16 v[92:95], v[228:231], v[172:175], v[92:95]
	v_mfma_f32_16x16x32_bf16 v[88:91], v[220:223], v[180:183], v[88:91]
	v_mfma_f32_16x16x32_bf16 v[84:87], v[228:231], v[180:183], v[84:87]
	v_mfma_f32_16x16x32_bf16 v[80:83], v[220:223], v[188:191], v[80:83]
	v_mfma_f32_16x16x32_bf16 v[76:79], v[228:231], v[188:191], v[76:79]
	v_mfma_f32_16x16x32_bf16 v[72:75], v[220:223], v[212:215], v[72:75]
	v_mfma_f32_16x16x32_bf16 v[68:71], v[228:231], v[212:215], v[68:71]
	s_setprio 0
	s_mov_b32 m0, s26
	v_lshl_add_u64 v[232:233], s[18:19], 0, v[134:135]
	s_barrier
	ds_read_b128 v[168:171], v146 offset:16384
	ds_read_b128 v[172:175], v146 offset:17408
	ds_read_b128 v[176:179], v146 offset:18432
	ds_read_b128 v[180:183], v146 offset:19456
	ds_read_b128 v[184:187], v146 offset:20480
	ds_read_b128 v[188:191], v146 offset:21504
	ds_read_b128 v[192:195], v146 offset:22528
	ds_read_b128 v[212:215], v146 offset:23552
	global_load_lds_dwordx4 v[232:233], off
	v_lshl_add_u64 v[234:235], s[18:19], 0, v[132:133]
	s_mov_b32 m0, s27
	s_nop 0
	global_load_lds_dwordx4 v[234:235], off
	s_barrier
	s_waitcnt lgkmcnt(0)
	s_setprio 1
	s_waitcnt lgkmcnt(0)
	v_mfma_f32_16x16x32_bf16 v[64:67], v[148:151], v[168:171], v[64:67]
	v_mfma_f32_16x16x32_bf16 v[60:63], v[156:159], v[168:171], v[60:63]
	v_mfma_f32_16x16x32_bf16 v[56:59], v[148:151], v[176:179], v[56:59]
	v_mfma_f32_16x16x32_bf16 v[52:55], v[156:159], v[176:179], v[52:55]
	v_mfma_f32_16x16x32_bf16 v[48:51], v[148:151], v[184:187], v[48:51]
	v_mfma_f32_16x16x32_bf16 v[44:47], v[156:159], v[184:187], v[44:47]
	v_mfma_f32_16x16x32_bf16 v[40:43], v[148:151], v[192:195], v[40:43]
	v_mfma_f32_16x16x32_bf16 v[36:39], v[156:159], v[192:195], v[36:39]
	v_mfma_f32_16x16x32_bf16 v[64:67], v[152:155], v[172:175], v[64:67]
	v_mfma_f32_16x16x32_bf16 v[60:63], v[160:163], v[172:175], v[60:63]
	v_mfma_f32_16x16x32_bf16 v[56:59], v[152:155], v[180:183], v[56:59]
	v_mfma_f32_16x16x32_bf16 v[52:55], v[160:163], v[180:183], v[52:55]
	v_mfma_f32_16x16x32_bf16 v[48:51], v[152:155], v[188:191], v[48:51]
	v_mfma_f32_16x16x32_bf16 v[44:47], v[160:163], v[188:191], v[44:47]
	v_mfma_f32_16x16x32_bf16 v[40:43], v[152:155], v[212:215], v[40:43]
	v_mfma_f32_16x16x32_bf16 v[36:39], v[160:163], v[212:215], v[36:39]
	s_setprio 0
	s_barrier
; #define PG8_WAIT_V(n) asm volatile("s_waitcnt vmcnt(" #n ")" ::: "memory")
; #define PG8_WAIT_L(n) asm volatile("s_waitcnt lgkmcnt(" #n ")" ::: "memory")
; #define PG8_BAR __builtin_amdgcn_s_barrier()
; #define PG8_SCHED __builtin_amdgcn_sched_barrier(0)
; template <class Epi, class AddrA, class AddrB>
; __device__ __forceinline__ void gemm_phase(const Sched S, const int lda, const int ldb, const int K, const AddrA addrA,
;                                            const AddrB addrB, const Epi E) {
;     ...
;       PG8_LDB(B0, 0, 0); PG8_SCHED; PG8_LDA(At, 0, 0); PG8_STAGE(PG8_SA(1, 1), a1 + hstepA, voffA);
;       PG8_WAIT_L(8); PG8_BAR; PG8_WAIT_L(0); PG8_MMA(0, 0, At, B0); PG8_BAR; PG8_SCHED;
;       PG8_LDB(B1, 0, 1); PG8_STAGE(PG8_SB(0, 0), b2, voffB);
;       PG8_BAR; PG8_WAIT_L(0); PG8_MMA(0, 1, At, B1); PG8_BAR;
;       PG8_LDA(At, 0, 1); PG8_STAGE(PG8_SA(0, 0), a2, voffA);
;       PG8_BAR; PG8_WAIT_L(0); PG8_MMA(1, 0, At, B0); PG8_BAR; PG8_SCHED;
;       PG8_STAGE(PG8_SB(0, 1), b2 + hstepB, voffB);
;       PG8_WAIT_V(6); PG8_BAR; PG8_MMA(1, 1, At, B1); PG8_BAR;
;       PG8_LDB(B0, 1, 0); PG8_SCHED; PG8_LDA(At, 1, 0); PG8_STAGE(PG8_SA(0, 1), a2 + hstepA, voffA);
;       PG8_WAIT_L(8); PG8_BAR; PG8_WAIT_L(0); PG8_MMA(0, 0, At, B0); PG8_BAR; PG8_SCHED;
;       PG8_LDB(B1, 1, 1); PG8_STAGE(PG8_SB(1, 0), b3, voffB);
;       PG8_BAR; PG8_WAIT_L(0); PG8_MMA(0, 1, At, B1); PG8_BAR;
;       PG8_LDA(At, 1, 1); PG8_STAGE(PG8_SA(1, 0), a3, voffA);
;       PG8_BAR; PG8_WAIT_L(0); PG8_MMA(1, 0, At, B0); PG8_BAR; PG8_SCHED;
;       PG8_STAGE(PG8_SB(1, 1), b3 + hstepB, voffB);
;       PG8_WAIT_V(6); PG8_BAR; PG8_MMA(1, 1, At, B1); PG8_BAR;
	s_add_u32 s40, s16, 0x80000
	s_addc_u32 s41, s17, 0
	s_add_i32 s39, s42, s25
	v_lshl_add_u64 v[148:149], s[40:41], 0, v[2:3]
	s_mov_b32 m0, s39
	s_nop 0
	global_load_lds_dwordx4 v[148:149], off
	v_lshl_add_u64 v[148:149], s[40:41], 0, v[0:1]
	s_add_i32 m0, s39, 0x2000
	s_nop 0
	global_load_lds_dwordx4 v[148:149], off
	s_waitcnt vmcnt(6)
	s_barrier
	s_setprio 1
	v_mfma_f32_16x16x32_bf16 v[32:35], v[216:219], v[168:171], v[32:35]
	v_mfma_f32_16x16x32_bf16 v[28:31], v[224:227], v[168:171], v[28:31]
	v_mfma_f32_16x16x32_bf16 v[24:27], v[216:219], v[176:179], v[24:27]
	v_mfma_f32_16x16x32_bf16 v[20:23], v[224:227], v[176:179], v[20:23]
	v_mfma_f32_16x16x32_bf16 v[16:19], v[216:219], v[184:187], v[16:19]
	v_mfma_f32_16x16x32_bf16 v[12:15], v[224:227], v[184:187], v[12:15]
	v_mfma_f32_16x16x32_bf16 v[8:11], v[216:219], v[192:195], v[8:11]
	v_mfma_f32_16x16x32_bf16 v[4:7], v[224:227], v[192:195], v[4:7]
	v_mfma_f32_16x16x32_bf16 v[32:35], v[220:223], v[172:175], v[32:35]
	v_mfma_f32_16x16x32_bf16 v[28:31], v[228:231], v[172:175], v[28:31]
	v_mfma_f32_16x16x32_bf16 v[24:27], v[220:223], v[180:183], v[24:27]
	v_mfma_f32_16x16x32_bf16 v[20:23], v[228:231], v[180:183], v[20:23]
	v_mfma_f32_16x16x32_bf16 v[16:19], v[220:223], v[188:191], v[16:19]
	v_mfma_f32_16x16x32_bf16 v[12:15], v[228:231], v[188:191], v[12:15]
	v_mfma_f32_16x16x32_bf16 v[8:11], v[220:223], v[212:215], v[8:11]
	v_mfma_f32_16x16x32_bf16 v[4:7], v[228:231], v[212:215], v[4:7]
	s_setprio 0
	s_add_i32 s39, 0, 0x18000
	v_add_u32_e32 v147, s39, v144
	s_barrier
	ds_read_b128 v[148:151], v147
	ds_read_b128 v[152:155], v147 offset:1024
	ds_read_b128 v[156:159], v147 offset:2048
	ds_read_b128 v[160:163], v147 offset:3072
	s_add_u32 s18, s18, 0x80000
	s_addc_u32 s19, s19, 0
	s_mov_b32 m0, s28
	v_lshl_add_u64 v[216:217], s[18:19], 0, v[134:135]
	ds_read_b128 v[168:171], v146 offset:32768
	ds_read_b128 v[172:175], v146 offset:33792
	ds_read_b128 v[176:179], v146 offset:34816
	ds_read_b128 v[180:183], v146 offset:35840
	ds_read_b128 v[184:187], v146 offset:36864
	ds_read_b128 v[188:191], v146 offset:37888
	ds_read_b128 v[192:195], v146 offset:38912
	ds_read_b128 v[212:215], v146 offset:39936
	global_load_lds_dwordx4 v[216:217], off
	v_lshl_add_u64 v[216:217], s[18:19], 0, v[132:133]
	s_mov_b32 m0, s29
	s_nop 0
	global_load_lds_dwordx4 v[216:217], off
	s_waitcnt lgkmcnt(8)
	s_barrier
	s_waitcnt lgkmcnt(0)
	s_setprio 1
	s_waitcnt lgkmcnt(0)
	v_mfma_f32_16x16x32_bf16 v[128:131], v[148:151], v[168:171], v[128:131]
	v_mfma_f32_16x16x32_bf16 v[124:127], v[156:159], v[168:171], v[124:127]
	v_mfma_f32_16x16x32_bf16 v[120:123], v[148:151], v[176:179], v[120:123]
	v_mfma_f32_16x16x32_bf16 v[116:119], v[156:159], v[176:179], v[116:119]
	v_mfma_f32_16x16x32_bf16 v[112:115], v[148:151], v[184:187], v[112:115]
	v_mfma_f32_16x16x32_bf16 v[108:111], v[156:159], v[184:187], v[108:111]
	v_mfma_f32_16x16x32_bf16 v[104:107], v[148:151], v[192:195], v[104:107]
	v_mfma_f32_16x16x32_bf16 v[100:103], v[156:159], v[192:195], v[100:103]
	v_mfma_f32_16x16x32_bf16 v[128:131], v[152:155], v[172:175], v[128:131]
	v_mfma_f32_16x16x32_bf16 v[124:127], v[160:163], v[172:175], v[124:127]
	v_mfma_f32_16x16x32_bf16 v[120:123], v[152:155], v[180:183], v[120:123]
	v_mfma_f32_16x16x32_bf16 v[116:119], v[160:163], v[180:183], v[116:119]
	v_mfma_f32_16x16x32_bf16 v[112:115], v[152:155], v[188:191], v[112:115]
	v_mfma_f32_16x16x32_bf16 v[108:111], v[160:163], v[188:191], v[108:111]
	v_mfma_f32_16x16x32_bf16 v[104:107], v[152:155], v[212:215], v[104:107]
	v_mfma_f32_16x16x32_bf16 v[100:103], v[160:163], v[212:215], v[100:103]
	s_setprio 0
	s_barrier
	s_add_i32 s18, 0, 0x1c000
	s_add_i32 s19, s39, s25
	v_add_u32_e32 v147, s18, v144
	v_lshl_add_u64 v[142:143], v[142:143], 0, s[52:53]
	s_mov_b32 m0, s19
	ds_read_b128 v[216:219], v147
	ds_read_b128 v[220:223], v147 offset:1024
	ds_read_b128 v[224:227], v147 offset:2048
	ds_read_b128 v[228:231], v147 offset:3072
	global_load_lds_dwordx4 v[142:143], off
	v_lshl_add_u64 v[142:143], v[196:197], 0, s[52:53]
	s_add_i32 m0, s19, 0x2000
	s_nop 0
	global_load_lds_dwordx4 v[142:143], off
	s_barrier
	s_waitcnt lgkmcnt(0)
	s_setprio 1
	s_waitcnt lgkmcnt(0)
	v_mfma_f32_16x16x32_bf16 v[96:99], v[216:219], v[168:171], v[96:99]
	v_mfma_f32_16x16x32_bf16 v[92:95], v[224:227], v[168:171], v[92:95]
	v_mfma_f32_16x16x32_bf16 v[88:91], v[216:219], v[176:179], v[88:91]
	v_mfma_f32_16x16x32_bf16 v[84:87], v[224:227], v[176:179], v[84:87]
	v_mfma_f32_16x16x32_bf16 v[80:83], v[216:219], v[184:187], v[80:83]
	v_mfma_f32_16x16x32_bf16 v[76:79], v[224:227], v[184:187], v[76:79]
	v_mfma_f32_16x16x32_bf16 v[72:75], v[216:219], v[192:195], v[72:75]
	v_mfma_f32_16x16x32_bf16 v[68:71], v[224:227], v[192:195], v[68:71]
	v_mfma_f32_16x16x32_bf16 v[96:99], v[220:223], v[172:175], v[96:99]
	v_mfma_f32_16x16x32_bf16 v[92:95], v[228:231], v[172:175], v[92:95]
	v_mfma_f32_16x16x32_bf16 v[88:91], v[220:223], v[180:183], v[88:91]
	v_mfma_f32_16x16x32_bf16 v[84:87], v[228:231], v[180:183], v[84:87]
	v_mfma_f32_16x16x32_bf16 v[80:83], v[220:223], v[188:191], v[80:83]
	v_mfma_f32_16x16x32_bf16 v[76:79], v[228:231], v[188:191], v[76:79]
	v_mfma_f32_16x16x32_bf16 v[72:75], v[220:223], v[212:215], v[72:75]
	v_mfma_f32_16x16x32_bf16 v[68:71], v[228:231], v[212:215], v[68:71]
	s_setprio 0
	s_mov_b32 m0, s30
	v_lshl_add_u64 v[142:143], v[232:233], 0, s[52:53]
	s_barrier
	ds_read_b128 v[168:171], v146 offset:49152
	ds_read_b128 v[172:175], v146 offset:50176
	ds_read_b128 v[176:179], v146 offset:51200
	ds_read_b128 v[180:183], v146 offset:52224
	ds_read_b128 v[184:187], v146 offset:53248
	ds_read_b128 v[188:191], v146 offset:54272
	ds_read_b128 v[192:195], v146 offset:55296
	ds_read_b128 v[212:215], v146 offset:56320
	global_load_lds_dwordx4 v[142:143], off
	v_lshl_add_u64 v[142:143], v[234:235], 0, s[52:53]
	s_mov_b32 m0, s31
	s_nop 0
	global_load_lds_dwordx4 v[142:143], off
	s_barrier
; #define PG8_WAIT_V(n) asm volatile("s_waitcnt vmcnt(" #n ")" ::: "memory")
; #define PG8_WAIT_L(n) asm volatile("s_waitcnt lgkmcnt(" #n ")" ::: "memory")
; #define PG8_BAR __builtin_amdgcn_s_barrier()
; #define PG8_SCHED __builtin_amdgcn_sched_barrier(0)
; template <class Epi, class AddrA, class AddrB>
; __device__ __forceinline__ void gemm_phase(const Sched S, const int lda, const int ldb, const int K, const AddrA addrA,
;                                            const AddrB addrB, const Epi E) {
;     ...
;       PG8_LDB(B0, 0, 0); PG8_SCHED; PG8_LDA(At, 0, 0); PG8_STAGE(PG8_SA(1, 1), a1 + hstepA, voffA);
;       PG8_WAIT_L(8); PG8_BAR; PG8_WAIT_L(0); PG8_MMA(0, 0, At, B0); PG8_BAR; PG8_SCHED;
;       PG8_LDB(B1, 0, 1); PG8_STAGE(PG8_SB(0, 0), b2, voffB);
;       PG8_BAR; PG8_WAIT_L(0); PG8_MMA(0, 1, At, B1); PG8_BAR;
;       PG8_LDA(At, 0, 1); PG8_STAGE(PG8_SA(0, 0), a2, voffA);
;       PG8_BAR; PG8_WAIT_L(0); PG8_MMA(1, 0, At, B0); PG8_BAR; PG8_SCHED;
;       PG8_STAGE(PG8_SB(0, 1), b2 + hstepB, voffB);
;       PG8_WAIT_V(6); PG8_BAR; PG8_MMA(1, 1, At, B1); PG8_BAR;
;       PG8_LDB(B0, 1, 0); PG8_SCHED; PG8_LDA(At, 1, 0); PG8_STAGE(PG8_SA(0, 1), a2 + hstepA, voffA);
;       PG8_WAIT_L(8); PG8_BAR; PG8_WAIT_L(0); PG8_MMA(0, 0, At, B0); PG8_BAR; PG8_SCHED;
;       PG8_LDB(B1, 1, 1); PG8_STAGE(PG8_SB(1, 0), b3, voffB);
;       PG8_BAR; PG8_WAIT_L(0); PG8_MMA(0, 1, At, B1); PG8_BAR;
;       PG8_LDA(At, 1, 1); PG8_STAGE(PG8_SA(1, 0), a3, voffA);
;       PG8_BAR; PG8_WAIT_L(0); PG8_MMA(1, 0, At, B0); PG8_BAR; PG8_SCHED;
;       PG8_STAGE(PG8_SB(1, 1), b3 + hstepB, voffB);
;       PG8_WAIT_V(6); PG8_BAR; PG8_MMA(1, 1, At, B1); PG8_BAR;
;   __device__ __forceinline__ void operator()(EPI_ARGS) const {
;     ...
;         f32x4 x0[4], x1[4];
; #pragma unroll
;         for (int m = 0; m < 4; ++m) {
;           const size_t o = (row0 + ai * HALF + m * 16) * DM + col0 + bj * HALF;
;           x0[m] = *(const f32x4*)(xres + o);
;           x1[m] = *(const f32x4*)(xres + o + 4);
;         }
;         __builtin_amdgcn_sched_barrier(0);
; #pragma unroll
;         for (int m = 0; m < 4; ++m) {
;           const size_t o = (row0 + ai * HALF + m * 16) * DM + col0 + bj * HALF;
;           *(f32x4*)(hbuf + o) = acc[ai][bj][m][0] + x0[m] * ALPHA;
;           *(f32x4*)(hbuf + o + 4) = acc[ai][bj][m][1] + x1[m] * ALPHA;
;         }
	s_waitcnt lgkmcnt(0)
	s_setprio 1
	s_waitcnt lgkmcnt(0)
	v_mfma_f32_16x16x32_bf16 v[64:67], v[148:151], v[168:171], v[64:67]
	v_mfma_f32_16x16x32_bf16 v[60:63], v[156:159], v[168:171], v[60:63]
	v_mfma_f32_16x16x32_bf16 v[56:59], v[148:151], v[176:179], v[56:59]
	v_mfma_f32_16x16x32_bf16 v[52:55], v[156:159], v[176:179], v[52:55]
	v_mfma_f32_16x16x32_bf16 v[48:51], v[148:151], v[184:187], v[48:51]
	v_mfma_f32_16x16x32_bf16 v[44:47], v[156:159], v[184:187], v[44:47]
	v_mfma_f32_16x16x32_bf16 v[40:43], v[148:151], v[192:195], v[40:43]
	v_mfma_f32_16x16x32_bf16 v[36:39], v[156:159], v[192:195], v[36:39]
	v_mfma_f32_16x16x32_bf16 v[64:67], v[152:155], v[172:175], v[64:67]
	v_mfma_f32_16x16x32_bf16 v[60:63], v[160:163], v[172:175], v[60:63]
	v_mfma_f32_16x16x32_bf16 v[56:59], v[152:155], v[180:183], v[56:59]
	v_mfma_f32_16x16x32_bf16 v[52:55], v[160:163], v[180:183], v[52:55]
	v_mfma_f32_16x16x32_bf16 v[48:51], v[152:155], v[188:191], v[48:51]
	v_mfma_f32_16x16x32_bf16 v[44:47], v[160:163], v[188:191], v[44:47]
	v_mfma_f32_16x16x32_bf16 v[40:43], v[152:155], v[212:215], v[40:43]
	v_mfma_f32_16x16x32_bf16 v[36:39], v[160:163], v[212:215], v[36:39]
	s_setprio 0
	s_barrier
	s_add_u32 s16, s16, 0x80080
	s_addc_u32 s17, s17, 0
	s_add_i32 s18, s18, s25
	v_lshl_add_u64 v[142:143], s[16:17], 0, v[2:3]
	s_mov_b32 m0, s18
	s_nop 0
	global_load_lds_dwordx4 v[142:143], off
	v_lshl_add_u64 v[142:143], s[16:17], 0, v[0:1]
	s_add_i32 m0, s18, 0x2000
	s_nop 0
	global_load_lds_dwordx4 v[142:143], off
	s_waitcnt vmcnt(6)
	s_barrier
	s_setprio 1
	v_mfma_f32_16x16x32_bf16 v[32:35], v[216:219], v[168:171], v[32:35]
	v_mfma_f32_16x16x32_bf16 v[28:31], v[224:227], v[168:171], v[28:31]
	v_mfma_f32_16x16x32_bf16 v[24:27], v[216:219], v[176:179], v[24:27]
	v_mfma_f32_16x16x32_bf16 v[20:23], v[224:227], v[176:179], v[20:23]
	v_mfma_f32_16x16x32_bf16 v[16:19], v[216:219], v[184:187], v[16:19]
	v_mfma_f32_16x16x32_bf16 v[12:15], v[224:227], v[184:187], v[12:15]
	v_mfma_f32_16x16x32_bf16 v[8:11], v[216:219], v[192:195], v[8:11]
	v_mfma_f32_16x16x32_bf16 v[4:7], v[224:227], v[192:195], v[4:7]
	v_mfma_f32_16x16x32_bf16 v[32:35], v[220:223], v[172:175], v[32:35]
	v_mfma_f32_16x16x32_bf16 v[28:31], v[228:231], v[172:175], v[28:31]
	v_mfma_f32_16x16x32_bf16 v[24:27], v[220:223], v[180:183], v[24:27]
	v_mfma_f32_16x16x32_bf16 v[20:23], v[228:231], v[180:183], v[20:23]
	v_mfma_f32_16x16x32_bf16 v[16:19], v[220:223], v[188:191], v[16:19]
	v_mfma_f32_16x16x32_bf16 v[12:15], v[228:231], v[188:191], v[12:15]
	v_mfma_f32_16x16x32_bf16 v[8:11], v[220:223], v[212:215], v[8:11]
	v_mfma_f32_16x16x32_bf16 v[4:7], v[228:231], v[212:215], v[4:7]
	s_setprio 0
	s_add_i32 s38, s38, 2
	s_add_u32 s36, s36, 0x100
	s_addc_u32 s37, s37, 0
	s_add_u32 s14, s14, 0x100
	s_addc_u32 s15, s15, 0
	s_cmp_gt_u32 s38, 29
	s_barrier
	s_cbranch_scc0 .LBB0_619
	s_ashr_i32 s13, s12, 31
	v_lshl_or_b32 v142, s34, 8, v145
	v_ashrrev_i32_e32 v143, 31, v142
	s_lshl_b64 s[12:13], s[12:13], 21
	v_lshlrev_b64 v[184:185], 2, v[142:143]
	v_lshl_add_u64 v[188:189], s[12:13], 0, v[136:137]
	v_lshl_add_u64 v[186:187], s[0:1], 0, v[184:185]
	v_or_b32_e32 v190, 0x20000, v188
	v_mov_b32_e32 v191, v189
	v_or_b32_e32 v192, 0x40000, v188
	v_mov_b32_e32 v193, v189
	v_or_b32_e32 v194, 0x60000, v188
	v_mov_b32_e32 v195, v189
	v_lshl_add_u64 v[142:143], v[186:187], 0, v[188:189]
	v_lshl_add_u64 v[160:161], v[186:187], 0, v[190:191]
	v_lshl_add_u64 v[172:173], v[186:187], 0, v[192:193]
	v_lshl_add_u64 v[180:181], v[186:187], 0, v[194:195]
	global_load_dwordx4 v[148:151], v[142:143], off
	global_load_dwordx4 v[152:155], v[142:143], off offset:16
	global_load_dwordx4 v[156:159], v[160:161], off
	s_nop 0
	global_load_dwordx4 v[160:163], v[160:161], off offset:16
	s_nop 0
	global_load_dwordx4 v[168:171], v[172:173], off
	s_nop 0
	global_load_dwordx4 v[172:175], v[172:173], off offset:16
	s_nop 0
	global_load_dwordx4 v[176:179], v[180:181], off
	s_nop 0
	global_load_dwordx4 v[180:183], v[180:181], off offset:16
	v_lshl_add_u64 v[184:185], s[48:49], 0, v[184:185]
	s_mov_b32 s14, 0x3fb504f3
	s_waitcnt vmcnt(0) lgkmcnt(0)
	v_pk_fma_f32 v[148:149], v[148:149], s[14:15], v[128:129] op_sel_hi:[1,0,1]
	v_lshl_add_u64 v[128:129], v[184:185], 0, v[188:189]
	v_pk_fma_f32 v[126:127], v[154:155], s[14:15], v[126:127] op_sel_hi:[1,0,1]
	v_pk_fma_f32 v[124:125], v[152:153], s[14:15], v[124:125] op_sel_hi:[1,0,1]
	global_store_dwordx4 v[128:129], v[124:127], off offset:16
	v_pk_fma_f32 v[118:119], v[162:163], s[14:15], v[118:119] op_sel_hi:[1,0,1]
	v_pk_fma_f32 v[116:117], v[160:161], s[14:15], v[116:117] op_sel_hi:[1,0,1]
	v_lshl_add_u64 v[124:125], v[184:185], 0, v[190:191]
	v_pk_fma_f32 v[122:123], v[158:159], s[14:15], v[122:123] op_sel_hi:[1,0,1]
	v_pk_fma_f32 v[120:121], v[156:157], s[14:15], v[120:121] op_sel_hi:[1,0,1]
	global_store_dwordx4 v[124:125], v[116:119], off offset:16
	v_pk_fma_f32 v[110:111], v[174:175], s[14:15], v[110:111] op_sel_hi:[1,0,1]
	v_pk_fma_f32 v[108:109], v[172:173], s[14:15], v[108:109] op_sel_hi:[1,0,1]
	v_lshl_add_u64 v[116:117], v[184:185], 0, v[192:193]
	s_mov_b64 s[12:13], 0x200
	v_pk_fma_f32 v[150:151], v[150:151], s[14:15], v[130:131] op_sel_hi:[1,0,1]
	global_store_dwordx4 v[124:125], v[120:123], off
	v_pk_fma_f32 v[114:115], v[170:171], s[14:15], v[114:115] op_sel_hi:[1,0,1]
	v_pk_fma_f32 v[112:113], v[168:169], s[14:15], v[112:113] op_sel_hi:[1,0,1]
	global_store_dwordx4 v[116:117], v[108:111], off offset:16
	v_pk_fma_f32 v[106:107], v[178:179], s[14:15], v[106:107] op_sel_hi:[1,0,1]
	v_pk_fma_f32 v[104:105], v[176:177], s[14:15], v[104:105] op_sel_hi:[1,0,1]
	v_lshl_add_u64 v[108:109], v[184:185], 0, v[194:195]
	v_pk_fma_f32 v[102:103], v[182:183], s[14:15], v[102:103] op_sel_hi:[1,0,1]
	v_pk_fma_f32 v[100:101], v[180:181], s[14:15], v[100:101] op_sel_hi:[1,0,1]
	v_lshl_add_u64 v[124:125], v[186:187], 0, s[12:13]
	global_store_dwordx4 v[128:129], v[148:151], off
	global_store_dwordx4 v[116:117], v[112:115], off
	global_store_dwordx4 v[108:109], v[104:107], off
	global_store_dwordx4 v[108:109], v[100:103], off offset:16
	v_lshl_add_u64 v[112:113], v[124:125], 0, v[190:191]
	v_lshl_add_u64 v[120:121], v[124:125], 0, v[192:193]
	v_lshl_add_u64 v[130:131], v[124:125], 0, v[194:195]
	global_load_dwordx4 v[100:103], v[142:143], off offset:512
	global_load_dwordx4 v[104:107], v[142:143], off offset:528
	global_load_dwordx4 v[108:111], v[112:113], off
	s_nop 0
	global_load_dwordx4 v[112:115], v[112:113], off offset:16
	s_nop 0
	global_load_dwordx4 v[116:119], v[120:121], off
	s_nop 0
	global_load_dwordx4 v[120:123], v[120:121], off offset:16
	s_nop 0
	global_load_dwordx4 v[124:127], v[130:131], off
	global_load_dwordx4 v[148:151], v[130:131], off offset:16
	s_mov_b32 s3, 0x100000
	s_waitcnt vmcnt(0) lgkmcnt(0)
;   __device__ __forceinline__ void operator()(EPI_ARGS) const {
;     ...
;         f32x4 x0[4], x1[4];
; #pragma unroll
;         for (int m = 0; m < 4; ++m) {
;           const size_t o = (row0 + ai * HALF + m * 16) * DM + col0 + bj * HALF;
;           x0[m] = *(const f32x4*)(xres + o);
;           x1[m] = *(const f32x4*)(xres + o + 4);
;         }
;         __builtin_amdgcn_sched_barrier(0);
; #pragma unroll
;         for (int m = 0; m < 4; ++m) {
;           const size_t o = (row0 + ai * HALF + m * 16) * DM + col0 + bj * HALF;
;           *(f32x4*)(hbuf + o) = acc[ai][bj][m][0] + x0[m] * ALPHA;
;           *(f32x4*)(hbuf + o + 4) = acc[ai][bj][m][1] + x1[m] * ALPHA;
;         }
	v_pk_fma_f32 v[96:97], v[100:101], s[14:15], v[96:97] op_sel_hi:[1,0,1]
	v_add_co_u32_e32 v100, vcc, s3, v142
	s_mov_b32 s5, 0x120000
	s_nop 0
	v_addc_co_u32_e32 v101, vcc, 0, v143, vcc
	v_pk_fma_f32 v[98:99], v[102:103], s[14:15], v[98:99] op_sel_hi:[1,0,1]
	v_add_co_u32_e32 v102, vcc, s5, v142
	v_lshl_add_u64 v[130:131], v[184:185], 0, s[12:13]
	v_pk_fma_f32 v[94:95], v[106:107], s[14:15], v[94:95] op_sel_hi:[1,0,1]
	v_pk_fma_f32 v[92:93], v[104:105], s[14:15], v[92:93] op_sel_hi:[1,0,1]
	v_addc_co_u32_e32 v103, vcc, 0, v143, vcc
	s_mov_b32 s12, 0x140000
	global_store_dwordx4 v[128:129], v[92:95], off offset:528
	v_pk_fma_f32 v[86:87], v[114:115], s[14:15], v[86:87] op_sel_hi:[1,0,1]
	v_pk_fma_f32 v[84:85], v[112:113], s[14:15], v[84:85] op_sel_hi:[1,0,1]
	v_lshl_add_u64 v[92:93], v[130:131], 0, v[190:191]
	v_add_co_u32_e32 v104, vcc, s12, v142
	global_store_dwordx4 v[92:93], v[84:87], off offset:16
	v_pk_fma_f32 v[78:79], v[122:123], s[14:15], v[78:79] op_sel_hi:[1,0,1]
	v_pk_fma_f32 v[76:77], v[120:121], s[14:15], v[76:77] op_sel_hi:[1,0,1]
	v_lshl_add_u64 v[84:85], v[130:131], 0, v[192:193]
	v_addc_co_u32_e32 v105, vcc, 0, v143, vcc
	s_mov_b32 s13, 0x160000
	v_pk_fma_f32 v[90:91], v[110:111], s[14:15], v[90:91] op_sel_hi:[1,0,1]
	v_pk_fma_f32 v[88:89], v[108:109], s[14:15], v[88:89] op_sel_hi:[1,0,1]
	v_pk_fma_f32 v[82:83], v[118:119], s[14:15], v[82:83] op_sel_hi:[1,0,1]
	v_pk_fma_f32 v[80:81], v[116:117], s[14:15], v[80:81] op_sel_hi:[1,0,1]
	global_store_dwordx4 v[84:85], v[76:79], off offset:16
	v_pk_fma_f32 v[74:75], v[126:127], s[14:15], v[74:75] op_sel_hi:[1,0,1]
	v_pk_fma_f32 v[72:73], v[124:125], s[14:15], v[72:73] op_sel_hi:[1,0,1]
	v_lshl_add_u64 v[76:77], v[130:131], 0, v[194:195]
	v_pk_fma_f32 v[70:71], v[150:151], s[14:15], v[70:71] op_sel_hi:[1,0,1]
	v_pk_fma_f32 v[68:69], v[148:149], s[14:15], v[68:69] op_sel_hi:[1,0,1]
	s_mov_b64 s[16:17], 0x100000
	s_mov_b64 s[18:19], 0x120000
	s_mov_b64 s[34:35], 0x140000
	s_mov_b64 s[36:37], 0x160000
	v_add_co_u32_e32 v106, vcc, s13, v142
	global_store_dwordx4 v[128:129], v[96:99], off offset:512
	global_store_dwordx4 v[92:93], v[88:91], off
	global_store_dwordx4 v[84:85], v[80:83], off
	global_store_dwordx4 v[76:77], v[72:75], off
	global_store_dwordx4 v[76:77], v[68:71], off offset:16
	v_lshl_add_u64 v[80:81], v[142:143], 0, s[18:19]
	v_lshl_add_u64 v[72:73], v[142:143], 0, s[16:17]
	v_lshl_add_u64 v[88:89], v[142:143], 0, s[34:35]
	v_lshl_add_u64 v[96:97], v[142:143], 0, s[36:37]
	v_addc_co_u32_e32 v107, vcc, 0, v143, vcc
	global_load_dwordx4 v[68:71], v[100:101], off
	s_nop 0
	global_load_dwordx4 v[72:75], v[72:73], off offset:16
	s_nop 0
	global_load_dwordx4 v[76:79], v[102:103], off
	s_nop 0
	global_load_dwordx4 v[80:83], v[80:81], off offset:16
	s_nop 0
	global_load_dwordx4 v[84:87], v[104:105], off
	s_nop 0
	global_load_dwordx4 v[88:91], v[88:89], off offset:16
	s_nop 0
	global_load_dwordx4 v[92:95], v[106:107], off
	s_nop 0
	global_load_dwordx4 v[96:99], v[96:97], off offset:16
	s_waitcnt vmcnt(0) lgkmcnt(0)
; #define PG8_WAIT_V(n) asm volatile("s_waitcnt vmcnt(" #n ")" ::: "memory")
; #define PG8_BAR __builtin_amdgcn_s_barrier()
; template <class Epi, class AddrA, class AddrB>
; __device__ __forceinline__ void gemm_phase(const Sched S, const int lda, const int ldb, const int K, const AddrA addrA,
;                                            const AddrB addrB, const Epi E) {
;     ...
;     if (!has_next) break;
;     if (!(Epi::KEEP && cur.br + 1 < S.nbr)) {
; #pragma unroll
;       for (int a = 0; a < 2; ++a)
; #pragma unroll
;         for (int b = 0; b < 2; ++b)
; #pragma unroll
;           for (int m = 0; m < 4; ++m)
; #pragma unroll
;             for (int n = 0; n < 2; ++n) acc[a][b][m][n] = (f32x4){0.f, 0.f, 0.f, 0.f};
;     }
;     cur = nxt; cA = nA; cB = nB; ++ui;
;   }
;   PG8_WAIT_V(0);
;   if (wr == 0) PG8_BAR;
;   PG8_BAR;
;   __device__ __forceinline__ void operator()(EPI_ARGS) const {
;     ...
;         f32x4 x0[4], x1[4];
; #pragma unroll
;         for (int m = 0; m < 4; ++m) {
;           const size_t o = (row0 + ai * HALF + m * 16) * DM + col0 + bj * HALF;
;           x0[m] = *(const f32x4*)(xres + o);
;           x1[m] = *(const f32x4*)(xres + o + 4);
;         }
;         __builtin_amdgcn_sched_barrier(0);
; #pragma unroll
;         for (int m = 0; m < 4; ++m) {
;           const size_t o = (row0 + ai * HALF + m * 16) * DM + col0 + bj * HALF;
;           *(f32x4*)(hbuf + o) = acc[ai][bj][m][0] + x0[m] * ALPHA;
;           *(f32x4*)(hbuf + o + 4) = acc[ai][bj][m][1] + x1[m] * ALPHA;
;         }
	v_pk_fma_f32 v[66:67], v[70:71], s[14:15], v[66:67] op_sel_hi:[1,0,1]
	v_add_co_u32_e32 v70, vcc, s3, v128
	v_pk_fma_f32 v[64:65], v[68:69], s[14:15], v[64:65] op_sel_hi:[1,0,1]
	v_lshl_add_u64 v[68:69], v[128:129], 0, s[16:17]
	v_addc_co_u32_e32 v71, vcc, 0, v129, vcc
	v_pk_fma_f32 v[62:63], v[74:75], s[14:15], v[62:63] op_sel_hi:[1,0,1]
	v_pk_fma_f32 v[60:61], v[72:73], s[14:15], v[60:61] op_sel_hi:[1,0,1]
	global_store_dwordx4 v[68:69], v[60:63], off offset:16
	v_add_co_u32_e32 v68, vcc, s5, v128
	s_nop 0
	v_lshl_add_u64 v[60:61], v[128:129], 0, s[18:19]
	v_addc_co_u32_e32 v69, vcc, 0, v129, vcc
	v_add_co_u32_e32 v72, vcc, s12, v128
	v_pk_fma_f32 v[54:55], v[82:83], s[14:15], v[54:55] op_sel_hi:[1,0,1]
	v_pk_fma_f32 v[52:53], v[80:81], s[14:15], v[52:53] op_sel_hi:[1,0,1]
	v_addc_co_u32_e32 v73, vcc, 0, v129, vcc
	global_store_dwordx4 v[60:61], v[52:55], off offset:16
	v_pk_fma_f32 v[46:47], v[90:91], s[14:15], v[46:47] op_sel_hi:[1,0,1]
	v_pk_fma_f32 v[44:45], v[88:89], s[14:15], v[44:45] op_sel_hi:[1,0,1]
	v_lshl_add_u64 v[52:53], v[128:129], 0, s[34:35]
	v_add_co_u32_e32 v74, vcc, s13, v128
	v_pk_fma_f32 v[58:59], v[78:79], s[14:15], v[58:59] op_sel_hi:[1,0,1]
	v_pk_fma_f32 v[56:57], v[76:77], s[14:15], v[56:57] op_sel_hi:[1,0,1]
	v_pk_fma_f32 v[50:51], v[86:87], s[14:15], v[50:51] op_sel_hi:[1,0,1]
	v_pk_fma_f32 v[48:49], v[84:85], s[14:15], v[48:49] op_sel_hi:[1,0,1]
	global_store_dwordx4 v[52:53], v[44:47], off offset:16
	v_pk_fma_f32 v[42:43], v[94:95], s[14:15], v[42:43] op_sel_hi:[1,0,1]
	v_pk_fma_f32 v[40:41], v[92:93], s[14:15], v[40:41] op_sel_hi:[1,0,1]
	v_lshl_add_u64 v[44:45], v[128:129], 0, s[36:37]
	v_addc_co_u32_e32 v75, vcc, 0, v129, vcc
	v_pk_fma_f32 v[38:39], v[98:99], s[14:15], v[38:39] op_sel_hi:[1,0,1]
	v_pk_fma_f32 v[36:37], v[96:97], s[14:15], v[36:37] op_sel_hi:[1,0,1]
	s_mov_b64 s[12:13], 0x100200
	s_mov_b64 s[16:17], 0x120200
	s_mov_b64 s[18:19], 0x140200
	s_mov_b64 s[34:35], 0x160200
	global_store_dwordx4 v[70:71], v[64:67], off
	global_store_dwordx4 v[68:69], v[56:59], off
	global_store_dwordx4 v[72:73], v[48:51], off
	global_store_dwordx4 v[74:75], v[40:43], off
	global_store_dwordx4 v[44:45], v[36:39], off offset:16
	v_lshl_add_u64 v[44:45], v[142:143], 0, s[12:13]
	v_lshl_add_u64 v[48:49], v[142:143], 0, s[16:17]
	v_lshl_add_u64 v[60:61], v[142:143], 0, s[18:19]
	v_lshl_add_u64 v[64:65], v[142:143], 0, s[34:35]
	global_load_dwordx4 v[36:39], v[100:101], off offset:512
	global_load_dwordx4 v[40:43], v[102:103], off offset:512
	s_nop 0
	global_load_dwordx4 v[44:47], v[44:45], off offset:16
	s_nop 0
	global_load_dwordx4 v[48:51], v[48:49], off offset:16
	s_nop 0
	global_load_dwordx4 v[52:55], v[104:105], off offset:512
	global_load_dwordx4 v[56:59], v[106:107], off offset:512
	s_nop 0
	global_load_dwordx4 v[60:63], v[60:61], off offset:16
	s_nop 0
	global_load_dwordx4 v[64:67], v[64:65], off offset:16
	s_waitcnt vmcnt(0) lgkmcnt(0)
	v_pk_fma_f32 v[32:33], v[36:37], s[14:15], v[32:33] op_sel_hi:[1,0,1]
	v_lshl_add_u64 v[36:37], v[128:129], 0, s[12:13]
	v_pk_fma_f32 v[30:31], v[46:47], s[14:15], v[30:31] op_sel_hi:[1,0,1]
	v_pk_fma_f32 v[28:29], v[44:45], s[14:15], v[28:29] op_sel_hi:[1,0,1]
	global_store_dwordx4 v[36:37], v[28:31], off offset:16
	v_pk_fma_f32 v[22:23], v[50:51], s[14:15], v[22:23] op_sel_hi:[1,0,1]
	v_pk_fma_f32 v[20:21], v[48:49], s[14:15], v[20:21] op_sel_hi:[1,0,1]
	v_lshl_add_u64 v[28:29], v[128:129], 0, s[16:17]
	global_store_dwordx4 v[28:29], v[20:23], off offset:16
	v_pk_fma_f32 v[14:15], v[62:63], s[14:15], v[14:15] op_sel_hi:[1,0,1]
	v_pk_fma_f32 v[12:13], v[60:61], s[14:15], v[12:13] op_sel_hi:[1,0,1]
	v_lshl_add_u64 v[20:21], v[128:129], 0, s[18:19]
	v_pk_fma_f32 v[34:35], v[38:39], s[14:15], v[34:35] op_sel_hi:[1,0,1]
	v_pk_fma_f32 v[26:27], v[42:43], s[14:15], v[26:27] op_sel_hi:[1,0,1]
	v_pk_fma_f32 v[24:25], v[40:41], s[14:15], v[24:25] op_sel_hi:[1,0,1]
	v_pk_fma_f32 v[18:19], v[54:55], s[14:15], v[18:19] op_sel_hi:[1,0,1]
	v_pk_fma_f32 v[16:17], v[52:53], s[14:15], v[16:17] op_sel_hi:[1,0,1]
	global_store_dwordx4 v[20:21], v[12:15], off offset:16
	v_pk_fma_f32 v[10:11], v[58:59], s[14:15], v[10:11] op_sel_hi:[1,0,1]
	v_pk_fma_f32 v[8:9], v[56:57], s[14:15], v[8:9] op_sel_hi:[1,0,1]
	v_lshl_add_u64 v[12:13], v[128:129], 0, s[34:35]
	v_pk_fma_f32 v[6:7], v[66:67], s[14:15], v[6:7] op_sel_hi:[1,0,1]
	v_pk_fma_f32 v[4:5], v[64:65], s[14:15], v[4:5] op_sel_hi:[1,0,1]
	s_and_b64 vcc, exec, s[6:7]
	s_mov_b32 s34, s4
	s_mov_b32 s12, s2
	s_mov_b64 s[14:15], s[10:11]
	s_mov_b64 s[16:17], s[8:9]
	global_store_dwordx4 v[70:71], v[32:35], off offset:512
	global_store_dwordx4 v[68:69], v[24:27], off offset:512
	global_store_dwordx4 v[72:73], v[16:19], off offset:512
	global_store_dwordx4 v[74:75], v[8:11], off offset:512
	global_store_dwordx4 v[12:13], v[4:7], off offset:16
	s_cbranch_vccz .LBB0_616
	s_waitcnt vmcnt(0)
	s_cmpk_gt_u32 s20, 0xff
	s_cbranch_scc1 .LBB0_623
	s_barrier

; __device__ __forceinline__ float wave_sum(float v) { return wave_last(wave_scan_add(v, 0)); }
; __device__ void phase_ln(const Params& p, int layer) {
;     ...
; #pragma unroll
;     for (int r = 0; r < 2; ++r) {
;       float sm = 0.f;
; #pragma unroll
;       for (int i = 0; i < 8; ++i) sm += (v[r][i][0] + v[r][i][1]) + (v[r][i][2] + v[r][i][3]);
;       sm = wave_sum(sm);
;       const float mu = sm * (1.0f / DM);
;       float ss = 0.f;
; #pragma unroll
;       for (int i = 0; i < 8; ++i) {
;         v[r][i] -= mu;
;         ss += (v[r][i][0] * v[r][i][0] + v[r][i][1] * v[r][i][1]) + (v[r][i][2] * v[r][i][2] + v[r][i][3] * v[r][i][3]);
;       }
;       ss = wave_sum(ss);
;       const float rs = rsqrtf(ss * (1.0f / DM) + EPS);
; #pragma unroll
;       for (int i = 0; i < 8; ++i) {
;         const int c = i * 256 + lane * 4;
;         const f32x4 g4 = *(const f32x4*)(gg + c), b4 = *(const f32x4*)(bb + c);
;         f32x4 y = v[r][i] * rs * g4 + b4;
;         *(f32x4*)(of + (row + r) * DM + c) = y;
;         if (layer == 0) *(u32x2*)(xb + (row + r) * DM + c) = pack4(y);
;       }
.LBB0_675:
	v_mov_b32_e32 v132, v124
	v_mov_b32_e32 v133, v128
	v_mov_b32_e32 v134, v125
	v_mov_b32_e32 v135, v129
	v_pk_add_f32 v[132:133], v[132:133], v[134:135]
	v_mov_b32_e32 v134, v126
	v_mov_b32_e32 v135, v130
	v_mov_b32_e32 v136, v127
	v_mov_b32_e32 v137, v131
	v_pk_add_f32 v[134:135], v[134:135], v[136:137]
	v_mov_b32_e32 v136, v120
	v_pk_add_f32 v[132:133], v[132:133], v[134:135]
	v_mov_b32_e32 v134, v121
	v_mov_b32_e32 v135, v122
	v_mov_b32_e32 v137, v123
	v_pk_add_f32 v[134:135], v[134:135], v[136:137]
	v_add_f32_e32 v133, 0, v133
	v_pk_add_f32 v[134:135], v[134:135], v[134:135] op_sel_hi:[0,1]
	v_add_f32_e32 v133, v132, v133
	v_add_f32_e32 v137, v116, v117
	v_add_f32_e32 v163, v118, v119
	v_mov_b32_e32 v136, v112
	v_mov_b32_e32 v162, v113
	v_mov_b32_e32 v134, v114
	v_mov_b32_e32 v132, v115
	v_pk_add_f32 v[136:137], v[136:137], v[162:163]
	v_pk_add_f32 v[132:133], v[134:135], v[132:133]
	v_mov_b32_e32 v134, v109
	v_pk_add_f32 v[132:133], v[136:137], v[132:133]
	v_mov_b32_e32 v135, v110
	v_mov_b32_e32 v136, v108
	v_mov_b32_e32 v137, v111
	v_pk_add_f32 v[134:135], v[134:135], v[136:137]
	v_pk_add_f32 v[132:133], v[132:133], v[132:133] op_sel_hi:[0,1]
	v_pk_add_f32 v[134:135], v[134:135], v[134:135] op_sel_hi:[0,1]
	v_add_f32_e32 v137, v104, v105
	v_add_f32_e32 v163, v106, v107
	v_mov_b32_e32 v136, v100
	v_mov_b32_e32 v162, v101
	v_mov_b32_e32 v134, v102
	v_mov_b32_e32 v132, v103
	v_pk_add_f32 v[136:137], v[136:137], v[162:163]
	v_pk_add_f32 v[132:133], v[134:135], v[132:133]
	s_nop 0
	v_pk_add_f32 v[132:133], v[136:137], v[132:133]
	s_nop 0
	v_add_f32_e32 v132, v132, v133
	v_mov_b32_e32 v133, v3
	s_nop 0
	v_add_f32_dpp v132, v132, v132 row_shr:1 row_mask:0xf bank_mask:0xf bound_ctrl:1
	s_nop 1
	v_add_f32_dpp v132, v132, v132 row_shr:2 row_mask:0xf bank_mask:0xf bound_ctrl:1
	s_nop 1
	v_add_f32_dpp v132, v132, v132 row_shr:4 row_mask:0xf bank_mask:0xf bound_ctrl:1
	s_nop 1
	v_add_f32_dpp v132, v132, v132 row_shr:8 row_mask:0xf bank_mask:0xf bound_ctrl:1
	s_nop 1
	v_mov_b32_dpp v133, v132 row_bcast:15 row_mask:0xa bank_mask:0xf
	v_add_f32_e32 v132, v132, v133
	v_mov_b32_e32 v133, v3
	s_nop 1
	v_mov_b32_dpp v133, v132 row_bcast:31 row_mask:0xc bank_mask:0xf
	v_add_f32_e32 v132, v132, v133
	s_nop 0
	v_readlane_b32 s2, v132, 63
	s_nop 1
	v_fma_f32 v129, s2, v210, v129
	v_fma_f32 v125, s2, v210, v125
	v_fma_f32 v181, s2, v210, v131
	v_fma_f32 v180, s2, v210, v130
	v_fmac_f32_e32 v128, s2, v210
	v_fmac_f32_e32 v124, s2, v210
	v_mov_b32_e32 v130, v129
	v_mov_b32_e32 v131, v125
	v_fma_f32 v177, s2, v210, v127
	v_fma_f32 v179, s2, v210, v126
	v_mov_b32_e32 v126, v128
	v_mov_b32_e32 v127, v124
	v_pk_mul_f32 v[130:131], v[130:131], v[130:131]
	v_mov_b32_e32 v176, v181
	v_pk_fma_f32 v[126:127], v[126:127], v[126:127], v[130:131]
	v_mov_b32_e32 v178, v180
	v_pk_mul_f32 v[130:131], v[176:177], v[176:177]
	v_fmac_f32_e32 v116, s2, v210
	v_pk_fma_f32 v[130:131], v[178:179], v[178:179], v[130:131]
	v_fma_f32 v175, s2, v210, v123
	v_fma_f32 v174, s2, v210, v122
	v_fma_f32 v121, s2, v210, v121
	v_fmac_f32_e32 v120, s2, v210
	v_fma_f32 v172, s2, v210, v118
	v_fma_f32 v117, s2, v210, v117
	v_mul_f32_e32 v118, v116, v116
	v_pk_add_f32 v[126:127], v[126:127], v[130:131]
	v_pk_mul_f32 v[122:123], v[174:175], v[174:175]
	v_pk_mul_f32 v[130:131], v[120:121], v[120:121]
	v_fma_f32 v173, s2, v210, v119
	v_pk_fma_f32 v[118:119], v[116:117], v[116:117], v[118:119] op_sel_hi:[1,1,0]
	v_pk_mov_b32 v[132:133], v[130:131], v[122:123] op_sel:[1,0]
	v_mov_b32_e32 v131, v123
	v_mul_f32_e32 v118, v172, v172
	v_pk_add_f32 v[122:123], v[132:133], v[130:131]
	v_pk_fma_f32 v[130:131], v[172:173], v[172:173], v[118:119] op_sel_hi:[1,1,0]
	v_fma_f32 v113, s2, v210, v113
	v_fmac_f32_e32 v112, s2, v210
	v_mul_f32_e32 v118, v112, v112
	v_mul_f32_e32 v130, v113, v113
	v_fma_f32 v171, s2, v210, v115
	v_fma_f32 v170, s2, v210, v114
	v_pk_add_f32 v[114:115], v[118:119], v[130:131]
	global_load_dwordx4 v[130:133], v[146:147], off
	global_load_dwordx4 v[134:137], v[0:1], off
	v_pk_add_f32 v[126:127], v[126:127], v[126:127] op_sel_hi:[0,1]
	v_pk_add_f32 v[122:123], v[122:123], v[122:123] op_sel_hi:[0,1]
	v_mul_f32_e32 v122, v170, v170
	v_mul_f32_e32 v126, v171, v171
	v_pk_add_f32 v[118:119], v[122:123], v[126:127]
	v_fma_f32 v169, s2, v210, v111
	v_fma_f32 v168, s2, v210, v110
	v_fma_f32 v109, s2, v210, v109
	v_fmac_f32_e32 v108, s2, v210
	v_fmac_f32_e32 v104, s2, v210
	v_pk_add_f32 v[114:115], v[114:115], v[118:119]
	v_pk_mul_f32 v[110:111], v[168:169], v[168:169]
	v_pk_mul_f32 v[118:119], v[108:109], v[108:109]
	v_fma_f32 v162, s2, v210, v106
	v_fma_f32 v105, s2, v210, v105
	v_mul_f32_e32 v106, v104, v104
	v_pk_mov_b32 v[122:123], v[118:119], v[110:111] op_sel:[1,0]
	v_mov_b32_e32 v119, v111
	v_fma_f32 v163, s2, v210, v107
	v_pk_fma_f32 v[106:107], v[104:105], v[104:105], v[106:107] op_sel_hi:[1,1,0]
	v_pk_add_f32 v[110:111], v[122:123], v[118:119]
	v_mul_f32_e32 v106, v162, v162
	v_pk_add_f32 v[114:115], v[114:115], v[114:115] op_sel_hi:[0,1]
	v_pk_add_f32 v[110:111], v[110:111], v[110:111] op_sel_hi:[0,1]
	v_pk_fma_f32 v[122:123], v[162:163], v[162:163], v[106:107] op_sel_hi:[1,1,0]
	v_fma_f32 v119, s2, v210, v103
	v_fma_f32 v118, s2, v210, v102
	v_fma_f32 v101, s2, v210, v101
	v_fmac_f32_e32 v100, s2, v210
	v_mul_f32_e32 v106, v100, v100
	v_mul_f32_e32 v122, v101, v101
	v_mul_f32_e32 v110, v118, v118
	v_mul_f32_e32 v114, v119, v119
	v_pk_add_f32 v[102:103], v[106:107], v[122:123]
	v_pk_add_f32 v[106:107], v[110:111], v[114:115]
	s_nop 0
	v_pk_add_f32 v[102:103], v[102:103], v[106:107]
	s_nop 0
	v_add_f32_e32 v102, v102, v103
	v_mov_b32_e32 v103, v3
	s_nop 0
	v_add_f32_dpp v102, v102, v102 row_shr:1 row_mask:0xf bank_mask:0xf bound_ctrl:1
	s_nop 1
	v_add_f32_dpp v102, v102, v102 row_shr:2 row_mask:0xf bank_mask:0xf bound_ctrl:1
	s_nop 1
	v_add_f32_dpp v102, v102, v102 row_shr:4 row_mask:0xf bank_mask:0xf bound_ctrl:1
	s_nop 1
	v_add_f32_dpp v102, v102, v102 row_shr:8 row_mask:0xf bank_mask:0xf bound_ctrl:1
	s_nop 1
	v_mov_b32_dpp v103, v102 row_bcast:15 row_mask:0xa bank_mask:0xf
	v_add_f32_e32 v102, v102, v103
	v_mov_b32_e32 v103, v3
	s_nop 1
	v_mov_b32_dpp v103, v102 row_bcast:31 row_mask:0xc bank_mask:0xf
	v_add_f32_e32 v102, v102, v103
	s_nop 0
	v_readlane_b32 s2, v102, 63
	s_nop 1
	v_fma_f32 v102, s2, v211, v201
	v_cmp_gt_f32_e32 vcc, s43, v102
	v_mul_f32_e32 v103, 0x4b800000, v102
	s_mov_b64 s[2:3], -1
	v_cndmask_b32_e32 v102, v102, v103, vcc
	v_rsq_f32_e32 v102, v102
	s_nop 0
	v_mul_f32_e32 v103, 0x45800000, v102
	v_cndmask_b32_e32 v122, v102, v103, vcc
	v_mov_b32_e32 v123, v122
	v_pk_mul_f32 v[102:103], v[128:129], v[122:123] op_sel_hi:[1,0]
	v_pk_mul_f32 v[106:107], v[180:181], v[122:123] op_sel_hi:[1,0]
	s_and_b64 vcc, exec, s[40:41]
	s_waitcnt vmcnt(0)
	v_pk_fma_f32 v[128:129], v[132:133], v[106:107], v[136:137]
	v_pk_fma_f32 v[126:127], v[130:131], v[102:103], v[134:135]
	v_lshl_add_u64 v[106:107], v[158:159], 0, v[2:3]
	v_pk_mul_f32 v[102:103], v[124:125], v[122:123]
	global_store_dwordx4 v[106:107], v[126:129], off
	s_cbranch_vccz .LBB0_677
; __device__ void phase_ln(const Params& p, int layer) {
;     ...
; #pragma unroll
;       for (int i = 0; i < 8; ++i) {
;         const int c = i * 256 + lane * 4;
;         const f32x4 g4 = *(const f32x4*)(gg + c), b4 = *(const f32x4*)(bb + c);
;         f32x4 y = v[r][i] * rs * g4 + b4;
;         *(f32x4*)(of + (row + r) * DM + c) = y;
;         if (layer == 0) *(u32x2*)(xb + (row + r) * DM + c) = pack4(y);
;       }
	global_load_dwordx4 v[130:133], v[146:147], off offset:1024
	global_load_dwordx4 v[134:137], v[0:1], off offset:1024
	v_mov_b32_e32 v110, v122
	v_mov_b32_e32 v111, v122
	v_mov_b32_e32 v176, v179
	v_pk_mul_f32 v[110:111], v[176:177], v[110:111]
	s_mov_b64 s[2:3], 0
	s_waitcnt vmcnt(0)
	v_pk_fma_f32 v[132:133], v[110:111], v[132:133], v[136:137]
	v_pk_fma_f32 v[130:131], v[102:103], v[130:131], v[134:135]
	global_store_dwordx4 v[106:107], v[130:133], off offset:1024
.LBB0_677:
	s_andn2_b64 vcc, exec, s[2:3]
	s_cbranch_vccnz .LBB0_679
	v_cvt_pk_bf16_f32 v110, v126, v127
	v_cvt_pk_bf16_f32 v111, v128, v129
	global_store_dwordx2 v[160:161], v[110:111], off
	global_load_dwordx4 v[124:127], v[146:147], off offset:1024
	global_load_dwordx4 v[128:131], v[0:1], off offset:1024
	v_mov_b32_e32 v110, v122
	v_mov_b32_e32 v111, v122
	v_mov_b32_e32 v176, v179
	v_pk_mul_f32 v[110:111], v[176:177], v[110:111]
	s_waitcnt vmcnt(0)
	v_pk_fma_f32 v[124:125], v[102:103], v[124:125], v[128:129]
	v_pk_fma_f32 v[126:127], v[110:111], v[126:127], v[130:131]
	global_store_dwordx4 v[106:107], v[124:127], off offset:1024
	v_cvt_pk_bf16_f32 v102, v124, v125
	v_cvt_pk_bf16_f32 v103, v126, v127
	global_store_dwordx2 v[160:161], v[102:103], off offset:512
.LBB0_679:
	global_load_dwordx4 v[124:127], v[146:147], off offset:2048
	global_load_dwordx4 v[128:131], v[0:1], off offset:2048
	v_mov_b32_e32 v110, v122
	v_mov_b32_e32 v111, v122
	v_pk_mul_f32 v[114:115], v[120:121], v[122:123]
	v_pk_mul_f32 v[102:103], v[116:117], v[122:123]
	v_pk_mul_f32 v[116:117], v[174:175], v[110:111]
	s_mov_b64 s[2:3], -1
	s_and_b64 vcc, exec, s[40:41]
	s_waitcnt vmcnt(0)
	v_pk_fma_f32 v[116:117], v[116:117], v[126:127], v[130:131]
	v_pk_fma_f32 v[114:115], v[114:115], v[124:125], v[128:129]
	global_store_dwordx4 v[106:107], v[114:117], off offset:2048
	s_cbranch_vccz .LBB0_681
	global_load_dwordx4 v[124:127], v[146:147], off offset:3072
	global_load_dwordx4 v[128:131], v[0:1], off offset:3072
	v_pk_mul_f32 v[110:111], v[172:173], v[110:111]
	s_mov_b64 s[2:3], 0
	s_waitcnt vmcnt(0)
	v_pk_fma_f32 v[126:127], v[110:111], v[126:127], v[130:131]
	v_pk_fma_f32 v[124:125], v[102:103], v[124:125], v[128:129]
	global_store_dwordx4 v[106:107], v[124:127], off offset:3072
.LBB0_681:
	s_andn2_b64 vcc, exec, s[2:3]
	s_cbranch_vccnz .LBB0_683
	v_cvt_pk_bf16_f32 v110, v114, v115
	v_cvt_pk_bf16_f32 v111, v116, v117
	global_store_dwordx2 v[160:161], v[110:111], off offset:1024
	global_load_dwordx4 v[114:117], v[146:147], off offset:3072
	global_load_dwordx4 v[124:127], v[0:1], off offset:3072
	v_mov_b32_e32 v110, v122
	v_mov_b32_e32 v111, v122
	v_pk_mul_f32 v[110:111], v[172:173], v[110:111]
	s_waitcnt vmcnt(0)
	v_pk_fma_f32 v[114:115], v[102:103], v[114:115], v[124:125]
	v_pk_fma_f32 v[116:117], v[110:111], v[116:117], v[126:127]
	global_store_dwordx4 v[106:107], v[114:117], off offset:3072
	v_cvt_pk_bf16_f32 v102, v114, v115
	v_cvt_pk_bf16_f32 v103, v116, v117
	global_store_dwordx2 v[160:161], v[102:103], off offset:1536
.LBB0_683:
	global_load_dwordx4 v[124:127], v[148:149], off
	global_load_dwordx4 v[128:131], v[138:139], off
	v_mov_b32_e32 v114, v122
	v_mov_b32_e32 v115, v122
	v_pk_mul_f32 v[102:103], v[170:171], v[114:115]
	v_pk_mul_f32 v[110:111], v[112:113], v[122:123]
	s_mov_b64 s[2:3], -1
	s_waitcnt vmcnt(0)
	v_pk_fma_f32 v[112:113], v[102:103], v[126:127], v[130:131]
	v_add_co_u32_e32 v102, vcc, 0x1000, v106
	v_pk_fma_f32 v[110:111], v[110:111], v[124:125], v[128:129]
	s_nop 0
	v_addc_co_u32_e32 v103, vcc, 0, v107, vcc
	global_store_dwordx4 v[102:103], v[110:113], off
	s_and_b64 vcc, exec, s[40:41]
	v_pk_mul_f32 v[102:103], v[108:109], v[122:123]
	s_cbranch_vccz .LBB0_685
	global_load_dwordx4 v[124:127], v[150:151], off
	global_load_dwordx4 v[128:131], v[140:141], off
	v_pk_mul_f32 v[108:109], v[168:169], v[114:115]
	s_mov_b64 s[2:3], 0
	s_waitcnt vmcnt(0)
	v_pk_fma_f32 v[116:117], v[108:109], v[126:127], v[130:131]
	v_add_co_u32_e32 v108, vcc, 0x1000, v106
	v_pk_fma_f32 v[114:115], v[102:103], v[124:125], v[128:129]
	s_nop 0
	v_addc_co_u32_e32 v109, vcc, 0, v107, vcc
	global_store_dwordx4 v[108:109], v[114:117], off offset:1024
.LBB0_685:
	s_andn2_b64 vcc, exec, s[2:3]
	s_cbranch_vccnz .LBB0_687
	v_cvt_pk_bf16_f32 v108, v110, v111
	v_cvt_pk_bf16_f32 v109, v112, v113
	global_store_dwordx2 v[160:161], v[108:109], off offset:2048
	global_load_dwordx4 v[108:111], v[150:151], off
	s_nop 0
	global_load_dwordx4 v[112:115], v[140:141], off
	v_mov_b32_e32 v116, v122
	v_mov_b32_e32 v117, v122
	v_pk_mul_f32 v[116:117], v[168:169], v[116:117]
	s_waitcnt vmcnt(0)
	v_pk_fma_f32 v[108:109], v[102:103], v[108:109], v[112:113]
	v_add_co_u32_e32 v102, vcc, 0x1000, v106
	v_pk_fma_f32 v[110:111], v[116:117], v[110:111], v[114:115]
	s_nop 0
	v_addc_co_u32_e32 v103, vcc, 0, v107, vcc
	global_store_dwordx4 v[102:103], v[108:111], off offset:1024
	v_cvt_pk_bf16_f32 v102, v108, v109
	v_cvt_pk_bf16_f32 v103, v110, v111
	global_store_dwordx2 v[160:161], v[102:103], off offset:2560
.LBB0_687:
	global_load_dwordx4 v[110:113], v[152:153], off
	global_load_dwordx4 v[114:117], v[142:143], off
	v_mov_b32_e32 v108, v122
	v_mov_b32_e32 v109, v122
	v_pk_mul_f32 v[102:103], v[162:163], v[108:109]
	v_pk_mul_f32 v[120:121], v[104:105], v[122:123]
	s_mov_b64 s[2:3], -1
	v_pk_mul_f32 v[100:101], v[100:101], v[122:123]
	s_waitcnt vmcnt(0)
	v_pk_fma_f32 v[104:105], v[102:103], v[112:113], v[116:117]
	v_pk_fma_f32 v[102:103], v[120:121], v[110:111], v[114:115]
	v_add_co_u32_e32 v110, vcc, 0x1000, v106
	s_nop 1
	v_addc_co_u32_e32 v111, vcc, 0, v107, vcc
	s_and_b64 vcc, exec, s[40:41]
	global_store_dwordx4 v[110:111], v[102:105], off offset:2048
	s_cbranch_vccz .LBB0_689
	global_load_dwordx4 v[110:113], v[154:155], off
	global_load_dwordx4 v[114:117], v[156:157], off
	v_pk_mul_f32 v[108:109], v[118:119], v[108:109]
	s_mov_b64 s[2:3], 0
	s_waitcnt vmcnt(0)
	v_pk_fma_f32 v[112:113], v[108:109], v[112:113], v[116:117]
	v_add_co_u32_e32 v108, vcc, 0x1000, v106
	v_pk_fma_f32 v[110:111], v[100:101], v[110:111], v[114:115]
	s_nop 0
	v_addc_co_u32_e32 v109, vcc, 0, v107, vcc
	global_store_dwordx4 v[108:109], v[110:113], off offset:3072
; __device__ __forceinline__ float wave_sum(float v) { return wave_last(wave_scan_add(v, 0)); }
; __device__ void phase_ln(const Params& p, int layer) {
;     ...
;     for (int r = 0; r < 2; ++r) {
;       float sm = 0.f;
; #pragma unroll
;       for (int i = 0; i < 8; ++i) sm += (v[r][i][0] + v[r][i][1]) + (v[r][i][2] + v[r][i][3]);
;       sm = wave_sum(sm);
;       const float mu = sm * (1.0f / DM);
;       float ss = 0.f;
; #pragma unroll
;       for (int i = 0; i < 8; ++i) {
;         v[r][i] -= mu;
;         ss += (v[r][i][0] * v[r][i][0] + v[r][i][1] * v[r][i][1]) + (v[r][i][2] * v[r][i][2] + v[r][i][3] * v[r][i][3]);
;       }
;       ss = wave_sum(ss);
;       const float rs = rsqrtf(ss * (1.0f / DM) + EPS);
; #pragma unroll
;       for (int i = 0; i < 8; ++i) {
;         const int c = i * 256 + lane * 4;
;         const f32x4 g4 = *(const f32x4*)(gg + c), b4 = *(const f32x4*)(bb + c);
;         f32x4 y = v[r][i] * rs * g4 + b4;
;         *(f32x4*)(of + (row + r) * DM + c) = y;
;         if (layer == 0) *(u32x2*)(xb + (row + r) * DM + c) = pack4(y);
;       }
.LBB0_689:
	s_andn2_b64 vcc, exec, s[2:3]
	s_cbranch_vccnz .LBB0_691
	v_cvt_pk_bf16_f32 v102, v102, v103
	v_cvt_pk_bf16_f32 v103, v104, v105
	global_store_dwordx2 v[160:161], v[102:103], off offset:3072
	global_load_dwordx4 v[102:105], v[154:155], off
	s_nop 0
	global_load_dwordx4 v[108:111], v[156:157], off
	v_mov_b32_e32 v123, v122
	v_pk_mul_f32 v[112:113], v[118:119], v[122:123]
	s_waitcnt vmcnt(0)
	v_pk_fma_f32 v[102:103], v[100:101], v[102:103], v[108:109]
	v_add_co_u32_e32 v100, vcc, 0x1000, v106
	v_pk_fma_f32 v[104:105], v[112:113], v[104:105], v[110:111]
	s_nop 0
	v_addc_co_u32_e32 v101, vcc, 0, v107, vcc
	global_store_dwordx4 v[100:101], v[102:105], off offset:3072
	v_cvt_pk_bf16_f32 v100, v102, v103
	v_cvt_pk_bf16_f32 v101, v104, v105
	global_store_dwordx2 v[160:161], v[100:101], off offset:3584
.LBB0_691:
	v_mov_b32_e32 v100, v92
	v_mov_b32_e32 v101, v96
	v_mov_b32_e32 v102, v93
	v_mov_b32_e32 v103, v97
	v_pk_add_f32 v[100:101], v[100:101], v[102:103]
	v_mov_b32_e32 v102, v94
	v_mov_b32_e32 v103, v98
	v_mov_b32_e32 v104, v95
	v_mov_b32_e32 v105, v99
	v_pk_add_f32 v[102:103], v[102:103], v[104:105]
	v_mov_b32_e32 v104, v88
	v_pk_add_f32 v[100:101], v[100:101], v[102:103]
	v_mov_b32_e32 v102, v89
	v_mov_b32_e32 v103, v90
	v_mov_b32_e32 v105, v91
	v_pk_add_f32 v[102:103], v[102:103], v[104:105]
	v_add_f32_e32 v101, 0, v101
	v_pk_add_f32 v[102:103], v[102:103], v[102:103] op_sel_hi:[0,1]
	v_add_f32_e32 v101, v100, v101
	v_add_f32_e32 v105, v84, v85
	v_add_f32_e32 v109, v86, v87
	v_mov_b32_e32 v104, v80
	v_mov_b32_e32 v108, v81
	v_mov_b32_e32 v102, v82
	v_mov_b32_e32 v100, v83
	v_pk_add_f32 v[104:105], v[104:105], v[108:109]
	v_pk_add_f32 v[100:101], v[102:103], v[100:101]
	v_mov_b32_e32 v102, v77
	v_pk_add_f32 v[100:101], v[104:105], v[100:101]
	v_mov_b32_e32 v103, v78
	v_mov_b32_e32 v104, v76
	v_mov_b32_e32 v105, v79
	v_pk_add_f32 v[102:103], v[102:103], v[104:105]
	v_pk_add_f32 v[100:101], v[100:101], v[100:101] op_sel_hi:[0,1]
	v_pk_add_f32 v[102:103], v[102:103], v[102:103] op_sel_hi:[0,1]
	v_add_f32_e32 v105, v72, v73
	v_add_f32_e32 v109, v74, v75
	v_mov_b32_e32 v104, v16
	v_mov_b32_e32 v108, v17
	v_mov_b32_e32 v102, v18
	v_mov_b32_e32 v100, v19
	v_pk_add_f32 v[104:105], v[104:105], v[108:109]
	v_pk_add_f32 v[100:101], v[102:103], v[100:101]
	s_nop 0
	v_pk_add_f32 v[100:101], v[104:105], v[100:101]
	s_nop 0
	v_add_f32_e32 v100, v100, v101
	v_mov_b32_e32 v101, v3
	s_nop 0
	v_add_f32_dpp v100, v100, v100 row_shr:1 row_mask:0xf bank_mask:0xf bound_ctrl:1
	s_nop 1
	v_add_f32_dpp v100, v100, v100 row_shr:2 row_mask:0xf bank_mask:0xf bound_ctrl:1
	s_nop 1
	v_add_f32_dpp v100, v100, v100 row_shr:4 row_mask:0xf bank_mask:0xf bound_ctrl:1
	s_nop 1
	v_add_f32_dpp v100, v100, v100 row_shr:8 row_mask:0xf bank_mask:0xf bound_ctrl:1
	s_nop 1
	v_mov_b32_dpp v101, v100 row_bcast:15 row_mask:0xa bank_mask:0xf
	v_add_f32_e32 v100, v100, v101
	v_mov_b32_e32 v101, v3
	s_nop 1
	v_mov_b32_dpp v101, v100 row_bcast:31 row_mask:0xc bank_mask:0xf
	v_add_f32_e32 v100, v100, v101
	s_nop 0
	v_readlane_b32 s2, v100, 63
	s_nop 1
	v_fma_f32 v97, s2, v210, v97
	v_fma_f32 v93, s2, v210, v93
	v_fma_f32 v119, s2, v210, v99
	v_fma_f32 v118, s2, v210, v98
	v_fmac_f32_e32 v96, s2, v210
	v_fmac_f32_e32 v92, s2, v210
	v_mov_b32_e32 v98, v97
	v_mov_b32_e32 v99, v93
	v_fma_f32 v115, s2, v210, v95
	v_fma_f32 v117, s2, v210, v94
	v_mov_b32_e32 v94, v96
	v_mov_b32_e32 v95, v92
	v_pk_mul_f32 v[98:99], v[98:99], v[98:99]
	v_mov_b32_e32 v114, v119
	v_pk_fma_f32 v[94:95], v[94:95], v[94:95], v[98:99]
	v_mov_b32_e32 v116, v118
	v_pk_mul_f32 v[98:99], v[114:115], v[114:115]
	v_fmac_f32_e32 v84, s2, v210
	v_pk_fma_f32 v[98:99], v[116:117], v[116:117], v[98:99]
	v_fma_f32 v113, s2, v210, v91
	v_fma_f32 v112, s2, v210, v90
	v_fma_f32 v89, s2, v210, v89
	v_fmac_f32_e32 v88, s2, v210
	v_fma_f32 v110, s2, v210, v86
	v_fma_f32 v85, s2, v210, v85
	v_mul_f32_e32 v86, v84, v84
	v_pk_add_f32 v[94:95], v[94:95], v[98:99]
	v_pk_mul_f32 v[90:91], v[112:113], v[112:113]
	v_pk_mul_f32 v[98:99], v[88:89], v[88:89]
	v_fma_f32 v111, s2, v210, v87
	v_pk_fma_f32 v[86:87], v[84:85], v[84:85], v[86:87] op_sel_hi:[1,1,0]
	v_pk_mov_b32 v[100:101], v[98:99], v[90:91] op_sel:[1,0]
	v_mov_b32_e32 v99, v91
	v_mul_f32_e32 v86, v110, v110
	v_pk_add_f32 v[90:91], v[100:101], v[98:99]
	v_pk_fma_f32 v[98:99], v[110:111], v[110:111], v[86:87] op_sel_hi:[1,1,0]
	v_fma_f32 v81, s2, v210, v81
	v_fmac_f32_e32 v80, s2, v210
	v_mul_f32_e32 v86, v80, v80
	v_mul_f32_e32 v98, v81, v81
	v_fma_f32 v109, s2, v210, v83
	v_fma_f32 v108, s2, v210, v82
	v_pk_add_f32 v[82:83], v[86:87], v[98:99]
	global_load_dwordx4 v[98:101], v[146:147], off
	global_load_dwordx4 v[102:105], v[0:1], off
	v_pk_add_f32 v[94:95], v[94:95], v[94:95] op_sel_hi:[0,1]
	v_pk_add_f32 v[90:91], v[90:91], v[90:91] op_sel_hi:[0,1]
	v_mul_f32_e32 v90, v108, v108
	v_mul_f32_e32 v94, v109, v109
	v_pk_add_f32 v[86:87], v[90:91], v[94:95]
	v_fma_f32 v91, s2, v210, v79
	v_fma_f32 v90, s2, v210, v78
	v_fma_f32 v77, s2, v210, v77
	v_fmac_f32_e32 v76, s2, v210
	v_pk_add_f32 v[82:83], v[82:83], v[86:87]
	v_pk_mul_f32 v[78:79], v[90:91], v[90:91]
	v_pk_mul_f32 v[86:87], v[76:77], v[76:77]
	v_fmac_f32_e32 v72, s2, v210
	v_pk_mov_b32 v[94:95], v[86:87], v[78:79] op_sel:[1,0]
	v_mov_b32_e32 v87, v79
	v_pk_add_f32 v[78:79], v[94:95], v[86:87]
	v_fma_f32 v74, s2, v210, v74
	v_pk_add_f32 v[78:79], v[78:79], v[78:79] op_sel_hi:[0,1]
	v_fma_f32 v73, s2, v210, v73
	v_mul_f32_e32 v78, v72, v72
	v_fma_f32 v75, s2, v210, v75
	v_pk_fma_f32 v[86:87], v[72:73], v[72:73], v[78:79] op_sel_hi:[1,1,0]
	v_mul_f32_e32 v78, v74, v74
	v_pk_add_f32 v[82:83], v[82:83], v[82:83] op_sel_hi:[0,1]
; __device__ __forceinline__ float wave_sum(float v) { return wave_last(wave_scan_add(v, 0)); }
; __device__ void phase_ln(const Params& p, int layer) {
;     ...
;       ss = wave_sum(ss);
;       const float rs = rsqrtf(ss * (1.0f / DM) + EPS);
; #pragma unroll
;       for (int i = 0; i < 8; ++i) {
;         const int c = i * 256 + lane * 4;
;         const f32x4 g4 = *(const f32x4*)(gg + c), b4 = *(const f32x4*)(bb + c);
;         f32x4 y = v[r][i] * rs * g4 + b4;
;         *(f32x4*)(of + (row + r) * DM + c) = y;
;         if (layer == 0) *(u32x2*)(xb + (row + r) * DM + c) = pack4(y);
;       }
	v_pk_fma_f32 v[94:95], v[74:75], v[74:75], v[78:79] op_sel_hi:[1,1,0]
	v_fma_f32 v19, s2, v210, v19
	v_fma_f32 v18, s2, v210, v18
	v_fma_f32 v17, s2, v210, v17
	v_fmac_f32_e32 v16, s2, v210
	v_mul_f32_e32 v86, v16, v16
	v_mul_f32_e32 v94, v17, v17
	v_mul_f32_e32 v78, v18, v18
	v_mul_f32_e32 v82, v19, v19
	v_pk_add_f32 v[86:87], v[86:87], v[94:95]
	v_pk_add_f32 v[78:79], v[78:79], v[82:83]
	s_nop 0
	v_pk_add_f32 v[78:79], v[86:87], v[78:79]
	s_nop 0
	v_add_f32_e32 v78, v78, v79
	v_mov_b32_e32 v79, v3
	s_nop 0
	v_add_f32_dpp v78, v78, v78 row_shr:1 row_mask:0xf bank_mask:0xf bound_ctrl:1
	s_nop 1
	v_add_f32_dpp v78, v78, v78 row_shr:2 row_mask:0xf bank_mask:0xf bound_ctrl:1
	s_nop 1
	v_add_f32_dpp v78, v78, v78 row_shr:4 row_mask:0xf bank_mask:0xf bound_ctrl:1
	s_nop 1
	v_add_f32_dpp v78, v78, v78 row_shr:8 row_mask:0xf bank_mask:0xf bound_ctrl:1
	s_nop 1
	v_mov_b32_dpp v79, v78 row_bcast:15 row_mask:0xa bank_mask:0xf
	v_add_f32_e32 v78, v78, v79
	v_mov_b32_e32 v79, v3
	s_nop 1
	v_mov_b32_dpp v79, v78 row_bcast:31 row_mask:0xc bank_mask:0xf
	v_add_f32_e32 v78, v78, v79
	s_nop 0
	v_readlane_b32 s2, v78, 63
	s_nop 1
	v_fma_f32 v78, s2, v211, v201
	v_cmp_gt_f32_e32 vcc, s43, v78
	v_mul_f32_e32 v79, 0x4b800000, v78
	s_mov_b64 s[2:3], -1
	v_cndmask_b32_e32 v78, v78, v79, vcc
	v_rsq_f32_e32 v78, v78
	s_nop 0
	v_mul_f32_e32 v79, 0x45800000, v78
	v_cndmask_b32_e32 v82, v78, v79, vcc
	v_mov_b32_e32 v83, v82
	v_pk_mul_f32 v[78:79], v[96:97], v[82:83] op_sel_hi:[1,0]
	v_pk_mul_f32 v[86:87], v[118:119], v[82:83] op_sel_hi:[1,0]
	s_waitcnt vmcnt(0)
	v_pk_fma_f32 v[94:95], v[98:99], v[78:79], v[102:103]
	v_add_co_u32_e32 v78, vcc, 0x2000, v106
	v_pk_fma_f32 v[96:97], v[100:101], v[86:87], v[104:105]
	s_nop 0
	v_addc_co_u32_e32 v79, vcc, 0, v107, vcc
	global_store_dwordx4 v[78:79], v[94:97], off
	s_and_b64 vcc, exec, s[40:41]
	v_pk_mul_f32 v[78:79], v[92:93], v[82:83]
	s_cbranch_vccz .LBB0_693
	global_load_dwordx4 v[98:101], v[146:147], off offset:1024
	global_load_dwordx4 v[102:105], v[0:1], off offset:1024
	v_mov_b32_e32 v86, v82
	v_mov_b32_e32 v87, v82
	v_mov_b32_e32 v114, v117
	v_pk_mul_f32 v[86:87], v[114:115], v[86:87]
	s_mov_b64 s[2:3], 0
	s_waitcnt vmcnt(0)
	v_pk_fma_f32 v[100:101], v[86:87], v[100:101], v[104:105]
	v_add_co_u32_e32 v86, vcc, 0x2000, v106
	v_pk_fma_f32 v[98:99], v[78:79], v[98:99], v[102:103]
	s_nop 0
	v_addc_co_u32_e32 v87, vcc, 0, v107, vcc
	global_store_dwordx4 v[86:87], v[98:101], off offset:1024
.LBB0_693:
	s_andn2_b64 vcc, exec, s[2:3]
	s_cbranch_vccnz .LBB0_695
	v_add_co_u32_e32 v100, vcc, 0x1000, v160
	v_cvt_pk_bf16_f32 v86, v94, v95
	v_cvt_pk_bf16_f32 v87, v96, v97
	v_mov_b32_e32 v114, v117
	s_nop 0
	v_addc_co_u32_e32 v101, vcc, 0, v161, vcc
	global_store_dwordx2 v[100:101], v[86:87], off
	global_load_dwordx4 v[92:95], v[146:147], off offset:1024
	global_load_dwordx4 v[96:99], v[0:1], off offset:1024
	v_mov_b32_e32 v86, v82
	v_mov_b32_e32 v87, v82
	v_pk_mul_f32 v[86:87], v[114:115], v[86:87]
	s_waitcnt vmcnt(0)
	v_pk_fma_f32 v[92:93], v[78:79], v[92:93], v[96:97]
	v_add_co_u32_e32 v78, vcc, 0x2000, v106
	v_pk_fma_f32 v[94:95], v[86:87], v[94:95], v[98:99]
	s_nop 0
	v_addc_co_u32_e32 v79, vcc, 0, v107, vcc
	global_store_dwordx4 v[78:79], v[92:95], off offset:1024
	v_cvt_pk_bf16_f32 v78, v92, v93
	v_cvt_pk_bf16_f32 v79, v94, v95
	global_store_dwordx2 v[100:101], v[78:79], off offset:512
.LBB0_695:
	global_load_dwordx4 v[94:97], v[146:147], off offset:2048
	s_nop 0
	global_load_dwordx4 v[98:101], v[0:1], off offset:2048
	v_mov_b32_e32 v92, v82
	v_mov_b32_e32 v93, v82
	v_pk_mul_f32 v[78:79], v[112:113], v[92:93]
	v_pk_mul_f32 v[86:87], v[88:89], v[82:83]
	s_mov_b64 s[2:3], -1
	s_waitcnt vmcnt(0)
	v_pk_fma_f32 v[88:89], v[78:79], v[96:97], v[100:101]
	v_add_co_u32_e32 v78, vcc, 0x2000, v106
	v_pk_fma_f32 v[86:87], v[86:87], v[94:95], v[98:99]
	s_nop 0
	v_addc_co_u32_e32 v79, vcc, 0, v107, vcc
	global_store_dwordx4 v[78:79], v[86:89], off offset:2048
	s_and_b64 vcc, exec, s[40:41]
	v_pk_mul_f32 v[78:79], v[84:85], v[82:83]
	s_cbranch_vccz .LBB0_697
	global_load_dwordx4 v[94:97], v[146:147], off offset:3072
	global_load_dwordx4 v[98:101], v[0:1], off offset:3072
	v_pk_mul_f32 v[84:85], v[110:111], v[92:93]
	s_mov_b64 s[2:3], 0
	s_waitcnt vmcnt(0)
	v_pk_fma_f32 v[96:97], v[84:85], v[96:97], v[100:101]
	v_add_co_u32_e32 v84, vcc, 0x2000, v106
	v_pk_fma_f32 v[94:95], v[78:79], v[94:95], v[98:99]
	s_nop 0
	v_addc_co_u32_e32 v85, vcc, 0, v107, vcc
	global_store_dwordx4 v[84:85], v[94:97], off offset:3072
; __device__ void phase_ln(const Params& p, int layer) {
;     ...
; #pragma unroll
;       for (int i = 0; i < 8; ++i) {
;         const int c = i * 256 + lane * 4;
;         const f32x4 g4 = *(const f32x4*)(gg + c), b4 = *(const f32x4*)(bb + c);
;         f32x4 y = v[r][i] * rs * g4 + b4;
;         *(f32x4*)(of + (row + r) * DM + c) = y;
;         if (layer == 0) *(u32x2*)(xb + (row + r) * DM + c) = pack4(y);
;       }
.LBB0_697:
	s_andn2_b64 vcc, exec, s[2:3]
	s_cbranch_vccnz .LBB0_699
	v_cvt_pk_bf16_f32 v85, v88, v89
	v_add_co_u32_e32 v88, vcc, 0x1000, v160
	v_cvt_pk_bf16_f32 v84, v86, v87
	v_mov_b32_e32 v96, v82
	s_nop 0
	v_addc_co_u32_e32 v89, vcc, 0, v161, vcc
	global_store_dwordx2 v[88:89], v[84:85], off offset:1024
	global_load_dwordx4 v[84:87], v[146:147], off offset:3072
	s_nop 0
	global_load_dwordx4 v[92:95], v[0:1], off offset:3072
	v_mov_b32_e32 v97, v82
	v_pk_mul_f32 v[96:97], v[110:111], v[96:97]
	s_waitcnt vmcnt(0)
	v_pk_fma_f32 v[84:85], v[78:79], v[84:85], v[92:93]
	v_add_co_u32_e32 v78, vcc, 0x2000, v106
	v_pk_fma_f32 v[86:87], v[96:97], v[86:87], v[94:95]
	s_nop 0
	v_addc_co_u32_e32 v79, vcc, 0, v107, vcc
	global_store_dwordx4 v[78:79], v[84:87], off offset:3072
	v_cvt_pk_bf16_f32 v78, v84, v85
	v_cvt_pk_bf16_f32 v79, v86, v87
	global_store_dwordx2 v[88:89], v[78:79], off offset:1536
.LBB0_699:
	global_load_dwordx4 v[86:89], v[148:149], off
	s_nop 0
	global_load_dwordx4 v[92:95], v[138:139], off
	v_mov_b32_e32 v84, v82
	v_mov_b32_e32 v85, v82
	v_pk_mul_f32 v[78:79], v[108:109], v[84:85]
	v_pk_mul_f32 v[96:97], v[80:81], v[82:83]
	s_mov_b64 s[2:3], -1
	v_pk_mul_f32 v[76:77], v[76:77], v[82:83]
	s_waitcnt vmcnt(0)
	v_pk_fma_f32 v[80:81], v[78:79], v[88:89], v[94:95]
	v_pk_fma_f32 v[78:79], v[96:97], v[86:87], v[92:93]
	v_add_co_u32_e32 v86, vcc, 0x3000, v106
	s_nop 1
	v_addc_co_u32_e32 v87, vcc, 0, v107, vcc
	s_and_b64 vcc, exec, s[40:41]
	global_store_dwordx4 v[86:87], v[78:81], off
	s_cbranch_vccz .LBB0_701
	global_load_dwordx4 v[86:89], v[150:151], off
	global_load_dwordx4 v[92:95], v[140:141], off
	v_pk_mul_f32 v[84:85], v[90:91], v[84:85]
	s_mov_b64 s[2:3], 0
	s_waitcnt vmcnt(0)
	v_pk_fma_f32 v[88:89], v[84:85], v[88:89], v[94:95]
	v_add_co_u32_e32 v84, vcc, 0x3000, v106
	v_pk_fma_f32 v[86:87], v[76:77], v[86:87], v[92:93]
	s_nop 0
	v_addc_co_u32_e32 v85, vcc, 0, v107, vcc
	global_store_dwordx4 v[84:85], v[86:89], off offset:1024
.LBB0_701:
	s_andn2_b64 vcc, exec, s[2:3]
	s_cbranch_vccnz .LBB0_703
	v_add_co_u32_e32 v88, vcc, 0x1000, v160
	v_cvt_pk_bf16_f32 v78, v78, v79
	v_cvt_pk_bf16_f32 v79, v80, v81
	v_mov_b32_e32 v92, v82
	s_nop 0
	v_addc_co_u32_e32 v89, vcc, 0, v161, vcc
	global_store_dwordx2 v[88:89], v[78:79], off offset:2048
	global_load_dwordx4 v[78:81], v[150:151], off
	s_nop 0
	global_load_dwordx4 v[84:87], v[140:141], off
	v_mov_b32_e32 v93, v82
	v_pk_mul_f32 v[90:91], v[90:91], v[92:93]
	s_waitcnt vmcnt(0)
	v_pk_fma_f32 v[78:79], v[76:77], v[78:79], v[84:85]
	v_add_co_u32_e32 v76, vcc, 0x3000, v106
	v_pk_fma_f32 v[80:81], v[90:91], v[80:81], v[86:87]
	s_nop 0
	v_addc_co_u32_e32 v77, vcc, 0, v107, vcc
	global_store_dwordx4 v[76:77], v[78:81], off offset:1024
	v_cvt_pk_bf16_f32 v76, v78, v79
	v_cvt_pk_bf16_f32 v77, v80, v81
	global_store_dwordx2 v[88:89], v[76:77], off offset:2560
.LBB0_703:
	global_load_dwordx4 v[78:81], v[152:153], off
	global_load_dwordx4 v[84:87], v[142:143], off
	v_pk_mul_f32 v[72:73], v[72:73], v[82:83]
	v_mov_b32_e32 v76, v82
	v_mov_b32_e32 v77, v82
	v_pk_mul_f32 v[74:75], v[74:75], v[76:77]
	s_mov_b64 s[2:3], -1
	v_pk_mul_f32 v[16:17], v[16:17], v[82:83]
	s_waitcnt vmcnt(0)
	v_pk_fma_f32 v[72:73], v[72:73], v[78:79], v[84:85]
	v_add_co_u32_e32 v78, vcc, 0x3000, v106
	v_pk_fma_f32 v[74:75], v[74:75], v[80:81], v[86:87]
	s_nop 0
	v_addc_co_u32_e32 v79, vcc, 0, v107, vcc
	s_and_b64 vcc, exec, s[40:41]
	global_store_dwordx4 v[78:79], v[72:75], off offset:2048
	s_cbranch_vccz .LBB0_705
	global_load_dwordx4 v[78:81], v[154:155], off
	global_load_dwordx4 v[84:87], v[156:157], off
	v_pk_mul_f32 v[76:77], v[18:19], v[76:77]
	s_mov_b64 s[2:3], 0
	s_waitcnt vmcnt(0)
	v_pk_fma_f32 v[80:81], v[76:77], v[80:81], v[86:87]
	v_add_co_u32_e32 v76, vcc, 0x3000, v106
	v_pk_fma_f32 v[78:79], v[16:17], v[78:79], v[84:85]
	s_nop 0
	v_addc_co_u32_e32 v77, vcc, 0, v107, vcc
	global_store_dwordx4 v[76:77], v[78:81], off offset:3072
.LBB0_705:
	s_andn2_b64 vcc, exec, s[2:3]
	s_cbranch_vccnz .LBB0_672
	v_add_co_u32_e32 v80, vcc, 0x1000, v160
	v_cvt_pk_bf16_f32 v72, v72, v73
	v_cvt_pk_bf16_f32 v73, v74, v75
	v_mov_b32_e32 v83, v82
	s_nop 0
	v_addc_co_u32_e32 v81, vcc, 0, v161, vcc
	global_store_dwordx2 v[80:81], v[72:73], off offset:3072
	global_load_dwordx4 v[72:75], v[154:155], off
	s_nop 0
	global_load_dwordx4 v[76:79], v[156:157], off
	v_pk_mul_f32 v[18:19], v[18:19], v[82:83]
	v_add_co_u32_e32 v82, vcc, 0x3000, v106
	s_waitcnt vmcnt(0)
	v_pk_fma_f32 v[18:19], v[18:19], v[74:75], v[78:79]
	v_addc_co_u32_e32 v83, vcc, 0, v107, vcc
	v_pk_fma_f32 v[16:17], v[16:17], v[72:73], v[76:77]
	global_store_dwordx4 v[82:83], v[16:19], off offset:3072
	s_nop 1
	v_cvt_pk_bf16_f32 v16, v16, v17
	v_cvt_pk_bf16_f32 v17, v18, v19
	global_store_dwordx2 v[80:81], v[16:17], off offset:3584
	s_branch .LBB0_672

; __device__ __forceinline__ unsigned xb_ld(unsigned* p) { return __hip_atomic_load(p, __ATOMIC_RELAXED, __HIP_MEMORY_SCOPE_AGENT); }
; __device__ __forceinline__ unsigned xb_add(unsigned* p, unsigned v) { return __hip_atomic_fetch_add(p, v, __ATOMIC_RELAXED, __HIP_MEMORY_SCOPE_AGENT); }
; #define XB_SPIN(cond, bar) do { unsigned _sp = 0; while (cond) { __builtin_amdgcn_s_sleep(1); \
;     if ((++_sp & 255u) == 0u) { if (xb_ld(&(bar)[XB_TMO])) break; if (_sp > XB_SPIN_CAP) { atomicAdd(&(bar)[XB_TMO], 1u); break; } } } } while (0)
; __device__ __forceinline__ void xcd_barrier(const XcdBarrier& b) {
;   asm volatile("s_waitcnt vmcnt(0)" ::: "memory");
;   __syncthreads();
;   if (threadIdx.x == 0) {
;     unsigned* bar = b.bar;
;     unsigned bx = b.x;
;     asm volatile("" : "+s"(bx));
;     __builtin_amdgcn_s_waitcnt(0);
;     unsigned nloc = b.st[0], nx = b.st[1];
;     if (nloc == 0u) { xcd_barrier_complete(bar, bx, nloc, nx); b.st[0] = nloc; b.st[1] = nx; }
;     const unsigned old = xb_add(&bar[XB_XSUB(bx)], 1u);
;     const unsigned gen = old / nloc;
;     if (old + 1u == (gen + 1u) * nloc) {
;       __builtin_amdgcn_fence(__ATOMIC_RELEASE, "agent");
;       asm volatile("s_waitcnt vmcnt(0)" ::: "memory");
;       const unsigned og = xb_add(&bar[XB_TOP], 1u);
;       const unsigned tg = og / nx;
;       if (og + 1u == (tg + 1u) * nx) xb_add(&bar[XB_TOPGEN], 1u);
;       else XB_SPIN(xb_ld(&bar[XB_TOPGEN]) == tg, bar);
;       __builtin_amdgcn_fence(__ATOMIC_ACQUIRE, "agent");
;       xb_add(&bar[XB_XGEN(bx)], 1u);
;       asm volatile("s_waitcnt vmcnt(0)" ::: "memory");
;     } else {
;       XB_SPIN(xb_ld(&bar[XB_XGEN(bx)]) == gen, bar);
;       __builtin_amdgcn_fence(__ATOMIC_ACQUIRE, "agent");
;       asm volatile("s_waitcnt vmcnt(0)" ::: "memory");
;     }
.LBB0_749:
	s_or_b64 exec, exec, s[0:1]
	s_and_saveexec_b64 s[0:1], s[4:5]
	s_cbranch_execz .LBB0_94
	global_atomic_add v[0:1], v165, off
	s_branch .LBB0_94
